# GEMM loops: s_setprio 1 issued before the pre-MFMA barrier so the MFMA segment starts at raised priority; on top of the vmcnt-8 version
# speedup vs baseline: 1.0159x; 1.0159x over previous
; #define PG8_STAGE(bufoff, gbase, voff) do { _Pragma("unroll") for (int _i = 0; _i < 2; ++_i) \
;         __builtin_amdgcn_global_load_lds((const unsigned*)((const char*)(gbase) + (voff)[_i]), (LAS unsigned*)(lds + (bufoff) + ldsw + _i * 8192), 16, 0, 0); } while (0)
; #define PG8_LDA(dst, b, h) do { _Pragma("unroll") for (int m = 0; m < 4; ++m) _Pragma("unroll") for (int k = 0; k < 2; ++k) dst[m][k] = *(const LAS bf16x8*)(lds + PG8_SA(b, h) + aoff + m * 2048 + k * 1024); } while (0)
; #define PG8_LDB(dst, b, h) do { _Pragma("unroll") for (int n = 0; n < 2; ++n) _Pragma("unroll") for (int k = 0; k < 2; ++k) dst[n][k] = *(const LAS bf16x8*)(lds + PG8_SB(b, h) + boff + n * 2048 + k * 1024); } while (0)
; #define PG8_MMA(ai, bj, At, Bt) do { __builtin_amdgcn_s_setprio(1); _Pragma("unroll") for (int m = 0; m < 4; ++m) _Pragma("unroll") for (int n = 0; n < 2; ++n) _Pragma("unroll") for (int k = 0; k < 2; ++k) \
;         acc[ai][bj][m][n] = __builtin_amdgcn_mfma_f32_16x16x32_bf16(Bt[n][k], At[m][k], acc[ai][bj][m][n], 0, 0, 0); __builtin_amdgcn_s_setprio(0); } while (0)
; #define PG8_WAIT_L(n) asm volatile("s_waitcnt lgkmcnt(" #n ")" ::: "memory")
; template <class Epi, class Sched>
; __device__ __forceinline__ void gemm_phase(LAS unsigned char* lds, const Gemm g, const Sched& S, const Epi& E) {
;     ...
;         const bool has_next = S.next(ui + 1, nxt);
;         const char* nA = has_next ? (const char*)g.A + (size_t)nxt.pm * tstep : cA; const char* nB = has_next ? (const char*)g.Bt + (size_t)nxt.pn * tstep : cB;
;         for (int t = 0; t < nt; t += 2) {
;             const bool last = (t == nt - 2);
;             const char* a1 = cA + (size_t)(t + 1) * kstep;
;             const char* a2 = last ? nA : cA + (size_t)(t + 2) * kstep; const char* b2 = last ? nB : cB + (size_t)(t + 2) * kstep;
;             const char* a3 = a2 + kstep; const char* b3 = b2 + kstep;
;             PG8_LDB(B0, 0, 0); PG8_SCHED; PG8_LDA(At, 0, 0); PG8_STAGE(PG8_SA(1, 1), a1 + hstep, voffA);
;             PG8_WAIT_L(8); PG8_BAR; PG8_WAIT_L(0); PG8_MMA(0, 0, At, B0); PG8_BAR; PG8_SCHED;
;             PG8_LDB(B1, 0, 1); PG8_STAGE(PG8_SB(0, 0), b2, voffB);
;             PG8_BAR; PG8_WAIT_L(0); PG8_MMA(0, 1, At, B1); PG8_BAR;
;             PG8_LDA(At, 0, 1); PG8_STAGE(PG8_SA(0, 0), a2, voffA);
;             PG8_BAR; PG8_WAIT_L(0); PG8_MMA(1, 0, At, B0); PG8_BAR; PG8_SCHED;
.LBB0_234:
	s_ashr_i32 s7, s6, 31
	v_cmp_lt_i64_e32 vcc, s[8:9], v[140:141]
	s_lshl_b64 s[8:9], s[6:7], 19
	s_add_u32 s8, s96, s8
	s_addc_u32 s9, s97, s9
	s_and_b64 s[10:11], vcc, exec
	s_cselect_b32 s7, s9, s15
	s_cselect_b32 s44, s8, s14
	s_ashr_i32 s5, s4, 31
	s_lshl_b64 s[10:11], s[4:5], 19
	s_add_u32 s10, s72, s10
	s_addc_u32 s11, s73, s11
	s_and_b64 s[16:17], vcc, exec
	s_cselect_b32 s5, s11, s19
	s_cselect_b32 s45, s10, s18
	s_add_u32 s14, s14, 0x40080
	s_addc_u32 s15, s15, 0
	s_add_u32 s46, s18, 0x100
	s_addc_u32 s47, s19, 0
	s_mov_b32 s48, -2
	ds_read_b128 v[150:153], v147
	ds_read_b128 v[154:157], v147 offset:1024
	ds_read_b128 v[158:161], v147 offset:2048
	ds_read_b128 v[162:165], v147 offset:3072
	s_add_u32 s16, s14, 0xfffc0080
	s_addc_u32 s17, s15, -1
	s_cmp_eq_u32 s48, 12
	s_cselect_b32 s23, s7, s17
	s_cselect_b32 s22, s44, s16
	s_cselect_b32 s19, s5, s47
	s_cselect_b32 s18, s45, s46
	s_add_i32 m0, s13, 0xc000
	ds_read_b128 v[166:169], v148
	ds_read_b128 v[170:173], v148 offset:1024
	ds_read_b128 v[174:177], v148 offset:2048
	ds_read_b128 v[178:181], v148 offset:3072
	ds_read_b128 v[182:185], v148 offset:4096
	ds_read_b128 v[186:189], v148 offset:5120
	ds_read_b128 v[190:193], v148 offset:6144
	ds_read_b128 v[194:197], v148 offset:7168
	global_load_lds_dwordx4 v136, s[14:15]
	s_add_i32 m0, s13, 0xe000
	s_nop 0
	global_load_lds_dwordx4 v138, s[14:15]
	s_waitcnt lgkmcnt(8)
	s_waitcnt vmcnt(8)
	s_setprio 1
	s_barrier
	s_waitcnt lgkmcnt(0)
	s_waitcnt lgkmcnt(0)
	v_mfma_f32_16x16x32_bf16 v[124:127], v[150:153], v[166:169], 0
	v_mfma_f32_16x16x32_bf16 v[116:119], v[158:161], v[166:169], 0
	v_mfma_f32_16x16x32_bf16 v[108:111], v[150:153], v[174:177], 0
	v_mfma_f32_16x16x32_bf16 v[100:103], v[158:161], v[174:177], 0
	v_mfma_f32_16x16x32_bf16 v[92:95], v[150:153], v[182:185], 0
	v_mfma_f32_16x16x32_bf16 v[84:87], v[158:161], v[182:185], 0
	v_mfma_f32_16x16x32_bf16 v[76:79], v[150:153], v[190:193], 0
	v_mfma_f32_16x16x32_bf16 v[68:71], v[158:161], v[190:193], 0
	v_mfma_f32_16x16x32_bf16 v[124:127], v[154:157], v[170:173], v[124:127]
	v_mfma_f32_16x16x32_bf16 v[116:119], v[162:165], v[170:173], v[116:119]
	v_mfma_f32_16x16x32_bf16 v[108:111], v[154:157], v[178:181], v[108:111]
	v_mfma_f32_16x16x32_bf16 v[100:103], v[162:165], v[178:181], v[100:103]
	v_mfma_f32_16x16x32_bf16 v[92:95], v[154:157], v[186:189], v[92:95]
	v_mfma_f32_16x16x32_bf16 v[84:87], v[162:165], v[186:189], v[84:87]
	v_mfma_f32_16x16x32_bf16 v[76:79], v[154:157], v[194:197], v[76:79]
	v_mfma_f32_16x16x32_bf16 v[68:71], v[162:165], v[194:197], v[68:71]
	s_setprio 0
	s_barrier
	s_add_i32 s16, s40, s25
	s_mov_b32 m0, s16
	ds_read_b128 v[202:205], v149
	ds_read_b128 v[206:209], v149 offset:1024
	ds_read_b128 v[210:213], v149 offset:2048
	ds_read_b128 v[214:217], v149 offset:3072
	global_load_lds_dwordx4 v132, s[18:19]
	s_add_i32 m0, s16, 0x2000
	s_nop 0
	global_load_lds_dwordx4 v128, s[18:19]
	s_waitcnt vmcnt(8)
	s_setprio 1
	s_barrier
	s_waitcnt lgkmcnt(0)
	s_waitcnt lgkmcnt(0)
	v_mfma_f32_16x16x32_bf16 v[120:123], v[202:205], v[166:169], 0
	v_mfma_f32_16x16x32_bf16 v[112:115], v[210:213], v[166:169], 0
	v_mfma_f32_16x16x32_bf16 v[104:107], v[202:205], v[174:177], 0
	v_mfma_f32_16x16x32_bf16 v[96:99], v[210:213], v[174:177], 0
	v_mfma_f32_16x16x32_bf16 v[88:91], v[202:205], v[182:185], 0
	v_mfma_f32_16x16x32_bf16 v[80:83], v[210:213], v[182:185], 0
	v_mfma_f32_16x16x32_bf16 v[72:75], v[202:205], v[190:193], 0
	v_mfma_f32_16x16x32_bf16 v[64:67], v[210:213], v[190:193], 0
	v_mfma_f32_16x16x32_bf16 v[120:123], v[206:209], v[170:173], v[120:123]
	v_mfma_f32_16x16x32_bf16 v[112:115], v[214:217], v[170:173], v[112:115]
	v_mfma_f32_16x16x32_bf16 v[104:107], v[206:209], v[178:181], v[104:107]
	v_mfma_f32_16x16x32_bf16 v[96:99], v[214:217], v[178:181], v[96:99]
	v_mfma_f32_16x16x32_bf16 v[88:91], v[206:209], v[186:189], v[88:91]
	v_mfma_f32_16x16x32_bf16 v[80:83], v[214:217], v[186:189], v[80:83]
	v_mfma_f32_16x16x32_bf16 v[72:75], v[206:209], v[194:197], v[72:75]
	v_mfma_f32_16x16x32_bf16 v[64:67], v[214:217], v[194:197], v[64:67]
	s_setprio 0
	s_mov_b32 m0, s13
	s_barrier
	ds_read_b128 v[166:169], v148 offset:16384
	ds_read_b128 v[170:173], v148 offset:17408
	ds_read_b128 v[174:177], v148 offset:18432
	ds_read_b128 v[178:181], v148 offset:19456
	ds_read_b128 v[182:185], v148 offset:20480
	ds_read_b128 v[186:189], v148 offset:21504
	ds_read_b128 v[190:193], v148 offset:22528
	ds_read_b128 v[194:197], v148 offset:23552
	global_load_lds_dwordx4 v134, s[22:23]
	s_mov_b32 m0, s28
	s_nop 0
	global_load_lds_dwordx4 v130, s[22:23]
	s_setprio 1
	s_barrier
	s_waitcnt lgkmcnt(0)
	s_waitcnt lgkmcnt(0)
	v_mfma_f32_16x16x32_bf16 v[60:63], v[150:153], v[166:169], 0
	v_mfma_f32_16x16x32_bf16 v[56:59], v[158:161], v[166:169], 0
	v_mfma_f32_16x16x32_bf16 v[44:47], v[150:153], v[174:177], 0
	v_mfma_f32_16x16x32_bf16 v[40:43], v[158:161], v[174:177], 0
	v_mfma_f32_16x16x32_bf16 v[28:31], v[150:153], v[182:185], 0
	v_mfma_f32_16x16x32_bf16 v[24:27], v[158:161], v[182:185], 0
	v_mfma_f32_16x16x32_bf16 v[12:15], v[150:153], v[190:193], 0
	v_mfma_f32_16x16x32_bf16 v[8:11], v[158:161], v[190:193], 0
	v_mfma_f32_16x16x32_bf16 v[60:63], v[154:157], v[170:173], v[60:63]
	v_mfma_f32_16x16x32_bf16 v[56:59], v[162:165], v[170:173], v[56:59]
	v_mfma_f32_16x16x32_bf16 v[44:47], v[154:157], v[178:181], v[44:47]
	v_mfma_f32_16x16x32_bf16 v[40:43], v[162:165], v[178:181], v[40:43]
	v_mfma_f32_16x16x32_bf16 v[28:31], v[154:157], v[186:189], v[28:31]
	v_mfma_f32_16x16x32_bf16 v[24:27], v[162:165], v[186:189], v[24:27]
	v_mfma_f32_16x16x32_bf16 v[12:15], v[154:157], v[194:197], v[12:15]
	v_mfma_f32_16x16x32_bf16 v[8:11], v[162:165], v[194:197], v[8:11]
	s_setprio 0
	s_barrier
; #define PG8_STAGE(bufoff, gbase, voff) do { _Pragma("unroll") for (int _i = 0; _i < 2; ++_i) \
;         __builtin_amdgcn_global_load_lds((const unsigned*)((const char*)(gbase) + (voff)[_i]), (LAS unsigned*)(lds + (bufoff) + ldsw + _i * 8192), 16, 0, 0); } while (0)
; #define PG8_LDA(dst, b, h) do { _Pragma("unroll") for (int m = 0; m < 4; ++m) _Pragma("unroll") for (int k = 0; k < 2; ++k) dst[m][k] = *(const LAS bf16x8*)(lds + PG8_SA(b, h) + aoff + m * 2048 + k * 1024); } while (0)
; #define PG8_LDB(dst, b, h) do { _Pragma("unroll") for (int n = 0; n < 2; ++n) _Pragma("unroll") for (int k = 0; k < 2; ++k) dst[n][k] = *(const LAS bf16x8*)(lds + PG8_SB(b, h) + boff + n * 2048 + k * 1024); } while (0)
; #define PG8_MMA(ai, bj, At, Bt) do { __builtin_amdgcn_s_setprio(1); _Pragma("unroll") for (int m = 0; m < 4; ++m) _Pragma("unroll") for (int n = 0; n < 2; ++n) _Pragma("unroll") for (int k = 0; k < 2; ++k) \
;         acc[ai][bj][m][n] = __builtin_amdgcn_mfma_f32_16x16x32_bf16(Bt[n][k], At[m][k], acc[ai][bj][m][n], 0, 0, 0); __builtin_amdgcn_s_setprio(0); } while (0)
; #define PG8_WAIT_V(n) asm volatile("s_waitcnt vmcnt(" #n ")" ::: "memory")
; #define PG8_WAIT_L(n) asm volatile("s_waitcnt lgkmcnt(" #n ")" ::: "memory")
; #define PG8_BAR __builtin_amdgcn_s_barrier()
; #define PG8_SCHED __builtin_amdgcn_sched_barrier(0)
; template <class Epi, class Sched>
; __device__ __forceinline__ void gemm_phase(LAS unsigned char* lds, const Gemm g, const Sched& S, const Epi& E) {
;     ...
;             PG8_STAGE(PG8_SB(0, 1), b2 + hstep, voffB);
;             PG8_WAIT_V(6); PG8_BAR; PG8_MMA(1, 1, At, B1); PG8_BAR;
;             PG8_LDB(B0, 1, 0); PG8_SCHED; PG8_LDA(At, 1, 0); PG8_STAGE(PG8_SA(0, 1), a2 + hstep, voffA);
;             PG8_WAIT_L(8); PG8_BAR; PG8_WAIT_L(0); PG8_MMA(0, 0, At, B0); PG8_BAR; PG8_SCHED;
;             PG8_LDB(B1, 1, 1); PG8_STAGE(PG8_SB(1, 0), b3, voffB);
;             PG8_BAR; PG8_WAIT_L(0); PG8_MMA(0, 1, At, B1); PG8_BAR;
;             PG8_LDA(At, 1, 1); PG8_STAGE(PG8_SA(1, 0), a3, voffA);
	s_add_u32 s16, s18, 0x40000
	s_addc_u32 s17, s19, 0
	s_add_i32 s20, s41, s25
	s_mov_b32 m0, s20
	s_nop 0
	global_load_lds_dwordx4 v132, s[16:17]
	s_add_i32 m0, s20, 0x2000
	s_nop 0
	global_load_lds_dwordx4 v128, s[16:17]
	s_add_u32 s16, s22, 0x40000
	s_addc_u32 s17, s23, 0
	s_mov_b32 m0, s29
	s_nop 0
	global_load_lds_dwordx4 v134, s[16:17]
	s_mov_b32 m0, s33
	s_nop 0
	global_load_lds_dwordx4 v130, s[16:17]
	s_waitcnt vmcnt(10)
	s_setprio 1
	s_barrier
	v_mfma_f32_16x16x32_bf16 v[52:55], v[202:205], v[166:169], 0
	v_mfma_f32_16x16x32_bf16 v[48:51], v[210:213], v[166:169], 0
	v_mfma_f32_16x16x32_bf16 v[36:39], v[202:205], v[174:177], 0
	v_mfma_f32_16x16x32_bf16 v[32:35], v[210:213], v[174:177], 0
	v_mfma_f32_16x16x32_bf16 v[20:23], v[202:205], v[182:185], 0
	v_mfma_f32_16x16x32_bf16 v[16:19], v[210:213], v[182:185], 0
	v_mfma_f32_16x16x32_bf16 v[4:7], v[202:205], v[190:193], 0
	v_mfma_f32_16x16x32_bf16 v[0:3], v[210:213], v[190:193], 0
	v_mfma_f32_16x16x32_bf16 v[52:55], v[206:209], v[170:173], v[52:55]
	v_mfma_f32_16x16x32_bf16 v[48:51], v[214:217], v[170:173], v[48:51]
	v_mfma_f32_16x16x32_bf16 v[36:39], v[206:209], v[178:181], v[36:39]
	v_mfma_f32_16x16x32_bf16 v[32:35], v[214:217], v[178:181], v[32:35]
	v_mfma_f32_16x16x32_bf16 v[20:23], v[206:209], v[186:189], v[20:23]
	v_mfma_f32_16x16x32_bf16 v[16:19], v[214:217], v[186:189], v[16:19]
	v_mfma_f32_16x16x32_bf16 v[4:7], v[206:209], v[194:197], v[4:7]
	v_mfma_f32_16x16x32_bf16 v[0:3], v[214:217], v[194:197], v[0:3]
	s_setprio 0
	s_add_i32 s20, 0, 0x18000
	v_add_u32_e32 v162, s20, v146
	s_barrier
	ds_read_b128 v[150:153], v162
	ds_read_b128 v[154:157], v162 offset:1024
	ds_read_b128 v[158:161], v162 offset:2048
	ds_read_b128 v[162:165], v162 offset:3072
	ds_read_b128 v[166:169], v148 offset:32768
	ds_read_b128 v[170:173], v148 offset:33792
	ds_read_b128 v[174:177], v148 offset:34816
	ds_read_b128 v[178:181], v148 offset:35840
	ds_read_b128 v[182:185], v148 offset:36864
	ds_read_b128 v[186:189], v148 offset:37888
	ds_read_b128 v[190:193], v148 offset:38912
	ds_read_b128 v[194:197], v148 offset:39936
	s_waitcnt lgkmcnt(8)
	s_waitcnt vmcnt(8)
	s_setprio 1
	s_barrier
	s_waitcnt lgkmcnt(0)
	s_waitcnt lgkmcnt(0)
	v_mfma_f32_16x16x32_bf16 v[124:127], v[150:153], v[166:169], v[124:127]
	v_mfma_f32_16x16x32_bf16 v[116:119], v[158:161], v[166:169], v[116:119]
	v_mfma_f32_16x16x32_bf16 v[108:111], v[150:153], v[174:177], v[108:111]
	v_mfma_f32_16x16x32_bf16 v[100:103], v[158:161], v[174:177], v[100:103]
	v_mfma_f32_16x16x32_bf16 v[92:95], v[150:153], v[182:185], v[92:95]
	v_mfma_f32_16x16x32_bf16 v[84:87], v[158:161], v[182:185], v[84:87]
	v_mfma_f32_16x16x32_bf16 v[76:79], v[150:153], v[190:193], v[76:79]
	v_mfma_f32_16x16x32_bf16 v[68:71], v[158:161], v[190:193], v[68:71]
	v_mfma_f32_16x16x32_bf16 v[124:127], v[154:157], v[170:173], v[124:127]
	v_mfma_f32_16x16x32_bf16 v[116:119], v[162:165], v[170:173], v[116:119]
	v_mfma_f32_16x16x32_bf16 v[108:111], v[154:157], v[178:181], v[108:111]
	v_mfma_f32_16x16x32_bf16 v[100:103], v[162:165], v[178:181], v[100:103]
	v_mfma_f32_16x16x32_bf16 v[92:95], v[154:157], v[186:189], v[92:95]
	v_mfma_f32_16x16x32_bf16 v[84:87], v[162:165], v[186:189], v[84:87]
	v_mfma_f32_16x16x32_bf16 v[76:79], v[154:157], v[194:197], v[76:79]
	v_mfma_f32_16x16x32_bf16 v[68:71], v[162:165], v[194:197], v[68:71]
	s_setprio 0
	s_barrier
	s_add_i32 s21, 0, 0x1c000
	s_add_i32 s16, s20, s25
	v_add_u32_e32 v214, s21, v146
	s_add_u32 s0, s18, 0x80
	s_addc_u32 s1, s19, 0
	s_mov_b32 m0, s16
	ds_read_b128 v[202:205], v214
	ds_read_b128 v[206:209], v214 offset:1024
	ds_read_b128 v[210:213], v214 offset:2048
	ds_read_b128 v[214:217], v214 offset:3072
	global_load_lds_dwordx4 v132, s[0:1]
	s_add_i32 m0, s16, 0x2000
	s_nop 0
	global_load_lds_dwordx4 v128, s[0:1]
	s_waitcnt vmcnt(8)
	s_setprio 1
	s_barrier
	s_waitcnt lgkmcnt(0)
	s_waitcnt lgkmcnt(0)
	v_mfma_f32_16x16x32_bf16 v[120:123], v[202:205], v[166:169], v[120:123]
	v_mfma_f32_16x16x32_bf16 v[112:115], v[210:213], v[166:169], v[112:115]
	v_mfma_f32_16x16x32_bf16 v[104:107], v[202:205], v[174:177], v[104:107]
	v_mfma_f32_16x16x32_bf16 v[96:99], v[210:213], v[174:177], v[96:99]
	v_mfma_f32_16x16x32_bf16 v[88:91], v[202:205], v[182:185], v[88:91]
	v_mfma_f32_16x16x32_bf16 v[80:83], v[210:213], v[182:185], v[80:83]
	v_mfma_f32_16x16x32_bf16 v[72:75], v[202:205], v[190:193], v[72:75]
	v_mfma_f32_16x16x32_bf16 v[64:67], v[210:213], v[190:193], v[64:67]
	v_mfma_f32_16x16x32_bf16 v[120:123], v[206:209], v[170:173], v[120:123]
	v_mfma_f32_16x16x32_bf16 v[112:115], v[214:217], v[170:173], v[112:115]
	v_mfma_f32_16x16x32_bf16 v[104:107], v[206:209], v[178:181], v[104:107]
	v_mfma_f32_16x16x32_bf16 v[96:99], v[214:217], v[178:181], v[96:99]
	v_mfma_f32_16x16x32_bf16 v[88:91], v[206:209], v[186:189], v[88:91]
	v_mfma_f32_16x16x32_bf16 v[80:83], v[214:217], v[186:189], v[80:83]
	v_mfma_f32_16x16x32_bf16 v[72:75], v[206:209], v[194:197], v[72:75]
	v_mfma_f32_16x16x32_bf16 v[64:67], v[214:217], v[194:197], v[64:67]
	s_setprio 0
	s_mov_b32 m0, s36
	s_add_u32 s0, s22, 0x80
	s_addc_u32 s1, s23, 0
	s_barrier
	ds_read_b128 v[166:169], v148 offset:49152
	ds_read_b128 v[170:173], v148 offset:50176
	ds_read_b128 v[174:177], v148 offset:51200
	ds_read_b128 v[178:181], v148 offset:52224
	ds_read_b128 v[182:185], v148 offset:53248
	ds_read_b128 v[186:189], v148 offset:54272
	ds_read_b128 v[190:193], v148 offset:55296
	ds_read_b128 v[194:197], v148 offset:56320
	global_load_lds_dwordx4 v134, s[0:1]
	s_mov_b32 m0, s37
	s_nop 0
	global_load_lds_dwordx4 v130, s[0:1]
	s_setprio 1
	s_barrier
; #define PG8_STAGE(bufoff, gbase, voff) do { _Pragma("unroll") for (int _i = 0; _i < 2; ++_i) \
;         __builtin_amdgcn_global_load_lds((const unsigned*)((const char*)(gbase) + (voff)[_i]), (LAS unsigned*)(lds + (bufoff) + ldsw + _i * 8192), 16, 0, 0); } while (0)
; #define PG8_LDA(dst, b, h) do { _Pragma("unroll") for (int m = 0; m < 4; ++m) _Pragma("unroll") for (int k = 0; k < 2; ++k) dst[m][k] = *(const LAS bf16x8*)(lds + PG8_SA(b, h) + aoff + m * 2048 + k * 1024); } while (0)
; #define PG8_LDB(dst, b, h) do { _Pragma("unroll") for (int n = 0; n < 2; ++n) _Pragma("unroll") for (int k = 0; k < 2; ++k) dst[n][k] = *(const LAS bf16x8*)(lds + PG8_SB(b, h) + boff + n * 2048 + k * 1024); } while (0)
; #define PG8_MMA(ai, bj, At, Bt) do { __builtin_amdgcn_s_setprio(1); _Pragma("unroll") for (int m = 0; m < 4; ++m) _Pragma("unroll") for (int n = 0; n < 2; ++n) _Pragma("unroll") for (int k = 0; k < 2; ++k) \
;         acc[ai][bj][m][n] = __builtin_amdgcn_mfma_f32_16x16x32_bf16(Bt[n][k], At[m][k], acc[ai][bj][m][n], 0, 0, 0); __builtin_amdgcn_s_setprio(0); } while (0)
; #define PG8_WAIT_V(n) asm volatile("s_waitcnt vmcnt(" #n ")" ::: "memory")
; #define PG8_WAIT_L(n) asm volatile("s_waitcnt lgkmcnt(" #n ")" ::: "memory")
; #define PG8_BAR __builtin_amdgcn_s_barrier()
; #define PG8_SCHED __builtin_amdgcn_sched_barrier(0)
; template <class Epi, class Sched>
; __device__ __forceinline__ void gemm_phase(LAS unsigned char* lds, const Gemm g, const Sched& S, const Epi& E) {
;     ...
;             PG8_LDB(B0, 0, 0); PG8_SCHED; PG8_LDA(At, 0, 0); PG8_STAGE(PG8_SA(1, 1), a1 + hstep, voffA);
;             PG8_WAIT_L(8); PG8_BAR; PG8_WAIT_L(0); PG8_MMA(0, 0, At, B0); PG8_BAR; PG8_SCHED;
;             PG8_LDB(B1, 0, 1); PG8_STAGE(PG8_SB(0, 0), b2, voffB);
;             PG8_BAR; PG8_WAIT_L(0); PG8_MMA(0, 1, At, B1); PG8_BAR;
;     ...
;             PG8_BAR; PG8_WAIT_L(0); PG8_MMA(1, 0, At, B0); PG8_BAR; PG8_SCHED;
;             PG8_STAGE(PG8_SB(1, 1), b3 + hstep, voffB);
;             PG8_WAIT_V(6); PG8_BAR; PG8_MMA(1, 1, At, B1); PG8_BAR;
	s_waitcnt lgkmcnt(0)
	s_waitcnt lgkmcnt(0)
	v_mfma_f32_16x16x32_bf16 v[60:63], v[150:153], v[166:169], v[60:63]
	v_mfma_f32_16x16x32_bf16 v[56:59], v[158:161], v[166:169], v[56:59]
	v_mfma_f32_16x16x32_bf16 v[44:47], v[150:153], v[174:177], v[44:47]
	v_mfma_f32_16x16x32_bf16 v[40:43], v[158:161], v[174:177], v[40:43]
	v_mfma_f32_16x16x32_bf16 v[28:31], v[150:153], v[182:185], v[28:31]
	v_mfma_f32_16x16x32_bf16 v[24:27], v[158:161], v[182:185], v[24:27]
	v_mfma_f32_16x16x32_bf16 v[12:15], v[150:153], v[190:193], v[12:15]
	v_mfma_f32_16x16x32_bf16 v[8:11], v[158:161], v[190:193], v[8:11]
	v_mfma_f32_16x16x32_bf16 v[60:63], v[154:157], v[170:173], v[60:63]
	v_mfma_f32_16x16x32_bf16 v[56:59], v[162:165], v[170:173], v[56:59]
	v_mfma_f32_16x16x32_bf16 v[44:47], v[154:157], v[178:181], v[44:47]
	v_mfma_f32_16x16x32_bf16 v[40:43], v[162:165], v[178:181], v[40:43]
	v_mfma_f32_16x16x32_bf16 v[28:31], v[154:157], v[186:189], v[28:31]
	v_mfma_f32_16x16x32_bf16 v[24:27], v[162:165], v[186:189], v[24:27]
	v_mfma_f32_16x16x32_bf16 v[12:15], v[154:157], v[194:197], v[12:15]
	v_mfma_f32_16x16x32_bf16 v[8:11], v[162:165], v[194:197], v[8:11]
	s_setprio 0
	s_barrier
	s_add_u32 s16, s18, 0x40080
	s_addc_u32 s17, s19, 0
	s_add_i32 s18, s21, s25
	s_mov_b32 m0, s18
	s_nop 0
	global_load_lds_dwordx4 v132, s[16:17]
	s_add_i32 m0, s18, 0x2000
	s_nop 0
	global_load_lds_dwordx4 v128, s[16:17]
	s_waitcnt vmcnt(8)
	s_setprio 1
	s_barrier
	v_mfma_f32_16x16x32_bf16 v[52:55], v[202:205], v[166:169], v[52:55]
	v_mfma_f32_16x16x32_bf16 v[48:51], v[210:213], v[166:169], v[48:51]
	v_mfma_f32_16x16x32_bf16 v[36:39], v[202:205], v[174:177], v[36:39]
	v_mfma_f32_16x16x32_bf16 v[32:35], v[210:213], v[174:177], v[32:35]
	v_mfma_f32_16x16x32_bf16 v[20:23], v[202:205], v[182:185], v[20:23]
	v_mfma_f32_16x16x32_bf16 v[16:19], v[210:213], v[182:185], v[16:19]
	v_mfma_f32_16x16x32_bf16 v[4:7], v[202:205], v[190:193], v[4:7]
	v_mfma_f32_16x16x32_bf16 v[0:3], v[210:213], v[190:193], v[0:3]
	v_mfma_f32_16x16x32_bf16 v[52:55], v[206:209], v[170:173], v[52:55]
	v_mfma_f32_16x16x32_bf16 v[48:51], v[214:217], v[170:173], v[48:51]
	v_mfma_f32_16x16x32_bf16 v[36:39], v[206:209], v[178:181], v[36:39]
	v_mfma_f32_16x16x32_bf16 v[32:35], v[214:217], v[178:181], v[32:35]
	v_mfma_f32_16x16x32_bf16 v[20:23], v[206:209], v[186:189], v[20:23]
	v_mfma_f32_16x16x32_bf16 v[16:19], v[214:217], v[186:189], v[16:19]
	v_mfma_f32_16x16x32_bf16 v[4:7], v[206:209], v[194:197], v[4:7]
	v_mfma_f32_16x16x32_bf16 v[0:3], v[214:217], v[194:197], v[0:3]
	s_setprio 0
	s_add_i32 s48, s48, 2
	s_add_u32 s14, s14, 0x100
	s_addc_u32 s15, s15, 0
	s_add_u32 s46, s46, 0x100
	s_addc_u32 s47, s47, 0
	s_cmp_gt_u32 s48, 13
	s_barrier
.LBB0_235:
	ds_read_b128 v[150:153], v147
	ds_read_b128 v[154:157], v147 offset:1024
	ds_read_b128 v[158:161], v147 offset:2048
	ds_read_b128 v[162:165], v147 offset:3072
	s_add_u32 s16, s14, 0xfffc0080
	s_addc_u32 s17, s15, -1
	s_cmp_eq_u32 s48, 12
	s_cselect_b32 s23, s7, s17
	s_cselect_b32 s22, s44, s16
	s_cselect_b32 s19, s5, s47
	s_cselect_b32 s18, s45, s46
	s_add_i32 m0, s13, 0xc000
	ds_read_b128 v[166:169], v148
	ds_read_b128 v[170:173], v148 offset:1024
	ds_read_b128 v[174:177], v148 offset:2048
	ds_read_b128 v[178:181], v148 offset:3072
	ds_read_b128 v[182:185], v148 offset:4096
	ds_read_b128 v[186:189], v148 offset:5120
	ds_read_b128 v[190:193], v148 offset:6144
	ds_read_b128 v[194:197], v148 offset:7168
	global_load_lds_dwordx4 v136, s[14:15]
	s_add_i32 m0, s13, 0xe000
	s_nop 0
	global_load_lds_dwordx4 v138, s[14:15]
	s_waitcnt lgkmcnt(8)
	s_waitcnt vmcnt(8)
	s_setprio 1
	s_barrier
	s_waitcnt lgkmcnt(0)
	s_waitcnt lgkmcnt(0)
	v_mfma_f32_16x16x32_bf16 v[124:127], v[150:153], v[166:169], v[124:127]
	v_mfma_f32_16x16x32_bf16 v[116:119], v[158:161], v[166:169], v[116:119]
	v_mfma_f32_16x16x32_bf16 v[108:111], v[150:153], v[174:177], v[108:111]
	v_mfma_f32_16x16x32_bf16 v[100:103], v[158:161], v[174:177], v[100:103]
	v_mfma_f32_16x16x32_bf16 v[92:95], v[150:153], v[182:185], v[92:95]
	v_mfma_f32_16x16x32_bf16 v[84:87], v[158:161], v[182:185], v[84:87]
	v_mfma_f32_16x16x32_bf16 v[76:79], v[150:153], v[190:193], v[76:79]
	v_mfma_f32_16x16x32_bf16 v[68:71], v[158:161], v[190:193], v[68:71]
	v_mfma_f32_16x16x32_bf16 v[124:127], v[154:157], v[170:173], v[124:127]
	v_mfma_f32_16x16x32_bf16 v[116:119], v[162:165], v[170:173], v[116:119]
	v_mfma_f32_16x16x32_bf16 v[108:111], v[154:157], v[178:181], v[108:111]
	v_mfma_f32_16x16x32_bf16 v[100:103], v[162:165], v[178:181], v[100:103]
	v_mfma_f32_16x16x32_bf16 v[92:95], v[154:157], v[186:189], v[92:95]
	v_mfma_f32_16x16x32_bf16 v[84:87], v[162:165], v[186:189], v[84:87]
	v_mfma_f32_16x16x32_bf16 v[76:79], v[154:157], v[194:197], v[76:79]
	v_mfma_f32_16x16x32_bf16 v[68:71], v[162:165], v[194:197], v[68:71]
	s_setprio 0
	s_barrier
	s_add_i32 s16, s40, s25
	s_mov_b32 m0, s16
	ds_read_b128 v[202:205], v149
	ds_read_b128 v[206:209], v149 offset:1024
	ds_read_b128 v[210:213], v149 offset:2048
	ds_read_b128 v[214:217], v149 offset:3072
	global_load_lds_dwordx4 v132, s[18:19]
	s_add_i32 m0, s16, 0x2000
	s_nop 0
	global_load_lds_dwordx4 v128, s[18:19]
	s_waitcnt vmcnt(8)
	s_setprio 1
	s_barrier
; #define PG8_STAGE(bufoff, gbase, voff) do { _Pragma("unroll") for (int _i = 0; _i < 2; ++_i) \
;         __builtin_amdgcn_global_load_lds((const unsigned*)((const char*)(gbase) + (voff)[_i]), (LAS unsigned*)(lds + (bufoff) + ldsw + _i * 8192), 16, 0, 0); } while (0)
; #define PG8_LDA(dst, b, h) do { _Pragma("unroll") for (int m = 0; m < 4; ++m) _Pragma("unroll") for (int k = 0; k < 2; ++k) dst[m][k] = *(const LAS bf16x8*)(lds + PG8_SA(b, h) + aoff + m * 2048 + k * 1024); } while (0)
; #define PG8_LDB(dst, b, h) do { _Pragma("unroll") for (int n = 0; n < 2; ++n) _Pragma("unroll") for (int k = 0; k < 2; ++k) dst[n][k] = *(const LAS bf16x8*)(lds + PG8_SB(b, h) + boff + n * 2048 + k * 1024); } while (0)
; #define PG8_MMA(ai, bj, At, Bt) do { __builtin_amdgcn_s_setprio(1); _Pragma("unroll") for (int m = 0; m < 4; ++m) _Pragma("unroll") for (int n = 0; n < 2; ++n) _Pragma("unroll") for (int k = 0; k < 2; ++k) \
;         acc[ai][bj][m][n] = __builtin_amdgcn_mfma_f32_16x16x32_bf16(Bt[n][k], At[m][k], acc[ai][bj][m][n], 0, 0, 0); __builtin_amdgcn_s_setprio(0); } while (0)
; #define PG8_WAIT_V(n) asm volatile("s_waitcnt vmcnt(" #n ")" ::: "memory")
; #define PG8_WAIT_L(n) asm volatile("s_waitcnt lgkmcnt(" #n ")" ::: "memory")
; #define PG8_BAR __builtin_amdgcn_s_barrier()
; #define PG8_SCHED __builtin_amdgcn_sched_barrier(0)
; template <class Epi, class Sched>
; __device__ __forceinline__ void gemm_phase(LAS unsigned char* lds, const Gemm g, const Sched& S, const Epi& E) {
;     ...
;             PG8_BAR; PG8_WAIT_L(0); PG8_MMA(0, 1, At, B1); PG8_BAR;
;             PG8_LDA(At, 0, 1); PG8_STAGE(PG8_SA(0, 0), a2, voffA);
;             PG8_BAR; PG8_WAIT_L(0); PG8_MMA(1, 0, At, B0); PG8_BAR; PG8_SCHED;
;             PG8_STAGE(PG8_SB(0, 1), b2 + hstep, voffB);
;             PG8_WAIT_V(6); PG8_BAR; PG8_MMA(1, 1, At, B1); PG8_BAR;
;             PG8_LDB(B0, 1, 0); PG8_SCHED; PG8_LDA(At, 1, 0); PG8_STAGE(PG8_SA(0, 1), a2 + hstep, voffA);
;             PG8_WAIT_L(8); PG8_BAR; PG8_WAIT_L(0); PG8_MMA(0, 0, At, B0); PG8_BAR; PG8_SCHED;
	s_waitcnt lgkmcnt(0)
	s_waitcnt lgkmcnt(0)
	v_mfma_f32_16x16x32_bf16 v[120:123], v[202:205], v[166:169], v[120:123]
	v_mfma_f32_16x16x32_bf16 v[112:115], v[210:213], v[166:169], v[112:115]
	v_mfma_f32_16x16x32_bf16 v[104:107], v[202:205], v[174:177], v[104:107]
	v_mfma_f32_16x16x32_bf16 v[96:99], v[210:213], v[174:177], v[96:99]
	v_mfma_f32_16x16x32_bf16 v[88:91], v[202:205], v[182:185], v[88:91]
	v_mfma_f32_16x16x32_bf16 v[80:83], v[210:213], v[182:185], v[80:83]
	v_mfma_f32_16x16x32_bf16 v[72:75], v[202:205], v[190:193], v[72:75]
	v_mfma_f32_16x16x32_bf16 v[64:67], v[210:213], v[190:193], v[64:67]
	v_mfma_f32_16x16x32_bf16 v[120:123], v[206:209], v[170:173], v[120:123]
	v_mfma_f32_16x16x32_bf16 v[112:115], v[214:217], v[170:173], v[112:115]
	v_mfma_f32_16x16x32_bf16 v[104:107], v[206:209], v[178:181], v[104:107]
	v_mfma_f32_16x16x32_bf16 v[96:99], v[214:217], v[178:181], v[96:99]
	v_mfma_f32_16x16x32_bf16 v[88:91], v[206:209], v[186:189], v[88:91]
	v_mfma_f32_16x16x32_bf16 v[80:83], v[214:217], v[186:189], v[80:83]
	v_mfma_f32_16x16x32_bf16 v[72:75], v[206:209], v[194:197], v[72:75]
	v_mfma_f32_16x16x32_bf16 v[64:67], v[214:217], v[194:197], v[64:67]
	s_setprio 0
	s_mov_b32 m0, s13
	s_barrier
	ds_read_b128 v[166:169], v148 offset:16384
	ds_read_b128 v[170:173], v148 offset:17408
	ds_read_b128 v[174:177], v148 offset:18432
	ds_read_b128 v[178:181], v148 offset:19456
	ds_read_b128 v[182:185], v148 offset:20480
	ds_read_b128 v[186:189], v148 offset:21504
	ds_read_b128 v[190:193], v148 offset:22528
	ds_read_b128 v[194:197], v148 offset:23552
	global_load_lds_dwordx4 v134, s[22:23]
	s_mov_b32 m0, s28
	s_nop 0
	global_load_lds_dwordx4 v130, s[22:23]
	s_setprio 1
	s_barrier
	s_waitcnt lgkmcnt(0)
	s_waitcnt lgkmcnt(0)
	v_mfma_f32_16x16x32_bf16 v[60:63], v[150:153], v[166:169], v[60:63]
	v_mfma_f32_16x16x32_bf16 v[56:59], v[158:161], v[166:169], v[56:59]
	v_mfma_f32_16x16x32_bf16 v[44:47], v[150:153], v[174:177], v[44:47]
	v_mfma_f32_16x16x32_bf16 v[40:43], v[158:161], v[174:177], v[40:43]
	v_mfma_f32_16x16x32_bf16 v[28:31], v[150:153], v[182:185], v[28:31]
	v_mfma_f32_16x16x32_bf16 v[24:27], v[158:161], v[182:185], v[24:27]
	v_mfma_f32_16x16x32_bf16 v[12:15], v[150:153], v[190:193], v[12:15]
	v_mfma_f32_16x16x32_bf16 v[8:11], v[158:161], v[190:193], v[8:11]
	v_mfma_f32_16x16x32_bf16 v[60:63], v[154:157], v[170:173], v[60:63]
	v_mfma_f32_16x16x32_bf16 v[56:59], v[162:165], v[170:173], v[56:59]
	v_mfma_f32_16x16x32_bf16 v[44:47], v[154:157], v[178:181], v[44:47]
	v_mfma_f32_16x16x32_bf16 v[40:43], v[162:165], v[178:181], v[40:43]
	v_mfma_f32_16x16x32_bf16 v[28:31], v[154:157], v[186:189], v[28:31]
	v_mfma_f32_16x16x32_bf16 v[24:27], v[162:165], v[186:189], v[24:27]
	v_mfma_f32_16x16x32_bf16 v[12:15], v[154:157], v[194:197], v[12:15]
	v_mfma_f32_16x16x32_bf16 v[8:11], v[162:165], v[194:197], v[8:11]
	s_setprio 0
	s_barrier
	s_add_u32 s16, s18, 0x40000
	s_addc_u32 s17, s19, 0
	s_add_i32 s20, s41, s25
	s_mov_b32 m0, s20
	s_nop 0
	global_load_lds_dwordx4 v132, s[16:17]
	s_add_i32 m0, s20, 0x2000
	s_nop 0
	global_load_lds_dwordx4 v128, s[16:17]
	s_add_u32 s16, s22, 0x40000
	s_addc_u32 s17, s23, 0
	s_mov_b32 m0, s29
	s_nop 0
	global_load_lds_dwordx4 v134, s[16:17]
	s_mov_b32 m0, s33
	s_nop 0
	global_load_lds_dwordx4 v130, s[16:17]
	s_waitcnt vmcnt(10)
	s_setprio 1
	s_barrier
	v_mfma_f32_16x16x32_bf16 v[52:55], v[202:205], v[166:169], v[52:55]
	v_mfma_f32_16x16x32_bf16 v[48:51], v[210:213], v[166:169], v[48:51]
	v_mfma_f32_16x16x32_bf16 v[36:39], v[202:205], v[174:177], v[36:39]
	v_mfma_f32_16x16x32_bf16 v[32:35], v[210:213], v[174:177], v[32:35]
	v_mfma_f32_16x16x32_bf16 v[20:23], v[202:205], v[182:185], v[20:23]
	v_mfma_f32_16x16x32_bf16 v[16:19], v[210:213], v[182:185], v[16:19]
	v_mfma_f32_16x16x32_bf16 v[4:7], v[202:205], v[190:193], v[4:7]
	v_mfma_f32_16x16x32_bf16 v[0:3], v[210:213], v[190:193], v[0:3]
	v_mfma_f32_16x16x32_bf16 v[52:55], v[206:209], v[170:173], v[52:55]
	v_mfma_f32_16x16x32_bf16 v[48:51], v[214:217], v[170:173], v[48:51]
	v_mfma_f32_16x16x32_bf16 v[36:39], v[206:209], v[178:181], v[36:39]
	v_mfma_f32_16x16x32_bf16 v[32:35], v[214:217], v[178:181], v[32:35]
	v_mfma_f32_16x16x32_bf16 v[20:23], v[206:209], v[186:189], v[20:23]
	v_mfma_f32_16x16x32_bf16 v[16:19], v[214:217], v[186:189], v[16:19]
	v_mfma_f32_16x16x32_bf16 v[4:7], v[206:209], v[194:197], v[4:7]
	v_mfma_f32_16x16x32_bf16 v[0:3], v[214:217], v[194:197], v[0:3]
	s_setprio 0
	s_add_i32 s20, 0, 0x18000
	v_add_u32_e32 v162, s20, v146
	s_barrier
	ds_read_b128 v[150:153], v162
	ds_read_b128 v[154:157], v162 offset:1024
	ds_read_b128 v[158:161], v162 offset:2048
	ds_read_b128 v[162:165], v162 offset:3072
	ds_read_b128 v[166:169], v148 offset:32768
	ds_read_b128 v[170:173], v148 offset:33792
	ds_read_b128 v[174:177], v148 offset:34816
	ds_read_b128 v[178:181], v148 offset:35840
	ds_read_b128 v[182:185], v148 offset:36864
	ds_read_b128 v[186:189], v148 offset:37888
	ds_read_b128 v[190:193], v148 offset:38912
	ds_read_b128 v[194:197], v148 offset:39936
	s_waitcnt lgkmcnt(8)
	s_waitcnt vmcnt(8)
	s_setprio 1
	s_barrier
; #define PG8_STAGE(bufoff, gbase, voff) do { _Pragma("unroll") for (int _i = 0; _i < 2; ++_i) \
;         __builtin_amdgcn_global_load_lds((const unsigned*)((const char*)(gbase) + (voff)[_i]), (LAS unsigned*)(lds + (bufoff) + ldsw + _i * 8192), 16, 0, 0); } while (0)
; #define PG8_LDA(dst, b, h) do { _Pragma("unroll") for (int m = 0; m < 4; ++m) _Pragma("unroll") for (int k = 0; k < 2; ++k) dst[m][k] = *(const LAS bf16x8*)(lds + PG8_SA(b, h) + aoff + m * 2048 + k * 1024); } while (0)
; #define PG8_LDB(dst, b, h) do { _Pragma("unroll") for (int n = 0; n < 2; ++n) _Pragma("unroll") for (int k = 0; k < 2; ++k) dst[n][k] = *(const LAS bf16x8*)(lds + PG8_SB(b, h) + boff + n * 2048 + k * 1024); } while (0)
; #define PG8_MMA(ai, bj, At, Bt) do { __builtin_amdgcn_s_setprio(1); _Pragma("unroll") for (int m = 0; m < 4; ++m) _Pragma("unroll") for (int n = 0; n < 2; ++n) _Pragma("unroll") for (int k = 0; k < 2; ++k) \
;         acc[ai][bj][m][n] = __builtin_amdgcn_mfma_f32_16x16x32_bf16(Bt[n][k], At[m][k], acc[ai][bj][m][n], 0, 0, 0); __builtin_amdgcn_s_setprio(0); } while (0)
; #define PG8_WAIT_V(n) asm volatile("s_waitcnt vmcnt(" #n ")" ::: "memory")
; #define PG8_WAIT_L(n) asm volatile("s_waitcnt lgkmcnt(" #n ")" ::: "memory")
; #define PG8_BAR __builtin_amdgcn_s_barrier()
; #define PG8_SCHED __builtin_amdgcn_sched_barrier(0)
; template <class Epi, class Sched>
; __device__ __forceinline__ void gemm_phase(LAS unsigned char* lds, const Gemm g, const Sched& S, const Epi& E) {
;     ...
;             PG8_WAIT_L(8); PG8_BAR; PG8_WAIT_L(0); PG8_MMA(0, 0, At, B0); PG8_BAR; PG8_SCHED;
;             PG8_LDB(B1, 1, 1); PG8_STAGE(PG8_SB(1, 0), b3, voffB);
;             PG8_BAR; PG8_WAIT_L(0); PG8_MMA(0, 1, At, B1); PG8_BAR;
;             PG8_LDA(At, 1, 1); PG8_STAGE(PG8_SA(1, 0), a3, voffA);
;             PG8_BAR; PG8_WAIT_L(0); PG8_MMA(1, 0, At, B0); PG8_BAR; PG8_SCHED;
;             PG8_STAGE(PG8_SB(1, 1), b3 + hstep, voffB);
;             PG8_WAIT_V(6); PG8_BAR; PG8_MMA(1, 1, At, B1); PG8_BAR;
	s_waitcnt lgkmcnt(0)
	s_waitcnt lgkmcnt(0)
	v_mfma_f32_16x16x32_bf16 v[124:127], v[150:153], v[166:169], v[124:127]
	v_mfma_f32_16x16x32_bf16 v[116:119], v[158:161], v[166:169], v[116:119]
	v_mfma_f32_16x16x32_bf16 v[108:111], v[150:153], v[174:177], v[108:111]
	v_mfma_f32_16x16x32_bf16 v[100:103], v[158:161], v[174:177], v[100:103]
	v_mfma_f32_16x16x32_bf16 v[92:95], v[150:153], v[182:185], v[92:95]
	v_mfma_f32_16x16x32_bf16 v[84:87], v[158:161], v[182:185], v[84:87]
	v_mfma_f32_16x16x32_bf16 v[76:79], v[150:153], v[190:193], v[76:79]
	v_mfma_f32_16x16x32_bf16 v[68:71], v[158:161], v[190:193], v[68:71]
	v_mfma_f32_16x16x32_bf16 v[124:127], v[154:157], v[170:173], v[124:127]
	v_mfma_f32_16x16x32_bf16 v[116:119], v[162:165], v[170:173], v[116:119]
	v_mfma_f32_16x16x32_bf16 v[108:111], v[154:157], v[178:181], v[108:111]
	v_mfma_f32_16x16x32_bf16 v[100:103], v[162:165], v[178:181], v[100:103]
	v_mfma_f32_16x16x32_bf16 v[92:95], v[154:157], v[186:189], v[92:95]
	v_mfma_f32_16x16x32_bf16 v[84:87], v[162:165], v[186:189], v[84:87]
	v_mfma_f32_16x16x32_bf16 v[76:79], v[154:157], v[194:197], v[76:79]
	v_mfma_f32_16x16x32_bf16 v[68:71], v[162:165], v[194:197], v[68:71]
	s_setprio 0
	s_barrier
	s_add_i32 s21, 0, 0x1c000
	s_add_i32 s16, s20, s25
	v_add_u32_e32 v214, s21, v146
	s_add_u32 s0, s18, 0x80
	s_addc_u32 s1, s19, 0
	s_mov_b32 m0, s16
	ds_read_b128 v[202:205], v214
	ds_read_b128 v[206:209], v214 offset:1024
	ds_read_b128 v[210:213], v214 offset:2048
	ds_read_b128 v[214:217], v214 offset:3072
	global_load_lds_dwordx4 v132, s[0:1]
	s_add_i32 m0, s16, 0x2000
	s_nop 0
	global_load_lds_dwordx4 v128, s[0:1]
	s_waitcnt vmcnt(8)
	s_setprio 1
	s_barrier
	s_waitcnt lgkmcnt(0)
	s_waitcnt lgkmcnt(0)
	v_mfma_f32_16x16x32_bf16 v[120:123], v[202:205], v[166:169], v[120:123]
	v_mfma_f32_16x16x32_bf16 v[112:115], v[210:213], v[166:169], v[112:115]
	v_mfma_f32_16x16x32_bf16 v[104:107], v[202:205], v[174:177], v[104:107]
	v_mfma_f32_16x16x32_bf16 v[96:99], v[210:213], v[174:177], v[96:99]
	v_mfma_f32_16x16x32_bf16 v[88:91], v[202:205], v[182:185], v[88:91]
	v_mfma_f32_16x16x32_bf16 v[80:83], v[210:213], v[182:185], v[80:83]
	v_mfma_f32_16x16x32_bf16 v[72:75], v[202:205], v[190:193], v[72:75]
	v_mfma_f32_16x16x32_bf16 v[64:67], v[210:213], v[190:193], v[64:67]
	v_mfma_f32_16x16x32_bf16 v[120:123], v[206:209], v[170:173], v[120:123]
	v_mfma_f32_16x16x32_bf16 v[112:115], v[214:217], v[170:173], v[112:115]
	v_mfma_f32_16x16x32_bf16 v[104:107], v[206:209], v[178:181], v[104:107]
	v_mfma_f32_16x16x32_bf16 v[96:99], v[214:217], v[178:181], v[96:99]
	v_mfma_f32_16x16x32_bf16 v[88:91], v[206:209], v[186:189], v[88:91]
	v_mfma_f32_16x16x32_bf16 v[80:83], v[214:217], v[186:189], v[80:83]
	v_mfma_f32_16x16x32_bf16 v[72:75], v[206:209], v[194:197], v[72:75]
	v_mfma_f32_16x16x32_bf16 v[64:67], v[214:217], v[194:197], v[64:67]
	s_setprio 0
	s_mov_b32 m0, s36
	s_add_u32 s0, s22, 0x80
	s_addc_u32 s1, s23, 0
	s_barrier
	ds_read_b128 v[166:169], v148 offset:49152
	ds_read_b128 v[170:173], v148 offset:50176
	ds_read_b128 v[174:177], v148 offset:51200
	ds_read_b128 v[178:181], v148 offset:52224
	ds_read_b128 v[182:185], v148 offset:53248
	ds_read_b128 v[186:189], v148 offset:54272
	ds_read_b128 v[190:193], v148 offset:55296
	ds_read_b128 v[194:197], v148 offset:56320
	global_load_lds_dwordx4 v134, s[0:1]
	s_mov_b32 m0, s37
	s_nop 0
	global_load_lds_dwordx4 v130, s[0:1]
	s_setprio 1
	s_barrier
	s_waitcnt lgkmcnt(0)
	s_waitcnt lgkmcnt(0)
	v_mfma_f32_16x16x32_bf16 v[60:63], v[150:153], v[166:169], v[60:63]
	v_mfma_f32_16x16x32_bf16 v[56:59], v[158:161], v[166:169], v[56:59]
	v_mfma_f32_16x16x32_bf16 v[44:47], v[150:153], v[174:177], v[44:47]
	v_mfma_f32_16x16x32_bf16 v[40:43], v[158:161], v[174:177], v[40:43]
	v_mfma_f32_16x16x32_bf16 v[28:31], v[150:153], v[182:185], v[28:31]
	v_mfma_f32_16x16x32_bf16 v[24:27], v[158:161], v[182:185], v[24:27]
	v_mfma_f32_16x16x32_bf16 v[12:15], v[150:153], v[190:193], v[12:15]
	v_mfma_f32_16x16x32_bf16 v[8:11], v[158:161], v[190:193], v[8:11]
	v_mfma_f32_16x16x32_bf16 v[60:63], v[154:157], v[170:173], v[60:63]
	v_mfma_f32_16x16x32_bf16 v[56:59], v[162:165], v[170:173], v[56:59]
	v_mfma_f32_16x16x32_bf16 v[44:47], v[154:157], v[178:181], v[44:47]
	v_mfma_f32_16x16x32_bf16 v[40:43], v[162:165], v[178:181], v[40:43]
	v_mfma_f32_16x16x32_bf16 v[28:31], v[154:157], v[186:189], v[28:31]
	v_mfma_f32_16x16x32_bf16 v[24:27], v[162:165], v[186:189], v[24:27]
	v_mfma_f32_16x16x32_bf16 v[12:15], v[154:157], v[194:197], v[12:15]
	v_mfma_f32_16x16x32_bf16 v[8:11], v[162:165], v[194:197], v[8:11]
	s_setprio 0
	s_barrier
	s_add_u32 s16, s18, 0x40080
	s_addc_u32 s17, s19, 0
	s_add_i32 s18, s21, s25
	s_mov_b32 m0, s18
	s_nop 0
	global_load_lds_dwordx4 v132, s[16:17]
	s_add_i32 m0, s18, 0x2000
	s_nop 0
	global_load_lds_dwordx4 v128, s[16:17]
	s_waitcnt vmcnt(8)
	s_setprio 1
	s_barrier
	v_mfma_f32_16x16x32_bf16 v[52:55], v[202:205], v[166:169], v[52:55]
	v_mfma_f32_16x16x32_bf16 v[48:51], v[210:213], v[166:169], v[48:51]
	v_mfma_f32_16x16x32_bf16 v[36:39], v[202:205], v[174:177], v[36:39]
	v_mfma_f32_16x16x32_bf16 v[32:35], v[210:213], v[174:177], v[32:35]
	v_mfma_f32_16x16x32_bf16 v[20:23], v[202:205], v[182:185], v[20:23]
	v_mfma_f32_16x16x32_bf16 v[16:19], v[210:213], v[182:185], v[16:19]
	v_mfma_f32_16x16x32_bf16 v[4:7], v[202:205], v[190:193], v[4:7]
	v_mfma_f32_16x16x32_bf16 v[0:3], v[210:213], v[190:193], v[0:3]
	v_mfma_f32_16x16x32_bf16 v[52:55], v[206:209], v[170:173], v[52:55]
	v_mfma_f32_16x16x32_bf16 v[48:51], v[214:217], v[170:173], v[48:51]
	v_mfma_f32_16x16x32_bf16 v[36:39], v[206:209], v[178:181], v[36:39]
	v_mfma_f32_16x16x32_bf16 v[32:35], v[214:217], v[178:181], v[32:35]
	v_mfma_f32_16x16x32_bf16 v[20:23], v[206:209], v[186:189], v[20:23]
	v_mfma_f32_16x16x32_bf16 v[16:19], v[214:217], v[186:189], v[16:19]
	v_mfma_f32_16x16x32_bf16 v[4:7], v[206:209], v[194:197], v[4:7]
	v_mfma_f32_16x16x32_bf16 v[0:3], v[214:217], v[194:197], v[0:3]
	s_setprio 0
	s_add_i32 s48, s48, 2
	s_add_u32 s14, s14, 0x100
	s_addc_u32 s15, s15, 0
	s_add_u32 s46, s46, 0x100
	s_addc_u32 s47, s47, 0
	s_cmp_gt_u32 s48, 13
	s_cbranch_scc1 .Lconc_last_g0
	s_barrier
	s_branch .LBB0_235

; #define PG8_STAGE(bufoff, gbase, voff) do { _Pragma("unroll") for (int _i = 0; _i < 2; ++_i) \
;         __builtin_amdgcn_global_load_lds((const unsigned*)((const char*)(gbase) + (voff)[_i]), (LAS unsigned*)(lds + (bufoff) + ldsw + _i * 8192), 16, 0, 0); } while (0)
; #define PG8_LDA(dst, b, h) do { _Pragma("unroll") for (int m = 0; m < 4; ++m) _Pragma("unroll") for (int k = 0; k < 2; ++k) dst[m][k] = *(const LAS bf16x8*)(lds + PG8_SA(b, h) + aoff + m * 2048 + k * 1024); } while (0)
; #define PG8_LDB(dst, b, h) do { _Pragma("unroll") for (int n = 0; n < 2; ++n) _Pragma("unroll") for (int k = 0; k < 2; ++k) dst[n][k] = *(const LAS bf16x8*)(lds + PG8_SB(b, h) + boff + n * 2048 + k * 1024); } while (0)
; #define PG8_WAIT_V(n) asm volatile("s_waitcnt vmcnt(" #n ")" ::: "memory")
; #define PG8_WAIT_L(n) asm volatile("s_waitcnt lgkmcnt(" #n ")" ::: "memory")
; #define PG8_BAR __builtin_amdgcn_s_barrier()
; #define PG8_SCHED __builtin_amdgcn_sched_barrier(0)
; template <class Epi, class Sched>
; __device__ __forceinline__ void gemm_phase(LAS unsigned char* lds, const Gemm g, const Sched& S, const Epi& E) {
;     ...
;         const bool has_next = S.next(ui + 1, nxt);
;         const char* nA = has_next ? (const char*)g.A + (size_t)nxt.pm * tstep : cA; const char* nB = has_next ? (const char*)g.Bt + (size_t)nxt.pn * tstep : cB;
;         for (int t = 0; t < nt; t += 2) {
;             const bool last = (t == nt - 2);
;             const char* a1 = cA + (size_t)(t + 1) * kstep;
;             const char* a2 = last ? nA : cA + (size_t)(t + 2) * kstep; const char* b2 = last ? nB : cB + (size_t)(t + 2) * kstep;
;             const char* a3 = a2 + kstep; const char* b3 = b2 + kstep;
;             PG8_LDB(B0, 0, 0); PG8_SCHED; PG8_LDA(At, 0, 0); PG8_STAGE(PG8_SA(1, 1), a1 + hstep, voffA);
;             PG8_WAIT_L(8); PG8_BAR; PG8_WAIT_L(0); PG8_MMA(0, 0, At, B0); PG8_BAR; PG8_SCHED;
;             PG8_LDB(B1, 0, 1); PG8_STAGE(PG8_SB(0, 0), b2, voffB);
;             PG8_BAR; PG8_WAIT_L(0); PG8_MMA(0, 1, At, B1); PG8_BAR;
;             PG8_LDA(At, 0, 1); PG8_STAGE(PG8_SA(0, 0), a2, voffA);
;             PG8_BAR; PG8_WAIT_L(0); PG8_MMA(1, 0, At, B0); PG8_BAR; PG8_SCHED;
;             PG8_STAGE(PG8_SB(0, 1), b2 + hstep, voffB);
;             PG8_WAIT_V(6); PG8_BAR; PG8_MMA(1, 1, At, B1); PG8_BAR;
.LBB0_304:
	s_add_u32 s0, s28, 0x100
	s_addc_u32 s67, s29, 0
	s_mov_b32 s68, -2
	ds_read_b128 v[144:147], v165
	ds_read_b128 v[148:151], v165 offset:1024
	ds_read_b128 v[152:155], v165 offset:2048
	ds_read_b128 v[156:159], v165 offset:3072
	s_add_u32 s28, s26, 0x100
	s_addc_u32 s29, s27, 0
	s_cmp_eq_u32 s68, 40
	s_cselect_b32 s37, s5, s29
	s_cselect_b32 s36, s4, s28
	s_cselect_b32 s35, s7, s67
	s_cselect_b32 s34, s6, s0
	v_lshl_add_u64 v[160:161], s[26:27], 0, v[136:137]
	s_add_i32 m0, s42, 0xc000
	ds_read_b128 v[168:171], v166
	ds_read_b128 v[172:175], v166 offset:1024
	ds_read_b128 v[176:179], v166 offset:2048
	ds_read_b128 v[180:183], v166 offset:3072
	ds_read_b128 v[184:187], v166 offset:4096
	ds_read_b128 v[188:191], v166 offset:5120
	ds_read_b128 v[192:195], v166 offset:6144
	ds_read_b128 v[196:199], v166 offset:7168
	global_load_lds_dwordx4 v[160:161], off
	v_lshl_add_u64 v[160:161], s[26:27], 0, v[138:139]
	s_add_i32 m0, s42, 0xe000
	s_nop 0
	global_load_lds_dwordx4 v[160:161], off
	s_waitcnt lgkmcnt(8)
	s_waitcnt vmcnt(8)
	s_setprio 1
	s_barrier
	s_waitcnt lgkmcnt(0)
	s_waitcnt lgkmcnt(0)
	v_mfma_f32_16x16x32_bf16 v[124:127], v[144:147], v[168:171], 0
	v_mfma_f32_16x16x32_bf16 v[120:123], v[152:155], v[168:171], 0
	v_mfma_f32_16x16x32_bf16 v[116:119], v[144:147], v[176:179], 0
	v_mfma_f32_16x16x32_bf16 v[104:107], v[152:155], v[176:179], 0
	v_mfma_f32_16x16x32_bf16 v[96:99], v[144:147], v[184:187], 0
	v_mfma_f32_16x16x32_bf16 v[88:91], v[152:155], v[184:187], 0
	v_mfma_f32_16x16x32_bf16 v[80:83], v[144:147], v[192:195], 0
	v_mfma_f32_16x16x32_bf16 v[72:75], v[152:155], v[192:195], 0
	v_mfma_f32_16x16x32_bf16 v[124:127], v[148:151], v[172:175], v[124:127]
	v_mfma_f32_16x16x32_bf16 v[120:123], v[156:159], v[172:175], v[120:123]
	v_mfma_f32_16x16x32_bf16 v[116:119], v[148:151], v[180:183], v[116:119]
	v_mfma_f32_16x16x32_bf16 v[104:107], v[156:159], v[180:183], v[104:107]
	v_mfma_f32_16x16x32_bf16 v[96:99], v[148:151], v[188:191], v[96:99]
	v_mfma_f32_16x16x32_bf16 v[88:91], v[156:159], v[188:191], v[88:91]
	v_mfma_f32_16x16x32_bf16 v[80:83], v[148:151], v[196:199], v[80:83]
	v_mfma_f32_16x16x32_bf16 v[72:75], v[156:159], v[196:199], v[72:75]
	s_setprio 0
	s_barrier
	s_add_i32 s16, s58, s40
	s_mov_b32 m0, s16
	ds_read_b128 v[202:205], v167
	ds_read_b128 v[206:209], v167 offset:1024
	ds_read_b128 v[210:213], v167 offset:2048
	ds_read_b128 v[214:217], v167 offset:3072
	global_load_lds_dwordx4 v132, s[34:35]
	s_add_i32 m0, s16, 0x2000
	s_nop 0
	global_load_lds_dwordx4 v128, s[34:35]
	s_waitcnt vmcnt(8)
	s_setprio 1
	s_barrier
	s_waitcnt lgkmcnt(0)
	s_waitcnt lgkmcnt(0)
	v_mfma_f32_16x16x32_bf16 v[112:115], v[202:205], v[168:171], 0
	v_mfma_f32_16x16x32_bf16 v[108:111], v[210:213], v[168:171], 0
	v_mfma_f32_16x16x32_bf16 v[100:103], v[202:205], v[176:179], 0
	v_mfma_f32_16x16x32_bf16 v[92:95], v[210:213], v[176:179], 0
	v_mfma_f32_16x16x32_bf16 v[84:87], v[202:205], v[184:187], 0
	v_mfma_f32_16x16x32_bf16 v[76:79], v[210:213], v[184:187], 0
	v_mfma_f32_16x16x32_bf16 v[68:71], v[202:205], v[192:195], 0
	v_mfma_f32_16x16x32_bf16 v[64:67], v[210:213], v[192:195], 0
	v_mfma_f32_16x16x32_bf16 v[112:115], v[206:209], v[172:175], v[112:115]
	v_mfma_f32_16x16x32_bf16 v[108:111], v[214:217], v[172:175], v[108:111]
	v_mfma_f32_16x16x32_bf16 v[100:103], v[206:209], v[180:183], v[100:103]
	v_mfma_f32_16x16x32_bf16 v[92:95], v[214:217], v[180:183], v[92:95]
	v_mfma_f32_16x16x32_bf16 v[84:87], v[206:209], v[188:191], v[84:87]
	v_mfma_f32_16x16x32_bf16 v[76:79], v[214:217], v[188:191], v[76:79]
	v_mfma_f32_16x16x32_bf16 v[68:71], v[206:209], v[196:199], v[68:71]
	v_mfma_f32_16x16x32_bf16 v[64:67], v[214:217], v[196:199], v[64:67]
	s_setprio 0
	s_mov_b32 m0, s42
	s_barrier
	ds_read_b128 v[168:171], v166 offset:16384
	ds_read_b128 v[172:175], v166 offset:17408
	ds_read_b128 v[176:179], v166 offset:18432
	ds_read_b128 v[180:183], v166 offset:19456
	ds_read_b128 v[184:187], v166 offset:20480
	ds_read_b128 v[188:191], v166 offset:21504
	ds_read_b128 v[192:195], v166 offset:22528
	ds_read_b128 v[196:199], v166 offset:23552
	global_load_lds_dwordx4 v134, s[36:37]
	s_mov_b32 m0, s43
	s_nop 0
	global_load_lds_dwordx4 v130, s[36:37]
	s_setprio 1
	s_barrier
	s_waitcnt lgkmcnt(0)
	s_waitcnt lgkmcnt(0)
	v_mfma_f32_16x16x32_bf16 v[60:63], v[144:147], v[168:171], 0
	v_mfma_f32_16x16x32_bf16 v[56:59], v[152:155], v[168:171], 0
	v_mfma_f32_16x16x32_bf16 v[48:51], v[144:147], v[176:179], 0
	v_mfma_f32_16x16x32_bf16 v[40:43], v[152:155], v[176:179], 0
	v_mfma_f32_16x16x32_bf16 v[32:35], v[144:147], v[184:187], 0
	v_mfma_f32_16x16x32_bf16 v[24:27], v[152:155], v[184:187], 0
	v_mfma_f32_16x16x32_bf16 v[16:19], v[144:147], v[192:195], 0
	v_mfma_f32_16x16x32_bf16 v[8:11], v[152:155], v[192:195], 0
	v_mfma_f32_16x16x32_bf16 v[60:63], v[148:151], v[172:175], v[60:63]
	v_mfma_f32_16x16x32_bf16 v[56:59], v[156:159], v[172:175], v[56:59]
	v_mfma_f32_16x16x32_bf16 v[48:51], v[148:151], v[180:183], v[48:51]
	v_mfma_f32_16x16x32_bf16 v[40:43], v[156:159], v[180:183], v[40:43]
	v_mfma_f32_16x16x32_bf16 v[32:35], v[148:151], v[188:191], v[32:35]
	v_mfma_f32_16x16x32_bf16 v[24:27], v[156:159], v[188:191], v[24:27]
	v_mfma_f32_16x16x32_bf16 v[16:19], v[148:151], v[196:199], v[16:19]
	v_mfma_f32_16x16x32_bf16 v[8:11], v[156:159], v[196:199], v[8:11]
	s_setprio 0
	s_barrier
	s_add_u32 s16, s34, 0xb0000
	s_addc_u32 s17, s35, 0
	s_add_i32 s20, s59, s40
	s_mov_b32 m0, s20
	s_nop 0
	global_load_lds_dwordx4 v132, s[16:17]
	s_add_i32 m0, s20, 0x2000
	s_nop 0
	global_load_lds_dwordx4 v128, s[16:17]
	s_add_u32 s16, s36, 0xb0000
	s_addc_u32 s17, s37, 0
	s_mov_b32 m0, s44
	s_nop 0
	global_load_lds_dwordx4 v134, s[16:17]
	s_mov_b32 m0, s45
	s_nop 0
	global_load_lds_dwordx4 v130, s[16:17]
	s_waitcnt vmcnt(10)
	s_setprio 1
	s_barrier
; #define PG8_STAGE(bufoff, gbase, voff) do { _Pragma("unroll") for (int _i = 0; _i < 2; ++_i) \
;         __builtin_amdgcn_global_load_lds((const unsigned*)((const char*)(gbase) + (voff)[_i]), (LAS unsigned*)(lds + (bufoff) + ldsw + _i * 8192), 16, 0, 0); } while (0)
; #define PG8_LDA(dst, b, h) do { _Pragma("unroll") for (int m = 0; m < 4; ++m) _Pragma("unroll") for (int k = 0; k < 2; ++k) dst[m][k] = *(const LAS bf16x8*)(lds + PG8_SA(b, h) + aoff + m * 2048 + k * 1024); } while (0)
; #define PG8_LDB(dst, b, h) do { _Pragma("unroll") for (int n = 0; n < 2; ++n) _Pragma("unroll") for (int k = 0; k < 2; ++k) dst[n][k] = *(const LAS bf16x8*)(lds + PG8_SB(b, h) + boff + n * 2048 + k * 1024); } while (0)
; #define PG8_MMA(ai, bj, At, Bt) do { __builtin_amdgcn_s_setprio(1); _Pragma("unroll") for (int m = 0; m < 4; ++m) _Pragma("unroll") for (int n = 0; n < 2; ++n) _Pragma("unroll") for (int k = 0; k < 2; ++k) \
;         acc[ai][bj][m][n] = __builtin_amdgcn_mfma_f32_16x16x32_bf16(Bt[n][k], At[m][k], acc[ai][bj][m][n], 0, 0, 0); __builtin_amdgcn_s_setprio(0); } while (0)
; #define PG8_WAIT_V(n) asm volatile("s_waitcnt vmcnt(" #n ")" ::: "memory")
; #define PG8_WAIT_L(n) asm volatile("s_waitcnt lgkmcnt(" #n ")" ::: "memory")
; #define PG8_BAR __builtin_amdgcn_s_barrier()
; #define PG8_SCHED __builtin_amdgcn_sched_barrier(0)
; template <class Epi, class Sched>
; __device__ __forceinline__ void gemm_phase(LAS unsigned char* lds, const Gemm g, const Sched& S, const Epi& E) {
;     ...
;             PG8_WAIT_V(6); PG8_BAR; PG8_MMA(1, 1, At, B1); PG8_BAR;
;             PG8_LDB(B0, 1, 0); PG8_SCHED; PG8_LDA(At, 1, 0); PG8_STAGE(PG8_SA(0, 1), a2 + hstep, voffA);
;             PG8_WAIT_L(8); PG8_BAR; PG8_WAIT_L(0); PG8_MMA(0, 0, At, B0); PG8_BAR; PG8_SCHED;
;             PG8_LDB(B1, 1, 1); PG8_STAGE(PG8_SB(1, 0), b3, voffB);
;             PG8_BAR; PG8_WAIT_L(0); PG8_MMA(0, 1, At, B1); PG8_BAR;
;             PG8_LDA(At, 1, 1); PG8_STAGE(PG8_SA(1, 0), a3, voffA);
	v_mfma_f32_16x16x32_bf16 v[52:55], v[202:205], v[168:171], 0
	v_mfma_f32_16x16x32_bf16 v[44:47], v[210:213], v[168:171], 0
	v_mfma_f32_16x16x32_bf16 v[36:39], v[202:205], v[176:179], 0
	v_mfma_f32_16x16x32_bf16 v[28:31], v[210:213], v[176:179], 0
	v_mfma_f32_16x16x32_bf16 v[20:23], v[202:205], v[184:187], 0
	v_mfma_f32_16x16x32_bf16 v[12:15], v[210:213], v[184:187], 0
	v_mfma_f32_16x16x32_bf16 v[4:7], v[202:205], v[192:195], 0
	v_mfma_f32_16x16x32_bf16 v[0:3], v[210:213], v[192:195], 0
	v_mfma_f32_16x16x32_bf16 v[52:55], v[206:209], v[172:175], v[52:55]
	v_mfma_f32_16x16x32_bf16 v[44:47], v[214:217], v[172:175], v[44:47]
	v_mfma_f32_16x16x32_bf16 v[36:39], v[206:209], v[180:183], v[36:39]
	v_mfma_f32_16x16x32_bf16 v[28:31], v[214:217], v[180:183], v[28:31]
	v_mfma_f32_16x16x32_bf16 v[20:23], v[206:209], v[188:191], v[20:23]
	v_mfma_f32_16x16x32_bf16 v[12:15], v[214:217], v[188:191], v[12:15]
	v_mfma_f32_16x16x32_bf16 v[4:7], v[206:209], v[196:199], v[4:7]
	v_mfma_f32_16x16x32_bf16 v[0:3], v[214:217], v[196:199], v[0:3]
	s_setprio 0
	s_add_i32 s20, 0, 0x18000
	v_add_u32_e32 v156, s20, v164
	s_barrier
	ds_read_b128 v[144:147], v156
	ds_read_b128 v[148:151], v156 offset:1024
	ds_read_b128 v[152:155], v156 offset:2048
	ds_read_b128 v[156:159], v156 offset:3072
	ds_read_b128 v[168:171], v166 offset:32768
	ds_read_b128 v[172:175], v166 offset:33792
	ds_read_b128 v[176:179], v166 offset:34816
	ds_read_b128 v[180:183], v166 offset:35840
	ds_read_b128 v[184:187], v166 offset:36864
	ds_read_b128 v[188:191], v166 offset:37888
	ds_read_b128 v[192:195], v166 offset:38912
	ds_read_b128 v[196:199], v166 offset:39936
	s_waitcnt lgkmcnt(8)
	s_waitcnt vmcnt(8)
	s_setprio 1
	s_barrier
	s_waitcnt lgkmcnt(0)
	s_waitcnt lgkmcnt(0)
	v_mfma_f32_16x16x32_bf16 v[124:127], v[144:147], v[168:171], v[124:127]
	v_mfma_f32_16x16x32_bf16 v[120:123], v[152:155], v[168:171], v[120:123]
	v_mfma_f32_16x16x32_bf16 v[116:119], v[144:147], v[176:179], v[116:119]
	v_mfma_f32_16x16x32_bf16 v[104:107], v[152:155], v[176:179], v[104:107]
	v_mfma_f32_16x16x32_bf16 v[96:99], v[144:147], v[184:187], v[96:99]
	v_mfma_f32_16x16x32_bf16 v[88:91], v[152:155], v[184:187], v[88:91]
	v_mfma_f32_16x16x32_bf16 v[80:83], v[144:147], v[192:195], v[80:83]
	v_mfma_f32_16x16x32_bf16 v[72:75], v[152:155], v[192:195], v[72:75]
	v_mfma_f32_16x16x32_bf16 v[124:127], v[148:151], v[172:175], v[124:127]
	v_mfma_f32_16x16x32_bf16 v[120:123], v[156:159], v[172:175], v[120:123]
	v_mfma_f32_16x16x32_bf16 v[116:119], v[148:151], v[180:183], v[116:119]
	v_mfma_f32_16x16x32_bf16 v[104:107], v[156:159], v[180:183], v[104:107]
	v_mfma_f32_16x16x32_bf16 v[96:99], v[148:151], v[188:191], v[96:99]
	v_mfma_f32_16x16x32_bf16 v[88:91], v[156:159], v[188:191], v[88:91]
	v_mfma_f32_16x16x32_bf16 v[80:83], v[148:151], v[196:199], v[80:83]
	v_mfma_f32_16x16x32_bf16 v[72:75], v[156:159], v[196:199], v[72:75]
	s_setprio 0
	s_barrier
	s_add_i32 s21, 0, 0x1c000
	s_add_i32 s16, s20, s40
	v_add_u32_e32 v214, s21, v164
	s_add_u32 s8, s34, 0x80
	s_addc_u32 s9, s35, 0
	s_mov_b32 m0, s16
	ds_read_b128 v[202:205], v214
	ds_read_b128 v[206:209], v214 offset:1024
	ds_read_b128 v[210:213], v214 offset:2048
	ds_read_b128 v[214:217], v214 offset:3072
	global_load_lds_dwordx4 v132, s[8:9]
	s_add_i32 m0, s16, 0x2000
	s_nop 0
	global_load_lds_dwordx4 v128, s[8:9]
	s_waitcnt vmcnt(8)
	s_setprio 1
	s_barrier
	s_waitcnt lgkmcnt(0)
	s_waitcnt lgkmcnt(0)
	v_mfma_f32_16x16x32_bf16 v[112:115], v[202:205], v[168:171], v[112:115]
	v_mfma_f32_16x16x32_bf16 v[108:111], v[210:213], v[168:171], v[108:111]
	v_mfma_f32_16x16x32_bf16 v[100:103], v[202:205], v[176:179], v[100:103]
	v_mfma_f32_16x16x32_bf16 v[92:95], v[210:213], v[176:179], v[92:95]
	v_mfma_f32_16x16x32_bf16 v[84:87], v[202:205], v[184:187], v[84:87]
	v_mfma_f32_16x16x32_bf16 v[76:79], v[210:213], v[184:187], v[76:79]
	v_mfma_f32_16x16x32_bf16 v[68:71], v[202:205], v[192:195], v[68:71]
	v_mfma_f32_16x16x32_bf16 v[64:67], v[210:213], v[192:195], v[64:67]
	v_mfma_f32_16x16x32_bf16 v[112:115], v[206:209], v[172:175], v[112:115]
	v_mfma_f32_16x16x32_bf16 v[108:111], v[214:217], v[172:175], v[108:111]
	v_mfma_f32_16x16x32_bf16 v[100:103], v[206:209], v[180:183], v[100:103]
	v_mfma_f32_16x16x32_bf16 v[92:95], v[214:217], v[180:183], v[92:95]
	v_mfma_f32_16x16x32_bf16 v[84:87], v[206:209], v[188:191], v[84:87]
	v_mfma_f32_16x16x32_bf16 v[76:79], v[214:217], v[188:191], v[76:79]
	v_mfma_f32_16x16x32_bf16 v[68:71], v[206:209], v[196:199], v[68:71]
	v_mfma_f32_16x16x32_bf16 v[64:67], v[214:217], v[196:199], v[64:67]
	s_setprio 0
	s_mov_b32 m0, s52
	s_add_u32 s8, s36, 0x80
	s_addc_u32 s9, s37, 0
	s_barrier
	ds_read_b128 v[168:171], v166 offset:49152
	ds_read_b128 v[172:175], v166 offset:50176
	ds_read_b128 v[176:179], v166 offset:51200
	ds_read_b128 v[180:183], v166 offset:52224
	ds_read_b128 v[184:187], v166 offset:53248
	ds_read_b128 v[188:191], v166 offset:54272
	ds_read_b128 v[192:195], v166 offset:55296
	ds_read_b128 v[196:199], v166 offset:56320
	global_load_lds_dwordx4 v134, s[8:9]
	s_mov_b32 m0, s53
	s_nop 0
	global_load_lds_dwordx4 v130, s[8:9]
	s_setprio 1
	s_barrier
; #define PG8_STAGE(bufoff, gbase, voff) do { _Pragma("unroll") for (int _i = 0; _i < 2; ++_i) \
;         __builtin_amdgcn_global_load_lds((const unsigned*)((const char*)(gbase) + (voff)[_i]), (LAS unsigned*)(lds + (bufoff) + ldsw + _i * 8192), 16, 0, 0); } while (0)
; #define PG8_LDA(dst, b, h) do { _Pragma("unroll") for (int m = 0; m < 4; ++m) _Pragma("unroll") for (int k = 0; k < 2; ++k) dst[m][k] = *(const LAS bf16x8*)(lds + PG8_SA(b, h) + aoff + m * 2048 + k * 1024); } while (0)
; #define PG8_LDB(dst, b, h) do { _Pragma("unroll") for (int n = 0; n < 2; ++n) _Pragma("unroll") for (int k = 0; k < 2; ++k) dst[n][k] = *(const LAS bf16x8*)(lds + PG8_SB(b, h) + boff + n * 2048 + k * 1024); } while (0)
; #define PG8_MMA(ai, bj, At, Bt) do { __builtin_amdgcn_s_setprio(1); _Pragma("unroll") for (int m = 0; m < 4; ++m) _Pragma("unroll") for (int n = 0; n < 2; ++n) _Pragma("unroll") for (int k = 0; k < 2; ++k) \
;         acc[ai][bj][m][n] = __builtin_amdgcn_mfma_f32_16x16x32_bf16(Bt[n][k], At[m][k], acc[ai][bj][m][n], 0, 0, 0); __builtin_amdgcn_s_setprio(0); } while (0)
; #define PG8_WAIT_V(n) asm volatile("s_waitcnt vmcnt(" #n ")" ::: "memory")
; #define PG8_WAIT_L(n) asm volatile("s_waitcnt lgkmcnt(" #n ")" ::: "memory")
; #define PG8_BAR __builtin_amdgcn_s_barrier()
; #define PG8_SCHED __builtin_amdgcn_sched_barrier(0)
; template <class Epi, class Sched>
; __device__ __forceinline__ void gemm_phase(LAS unsigned char* lds, const Gemm g, const Sched& S, const Epi& E) {
;     ...
;             PG8_LDB(B0, 0, 0); PG8_SCHED; PG8_LDA(At, 0, 0); PG8_STAGE(PG8_SA(1, 1), a1 + hstep, voffA);
;             PG8_WAIT_L(8); PG8_BAR; PG8_WAIT_L(0); PG8_MMA(0, 0, At, B0); PG8_BAR; PG8_SCHED;
;             PG8_LDB(B1, 0, 1); PG8_STAGE(PG8_SB(0, 0), b2, voffB);
;             PG8_BAR; PG8_WAIT_L(0); PG8_MMA(0, 1, At, B1); PG8_BAR;
;     ...
;             PG8_BAR; PG8_WAIT_L(0); PG8_MMA(1, 0, At, B0); PG8_BAR; PG8_SCHED;
;             PG8_STAGE(PG8_SB(1, 1), b3 + hstep, voffB);
;             PG8_WAIT_V(6); PG8_BAR; PG8_MMA(1, 1, At, B1); PG8_BAR;
	s_waitcnt lgkmcnt(0)
	s_waitcnt lgkmcnt(0)
	v_mfma_f32_16x16x32_bf16 v[60:63], v[144:147], v[168:171], v[60:63]
	v_mfma_f32_16x16x32_bf16 v[56:59], v[152:155], v[168:171], v[56:59]
	v_mfma_f32_16x16x32_bf16 v[48:51], v[144:147], v[176:179], v[48:51]
	v_mfma_f32_16x16x32_bf16 v[40:43], v[152:155], v[176:179], v[40:43]
	v_mfma_f32_16x16x32_bf16 v[32:35], v[144:147], v[184:187], v[32:35]
	v_mfma_f32_16x16x32_bf16 v[24:27], v[152:155], v[184:187], v[24:27]
	v_mfma_f32_16x16x32_bf16 v[16:19], v[144:147], v[192:195], v[16:19]
	v_mfma_f32_16x16x32_bf16 v[8:11], v[152:155], v[192:195], v[8:11]
	v_mfma_f32_16x16x32_bf16 v[60:63], v[148:151], v[172:175], v[60:63]
	v_mfma_f32_16x16x32_bf16 v[56:59], v[156:159], v[172:175], v[56:59]
	v_mfma_f32_16x16x32_bf16 v[48:51], v[148:151], v[180:183], v[48:51]
	v_mfma_f32_16x16x32_bf16 v[40:43], v[156:159], v[180:183], v[40:43]
	v_mfma_f32_16x16x32_bf16 v[32:35], v[148:151], v[188:191], v[32:35]
	v_mfma_f32_16x16x32_bf16 v[24:27], v[156:159], v[188:191], v[24:27]
	v_mfma_f32_16x16x32_bf16 v[16:19], v[148:151], v[196:199], v[16:19]
	v_mfma_f32_16x16x32_bf16 v[8:11], v[156:159], v[196:199], v[8:11]
	s_setprio 0
	s_barrier
	s_add_u32 s16, s34, 0xb0080
	s_addc_u32 s17, s35, 0
	s_add_i32 s20, s21, s40
	s_mov_b32 m0, s20
	s_nop 0
	global_load_lds_dwordx4 v132, s[16:17]
	s_add_i32 m0, s20, 0x2000
	s_nop 0
	global_load_lds_dwordx4 v128, s[16:17]
	s_waitcnt vmcnt(8)
	s_setprio 1
	s_barrier
	v_mfma_f32_16x16x32_bf16 v[52:55], v[202:205], v[168:171], v[52:55]
	v_mfma_f32_16x16x32_bf16 v[44:47], v[210:213], v[168:171], v[44:47]
	v_mfma_f32_16x16x32_bf16 v[36:39], v[202:205], v[176:179], v[36:39]
	v_mfma_f32_16x16x32_bf16 v[28:31], v[210:213], v[176:179], v[28:31]
	v_mfma_f32_16x16x32_bf16 v[20:23], v[202:205], v[184:187], v[20:23]
	v_mfma_f32_16x16x32_bf16 v[12:15], v[210:213], v[184:187], v[12:15]
	v_mfma_f32_16x16x32_bf16 v[4:7], v[202:205], v[192:195], v[4:7]
	v_mfma_f32_16x16x32_bf16 v[0:3], v[210:213], v[192:195], v[0:3]
	v_mfma_f32_16x16x32_bf16 v[52:55], v[206:209], v[172:175], v[52:55]
	v_mfma_f32_16x16x32_bf16 v[44:47], v[214:217], v[172:175], v[44:47]
	v_mfma_f32_16x16x32_bf16 v[36:39], v[206:209], v[180:183], v[36:39]
	v_mfma_f32_16x16x32_bf16 v[28:31], v[214:217], v[180:183], v[28:31]
	v_mfma_f32_16x16x32_bf16 v[20:23], v[206:209], v[188:191], v[20:23]
	v_mfma_f32_16x16x32_bf16 v[12:15], v[214:217], v[188:191], v[12:15]
	v_mfma_f32_16x16x32_bf16 v[4:7], v[206:209], v[196:199], v[4:7]
	v_mfma_f32_16x16x32_bf16 v[0:3], v[214:217], v[196:199], v[0:3]
	s_setprio 0
	s_add_i32 s68, s68, 2
	s_add_u32 s0, s0, 0x100
	s_addc_u32 s67, s67, 0
	s_cmp_gt_u32 s68, 41
	s_mov_b64 s[26:27], s[28:29]
	s_barrier
.LBB0_305:
	ds_read_b128 v[144:147], v165
	ds_read_b128 v[148:151], v165 offset:1024
	ds_read_b128 v[152:155], v165 offset:2048
	ds_read_b128 v[156:159], v165 offset:3072
	s_add_u32 s28, s26, 0x100
	s_addc_u32 s29, s27, 0
	s_cmp_eq_u32 s68, 40
	s_cselect_b32 s37, s5, s29
	s_cselect_b32 s36, s4, s28
	s_cselect_b32 s35, s7, s67
	s_cselect_b32 s34, s6, s0
	v_lshl_add_u64 v[160:161], s[26:27], 0, v[136:137]
	s_add_i32 m0, s42, 0xc000
	ds_read_b128 v[168:171], v166
	ds_read_b128 v[172:175], v166 offset:1024
	ds_read_b128 v[176:179], v166 offset:2048
	ds_read_b128 v[180:183], v166 offset:3072
	ds_read_b128 v[184:187], v166 offset:4096
	ds_read_b128 v[188:191], v166 offset:5120
	ds_read_b128 v[192:195], v166 offset:6144
	ds_read_b128 v[196:199], v166 offset:7168
	global_load_lds_dwordx4 v[160:161], off
	v_lshl_add_u64 v[160:161], s[26:27], 0, v[138:139]
	s_add_i32 m0, s42, 0xe000
	s_nop 0
	global_load_lds_dwordx4 v[160:161], off
	s_waitcnt lgkmcnt(8)
	s_waitcnt vmcnt(8)
	s_setprio 1
	s_barrier
	s_waitcnt lgkmcnt(0)
	s_waitcnt lgkmcnt(0)
	v_mfma_f32_16x16x32_bf16 v[124:127], v[144:147], v[168:171], v[124:127]
	v_mfma_f32_16x16x32_bf16 v[120:123], v[152:155], v[168:171], v[120:123]
	v_mfma_f32_16x16x32_bf16 v[116:119], v[144:147], v[176:179], v[116:119]
	v_mfma_f32_16x16x32_bf16 v[104:107], v[152:155], v[176:179], v[104:107]
	v_mfma_f32_16x16x32_bf16 v[96:99], v[144:147], v[184:187], v[96:99]
	v_mfma_f32_16x16x32_bf16 v[88:91], v[152:155], v[184:187], v[88:91]
	v_mfma_f32_16x16x32_bf16 v[80:83], v[144:147], v[192:195], v[80:83]
	v_mfma_f32_16x16x32_bf16 v[72:75], v[152:155], v[192:195], v[72:75]
	v_mfma_f32_16x16x32_bf16 v[124:127], v[148:151], v[172:175], v[124:127]
	v_mfma_f32_16x16x32_bf16 v[120:123], v[156:159], v[172:175], v[120:123]
	v_mfma_f32_16x16x32_bf16 v[116:119], v[148:151], v[180:183], v[116:119]
	v_mfma_f32_16x16x32_bf16 v[104:107], v[156:159], v[180:183], v[104:107]
	v_mfma_f32_16x16x32_bf16 v[96:99], v[148:151], v[188:191], v[96:99]
	v_mfma_f32_16x16x32_bf16 v[88:91], v[156:159], v[188:191], v[88:91]
	v_mfma_f32_16x16x32_bf16 v[80:83], v[148:151], v[196:199], v[80:83]
	v_mfma_f32_16x16x32_bf16 v[72:75], v[156:159], v[196:199], v[72:75]
	s_setprio 0
	s_barrier
	s_add_i32 s16, s58, s40
	s_mov_b32 m0, s16
	ds_read_b128 v[202:205], v167
	ds_read_b128 v[206:209], v167 offset:1024
	ds_read_b128 v[210:213], v167 offset:2048
	ds_read_b128 v[214:217], v167 offset:3072
	global_load_lds_dwordx4 v132, s[34:35]
	s_add_i32 m0, s16, 0x2000
	s_nop 0
	global_load_lds_dwordx4 v128, s[34:35]
	s_waitcnt vmcnt(8)
	s_setprio 1
	s_barrier
; #define PG8_STAGE(bufoff, gbase, voff) do { _Pragma("unroll") for (int _i = 0; _i < 2; ++_i) \
;         __builtin_amdgcn_global_load_lds((const unsigned*)((const char*)(gbase) + (voff)[_i]), (LAS unsigned*)(lds + (bufoff) + ldsw + _i * 8192), 16, 0, 0); } while (0)
; #define PG8_LDA(dst, b, h) do { _Pragma("unroll") for (int m = 0; m < 4; ++m) _Pragma("unroll") for (int k = 0; k < 2; ++k) dst[m][k] = *(const LAS bf16x8*)(lds + PG8_SA(b, h) + aoff + m * 2048 + k * 1024); } while (0)
; #define PG8_LDB(dst, b, h) do { _Pragma("unroll") for (int n = 0; n < 2; ++n) _Pragma("unroll") for (int k = 0; k < 2; ++k) dst[n][k] = *(const LAS bf16x8*)(lds + PG8_SB(b, h) + boff + n * 2048 + k * 1024); } while (0)
; #define PG8_MMA(ai, bj, At, Bt) do { __builtin_amdgcn_s_setprio(1); _Pragma("unroll") for (int m = 0; m < 4; ++m) _Pragma("unroll") for (int n = 0; n < 2; ++n) _Pragma("unroll") for (int k = 0; k < 2; ++k) \
;         acc[ai][bj][m][n] = __builtin_amdgcn_mfma_f32_16x16x32_bf16(Bt[n][k], At[m][k], acc[ai][bj][m][n], 0, 0, 0); __builtin_amdgcn_s_setprio(0); } while (0)
; #define PG8_WAIT_V(n) asm volatile("s_waitcnt vmcnt(" #n ")" ::: "memory")
; #define PG8_WAIT_L(n) asm volatile("s_waitcnt lgkmcnt(" #n ")" ::: "memory")
; #define PG8_BAR __builtin_amdgcn_s_barrier()
; #define PG8_SCHED __builtin_amdgcn_sched_barrier(0)
; template <class Epi, class Sched>
; __device__ __forceinline__ void gemm_phase(LAS unsigned char* lds, const Gemm g, const Sched& S, const Epi& E) {
;     ...
;             PG8_BAR; PG8_WAIT_L(0); PG8_MMA(0, 1, At, B1); PG8_BAR;
;             PG8_LDA(At, 0, 1); PG8_STAGE(PG8_SA(0, 0), a2, voffA);
;             PG8_BAR; PG8_WAIT_L(0); PG8_MMA(1, 0, At, B0); PG8_BAR; PG8_SCHED;
;             PG8_STAGE(PG8_SB(0, 1), b2 + hstep, voffB);
;             PG8_WAIT_V(6); PG8_BAR; PG8_MMA(1, 1, At, B1); PG8_BAR;
;             PG8_LDB(B0, 1, 0); PG8_SCHED; PG8_LDA(At, 1, 0); PG8_STAGE(PG8_SA(0, 1), a2 + hstep, voffA);
;             PG8_WAIT_L(8); PG8_BAR; PG8_WAIT_L(0); PG8_MMA(0, 0, At, B0); PG8_BAR; PG8_SCHED;
	s_waitcnt lgkmcnt(0)
	s_waitcnt lgkmcnt(0)
	v_mfma_f32_16x16x32_bf16 v[112:115], v[202:205], v[168:171], v[112:115]
	v_mfma_f32_16x16x32_bf16 v[108:111], v[210:213], v[168:171], v[108:111]
	v_mfma_f32_16x16x32_bf16 v[100:103], v[202:205], v[176:179], v[100:103]
	v_mfma_f32_16x16x32_bf16 v[92:95], v[210:213], v[176:179], v[92:95]
	v_mfma_f32_16x16x32_bf16 v[84:87], v[202:205], v[184:187], v[84:87]
	v_mfma_f32_16x16x32_bf16 v[76:79], v[210:213], v[184:187], v[76:79]
	v_mfma_f32_16x16x32_bf16 v[68:71], v[202:205], v[192:195], v[68:71]
	v_mfma_f32_16x16x32_bf16 v[64:67], v[210:213], v[192:195], v[64:67]
	v_mfma_f32_16x16x32_bf16 v[112:115], v[206:209], v[172:175], v[112:115]
	v_mfma_f32_16x16x32_bf16 v[108:111], v[214:217], v[172:175], v[108:111]
	v_mfma_f32_16x16x32_bf16 v[100:103], v[206:209], v[180:183], v[100:103]
	v_mfma_f32_16x16x32_bf16 v[92:95], v[214:217], v[180:183], v[92:95]
	v_mfma_f32_16x16x32_bf16 v[84:87], v[206:209], v[188:191], v[84:87]
	v_mfma_f32_16x16x32_bf16 v[76:79], v[214:217], v[188:191], v[76:79]
	v_mfma_f32_16x16x32_bf16 v[68:71], v[206:209], v[196:199], v[68:71]
	v_mfma_f32_16x16x32_bf16 v[64:67], v[214:217], v[196:199], v[64:67]
	s_setprio 0
	s_mov_b32 m0, s42
	s_barrier
	ds_read_b128 v[168:171], v166 offset:16384
	ds_read_b128 v[172:175], v166 offset:17408
	ds_read_b128 v[176:179], v166 offset:18432
	ds_read_b128 v[180:183], v166 offset:19456
	ds_read_b128 v[184:187], v166 offset:20480
	ds_read_b128 v[188:191], v166 offset:21504
	ds_read_b128 v[192:195], v166 offset:22528
	ds_read_b128 v[196:199], v166 offset:23552
	global_load_lds_dwordx4 v134, s[36:37]
	s_mov_b32 m0, s43
	s_nop 0
	global_load_lds_dwordx4 v130, s[36:37]
	s_setprio 1
	s_barrier
	s_waitcnt lgkmcnt(0)
	s_waitcnt lgkmcnt(0)
	v_mfma_f32_16x16x32_bf16 v[60:63], v[144:147], v[168:171], v[60:63]
	v_mfma_f32_16x16x32_bf16 v[56:59], v[152:155], v[168:171], v[56:59]
	v_mfma_f32_16x16x32_bf16 v[48:51], v[144:147], v[176:179], v[48:51]
	v_mfma_f32_16x16x32_bf16 v[40:43], v[152:155], v[176:179], v[40:43]
	v_mfma_f32_16x16x32_bf16 v[32:35], v[144:147], v[184:187], v[32:35]
	v_mfma_f32_16x16x32_bf16 v[24:27], v[152:155], v[184:187], v[24:27]
	v_mfma_f32_16x16x32_bf16 v[16:19], v[144:147], v[192:195], v[16:19]
	v_mfma_f32_16x16x32_bf16 v[8:11], v[152:155], v[192:195], v[8:11]
	v_mfma_f32_16x16x32_bf16 v[60:63], v[148:151], v[172:175], v[60:63]
	v_mfma_f32_16x16x32_bf16 v[56:59], v[156:159], v[172:175], v[56:59]
	v_mfma_f32_16x16x32_bf16 v[48:51], v[148:151], v[180:183], v[48:51]
	v_mfma_f32_16x16x32_bf16 v[40:43], v[156:159], v[180:183], v[40:43]
	v_mfma_f32_16x16x32_bf16 v[32:35], v[148:151], v[188:191], v[32:35]
	v_mfma_f32_16x16x32_bf16 v[24:27], v[156:159], v[188:191], v[24:27]
	v_mfma_f32_16x16x32_bf16 v[16:19], v[148:151], v[196:199], v[16:19]
	v_mfma_f32_16x16x32_bf16 v[8:11], v[156:159], v[196:199], v[8:11]
	s_setprio 0
	s_barrier
	s_add_u32 s16, s34, 0xb0000
	s_addc_u32 s17, s35, 0
	s_add_i32 s20, s59, s40
	s_mov_b32 m0, s20
	s_nop 0
	global_load_lds_dwordx4 v132, s[16:17]
	s_add_i32 m0, s20, 0x2000
	s_nop 0
	global_load_lds_dwordx4 v128, s[16:17]
	s_add_u32 s16, s36, 0xb0000
	s_addc_u32 s17, s37, 0
	s_mov_b32 m0, s44
	s_nop 0
	global_load_lds_dwordx4 v134, s[16:17]
	s_mov_b32 m0, s45
	s_nop 0
	global_load_lds_dwordx4 v130, s[16:17]
	s_waitcnt vmcnt(10)
	s_setprio 1
	s_barrier
	v_mfma_f32_16x16x32_bf16 v[52:55], v[202:205], v[168:171], v[52:55]
	v_mfma_f32_16x16x32_bf16 v[44:47], v[210:213], v[168:171], v[44:47]
	v_mfma_f32_16x16x32_bf16 v[36:39], v[202:205], v[176:179], v[36:39]
	v_mfma_f32_16x16x32_bf16 v[28:31], v[210:213], v[176:179], v[28:31]
	v_mfma_f32_16x16x32_bf16 v[20:23], v[202:205], v[184:187], v[20:23]
	v_mfma_f32_16x16x32_bf16 v[12:15], v[210:213], v[184:187], v[12:15]
	v_mfma_f32_16x16x32_bf16 v[4:7], v[202:205], v[192:195], v[4:7]
	v_mfma_f32_16x16x32_bf16 v[0:3], v[210:213], v[192:195], v[0:3]
	v_mfma_f32_16x16x32_bf16 v[52:55], v[206:209], v[172:175], v[52:55]
	v_mfma_f32_16x16x32_bf16 v[44:47], v[214:217], v[172:175], v[44:47]
	v_mfma_f32_16x16x32_bf16 v[36:39], v[206:209], v[180:183], v[36:39]
	v_mfma_f32_16x16x32_bf16 v[28:31], v[214:217], v[180:183], v[28:31]
	v_mfma_f32_16x16x32_bf16 v[20:23], v[206:209], v[188:191], v[20:23]
	v_mfma_f32_16x16x32_bf16 v[12:15], v[214:217], v[188:191], v[12:15]
	v_mfma_f32_16x16x32_bf16 v[4:7], v[206:209], v[196:199], v[4:7]
	v_mfma_f32_16x16x32_bf16 v[0:3], v[214:217], v[196:199], v[0:3]
	s_setprio 0
	s_add_i32 s20, 0, 0x18000
	v_add_u32_e32 v156, s20, v164
	s_barrier
	ds_read_b128 v[144:147], v156
	ds_read_b128 v[148:151], v156 offset:1024
	ds_read_b128 v[152:155], v156 offset:2048
	ds_read_b128 v[156:159], v156 offset:3072
	ds_read_b128 v[168:171], v166 offset:32768
	ds_read_b128 v[172:175], v166 offset:33792
	ds_read_b128 v[176:179], v166 offset:34816
	ds_read_b128 v[180:183], v166 offset:35840
	ds_read_b128 v[184:187], v166 offset:36864
	ds_read_b128 v[188:191], v166 offset:37888
	ds_read_b128 v[192:195], v166 offset:38912
	ds_read_b128 v[196:199], v166 offset:39936
	s_waitcnt lgkmcnt(8)
	s_waitcnt vmcnt(8)
	s_setprio 1
	s_barrier
; #define PG8_STAGE(bufoff, gbase, voff) do { _Pragma("unroll") for (int _i = 0; _i < 2; ++_i) \
;         __builtin_amdgcn_global_load_lds((const unsigned*)((const char*)(gbase) + (voff)[_i]), (LAS unsigned*)(lds + (bufoff) + ldsw + _i * 8192), 16, 0, 0); } while (0)
; #define PG8_LDA(dst, b, h) do { _Pragma("unroll") for (int m = 0; m < 4; ++m) _Pragma("unroll") for (int k = 0; k < 2; ++k) dst[m][k] = *(const LAS bf16x8*)(lds + PG8_SA(b, h) + aoff + m * 2048 + k * 1024); } while (0)
; #define PG8_LDB(dst, b, h) do { _Pragma("unroll") for (int n = 0; n < 2; ++n) _Pragma("unroll") for (int k = 0; k < 2; ++k) dst[n][k] = *(const LAS bf16x8*)(lds + PG8_SB(b, h) + boff + n * 2048 + k * 1024); } while (0)
; #define PG8_MMA(ai, bj, At, Bt) do { __builtin_amdgcn_s_setprio(1); _Pragma("unroll") for (int m = 0; m < 4; ++m) _Pragma("unroll") for (int n = 0; n < 2; ++n) _Pragma("unroll") for (int k = 0; k < 2; ++k) \
;         acc[ai][bj][m][n] = __builtin_amdgcn_mfma_f32_16x16x32_bf16(Bt[n][k], At[m][k], acc[ai][bj][m][n], 0, 0, 0); __builtin_amdgcn_s_setprio(0); } while (0)
; #define PG8_WAIT_V(n) asm volatile("s_waitcnt vmcnt(" #n ")" ::: "memory")
; #define PG8_WAIT_L(n) asm volatile("s_waitcnt lgkmcnt(" #n ")" ::: "memory")
; #define PG8_BAR __builtin_amdgcn_s_barrier()
; template <class Epi, class Sched>
; __device__ __forceinline__ void gemm_phase(LAS unsigned char* lds, const Gemm g, const Sched& S, const Epi& E) {
;     ...
;             PG8_WAIT_L(8); PG8_BAR; PG8_WAIT_L(0); PG8_MMA(0, 0, At, B0); PG8_BAR; PG8_SCHED;
;             PG8_LDB(B1, 1, 1); PG8_STAGE(PG8_SB(1, 0), b3, voffB);
;             PG8_BAR; PG8_WAIT_L(0); PG8_MMA(0, 1, At, B1); PG8_BAR;
;             PG8_LDA(At, 1, 1); PG8_STAGE(PG8_SA(1, 0), a3, voffA);
;             PG8_BAR; PG8_WAIT_L(0); PG8_MMA(1, 0, At, B0); PG8_BAR; PG8_SCHED;
;             PG8_STAGE(PG8_SB(1, 1), b3 + hstep, voffB);
;             PG8_WAIT_V(6); PG8_BAR; PG8_MMA(1, 1, At, B1); PG8_BAR;
;     __device__ __forceinline__ void operator()(const AccT& acc, const Unit& u, int wr, int wc, int fr, int fq) const {
;         asm volatile("" : "+v"(fr), "+v"(fq));
;         const int rowt = u.pm * 256; const bool isc = rowt >= MX; const int b = isc ? 32 : (rowt >> 11);
;         const float* res = isc ? res_c + (size_t)(rowt - MX) * DM : res_x + (size_t)rowt * DM; bf16_t* out = hb + (size_t)rowt * DM;
	s_waitcnt lgkmcnt(0)
	s_waitcnt lgkmcnt(0)
	v_mfma_f32_16x16x32_bf16 v[124:127], v[144:147], v[168:171], v[124:127]
	v_mfma_f32_16x16x32_bf16 v[120:123], v[152:155], v[168:171], v[120:123]
	v_mfma_f32_16x16x32_bf16 v[116:119], v[144:147], v[176:179], v[116:119]
	v_mfma_f32_16x16x32_bf16 v[104:107], v[152:155], v[176:179], v[104:107]
	v_mfma_f32_16x16x32_bf16 v[96:99], v[144:147], v[184:187], v[96:99]
	v_mfma_f32_16x16x32_bf16 v[88:91], v[152:155], v[184:187], v[88:91]
	v_mfma_f32_16x16x32_bf16 v[80:83], v[144:147], v[192:195], v[80:83]
	v_mfma_f32_16x16x32_bf16 v[72:75], v[152:155], v[192:195], v[72:75]
	v_mfma_f32_16x16x32_bf16 v[124:127], v[148:151], v[172:175], v[124:127]
	v_mfma_f32_16x16x32_bf16 v[120:123], v[156:159], v[172:175], v[120:123]
	v_mfma_f32_16x16x32_bf16 v[116:119], v[148:151], v[180:183], v[116:119]
	v_mfma_f32_16x16x32_bf16 v[104:107], v[156:159], v[180:183], v[104:107]
	v_mfma_f32_16x16x32_bf16 v[96:99], v[148:151], v[188:191], v[96:99]
	v_mfma_f32_16x16x32_bf16 v[88:91], v[156:159], v[188:191], v[88:91]
	v_mfma_f32_16x16x32_bf16 v[80:83], v[148:151], v[196:199], v[80:83]
	v_mfma_f32_16x16x32_bf16 v[72:75], v[156:159], v[196:199], v[72:75]
	s_setprio 0
	s_barrier
	s_add_i32 s21, 0, 0x1c000
	s_add_i32 s16, s20, s40
	v_add_u32_e32 v214, s21, v164
	s_add_u32 s8, s34, 0x80
	s_addc_u32 s9, s35, 0
	s_mov_b32 m0, s16
	ds_read_b128 v[202:205], v214
	ds_read_b128 v[206:209], v214 offset:1024
	ds_read_b128 v[210:213], v214 offset:2048
	ds_read_b128 v[214:217], v214 offset:3072
	global_load_lds_dwordx4 v132, s[8:9]
	s_add_i32 m0, s16, 0x2000
	s_nop 0
	global_load_lds_dwordx4 v128, s[8:9]
	s_waitcnt vmcnt(8)
	s_setprio 1
	s_barrier
	s_waitcnt lgkmcnt(0)
	s_waitcnt lgkmcnt(0)
	v_mfma_f32_16x16x32_bf16 v[112:115], v[202:205], v[168:171], v[112:115]
	v_mfma_f32_16x16x32_bf16 v[108:111], v[210:213], v[168:171], v[108:111]
	v_mfma_f32_16x16x32_bf16 v[100:103], v[202:205], v[176:179], v[100:103]
	v_mfma_f32_16x16x32_bf16 v[92:95], v[210:213], v[176:179], v[92:95]
	v_mfma_f32_16x16x32_bf16 v[84:87], v[202:205], v[184:187], v[84:87]
	v_mfma_f32_16x16x32_bf16 v[76:79], v[210:213], v[184:187], v[76:79]
	v_mfma_f32_16x16x32_bf16 v[68:71], v[202:205], v[192:195], v[68:71]
	v_mfma_f32_16x16x32_bf16 v[64:67], v[210:213], v[192:195], v[64:67]
	v_mfma_f32_16x16x32_bf16 v[112:115], v[206:209], v[172:175], v[112:115]
	v_mfma_f32_16x16x32_bf16 v[108:111], v[214:217], v[172:175], v[108:111]
	v_mfma_f32_16x16x32_bf16 v[100:103], v[206:209], v[180:183], v[100:103]
	v_mfma_f32_16x16x32_bf16 v[92:95], v[214:217], v[180:183], v[92:95]
	v_mfma_f32_16x16x32_bf16 v[84:87], v[206:209], v[188:191], v[84:87]
	v_mfma_f32_16x16x32_bf16 v[76:79], v[214:217], v[188:191], v[76:79]
	v_mfma_f32_16x16x32_bf16 v[68:71], v[206:209], v[196:199], v[68:71]
	v_mfma_f32_16x16x32_bf16 v[64:67], v[214:217], v[196:199], v[64:67]
	s_setprio 0
	s_mov_b32 m0, s52
	s_add_u32 s8, s36, 0x80
	s_addc_u32 s9, s37, 0
	s_barrier
	ds_read_b128 v[168:171], v166 offset:49152
	ds_read_b128 v[172:175], v166 offset:50176
	ds_read_b128 v[176:179], v166 offset:51200
	ds_read_b128 v[180:183], v166 offset:52224
	ds_read_b128 v[184:187], v166 offset:53248
	ds_read_b128 v[188:191], v166 offset:54272
	ds_read_b128 v[192:195], v166 offset:55296
	ds_read_b128 v[196:199], v166 offset:56320
	global_load_lds_dwordx4 v134, s[8:9]
	s_mov_b32 m0, s53
	s_nop 0
	global_load_lds_dwordx4 v130, s[8:9]
	s_setprio 1
	s_barrier
	s_waitcnt lgkmcnt(0)
	s_waitcnt lgkmcnt(0)
	v_mfma_f32_16x16x32_bf16 v[60:63], v[144:147], v[168:171], v[60:63]
	v_mfma_f32_16x16x32_bf16 v[56:59], v[152:155], v[168:171], v[56:59]
	v_mfma_f32_16x16x32_bf16 v[48:51], v[144:147], v[176:179], v[48:51]
	v_mfma_f32_16x16x32_bf16 v[40:43], v[152:155], v[176:179], v[40:43]
	v_mfma_f32_16x16x32_bf16 v[32:35], v[144:147], v[184:187], v[32:35]
	v_mfma_f32_16x16x32_bf16 v[24:27], v[152:155], v[184:187], v[24:27]
	v_mfma_f32_16x16x32_bf16 v[16:19], v[144:147], v[192:195], v[16:19]
	v_mfma_f32_16x16x32_bf16 v[8:11], v[152:155], v[192:195], v[8:11]
	v_mfma_f32_16x16x32_bf16 v[60:63], v[148:151], v[172:175], v[60:63]
	v_mfma_f32_16x16x32_bf16 v[56:59], v[156:159], v[172:175], v[56:59]
	v_mfma_f32_16x16x32_bf16 v[48:51], v[148:151], v[180:183], v[48:51]
	v_mfma_f32_16x16x32_bf16 v[40:43], v[156:159], v[180:183], v[40:43]
	v_mfma_f32_16x16x32_bf16 v[32:35], v[148:151], v[188:191], v[32:35]
	v_mfma_f32_16x16x32_bf16 v[24:27], v[156:159], v[188:191], v[24:27]
	v_mfma_f32_16x16x32_bf16 v[16:19], v[148:151], v[196:199], v[16:19]
	v_mfma_f32_16x16x32_bf16 v[8:11], v[156:159], v[196:199], v[8:11]
	s_setprio 0
	s_barrier
	s_add_u32 s16, s34, 0xb0080
	s_addc_u32 s17, s35, 0
	s_add_i32 s20, s21, s40
	s_mov_b32 m0, s20
	s_nop 0
	global_load_lds_dwordx4 v132, s[16:17]
	s_add_i32 m0, s20, 0x2000
	s_nop 0
	global_load_lds_dwordx4 v128, s[16:17]
	s_waitcnt vmcnt(8)
	s_setprio 1
	s_barrier
	v_mfma_f32_16x16x32_bf16 v[52:55], v[202:205], v[168:171], v[52:55]
	v_mfma_f32_16x16x32_bf16 v[44:47], v[210:213], v[168:171], v[44:47]
	v_mfma_f32_16x16x32_bf16 v[36:39], v[202:205], v[176:179], v[36:39]
	v_mfma_f32_16x16x32_bf16 v[28:31], v[210:213], v[176:179], v[28:31]
	v_mfma_f32_16x16x32_bf16 v[20:23], v[202:205], v[184:187], v[20:23]
	v_mfma_f32_16x16x32_bf16 v[12:15], v[210:213], v[184:187], v[12:15]
	v_mfma_f32_16x16x32_bf16 v[4:7], v[202:205], v[192:195], v[4:7]
	v_mfma_f32_16x16x32_bf16 v[0:3], v[210:213], v[192:195], v[0:3]
	v_mfma_f32_16x16x32_bf16 v[52:55], v[206:209], v[172:175], v[52:55]
	v_mfma_f32_16x16x32_bf16 v[44:47], v[214:217], v[172:175], v[44:47]
	v_mfma_f32_16x16x32_bf16 v[36:39], v[206:209], v[180:183], v[36:39]
	v_mfma_f32_16x16x32_bf16 v[28:31], v[214:217], v[180:183], v[28:31]
	v_mfma_f32_16x16x32_bf16 v[20:23], v[206:209], v[188:191], v[20:23]
	v_mfma_f32_16x16x32_bf16 v[12:15], v[214:217], v[188:191], v[12:15]
	v_mfma_f32_16x16x32_bf16 v[4:7], v[206:209], v[196:199], v[4:7]
	v_mfma_f32_16x16x32_bf16 v[0:3], v[214:217], v[196:199], v[0:3]
	s_setprio 0
	s_add_i32 s68, s68, 2
	s_add_u32 s0, s0, 0x100
	s_addc_u32 s67, s67, 0
	s_cmp_gt_u32 s68, 41
	s_mov_b64 s[26:27], s[28:29]
	s_barrier
	s_cbranch_scc0 .LBB0_305
	s_lshl_b32 s0, s66, 8
	v_mov_b32_e32 v145, v163
	v_mov_b32_e32 v144, v162
	s_cmpk_lt_i32 s66, 0x100
	s_cbranch_scc0 .LBB0_308
	s_ashr_i32 s29, s0, 31
	s_mov_b32 s28, s0
	s_lshl_b64 s[16:17], s[28:29], 12
	v_readlane_b32 s80, v254, 23
	v_readlane_b32 s81, v254, 24
	s_add_u32 s26, s80, s16
	v_readlane_b32 s82, v254, 25
	v_readlane_b32 s83, v254, 26
	v_readlane_b32 s84, v254, 27
	v_readlane_b32 s85, v254, 28
	v_readlane_b32 s86, v254, 29
	v_readlane_b32 s87, v254, 30
	v_readlane_b32 s88, v254, 31
	v_readlane_b32 s89, v254, 32
	v_readlane_b32 s90, v254, 33
	v_readlane_b32 s91, v254, 34
	v_readlane_b32 s92, v254, 35
	v_readlane_b32 s93, v254, 36
	v_readlane_b32 s94, v254, 37
	v_readlane_b32 s95, v254, 38
	s_addc_u32 s27, s81, s17
	s_cbranch_execnz .LBB0_297
	s_branch .LBB0_296

; #define PG8_STAGE(bufoff, gbase, voff) do { _Pragma("unroll") for (int _i = 0; _i < 2; ++_i) \
;         __builtin_amdgcn_global_load_lds((const unsigned*)((const char*)(gbase) + (voff)[_i]), (LAS unsigned*)(lds + (bufoff) + ldsw + _i * 8192), 16, 0, 0); } while (0)
; #define PG8_LDA(dst, b, h) do { _Pragma("unroll") for (int m = 0; m < 4; ++m) _Pragma("unroll") for (int k = 0; k < 2; ++k) dst[m][k] = *(const LAS bf16x8*)(lds + PG8_SA(b, h) + aoff + m * 2048 + k * 1024); } while (0)
; #define PG8_LDB(dst, b, h) do { _Pragma("unroll") for (int n = 0; n < 2; ++n) _Pragma("unroll") for (int k = 0; k < 2; ++k) dst[n][k] = *(const LAS bf16x8*)(lds + PG8_SB(b, h) + boff + n * 2048 + k * 1024); } while (0)
; #define PG8_MMA(ai, bj, At, Bt) do { __builtin_amdgcn_s_setprio(1); _Pragma("unroll") for (int m = 0; m < 4; ++m) _Pragma("unroll") for (int n = 0; n < 2; ++n) _Pragma("unroll") for (int k = 0; k < 2; ++k) \
;         acc[ai][bj][m][n] = __builtin_amdgcn_mfma_f32_16x16x32_bf16(Bt[n][k], At[m][k], acc[ai][bj][m][n], 0, 0, 0); __builtin_amdgcn_s_setprio(0); } while (0)
; #define PG8_WAIT_L(n) asm volatile("s_waitcnt lgkmcnt(" #n ")" ::: "memory")
; template <class Epi, class Sched>
; __device__ __forceinline__ void gemm_phase(LAS unsigned char* lds, const Gemm g, const Sched& S, const Epi& E) {
;     ...
;         const bool has_next = S.next(ui + 1, nxt);
;         const char* nA = has_next ? (const char*)g.A + (size_t)nxt.pm * tstep : cA; const char* nB = has_next ? (const char*)g.Bt + (size_t)nxt.pn * tstep : cB;
;         for (int t = 0; t < nt; t += 2) {
;             const bool last = (t == nt - 2);
;             const char* a1 = cA + (size_t)(t + 1) * kstep;
;             const char* a2 = last ? nA : cA + (size_t)(t + 2) * kstep; const char* b2 = last ? nB : cB + (size_t)(t + 2) * kstep;
;             const char* a3 = a2 + kstep; const char* b3 = b2 + kstep;
;             PG8_LDB(B0, 0, 0); PG8_SCHED; PG8_LDA(At, 0, 0); PG8_STAGE(PG8_SA(1, 1), a1 + hstep, voffA);
;             PG8_WAIT_L(8); PG8_BAR; PG8_WAIT_L(0); PG8_MMA(0, 0, At, B0); PG8_BAR; PG8_SCHED;
;             PG8_LDB(B1, 0, 1); PG8_STAGE(PG8_SB(0, 0), b2, voffB);
;             PG8_BAR; PG8_WAIT_L(0); PG8_MMA(0, 1, At, B1); PG8_BAR;
;             PG8_LDA(At, 0, 1); PG8_STAGE(PG8_SA(0, 0), a2, voffA);
;             PG8_BAR; PG8_WAIT_L(0); PG8_MMA(1, 0, At, B0); PG8_BAR; PG8_SCHED;
.LBB0_577:
	s_ashr_i32 s21, s20, 31
	v_cmp_lt_i64_e32 vcc, s[22:23], v[156:157]
	s_lshl_b64 s[22:23], s[20:21], 19
	s_add_u32 s22, s96, s22
	s_addc_u32 s23, s97, s23
	s_and_b64 s[24:25], vcc, exec
	s_cselect_b32 s5, s23, s7
	s_cselect_b32 s21, s22, s6
	s_ashr_i32 s19, s18, 31
	s_lshl_b64 s[24:25], s[18:19], 19
	s_add_u32 s24, s31, s24
	s_addc_u32 s25, s33, s25
	s_and_b64 s[28:29], vcc, exec
	s_cselect_b32 s19, s25, s27
	s_cselect_b32 s53, s24, s26
	s_add_u32 s6, s6, 0x40080
	s_addc_u32 s7, s7, 0
	s_add_u32 s54, s26, 0x100
	s_addc_u32 s55, s27, 0
	s_mov_b32 s56, -2
	s_waitcnt lgkmcnt(0)
	ds_read_b128 v[128:131], v167
	ds_read_b128 v[132:135], v167 offset:1024
	ds_read_b128 v[136:139], v167 offset:2048
	ds_read_b128 v[160:163], v167 offset:3072
	s_add_u32 s26, s6, 0xfffc0080
	s_addc_u32 s27, s7, -1
	s_cmp_eq_u32 s56, 12
	s_cselect_b32 s29, s5, s27
	s_cselect_b32 s28, s21, s26
	s_cselect_b32 s27, s19, s55
	s_cselect_b32 s26, s53, s54
	s_add_i32 m0, s37, 0xc000
	ds_read_b128 v[170:173], v168
	ds_read_b128 v[174:177], v168 offset:1024
	ds_read_b128 v[178:181], v168 offset:2048
	ds_read_b128 v[182:185], v168 offset:3072
	ds_read_b128 v[186:189], v168 offset:4096
	ds_read_b128 v[190:193], v168 offset:5120
	ds_read_b128 v[194:197], v168 offset:6144
	ds_read_b128 v[202:205], v168 offset:7168
	global_load_lds_dwordx4 v152, s[6:7]
	s_add_i32 m0, s37, 0xe000
	s_nop 0
	global_load_lds_dwordx4 v154, s[6:7]
	s_waitcnt lgkmcnt(8)
	s_waitcnt vmcnt(8)
	s_setprio 1
	s_barrier
	s_waitcnt lgkmcnt(0)
	s_waitcnt lgkmcnt(0)
	v_mfma_f32_16x16x32_bf16 v[124:127], v[128:131], v[170:173], 0
	v_mfma_f32_16x16x32_bf16 v[120:123], v[136:139], v[170:173], 0
	v_mfma_f32_16x16x32_bf16 v[108:111], v[128:131], v[178:181], 0
	v_mfma_f32_16x16x32_bf16 v[104:107], v[136:139], v[178:181], 0
	v_mfma_f32_16x16x32_bf16 v[92:95], v[128:131], v[186:189], 0
	v_mfma_f32_16x16x32_bf16 v[88:91], v[136:139], v[186:189], 0
	v_mfma_f32_16x16x32_bf16 v[76:79], v[128:131], v[194:197], 0
	v_mfma_f32_16x16x32_bf16 v[72:75], v[136:139], v[194:197], 0
	v_mfma_f32_16x16x32_bf16 v[124:127], v[132:135], v[174:177], v[124:127]
	v_mfma_f32_16x16x32_bf16 v[120:123], v[160:163], v[174:177], v[120:123]
	v_mfma_f32_16x16x32_bf16 v[108:111], v[132:135], v[182:185], v[108:111]
	v_mfma_f32_16x16x32_bf16 v[104:107], v[160:163], v[182:185], v[104:107]
	v_mfma_f32_16x16x32_bf16 v[92:95], v[132:135], v[190:193], v[92:95]
	v_mfma_f32_16x16x32_bf16 v[88:91], v[160:163], v[190:193], v[88:91]
	v_mfma_f32_16x16x32_bf16 v[76:79], v[132:135], v[202:205], v[76:79]
	v_mfma_f32_16x16x32_bf16 v[72:75], v[160:163], v[202:205], v[72:75]
	s_setprio 0
	s_barrier
	s_add_i32 s57, s48, s34
	s_mov_b32 m0, s57
	ds_read_b128 v[206:209], v169
	ds_read_b128 v[210:213], v169 offset:1024
	ds_read_b128 v[214:217], v169 offset:2048
	ds_read_b128 v[218:221], v169 offset:3072
	global_load_lds_dwordx4 v146, s[26:27]
	s_add_i32 m0, s57, 0x2000
	s_nop 0
	global_load_lds_dwordx4 v142, s[26:27]
	s_waitcnt vmcnt(8)
	s_setprio 1
	s_barrier
	s_waitcnt lgkmcnt(0)
	s_waitcnt lgkmcnt(0)
	v_mfma_f32_16x16x32_bf16 v[116:119], v[206:209], v[170:173], 0
	v_mfma_f32_16x16x32_bf16 v[112:115], v[214:217], v[170:173], 0
	v_mfma_f32_16x16x32_bf16 v[100:103], v[206:209], v[178:181], 0
	v_mfma_f32_16x16x32_bf16 v[96:99], v[214:217], v[178:181], 0
	v_mfma_f32_16x16x32_bf16 v[84:87], v[206:209], v[186:189], 0
	v_mfma_f32_16x16x32_bf16 v[80:83], v[214:217], v[186:189], 0
	v_mfma_f32_16x16x32_bf16 v[68:71], v[206:209], v[194:197], 0
	v_mfma_f32_16x16x32_bf16 v[64:67], v[214:217], v[194:197], 0
	v_mfma_f32_16x16x32_bf16 v[116:119], v[210:213], v[174:177], v[116:119]
	v_mfma_f32_16x16x32_bf16 v[112:115], v[218:221], v[174:177], v[112:115]
	v_mfma_f32_16x16x32_bf16 v[100:103], v[210:213], v[182:185], v[100:103]
	v_mfma_f32_16x16x32_bf16 v[96:99], v[218:221], v[182:185], v[96:99]
	v_mfma_f32_16x16x32_bf16 v[84:87], v[210:213], v[190:193], v[84:87]
	v_mfma_f32_16x16x32_bf16 v[80:83], v[218:221], v[190:193], v[80:83]
	v_mfma_f32_16x16x32_bf16 v[68:71], v[210:213], v[202:205], v[68:71]
	v_mfma_f32_16x16x32_bf16 v[64:67], v[218:221], v[202:205], v[64:67]
	s_setprio 0
	s_mov_b32 m0, s37
	v_lshl_add_u64 v[222:223], s[28:29], 0, v[148:149]
	s_barrier
	ds_read_b128 v[170:173], v168 offset:16384
	ds_read_b128 v[174:177], v168 offset:17408
	ds_read_b128 v[178:181], v168 offset:18432
	ds_read_b128 v[182:185], v168 offset:19456
	ds_read_b128 v[186:189], v168 offset:20480
	ds_read_b128 v[190:193], v168 offset:21504
	ds_read_b128 v[194:197], v168 offset:22528
	ds_read_b128 v[202:205], v168 offset:23552
	global_load_lds_dwordx4 v148, s[28:29]
	v_lshl_add_u64 v[224:225], s[28:29], 0, v[144:145]
	s_mov_b32 m0, s38
	s_nop 0
	global_load_lds_dwordx4 v144, s[28:29]
	s_setprio 1
	s_barrier
	s_waitcnt lgkmcnt(0)
	s_waitcnt lgkmcnt(0)
	v_mfma_f32_16x16x32_bf16 v[60:63], v[128:131], v[170:173], 0
	v_mfma_f32_16x16x32_bf16 v[56:59], v[136:139], v[170:173], 0
	v_mfma_f32_16x16x32_bf16 v[44:47], v[128:131], v[178:181], 0
	v_mfma_f32_16x16x32_bf16 v[40:43], v[136:139], v[178:181], 0
	v_mfma_f32_16x16x32_bf16 v[28:31], v[128:131], v[186:189], 0
	v_mfma_f32_16x16x32_bf16 v[24:27], v[136:139], v[186:189], 0
	v_mfma_f32_16x16x32_bf16 v[12:15], v[128:131], v[194:197], 0
	v_mfma_f32_16x16x32_bf16 v[8:11], v[136:139], v[194:197], 0
	v_mfma_f32_16x16x32_bf16 v[60:63], v[132:135], v[174:177], v[60:63]
	v_mfma_f32_16x16x32_bf16 v[56:59], v[160:163], v[174:177], v[56:59]
	v_mfma_f32_16x16x32_bf16 v[44:47], v[132:135], v[182:185], v[44:47]
	v_mfma_f32_16x16x32_bf16 v[40:43], v[160:163], v[182:185], v[40:43]
	v_mfma_f32_16x16x32_bf16 v[28:31], v[132:135], v[190:193], v[28:31]
	v_mfma_f32_16x16x32_bf16 v[24:27], v[160:163], v[190:193], v[24:27]
	v_mfma_f32_16x16x32_bf16 v[12:15], v[132:135], v[202:205], v[12:15]
	v_mfma_f32_16x16x32_bf16 v[8:11], v[160:163], v[202:205], v[8:11]
	s_setprio 0
	s_barrier
; #define PG8_STAGE(bufoff, gbase, voff) do { _Pragma("unroll") for (int _i = 0; _i < 2; ++_i) \
;         __builtin_amdgcn_global_load_lds((const unsigned*)((const char*)(gbase) + (voff)[_i]), (LAS unsigned*)(lds + (bufoff) + ldsw + _i * 8192), 16, 0, 0); } while (0)
; #define PG8_LDA(dst, b, h) do { _Pragma("unroll") for (int m = 0; m < 4; ++m) _Pragma("unroll") for (int k = 0; k < 2; ++k) dst[m][k] = *(const LAS bf16x8*)(lds + PG8_SA(b, h) + aoff + m * 2048 + k * 1024); } while (0)
; #define PG8_LDB(dst, b, h) do { _Pragma("unroll") for (int n = 0; n < 2; ++n) _Pragma("unroll") for (int k = 0; k < 2; ++k) dst[n][k] = *(const LAS bf16x8*)(lds + PG8_SB(b, h) + boff + n * 2048 + k * 1024); } while (0)
; #define PG8_MMA(ai, bj, At, Bt) do { __builtin_amdgcn_s_setprio(1); _Pragma("unroll") for (int m = 0; m < 4; ++m) _Pragma("unroll") for (int n = 0; n < 2; ++n) _Pragma("unroll") for (int k = 0; k < 2; ++k) \
;         acc[ai][bj][m][n] = __builtin_amdgcn_mfma_f32_16x16x32_bf16(Bt[n][k], At[m][k], acc[ai][bj][m][n], 0, 0, 0); __builtin_amdgcn_s_setprio(0); } while (0)
; #define PG8_WAIT_V(n) asm volatile("s_waitcnt vmcnt(" #n ")" ::: "memory")
; #define PG8_WAIT_L(n) asm volatile("s_waitcnt lgkmcnt(" #n ")" ::: "memory")
; #define PG8_BAR __builtin_amdgcn_s_barrier()
; #define PG8_SCHED __builtin_amdgcn_sched_barrier(0)
; template <class Epi, class Sched>
; __device__ __forceinline__ void gemm_phase(LAS unsigned char* lds, const Gemm g, const Sched& S, const Epi& E) {
;     ...
;             PG8_STAGE(PG8_SB(0, 1), b2 + hstep, voffB);
;             PG8_WAIT_V(6); PG8_BAR; PG8_MMA(1, 1, At, B1); PG8_BAR;
;             PG8_LDB(B0, 1, 0); PG8_SCHED; PG8_LDA(At, 1, 0); PG8_STAGE(PG8_SA(0, 1), a2 + hstep, voffA);
;             PG8_WAIT_L(8); PG8_BAR; PG8_WAIT_L(0); PG8_MMA(0, 0, At, B0); PG8_BAR; PG8_SCHED;
;             PG8_LDB(B1, 1, 1); PG8_STAGE(PG8_SB(1, 0), b3, voffB);
;             PG8_BAR; PG8_WAIT_L(0); PG8_MMA(0, 1, At, B1); PG8_BAR;
;             PG8_LDA(At, 1, 1); PG8_STAGE(PG8_SA(1, 0), a3, voffA);
	s_add_u32 s58, s26, 0x40000
	s_addc_u32 s59, s27, 0
	s_add_i32 s57, s49, s34
	s_mov_b32 m0, s57
	s_nop 0
	global_load_lds_dwordx4 v146, s[58:59]
	s_add_i32 m0, s57, 0x2000
	s_nop 0
	global_load_lds_dwordx4 v142, s[58:59]
	s_add_u32 s28, s28, 0x40000
	s_addc_u32 s29, s29, 0
	s_mov_b32 m0, s39
	s_nop 0
	global_load_lds_dwordx4 v148, s[28:29]
	s_mov_b32 m0, s40
	s_nop 0
	global_load_lds_dwordx4 v144, s[28:29]
	s_waitcnt vmcnt(10)
	s_setprio 1
	s_barrier
	v_mfma_f32_16x16x32_bf16 v[52:55], v[206:209], v[170:173], 0
	v_mfma_f32_16x16x32_bf16 v[48:51], v[214:217], v[170:173], 0
	v_mfma_f32_16x16x32_bf16 v[36:39], v[206:209], v[178:181], 0
	v_mfma_f32_16x16x32_bf16 v[32:35], v[214:217], v[178:181], 0
	v_mfma_f32_16x16x32_bf16 v[20:23], v[206:209], v[186:189], 0
	v_mfma_f32_16x16x32_bf16 v[16:19], v[214:217], v[186:189], 0
	v_mfma_f32_16x16x32_bf16 v[4:7], v[206:209], v[194:197], 0
	v_mfma_f32_16x16x32_bf16 v[0:3], v[214:217], v[194:197], 0
	v_mfma_f32_16x16x32_bf16 v[52:55], v[210:213], v[174:177], v[52:55]
	v_mfma_f32_16x16x32_bf16 v[48:51], v[218:221], v[174:177], v[48:51]
	v_mfma_f32_16x16x32_bf16 v[36:39], v[210:213], v[182:185], v[36:39]
	v_mfma_f32_16x16x32_bf16 v[32:35], v[218:221], v[182:185], v[32:35]
	v_mfma_f32_16x16x32_bf16 v[20:23], v[210:213], v[190:193], v[20:23]
	v_mfma_f32_16x16x32_bf16 v[16:19], v[218:221], v[190:193], v[16:19]
	v_mfma_f32_16x16x32_bf16 v[4:7], v[210:213], v[202:205], v[4:7]
	v_mfma_f32_16x16x32_bf16 v[0:3], v[218:221], v[202:205], v[0:3]
	s_setprio 0
	s_add_i32 s57, 0, 0x18000
	v_add_u32_e32 v150, s57, v166
	s_barrier
	ds_read_b128 v[128:131], v150
	ds_read_b128 v[132:135], v150 offset:1024
	ds_read_b128 v[136:139], v150 offset:2048
	ds_read_b128 v[160:163], v150 offset:3072
	ds_read_b128 v[170:173], v168 offset:32768
	ds_read_b128 v[174:177], v168 offset:33792
	ds_read_b128 v[178:181], v168 offset:34816
	ds_read_b128 v[182:185], v168 offset:35840
	ds_read_b128 v[186:189], v168 offset:36864
	ds_read_b128 v[190:193], v168 offset:37888
	ds_read_b128 v[194:197], v168 offset:38912
	ds_read_b128 v[202:205], v168 offset:39936
	s_waitcnt lgkmcnt(8)
	s_waitcnt vmcnt(8)
	s_setprio 1
	s_barrier
	s_waitcnt lgkmcnt(0)
	s_waitcnt lgkmcnt(0)
	v_mfma_f32_16x16x32_bf16 v[124:127], v[128:131], v[170:173], v[124:127]
	v_mfma_f32_16x16x32_bf16 v[120:123], v[136:139], v[170:173], v[120:123]
	v_mfma_f32_16x16x32_bf16 v[108:111], v[128:131], v[178:181], v[108:111]
	v_mfma_f32_16x16x32_bf16 v[104:107], v[136:139], v[178:181], v[104:107]
	v_mfma_f32_16x16x32_bf16 v[92:95], v[128:131], v[186:189], v[92:95]
	v_mfma_f32_16x16x32_bf16 v[88:91], v[136:139], v[186:189], v[88:91]
	v_mfma_f32_16x16x32_bf16 v[76:79], v[128:131], v[194:197], v[76:79]
	v_mfma_f32_16x16x32_bf16 v[72:75], v[136:139], v[194:197], v[72:75]
	v_mfma_f32_16x16x32_bf16 v[124:127], v[132:135], v[174:177], v[124:127]
	v_mfma_f32_16x16x32_bf16 v[120:123], v[160:163], v[174:177], v[120:123]
	v_mfma_f32_16x16x32_bf16 v[108:111], v[132:135], v[182:185], v[108:111]
	v_mfma_f32_16x16x32_bf16 v[104:107], v[160:163], v[182:185], v[104:107]
	v_mfma_f32_16x16x32_bf16 v[92:95], v[132:135], v[190:193], v[92:95]
	v_mfma_f32_16x16x32_bf16 v[88:91], v[160:163], v[190:193], v[88:91]
	v_mfma_f32_16x16x32_bf16 v[76:79], v[132:135], v[202:205], v[76:79]
	v_mfma_f32_16x16x32_bf16 v[72:75], v[160:163], v[202:205], v[72:75]
	s_setprio 0
	s_barrier
	s_add_i32 s28, 0, 0x1c000
	s_add_i32 s29, s57, s34
	v_add_u32_e32 v150, s28, v166
	s_add_u32 s0, s26, 0x80
	s_addc_u32 s1, s27, 0
	s_mov_b32 m0, s29
	ds_read_b128 v[206:209], v150
	ds_read_b128 v[210:213], v150 offset:1024
	ds_read_b128 v[214:217], v150 offset:2048
	ds_read_b128 v[218:221], v150 offset:3072
	global_load_lds_dwordx4 v146, s[0:1]
	s_add_i32 m0, s29, 0x2000
	s_nop 0
	global_load_lds_dwordx4 v142, s[0:1]
	s_waitcnt vmcnt(8)
	s_setprio 1
	s_barrier
	s_waitcnt lgkmcnt(0)
	s_waitcnt lgkmcnt(0)
	v_mfma_f32_16x16x32_bf16 v[116:119], v[206:209], v[170:173], v[116:119]
	v_mfma_f32_16x16x32_bf16 v[112:115], v[214:217], v[170:173], v[112:115]
	v_mfma_f32_16x16x32_bf16 v[100:103], v[206:209], v[178:181], v[100:103]
	v_mfma_f32_16x16x32_bf16 v[96:99], v[214:217], v[178:181], v[96:99]
	v_mfma_f32_16x16x32_bf16 v[84:87], v[206:209], v[186:189], v[84:87]
	v_mfma_f32_16x16x32_bf16 v[80:83], v[214:217], v[186:189], v[80:83]
	v_mfma_f32_16x16x32_bf16 v[68:71], v[206:209], v[194:197], v[68:71]
	v_mfma_f32_16x16x32_bf16 v[64:67], v[214:217], v[194:197], v[64:67]
	v_mfma_f32_16x16x32_bf16 v[116:119], v[210:213], v[174:177], v[116:119]
	v_mfma_f32_16x16x32_bf16 v[112:115], v[218:221], v[174:177], v[112:115]
	v_mfma_f32_16x16x32_bf16 v[100:103], v[210:213], v[182:185], v[100:103]
	v_mfma_f32_16x16x32_bf16 v[96:99], v[218:221], v[182:185], v[96:99]
	v_mfma_f32_16x16x32_bf16 v[84:87], v[210:213], v[190:193], v[84:87]
	v_mfma_f32_16x16x32_bf16 v[80:83], v[218:221], v[190:193], v[80:83]
	v_mfma_f32_16x16x32_bf16 v[68:71], v[210:213], v[202:205], v[68:71]
	v_mfma_f32_16x16x32_bf16 v[64:67], v[218:221], v[202:205], v[64:67]
	s_setprio 0
	s_mov_b32 m0, s44
	s_mov_b64 s[0:1], 0x80
	v_lshl_add_u64 v[140:141], v[222:223], 0, s[0:1]
	s_barrier
	ds_read_b128 v[170:173], v168 offset:49152
	ds_read_b128 v[174:177], v168 offset:50176
	ds_read_b128 v[178:181], v168 offset:51200
	ds_read_b128 v[182:185], v168 offset:52224
	ds_read_b128 v[186:189], v168 offset:53248
	ds_read_b128 v[190:193], v168 offset:54272
	ds_read_b128 v[194:197], v168 offset:55296
	ds_read_b128 v[202:205], v168 offset:56320
	global_load_lds_dwordx4 v[140:141], off
	v_lshl_add_u64 v[140:141], v[224:225], 0, s[0:1]
	s_mov_b32 m0, s45
	s_nop 0
	global_load_lds_dwordx4 v[140:141], off
	s_setprio 1
	s_barrier
; #define PG8_STAGE(bufoff, gbase, voff) do { _Pragma("unroll") for (int _i = 0; _i < 2; ++_i) \
;         __builtin_amdgcn_global_load_lds((const unsigned*)((const char*)(gbase) + (voff)[_i]), (LAS unsigned*)(lds + (bufoff) + ldsw + _i * 8192), 16, 0, 0); } while (0)
; #define PG8_LDA(dst, b, h) do { _Pragma("unroll") for (int m = 0; m < 4; ++m) _Pragma("unroll") for (int k = 0; k < 2; ++k) dst[m][k] = *(const LAS bf16x8*)(lds + PG8_SA(b, h) + aoff + m * 2048 + k * 1024); } while (0)
; #define PG8_LDB(dst, b, h) do { _Pragma("unroll") for (int n = 0; n < 2; ++n) _Pragma("unroll") for (int k = 0; k < 2; ++k) dst[n][k] = *(const LAS bf16x8*)(lds + PG8_SB(b, h) + boff + n * 2048 + k * 1024); } while (0)
; #define PG8_MMA(ai, bj, At, Bt) do { __builtin_amdgcn_s_setprio(1); _Pragma("unroll") for (int m = 0; m < 4; ++m) _Pragma("unroll") for (int n = 0; n < 2; ++n) _Pragma("unroll") for (int k = 0; k < 2; ++k) \
;         acc[ai][bj][m][n] = __builtin_amdgcn_mfma_f32_16x16x32_bf16(Bt[n][k], At[m][k], acc[ai][bj][m][n], 0, 0, 0); __builtin_amdgcn_s_setprio(0); } while (0)
; #define PG8_WAIT_V(n) asm volatile("s_waitcnt vmcnt(" #n ")" ::: "memory")
; #define PG8_WAIT_L(n) asm volatile("s_waitcnt lgkmcnt(" #n ")" ::: "memory")
; #define PG8_BAR __builtin_amdgcn_s_barrier()
; #define PG8_SCHED __builtin_amdgcn_sched_barrier(0)
; template <class Epi, class Sched>
; __device__ __forceinline__ void gemm_phase(LAS unsigned char* lds, const Gemm g, const Sched& S, const Epi& E) {
;     ...
;             PG8_LDB(B0, 0, 0); PG8_SCHED; PG8_LDA(At, 0, 0); PG8_STAGE(PG8_SA(1, 1), a1 + hstep, voffA);
;             PG8_WAIT_L(8); PG8_BAR; PG8_WAIT_L(0); PG8_MMA(0, 0, At, B0); PG8_BAR; PG8_SCHED;
;             PG8_LDB(B1, 0, 1); PG8_STAGE(PG8_SB(0, 0), b2, voffB);
;             PG8_BAR; PG8_WAIT_L(0); PG8_MMA(0, 1, At, B1); PG8_BAR;
;     ...
;             PG8_BAR; PG8_WAIT_L(0); PG8_MMA(1, 0, At, B0); PG8_BAR; PG8_SCHED;
;             PG8_STAGE(PG8_SB(1, 1), b3 + hstep, voffB);
;             PG8_WAIT_V(6); PG8_BAR; PG8_MMA(1, 1, At, B1); PG8_BAR;
	s_waitcnt lgkmcnt(0)
	s_waitcnt lgkmcnt(0)
	v_mfma_f32_16x16x32_bf16 v[60:63], v[128:131], v[170:173], v[60:63]
	v_mfma_f32_16x16x32_bf16 v[56:59], v[136:139], v[170:173], v[56:59]
	v_mfma_f32_16x16x32_bf16 v[44:47], v[128:131], v[178:181], v[44:47]
	v_mfma_f32_16x16x32_bf16 v[40:43], v[136:139], v[178:181], v[40:43]
	v_mfma_f32_16x16x32_bf16 v[28:31], v[128:131], v[186:189], v[28:31]
	v_mfma_f32_16x16x32_bf16 v[24:27], v[136:139], v[186:189], v[24:27]
	v_mfma_f32_16x16x32_bf16 v[12:15], v[128:131], v[194:197], v[12:15]
	v_mfma_f32_16x16x32_bf16 v[8:11], v[136:139], v[194:197], v[8:11]
	v_mfma_f32_16x16x32_bf16 v[60:63], v[132:135], v[174:177], v[60:63]
	v_mfma_f32_16x16x32_bf16 v[56:59], v[160:163], v[174:177], v[56:59]
	v_mfma_f32_16x16x32_bf16 v[44:47], v[132:135], v[182:185], v[44:47]
	v_mfma_f32_16x16x32_bf16 v[40:43], v[160:163], v[182:185], v[40:43]
	v_mfma_f32_16x16x32_bf16 v[28:31], v[132:135], v[190:193], v[28:31]
	v_mfma_f32_16x16x32_bf16 v[24:27], v[160:163], v[190:193], v[24:27]
	v_mfma_f32_16x16x32_bf16 v[12:15], v[132:135], v[202:205], v[12:15]
	v_mfma_f32_16x16x32_bf16 v[8:11], v[160:163], v[202:205], v[8:11]
	s_setprio 0
	s_barrier
	s_add_u32 s26, s26, 0x40080
	s_addc_u32 s27, s27, 0
	s_add_i32 s28, s28, s34
	s_mov_b32 m0, s28
	s_nop 0
	global_load_lds_dwordx4 v146, s[26:27]
	s_add_i32 m0, s28, 0x2000
	s_nop 0
	global_load_lds_dwordx4 v142, s[26:27]
	s_waitcnt vmcnt(8)
	s_setprio 1
	s_barrier
	v_mfma_f32_16x16x32_bf16 v[52:55], v[206:209], v[170:173], v[52:55]
	v_mfma_f32_16x16x32_bf16 v[48:51], v[214:217], v[170:173], v[48:51]
	v_mfma_f32_16x16x32_bf16 v[36:39], v[206:209], v[178:181], v[36:39]
	v_mfma_f32_16x16x32_bf16 v[32:35], v[214:217], v[178:181], v[32:35]
	v_mfma_f32_16x16x32_bf16 v[20:23], v[206:209], v[186:189], v[20:23]
	v_mfma_f32_16x16x32_bf16 v[16:19], v[214:217], v[186:189], v[16:19]
	v_mfma_f32_16x16x32_bf16 v[4:7], v[206:209], v[194:197], v[4:7]
	v_mfma_f32_16x16x32_bf16 v[0:3], v[214:217], v[194:197], v[0:3]
	v_mfma_f32_16x16x32_bf16 v[52:55], v[210:213], v[174:177], v[52:55]
	v_mfma_f32_16x16x32_bf16 v[48:51], v[218:221], v[174:177], v[48:51]
	v_mfma_f32_16x16x32_bf16 v[36:39], v[210:213], v[182:185], v[36:39]
	v_mfma_f32_16x16x32_bf16 v[32:35], v[218:221], v[182:185], v[32:35]
	v_mfma_f32_16x16x32_bf16 v[20:23], v[210:213], v[190:193], v[20:23]
	v_mfma_f32_16x16x32_bf16 v[16:19], v[218:221], v[190:193], v[16:19]
	v_mfma_f32_16x16x32_bf16 v[4:7], v[210:213], v[202:205], v[4:7]
	v_mfma_f32_16x16x32_bf16 v[0:3], v[218:221], v[202:205], v[0:3]
	s_setprio 0
	s_add_i32 s56, s56, 2
	s_add_u32 s6, s6, 0x100
	s_addc_u32 s7, s7, 0
	s_add_u32 s54, s54, 0x100
	s_addc_u32 s55, s55, 0
	s_cmp_gt_u32 s56, 13
	s_barrier
.LBB0_578:
	ds_read_b128 v[128:131], v167
	ds_read_b128 v[132:135], v167 offset:1024
	ds_read_b128 v[136:139], v167 offset:2048
	ds_read_b128 v[160:163], v167 offset:3072
	s_add_u32 s26, s6, 0xfffc0080
	s_addc_u32 s27, s7, -1
	s_cmp_eq_u32 s56, 12
	s_cselect_b32 s29, s5, s27
	s_cselect_b32 s28, s21, s26
	s_cselect_b32 s27, s19, s55
	s_cselect_b32 s26, s53, s54
	s_add_i32 m0, s37, 0xc000
	ds_read_b128 v[170:173], v168
	ds_read_b128 v[174:177], v168 offset:1024
	ds_read_b128 v[178:181], v168 offset:2048
	ds_read_b128 v[182:185], v168 offset:3072
	ds_read_b128 v[186:189], v168 offset:4096
	ds_read_b128 v[190:193], v168 offset:5120
	ds_read_b128 v[194:197], v168 offset:6144
	ds_read_b128 v[202:205], v168 offset:7168
	global_load_lds_dwordx4 v152, s[6:7]
	s_add_i32 m0, s37, 0xe000
	s_nop 0
	global_load_lds_dwordx4 v154, s[6:7]
	s_waitcnt lgkmcnt(8)
	s_waitcnt vmcnt(8)
	s_setprio 1
	s_barrier
	s_waitcnt lgkmcnt(0)
	s_waitcnt lgkmcnt(0)
	v_mfma_f32_16x16x32_bf16 v[124:127], v[128:131], v[170:173], v[124:127]
	v_mfma_f32_16x16x32_bf16 v[120:123], v[136:139], v[170:173], v[120:123]
	v_mfma_f32_16x16x32_bf16 v[108:111], v[128:131], v[178:181], v[108:111]
	v_mfma_f32_16x16x32_bf16 v[104:107], v[136:139], v[178:181], v[104:107]
	v_mfma_f32_16x16x32_bf16 v[92:95], v[128:131], v[186:189], v[92:95]
	v_mfma_f32_16x16x32_bf16 v[88:91], v[136:139], v[186:189], v[88:91]
	v_mfma_f32_16x16x32_bf16 v[76:79], v[128:131], v[194:197], v[76:79]
	v_mfma_f32_16x16x32_bf16 v[72:75], v[136:139], v[194:197], v[72:75]
	v_mfma_f32_16x16x32_bf16 v[124:127], v[132:135], v[174:177], v[124:127]
	v_mfma_f32_16x16x32_bf16 v[120:123], v[160:163], v[174:177], v[120:123]
	v_mfma_f32_16x16x32_bf16 v[108:111], v[132:135], v[182:185], v[108:111]
	v_mfma_f32_16x16x32_bf16 v[104:107], v[160:163], v[182:185], v[104:107]
	v_mfma_f32_16x16x32_bf16 v[92:95], v[132:135], v[190:193], v[92:95]
	v_mfma_f32_16x16x32_bf16 v[88:91], v[160:163], v[190:193], v[88:91]
	v_mfma_f32_16x16x32_bf16 v[76:79], v[132:135], v[202:205], v[76:79]
	v_mfma_f32_16x16x32_bf16 v[72:75], v[160:163], v[202:205], v[72:75]
	s_setprio 0
	s_barrier
	s_add_i32 s57, s48, s34
	s_mov_b32 m0, s57
	ds_read_b128 v[206:209], v169
	ds_read_b128 v[210:213], v169 offset:1024
	ds_read_b128 v[214:217], v169 offset:2048
	ds_read_b128 v[218:221], v169 offset:3072
	global_load_lds_dwordx4 v146, s[26:27]
	s_add_i32 m0, s57, 0x2000
	s_nop 0
	global_load_lds_dwordx4 v142, s[26:27]
	s_waitcnt vmcnt(8)
	s_setprio 1
	s_barrier
; #define PG8_STAGE(bufoff, gbase, voff) do { _Pragma("unroll") for (int _i = 0; _i < 2; ++_i) \
;         __builtin_amdgcn_global_load_lds((const unsigned*)((const char*)(gbase) + (voff)[_i]), (LAS unsigned*)(lds + (bufoff) + ldsw + _i * 8192), 16, 0, 0); } while (0)
; #define PG8_LDA(dst, b, h) do { _Pragma("unroll") for (int m = 0; m < 4; ++m) _Pragma("unroll") for (int k = 0; k < 2; ++k) dst[m][k] = *(const LAS bf16x8*)(lds + PG8_SA(b, h) + aoff + m * 2048 + k * 1024); } while (0)
; #define PG8_LDB(dst, b, h) do { _Pragma("unroll") for (int n = 0; n < 2; ++n) _Pragma("unroll") for (int k = 0; k < 2; ++k) dst[n][k] = *(const LAS bf16x8*)(lds + PG8_SB(b, h) + boff + n * 2048 + k * 1024); } while (0)
; #define PG8_MMA(ai, bj, At, Bt) do { __builtin_amdgcn_s_setprio(1); _Pragma("unroll") for (int m = 0; m < 4; ++m) _Pragma("unroll") for (int n = 0; n < 2; ++n) _Pragma("unroll") for (int k = 0; k < 2; ++k) \
;         acc[ai][bj][m][n] = __builtin_amdgcn_mfma_f32_16x16x32_bf16(Bt[n][k], At[m][k], acc[ai][bj][m][n], 0, 0, 0); __builtin_amdgcn_s_setprio(0); } while (0)
; #define PG8_WAIT_V(n) asm volatile("s_waitcnt vmcnt(" #n ")" ::: "memory")
; #define PG8_WAIT_L(n) asm volatile("s_waitcnt lgkmcnt(" #n ")" ::: "memory")
; #define PG8_BAR __builtin_amdgcn_s_barrier()
; #define PG8_SCHED __builtin_amdgcn_sched_barrier(0)
; template <class Epi, class Sched>
; __device__ __forceinline__ void gemm_phase(LAS unsigned char* lds, const Gemm g, const Sched& S, const Epi& E) {
;     ...
;             PG8_BAR; PG8_WAIT_L(0); PG8_MMA(0, 1, At, B1); PG8_BAR;
;             PG8_LDA(At, 0, 1); PG8_STAGE(PG8_SA(0, 0), a2, voffA);
;             PG8_BAR; PG8_WAIT_L(0); PG8_MMA(1, 0, At, B0); PG8_BAR; PG8_SCHED;
;             PG8_STAGE(PG8_SB(0, 1), b2 + hstep, voffB);
;             PG8_WAIT_V(6); PG8_BAR; PG8_MMA(1, 1, At, B1); PG8_BAR;
;             PG8_LDB(B0, 1, 0); PG8_SCHED; PG8_LDA(At, 1, 0); PG8_STAGE(PG8_SA(0, 1), a2 + hstep, voffA);
;             PG8_WAIT_L(8); PG8_BAR; PG8_WAIT_L(0); PG8_MMA(0, 0, At, B0); PG8_BAR; PG8_SCHED;
	s_waitcnt lgkmcnt(0)
	s_waitcnt lgkmcnt(0)
	v_mfma_f32_16x16x32_bf16 v[116:119], v[206:209], v[170:173], v[116:119]
	v_mfma_f32_16x16x32_bf16 v[112:115], v[214:217], v[170:173], v[112:115]
	v_mfma_f32_16x16x32_bf16 v[100:103], v[206:209], v[178:181], v[100:103]
	v_mfma_f32_16x16x32_bf16 v[96:99], v[214:217], v[178:181], v[96:99]
	v_mfma_f32_16x16x32_bf16 v[84:87], v[206:209], v[186:189], v[84:87]
	v_mfma_f32_16x16x32_bf16 v[80:83], v[214:217], v[186:189], v[80:83]
	v_mfma_f32_16x16x32_bf16 v[68:71], v[206:209], v[194:197], v[68:71]
	v_mfma_f32_16x16x32_bf16 v[64:67], v[214:217], v[194:197], v[64:67]
	v_mfma_f32_16x16x32_bf16 v[116:119], v[210:213], v[174:177], v[116:119]
	v_mfma_f32_16x16x32_bf16 v[112:115], v[218:221], v[174:177], v[112:115]
	v_mfma_f32_16x16x32_bf16 v[100:103], v[210:213], v[182:185], v[100:103]
	v_mfma_f32_16x16x32_bf16 v[96:99], v[218:221], v[182:185], v[96:99]
	v_mfma_f32_16x16x32_bf16 v[84:87], v[210:213], v[190:193], v[84:87]
	v_mfma_f32_16x16x32_bf16 v[80:83], v[218:221], v[190:193], v[80:83]
	v_mfma_f32_16x16x32_bf16 v[68:71], v[210:213], v[202:205], v[68:71]
	v_mfma_f32_16x16x32_bf16 v[64:67], v[218:221], v[202:205], v[64:67]
	s_setprio 0
	s_mov_b32 m0, s37
	v_lshl_add_u64 v[222:223], s[28:29], 0, v[148:149]
	s_barrier
	ds_read_b128 v[170:173], v168 offset:16384
	ds_read_b128 v[174:177], v168 offset:17408
	ds_read_b128 v[178:181], v168 offset:18432
	ds_read_b128 v[182:185], v168 offset:19456
	ds_read_b128 v[186:189], v168 offset:20480
	ds_read_b128 v[190:193], v168 offset:21504
	ds_read_b128 v[194:197], v168 offset:22528
	ds_read_b128 v[202:205], v168 offset:23552
	global_load_lds_dwordx4 v148, s[28:29]
	v_lshl_add_u64 v[224:225], s[28:29], 0, v[144:145]
	s_mov_b32 m0, s38
	s_nop 0
	global_load_lds_dwordx4 v144, s[28:29]
	s_setprio 1
	s_barrier
	s_waitcnt lgkmcnt(0)
	s_waitcnt lgkmcnt(0)
	v_mfma_f32_16x16x32_bf16 v[60:63], v[128:131], v[170:173], v[60:63]
	v_mfma_f32_16x16x32_bf16 v[56:59], v[136:139], v[170:173], v[56:59]
	v_mfma_f32_16x16x32_bf16 v[44:47], v[128:131], v[178:181], v[44:47]
	v_mfma_f32_16x16x32_bf16 v[40:43], v[136:139], v[178:181], v[40:43]
	v_mfma_f32_16x16x32_bf16 v[28:31], v[128:131], v[186:189], v[28:31]
	v_mfma_f32_16x16x32_bf16 v[24:27], v[136:139], v[186:189], v[24:27]
	v_mfma_f32_16x16x32_bf16 v[12:15], v[128:131], v[194:197], v[12:15]
	v_mfma_f32_16x16x32_bf16 v[8:11], v[136:139], v[194:197], v[8:11]
	v_mfma_f32_16x16x32_bf16 v[60:63], v[132:135], v[174:177], v[60:63]
	v_mfma_f32_16x16x32_bf16 v[56:59], v[160:163], v[174:177], v[56:59]
	v_mfma_f32_16x16x32_bf16 v[44:47], v[132:135], v[182:185], v[44:47]
	v_mfma_f32_16x16x32_bf16 v[40:43], v[160:163], v[182:185], v[40:43]
	v_mfma_f32_16x16x32_bf16 v[28:31], v[132:135], v[190:193], v[28:31]
	v_mfma_f32_16x16x32_bf16 v[24:27], v[160:163], v[190:193], v[24:27]
	v_mfma_f32_16x16x32_bf16 v[12:15], v[132:135], v[202:205], v[12:15]
	v_mfma_f32_16x16x32_bf16 v[8:11], v[160:163], v[202:205], v[8:11]
	s_setprio 0
	s_barrier
	s_add_u32 s58, s26, 0x40000
	s_addc_u32 s59, s27, 0
	s_add_i32 s57, s49, s34
	s_mov_b32 m0, s57
	s_nop 0
	global_load_lds_dwordx4 v146, s[58:59]
	s_add_i32 m0, s57, 0x2000
	s_nop 0
	global_load_lds_dwordx4 v142, s[58:59]
	s_add_u32 s28, s28, 0x40000
	s_addc_u32 s29, s29, 0
	s_mov_b32 m0, s39
	s_nop 0
	global_load_lds_dwordx4 v148, s[28:29]
	s_mov_b32 m0, s40
	s_nop 0
	global_load_lds_dwordx4 v144, s[28:29]
	s_waitcnt vmcnt(10)
	s_setprio 1
	s_barrier
	v_mfma_f32_16x16x32_bf16 v[52:55], v[206:209], v[170:173], v[52:55]
	v_mfma_f32_16x16x32_bf16 v[48:51], v[214:217], v[170:173], v[48:51]
	v_mfma_f32_16x16x32_bf16 v[36:39], v[206:209], v[178:181], v[36:39]
	v_mfma_f32_16x16x32_bf16 v[32:35], v[214:217], v[178:181], v[32:35]
	v_mfma_f32_16x16x32_bf16 v[20:23], v[206:209], v[186:189], v[20:23]
	v_mfma_f32_16x16x32_bf16 v[16:19], v[214:217], v[186:189], v[16:19]
	v_mfma_f32_16x16x32_bf16 v[4:7], v[206:209], v[194:197], v[4:7]
	v_mfma_f32_16x16x32_bf16 v[0:3], v[214:217], v[194:197], v[0:3]
	v_mfma_f32_16x16x32_bf16 v[52:55], v[210:213], v[174:177], v[52:55]
	v_mfma_f32_16x16x32_bf16 v[48:51], v[218:221], v[174:177], v[48:51]
	v_mfma_f32_16x16x32_bf16 v[36:39], v[210:213], v[182:185], v[36:39]
	v_mfma_f32_16x16x32_bf16 v[32:35], v[218:221], v[182:185], v[32:35]
	v_mfma_f32_16x16x32_bf16 v[20:23], v[210:213], v[190:193], v[20:23]
	v_mfma_f32_16x16x32_bf16 v[16:19], v[218:221], v[190:193], v[16:19]
	v_mfma_f32_16x16x32_bf16 v[4:7], v[210:213], v[202:205], v[4:7]
	v_mfma_f32_16x16x32_bf16 v[0:3], v[218:221], v[202:205], v[0:3]
	s_setprio 0
	s_add_i32 s57, 0, 0x18000
	v_add_u32_e32 v150, s57, v166
	s_barrier
	ds_read_b128 v[128:131], v150
	ds_read_b128 v[132:135], v150 offset:1024
	ds_read_b128 v[136:139], v150 offset:2048
	ds_read_b128 v[160:163], v150 offset:3072
	ds_read_b128 v[170:173], v168 offset:32768
	ds_read_b128 v[174:177], v168 offset:33792
	ds_read_b128 v[178:181], v168 offset:34816
	ds_read_b128 v[182:185], v168 offset:35840
	ds_read_b128 v[186:189], v168 offset:36864
	ds_read_b128 v[190:193], v168 offset:37888
	ds_read_b128 v[194:197], v168 offset:38912
	ds_read_b128 v[202:205], v168 offset:39936
	s_waitcnt lgkmcnt(8)
	s_waitcnt vmcnt(8)
	s_setprio 1
	s_barrier
; #define PG8_STAGE(bufoff, gbase, voff) do { _Pragma("unroll") for (int _i = 0; _i < 2; ++_i) \
;         __builtin_amdgcn_global_load_lds((const unsigned*)((const char*)(gbase) + (voff)[_i]), (LAS unsigned*)(lds + (bufoff) + ldsw + _i * 8192), 16, 0, 0); } while (0)
; #define PG8_LDA(dst, b, h) do { _Pragma("unroll") for (int m = 0; m < 4; ++m) _Pragma("unroll") for (int k = 0; k < 2; ++k) dst[m][k] = *(const LAS bf16x8*)(lds + PG8_SA(b, h) + aoff + m * 2048 + k * 1024); } while (0)
; #define PG8_LDB(dst, b, h) do { _Pragma("unroll") for (int n = 0; n < 2; ++n) _Pragma("unroll") for (int k = 0; k < 2; ++k) dst[n][k] = *(const LAS bf16x8*)(lds + PG8_SB(b, h) + boff + n * 2048 + k * 1024); } while (0)
; #define PG8_MMA(ai, bj, At, Bt) do { __builtin_amdgcn_s_setprio(1); _Pragma("unroll") for (int m = 0; m < 4; ++m) _Pragma("unroll") for (int n = 0; n < 2; ++n) _Pragma("unroll") for (int k = 0; k < 2; ++k) \
;         acc[ai][bj][m][n] = __builtin_amdgcn_mfma_f32_16x16x32_bf16(Bt[n][k], At[m][k], acc[ai][bj][m][n], 0, 0, 0); __builtin_amdgcn_s_setprio(0); } while (0)
; #define PG8_WAIT_L(n) asm volatile("s_waitcnt lgkmcnt(" #n ")" ::: "memory")
; #define PG8_BAR __builtin_amdgcn_s_barrier()
; #define PG8_SCHED __builtin_amdgcn_sched_barrier(0)
; template <class Epi, class Sched>
; __device__ __forceinline__ void gemm_phase(LAS unsigned char* lds, const Gemm g, const Sched& S, const Epi& E) {
;     ...
;             PG8_WAIT_L(8); PG8_BAR; PG8_WAIT_L(0); PG8_MMA(0, 0, At, B0); PG8_BAR; PG8_SCHED;
;             PG8_LDB(B1, 1, 1); PG8_STAGE(PG8_SB(1, 0), b3, voffB);
;             PG8_BAR; PG8_WAIT_L(0); PG8_MMA(0, 1, At, B1); PG8_BAR;
;             PG8_LDA(At, 1, 1); PG8_STAGE(PG8_SA(1, 0), a3, voffA);
	s_waitcnt lgkmcnt(0)
	s_waitcnt lgkmcnt(0)
	v_mfma_f32_16x16x32_bf16 v[124:127], v[128:131], v[170:173], v[124:127]
	v_mfma_f32_16x16x32_bf16 v[120:123], v[136:139], v[170:173], v[120:123]
	v_mfma_f32_16x16x32_bf16 v[108:111], v[128:131], v[178:181], v[108:111]
	v_mfma_f32_16x16x32_bf16 v[104:107], v[136:139], v[178:181], v[104:107]
	v_mfma_f32_16x16x32_bf16 v[92:95], v[128:131], v[186:189], v[92:95]
	v_mfma_f32_16x16x32_bf16 v[88:91], v[136:139], v[186:189], v[88:91]
	v_mfma_f32_16x16x32_bf16 v[76:79], v[128:131], v[194:197], v[76:79]
	v_mfma_f32_16x16x32_bf16 v[72:75], v[136:139], v[194:197], v[72:75]
	v_mfma_f32_16x16x32_bf16 v[124:127], v[132:135], v[174:177], v[124:127]
	v_mfma_f32_16x16x32_bf16 v[120:123], v[160:163], v[174:177], v[120:123]
	v_mfma_f32_16x16x32_bf16 v[108:111], v[132:135], v[182:185], v[108:111]
	v_mfma_f32_16x16x32_bf16 v[104:107], v[160:163], v[182:185], v[104:107]
	v_mfma_f32_16x16x32_bf16 v[92:95], v[132:135], v[190:193], v[92:95]
	v_mfma_f32_16x16x32_bf16 v[88:91], v[160:163], v[190:193], v[88:91]
	v_mfma_f32_16x16x32_bf16 v[76:79], v[132:135], v[202:205], v[76:79]
	v_mfma_f32_16x16x32_bf16 v[72:75], v[160:163], v[202:205], v[72:75]
	s_setprio 0
	s_barrier
	s_add_i32 s28, 0, 0x1c000
	s_add_i32 s29, s57, s34
	v_add_u32_e32 v150, s28, v166
	s_add_u32 s0, s26, 0x80
	s_addc_u32 s1, s27, 0
	s_mov_b32 m0, s29
	ds_read_b128 v[206:209], v150
	ds_read_b128 v[210:213], v150 offset:1024
	ds_read_b128 v[214:217], v150 offset:2048
	ds_read_b128 v[218:221], v150 offset:3072
	global_load_lds_dwordx4 v146, s[0:1]
	s_add_i32 m0, s29, 0x2000
	s_nop 0
	global_load_lds_dwordx4 v142, s[0:1]
	s_waitcnt vmcnt(8)
	s_setprio 1
	s_barrier
	s_waitcnt lgkmcnt(0)
	s_waitcnt lgkmcnt(0)
	v_mfma_f32_16x16x32_bf16 v[116:119], v[206:209], v[170:173], v[116:119]
	v_mfma_f32_16x16x32_bf16 v[112:115], v[214:217], v[170:173], v[112:115]
	v_mfma_f32_16x16x32_bf16 v[100:103], v[206:209], v[178:181], v[100:103]
	v_mfma_f32_16x16x32_bf16 v[96:99], v[214:217], v[178:181], v[96:99]
	v_mfma_f32_16x16x32_bf16 v[84:87], v[206:209], v[186:189], v[84:87]
	v_mfma_f32_16x16x32_bf16 v[80:83], v[214:217], v[186:189], v[80:83]
	v_mfma_f32_16x16x32_bf16 v[68:71], v[206:209], v[194:197], v[68:71]
	v_mfma_f32_16x16x32_bf16 v[64:67], v[214:217], v[194:197], v[64:67]
	v_mfma_f32_16x16x32_bf16 v[116:119], v[210:213], v[174:177], v[116:119]
	v_mfma_f32_16x16x32_bf16 v[112:115], v[218:221], v[174:177], v[112:115]
	v_mfma_f32_16x16x32_bf16 v[100:103], v[210:213], v[182:185], v[100:103]
	v_mfma_f32_16x16x32_bf16 v[96:99], v[218:221], v[182:185], v[96:99]
	v_mfma_f32_16x16x32_bf16 v[84:87], v[210:213], v[190:193], v[84:87]
	v_mfma_f32_16x16x32_bf16 v[80:83], v[218:221], v[190:193], v[80:83]
	v_mfma_f32_16x16x32_bf16 v[68:71], v[210:213], v[202:205], v[68:71]
	v_mfma_f32_16x16x32_bf16 v[64:67], v[218:221], v[202:205], v[64:67]
	s_setprio 0
	s_mov_b32 m0, s44
	s_mov_b64 s[0:1], 0x80
	v_lshl_add_u64 v[140:141], v[222:223], 0, s[0:1]
	s_barrier
	ds_read_b128 v[170:173], v168 offset:49152
	ds_read_b128 v[174:177], v168 offset:50176
	ds_read_b128 v[178:181], v168 offset:51200
	ds_read_b128 v[182:185], v168 offset:52224
	ds_read_b128 v[186:189], v168 offset:53248
	ds_read_b128 v[190:193], v168 offset:54272
	ds_read_b128 v[194:197], v168 offset:55296
	ds_read_b128 v[202:205], v168 offset:56320
	global_load_lds_dwordx4 v[140:141], off
	v_lshl_add_u64 v[140:141], v[224:225], 0, s[0:1]
	s_mov_b32 m0, s45
	s_nop 0
	global_load_lds_dwordx4 v[140:141], off
	s_setprio 1
	s_barrier
; #define PG8_STAGE(bufoff, gbase, voff) do { _Pragma("unroll") for (int _i = 0; _i < 2; ++_i) \
;         __builtin_amdgcn_global_load_lds((const unsigned*)((const char*)(gbase) + (voff)[_i]), (LAS unsigned*)(lds + (bufoff) + ldsw + _i * 8192), 16, 0, 0); } while (0)
; #define PG8_MMA(ai, bj, At, Bt) do { __builtin_amdgcn_s_setprio(1); _Pragma("unroll") for (int m = 0; m < 4; ++m) _Pragma("unroll") for (int n = 0; n < 2; ++n) _Pragma("unroll") for (int k = 0; k < 2; ++k) \
;         acc[ai][bj][m][n] = __builtin_amdgcn_mfma_f32_16x16x32_bf16(Bt[n][k], At[m][k], acc[ai][bj][m][n], 0, 0, 0); __builtin_amdgcn_s_setprio(0); } while (0)
; #define PG8_WAIT_V(n) asm volatile("s_waitcnt vmcnt(" #n ")" ::: "memory")
; #define PG8_WAIT_L(n) asm volatile("s_waitcnt lgkmcnt(" #n ")" ::: "memory")
; #define PG8_BAR __builtin_amdgcn_s_barrier()
; #define PG8_SCHED __builtin_amdgcn_sched_barrier(0)
; template <class Epi, class Sched>
; __device__ __forceinline__ void gemm_phase(LAS unsigned char* lds, const Gemm g, const Sched& S, const Epi& E) {
;     ...
;             PG8_BAR; PG8_WAIT_L(0); PG8_MMA(1, 0, At, B0); PG8_BAR; PG8_SCHED;
;             PG8_STAGE(PG8_SB(1, 1), b3 + hstep, voffB);
;             PG8_WAIT_V(6); PG8_BAR; PG8_MMA(1, 1, At, B1); PG8_BAR;
;     __device__ __forceinline__ void operator()(const AccT& acc, const Unit& u, int wr, int wc, int fr, int fq) const {
;         asm volatile("" : "+v"(fr), "+v"(fq));
;         const int row0 = u.pm * 256 + wr * 64 + fr, col0 = u.pn * 256 + wc * 32 + 8 * fq;
;         const bool rope = u.pn < 2;
;         const int i = 4 * (wc & 1) + fq;
; #pragma unroll
;         for (int ai = 0; ai < 2; ++ai)
; #pragma unroll
;             for (int m = 0; m < 4; ++m) {
;                 const int row = row0 + ai * 128 + m * 16;
;                 f32x4 cs = {1.f, 1.f, 1.f, 1.f}, sn = {0.f, 0.f, 0.f, 0.f};
;                 if (rope) { const int t = row & 2047; const int pos = (i < 4) ? (t >> 6) : (t & 63);
;                     cs = *(const f32x4*)(ropeA + pos * 16 + ((4 * i) & 15)); sn = *(const f32x4*)(ropeA + 1024 + pos * 16 + ((4 * i) & 15)); }
	s_waitcnt lgkmcnt(0)
	s_waitcnt lgkmcnt(0)
	v_mfma_f32_16x16x32_bf16 v[60:63], v[128:131], v[170:173], v[60:63]
	v_mfma_f32_16x16x32_bf16 v[56:59], v[136:139], v[170:173], v[56:59]
	v_mfma_f32_16x16x32_bf16 v[44:47], v[128:131], v[178:181], v[44:47]
	v_mfma_f32_16x16x32_bf16 v[40:43], v[136:139], v[178:181], v[40:43]
	v_mfma_f32_16x16x32_bf16 v[28:31], v[128:131], v[186:189], v[28:31]
	v_mfma_f32_16x16x32_bf16 v[24:27], v[136:139], v[186:189], v[24:27]
	v_mfma_f32_16x16x32_bf16 v[12:15], v[128:131], v[194:197], v[12:15]
	v_mfma_f32_16x16x32_bf16 v[8:11], v[136:139], v[194:197], v[8:11]
	v_mfma_f32_16x16x32_bf16 v[60:63], v[132:135], v[174:177], v[60:63]
	v_mfma_f32_16x16x32_bf16 v[56:59], v[160:163], v[174:177], v[56:59]
	v_mfma_f32_16x16x32_bf16 v[44:47], v[132:135], v[182:185], v[44:47]
	v_mfma_f32_16x16x32_bf16 v[40:43], v[160:163], v[182:185], v[40:43]
	v_mfma_f32_16x16x32_bf16 v[28:31], v[132:135], v[190:193], v[28:31]
	v_mfma_f32_16x16x32_bf16 v[24:27], v[160:163], v[190:193], v[24:27]
	v_mfma_f32_16x16x32_bf16 v[12:15], v[132:135], v[202:205], v[12:15]
	v_mfma_f32_16x16x32_bf16 v[8:11], v[160:163], v[202:205], v[8:11]
	s_setprio 0
	s_barrier
	s_add_u32 s26, s26, 0x40080
	s_addc_u32 s27, s27, 0
	s_add_i32 s28, s28, s34
	s_mov_b32 m0, s28
	s_nop 0
	global_load_lds_dwordx4 v146, s[26:27]
	s_add_i32 m0, s28, 0x2000
	s_nop 0
	global_load_lds_dwordx4 v142, s[26:27]
	s_waitcnt vmcnt(8)
	s_setprio 1
	s_barrier
	v_mfma_f32_16x16x32_bf16 v[52:55], v[206:209], v[170:173], v[52:55]
	v_mfma_f32_16x16x32_bf16 v[48:51], v[214:217], v[170:173], v[48:51]
	v_mfma_f32_16x16x32_bf16 v[36:39], v[206:209], v[178:181], v[36:39]
	v_mfma_f32_16x16x32_bf16 v[32:35], v[214:217], v[178:181], v[32:35]
	v_mfma_f32_16x16x32_bf16 v[20:23], v[206:209], v[186:189], v[20:23]
	v_mfma_f32_16x16x32_bf16 v[16:19], v[214:217], v[186:189], v[16:19]
	v_mfma_f32_16x16x32_bf16 v[4:7], v[206:209], v[194:197], v[4:7]
	v_mfma_f32_16x16x32_bf16 v[0:3], v[214:217], v[194:197], v[0:3]
	v_mfma_f32_16x16x32_bf16 v[52:55], v[210:213], v[174:177], v[52:55]
	v_mfma_f32_16x16x32_bf16 v[48:51], v[218:221], v[174:177], v[48:51]
	v_mfma_f32_16x16x32_bf16 v[36:39], v[210:213], v[182:185], v[36:39]
	v_mfma_f32_16x16x32_bf16 v[32:35], v[218:221], v[182:185], v[32:35]
	v_mfma_f32_16x16x32_bf16 v[20:23], v[210:213], v[190:193], v[20:23]
	v_mfma_f32_16x16x32_bf16 v[16:19], v[218:221], v[190:193], v[16:19]
	v_mfma_f32_16x16x32_bf16 v[4:7], v[210:213], v[202:205], v[4:7]
	v_mfma_f32_16x16x32_bf16 v[0:3], v[218:221], v[202:205], v[0:3]
	s_setprio 0
	s_add_i32 s56, s56, 2
	s_add_u32 s6, s6, 0x100
	s_addc_u32 s7, s7, 0
	s_add_u32 s54, s54, 0x100
	s_addc_u32 s55, s55, 0
	s_cmp_gt_u32 s56, 13
	s_barrier
	s_cbranch_scc0 .LBB0_578
	v_mov_b32_e32 v129, v165
	v_mov_b32_e32 v173, v164
	s_lshl_b32 s4, s4, 8
	s_add_i32 s4, s4, s42
	v_add_u32_e32 v128, s46, v129
	v_add_u32_e32 v170, s4, v173
	v_cmp_gt_i32_e64 s[4:5], 4, v128
	v_lshlrev_b32_e32 v128, 2, v128
	s_cmp_lt_i32 s52, 2
	v_and_b32_e32 v130, 12, v128
	s_cselect_b64 s[26:27], -1, 0
	s_cmp_gt_i32 s52, 1
	v_and_b32_e32 v172, 63, v173
	v_mov_b32_e32 v128, 1.0
	v_mov_b32_e32 v132, 0
	v_lshlrev_b32_e32 v162, 2, v130
	v_mov_b32_e32 v134, 0
	v_mov_b32_e32 v135, 0
	v_mov_b32_e32 v136, 0
	v_mov_b32_e32 v137, 0
	v_mov_b32_e32 v138, 1.0
	v_mov_b32_e32 v139, 1.0
	v_mov_b32_e32 v140, 1.0
	v_mov_b32_e32 v141, 1.0
	s_cbranch_scc1 .LBB0_581
	v_bfe_u32 v130, v170, 6, 5
	v_cndmask_b32_e64 v130, v172, v130, s[4:5]
	v_lshlrev_b32_e32 v150, 6, v130
	v_lshl_add_u64 v[130:131], s[16:17], 0, v[150:151]
	v_mov_b32_e32 v163, v151
	v_lshl_add_u64 v[134:135], s[8:9], 0, v[150:151]
	v_lshl_add_u64 v[130:131], v[130:131], 0, v[162:163]
	v_lshl_add_u64 v[134:135], v[134:135], 0, v[162:163]
	global_load_dwordx4 v[138:141], v[130:131], off
	s_nop 0
	global_load_dwordx4 v[134:137], v[134:135], off
	s_waitcnt vmcnt(0)

; #define PG8_STAGE(bufoff, gbase, voff) do { _Pragma("unroll") for (int _i = 0; _i < 2; ++_i) \
;         __builtin_amdgcn_global_load_lds((const unsigned*)((const char*)(gbase) + (voff)[_i]), (LAS unsigned*)(lds + (bufoff) + ldsw + _i * 8192), 16, 0, 0); } while (0)
; #define PG8_LDA(dst, b, h) do { _Pragma("unroll") for (int m = 0; m < 4; ++m) _Pragma("unroll") for (int k = 0; k < 2; ++k) dst[m][k] = *(const LAS bf16x8*)(lds + PG8_SA(b, h) + aoff + m * 2048 + k * 1024); } while (0)
; #define PG8_LDB(dst, b, h) do { _Pragma("unroll") for (int n = 0; n < 2; ++n) _Pragma("unroll") for (int k = 0; k < 2; ++k) dst[n][k] = *(const LAS bf16x8*)(lds + PG8_SB(b, h) + boff + n * 2048 + k * 1024); } while (0)
; #define PG8_MMA(ai, bj, At, Bt) do { __builtin_amdgcn_s_setprio(1); _Pragma("unroll") for (int m = 0; m < 4; ++m) _Pragma("unroll") for (int n = 0; n < 2; ++n) _Pragma("unroll") for (int k = 0; k < 2; ++k) \
;         acc[ai][bj][m][n] = __builtin_amdgcn_mfma_f32_16x16x32_bf16(Bt[n][k], At[m][k], acc[ai][bj][m][n], 0, 0, 0); __builtin_amdgcn_s_setprio(0); } while (0)
; #define PG8_WAIT_L(n) asm volatile("s_waitcnt lgkmcnt(" #n ")" ::: "memory")
; template <class Epi, class Sched>
; __device__ __forceinline__ void gemm_phase(LAS unsigned char* lds, const Gemm g, const Sched& S, const Epi& E) {
;     ...
;         const bool has_next = S.next(ui + 1, nxt);
;         const char* nA = has_next ? (const char*)g.A + (size_t)nxt.pm * tstep : cA; const char* nB = has_next ? (const char*)g.Bt + (size_t)nxt.pn * tstep : cB;
;         for (int t = 0; t < nt; t += 2) {
;             const bool last = (t == nt - 2);
;             const char* a1 = cA + (size_t)(t + 1) * kstep;
;             const char* a2 = last ? nA : cA + (size_t)(t + 2) * kstep; const char* b2 = last ? nB : cB + (size_t)(t + 2) * kstep;
;             const char* a3 = a2 + kstep; const char* b3 = b2 + kstep;
;             PG8_LDB(B0, 0, 0); PG8_SCHED; PG8_LDA(At, 0, 0); PG8_STAGE(PG8_SA(1, 1), a1 + hstep, voffA);
;             PG8_WAIT_L(8); PG8_BAR; PG8_WAIT_L(0); PG8_MMA(0, 0, At, B0); PG8_BAR; PG8_SCHED;
;             PG8_LDB(B1, 0, 1); PG8_STAGE(PG8_SB(0, 0), b2, voffB);
;             PG8_BAR; PG8_WAIT_L(0); PG8_MMA(0, 1, At, B1); PG8_BAR;
;             PG8_LDA(At, 0, 1); PG8_STAGE(PG8_SA(0, 0), a2, voffA);
;             PG8_BAR; PG8_WAIT_L(0); PG8_MMA(1, 0, At, B0); PG8_BAR; PG8_SCHED;
.LBB0_612:
	s_ashr_i32 s35, s34, 31
	v_cmp_lt_i64_e32 vcc, s[6:7], v[142:143]
	s_lshl_b64 s[6:7], s[34:35], 19
	s_add_u32 s36, s40, s6
	s_addc_u32 s37, s41, s7
	s_and_b64 s[6:7], vcc, exec
	s_cselect_b32 s8, s37, s1
	s_cselect_b32 s9, s36, s0
	s_ashr_i32 s31, s30, 31
	s_lshl_b64 s[6:7], s[30:31], 19
	s_add_u32 s38, s96, s6
	s_addc_u32 s39, s97, s7
	s_and_b64 s[6:7], vcc, exec
	s_cselect_b32 s31, s39, s5
	s_cselect_b32 s35, s38, s4
	s_add_u32 s0, s0, 0x40080
	s_addc_u32 s1, s1, 0
	s_add_u32 s65, s4, 0x100
	s_addc_u32 s66, s5, 0
	s_mov_b32 s67, -2
	s_waitcnt lgkmcnt(0)
	ds_read_b128 v[146:149], v171
	ds_read_b128 v[150:153], v171 offset:1024
	ds_read_b128 v[154:157], v171 offset:2048
	ds_read_b128 v[158:161], v171 offset:3072
	s_add_u32 s4, s0, 0xfffc0080
	s_addc_u32 s5, s1, -1
	s_cmp_eq_u32 s67, 12
	s_cselect_b32 s7, s8, s5
	s_cselect_b32 s6, s9, s4
	s_cselect_b32 s5, s31, s66
	s_cselect_b32 s4, s35, s65
	s_add_i32 m0, s45, 0xc000
	ds_read_b128 v[162:165], v172
	ds_read_b128 v[178:181], v172 offset:1024
	ds_read_b128 v[182:185], v172 offset:2048
	ds_read_b128 v[186:189], v172 offset:3072
	ds_read_b128 v[190:193], v172 offset:4096
	ds_read_b128 v[194:197], v172 offset:5120
	ds_read_b128 v[202:205], v172 offset:6144
	ds_read_b128 v[206:209], v172 offset:7168
	global_load_lds_dwordx4 v138, s[0:1]
	s_add_i32 m0, s45, 0xe000
	s_nop 0
	global_load_lds_dwordx4 v140, s[0:1]
	s_waitcnt lgkmcnt(8)
	s_waitcnt vmcnt(8)
	s_setprio 1
	s_barrier
	s_waitcnt lgkmcnt(0)
	s_waitcnt lgkmcnt(0)
	v_mfma_f32_16x16x32_bf16 v[124:127], v[146:149], v[162:165], 0
	v_mfma_f32_16x16x32_bf16 v[120:123], v[154:157], v[162:165], 0
	v_mfma_f32_16x16x32_bf16 v[108:111], v[146:149], v[182:185], 0
	v_mfma_f32_16x16x32_bf16 v[104:107], v[154:157], v[182:185], 0
	v_mfma_f32_16x16x32_bf16 v[92:95], v[146:149], v[190:193], 0
	v_mfma_f32_16x16x32_bf16 v[88:91], v[154:157], v[190:193], 0
	v_mfma_f32_16x16x32_bf16 v[76:79], v[146:149], v[202:205], 0
	v_mfma_f32_16x16x32_bf16 v[72:75], v[154:157], v[202:205], 0
	v_mfma_f32_16x16x32_bf16 v[124:127], v[150:153], v[178:181], v[124:127]
	v_mfma_f32_16x16x32_bf16 v[120:123], v[158:161], v[178:181], v[120:123]
	v_mfma_f32_16x16x32_bf16 v[108:111], v[150:153], v[186:189], v[108:111]
	v_mfma_f32_16x16x32_bf16 v[104:107], v[158:161], v[186:189], v[104:107]
	v_mfma_f32_16x16x32_bf16 v[92:95], v[150:153], v[194:197], v[92:95]
	v_mfma_f32_16x16x32_bf16 v[88:91], v[158:161], v[194:197], v[88:91]
	v_mfma_f32_16x16x32_bf16 v[76:79], v[150:153], v[206:209], v[76:79]
	v_mfma_f32_16x16x32_bf16 v[72:75], v[158:161], v[206:209], v[72:75]
	s_setprio 0
	s_barrier
	s_add_i32 s68, s57, s44
	s_mov_b32 m0, s68
	ds_read_b128 v[210:213], v173
	ds_read_b128 v[214:217], v173 offset:1024
	ds_read_b128 v[218:221], v173 offset:2048
	ds_read_b128 v[222:225], v173 offset:3072
	global_load_lds_dwordx4 v130, s[4:5]
	s_add_i32 m0, s68, 0x2000
	s_nop 0
	global_load_lds_dwordx4 v134, s[4:5]
	s_waitcnt vmcnt(8)
	s_setprio 1
	s_barrier
	s_waitcnt lgkmcnt(0)
	s_waitcnt lgkmcnt(0)
	v_mfma_f32_16x16x32_bf16 v[116:119], v[210:213], v[162:165], 0
	v_mfma_f32_16x16x32_bf16 v[112:115], v[218:221], v[162:165], 0
	v_mfma_f32_16x16x32_bf16 v[100:103], v[210:213], v[182:185], 0
	v_mfma_f32_16x16x32_bf16 v[96:99], v[218:221], v[182:185], 0
	v_mfma_f32_16x16x32_bf16 v[84:87], v[210:213], v[190:193], 0
	v_mfma_f32_16x16x32_bf16 v[80:83], v[218:221], v[190:193], 0
	v_mfma_f32_16x16x32_bf16 v[68:71], v[210:213], v[202:205], 0
	v_mfma_f32_16x16x32_bf16 v[64:67], v[218:221], v[202:205], 0
	v_mfma_f32_16x16x32_bf16 v[116:119], v[214:217], v[178:181], v[116:119]
	v_mfma_f32_16x16x32_bf16 v[112:115], v[222:225], v[178:181], v[112:115]
	v_mfma_f32_16x16x32_bf16 v[100:103], v[214:217], v[186:189], v[100:103]
	v_mfma_f32_16x16x32_bf16 v[96:99], v[222:225], v[186:189], v[96:99]
	v_mfma_f32_16x16x32_bf16 v[84:87], v[214:217], v[194:197], v[84:87]
	v_mfma_f32_16x16x32_bf16 v[80:83], v[222:225], v[194:197], v[80:83]
	v_mfma_f32_16x16x32_bf16 v[68:71], v[214:217], v[206:209], v[68:71]
	v_mfma_f32_16x16x32_bf16 v[64:67], v[222:225], v[206:209], v[64:67]
	s_setprio 0
	s_mov_b32 m0, s45
	v_lshl_add_u64 v[226:227], s[6:7], 0, v[128:129]
	s_barrier
	ds_read_b128 v[162:165], v172 offset:16384
	ds_read_b128 v[178:181], v172 offset:17408
	ds_read_b128 v[182:185], v172 offset:18432
	ds_read_b128 v[186:189], v172 offset:19456
	ds_read_b128 v[190:193], v172 offset:20480
	ds_read_b128 v[194:197], v172 offset:21504
	ds_read_b128 v[202:205], v172 offset:22528
	ds_read_b128 v[206:209], v172 offset:23552
	global_load_lds_dwordx4 v128, s[6:7]
	v_lshl_add_u64 v[228:229], s[6:7], 0, v[132:133]
	s_mov_b32 m0, s46
	s_nop 0
	global_load_lds_dwordx4 v132, s[6:7]
	s_setprio 1
	s_barrier
	s_waitcnt lgkmcnt(0)
	s_waitcnt lgkmcnt(0)
	v_mfma_f32_16x16x32_bf16 v[60:63], v[146:149], v[162:165], 0
	v_mfma_f32_16x16x32_bf16 v[56:59], v[154:157], v[162:165], 0
	v_mfma_f32_16x16x32_bf16 v[44:47], v[146:149], v[182:185], 0
	v_mfma_f32_16x16x32_bf16 v[40:43], v[154:157], v[182:185], 0
	v_mfma_f32_16x16x32_bf16 v[28:31], v[146:149], v[190:193], 0
	v_mfma_f32_16x16x32_bf16 v[24:27], v[154:157], v[190:193], 0
	v_mfma_f32_16x16x32_bf16 v[12:15], v[146:149], v[202:205], 0
	v_mfma_f32_16x16x32_bf16 v[8:11], v[154:157], v[202:205], 0
	v_mfma_f32_16x16x32_bf16 v[60:63], v[150:153], v[178:181], v[60:63]
	v_mfma_f32_16x16x32_bf16 v[56:59], v[158:161], v[178:181], v[56:59]
	v_mfma_f32_16x16x32_bf16 v[44:47], v[150:153], v[186:189], v[44:47]
	v_mfma_f32_16x16x32_bf16 v[40:43], v[158:161], v[186:189], v[40:43]
	v_mfma_f32_16x16x32_bf16 v[28:31], v[150:153], v[194:197], v[28:31]
	v_mfma_f32_16x16x32_bf16 v[24:27], v[158:161], v[194:197], v[24:27]
	v_mfma_f32_16x16x32_bf16 v[12:15], v[150:153], v[206:209], v[12:15]
	v_mfma_f32_16x16x32_bf16 v[8:11], v[158:161], v[206:209], v[8:11]
	s_setprio 0
	s_barrier
; #define PG8_STAGE(bufoff, gbase, voff) do { _Pragma("unroll") for (int _i = 0; _i < 2; ++_i) \
;         __builtin_amdgcn_global_load_lds((const unsigned*)((const char*)(gbase) + (voff)[_i]), (LAS unsigned*)(lds + (bufoff) + ldsw + _i * 8192), 16, 0, 0); } while (0)
; #define PG8_LDA(dst, b, h) do { _Pragma("unroll") for (int m = 0; m < 4; ++m) _Pragma("unroll") for (int k = 0; k < 2; ++k) dst[m][k] = *(const LAS bf16x8*)(lds + PG8_SA(b, h) + aoff + m * 2048 + k * 1024); } while (0)
; #define PG8_LDB(dst, b, h) do { _Pragma("unroll") for (int n = 0; n < 2; ++n) _Pragma("unroll") for (int k = 0; k < 2; ++k) dst[n][k] = *(const LAS bf16x8*)(lds + PG8_SB(b, h) + boff + n * 2048 + k * 1024); } while (0)
; #define PG8_MMA(ai, bj, At, Bt) do { __builtin_amdgcn_s_setprio(1); _Pragma("unroll") for (int m = 0; m < 4; ++m) _Pragma("unroll") for (int n = 0; n < 2; ++n) _Pragma("unroll") for (int k = 0; k < 2; ++k) \
;         acc[ai][bj][m][n] = __builtin_amdgcn_mfma_f32_16x16x32_bf16(Bt[n][k], At[m][k], acc[ai][bj][m][n], 0, 0, 0); __builtin_amdgcn_s_setprio(0); } while (0)
; #define PG8_WAIT_V(n) asm volatile("s_waitcnt vmcnt(" #n ")" ::: "memory")
; #define PG8_WAIT_L(n) asm volatile("s_waitcnt lgkmcnt(" #n ")" ::: "memory")
; #define PG8_BAR __builtin_amdgcn_s_barrier()
; #define PG8_SCHED __builtin_amdgcn_sched_barrier(0)
; template <class Epi, class Sched>
; __device__ __forceinline__ void gemm_phase(LAS unsigned char* lds, const Gemm g, const Sched& S, const Epi& E) {
;     ...
;             PG8_STAGE(PG8_SB(0, 1), b2 + hstep, voffB);
;             PG8_WAIT_V(6); PG8_BAR; PG8_MMA(1, 1, At, B1); PG8_BAR;
;             PG8_LDB(B0, 1, 0); PG8_SCHED; PG8_LDA(At, 1, 0); PG8_STAGE(PG8_SA(0, 1), a2 + hstep, voffA);
;             PG8_WAIT_L(8); PG8_BAR; PG8_WAIT_L(0); PG8_MMA(0, 0, At, B0); PG8_BAR; PG8_SCHED;
;             PG8_LDB(B1, 1, 1); PG8_STAGE(PG8_SB(1, 0), b3, voffB);
;             PG8_BAR; PG8_WAIT_L(0); PG8_MMA(0, 1, At, B1); PG8_BAR;
;             PG8_LDA(At, 1, 1); PG8_STAGE(PG8_SA(1, 0), a3, voffA);
	s_add_u32 s68, s4, 0x40000
	s_addc_u32 s69, s5, 0
	s_add_i32 s70, s58, s44
	s_mov_b32 m0, s70
	s_nop 0
	global_load_lds_dwordx4 v130, s[68:69]
	s_add_i32 m0, s70, 0x2000
	s_nop 0
	global_load_lds_dwordx4 v134, s[68:69]
	s_add_u32 s6, s6, 0x40000
	s_addc_u32 s7, s7, 0
	s_mov_b32 m0, s47
	s_nop 0
	global_load_lds_dwordx4 v128, s[6:7]
	s_mov_b32 m0, s48
	s_nop 0
	global_load_lds_dwordx4 v132, s[6:7]
	s_waitcnt vmcnt(10)
	s_setprio 1
	s_barrier
	v_mfma_f32_16x16x32_bf16 v[52:55], v[210:213], v[162:165], 0
	v_mfma_f32_16x16x32_bf16 v[48:51], v[218:221], v[162:165], 0
	v_mfma_f32_16x16x32_bf16 v[36:39], v[210:213], v[182:185], 0
	v_mfma_f32_16x16x32_bf16 v[32:35], v[218:221], v[182:185], 0
	v_mfma_f32_16x16x32_bf16 v[20:23], v[210:213], v[190:193], 0
	v_mfma_f32_16x16x32_bf16 v[16:19], v[218:221], v[190:193], 0
	v_mfma_f32_16x16x32_bf16 v[4:7], v[210:213], v[202:205], 0
	v_mfma_f32_16x16x32_bf16 v[0:3], v[218:221], v[202:205], 0
	v_mfma_f32_16x16x32_bf16 v[52:55], v[214:217], v[178:181], v[52:55]
	v_mfma_f32_16x16x32_bf16 v[48:51], v[222:225], v[178:181], v[48:51]
	v_mfma_f32_16x16x32_bf16 v[36:39], v[214:217], v[186:189], v[36:39]
	v_mfma_f32_16x16x32_bf16 v[32:35], v[222:225], v[186:189], v[32:35]
	v_mfma_f32_16x16x32_bf16 v[20:23], v[214:217], v[194:197], v[20:23]
	v_mfma_f32_16x16x32_bf16 v[16:19], v[222:225], v[194:197], v[16:19]
	v_mfma_f32_16x16x32_bf16 v[4:7], v[214:217], v[206:209], v[4:7]
	v_mfma_f32_16x16x32_bf16 v[0:3], v[222:225], v[206:209], v[0:3]
	s_setprio 0
	s_add_i32 s68, 0, 0x18000
	v_add_u32_e32 v136, s68, v170
	s_barrier
	ds_read_b128 v[146:149], v136
	ds_read_b128 v[150:153], v136 offset:1024
	ds_read_b128 v[154:157], v136 offset:2048
	ds_read_b128 v[158:161], v136 offset:3072
	ds_read_b128 v[162:165], v172 offset:32768
	ds_read_b128 v[178:181], v172 offset:33792
	ds_read_b128 v[182:185], v172 offset:34816
	ds_read_b128 v[186:189], v172 offset:35840
	ds_read_b128 v[190:193], v172 offset:36864
	ds_read_b128 v[194:197], v172 offset:37888
	ds_read_b128 v[202:205], v172 offset:38912
	ds_read_b128 v[206:209], v172 offset:39936
	s_waitcnt lgkmcnt(8)
	s_waitcnt vmcnt(8)
	s_setprio 1
	s_barrier
	s_waitcnt lgkmcnt(0)
	s_waitcnt lgkmcnt(0)
	v_mfma_f32_16x16x32_bf16 v[124:127], v[146:149], v[162:165], v[124:127]
	v_mfma_f32_16x16x32_bf16 v[120:123], v[154:157], v[162:165], v[120:123]
	v_mfma_f32_16x16x32_bf16 v[108:111], v[146:149], v[182:185], v[108:111]
	v_mfma_f32_16x16x32_bf16 v[104:107], v[154:157], v[182:185], v[104:107]
	v_mfma_f32_16x16x32_bf16 v[92:95], v[146:149], v[190:193], v[92:95]
	v_mfma_f32_16x16x32_bf16 v[88:91], v[154:157], v[190:193], v[88:91]
	v_mfma_f32_16x16x32_bf16 v[76:79], v[146:149], v[202:205], v[76:79]
	v_mfma_f32_16x16x32_bf16 v[72:75], v[154:157], v[202:205], v[72:75]
	v_mfma_f32_16x16x32_bf16 v[124:127], v[150:153], v[178:181], v[124:127]
	v_mfma_f32_16x16x32_bf16 v[120:123], v[158:161], v[178:181], v[120:123]
	v_mfma_f32_16x16x32_bf16 v[108:111], v[150:153], v[186:189], v[108:111]
	v_mfma_f32_16x16x32_bf16 v[104:107], v[158:161], v[186:189], v[104:107]
	v_mfma_f32_16x16x32_bf16 v[92:95], v[150:153], v[194:197], v[92:95]
	v_mfma_f32_16x16x32_bf16 v[88:91], v[158:161], v[194:197], v[88:91]
	v_mfma_f32_16x16x32_bf16 v[76:79], v[150:153], v[206:209], v[76:79]
	v_mfma_f32_16x16x32_bf16 v[72:75], v[158:161], v[206:209], v[72:75]
	s_setprio 0
	s_barrier
	s_add_i32 s6, 0, 0x1c000
	s_add_i32 s7, s68, s44
	v_add_u32_e32 v136, s6, v170
	s_add_u32 s20, s4, 0x80
	s_addc_u32 s21, s5, 0
	s_mov_b32 m0, s7
	ds_read_b128 v[210:213], v136
	ds_read_b128 v[214:217], v136 offset:1024
	ds_read_b128 v[218:221], v136 offset:2048
	ds_read_b128 v[222:225], v136 offset:3072
	global_load_lds_dwordx4 v130, s[20:21]
	s_add_i32 m0, s7, 0x2000
	s_nop 0
	global_load_lds_dwordx4 v134, s[20:21]
	s_waitcnt vmcnt(8)
	s_setprio 1
	s_barrier
	s_waitcnt lgkmcnt(0)
	s_waitcnt lgkmcnt(0)
	v_mfma_f32_16x16x32_bf16 v[116:119], v[210:213], v[162:165], v[116:119]
	v_mfma_f32_16x16x32_bf16 v[112:115], v[218:221], v[162:165], v[112:115]
	v_mfma_f32_16x16x32_bf16 v[100:103], v[210:213], v[182:185], v[100:103]
	v_mfma_f32_16x16x32_bf16 v[96:99], v[218:221], v[182:185], v[96:99]
	v_mfma_f32_16x16x32_bf16 v[84:87], v[210:213], v[190:193], v[84:87]
	v_mfma_f32_16x16x32_bf16 v[80:83], v[218:221], v[190:193], v[80:83]
	v_mfma_f32_16x16x32_bf16 v[68:71], v[210:213], v[202:205], v[68:71]
	v_mfma_f32_16x16x32_bf16 v[64:67], v[218:221], v[202:205], v[64:67]
	v_mfma_f32_16x16x32_bf16 v[116:119], v[214:217], v[178:181], v[116:119]
	v_mfma_f32_16x16x32_bf16 v[112:115], v[222:225], v[178:181], v[112:115]
	v_mfma_f32_16x16x32_bf16 v[100:103], v[214:217], v[186:189], v[100:103]
	v_mfma_f32_16x16x32_bf16 v[96:99], v[222:225], v[186:189], v[96:99]
	v_mfma_f32_16x16x32_bf16 v[84:87], v[214:217], v[194:197], v[84:87]
	v_mfma_f32_16x16x32_bf16 v[80:83], v[222:225], v[194:197], v[80:83]
	v_mfma_f32_16x16x32_bf16 v[68:71], v[214:217], v[206:209], v[68:71]
	v_mfma_f32_16x16x32_bf16 v[64:67], v[222:225], v[206:209], v[64:67]
	s_setprio 0
	s_mov_b32 m0, s54
	s_mov_b64 s[20:21], 0x80
	v_lshl_add_u64 v[166:167], v[226:227], 0, s[20:21]
	s_barrier
	ds_read_b128 v[162:165], v172 offset:49152
	ds_read_b128 v[178:181], v172 offset:50176
	ds_read_b128 v[182:185], v172 offset:51200
	ds_read_b128 v[186:189], v172 offset:52224
	ds_read_b128 v[190:193], v172 offset:53248
	ds_read_b128 v[194:197], v172 offset:54272
	ds_read_b128 v[202:205], v172 offset:55296
	ds_read_b128 v[206:209], v172 offset:56320
	global_load_lds_dwordx4 v[166:167], off
	v_lshl_add_u64 v[166:167], v[228:229], 0, s[20:21]
	s_mov_b32 m0, s55
	s_nop 0
	global_load_lds_dwordx4 v[166:167], off
	s_setprio 1
	s_barrier
; #define PG8_STAGE(bufoff, gbase, voff) do { _Pragma("unroll") for (int _i = 0; _i < 2; ++_i) \
;         __builtin_amdgcn_global_load_lds((const unsigned*)((const char*)(gbase) + (voff)[_i]), (LAS unsigned*)(lds + (bufoff) + ldsw + _i * 8192), 16, 0, 0); } while (0)
; #define PG8_LDA(dst, b, h) do { _Pragma("unroll") for (int m = 0; m < 4; ++m) _Pragma("unroll") for (int k = 0; k < 2; ++k) dst[m][k] = *(const LAS bf16x8*)(lds + PG8_SA(b, h) + aoff + m * 2048 + k * 1024); } while (0)
; #define PG8_LDB(dst, b, h) do { _Pragma("unroll") for (int n = 0; n < 2; ++n) _Pragma("unroll") for (int k = 0; k < 2; ++k) dst[n][k] = *(const LAS bf16x8*)(lds + PG8_SB(b, h) + boff + n * 2048 + k * 1024); } while (0)
; #define PG8_MMA(ai, bj, At, Bt) do { __builtin_amdgcn_s_setprio(1); _Pragma("unroll") for (int m = 0; m < 4; ++m) _Pragma("unroll") for (int n = 0; n < 2; ++n) _Pragma("unroll") for (int k = 0; k < 2; ++k) \
;         acc[ai][bj][m][n] = __builtin_amdgcn_mfma_f32_16x16x32_bf16(Bt[n][k], At[m][k], acc[ai][bj][m][n], 0, 0, 0); __builtin_amdgcn_s_setprio(0); } while (0)
; #define PG8_WAIT_V(n) asm volatile("s_waitcnt vmcnt(" #n ")" ::: "memory")
; #define PG8_WAIT_L(n) asm volatile("s_waitcnt lgkmcnt(" #n ")" ::: "memory")
; #define PG8_BAR __builtin_amdgcn_s_barrier()
; #define PG8_SCHED __builtin_amdgcn_sched_barrier(0)
; template <class Epi, class Sched>
; __device__ __forceinline__ void gemm_phase(LAS unsigned char* lds, const Gemm g, const Sched& S, const Epi& E) {
;     ...
;             PG8_LDB(B0, 0, 0); PG8_SCHED; PG8_LDA(At, 0, 0); PG8_STAGE(PG8_SA(1, 1), a1 + hstep, voffA);
;             PG8_WAIT_L(8); PG8_BAR; PG8_WAIT_L(0); PG8_MMA(0, 0, At, B0); PG8_BAR; PG8_SCHED;
;             PG8_LDB(B1, 0, 1); PG8_STAGE(PG8_SB(0, 0), b2, voffB);
;             PG8_BAR; PG8_WAIT_L(0); PG8_MMA(0, 1, At, B1); PG8_BAR;
;     ...
;             PG8_BAR; PG8_WAIT_L(0); PG8_MMA(1, 0, At, B0); PG8_BAR; PG8_SCHED;
;             PG8_STAGE(PG8_SB(1, 1), b3 + hstep, voffB);
;             PG8_WAIT_V(6); PG8_BAR; PG8_MMA(1, 1, At, B1); PG8_BAR;
	s_waitcnt lgkmcnt(0)
	s_waitcnt lgkmcnt(0)
	v_mfma_f32_16x16x32_bf16 v[60:63], v[146:149], v[162:165], v[60:63]
	v_mfma_f32_16x16x32_bf16 v[56:59], v[154:157], v[162:165], v[56:59]
	v_mfma_f32_16x16x32_bf16 v[44:47], v[146:149], v[182:185], v[44:47]
	v_mfma_f32_16x16x32_bf16 v[40:43], v[154:157], v[182:185], v[40:43]
	v_mfma_f32_16x16x32_bf16 v[28:31], v[146:149], v[190:193], v[28:31]
	v_mfma_f32_16x16x32_bf16 v[24:27], v[154:157], v[190:193], v[24:27]
	v_mfma_f32_16x16x32_bf16 v[12:15], v[146:149], v[202:205], v[12:15]
	v_mfma_f32_16x16x32_bf16 v[8:11], v[154:157], v[202:205], v[8:11]
	v_mfma_f32_16x16x32_bf16 v[60:63], v[150:153], v[178:181], v[60:63]
	v_mfma_f32_16x16x32_bf16 v[56:59], v[158:161], v[178:181], v[56:59]
	v_mfma_f32_16x16x32_bf16 v[44:47], v[150:153], v[186:189], v[44:47]
	v_mfma_f32_16x16x32_bf16 v[40:43], v[158:161], v[186:189], v[40:43]
	v_mfma_f32_16x16x32_bf16 v[28:31], v[150:153], v[194:197], v[28:31]
	v_mfma_f32_16x16x32_bf16 v[24:27], v[158:161], v[194:197], v[24:27]
	v_mfma_f32_16x16x32_bf16 v[12:15], v[150:153], v[206:209], v[12:15]
	v_mfma_f32_16x16x32_bf16 v[8:11], v[158:161], v[206:209], v[8:11]
	s_setprio 0
	s_barrier
	s_add_u32 s4, s4, 0x40080
	s_addc_u32 s5, s5, 0
	s_add_i32 s6, s6, s44
	s_mov_b32 m0, s6
	s_nop 0
	global_load_lds_dwordx4 v130, s[4:5]
	s_add_i32 m0, s6, 0x2000
	s_nop 0
	global_load_lds_dwordx4 v134, s[4:5]
	s_waitcnt vmcnt(8)
	s_setprio 1
	s_barrier
	v_mfma_f32_16x16x32_bf16 v[52:55], v[210:213], v[162:165], v[52:55]
	v_mfma_f32_16x16x32_bf16 v[48:51], v[218:221], v[162:165], v[48:51]
	v_mfma_f32_16x16x32_bf16 v[36:39], v[210:213], v[182:185], v[36:39]
	v_mfma_f32_16x16x32_bf16 v[32:35], v[218:221], v[182:185], v[32:35]
	v_mfma_f32_16x16x32_bf16 v[20:23], v[210:213], v[190:193], v[20:23]
	v_mfma_f32_16x16x32_bf16 v[16:19], v[218:221], v[190:193], v[16:19]
	v_mfma_f32_16x16x32_bf16 v[4:7], v[210:213], v[202:205], v[4:7]
	v_mfma_f32_16x16x32_bf16 v[0:3], v[218:221], v[202:205], v[0:3]
	v_mfma_f32_16x16x32_bf16 v[52:55], v[214:217], v[178:181], v[52:55]
	v_mfma_f32_16x16x32_bf16 v[48:51], v[222:225], v[178:181], v[48:51]
	v_mfma_f32_16x16x32_bf16 v[36:39], v[214:217], v[186:189], v[36:39]
	v_mfma_f32_16x16x32_bf16 v[32:35], v[222:225], v[186:189], v[32:35]
	v_mfma_f32_16x16x32_bf16 v[20:23], v[214:217], v[194:197], v[20:23]
	v_mfma_f32_16x16x32_bf16 v[16:19], v[222:225], v[194:197], v[16:19]
	v_mfma_f32_16x16x32_bf16 v[4:7], v[214:217], v[206:209], v[4:7]
	v_mfma_f32_16x16x32_bf16 v[0:3], v[222:225], v[206:209], v[0:3]
	s_setprio 0
	s_add_i32 s67, s67, 2
	s_add_u32 s0, s0, 0x100
	s_addc_u32 s1, s1, 0
	s_add_u32 s65, s65, 0x100
	s_addc_u32 s66, s66, 0
	s_cmp_gt_u32 s67, 13
	s_barrier
.LBB0_613:
	ds_read_b128 v[146:149], v171
	ds_read_b128 v[150:153], v171 offset:1024
	ds_read_b128 v[154:157], v171 offset:2048
	ds_read_b128 v[158:161], v171 offset:3072
	s_add_u32 s4, s0, 0xfffc0080
	s_addc_u32 s5, s1, -1
	s_cmp_eq_u32 s67, 12
	s_cselect_b32 s7, s8, s5
	s_cselect_b32 s6, s9, s4
	s_cselect_b32 s5, s31, s66
	s_cselect_b32 s4, s35, s65
	s_add_i32 m0, s45, 0xc000
	ds_read_b128 v[162:165], v172
	ds_read_b128 v[178:181], v172 offset:1024
	ds_read_b128 v[182:185], v172 offset:2048
	ds_read_b128 v[186:189], v172 offset:3072
	ds_read_b128 v[190:193], v172 offset:4096
	ds_read_b128 v[194:197], v172 offset:5120
	ds_read_b128 v[202:205], v172 offset:6144
	ds_read_b128 v[206:209], v172 offset:7168
	global_load_lds_dwordx4 v138, s[0:1]
	s_add_i32 m0, s45, 0xe000
	s_nop 0
	global_load_lds_dwordx4 v140, s[0:1]
	s_waitcnt lgkmcnt(8)
	s_waitcnt vmcnt(8)
	s_setprio 1
	s_barrier
	s_waitcnt lgkmcnt(0)
	s_waitcnt lgkmcnt(0)
	v_mfma_f32_16x16x32_bf16 v[124:127], v[146:149], v[162:165], v[124:127]
	v_mfma_f32_16x16x32_bf16 v[120:123], v[154:157], v[162:165], v[120:123]
	v_mfma_f32_16x16x32_bf16 v[108:111], v[146:149], v[182:185], v[108:111]
	v_mfma_f32_16x16x32_bf16 v[104:107], v[154:157], v[182:185], v[104:107]
	v_mfma_f32_16x16x32_bf16 v[92:95], v[146:149], v[190:193], v[92:95]
	v_mfma_f32_16x16x32_bf16 v[88:91], v[154:157], v[190:193], v[88:91]
	v_mfma_f32_16x16x32_bf16 v[76:79], v[146:149], v[202:205], v[76:79]
	v_mfma_f32_16x16x32_bf16 v[72:75], v[154:157], v[202:205], v[72:75]
	v_mfma_f32_16x16x32_bf16 v[124:127], v[150:153], v[178:181], v[124:127]
	v_mfma_f32_16x16x32_bf16 v[120:123], v[158:161], v[178:181], v[120:123]
	v_mfma_f32_16x16x32_bf16 v[108:111], v[150:153], v[186:189], v[108:111]
	v_mfma_f32_16x16x32_bf16 v[104:107], v[158:161], v[186:189], v[104:107]
	v_mfma_f32_16x16x32_bf16 v[92:95], v[150:153], v[194:197], v[92:95]
	v_mfma_f32_16x16x32_bf16 v[88:91], v[158:161], v[194:197], v[88:91]
	v_mfma_f32_16x16x32_bf16 v[76:79], v[150:153], v[206:209], v[76:79]
	v_mfma_f32_16x16x32_bf16 v[72:75], v[158:161], v[206:209], v[72:75]
	s_setprio 0
	s_barrier
	s_add_i32 s68, s57, s44
	s_mov_b32 m0, s68
	ds_read_b128 v[210:213], v173
	ds_read_b128 v[214:217], v173 offset:1024
	ds_read_b128 v[218:221], v173 offset:2048
	ds_read_b128 v[222:225], v173 offset:3072
	global_load_lds_dwordx4 v130, s[4:5]
	s_add_i32 m0, s68, 0x2000
	s_nop 0
	global_load_lds_dwordx4 v134, s[4:5]
	s_waitcnt vmcnt(8)
	s_setprio 1
	s_barrier
; #define PG8_STAGE(bufoff, gbase, voff) do { _Pragma("unroll") for (int _i = 0; _i < 2; ++_i) \
;         __builtin_amdgcn_global_load_lds((const unsigned*)((const char*)(gbase) + (voff)[_i]), (LAS unsigned*)(lds + (bufoff) + ldsw + _i * 8192), 16, 0, 0); } while (0)
; #define PG8_LDA(dst, b, h) do { _Pragma("unroll") for (int m = 0; m < 4; ++m) _Pragma("unroll") for (int k = 0; k < 2; ++k) dst[m][k] = *(const LAS bf16x8*)(lds + PG8_SA(b, h) + aoff + m * 2048 + k * 1024); } while (0)
; #define PG8_LDB(dst, b, h) do { _Pragma("unroll") for (int n = 0; n < 2; ++n) _Pragma("unroll") for (int k = 0; k < 2; ++k) dst[n][k] = *(const LAS bf16x8*)(lds + PG8_SB(b, h) + boff + n * 2048 + k * 1024); } while (0)
; #define PG8_MMA(ai, bj, At, Bt) do { __builtin_amdgcn_s_setprio(1); _Pragma("unroll") for (int m = 0; m < 4; ++m) _Pragma("unroll") for (int n = 0; n < 2; ++n) _Pragma("unroll") for (int k = 0; k < 2; ++k) \
;         acc[ai][bj][m][n] = __builtin_amdgcn_mfma_f32_16x16x32_bf16(Bt[n][k], At[m][k], acc[ai][bj][m][n], 0, 0, 0); __builtin_amdgcn_s_setprio(0); } while (0)
; #define PG8_WAIT_V(n) asm volatile("s_waitcnt vmcnt(" #n ")" ::: "memory")
; #define PG8_WAIT_L(n) asm volatile("s_waitcnt lgkmcnt(" #n ")" ::: "memory")
; #define PG8_BAR __builtin_amdgcn_s_barrier()
; #define PG8_SCHED __builtin_amdgcn_sched_barrier(0)
; template <class Epi, class Sched>
; __device__ __forceinline__ void gemm_phase(LAS unsigned char* lds, const Gemm g, const Sched& S, const Epi& E) {
;     ...
;             PG8_BAR; PG8_WAIT_L(0); PG8_MMA(0, 1, At, B1); PG8_BAR;
;             PG8_LDA(At, 0, 1); PG8_STAGE(PG8_SA(0, 0), a2, voffA);
;             PG8_BAR; PG8_WAIT_L(0); PG8_MMA(1, 0, At, B0); PG8_BAR; PG8_SCHED;
;             PG8_STAGE(PG8_SB(0, 1), b2 + hstep, voffB);
;             PG8_WAIT_V(6); PG8_BAR; PG8_MMA(1, 1, At, B1); PG8_BAR;
;             PG8_LDB(B0, 1, 0); PG8_SCHED; PG8_LDA(At, 1, 0); PG8_STAGE(PG8_SA(0, 1), a2 + hstep, voffA);
;             PG8_WAIT_L(8); PG8_BAR; PG8_WAIT_L(0); PG8_MMA(0, 0, At, B0); PG8_BAR; PG8_SCHED;
	s_waitcnt lgkmcnt(0)
	s_waitcnt lgkmcnt(0)
	v_mfma_f32_16x16x32_bf16 v[116:119], v[210:213], v[162:165], v[116:119]
	v_mfma_f32_16x16x32_bf16 v[112:115], v[218:221], v[162:165], v[112:115]
	v_mfma_f32_16x16x32_bf16 v[100:103], v[210:213], v[182:185], v[100:103]
	v_mfma_f32_16x16x32_bf16 v[96:99], v[218:221], v[182:185], v[96:99]
	v_mfma_f32_16x16x32_bf16 v[84:87], v[210:213], v[190:193], v[84:87]
	v_mfma_f32_16x16x32_bf16 v[80:83], v[218:221], v[190:193], v[80:83]
	v_mfma_f32_16x16x32_bf16 v[68:71], v[210:213], v[202:205], v[68:71]
	v_mfma_f32_16x16x32_bf16 v[64:67], v[218:221], v[202:205], v[64:67]
	v_mfma_f32_16x16x32_bf16 v[116:119], v[214:217], v[178:181], v[116:119]
	v_mfma_f32_16x16x32_bf16 v[112:115], v[222:225], v[178:181], v[112:115]
	v_mfma_f32_16x16x32_bf16 v[100:103], v[214:217], v[186:189], v[100:103]
	v_mfma_f32_16x16x32_bf16 v[96:99], v[222:225], v[186:189], v[96:99]
	v_mfma_f32_16x16x32_bf16 v[84:87], v[214:217], v[194:197], v[84:87]
	v_mfma_f32_16x16x32_bf16 v[80:83], v[222:225], v[194:197], v[80:83]
	v_mfma_f32_16x16x32_bf16 v[68:71], v[214:217], v[206:209], v[68:71]
	v_mfma_f32_16x16x32_bf16 v[64:67], v[222:225], v[206:209], v[64:67]
	s_setprio 0
	s_mov_b32 m0, s45
	v_lshl_add_u64 v[226:227], s[6:7], 0, v[128:129]
	s_barrier
	ds_read_b128 v[162:165], v172 offset:16384
	ds_read_b128 v[178:181], v172 offset:17408
	ds_read_b128 v[182:185], v172 offset:18432
	ds_read_b128 v[186:189], v172 offset:19456
	ds_read_b128 v[190:193], v172 offset:20480
	ds_read_b128 v[194:197], v172 offset:21504
	ds_read_b128 v[202:205], v172 offset:22528
	ds_read_b128 v[206:209], v172 offset:23552
	global_load_lds_dwordx4 v128, s[6:7]
	v_lshl_add_u64 v[228:229], s[6:7], 0, v[132:133]
	s_mov_b32 m0, s46
	s_nop 0
	global_load_lds_dwordx4 v132, s[6:7]
	s_setprio 1
	s_barrier
	s_waitcnt lgkmcnt(0)
	s_waitcnt lgkmcnt(0)
	v_mfma_f32_16x16x32_bf16 v[60:63], v[146:149], v[162:165], v[60:63]
	v_mfma_f32_16x16x32_bf16 v[56:59], v[154:157], v[162:165], v[56:59]
	v_mfma_f32_16x16x32_bf16 v[44:47], v[146:149], v[182:185], v[44:47]
	v_mfma_f32_16x16x32_bf16 v[40:43], v[154:157], v[182:185], v[40:43]
	v_mfma_f32_16x16x32_bf16 v[28:31], v[146:149], v[190:193], v[28:31]
	v_mfma_f32_16x16x32_bf16 v[24:27], v[154:157], v[190:193], v[24:27]
	v_mfma_f32_16x16x32_bf16 v[12:15], v[146:149], v[202:205], v[12:15]
	v_mfma_f32_16x16x32_bf16 v[8:11], v[154:157], v[202:205], v[8:11]
	v_mfma_f32_16x16x32_bf16 v[60:63], v[150:153], v[178:181], v[60:63]
	v_mfma_f32_16x16x32_bf16 v[56:59], v[158:161], v[178:181], v[56:59]
	v_mfma_f32_16x16x32_bf16 v[44:47], v[150:153], v[186:189], v[44:47]
	v_mfma_f32_16x16x32_bf16 v[40:43], v[158:161], v[186:189], v[40:43]
	v_mfma_f32_16x16x32_bf16 v[28:31], v[150:153], v[194:197], v[28:31]
	v_mfma_f32_16x16x32_bf16 v[24:27], v[158:161], v[194:197], v[24:27]
	v_mfma_f32_16x16x32_bf16 v[12:15], v[150:153], v[206:209], v[12:15]
	v_mfma_f32_16x16x32_bf16 v[8:11], v[158:161], v[206:209], v[8:11]
	s_setprio 0
	s_barrier
	s_add_u32 s68, s4, 0x40000
	s_addc_u32 s69, s5, 0
	s_add_i32 s70, s58, s44
	s_mov_b32 m0, s70
	s_nop 0
	global_load_lds_dwordx4 v130, s[68:69]
	s_add_i32 m0, s70, 0x2000
	s_nop 0
	global_load_lds_dwordx4 v134, s[68:69]
	s_add_u32 s6, s6, 0x40000
	s_addc_u32 s7, s7, 0
	s_mov_b32 m0, s47
	s_nop 0
	global_load_lds_dwordx4 v128, s[6:7]
	s_mov_b32 m0, s48
	s_nop 0
	global_load_lds_dwordx4 v132, s[6:7]
	s_waitcnt vmcnt(10)
	s_setprio 1
	s_barrier
	v_mfma_f32_16x16x32_bf16 v[52:55], v[210:213], v[162:165], v[52:55]
	v_mfma_f32_16x16x32_bf16 v[48:51], v[218:221], v[162:165], v[48:51]
	v_mfma_f32_16x16x32_bf16 v[36:39], v[210:213], v[182:185], v[36:39]
	v_mfma_f32_16x16x32_bf16 v[32:35], v[218:221], v[182:185], v[32:35]
	v_mfma_f32_16x16x32_bf16 v[20:23], v[210:213], v[190:193], v[20:23]
	v_mfma_f32_16x16x32_bf16 v[16:19], v[218:221], v[190:193], v[16:19]
	v_mfma_f32_16x16x32_bf16 v[4:7], v[210:213], v[202:205], v[4:7]
	v_mfma_f32_16x16x32_bf16 v[0:3], v[218:221], v[202:205], v[0:3]
	v_mfma_f32_16x16x32_bf16 v[52:55], v[214:217], v[178:181], v[52:55]
	v_mfma_f32_16x16x32_bf16 v[48:51], v[222:225], v[178:181], v[48:51]
	v_mfma_f32_16x16x32_bf16 v[36:39], v[214:217], v[186:189], v[36:39]
	v_mfma_f32_16x16x32_bf16 v[32:35], v[222:225], v[186:189], v[32:35]
	v_mfma_f32_16x16x32_bf16 v[20:23], v[214:217], v[194:197], v[20:23]
	v_mfma_f32_16x16x32_bf16 v[16:19], v[222:225], v[194:197], v[16:19]
	v_mfma_f32_16x16x32_bf16 v[4:7], v[214:217], v[206:209], v[4:7]
	v_mfma_f32_16x16x32_bf16 v[0:3], v[222:225], v[206:209], v[0:3]
	s_setprio 0
	s_add_i32 s68, 0, 0x18000
	v_add_u32_e32 v136, s68, v170
	s_barrier
	ds_read_b128 v[146:149], v136
	ds_read_b128 v[150:153], v136 offset:1024
	ds_read_b128 v[154:157], v136 offset:2048
	ds_read_b128 v[158:161], v136 offset:3072
	ds_read_b128 v[162:165], v172 offset:32768
	ds_read_b128 v[178:181], v172 offset:33792
	ds_read_b128 v[182:185], v172 offset:34816
	ds_read_b128 v[186:189], v172 offset:35840
	ds_read_b128 v[190:193], v172 offset:36864
	ds_read_b128 v[194:197], v172 offset:37888
	ds_read_b128 v[202:205], v172 offset:38912
	ds_read_b128 v[206:209], v172 offset:39936
	s_waitcnt lgkmcnt(8)
	s_waitcnt vmcnt(8)
	s_setprio 1
	s_barrier
; #define PG8_STAGE(bufoff, gbase, voff) do { _Pragma("unroll") for (int _i = 0; _i < 2; ++_i) \
;         __builtin_amdgcn_global_load_lds((const unsigned*)((const char*)(gbase) + (voff)[_i]), (LAS unsigned*)(lds + (bufoff) + ldsw + _i * 8192), 16, 0, 0); } while (0)
; #define PG8_LDA(dst, b, h) do { _Pragma("unroll") for (int m = 0; m < 4; ++m) _Pragma("unroll") for (int k = 0; k < 2; ++k) dst[m][k] = *(const LAS bf16x8*)(lds + PG8_SA(b, h) + aoff + m * 2048 + k * 1024); } while (0)
; #define PG8_LDB(dst, b, h) do { _Pragma("unroll") for (int n = 0; n < 2; ++n) _Pragma("unroll") for (int k = 0; k < 2; ++k) dst[n][k] = *(const LAS bf16x8*)(lds + PG8_SB(b, h) + boff + n * 2048 + k * 1024); } while (0)
; #define PG8_WAIT_V(n) asm volatile("s_waitcnt vmcnt(" #n ")" ::: "memory")
; #define PG8_WAIT_L(n) asm volatile("s_waitcnt lgkmcnt(" #n ")" ::: "memory")
; #define PG8_BAR __builtin_amdgcn_s_barrier()
; #define PG8_SCHED __builtin_amdgcn_sched_barrier(0)
; template <class Epi, class Sched>
; __device__ __forceinline__ void gemm_phase(LAS unsigned char* lds, const Gemm g, const Sched& S, const Epi& E) {
;     ...
;             PG8_LDB(B0, 0, 0); PG8_SCHED; PG8_LDA(At, 0, 0); PG8_STAGE(PG8_SA(1, 1), a1 + hstep, voffA);
;             PG8_WAIT_L(8); PG8_BAR; PG8_WAIT_L(0); PG8_MMA(0, 0, At, B0); PG8_BAR; PG8_SCHED;
;             PG8_LDB(B1, 0, 1); PG8_STAGE(PG8_SB(0, 0), b2, voffB);
;             PG8_BAR; PG8_WAIT_L(0); PG8_MMA(0, 1, At, B1); PG8_BAR;
;             PG8_LDA(At, 0, 1); PG8_STAGE(PG8_SA(0, 0), a2, voffA);
;             PG8_BAR; PG8_WAIT_L(0); PG8_MMA(1, 0, At, B0); PG8_BAR; PG8_SCHED;
;             PG8_STAGE(PG8_SB(0, 1), b2 + hstep, voffB);
;             PG8_WAIT_V(6); PG8_BAR; PG8_MMA(1, 1, At, B1); PG8_BAR;
;             PG8_LDB(B0, 1, 0); PG8_SCHED; PG8_LDA(At, 1, 0); PG8_STAGE(PG8_SA(0, 1), a2 + hstep, voffA);
;             PG8_WAIT_L(8); PG8_BAR; PG8_WAIT_L(0); PG8_MMA(0, 0, At, B0); PG8_BAR; PG8_SCHED;
;             PG8_LDB(B1, 1, 1); PG8_STAGE(PG8_SB(1, 0), b3, voffB);
;             PG8_BAR; PG8_WAIT_L(0); PG8_MMA(0, 1, At, B1); PG8_BAR;
;             PG8_LDA(At, 1, 1); PG8_STAGE(PG8_SA(1, 0), a3, voffA);
;             PG8_BAR; PG8_WAIT_L(0); PG8_MMA(1, 0, At, B0); PG8_BAR; PG8_SCHED;
;             PG8_STAGE(PG8_SB(1, 1), b3 + hstep, voffB);
;             PG8_WAIT_V(6); PG8_BAR; PG8_MMA(1, 1, At, B1); PG8_BAR;
	s_waitcnt lgkmcnt(0)
	s_waitcnt lgkmcnt(0)
	v_mfma_f32_16x16x32_bf16 v[124:127], v[146:149], v[162:165], v[124:127]
	v_mfma_f32_16x16x32_bf16 v[120:123], v[154:157], v[162:165], v[120:123]
	v_mfma_f32_16x16x32_bf16 v[108:111], v[146:149], v[182:185], v[108:111]
	v_mfma_f32_16x16x32_bf16 v[104:107], v[154:157], v[182:185], v[104:107]
	v_mfma_f32_16x16x32_bf16 v[92:95], v[146:149], v[190:193], v[92:95]
	v_mfma_f32_16x16x32_bf16 v[88:91], v[154:157], v[190:193], v[88:91]
	v_mfma_f32_16x16x32_bf16 v[76:79], v[146:149], v[202:205], v[76:79]
	v_mfma_f32_16x16x32_bf16 v[72:75], v[154:157], v[202:205], v[72:75]
	v_mfma_f32_16x16x32_bf16 v[124:127], v[150:153], v[178:181], v[124:127]
	v_mfma_f32_16x16x32_bf16 v[120:123], v[158:161], v[178:181], v[120:123]
	v_mfma_f32_16x16x32_bf16 v[108:111], v[150:153], v[186:189], v[108:111]
	v_mfma_f32_16x16x32_bf16 v[104:107], v[158:161], v[186:189], v[104:107]
	v_mfma_f32_16x16x32_bf16 v[92:95], v[150:153], v[194:197], v[92:95]
	v_mfma_f32_16x16x32_bf16 v[88:91], v[158:161], v[194:197], v[88:91]
	v_mfma_f32_16x16x32_bf16 v[76:79], v[150:153], v[206:209], v[76:79]
	v_mfma_f32_16x16x32_bf16 v[72:75], v[158:161], v[206:209], v[72:75]
	s_setprio 0
	s_barrier
	s_add_i32 s6, 0, 0x1c000
	s_add_i32 s7, s68, s44
	v_add_u32_e32 v136, s6, v170
	s_add_u32 s20, s4, 0x80
	s_addc_u32 s21, s5, 0
	s_mov_b32 m0, s7
	ds_read_b128 v[210:213], v136
	ds_read_b128 v[214:217], v136 offset:1024
	ds_read_b128 v[218:221], v136 offset:2048
	ds_read_b128 v[222:225], v136 offset:3072
	global_load_lds_dwordx4 v130, s[20:21]
	s_add_i32 m0, s7, 0x2000
	s_nop 0
	global_load_lds_dwordx4 v134, s[20:21]
	s_waitcnt vmcnt(8)
	s_setprio 1
	s_barrier
	s_waitcnt lgkmcnt(0)
	s_waitcnt lgkmcnt(0)
	v_mfma_f32_16x16x32_bf16 v[116:119], v[210:213], v[162:165], v[116:119]
	v_mfma_f32_16x16x32_bf16 v[112:115], v[218:221], v[162:165], v[112:115]
	v_mfma_f32_16x16x32_bf16 v[100:103], v[210:213], v[182:185], v[100:103]
	v_mfma_f32_16x16x32_bf16 v[96:99], v[218:221], v[182:185], v[96:99]
	v_mfma_f32_16x16x32_bf16 v[84:87], v[210:213], v[190:193], v[84:87]
	v_mfma_f32_16x16x32_bf16 v[80:83], v[218:221], v[190:193], v[80:83]
	v_mfma_f32_16x16x32_bf16 v[68:71], v[210:213], v[202:205], v[68:71]
	v_mfma_f32_16x16x32_bf16 v[64:67], v[218:221], v[202:205], v[64:67]
	v_mfma_f32_16x16x32_bf16 v[116:119], v[214:217], v[178:181], v[116:119]
	v_mfma_f32_16x16x32_bf16 v[112:115], v[222:225], v[178:181], v[112:115]
	v_mfma_f32_16x16x32_bf16 v[100:103], v[214:217], v[186:189], v[100:103]
	v_mfma_f32_16x16x32_bf16 v[96:99], v[222:225], v[186:189], v[96:99]
	v_mfma_f32_16x16x32_bf16 v[84:87], v[214:217], v[194:197], v[84:87]
	v_mfma_f32_16x16x32_bf16 v[80:83], v[222:225], v[194:197], v[80:83]
	v_mfma_f32_16x16x32_bf16 v[68:71], v[214:217], v[206:209], v[68:71]
	v_mfma_f32_16x16x32_bf16 v[64:67], v[222:225], v[206:209], v[64:67]
	s_setprio 0
	s_mov_b32 m0, s54
	s_mov_b64 s[20:21], 0x80
	v_lshl_add_u64 v[166:167], v[226:227], 0, s[20:21]
	s_barrier
	ds_read_b128 v[162:165], v172 offset:49152
	ds_read_b128 v[178:181], v172 offset:50176
	ds_read_b128 v[182:185], v172 offset:51200
	ds_read_b128 v[186:189], v172 offset:52224
	ds_read_b128 v[190:193], v172 offset:53248
	ds_read_b128 v[194:197], v172 offset:54272
	ds_read_b128 v[202:205], v172 offset:55296
	ds_read_b128 v[206:209], v172 offset:56320
	global_load_lds_dwordx4 v[166:167], off
	v_lshl_add_u64 v[166:167], v[228:229], 0, s[20:21]
	s_mov_b32 m0, s55
	s_nop 0
	global_load_lds_dwordx4 v[166:167], off
	s_setprio 1
	s_barrier
	s_waitcnt lgkmcnt(0)
	s_waitcnt lgkmcnt(0)
	v_mfma_f32_16x16x32_bf16 v[60:63], v[146:149], v[162:165], v[60:63]
	v_mfma_f32_16x16x32_bf16 v[56:59], v[154:157], v[162:165], v[56:59]
	v_mfma_f32_16x16x32_bf16 v[44:47], v[146:149], v[182:185], v[44:47]
	v_mfma_f32_16x16x32_bf16 v[40:43], v[154:157], v[182:185], v[40:43]
	v_mfma_f32_16x16x32_bf16 v[28:31], v[146:149], v[190:193], v[28:31]
	v_mfma_f32_16x16x32_bf16 v[24:27], v[154:157], v[190:193], v[24:27]
	v_mfma_f32_16x16x32_bf16 v[12:15], v[146:149], v[202:205], v[12:15]
	v_mfma_f32_16x16x32_bf16 v[8:11], v[154:157], v[202:205], v[8:11]
	v_mfma_f32_16x16x32_bf16 v[60:63], v[150:153], v[178:181], v[60:63]
	v_mfma_f32_16x16x32_bf16 v[56:59], v[158:161], v[178:181], v[56:59]
	v_mfma_f32_16x16x32_bf16 v[44:47], v[150:153], v[186:189], v[44:47]
	v_mfma_f32_16x16x32_bf16 v[40:43], v[158:161], v[186:189], v[40:43]
	v_mfma_f32_16x16x32_bf16 v[28:31], v[150:153], v[194:197], v[28:31]
	v_mfma_f32_16x16x32_bf16 v[24:27], v[158:161], v[194:197], v[24:27]
	v_mfma_f32_16x16x32_bf16 v[12:15], v[150:153], v[206:209], v[12:15]
	v_mfma_f32_16x16x32_bf16 v[8:11], v[158:161], v[206:209], v[8:11]
	s_setprio 0
	s_barrier
	s_add_u32 s4, s4, 0x40080
	s_addc_u32 s5, s5, 0
	s_add_i32 s6, s6, s44
	s_mov_b32 m0, s6
	s_nop 0
	global_load_lds_dwordx4 v130, s[4:5]
	s_add_i32 m0, s6, 0x2000
	s_nop 0
	global_load_lds_dwordx4 v134, s[4:5]
	s_waitcnt vmcnt(8)
	s_setprio 1
	s_barrier
	v_mfma_f32_16x16x32_bf16 v[52:55], v[210:213], v[162:165], v[52:55]
	v_mfma_f32_16x16x32_bf16 v[48:51], v[218:221], v[162:165], v[48:51]
	v_mfma_f32_16x16x32_bf16 v[36:39], v[210:213], v[182:185], v[36:39]
	v_mfma_f32_16x16x32_bf16 v[32:35], v[218:221], v[182:185], v[32:35]
	v_mfma_f32_16x16x32_bf16 v[20:23], v[210:213], v[190:193], v[20:23]
	v_mfma_f32_16x16x32_bf16 v[16:19], v[218:221], v[190:193], v[16:19]
	v_mfma_f32_16x16x32_bf16 v[4:7], v[210:213], v[202:205], v[4:7]
	v_mfma_f32_16x16x32_bf16 v[0:3], v[218:221], v[202:205], v[0:3]
	v_mfma_f32_16x16x32_bf16 v[52:55], v[214:217], v[178:181], v[52:55]
	v_mfma_f32_16x16x32_bf16 v[48:51], v[222:225], v[178:181], v[48:51]
	v_mfma_f32_16x16x32_bf16 v[36:39], v[214:217], v[186:189], v[36:39]
	v_mfma_f32_16x16x32_bf16 v[32:35], v[222:225], v[186:189], v[32:35]
	v_mfma_f32_16x16x32_bf16 v[20:23], v[214:217], v[194:197], v[20:23]
	v_mfma_f32_16x16x32_bf16 v[16:19], v[222:225], v[194:197], v[16:19]
	v_mfma_f32_16x16x32_bf16 v[4:7], v[214:217], v[206:209], v[4:7]
	v_mfma_f32_16x16x32_bf16 v[0:3], v[222:225], v[206:209], v[0:3]
	s_setprio 0
	s_add_i32 s67, s67, 2
	s_add_u32 s0, s0, 0x100
	s_addc_u32 s1, s1, 0
	s_add_u32 s65, s65, 0x100
	s_addc_u32 s66, s66, 0
	s_cmp_gt_u32 s67, 13
	s_barrier
;     __device__ __forceinline__ void operator()(const AccT& acc, const Unit& u, int wr, int wc, int fr, int fq) const {
;     ...
;         const int rbase = wr * 64 + fr;
;         const int tb = u.pn * 256 + wc * 32 + 8 * fq;
;         const int o0 = wc * 32 + 8 * fq;
;         const int j = fr & 3; const float sgn = ((fr >> 2) & 1) ? 1.0f : -1.0f;
; #pragma unroll
;         for (int ai = 0; ai < 2; ++ai) {
;             const int hh = 2 * ai + wr;
;             const float l2f = lgd[hh] * 1.4426950408889634f, l2b = lgd[4 + hh] * 1.4426950408889634f;
;             const float zf0 = exp2f((float)(127 - o0) * l2f), zfs = exp2f(-l2f), zb0 = exp2f((float)o0 * l2b), zbs = exp2f(l2b);
; #pragma unroll
;             for (int m = 0; m < 4; ++m) {
;                 const int r = rbase + ai * 128 + m * 16;
;                 const int d = 4 * (2 * m + (fr >> 3)) + j;
; #pragma unroll
;                 for (int bj = 0; bj < 2; ++bj) {
;                     const int t0 = tb + bj * 128;
;                     float v[8];
; #pragma unroll
;                     for (int jj = 0; jj < 4; ++jj) { v[jj] = acc[ai][bj][m][0][jj]; v[4 + jj] = acc[ai][bj][m][1][jj]; }
;                     if constexpr (ROPE) {
;                         const int t = t0 & 2047;
; #pragma unroll
;                         for (int hf = 0; hf < 2; ++hf) {
;                             f32x4 cs, sn;
;                             if (m < 2) { const float c1 = ropeA[(t >> 6) * 16 + d], s1 = ropeA[1024 + (t >> 6) * 16 + d]; cs = (f32x4){c1, c1, c1, c1}; sn = (f32x4){s1, s1, s1, s1}; }
;                             else { const float* cb = ropeA + 2048 + (d - 16) * 64 + (t & 63) + 4 * hf; cs = *(const f32x4*)(cb); sn = *(const f32x4*)(cb + 1024); }
; #pragma unroll
;                             for (int jj = 0; jj < 4; ++jj) { const float pr = __shfl_xor(v[4 * hf + jj], 4); v[4 * hf + jj] = v[4 * hf + jj] * cs[jj] + sgn * pr * sn[jj]; }
;                             __builtin_amdgcn_sched_barrier(0);
;                         }
;                     }
;                     float zf[8], zb[8]; zf[0] = zf0; zb[0] = zb0;
; #pragma unroll
;                     for (int jj = 1; jj < 8; ++jj) { zf[jj] = zf[jj - 1] * zfs; zb[jj] = zb[jj - 1] * zbs; }
;                     u32x4 wf, wb;
	s_cbranch_scc0 .LBB0_613
	v_mov_b32_e32 v136, v169
	v_mov_b32_e32 v150, v168
	s_lshl_b32 s0, s33, 8
	global_load_dword v154, v137, s[22:23]
	global_load_dword v155, v137, s[22:23] offset:16
	s_or_b32 s0, s0, s53
	v_lshlrev_b32_e32 v151, 3, v136
	v_ashrrev_i32_e32 v136, 1, v150
	v_add_u32_e32 v162, s0, v151
	v_bfi_b32 v136, -4, v136, v150
	v_lshrrev_b32_e32 v146, 2, v162
	v_add_u32_e32 v192, 0x400, v136
	v_and_b32_e32 v187, 0x1f0, v146
	v_add_u32_e32 v146, v192, v187
	v_add_u32_e32 v148, v187, v136
	v_ashrrev_i32_e32 v147, 31, v146
	v_ashrrev_i32_e32 v149, 31, v148
	v_lshl_add_u64 v[146:147], v[146:147], 2, s[16:17]
	v_lshl_add_u64 v[148:149], v[148:149], 2, s[16:17]
	global_load_dword v153, v[146:147], off
	global_load_dword v166, v[148:149], off
	v_and_b32_e32 v157, 64, v174
	v_xor_b32_e32 v156, 4, v174
	v_add_u32_e32 v157, 64, v157
	v_cmp_lt_i32_e32 vcc, v156, v157
	v_mov_b32_e32 v152, v124
	v_add_u32_e32 v151, s53, v151
	v_cndmask_b32_e32 v156, v174, v156, vcc
	v_lshlrev_b32_e32 v177, 2, v156
	ds_bpermute_b32 v124, v177, v124
	v_sub_u32_e32 v156, 0x7f, v151
	v_add_u32_e32 v164, s52, v150
	v_and_b32_e32 v150, 4, v150
	v_cvt_f32_i32_e32 v179, v156
	v_cvt_f32_i32_e32 v178, v151
	v_cmp_eq_u32_e32 vcc, 0, v150
	ds_bpermute_b32 v157, v177, v125
	ds_bpermute_b32 v158, v177, v127
	s_waitcnt lgkmcnt(0)
	v_cndmask_b32_e64 v167, v124, -v124, vcc
	ds_bpermute_b32 v151, v177, v126
	v_ashrrev_i32_e32 v165, 31, v164
	v_and_b32_e32 v186, 56, v162
	s_waitcnt lgkmcnt(0)
	v_cndmask_b32_e64 v151, v151, -v151, vcc
	s_waitcnt vmcnt(0)
	v_mul_f32_e32 v124, 0x3fb8aa3b, v154
	v_mul_f32_e32 v150, 0x3fb8aa3b, v155
	v_cmp_lt_f32_e64 s[4:5], s60, v124
	v_mul_f32_e32 v156, v124, v179
	v_cmp_gt_f32_e64 s[6:7], s59, v150
	v_cndmask_b32_e64 v159, 0, v176, s[4:5]
	v_mul_f32_e32 v160, v150, v178
	v_cndmask_b32_e64 v161, 0, v176, s[6:7]
	v_cmp_gt_f32_e64 s[8:9], s59, v156
	v_fmac_f32_e32 v159, 0xbfb8aa3b, v154
	s_and_b64 s[0:1], s[4:5], exec
	v_cmp_gt_f32_e64 s[4:5], s59, v160
	v_fmac_f32_e32 v161, 0x3fb8aa3b, v155
	v_cndmask_b32_e64 v154, 0, v176, s[8:9]
	v_exp_f32_e32 v155, v159
	v_cndmask_b32_e64 v159, 0, v176, s[4:5]
	v_fmac_f32_e32 v154, v124, v179
	v_fmac_f32_e32 v159, v150, v178
	v_exp_f32_e32 v150, v154
	v_cndmask_b32_e64 v156, 0, v175, s[8:9]
	s_cselect_b32 s8, 0xffffffc0, 0
	v_exp_f32_e32 v161, v161
	v_exp_f32_e32 v159, v159
	v_ldexp_f32 v163, v155, s8
	v_pk_mul_f32 v[154:155], v[152:153], v[166:167]
	v_cndmask_b32_e64 v167, v157, -v157, vcc
	v_mov_b32_e32 v152, v125
	s_and_b64 s[0:1], s[6:7], exec
	v_add_f32_e32 v190, v154, v155
	v_pk_mul_f32 v[154:155], v[152:153], v[166:167]
	v_cndmask_b32_e64 v167, v158, -v158, vcc
	v_mov_b32_e32 v152, v127
	v_cndmask_b32_e64 v160, 0, v175, s[4:5]
	s_cselect_b32 s0, 0xffffffc0, 0
	v_ldexp_f32 v180, v150, v156
	v_add_f32_e32 v191, v154, v155
	v_pk_mul_f32 v[154:155], v[152:153], v[166:167]
	v_ldexp_f32 v124, v161, s0
	v_mul_f32_e32 v161, v126, v166
	v_ldexp_f32 v150, v159, v160
	v_mul_f32_e32 v181, v163, v180
	v_add_f32_e32 v193, v154, v155
	global_load_dword v188, v[148:149], off
	global_load_dword v157, v[146:147], off
	ds_bpermute_b32 v127, v177, v121
	v_mov_b32_e32 v156, v121
	ds_bpermute_b32 v121, v177, v123
	ds_bpermute_b32 v125, v177, v120
	ds_bpermute_b32 v152, v177, v122
	s_waitcnt lgkmcnt(3)
	v_cndmask_b32_e64 v189, v127, -v127, vcc
	s_waitcnt lgkmcnt(1)
	v_cndmask_b32_e64 v158, v125, -v125, vcc
	s_waitcnt lgkmcnt(0)
	v_cndmask_b32_e64 v127, v152, -v152, vcc
	s_waitcnt vmcnt(1)
	v_mul_f32_e32 v159, v120, v188
	s_waitcnt vmcnt(0)
	v_pk_mul_f32 v[154:155], v[156:157], v[188:189]
	v_cndmask_b32_e64 v189, v121, -v121, vcc
	v_mov_b32_e32 v156, v123
	v_add_f32_e32 v121, v154, v155
	v_pk_mul_f32 v[154:155], v[156:157], v[188:189]
	s_nop 0
	v_add_f32_e32 v123, v154, v155
	v_mov_b32_e32 v125, v153
	v_pk_mul_f32 v[152:153], v[124:125], v[150:151]
	v_mov_b32_e32 v125, v161
	v_pk_mul_f32 v[154:155], v[124:125], v[152:153]
	v_mov_b32_e32 v125, v157
	v_mov_b32_e32 v155, v158
	v_pk_mul_f32 v[156:157], v[124:125], v[154:155]
	v_mov_b32_e32 v158, v124
	v_pk_mul_f32 v[158:159], v[158:159], v[156:157]
	v_mul_f32_e32 v167, v163, v181
	v_mov_b32_e32 v159, v127
	v_mul_f32_e32 v183, v163, v167
	v_pk_mul_f32 v[160:161], v[124:125], v[158:159]
	v_mul_f32_e32 v182, v163, v183
	v_mul_f32_e32 v151, v124, v160
	v_mul_f32_e32 v185, v163, v182
	v_mul_f32_e32 v155, v124, v151
	v_mul_f32_e32 v124, v180, v190
	v_mul_f32_e32 v125, v181, v191
	v_fma_f32 v153, v126, v166, v153
	v_mul_f32_e32 v184, v163, v185
	v_cvt_pk_bf16_f32 v124, v124, v125
	v_mul_f32_e32 v125, v167, v153
	v_mul_f32_e32 v126, v183, v193
	v_fma_f32 v120, v120, v188, v157
	v_mul_f32_e32 v159, v163, v184
	v_cvt_pk_bf16_f32 v125, v125, v126
	v_mul_f32_e32 v126, v182, v120
	v_mul_f32_e32 v127, v185, v121
	v_fma_f32 v122, v122, v188, v161
	v_cvt_pk_bf16_f32 v126, v126, v127
	v_mul_f32_e32 v127, v184, v122
	v_mul_f32_e32 v157, v159, v123
	v_cvt_pk_bf16_f32 v127, v127, v157
	v_mul_f32_e32 v157, v150, v190
	v_mul_f32_e32 v120, v158, v120
	v_mul_f32_e32 v121, v160, v121
	v_mul_f32_e32 v161, v152, v191
	v_cvt_pk_bf16_f32 v188, v157, v161
	v_mul_f32_e32 v153, v154, v153
	v_mul_f32_e32 v157, v156, v193
	v_cvt_pk_bf16_f32 v189, v153, v157
	v_cvt_pk_bf16_f32 v190, v120, v121
	v_mul_f32_e32 v120, v151, v122
	v_mul_f32_e32 v121, v155, v123
	v_cvt_pk_bf16_f32 v191, v120, v121
	v_lshlrev_b64 v[120:121], 17, v[164:165]
	v_lshl_add_u64 v[120:121], s[80:81], 0, v[120:121]
	v_ashrrev_i32_e32 v163, 31, v162
	v_lshl_add_u64 v[120:121], v[162:163], 1, v[120:121]
	s_mov_b64 s[0:1], 0x2000000
	global_store_dwordx4 v[120:121], v[124:127], off
	s_nop 1
	v_lshl_add_u64 v[126:127], v[120:121], 0, s[0:1]
	s_brev_b32 s0, 64
	v_add_co_u32_e64 v122, s[4:5], s0, v120
	s_nop 1
	v_addc_co_u32_e64 v123, s[4:5], 0, v121, s[4:5]
	global_store_dwordx4 v[122:123], v[188:191], off
	v_add_u32_e32 v122, 0x80, v162
	v_lshrrev_b32_e32 v122, 2, v122
	v_and_b32_e32 v153, 0x1f0, v122
	v_add_u32_e32 v122, v153, v192
	v_add_u32_e32 v124, v153, v136
	v_ashrrev_i32_e32 v123, 31, v122
	v_ashrrev_i32_e32 v125, 31, v124
	v_lshl_add_u64 v[122:123], v[122:123], 2, s[16:17]
	v_lshl_add_u64 v[124:125], v[124:125], 2, s[16:17]
	global_load_dword v163, v[122:123], off
	global_load_dword v164, v[124:125], off
	ds_bpermute_b32 v157, v177, v116
	v_mov_b32_e32 v162, v116
	ds_bpermute_b32 v116, v177, v117
	ds_bpermute_b32 v161, v177, v118
	ds_bpermute_b32 v166, v177, v119
	s_waitcnt lgkmcnt(3)
; __device__ __forceinline__ unsigned cvt_pk_bf16(float lo, float hi) { unsigned r; asm volatile("v_cvt_pk_bf16_f32 %0, %1, %2" : "=v"(r) : "v"(lo), "v"(hi)); return r; }
;     __device__ __forceinline__ void operator()(const AccT& acc, const Unit& u, int wr, int wc, int fr, int fq) const {
;     ...
;                 const int r = rbase + ai * 128 + m * 16;
;                 const int d = 4 * (2 * m + (fr >> 3)) + j;
; #pragma unroll
;                 for (int bj = 0; bj < 2; ++bj) {
;                     const int t0 = tb + bj * 128;
;                     float v[8];
; #pragma unroll
;                     for (int jj = 0; jj < 4; ++jj) { v[jj] = acc[ai][bj][m][0][jj]; v[4 + jj] = acc[ai][bj][m][1][jj]; }
;                     if constexpr (ROPE) {
;                         const int t = t0 & 2047;
; #pragma unroll
;                         for (int hf = 0; hf < 2; ++hf) {
;                             f32x4 cs, sn;
;                             if (m < 2) { const float c1 = ropeA[(t >> 6) * 16 + d], s1 = ropeA[1024 + (t >> 6) * 16 + d]; cs = (f32x4){c1, c1, c1, c1}; sn = (f32x4){s1, s1, s1, s1}; }
;                             else { const float* cb = ropeA + 2048 + (d - 16) * 64 + (t & 63) + 4 * hf; cs = *(const f32x4*)(cb); sn = *(const f32x4*)(cb + 1024); }
; #pragma unroll
;                             for (int jj = 0; jj < 4; ++jj) { const float pr = __shfl_xor(v[4 * hf + jj], 4); v[4 * hf + jj] = v[4 * hf + jj] * cs[jj] + sgn * pr * sn[jj]; }
;                             __builtin_amdgcn_sched_barrier(0);
;                         }
;                     }
;                     float zf[8], zb[8]; zf[0] = zf0; zb[0] = zb0;
; #pragma unroll
;                     for (int jj = 1; jj < 8; ++jj) { zf[jj] = zf[jj - 1] * zfs; zb[jj] = zb[jj - 1] * zbs; }
;                     u32x4 wf, wb;
;                     wf.x = cvt_pk_bf16(v[0] * zf[0], v[1] * zf[1]); wf.y = cvt_pk_bf16(v[2] * zf[2], v[3] * zf[3]); wf.z = cvt_pk_bf16(v[4] * zf[4], v[5] * zf[5]); wf.w = cvt_pk_bf16(v[6] * zf[6], v[7] * zf[7]);
;                     wb.x = cvt_pk_bf16(v[0] * zb[0], v[1] * zb[1]); wb.y = cvt_pk_bf16(v[2] * zb[2], v[3] * zb[3]); wb.z = cvt_pk_bf16(v[4] * zb[4], v[5] * zb[5]); wb.w = cvt_pk_bf16(v[6] * zb[6], v[7] * zb[7]);
;                     *(u32x4*)(KTZ + (size_t)r * NT + t0) = wf;
;                     *(u32x4*)(KTZ + (size_t)(256 + r) * NT + t0) = wb;
	v_cndmask_b32_e64 v165, v157, -v157, vcc
	s_waitcnt vmcnt(0)
	v_pk_mul_f32 v[188:189], v[162:163], v[164:165]
	s_waitcnt lgkmcnt(2)
	v_cndmask_b32_e64 v165, v116, -v116, vcc
	v_mov_b32_e32 v162, v117
	v_pk_mul_f32 v[116:117], v[162:163], v[164:165]
	s_waitcnt lgkmcnt(1)
	v_cndmask_b32_e64 v165, v161, -v161, vcc
	v_mov_b32_e32 v162, v118
	v_add_f32_e32 v161, v116, v117
	v_pk_mul_f32 v[116:117], v[162:163], v[164:165]
	s_waitcnt lgkmcnt(0)
	v_cndmask_b32_e64 v165, v166, -v166, vcc
	v_mov_b32_e32 v162, v119
	v_add_f32_e32 v166, v116, v117
	v_pk_mul_f32 v[116:117], v[162:163], v[164:165]
	v_add_f32_e32 v157, v188, v189
	v_add_f32_e32 v164, v116, v117
	global_load_dword v117, v[122:123], off
	global_load_dword v118, v[124:125], off
	ds_bpermute_b32 v119, v177, v112
	v_mov_b32_e32 v116, v112
	ds_bpermute_b32 v112, v177, v113
	ds_bpermute_b32 v165, v177, v114
	ds_bpermute_b32 v188, v177, v115
	s_waitcnt lgkmcnt(3)
	v_cndmask_b32_e64 v119, v119, -v119, vcc
	s_waitcnt vmcnt(0)
	v_pk_mul_f32 v[162:163], v[116:117], v[118:119]
	s_waitcnt lgkmcnt(2)
	v_cndmask_b32_e64 v119, v112, -v112, vcc
	v_mov_b32_e32 v116, v113
	v_pk_mul_f32 v[112:113], v[116:117], v[118:119]
	s_waitcnt lgkmcnt(1)
	v_cndmask_b32_e64 v119, v165, -v165, vcc
	v_mov_b32_e32 v116, v114
	v_add_f32_e32 v162, v162, v163
	v_add_f32_e32 v163, v112, v113
	v_pk_mul_f32 v[112:113], v[116:117], v[118:119]
	s_waitcnt lgkmcnt(0)
	v_cndmask_b32_e64 v119, v188, -v188, vcc
	v_mov_b32_e32 v116, v115
	v_add_f32_e32 v165, v112, v113
	v_pk_mul_f32 v[112:113], v[116:117], v[118:119]
	s_nop 0
	v_add_f32_e32 v119, v112, v113
	v_mul_f32_e32 v112, v180, v157
	v_mul_f32_e32 v113, v181, v161
	v_cvt_pk_bf16_f32 v112, v112, v113
	v_mul_f32_e32 v113, v167, v166
	v_mul_f32_e32 v114, v183, v164
	v_cvt_pk_bf16_f32 v113, v113, v114
	v_mul_f32_e32 v114, v182, v162
	v_mul_f32_e32 v115, v185, v163
	v_cvt_pk_bf16_f32 v114, v114, v115
	v_mul_f32_e32 v115, v184, v165
	v_mul_f32_e32 v116, v159, v119
	v_cvt_pk_bf16_f32 v115, v115, v116
	v_mul_f32_e32 v116, v150, v157
	v_mul_f32_e32 v117, v152, v161
	v_cvt_pk_bf16_f32 v116, v116, v117
	v_mul_f32_e32 v117, v154, v166
	v_mul_f32_e32 v118, v156, v164
	v_cvt_pk_bf16_f32 v117, v117, v118
	v_mul_f32_e32 v118, v158, v162
	v_mul_f32_e32 v157, v160, v163
	v_mul_f32_e32 v119, v155, v119
	v_cvt_pk_bf16_f32 v118, v118, v157
	v_mul_f32_e32 v157, v151, v165
	v_cvt_pk_bf16_f32 v119, v157, v119
	global_store_dwordx4 v[120:121], v[112:115], off offset:256
	global_store_dwordx4 v[126:127], v[116:119], off offset:256
	v_add_u32_e32 v161, 0x408, v136
	v_add_u32_e32 v157, 8, v136
	v_add_u32_e32 v112, v161, v187
	v_add_u32_e32 v114, v187, v157
	v_ashrrev_i32_e32 v113, 31, v112
	v_ashrrev_i32_e32 v115, 31, v114
	v_lshl_add_u64 v[112:113], v[112:113], 2, s[16:17]
	v_lshl_add_u64 v[114:115], v[114:115], 2, s[16:17]
	global_load_dword v117, v[112:113], off
	global_load_dword v118, v[114:115], off
	ds_bpermute_b32 v119, v177, v108
	v_mov_b32_e32 v116, v108
	ds_bpermute_b32 v108, v177, v109
	ds_bpermute_b32 v162, v177, v110
	ds_bpermute_b32 v163, v177, v111
	s_waitcnt lgkmcnt(3)
	v_cndmask_b32_e64 v119, v119, -v119, vcc
	s_waitcnt vmcnt(0)
	v_pk_mul_f32 v[126:127], v[116:117], v[118:119]
	s_waitcnt lgkmcnt(2)
	v_cndmask_b32_e64 v119, v108, -v108, vcc
	v_mov_b32_e32 v116, v109
	v_pk_mul_f32 v[108:109], v[116:117], v[118:119]
	s_waitcnt lgkmcnt(1)
	v_cndmask_b32_e64 v119, v162, -v162, vcc
	v_mov_b32_e32 v116, v110
	v_add_f32_e32 v126, v126, v127
	v_add_f32_e32 v127, v108, v109
	v_pk_mul_f32 v[108:109], v[116:117], v[118:119]
	s_waitcnt lgkmcnt(0)
	v_cndmask_b32_e64 v119, v163, -v163, vcc
	v_mov_b32_e32 v116, v111
	v_add_f32_e32 v162, v108, v109
	v_pk_mul_f32 v[108:109], v[116:117], v[118:119]
	s_nop 0
	v_add_f32_e32 v118, v108, v109
	global_load_dword v109, v[112:113], off
	global_load_dword v110, v[114:115], off
	ds_bpermute_b32 v111, v177, v104
	v_mov_b32_e32 v108, v104
	ds_bpermute_b32 v104, v177, v105
	ds_bpermute_b32 v119, v177, v106
	ds_bpermute_b32 v163, v177, v107
	s_waitcnt lgkmcnt(3)
	v_cndmask_b32_e64 v111, v111, -v111, vcc
	s_waitcnt vmcnt(0)
	v_pk_mul_f32 v[116:117], v[108:109], v[110:111]
	s_waitcnt lgkmcnt(2)
	v_cndmask_b32_e64 v111, v104, -v104, vcc
	v_mov_b32_e32 v108, v105
	v_pk_mul_f32 v[104:105], v[108:109], v[110:111]
	s_waitcnt lgkmcnt(1)
	v_cndmask_b32_e64 v111, v119, -v119, vcc
	v_mov_b32_e32 v108, v106
	v_add_f32_e32 v119, v104, v105
	v_pk_mul_f32 v[104:105], v[108:109], v[110:111]
	s_waitcnt lgkmcnt(0)
	v_cndmask_b32_e64 v111, v163, -v163, vcc
	v_mov_b32_e32 v108, v107
	v_add_f32_e32 v163, v104, v105
	v_pk_mul_f32 v[104:105], v[108:109], v[110:111]
	v_add_f32_e32 v164, v116, v117
	v_add_f32_e32 v108, v104, v105
	v_mul_f32_e32 v104, v180, v126
	v_mul_f32_e32 v105, v181, v127
	v_cvt_pk_bf16_f32 v104, v104, v105
	v_mul_f32_e32 v105, v167, v162
	v_mul_f32_e32 v106, v183, v118
	v_cvt_pk_bf16_f32 v105, v105, v106
	v_mul_f32_e32 v106, v182, v164
	v_mul_f32_e32 v107, v185, v119
	v_cvt_pk_bf16_f32 v106, v106, v107
	v_mul_f32_e32 v107, v184, v163
	v_mul_f32_e32 v109, v159, v108
	v_cvt_pk_bf16_f32 v107, v107, v109
	v_mul_f32_e32 v109, v150, v126
	v_mul_f32_e32 v110, v152, v127
	v_cvt_pk_bf16_f32 v116, v109, v110
	v_mul_f32_e32 v109, v154, v162
	v_mul_f32_e32 v110, v156, v118
	v_cvt_pk_bf16_f32 v117, v109, v110
	v_mul_f32_e32 v109, v158, v164
	v_mul_f32_e32 v110, v160, v119
	v_cvt_pk_bf16_f32 v118, v109, v110
	v_mul_f32_e32 v109, v151, v163
	v_mul_f32_e32 v108, v155, v108
	s_mov_b64 s[0:1], 0x200000
	v_cvt_pk_bf16_f32 v119, v109, v108
	v_lshl_add_u64 v[108:109], v[120:121], 0, s[0:1]
	s_mov_b32 s0, 0x200000
	v_add_co_u32_e64 v110, s[4:5], s0, v120
	s_mov_b64 s[0:1], 0x2200000
	s_nop 0
	v_addc_co_u32_e64 v111, s[4:5], 0, v121, s[4:5]
	global_store_dwordx4 v[110:111], v[104:107], off
	v_lshl_add_u64 v[110:111], v[120:121], 0, s[0:1]
	s_mov_b32 s0, 0x2200000
	v_add_co_u32_e64 v104, s[4:5], s0, v120
	s_nop 1
	v_addc_co_u32_e64 v105, s[4:5], 0, v121, s[4:5]
	global_store_dwordx4 v[104:105], v[116:119], off
	v_add_u32_e32 v104, v153, v161
	v_add_u32_e32 v106, v153, v157
	v_ashrrev_i32_e32 v105, 31, v104
	v_ashrrev_i32_e32 v107, 31, v106
	v_lshl_add_u64 v[104:105], v[104:105], 2, s[16:17]
	v_lshl_add_u64 v[106:107], v[106:107], 2, s[16:17]
	global_load_dword v117, v[104:105], off
	global_load_dword v118, v[106:107], off
	ds_bpermute_b32 v119, v177, v100
	v_mov_b32_e32 v116, v100
	ds_bpermute_b32 v100, v177, v101
	ds_bpermute_b32 v153, v177, v102
	ds_bpermute_b32 v157, v177, v103
	s_waitcnt lgkmcnt(3)
; __device__ __forceinline__ unsigned cvt_pk_bf16(float lo, float hi) { unsigned r; asm volatile("v_cvt_pk_bf16_f32 %0, %1, %2" : "=v"(r) : "v"(lo), "v"(hi)); return r; }
;     __device__ __forceinline__ void operator()(const AccT& acc, const Unit& u, int wr, int wc, int fr, int fq) const {
;     ...
;                     if constexpr (ROPE) {
;                         const int t = t0 & 2047;
; #pragma unroll
;                         for (int hf = 0; hf < 2; ++hf) {
;                             f32x4 cs, sn;
;                             if (m < 2) { const float c1 = ropeA[(t >> 6) * 16 + d], s1 = ropeA[1024 + (t >> 6) * 16 + d]; cs = (f32x4){c1, c1, c1, c1}; sn = (f32x4){s1, s1, s1, s1}; }
;                             else { const float* cb = ropeA + 2048 + (d - 16) * 64 + (t & 63) + 4 * hf; cs = *(const f32x4*)(cb); sn = *(const f32x4*)(cb + 1024); }
; #pragma unroll
;                             for (int jj = 0; jj < 4; ++jj) { const float pr = __shfl_xor(v[4 * hf + jj], 4); v[4 * hf + jj] = v[4 * hf + jj] * cs[jj] + sgn * pr * sn[jj]; }
;                             __builtin_amdgcn_sched_barrier(0);
;                         }
;                     }
;                     float zf[8], zb[8]; zf[0] = zf0; zb[0] = zb0;
; #pragma unroll
;                     for (int jj = 1; jj < 8; ++jj) { zf[jj] = zf[jj - 1] * zfs; zb[jj] = zb[jj - 1] * zbs; }
;                     u32x4 wf, wb;
;                     wf.x = cvt_pk_bf16(v[0] * zf[0], v[1] * zf[1]); wf.y = cvt_pk_bf16(v[2] * zf[2], v[3] * zf[3]); wf.z = cvt_pk_bf16(v[4] * zf[4], v[5] * zf[5]); wf.w = cvt_pk_bf16(v[6] * zf[6], v[7] * zf[7]);
;                     wb.x = cvt_pk_bf16(v[0] * zb[0], v[1] * zb[1]); wb.y = cvt_pk_bf16(v[2] * zb[2], v[3] * zb[3]); wb.z = cvt_pk_bf16(v[4] * zb[4], v[5] * zb[5]); wb.w = cvt_pk_bf16(v[6] * zb[6], v[7] * zb[7]);
;                     *(u32x4*)(KTZ + (size_t)r * NT + t0) = wf;
;                     *(u32x4*)(KTZ + (size_t)(256 + r) * NT + t0) = wb;
	v_cndmask_b32_e64 v119, v119, -v119, vcc
	s_waitcnt vmcnt(0)
	v_pk_mul_f32 v[126:127], v[116:117], v[118:119]
	s_waitcnt lgkmcnt(2)
	v_cndmask_b32_e64 v119, v100, -v100, vcc
	v_mov_b32_e32 v116, v101
	v_pk_mul_f32 v[100:101], v[116:117], v[118:119]
	s_waitcnt lgkmcnt(1)
	v_cndmask_b32_e64 v119, v153, -v153, vcc
	v_mov_b32_e32 v116, v102
	v_add_f32_e32 v126, v126, v127
	v_add_f32_e32 v127, v100, v101
	v_pk_mul_f32 v[100:101], v[116:117], v[118:119]
	s_waitcnt lgkmcnt(0)
	v_cndmask_b32_e64 v119, v157, -v157, vcc
	v_mov_b32_e32 v116, v103
	v_add_f32_e32 v153, v100, v101
	v_pk_mul_f32 v[100:101], v[116:117], v[118:119]
	s_nop 0
	v_add_f32_e32 v118, v100, v101
	global_load_dword v101, v[104:105], off
	global_load_dword v102, v[106:107], off
	ds_bpermute_b32 v103, v177, v96
	v_mov_b32_e32 v100, v96
	ds_bpermute_b32 v96, v177, v97
	ds_bpermute_b32 v119, v177, v98
	ds_bpermute_b32 v157, v177, v99
	s_waitcnt lgkmcnt(3)
	v_cndmask_b32_e64 v103, v103, -v103, vcc
	s_waitcnt vmcnt(0)
	v_pk_mul_f32 v[116:117], v[100:101], v[102:103]
	s_waitcnt lgkmcnt(2)
	v_cndmask_b32_e64 v103, v96, -v96, vcc
	v_mov_b32_e32 v100, v97
	v_pk_mul_f32 v[96:97], v[100:101], v[102:103]
	s_waitcnt lgkmcnt(1)
	v_cndmask_b32_e64 v103, v119, -v119, vcc
	v_mov_b32_e32 v100, v98
	v_add_f32_e32 v116, v116, v117
	v_add_f32_e32 v117, v96, v97
	v_pk_mul_f32 v[96:97], v[100:101], v[102:103]
	s_waitcnt lgkmcnt(0)
	v_cndmask_b32_e64 v103, v157, -v157, vcc
	v_mov_b32_e32 v100, v99
	v_add_f32_e32 v119, v96, v97
	v_pk_mul_f32 v[96:97], v[100:101], v[102:103]
	s_nop 0
	v_add_f32_e32 v103, v96, v97
	v_mul_f32_e32 v96, v180, v126
	v_mul_f32_e32 v97, v181, v127
	v_cvt_pk_bf16_f32 v96, v96, v97
	v_mul_f32_e32 v97, v167, v153
	v_mul_f32_e32 v98, v183, v118
	v_cvt_pk_bf16_f32 v97, v97, v98
	v_mul_f32_e32 v98, v182, v116
	v_mul_f32_e32 v99, v185, v117
	v_cvt_pk_bf16_f32 v98, v98, v99
	v_mul_f32_e32 v99, v184, v119
	v_mul_f32_e32 v100, v159, v103
	v_cvt_pk_bf16_f32 v99, v99, v100
	v_mul_f32_e32 v100, v150, v126
	v_mul_f32_e32 v101, v152, v127
	v_cvt_pk_bf16_f32 v100, v100, v101
	v_mul_f32_e32 v101, v154, v153
	v_mul_f32_e32 v102, v156, v118
	v_cvt_pk_bf16_f32 v101, v101, v102
	v_mul_f32_e32 v102, v158, v116
	v_mul_f32_e32 v116, v160, v117
	v_mul_f32_e32 v103, v155, v103
	v_cvt_pk_bf16_f32 v102, v102, v116
	v_mul_f32_e32 v116, v151, v119
	v_cvt_pk_bf16_f32 v103, v116, v103
	global_store_dwordx4 v[108:109], v[96:99], off offset:256
	global_store_dwordx4 v[110:111], v[100:103], off offset:256
	s_nop 1
	v_lshlrev_b32_e32 v100, 6, v136
	v_ashrrev_i32_e32 v101, 31, v100
	v_lshlrev_b64 v[102:103], 2, v[100:101]
	v_lshl_add_u64 v[96:97], s[24:25], 0, v[102:103]
	v_lshlrev_b32_e32 v136, 2, v186
	v_lshl_add_u64 v[96:97], v[96:97], 0, v[136:137]
	v_add_co_u32_e64 v98, s[4:5], s61, v96
	ds_bpermute_b32 v101, v177, v92
	s_nop 0
	v_addc_co_u32_e64 v99, s[4:5], 0, v97, s[4:5]
	global_load_dwordx4 v[108:111], v[98:99], off
	global_load_dwordx4 v[116:119], v[96:97], off
	ds_bpermute_b32 v127, v177, v93
	ds_bpermute_b32 v153, v177, v94
	ds_bpermute_b32 v157, v177, v95
	v_mov_b32_e32 v126, v92
	v_mov_b32_e32 v92, v94
	s_waitcnt lgkmcnt(3)
	v_cndmask_b32_e64 v163, v101, -v101, vcc
	s_waitcnt lgkmcnt(2)
	v_cndmask_b32_e64 v165, v127, -v127, vcc
	s_waitcnt lgkmcnt(1)
	v_cndmask_b32_e64 v187, v153, -v153, vcc
	s_waitcnt lgkmcnt(0)
	v_cndmask_b32_e64 v189, v157, -v157, vcc
	s_waitcnt vmcnt(1)
	v_mov_b32_e32 v127, v108
	s_waitcnt vmcnt(0)
	v_mov_b32_e32 v162, v116
	v_mov_b32_e32 v108, v93
	v_mov_b32_e32 v164, v117
	v_mov_b32_e32 v93, v110
	v_mov_b32_e32 v186, v118
	v_mov_b32_e32 v110, v95
	v_mov_b32_e32 v188, v119
	v_pk_mul_f32 v[94:95], v[126:127], v[162:163]
	v_pk_mul_f32 v[108:109], v[108:109], v[164:165]
	v_pk_mul_f32 v[92:93], v[92:93], v[186:187]
	v_pk_mul_f32 v[110:111], v[110:111], v[188:189]
	v_add_f32_e32 v101, v94, v95
	v_add_f32_e32 v153, v108, v109
	v_add_f32_e32 v157, v92, v93
	v_add_f32_e32 v161, v110, v111
	v_lshl_add_u64 v[92:93], s[16:17], 0, v[102:103]
	v_lshl_add_u64 v[94:95], v[92:93], 0, v[136:137]
	v_add_co_u32_e64 v92, s[4:5], s62, v94
	ds_bpermute_b32 v103, v177, v88
	s_nop 0
	v_addc_co_u32_e64 v93, s[4:5], 0, v95, s[4:5]
	v_add_co_u32_e64 v94, s[4:5], s49, v94
	ds_bpermute_b32 v126, v177, v89
	s_nop 0
	v_addc_co_u32_e64 v95, s[4:5], 0, v95, s[4:5]
	global_load_dwordx4 v[108:111], v[92:93], off offset:16
	global_load_dwordx4 v[116:119], v[94:95], off offset:16
	ds_bpermute_b32 v162, v177, v90
	ds_bpermute_b32 v164, v177, v91
	v_mov_b32_e32 v102, v88
	v_mov_b32_e32 v88, v90
	s_waitcnt lgkmcnt(3)
	v_cndmask_b32_e64 v127, v103, -v103, vcc
	s_waitcnt lgkmcnt(2)
	v_cndmask_b32_e64 v163, v126, -v126, vcc
	s_waitcnt lgkmcnt(1)
	v_cndmask_b32_e64 v165, v162, -v162, vcc
	s_waitcnt lgkmcnt(0)
	v_cndmask_b32_e64 v187, v164, -v164, vcc
	s_waitcnt vmcnt(1)
	v_mov_b32_e32 v103, v108
	s_waitcnt vmcnt(0)
; __device__ __forceinline__ unsigned cvt_pk_bf16(float lo, float hi) { unsigned r; asm volatile("v_cvt_pk_bf16_f32 %0, %1, %2" : "=v"(r) : "v"(lo), "v"(hi)); return r; }
;     __device__ __forceinline__ void operator()(const AccT& acc, const Unit& u, int wr, int wc, int fr, int fq) const {
;     ...
;                     if constexpr (ROPE) {
;                         const int t = t0 & 2047;
; #pragma unroll
;                         for (int hf = 0; hf < 2; ++hf) {
;                             f32x4 cs, sn;
;                             if (m < 2) { const float c1 = ropeA[(t >> 6) * 16 + d], s1 = ropeA[1024 + (t >> 6) * 16 + d]; cs = (f32x4){c1, c1, c1, c1}; sn = (f32x4){s1, s1, s1, s1}; }
;                             else { const float* cb = ropeA + 2048 + (d - 16) * 64 + (t & 63) + 4 * hf; cs = *(const f32x4*)(cb); sn = *(const f32x4*)(cb + 1024); }
; #pragma unroll
;                             for (int jj = 0; jj < 4; ++jj) { const float pr = __shfl_xor(v[4 * hf + jj], 4); v[4 * hf + jj] = v[4 * hf + jj] * cs[jj] + sgn * pr * sn[jj]; }
;                             __builtin_amdgcn_sched_barrier(0);
;                         }
;                     }
;                     float zf[8], zb[8]; zf[0] = zf0; zb[0] = zb0;
; #pragma unroll
;                     for (int jj = 1; jj < 8; ++jj) { zf[jj] = zf[jj - 1] * zfs; zb[jj] = zb[jj - 1] * zbs; }
;                     u32x4 wf, wb;
;                     wf.x = cvt_pk_bf16(v[0] * zf[0], v[1] * zf[1]); wf.y = cvt_pk_bf16(v[2] * zf[2], v[3] * zf[3]); wf.z = cvt_pk_bf16(v[4] * zf[4], v[5] * zf[5]); wf.w = cvt_pk_bf16(v[6] * zf[6], v[7] * zf[7]);
;                     wb.x = cvt_pk_bf16(v[0] * zb[0], v[1] * zb[1]); wb.y = cvt_pk_bf16(v[2] * zb[2], v[3] * zb[3]); wb.z = cvt_pk_bf16(v[4] * zb[4], v[5] * zb[5]); wb.w = cvt_pk_bf16(v[6] * zb[6], v[7] * zb[7]);
;                     *(u32x4*)(KTZ + (size_t)r * NT + t0) = wf;
;                     *(u32x4*)(KTZ + (size_t)(256 + r) * NT + t0) = wb;
	v_mov_b32_e32 v126, v116
	v_mov_b32_e32 v108, v89
	v_mov_b32_e32 v162, v117
	v_mov_b32_e32 v89, v110
	v_mov_b32_e32 v164, v118
	v_mov_b32_e32 v110, v91
	v_mov_b32_e32 v186, v119
	v_pk_mul_f32 v[90:91], v[102:103], v[126:127]
	v_pk_mul_f32 v[102:103], v[108:109], v[162:163]
	v_pk_mul_f32 v[88:89], v[88:89], v[164:165]
	v_pk_mul_f32 v[108:109], v[110:111], v[186:187]
	v_add_f32_e32 v90, v90, v91
	v_add_f32_e32 v91, v102, v103
	v_add_f32_e32 v88, v88, v89
	v_add_f32_e32 v89, v108, v109
	v_mul_f32_e32 v102, v180, v101
	v_mul_f32_e32 v103, v181, v153
	v_cvt_pk_bf16_f32 v108, v102, v103
	v_mul_f32_e32 v102, v167, v157
	v_mul_f32_e32 v103, v183, v161
	v_cvt_pk_bf16_f32 v109, v102, v103
	v_mul_f32_e32 v102, v182, v90
	v_mul_f32_e32 v103, v185, v91
	v_cvt_pk_bf16_f32 v110, v102, v103
	v_mul_f32_e32 v102, v184, v88
	v_mul_f32_e32 v103, v159, v89
	v_cvt_pk_bf16_f32 v111, v102, v103
	v_mul_f32_e32 v101, v150, v101
	v_mul_f32_e32 v102, v152, v153
	v_mul_f32_e32 v88, v151, v88
	v_mul_f32_e32 v89, v155, v89
	s_mov_b64 s[0:1], 0x400000
	v_cvt_pk_bf16_f32 v116, v101, v102
	v_mul_f32_e32 v101, v154, v157
	v_mul_f32_e32 v102, v156, v161
	v_cvt_pk_bf16_f32 v117, v101, v102
	v_mul_f32_e32 v90, v158, v90
	v_mul_f32_e32 v91, v160, v91
	v_cvt_pk_bf16_f32 v118, v90, v91
	v_cvt_pk_bf16_f32 v119, v88, v89
	v_lshl_add_u64 v[88:89], v[120:121], 0, s[0:1]
	s_mov_b32 s0, 0x400000
	v_add_co_u32_e64 v90, s[4:5], s0, v120
	s_mov_b64 s[0:1], 0x2400000
	s_nop 0
	v_addc_co_u32_e64 v91, s[4:5], 0, v121, s[4:5]
	global_store_dwordx4 v[90:91], v[108:111], off
	v_lshl_add_u64 v[90:91], v[120:121], 0, s[0:1]
	s_mov_b32 s0, 0x2400000
	v_add_co_u32_e64 v102, s[4:5], s0, v120
	s_nop 1
	v_addc_co_u32_e64 v103, s[4:5], 0, v121, s[4:5]
	global_store_dwordx4 v[102:103], v[116:119], off
	global_load_dwordx4 v[108:111], v[98:99], off
	s_nop 0
	global_load_dwordx4 v[116:119], v[96:97], off
	ds_bpermute_b32 v101, v177, v84
	ds_bpermute_b32 v103, v177, v85
	ds_bpermute_b32 v126, v177, v86
	ds_bpermute_b32 v153, v177, v87
	v_mov_b32_e32 v102, v84
	v_mov_b32_e32 v84, v86
	s_waitcnt lgkmcnt(3)
	v_cndmask_b32_e64 v127, v101, -v101, vcc
	s_waitcnt lgkmcnt(2)
	v_cndmask_b32_e64 v163, v103, -v103, vcc
	s_waitcnt lgkmcnt(1)
	v_cndmask_b32_e64 v165, v126, -v126, vcc
	s_waitcnt lgkmcnt(0)
	v_cndmask_b32_e64 v187, v153, -v153, vcc
	s_waitcnt vmcnt(1)
	v_mov_b32_e32 v103, v108
	s_waitcnt vmcnt(0)
	v_mov_b32_e32 v126, v116
	v_mov_b32_e32 v108, v85
	v_mov_b32_e32 v162, v117
	v_mov_b32_e32 v85, v110
	v_mov_b32_e32 v164, v118
	v_mov_b32_e32 v110, v87
	v_mov_b32_e32 v186, v119
	v_pk_mul_f32 v[86:87], v[102:103], v[126:127]
	v_pk_mul_f32 v[102:103], v[108:109], v[162:163]
	v_pk_mul_f32 v[84:85], v[84:85], v[164:165]
	v_pk_mul_f32 v[108:109], v[110:111], v[186:187]
	v_add_f32_e32 v101, v86, v87
	v_add_f32_e32 v153, v102, v103
	v_add_f32_e32 v157, v84, v85
	v_add_f32_e32 v161, v108, v109
	global_load_dwordx4 v[84:87], v[92:93], off offset:16
	global_load_dwordx4 v[108:111], v[94:95], off offset:16
	ds_bpermute_b32 v103, v177, v80
	ds_bpermute_b32 v116, v177, v81
	ds_bpermute_b32 v118, v177, v82
	ds_bpermute_b32 v126, v177, v83
	v_mov_b32_e32 v102, v80
	v_mov_b32_e32 v80, v82
	s_waitcnt lgkmcnt(3)
	v_cndmask_b32_e64 v117, v103, -v103, vcc
	s_waitcnt lgkmcnt(2)
	v_cndmask_b32_e64 v119, v116, -v116, vcc
	s_waitcnt lgkmcnt(1)
	v_cndmask_b32_e64 v127, v118, -v118, vcc
	s_waitcnt lgkmcnt(0)
	v_cndmask_b32_e64 v163, v126, -v126, vcc
	s_waitcnt vmcnt(1)
	v_mov_b32_e32 v103, v84
	s_waitcnt vmcnt(0)
	v_mov_b32_e32 v116, v108
	v_mov_b32_e32 v84, v81
	v_mov_b32_e32 v118, v109
	v_mov_b32_e32 v81, v86
	v_mov_b32_e32 v126, v110
	v_mov_b32_e32 v86, v83
	v_mov_b32_e32 v162, v111
	v_pk_mul_f32 v[82:83], v[102:103], v[116:117]
	v_pk_mul_f32 v[84:85], v[84:85], v[118:119]
	v_pk_mul_f32 v[80:81], v[80:81], v[126:127]
	v_pk_mul_f32 v[86:87], v[86:87], v[162:163]
	v_add_f32_e32 v102, v82, v83
	v_add_f32_e32 v103, v84, v85
	v_add_f32_e32 v108, v80, v81
	v_add_f32_e32 v87, v86, v87
	v_mul_f32_e32 v80, v180, v101
	v_mul_f32_e32 v81, v181, v153
	v_cvt_pk_bf16_f32 v80, v80, v81
	v_mul_f32_e32 v81, v167, v157
	v_mul_f32_e32 v82, v183, v161
	v_cvt_pk_bf16_f32 v81, v81, v82
	v_mul_f32_e32 v82, v182, v102
	v_mul_f32_e32 v83, v185, v103
	v_cvt_pk_bf16_f32 v82, v82, v83
	v_mul_f32_e32 v83, v184, v108
	v_mul_f32_e32 v84, v159, v87
	v_cvt_pk_bf16_f32 v83, v83, v84
	v_mul_f32_e32 v84, v150, v101
	v_mul_f32_e32 v85, v152, v153
	v_cvt_pk_bf16_f32 v84, v84, v85
	v_mul_f32_e32 v85, v154, v157
	v_mul_f32_e32 v86, v156, v161
	v_cvt_pk_bf16_f32 v85, v85, v86
	v_mul_f32_e32 v86, v158, v102
	v_mul_f32_e32 v101, v160, v103
	v_mul_f32_e32 v87, v155, v87
	v_cvt_pk_bf16_f32 v86, v86, v101
	v_mul_f32_e32 v101, v151, v108
	v_cvt_pk_bf16_f32 v87, v101, v87
	global_store_dwordx4 v[88:89], v[80:83], off offset:256
	global_store_dwordx4 v[90:91], v[84:87], off offset:256
	s_nop 0
	v_add_u32_e32 v80, 0x200, v100
	v_ashrrev_i32_e32 v81, 31, v80
	v_lshl_add_u64 v[82:83], s[24:25], 0, v[136:137]
	v_lshlrev_b64 v[100:101], 2, v[80:81]
	v_lshl_add_u64 v[80:81], v[82:83], 0, v[100:101]
	v_add_co_u32_e64 v82, s[4:5], s61, v80
	ds_bpermute_b32 v103, v177, v76
	s_nop 0
	v_addc_co_u32_e64 v83, s[4:5], 0, v81, s[4:5]
	global_load_dwordx4 v[84:87], v[82:83], off
	global_load_dwordx4 v[88:91], v[80:81], off
	ds_bpermute_b32 v108, v177, v77
	ds_bpermute_b32 v110, v177, v78
	ds_bpermute_b32 v116, v177, v79
	v_mov_b32_e32 v102, v76
	v_mov_b32_e32 v76, v78
	s_waitcnt lgkmcnt(3)
	v_cndmask_b32_e64 v109, v103, -v103, vcc
	s_waitcnt lgkmcnt(2)
	v_cndmask_b32_e64 v111, v108, -v108, vcc
	s_waitcnt lgkmcnt(1)
	v_cndmask_b32_e64 v117, v110, -v110, vcc
	s_waitcnt lgkmcnt(0)
; __device__ __forceinline__ unsigned cvt_pk_bf16(float lo, float hi) { unsigned r; asm volatile("v_cvt_pk_bf16_f32 %0, %1, %2" : "=v"(r) : "v"(lo), "v"(hi)); return r; }
;     __device__ __forceinline__ void operator()(const AccT& acc, const Unit& u, int wr, int wc, int fr, int fq) const {
;     ...
;                     if constexpr (ROPE) {
;                         const int t = t0 & 2047;
; #pragma unroll
;                         for (int hf = 0; hf < 2; ++hf) {
;                             f32x4 cs, sn;
;                             if (m < 2) { const float c1 = ropeA[(t >> 6) * 16 + d], s1 = ropeA[1024 + (t >> 6) * 16 + d]; cs = (f32x4){c1, c1, c1, c1}; sn = (f32x4){s1, s1, s1, s1}; }
;                             else { const float* cb = ropeA + 2048 + (d - 16) * 64 + (t & 63) + 4 * hf; cs = *(const f32x4*)(cb); sn = *(const f32x4*)(cb + 1024); }
; #pragma unroll
;                             for (int jj = 0; jj < 4; ++jj) { const float pr = __shfl_xor(v[4 * hf + jj], 4); v[4 * hf + jj] = v[4 * hf + jj] * cs[jj] + sgn * pr * sn[jj]; }
;                             __builtin_amdgcn_sched_barrier(0);
;                         }
;                     }
;                     float zf[8], zb[8]; zf[0] = zf0; zb[0] = zb0;
; #pragma unroll
;                     for (int jj = 1; jj < 8; ++jj) { zf[jj] = zf[jj - 1] * zfs; zb[jj] = zb[jj - 1] * zbs; }
;                     u32x4 wf, wb;
;                     wf.x = cvt_pk_bf16(v[0] * zf[0], v[1] * zf[1]); wf.y = cvt_pk_bf16(v[2] * zf[2], v[3] * zf[3]); wf.z = cvt_pk_bf16(v[4] * zf[4], v[5] * zf[5]); wf.w = cvt_pk_bf16(v[6] * zf[6], v[7] * zf[7]);
;                     wb.x = cvt_pk_bf16(v[0] * zb[0], v[1] * zb[1]); wb.y = cvt_pk_bf16(v[2] * zb[2], v[3] * zb[3]); wb.z = cvt_pk_bf16(v[4] * zb[4], v[5] * zb[5]); wb.w = cvt_pk_bf16(v[6] * zb[6], v[7] * zb[7]);
;                     *(u32x4*)(KTZ + (size_t)r * NT + t0) = wf;
;                     *(u32x4*)(KTZ + (size_t)(256 + r) * NT + t0) = wb;
	v_cndmask_b32_e64 v119, v116, -v116, vcc
	s_waitcnt vmcnt(1)
	v_mov_b32_e32 v103, v84
	s_waitcnt vmcnt(0)
	v_mov_b32_e32 v108, v88
	v_mov_b32_e32 v84, v77
	v_mov_b32_e32 v110, v89
	v_mov_b32_e32 v77, v86
	v_mov_b32_e32 v116, v90
	v_mov_b32_e32 v86, v79
	v_mov_b32_e32 v118, v91
	v_pk_mul_f32 v[78:79], v[102:103], v[108:109]
	v_pk_mul_f32 v[84:85], v[84:85], v[110:111]
	v_pk_mul_f32 v[76:77], v[76:77], v[116:117]
	v_pk_mul_f32 v[86:87], v[86:87], v[118:119]
	v_add_f32_e32 v118, v78, v79
	v_add_f32_e32 v119, v84, v85
	v_add_f32_e32 v126, v76, v77
	v_add_f32_e32 v127, v86, v87
	v_lshl_add_u64 v[76:77], s[16:17], 0, v[100:101]
	v_lshl_add_u64 v[78:79], v[76:77], 0, v[136:137]
	v_add_co_u32_e64 v76, s[4:5], s62, v78
	ds_bpermute_b32 v101, v177, v72
	s_nop 0
	v_addc_co_u32_e64 v77, s[4:5], 0, v79, s[4:5]
	v_add_co_u32_e64 v78, s[4:5], s49, v78
	ds_bpermute_b32 v102, v177, v73
	s_nop 0
	v_addc_co_u32_e64 v79, s[4:5], 0, v79, s[4:5]
	global_load_dwordx4 v[84:87], v[76:77], off offset:16
	global_load_dwordx4 v[88:91], v[78:79], off offset:16
	ds_bpermute_b32 v108, v177, v74
	ds_bpermute_b32 v110, v177, v75
	v_mov_b32_e32 v100, v72
	v_mov_b32_e32 v72, v74
	s_waitcnt lgkmcnt(3)
	v_cndmask_b32_e64 v103, v101, -v101, vcc
	s_waitcnt lgkmcnt(2)
	v_cndmask_b32_e64 v109, v102, -v102, vcc
	s_waitcnt lgkmcnt(1)
	v_cndmask_b32_e64 v111, v108, -v108, vcc
	s_waitcnt lgkmcnt(0)
	v_cndmask_b32_e64 v117, v110, -v110, vcc
	s_waitcnt vmcnt(1)
	v_mov_b32_e32 v101, v84
	s_waitcnt vmcnt(0)
	v_mov_b32_e32 v102, v88
	v_mov_b32_e32 v84, v73
	v_mov_b32_e32 v108, v89
	v_mov_b32_e32 v73, v86
	v_mov_b32_e32 v110, v90
	v_mov_b32_e32 v86, v75
	v_mov_b32_e32 v116, v91
	v_pk_mul_f32 v[74:75], v[100:101], v[102:103]
	v_pk_mul_f32 v[84:85], v[84:85], v[108:109]
	v_pk_mul_f32 v[72:73], v[72:73], v[110:111]
	v_pk_mul_f32 v[86:87], v[86:87], v[116:117]
	v_add_f32_e32 v74, v74, v75
	v_add_f32_e32 v75, v84, v85
	v_add_f32_e32 v72, v72, v73
	v_add_f32_e32 v73, v86, v87
	v_mul_f32_e32 v84, v180, v118
	v_mul_f32_e32 v85, v181, v119
	v_cvt_pk_bf16_f32 v84, v84, v85
	v_mul_f32_e32 v85, v167, v126
	v_mul_f32_e32 v86, v183, v127
	v_cvt_pk_bf16_f32 v85, v85, v86
	v_mul_f32_e32 v86, v182, v74
	v_mul_f32_e32 v87, v185, v75
	v_cvt_pk_bf16_f32 v86, v86, v87
	v_mul_f32_e32 v87, v184, v72
	v_mul_f32_e32 v88, v159, v73
	v_cvt_pk_bf16_f32 v87, v87, v88
	v_mul_f32_e32 v88, v150, v118
	v_mul_f32_e32 v89, v152, v119
	v_cvt_pk_bf16_f32 v88, v88, v89
	v_mul_f32_e32 v89, v154, v126
	v_mul_f32_e32 v90, v156, v127
	v_mul_f32_e32 v72, v151, v72
	v_mul_f32_e32 v73, v155, v73
	s_mov_b64 s[0:1], 0x600000
	v_cvt_pk_bf16_f32 v89, v89, v90
	v_mul_f32_e32 v74, v158, v74
	v_mul_f32_e32 v75, v160, v75
	v_cvt_pk_bf16_f32 v90, v74, v75
	v_cvt_pk_bf16_f32 v91, v72, v73
	v_lshl_add_u64 v[72:73], v[120:121], 0, s[0:1]
	s_mov_b32 s0, 0x600000
	v_add_co_u32_e64 v74, s[4:5], s0, v120
	s_mov_b64 s[0:1], 0x2600000
	s_nop 0
	v_addc_co_u32_e64 v75, s[4:5], 0, v121, s[4:5]
	global_store_dwordx4 v[74:75], v[84:87], off
	v_lshl_add_u64 v[74:75], v[120:121], 0, s[0:1]
	s_mov_b32 s0, 0x2600000
	v_add_co_u32_e64 v84, s[4:5], s0, v120
	s_nop 1
	v_addc_co_u32_e64 v85, s[4:5], 0, v121, s[4:5]
	global_store_dwordx4 v[84:85], v[88:91], off
	global_load_dwordx4 v[84:87], v[82:83], off
	s_nop 0
	global_load_dwordx4 v[88:91], v[80:81], off
	ds_bpermute_b32 v101, v177, v68
	ds_bpermute_b32 v102, v177, v69
	ds_bpermute_b32 v108, v177, v70
	ds_bpermute_b32 v110, v177, v71
	v_mov_b32_e32 v100, v68
	v_mov_b32_e32 v68, v70
	s_waitcnt lgkmcnt(3)
	v_cndmask_b32_e64 v103, v101, -v101, vcc
	s_waitcnt lgkmcnt(2)
	v_cndmask_b32_e64 v109, v102, -v102, vcc
	s_waitcnt lgkmcnt(1)
	v_cndmask_b32_e64 v111, v108, -v108, vcc
	s_waitcnt lgkmcnt(0)
	v_cndmask_b32_e64 v117, v110, -v110, vcc
	s_waitcnt vmcnt(1)
	v_mov_b32_e32 v101, v84
	s_waitcnt vmcnt(0)
	v_mov_b32_e32 v102, v88
	v_mov_b32_e32 v84, v69
	v_mov_b32_e32 v108, v89
	v_mov_b32_e32 v69, v86
	v_mov_b32_e32 v110, v90
	v_mov_b32_e32 v86, v71
	v_mov_b32_e32 v116, v91
	v_pk_mul_f32 v[70:71], v[100:101], v[102:103]
	v_pk_mul_f32 v[84:85], v[84:85], v[108:109]
	v_pk_mul_f32 v[68:69], v[68:69], v[110:111]
	v_pk_mul_f32 v[86:87], v[86:87], v[116:117]
	v_add_f32_e32 v110, v70, v71
	v_add_f32_e32 v111, v84, v85
	v_add_f32_e32 v116, v68, v69
	v_add_f32_e32 v117, v86, v87
	global_load_dwordx4 v[68:71], v[76:77], off offset:16
	global_load_dwordx4 v[84:87], v[78:79], off offset:16
	ds_bpermute_b32 v89, v177, v64
	ds_bpermute_b32 v90, v177, v65
	ds_bpermute_b32 v100, v177, v66
	ds_bpermute_b32 v102, v177, v67
	v_mov_b32_e32 v88, v64
	v_mov_b32_e32 v64, v66
	s_waitcnt lgkmcnt(3)
	v_cndmask_b32_e64 v91, v89, -v89, vcc
	s_waitcnt lgkmcnt(2)
	v_cndmask_b32_e64 v101, v90, -v90, vcc
	s_waitcnt lgkmcnt(1)
	v_cndmask_b32_e64 v103, v100, -v100, vcc
	s_waitcnt lgkmcnt(0)
	v_cndmask_b32_e64 v109, v102, -v102, vcc
	s_waitcnt vmcnt(1)
	v_mov_b32_e32 v89, v68
	s_waitcnt vmcnt(0)
;     __device__ __forceinline__ void operator()(const AccT& acc, const Unit& u, int wr, int wc, int fr, int fq) const {
;     ...
;         for (int ai = 0; ai < 2; ++ai) {
;             const int hh = 2 * ai + wr;
;             const float l2f = lgd[hh] * 1.4426950408889634f, l2b = lgd[4 + hh] * 1.4426950408889634f;
;             const float zf0 = exp2f((float)(127 - o0) * l2f), zfs = exp2f(-l2f), zb0 = exp2f((float)o0 * l2b), zbs = exp2f(l2b);
; #pragma unroll
;             for (int m = 0; m < 4; ++m) {
;                 const int r = rbase + ai * 128 + m * 16;
;                 const int d = 4 * (2 * m + (fr >> 3)) + j;
; #pragma unroll
;                 for (int bj = 0; bj < 2; ++bj) {
;                     const int t0 = tb + bj * 128;
;                     float v[8];
; #pragma unroll
;                     for (int jj = 0; jj < 4; ++jj) { v[jj] = acc[ai][bj][m][0][jj]; v[4 + jj] = acc[ai][bj][m][1][jj]; }
;                     if constexpr (ROPE) {
;                         const int t = t0 & 2047;
; #pragma unroll
;                         for (int hf = 0; hf < 2; ++hf) {
;                             f32x4 cs, sn;
;                             if (m < 2) { const float c1 = ropeA[(t >> 6) * 16 + d], s1 = ropeA[1024 + (t >> 6) * 16 + d]; cs = (f32x4){c1, c1, c1, c1}; sn = (f32x4){s1, s1, s1, s1}; }
;                             else { const float* cb = ropeA + 2048 + (d - 16) * 64 + (t & 63) + 4 * hf; cs = *(const f32x4*)(cb); sn = *(const f32x4*)(cb + 1024); }
; #pragma unroll
;                             for (int jj = 0; jj < 4; ++jj) { const float pr = __shfl_xor(v[4 * hf + jj], 4); v[4 * hf + jj] = v[4 * hf + jj] * cs[jj] + sgn * pr * sn[jj]; }
;                             __builtin_amdgcn_sched_barrier(0);
;                         }
;                     }
;                     float zf[8], zb[8]; zf[0] = zf0; zb[0] = zb0;
; #pragma unroll
;                     for (int jj = 1; jj < 8; ++jj) { zf[jj] = zf[jj - 1] * zfs; zb[jj] = zb[jj - 1] * zbs; }
;                     u32x4 wf, wb;
;                     wf.x = cvt_pk_bf16(v[0] * zf[0], v[1] * zf[1]); wf.y = cvt_pk_bf16(v[2] * zf[2], v[3] * zf[3]); wf.z = cvt_pk_bf16(v[4] * zf[4], v[5] * zf[5]); wf.w = cvt_pk_bf16(v[6] * zf[6], v[7] * zf[7]);
	v_mov_b32_e32 v90, v84
	v_mov_b32_e32 v68, v65
	v_mov_b32_e32 v100, v85
	v_mov_b32_e32 v65, v70
	v_mov_b32_e32 v102, v86
	v_mov_b32_e32 v70, v67
	v_mov_b32_e32 v108, v87
	v_pk_mul_f32 v[66:67], v[88:89], v[90:91]
	v_pk_mul_f32 v[68:69], v[68:69], v[100:101]
	v_pk_mul_f32 v[64:65], v[64:65], v[102:103]
	v_pk_mul_f32 v[70:71], v[70:71], v[108:109]
	v_add_f32_e32 v84, v66, v67
	v_add_f32_e32 v85, v68, v69
	v_add_f32_e32 v86, v64, v65
	v_add_f32_e32 v71, v70, v71
	v_mul_f32_e32 v64, v180, v110
	v_mul_f32_e32 v65, v181, v111
	v_cvt_pk_bf16_f32 v64, v64, v65
	v_mul_f32_e32 v65, v167, v116
	v_mul_f32_e32 v66, v183, v117
	v_cvt_pk_bf16_f32 v65, v65, v66
	v_mul_f32_e32 v66, v182, v84
	v_mul_f32_e32 v67, v185, v85
	v_cvt_pk_bf16_f32 v66, v66, v67
	v_mul_f32_e32 v67, v184, v86
	v_mul_f32_e32 v68, v159, v71
	v_cvt_pk_bf16_f32 v67, v67, v68
	v_mul_f32_e32 v68, v150, v110
	v_mul_f32_e32 v69, v152, v111
	v_cvt_pk_bf16_f32 v68, v68, v69
	v_mul_f32_e32 v69, v154, v116
	v_mul_f32_e32 v70, v156, v117
	v_cvt_pk_bf16_f32 v69, v69, v70
	v_mul_f32_e32 v70, v158, v84
	v_mul_f32_e32 v84, v160, v85
	v_mul_f32_e32 v71, v155, v71
	v_cvt_pk_bf16_f32 v70, v70, v84
	v_mul_f32_e32 v84, v151, v86
	v_cvt_pk_bf16_f32 v71, v84, v71
	global_store_dwordx4 v[72:73], v[64:67], off offset:256
	global_store_dwordx4 v[74:75], v[68:71], off offset:256
	global_load_dword v64, v137, s[22:23] offset:8
	s_nop 0
	global_load_dword v70, v137, s[22:23] offset:24
	global_load_dword v67, v[146:147], off
	global_load_dword v74, v[148:149], off
	ds_bpermute_b32 v65, v177, v60
	ds_bpermute_b32 v68, v177, v62
	v_mov_b32_e32 v66, v60
	ds_bpermute_b32 v60, v177, v61
	ds_bpermute_b32 v71, v177, v63
	s_waitcnt lgkmcnt(3)
	v_cndmask_b32_e64 v75, v65, -v65, vcc
	s_waitcnt lgkmcnt(2)
	v_cndmask_b32_e64 v65, v68, -v68, vcc
	s_waitcnt vmcnt(3)
	v_mul_f32_e32 v72, 0x3fb8aa3b, v64
	s_waitcnt vmcnt(2)
	v_mul_f32_e32 v73, 0x3fb8aa3b, v70
	v_mul_f32_e32 v84, v72, v179
	s_waitcnt vmcnt(0)
	v_pk_mul_f32 v[68:69], v[66:67], v[74:75]
	s_waitcnt lgkmcnt(1)
	v_cndmask_b32_e64 v75, v60, -v60, vcc
	v_mov_b32_e32 v66, v61
	v_cmp_lt_f32_e64 s[4:5], s60, v72
	v_mul_f32_e32 v87, v73, v178
	v_pk_mul_f32 v[60:61], v[66:67], v[74:75]
	s_waitcnt lgkmcnt(0)
	v_cndmask_b32_e64 v75, v71, -v71, vcc
	v_mov_b32_e32 v66, v63
	v_cmp_gt_f32_e64 s[8:9], s59, v84
	v_cndmask_b32_e64 v86, 0, v176, s[4:5]
	v_cmp_gt_f32_e64 s[6:7], s59, v73
	s_and_b64 s[0:1], s[4:5], exec
	v_cmp_gt_f32_e64 s[4:5], s59, v87
	v_add_f32_e32 v110, v60, v61
	v_pk_mul_f32 v[60:61], v[66:67], v[74:75]
	v_cndmask_b32_e64 v66, 0, v176, s[8:9]
	v_cndmask_b32_e64 v88, 0, v176, s[6:7]
	v_add_f32_e32 v89, v68, v69
	v_fmac_f32_e32 v86, 0xbfb8aa3b, v64
	v_cndmask_b32_e64 v69, 0, v176, s[4:5]
	v_fmac_f32_e32 v66, v72, v179
	v_fmac_f32_e32 v88, 0x3fb8aa3b, v70
	v_exp_f32_e32 v68, v86
	v_fmac_f32_e32 v69, v73, v178
	v_exp_f32_e32 v66, v66
	v_exp_f32_e32 v70, v88
	v_exp_f32_e32 v69, v69
	v_cndmask_b32_e64 v63, 0, v175, s[8:9]
	s_cselect_b32 s8, 0xffffffc0, 0
	s_and_b64 s[0:1], s[6:7], exec
	v_cndmask_b32_e64 v64, 0, v175, s[4:5]
	s_cselect_b32 s0, 0xffffffc0, 0
	v_ldexp_f32 v100, v68, s8
	v_ldexp_f32 v63, v66, v63
	v_mul_f32_e32 v85, v62, v74
	v_ldexp_f32 v90, v70, s0
	v_ldexp_f32 v64, v69, v64
	v_mul_f32_e32 v75, v100, v63
	v_add_f32_e32 v111, v60, v61
	global_load_dword v108, v[148:149], off
	global_load_dword v69, v[146:147], off
	ds_bpermute_b32 v61, v177, v57
	ds_bpermute_b32 v60, v177, v56
	v_mov_b32_e32 v68, v57
	ds_bpermute_b32 v57, v177, v59
	ds_bpermute_b32 v66, v177, v58
	s_waitcnt lgkmcnt(3)
	v_cndmask_b32_e64 v109, v61, -v61, vcc
	s_waitcnt lgkmcnt(2)
	v_cndmask_b32_e64 v70, v60, -v60, vcc
	s_waitcnt lgkmcnt(0)
	v_cndmask_b32_e64 v72, v66, -v66, vcc
	s_waitcnt vmcnt(1)
	v_mul_f32_e32 v71, v56, v108
	s_waitcnt vmcnt(0)
	v_pk_mul_f32 v[60:61], v[68:69], v[108:109]
	v_cndmask_b32_e64 v109, v57, -v57, vcc
	v_mov_b32_e32 v68, v59
	v_add_f32_e32 v57, v60, v61
	v_pk_mul_f32 v[60:61], v[68:69], v[108:109]
	s_nop 0
	v_add_f32_e32 v59, v60, v61
	v_mov_b32_e32 v91, v67
	v_pk_mul_f32 v[60:61], v[90:91], v[64:65]
	v_mov_b32_e32 v91, v85
	v_pk_mul_f32 v[66:67], v[90:91], v[60:61]
	v_mov_b32_e32 v91, v69
	v_mov_b32_e32 v67, v70
	v_mul_f32_e32 v84, v100, v75
	v_pk_mul_f32 v[68:69], v[90:91], v[66:67]
	v_mov_b32_e32 v70, v90
	v_mul_f32_e32 v86, v100, v84
	v_pk_mul_f32 v[70:71], v[70:71], v[68:69]
	v_mul_f32_e32 v85, v100, v86
	v_mov_b32_e32 v71, v72
	v_mul_f32_e32 v88, v100, v85
	v_pk_mul_f32 v[72:73], v[90:91], v[70:71]
	v_fma_f32 v61, v62, v74, v61
	v_mul_f32_e32 v87, v100, v88
	v_mul_f32_e32 v65, v90, v72
	v_mul_f32_e32 v62, v84, v61
	v_fma_f32 v56, v56, v108, v69
	v_mul_f32_e32 v71, v100, v87
	v_mul_f32_e32 v67, v90, v65
	v_mul_f32_e32 v90, v63, v89
	v_mul_f32_e32 v91, v75, v110
	v_cvt_pk_bf16_f32 v100, v90, v91
	v_mul_f32_e32 v74, v86, v111
	v_cvt_pk_bf16_f32 v101, v62, v74
	v_mul_f32_e32 v62, v85, v56
	v_fma_f32 v58, v58, v108, v73
	v_mul_f32_e32 v69, v88, v57
	v_cvt_pk_bf16_f32 v102, v62, v69
	v_mul_f32_e32 v62, v87, v58
	v_mul_f32_e32 v69, v71, v59
	v_cvt_pk_bf16_f32 v103, v62, v69
	v_mul_f32_e32 v62, v64, v89
	v_mul_f32_e32 v56, v70, v56
	v_mul_f32_e32 v57, v72, v57
	v_mul_f32_e32 v69, v60, v110
	v_cvt_pk_bf16_f32 v108, v62, v69
	v_mul_f32_e32 v61, v66, v61
	v_mul_f32_e32 v62, v68, v111
	v_cvt_pk_bf16_f32 v109, v61, v62
	v_cvt_pk_bf16_f32 v110, v56, v57
	v_mul_f32_e32 v56, v65, v58
	v_mul_f32_e32 v57, v67, v59
	s_mov_b64 s[0:1], 0x1000000
	v_cvt_pk_bf16_f32 v111, v56, v57
	v_lshl_add_u64 v[56:57], v[120:121], 0, s[0:1]
	s_mov_b32 s0, 0x1000000
	v_add_co_u32_e64 v58, s[4:5], s0, v120
	s_mov_b64 s[0:1], 0x3000000
	s_nop 0
	v_addc_co_u32_e64 v59, s[4:5], 0, v121, s[4:5]
	global_store_dwordx4 v[58:59], v[100:103], off
	v_lshl_add_u64 v[58:59], v[120:121], 0, s[0:1]
	s_mov_b32 s0, 0x3000000
	v_add_co_u32_e64 v90, s[4:5], s0, v120
	s_nop 1
	v_addc_co_u32_e64 v91, s[4:5], 0, v121, s[4:5]
	global_store_dwordx4 v[90:91], v[108:111], off
	global_load_dword v91, v[122:123], off
	s_nop 0
	global_load_dword v100, v[124:125], off
	ds_bpermute_b32 v61, v177, v52
	v_mov_b32_e32 v90, v52
	ds_bpermute_b32 v52, v177, v53
	ds_bpermute_b32 v62, v177, v54
	ds_bpermute_b32 v69, v177, v55
	s_waitcnt lgkmcnt(3)
;     __device__ __forceinline__ void operator()(const AccT& acc, const Unit& u, int wr, int wc, int fr, int fq) const {
;     ...
;             for (int m = 0; m < 4; ++m) {
;                 const int r = rbase + ai * 128 + m * 16;
;                 const int d = 4 * (2 * m + (fr >> 3)) + j;
; #pragma unroll
;                 for (int bj = 0; bj < 2; ++bj) {
;                     const int t0 = tb + bj * 128;
;                     float v[8];
; #pragma unroll
;                     for (int jj = 0; jj < 4; ++jj) { v[jj] = acc[ai][bj][m][0][jj]; v[4 + jj] = acc[ai][bj][m][1][jj]; }
;                     if constexpr (ROPE) {
;                         const int t = t0 & 2047;
; #pragma unroll
;                         for (int hf = 0; hf < 2; ++hf) {
;                             f32x4 cs, sn;
;                             if (m < 2) { const float c1 = ropeA[(t >> 6) * 16 + d], s1 = ropeA[1024 + (t >> 6) * 16 + d]; cs = (f32x4){c1, c1, c1, c1}; sn = (f32x4){s1, s1, s1, s1}; }
;                             else { const float* cb = ropeA + 2048 + (d - 16) * 64 + (t & 63) + 4 * hf; cs = *(const f32x4*)(cb); sn = *(const f32x4*)(cb + 1024); }
; #pragma unroll
;                             for (int jj = 0; jj < 4; ++jj) { const float pr = __shfl_xor(v[4 * hf + jj], 4); v[4 * hf + jj] = v[4 * hf + jj] * cs[jj] + sgn * pr * sn[jj]; }
;                             __builtin_amdgcn_sched_barrier(0);
;                         }
;                     }
;                     float zf[8], zb[8]; zf[0] = zf0; zb[0] = zb0;
; #pragma unroll
;                     for (int jj = 1; jj < 8; ++jj) { zf[jj] = zf[jj - 1] * zfs; zb[jj] = zb[jj - 1] * zbs; }
;                     u32x4 wf, wb;
;                     wf.x = cvt_pk_bf16(v[0] * zf[0], v[1] * zf[1]); wf.y = cvt_pk_bf16(v[2] * zf[2], v[3] * zf[3]); wf.z = cvt_pk_bf16(v[4] * zf[4], v[5] * zf[5]); wf.w = cvt_pk_bf16(v[6] * zf[6], v[7] * zf[7]);
;                     wb.x = cvt_pk_bf16(v[0] * zb[0], v[1] * zb[1]); wb.y = cvt_pk_bf16(v[2] * zb[2], v[3] * zb[3]); wb.z = cvt_pk_bf16(v[4] * zb[4], v[5] * zb[5]); wb.w = cvt_pk_bf16(v[6] * zb[6], v[7] * zb[7]);
;                     *(u32x4*)(KTZ + (size_t)r * NT + t0) = wf;
;                     *(u32x4*)(KTZ + (size_t)(256 + r) * NT + t0) = wb;
	v_cndmask_b32_e64 v101, v61, -v61, vcc
	s_waitcnt vmcnt(0)
	v_pk_mul_f32 v[102:103], v[90:91], v[100:101]
	s_waitcnt lgkmcnt(2)
	v_cndmask_b32_e64 v101, v52, -v52, vcc
	v_mov_b32_e32 v90, v53
	v_pk_mul_f32 v[52:53], v[90:91], v[100:101]
	s_waitcnt lgkmcnt(1)
	v_cndmask_b32_e64 v101, v62, -v62, vcc
	v_mov_b32_e32 v90, v54
	v_add_f32_e32 v62, v52, v53
	v_pk_mul_f32 v[52:53], v[90:91], v[100:101]
	s_waitcnt lgkmcnt(0)
	v_cndmask_b32_e64 v101, v69, -v69, vcc
	v_mov_b32_e32 v90, v55
	v_add_f32_e32 v69, v52, v53
	v_pk_mul_f32 v[52:53], v[90:91], v[100:101]
	v_add_f32_e32 v61, v102, v103
	v_add_f32_e32 v73, v52, v53
	global_load_dword v53, v[122:123], off
	global_load_dword v54, v[124:125], off
	ds_bpermute_b32 v55, v177, v48
	v_mov_b32_e32 v52, v48
	ds_bpermute_b32 v48, v177, v49
	ds_bpermute_b32 v74, v177, v50
	ds_bpermute_b32 v89, v177, v51
	s_waitcnt lgkmcnt(3)
	v_cndmask_b32_e64 v55, v55, -v55, vcc
	s_waitcnt vmcnt(0)
	v_pk_mul_f32 v[90:91], v[52:53], v[54:55]
	s_waitcnt lgkmcnt(2)
	v_cndmask_b32_e64 v55, v48, -v48, vcc
	v_mov_b32_e32 v52, v49
	v_pk_mul_f32 v[48:49], v[52:53], v[54:55]
	s_waitcnt lgkmcnt(1)
	v_cndmask_b32_e64 v55, v74, -v74, vcc
	v_mov_b32_e32 v52, v50
	v_add_f32_e32 v74, v48, v49
	v_pk_mul_f32 v[48:49], v[52:53], v[54:55]
	s_waitcnt lgkmcnt(0)
	v_cndmask_b32_e64 v55, v89, -v89, vcc
	v_mov_b32_e32 v52, v51
	v_add_f32_e32 v89, v48, v49
	v_pk_mul_f32 v[48:49], v[52:53], v[54:55]
	v_add_f32_e32 v90, v90, v91
	v_add_f32_e32 v55, v48, v49
	v_mul_f32_e32 v48, v63, v61
	v_mul_f32_e32 v49, v75, v62
	v_cvt_pk_bf16_f32 v48, v48, v49
	v_mul_f32_e32 v49, v84, v69
	v_mul_f32_e32 v50, v86, v73
	v_cvt_pk_bf16_f32 v49, v49, v50
	v_mul_f32_e32 v50, v85, v90
	v_mul_f32_e32 v51, v88, v74
	v_cvt_pk_bf16_f32 v50, v50, v51
	v_mul_f32_e32 v51, v87, v89
	v_mul_f32_e32 v52, v71, v55
	v_cvt_pk_bf16_f32 v51, v51, v52
	v_mul_f32_e32 v52, v64, v61
	v_mul_f32_e32 v53, v60, v62
	v_cvt_pk_bf16_f32 v52, v52, v53
	v_mul_f32_e32 v53, v66, v69
	v_mul_f32_e32 v54, v68, v73
	v_cvt_pk_bf16_f32 v53, v53, v54
	v_mul_f32_e32 v54, v70, v90
	v_mul_f32_e32 v61, v72, v74
	v_mul_f32_e32 v55, v67, v55
	v_cvt_pk_bf16_f32 v54, v54, v61
	v_mul_f32_e32 v61, v65, v89
	v_cvt_pk_bf16_f32 v55, v61, v55
	global_store_dwordx4 v[56:57], v[48:51], off offset:256
	global_store_dwordx4 v[58:59], v[52:55], off offset:256
	global_load_dword v49, v[112:113], off
	s_nop 0
	global_load_dword v50, v[114:115], off
	ds_bpermute_b32 v51, v177, v44
	v_mov_b32_e32 v48, v44
	ds_bpermute_b32 v44, v177, v45
	ds_bpermute_b32 v54, v177, v46
	ds_bpermute_b32 v55, v177, v47
	s_waitcnt lgkmcnt(3)
	v_cndmask_b32_e64 v51, v51, -v51, vcc
	s_waitcnt vmcnt(0)
	v_pk_mul_f32 v[52:53], v[48:49], v[50:51]
	s_waitcnt lgkmcnt(2)
	v_cndmask_b32_e64 v51, v44, -v44, vcc
	v_mov_b32_e32 v48, v45
	v_pk_mul_f32 v[44:45], v[48:49], v[50:51]
	s_waitcnt lgkmcnt(1)
	v_cndmask_b32_e64 v51, v54, -v54, vcc
	v_mov_b32_e32 v48, v46
	v_add_f32_e32 v52, v52, v53
	v_add_f32_e32 v53, v44, v45
	v_pk_mul_f32 v[44:45], v[48:49], v[50:51]
	s_waitcnt lgkmcnt(0)
	v_cndmask_b32_e64 v51, v55, -v55, vcc
	v_mov_b32_e32 v48, v47
	v_add_f32_e32 v54, v44, v45
	v_pk_mul_f32 v[44:45], v[48:49], v[50:51]
	s_nop 0
	v_add_f32_e32 v50, v44, v45
	global_load_dword v45, v[112:113], off
	global_load_dword v46, v[114:115], off
	ds_bpermute_b32 v47, v177, v40
	v_mov_b32_e32 v44, v40
	ds_bpermute_b32 v40, v177, v41
	ds_bpermute_b32 v51, v177, v42
	ds_bpermute_b32 v55, v177, v43
	s_waitcnt lgkmcnt(3)
	v_cndmask_b32_e64 v47, v47, -v47, vcc
	s_waitcnt vmcnt(0)
	v_pk_mul_f32 v[48:49], v[44:45], v[46:47]
	s_waitcnt lgkmcnt(2)
	v_cndmask_b32_e64 v47, v40, -v40, vcc
	v_mov_b32_e32 v44, v41
	v_pk_mul_f32 v[40:41], v[44:45], v[46:47]
	s_waitcnt lgkmcnt(1)
	v_cndmask_b32_e64 v47, v51, -v51, vcc
	v_mov_b32_e32 v44, v42
	v_add_f32_e32 v48, v48, v49
	v_add_f32_e32 v49, v40, v41
	v_pk_mul_f32 v[40:41], v[44:45], v[46:47]
	s_waitcnt lgkmcnt(0)
	v_cndmask_b32_e64 v47, v55, -v55, vcc
	v_mov_b32_e32 v44, v43
	v_add_f32_e32 v51, v40, v41
	v_pk_mul_f32 v[40:41], v[44:45], v[46:47]
	s_nop 0
	v_add_f32_e32 v40, v40, v41
	v_mul_f32_e32 v41, v63, v52
	v_mul_f32_e32 v42, v75, v53
	v_cvt_pk_bf16_f32 v42, v41, v42
	v_mul_f32_e32 v41, v84, v54
	v_mul_f32_e32 v43, v86, v50
	v_cvt_pk_bf16_f32 v43, v41, v43
	v_mul_f32_e32 v41, v85, v48
	v_mul_f32_e32 v44, v88, v49
	v_cvt_pk_bf16_f32 v44, v41, v44
	v_mul_f32_e32 v41, v87, v51
	v_mul_f32_e32 v45, v71, v40
	v_cvt_pk_bf16_f32 v45, v41, v45
	v_mul_f32_e32 v41, v64, v52
	v_mul_f32_e32 v46, v60, v53
	v_cvt_pk_bf16_f32 v46, v41, v46
	v_mul_f32_e32 v41, v66, v54
	v_mul_f32_e32 v47, v68, v50
	v_cvt_pk_bf16_f32 v47, v41, v47
	v_mul_f32_e32 v41, v70, v48
	v_mul_f32_e32 v48, v72, v49
	v_cvt_pk_bf16_f32 v48, v41, v48
	v_mul_f32_e32 v41, v65, v51
	v_mul_f32_e32 v40, v67, v40
	s_mov_b64 s[0:1], 0x1200000
	v_cvt_pk_bf16_f32 v49, v41, v40
	v_lshl_add_u64 v[40:41], v[120:121], 0, s[0:1]
	s_mov_b32 s0, 0x1200000
	v_add_co_u32_e64 v50, s[4:5], s0, v120
	s_mov_b64 s[0:1], 0x3200000
	s_nop 0
	v_addc_co_u32_e64 v51, s[4:5], 0, v121, s[4:5]
	global_store_dwordx4 v[50:51], v[42:45], off
	s_nop 1
	v_lshl_add_u64 v[42:43], v[120:121], 0, s[0:1]
	s_mov_b32 s0, 0x3200000
	v_add_co_u32_e64 v44, s[4:5], s0, v120
	s_nop 1
	v_addc_co_u32_e64 v45, s[4:5], 0, v121, s[4:5]
	global_store_dwordx4 v[44:45], v[46:49], off
	global_load_dword v45, v[104:105], off
	s_nop 0
	global_load_dword v46, v[106:107], off
	ds_bpermute_b32 v47, v177, v36
	v_mov_b32_e32 v44, v36
	ds_bpermute_b32 v36, v177, v37
	ds_bpermute_b32 v50, v177, v38
	ds_bpermute_b32 v51, v177, v39
	s_waitcnt lgkmcnt(3)
	v_cndmask_b32_e64 v47, v47, -v47, vcc
	s_waitcnt vmcnt(0)
	v_pk_mul_f32 v[48:49], v[44:45], v[46:47]
	s_waitcnt lgkmcnt(2)
;     __device__ __forceinline__ void operator()(const AccT& acc, const Unit& u, int wr, int wc, int fr, int fq) const {
;     ...
;             for (int m = 0; m < 4; ++m) {
;                 const int r = rbase + ai * 128 + m * 16;
;                 const int d = 4 * (2 * m + (fr >> 3)) + j;
; #pragma unroll
;                 for (int bj = 0; bj < 2; ++bj) {
;                     const int t0 = tb + bj * 128;
;                     float v[8];
; #pragma unroll
;                     for (int jj = 0; jj < 4; ++jj) { v[jj] = acc[ai][bj][m][0][jj]; v[4 + jj] = acc[ai][bj][m][1][jj]; }
;                     if constexpr (ROPE) {
;                         const int t = t0 & 2047;
; #pragma unroll
;                         for (int hf = 0; hf < 2; ++hf) {
;                             f32x4 cs, sn;
;                             if (m < 2) { const float c1 = ropeA[(t >> 6) * 16 + d], s1 = ropeA[1024 + (t >> 6) * 16 + d]; cs = (f32x4){c1, c1, c1, c1}; sn = (f32x4){s1, s1, s1, s1}; }
;                             else { const float* cb = ropeA + 2048 + (d - 16) * 64 + (t & 63) + 4 * hf; cs = *(const f32x4*)(cb); sn = *(const f32x4*)(cb + 1024); }
; #pragma unroll
;                             for (int jj = 0; jj < 4; ++jj) { const float pr = __shfl_xor(v[4 * hf + jj], 4); v[4 * hf + jj] = v[4 * hf + jj] * cs[jj] + sgn * pr * sn[jj]; }
;                             __builtin_amdgcn_sched_barrier(0);
;                         }
;                     }
;                     float zf[8], zb[8]; zf[0] = zf0; zb[0] = zb0;
; #pragma unroll
;                     for (int jj = 1; jj < 8; ++jj) { zf[jj] = zf[jj - 1] * zfs; zb[jj] = zb[jj - 1] * zbs; }
;                     u32x4 wf, wb;
;                     wf.x = cvt_pk_bf16(v[0] * zf[0], v[1] * zf[1]); wf.y = cvt_pk_bf16(v[2] * zf[2], v[3] * zf[3]); wf.z = cvt_pk_bf16(v[4] * zf[4], v[5] * zf[5]); wf.w = cvt_pk_bf16(v[6] * zf[6], v[7] * zf[7]);
;                     wb.x = cvt_pk_bf16(v[0] * zb[0], v[1] * zb[1]); wb.y = cvt_pk_bf16(v[2] * zb[2], v[3] * zb[3]); wb.z = cvt_pk_bf16(v[4] * zb[4], v[5] * zb[5]); wb.w = cvt_pk_bf16(v[6] * zb[6], v[7] * zb[7]);
;                     *(u32x4*)(KTZ + (size_t)r * NT + t0) = wf;
;                     *(u32x4*)(KTZ + (size_t)(256 + r) * NT + t0) = wb;
	v_cndmask_b32_e64 v47, v36, -v36, vcc
	v_mov_b32_e32 v44, v37
	v_pk_mul_f32 v[36:37], v[44:45], v[46:47]
	s_waitcnt lgkmcnt(1)
	v_cndmask_b32_e64 v47, v50, -v50, vcc
	v_mov_b32_e32 v44, v38
	v_add_f32_e32 v48, v48, v49
	v_add_f32_e32 v49, v36, v37
	v_pk_mul_f32 v[36:37], v[44:45], v[46:47]
	s_waitcnt lgkmcnt(0)
	v_cndmask_b32_e64 v47, v51, -v51, vcc
	v_mov_b32_e32 v44, v39
	v_add_f32_e32 v50, v36, v37
	v_pk_mul_f32 v[36:37], v[44:45], v[46:47]
	s_nop 0
	v_add_f32_e32 v46, v36, v37
	global_load_dword v37, v[104:105], off
	global_load_dword v38, v[106:107], off
	ds_bpermute_b32 v39, v177, v32
	v_mov_b32_e32 v36, v32
	ds_bpermute_b32 v32, v177, v33
	ds_bpermute_b32 v47, v177, v34
	ds_bpermute_b32 v51, v177, v35
	s_waitcnt lgkmcnt(3)
	v_cndmask_b32_e64 v39, v39, -v39, vcc
	s_waitcnt vmcnt(0)
	v_pk_mul_f32 v[44:45], v[36:37], v[38:39]
	s_waitcnt lgkmcnt(2)
	v_cndmask_b32_e64 v39, v32, -v32, vcc
	v_mov_b32_e32 v36, v33
	v_pk_mul_f32 v[32:33], v[36:37], v[38:39]
	s_waitcnt lgkmcnt(1)
	v_cndmask_b32_e64 v39, v47, -v47, vcc
	v_mov_b32_e32 v36, v34
	v_add_f32_e32 v44, v44, v45
	v_add_f32_e32 v45, v32, v33
	v_pk_mul_f32 v[32:33], v[36:37], v[38:39]
	s_waitcnt lgkmcnt(0)
	v_cndmask_b32_e64 v39, v51, -v51, vcc
	v_mov_b32_e32 v36, v35
	v_add_f32_e32 v47, v32, v33
	v_pk_mul_f32 v[32:33], v[36:37], v[38:39]
	s_nop 0
	v_add_f32_e32 v39, v32, v33
	v_mul_f32_e32 v32, v63, v48
	v_mul_f32_e32 v33, v75, v49
	v_cvt_pk_bf16_f32 v32, v32, v33
	v_mul_f32_e32 v33, v84, v50
	v_mul_f32_e32 v34, v86, v46
	v_cvt_pk_bf16_f32 v33, v33, v34
	v_mul_f32_e32 v34, v85, v44
	v_mul_f32_e32 v35, v88, v45
	v_cvt_pk_bf16_f32 v34, v34, v35
	v_mul_f32_e32 v35, v87, v47
	v_mul_f32_e32 v36, v71, v39
	v_cvt_pk_bf16_f32 v35, v35, v36
	v_mul_f32_e32 v36, v64, v48
	v_mul_f32_e32 v37, v60, v49
	v_cvt_pk_bf16_f32 v36, v36, v37
	v_mul_f32_e32 v37, v66, v50
	v_mul_f32_e32 v38, v68, v46
	v_cvt_pk_bf16_f32 v37, v37, v38
	v_mul_f32_e32 v38, v70, v44
	v_mul_f32_e32 v44, v72, v45
	v_mul_f32_e32 v39, v67, v39
	v_cvt_pk_bf16_f32 v38, v38, v44
	v_mul_f32_e32 v44, v65, v47
	v_cvt_pk_bf16_f32 v39, v44, v39
	global_store_dwordx4 v[40:41], v[32:35], off offset:256
	global_store_dwordx4 v[42:43], v[36:39], off offset:256
	global_load_dwordx4 v[32:35], v[98:99], off
	s_nop 0
	global_load_dwordx4 v[36:39], v[96:97], off
	ds_bpermute_b32 v41, v177, v28
	ds_bpermute_b32 v42, v177, v29
	ds_bpermute_b32 v44, v177, v30
	ds_bpermute_b32 v46, v177, v31
	v_mov_b32_e32 v40, v28
	v_mov_b32_e32 v28, v30
	s_waitcnt lgkmcnt(3)
	v_cndmask_b32_e64 v43, v41, -v41, vcc
	s_waitcnt lgkmcnt(2)
	v_cndmask_b32_e64 v45, v42, -v42, vcc
	s_waitcnt lgkmcnt(1)
	v_cndmask_b32_e64 v47, v44, -v44, vcc
	s_waitcnt lgkmcnt(0)
	v_cndmask_b32_e64 v49, v46, -v46, vcc
	s_waitcnt vmcnt(1)
	v_mov_b32_e32 v41, v32
	s_waitcnt vmcnt(0)
	v_mov_b32_e32 v42, v36
	v_mov_b32_e32 v32, v29
	v_mov_b32_e32 v44, v37
	v_mov_b32_e32 v29, v34
	v_mov_b32_e32 v46, v38
	v_mov_b32_e32 v34, v31
	v_mov_b32_e32 v48, v39
	v_pk_mul_f32 v[30:31], v[40:41], v[42:43]
	v_pk_mul_f32 v[32:33], v[32:33], v[44:45]
	v_pk_mul_f32 v[28:29], v[28:29], v[46:47]
	v_pk_mul_f32 v[34:35], v[34:35], v[48:49]
	v_add_f32_e32 v46, v30, v31
	v_add_f32_e32 v47, v32, v33
	v_add_f32_e32 v48, v28, v29
	v_add_f32_e32 v49, v34, v35
	global_load_dwordx4 v[28:31], v[92:93], off offset:16
	global_load_dwordx4 v[32:35], v[94:95], off offset:16
	ds_bpermute_b32 v37, v177, v24
	ds_bpermute_b32 v38, v177, v25
	ds_bpermute_b32 v40, v177, v26
	ds_bpermute_b32 v42, v177, v27
	v_mov_b32_e32 v36, v24
	v_mov_b32_e32 v24, v26
	s_waitcnt lgkmcnt(3)
	v_cndmask_b32_e64 v39, v37, -v37, vcc
	s_waitcnt lgkmcnt(2)
	v_cndmask_b32_e64 v41, v38, -v38, vcc
	s_waitcnt lgkmcnt(1)
	v_cndmask_b32_e64 v43, v40, -v40, vcc
	s_waitcnt lgkmcnt(0)
	v_cndmask_b32_e64 v45, v42, -v42, vcc
	s_waitcnt vmcnt(1)
	v_mov_b32_e32 v37, v28
	s_waitcnt vmcnt(0)
	v_mov_b32_e32 v38, v32
	v_mov_b32_e32 v28, v25
	v_mov_b32_e32 v40, v33
	v_mov_b32_e32 v25, v30
	v_mov_b32_e32 v42, v34
	v_mov_b32_e32 v30, v27
	v_mov_b32_e32 v44, v35
	v_pk_mul_f32 v[26:27], v[36:37], v[38:39]
	v_pk_mul_f32 v[28:29], v[28:29], v[40:41]
	v_pk_mul_f32 v[24:25], v[24:25], v[42:43]
	v_pk_mul_f32 v[30:31], v[30:31], v[44:45]
	v_add_f32_e32 v32, v26, v27
	v_add_f32_e32 v33, v28, v29
	v_add_f32_e32 v24, v24, v25
	v_add_f32_e32 v25, v30, v31
	v_mul_f32_e32 v26, v63, v46
	v_mul_f32_e32 v27, v75, v47
	v_cvt_pk_bf16_f32 v26, v26, v27
	v_mul_f32_e32 v27, v84, v48
	v_mul_f32_e32 v28, v86, v49
	v_cvt_pk_bf16_f32 v27, v27, v28
	v_mul_f32_e32 v28, v85, v32
	v_mul_f32_e32 v29, v88, v33
	v_cvt_pk_bf16_f32 v28, v28, v29
	v_mul_f32_e32 v29, v87, v24
	v_mul_f32_e32 v30, v71, v25
	v_cvt_pk_bf16_f32 v29, v29, v30
	v_mul_f32_e32 v30, v64, v46
	v_mul_f32_e32 v31, v60, v47
	v_cvt_pk_bf16_f32 v30, v30, v31
	v_mul_f32_e32 v31, v66, v48
	v_mul_f32_e32 v32, v70, v32
	v_mul_f32_e32 v33, v72, v33
	v_mul_f32_e32 v24, v65, v24
	v_mul_f32_e32 v25, v67, v25
	s_mov_b64 s[0:1], 0x1400000
	v_mul_f32_e32 v34, v68, v49
	v_cvt_pk_bf16_f32 v31, v31, v34
	v_cvt_pk_bf16_f32 v32, v32, v33
	v_cvt_pk_bf16_f32 v33, v24, v25
	v_lshl_add_u64 v[24:25], v[120:121], 0, s[0:1]
	s_mov_b32 s0, 0x1400000
	v_add_co_u32_e64 v34, s[4:5], s0, v120
	s_mov_b64 s[0:1], 0x3400000
	s_nop 0
	v_addc_co_u32_e64 v35, s[4:5], 0, v121, s[4:5]
	global_store_dwordx4 v[34:35], v[26:29], off
	s_nop 1
	v_lshl_add_u64 v[26:27], v[120:121], 0, s[0:1]
	s_mov_b32 s0, 0x3400000
	v_add_co_u32_e64 v28, s[4:5], s0, v120
	s_nop 1
	v_addc_co_u32_e64 v29, s[4:5], 0, v121, s[4:5]
	global_store_dwordx4 v[28:29], v[30:33], off
	global_load_dwordx4 v[28:31], v[98:99], off
	s_nop 0
	global_load_dwordx4 v[32:35], v[96:97], off
	ds_bpermute_b32 v37, v177, v20
	ds_bpermute_b32 v38, v177, v21
	ds_bpermute_b32 v40, v177, v22
	ds_bpermute_b32 v42, v177, v23
	v_mov_b32_e32 v36, v20
	v_mov_b32_e32 v20, v22
	s_waitcnt lgkmcnt(3)
;     __device__ __forceinline__ void operator()(const AccT& acc, const Unit& u, int wr, int wc, int fr, int fq) const {
;     ...
;             for (int m = 0; m < 4; ++m) {
;                 const int r = rbase + ai * 128 + m * 16;
;                 const int d = 4 * (2 * m + (fr >> 3)) + j;
; #pragma unroll
;                 for (int bj = 0; bj < 2; ++bj) {
;                     const int t0 = tb + bj * 128;
;                     float v[8];
; #pragma unroll
;                     for (int jj = 0; jj < 4; ++jj) { v[jj] = acc[ai][bj][m][0][jj]; v[4 + jj] = acc[ai][bj][m][1][jj]; }
;                     if constexpr (ROPE) {
;                         const int t = t0 & 2047;
; #pragma unroll
;                         for (int hf = 0; hf < 2; ++hf) {
;                             f32x4 cs, sn;
;                             if (m < 2) { const float c1 = ropeA[(t >> 6) * 16 + d], s1 = ropeA[1024 + (t >> 6) * 16 + d]; cs = (f32x4){c1, c1, c1, c1}; sn = (f32x4){s1, s1, s1, s1}; }
;                             else { const float* cb = ropeA + 2048 + (d - 16) * 64 + (t & 63) + 4 * hf; cs = *(const f32x4*)(cb); sn = *(const f32x4*)(cb + 1024); }
; #pragma unroll
;                             for (int jj = 0; jj < 4; ++jj) { const float pr = __shfl_xor(v[4 * hf + jj], 4); v[4 * hf + jj] = v[4 * hf + jj] * cs[jj] + sgn * pr * sn[jj]; }
;                             __builtin_amdgcn_sched_barrier(0);
;                         }
;                     }
;                     float zf[8], zb[8]; zf[0] = zf0; zb[0] = zb0;
; #pragma unroll
;                     for (int jj = 1; jj < 8; ++jj) { zf[jj] = zf[jj - 1] * zfs; zb[jj] = zb[jj - 1] * zbs; }
;                     u32x4 wf, wb;
;                     wf.x = cvt_pk_bf16(v[0] * zf[0], v[1] * zf[1]); wf.y = cvt_pk_bf16(v[2] * zf[2], v[3] * zf[3]); wf.z = cvt_pk_bf16(v[4] * zf[4], v[5] * zf[5]); wf.w = cvt_pk_bf16(v[6] * zf[6], v[7] * zf[7]);
;                     wb.x = cvt_pk_bf16(v[0] * zb[0], v[1] * zb[1]); wb.y = cvt_pk_bf16(v[2] * zb[2], v[3] * zb[3]); wb.z = cvt_pk_bf16(v[4] * zb[4], v[5] * zb[5]); wb.w = cvt_pk_bf16(v[6] * zb[6], v[7] * zb[7]);
;                     *(u32x4*)(KTZ + (size_t)r * NT + t0) = wf;
;                     *(u32x4*)(KTZ + (size_t)(256 + r) * NT + t0) = wb;
	v_cndmask_b32_e64 v39, v37, -v37, vcc
	s_waitcnt lgkmcnt(2)
	v_cndmask_b32_e64 v41, v38, -v38, vcc
	s_waitcnt lgkmcnt(1)
	v_cndmask_b32_e64 v43, v40, -v40, vcc
	s_waitcnt lgkmcnt(0)
	v_cndmask_b32_e64 v45, v42, -v42, vcc
	s_waitcnt vmcnt(1)
	v_mov_b32_e32 v37, v28
	s_waitcnt vmcnt(0)
	v_mov_b32_e32 v38, v32
	v_mov_b32_e32 v28, v21
	v_mov_b32_e32 v40, v33
	v_mov_b32_e32 v21, v30
	v_mov_b32_e32 v42, v34
	v_mov_b32_e32 v30, v23
	v_mov_b32_e32 v44, v35
	v_pk_mul_f32 v[22:23], v[36:37], v[38:39]
	v_pk_mul_f32 v[28:29], v[28:29], v[40:41]
	v_pk_mul_f32 v[20:21], v[20:21], v[42:43]
	v_pk_mul_f32 v[30:31], v[30:31], v[44:45]
	v_add_f32_e32 v42, v22, v23
	v_add_f32_e32 v43, v28, v29
	v_add_f32_e32 v44, v20, v21
	v_add_f32_e32 v45, v30, v31
	global_load_dwordx4 v[20:23], v[92:93], off offset:16
	global_load_dwordx4 v[28:31], v[94:95], off offset:16
	ds_bpermute_b32 v33, v177, v16
	ds_bpermute_b32 v34, v177, v17
	ds_bpermute_b32 v36, v177, v18
	ds_bpermute_b32 v38, v177, v19
	v_mov_b32_e32 v32, v16
	v_mov_b32_e32 v16, v18
	s_waitcnt lgkmcnt(3)
	v_cndmask_b32_e64 v35, v33, -v33, vcc
	s_waitcnt lgkmcnt(2)
	v_cndmask_b32_e64 v37, v34, -v34, vcc
	s_waitcnt lgkmcnt(1)
	v_cndmask_b32_e64 v39, v36, -v36, vcc
	s_waitcnt lgkmcnt(0)
	v_cndmask_b32_e64 v41, v38, -v38, vcc
	s_waitcnt vmcnt(1)
	v_mov_b32_e32 v33, v20
	s_waitcnt vmcnt(0)
	v_mov_b32_e32 v34, v28
	v_mov_b32_e32 v20, v17
	v_mov_b32_e32 v36, v29
	v_mov_b32_e32 v17, v22
	v_mov_b32_e32 v38, v30
	v_mov_b32_e32 v22, v19
	v_mov_b32_e32 v40, v31
	v_pk_mul_f32 v[18:19], v[32:33], v[34:35]
	v_pk_mul_f32 v[20:21], v[20:21], v[36:37]
	v_pk_mul_f32 v[16:17], v[16:17], v[38:39]
	v_pk_mul_f32 v[22:23], v[22:23], v[40:41]
	v_add_f32_e32 v28, v18, v19
	v_add_f32_e32 v29, v20, v21
	v_add_f32_e32 v30, v16, v17
	v_add_f32_e32 v23, v22, v23
	v_mul_f32_e32 v16, v63, v42
	v_mul_f32_e32 v17, v75, v43
	v_cvt_pk_bf16_f32 v16, v16, v17
	v_mul_f32_e32 v17, v84, v44
	v_mul_f32_e32 v18, v86, v45
	v_cvt_pk_bf16_f32 v17, v17, v18
	v_mul_f32_e32 v18, v85, v28
	v_mul_f32_e32 v19, v88, v29
	v_cvt_pk_bf16_f32 v18, v18, v19
	v_mul_f32_e32 v19, v87, v30
	v_mul_f32_e32 v20, v71, v23
	v_cvt_pk_bf16_f32 v19, v19, v20
	v_mul_f32_e32 v20, v64, v42
	v_mul_f32_e32 v21, v60, v43
	v_cvt_pk_bf16_f32 v20, v20, v21
	v_mul_f32_e32 v21, v66, v44
	v_mul_f32_e32 v22, v68, v45
	v_cvt_pk_bf16_f32 v21, v21, v22
	v_mul_f32_e32 v22, v70, v28
	v_mul_f32_e32 v28, v72, v29
	v_mul_f32_e32 v23, v67, v23
	v_cvt_pk_bf16_f32 v22, v22, v28
	v_mul_f32_e32 v28, v65, v30
	v_cvt_pk_bf16_f32 v23, v28, v23
	global_store_dwordx4 v[24:25], v[16:19], off offset:256
	global_store_dwordx4 v[26:27], v[20:23], off offset:256
	global_load_dwordx4 v[16:19], v[82:83], off
	s_nop 0
	global_load_dwordx4 v[20:23], v[80:81], off
	ds_bpermute_b32 v25, v177, v12
	ds_bpermute_b32 v26, v177, v13
	ds_bpermute_b32 v28, v177, v14
	ds_bpermute_b32 v30, v177, v15
	v_mov_b32_e32 v24, v12
	v_mov_b32_e32 v12, v14
	s_waitcnt lgkmcnt(3)
	v_cndmask_b32_e64 v27, v25, -v25, vcc
	s_waitcnt lgkmcnt(2)
	v_cndmask_b32_e64 v29, v26, -v26, vcc
	s_waitcnt lgkmcnt(1)
	v_cndmask_b32_e64 v31, v28, -v28, vcc
	s_waitcnt lgkmcnt(0)
	v_cndmask_b32_e64 v33, v30, -v30, vcc
	s_waitcnt vmcnt(1)
	v_mov_b32_e32 v25, v16
	s_waitcnt vmcnt(0)
	v_mov_b32_e32 v26, v20
	v_mov_b32_e32 v16, v13
	v_mov_b32_e32 v28, v21
	v_mov_b32_e32 v13, v18
	v_mov_b32_e32 v30, v22
	v_mov_b32_e32 v18, v15
	v_mov_b32_e32 v32, v23
	v_pk_mul_f32 v[14:15], v[24:25], v[26:27]
	v_pk_mul_f32 v[16:17], v[16:17], v[28:29]
	v_pk_mul_f32 v[12:13], v[12:13], v[30:31]
	v_pk_mul_f32 v[18:19], v[18:19], v[32:33]
	v_add_f32_e32 v30, v14, v15
	v_add_f32_e32 v31, v16, v17
	v_add_f32_e32 v32, v12, v13
	v_add_f32_e32 v33, v18, v19
	global_load_dwordx4 v[12:15], v[76:77], off offset:16
	global_load_dwordx4 v[16:19], v[78:79], off offset:16
	ds_bpermute_b32 v21, v177, v8
	ds_bpermute_b32 v22, v177, v9
	ds_bpermute_b32 v24, v177, v10
	ds_bpermute_b32 v26, v177, v11
	v_mov_b32_e32 v20, v8
	v_mov_b32_e32 v8, v10
	s_waitcnt lgkmcnt(3)
	v_cndmask_b32_e64 v23, v21, -v21, vcc
	s_waitcnt lgkmcnt(2)
	v_cndmask_b32_e64 v25, v22, -v22, vcc
	s_waitcnt lgkmcnt(1)
	v_cndmask_b32_e64 v27, v24, -v24, vcc
	s_waitcnt lgkmcnt(0)
	v_cndmask_b32_e64 v29, v26, -v26, vcc
	s_waitcnt vmcnt(1)
	v_mov_b32_e32 v21, v12
	s_waitcnt vmcnt(0)
;     __device__ __forceinline__ void operator()(const AccT& acc, const Unit& u, int wr, int wc, int fr, int fq) const {
;     ...
;             for (int m = 0; m < 4; ++m) {
;                 const int r = rbase + ai * 128 + m * 16;
;                 const int d = 4 * (2 * m + (fr >> 3)) + j;
; #pragma unroll
;                 for (int bj = 0; bj < 2; ++bj) {
;                     const int t0 = tb + bj * 128;
;                     float v[8];
; #pragma unroll
;                     for (int jj = 0; jj < 4; ++jj) { v[jj] = acc[ai][bj][m][0][jj]; v[4 + jj] = acc[ai][bj][m][1][jj]; }
;                     if constexpr (ROPE) {
;                         const int t = t0 & 2047;
; #pragma unroll
;                         for (int hf = 0; hf < 2; ++hf) {
;                             f32x4 cs, sn;
;                             if (m < 2) { const float c1 = ropeA[(t >> 6) * 16 + d], s1 = ropeA[1024 + (t >> 6) * 16 + d]; cs = (f32x4){c1, c1, c1, c1}; sn = (f32x4){s1, s1, s1, s1}; }
;                             else { const float* cb = ropeA + 2048 + (d - 16) * 64 + (t & 63) + 4 * hf; cs = *(const f32x4*)(cb); sn = *(const f32x4*)(cb + 1024); }
; #pragma unroll
;                             for (int jj = 0; jj < 4; ++jj) { const float pr = __shfl_xor(v[4 * hf + jj], 4); v[4 * hf + jj] = v[4 * hf + jj] * cs[jj] + sgn * pr * sn[jj]; }
;                             __builtin_amdgcn_sched_barrier(0);
;                         }
;                     }
;                     float zf[8], zb[8]; zf[0] = zf0; zb[0] = zb0;
; #pragma unroll
;                     for (int jj = 1; jj < 8; ++jj) { zf[jj] = zf[jj - 1] * zfs; zb[jj] = zb[jj - 1] * zbs; }
;                     u32x4 wf, wb;
;                     wf.x = cvt_pk_bf16(v[0] * zf[0], v[1] * zf[1]); wf.y = cvt_pk_bf16(v[2] * zf[2], v[3] * zf[3]); wf.z = cvt_pk_bf16(v[4] * zf[4], v[5] * zf[5]); wf.w = cvt_pk_bf16(v[6] * zf[6], v[7] * zf[7]);
;                     wb.x = cvt_pk_bf16(v[0] * zb[0], v[1] * zb[1]); wb.y = cvt_pk_bf16(v[2] * zb[2], v[3] * zb[3]); wb.z = cvt_pk_bf16(v[4] * zb[4], v[5] * zb[5]); wb.w = cvt_pk_bf16(v[6] * zb[6], v[7] * zb[7]);
;                     *(u32x4*)(KTZ + (size_t)r * NT + t0) = wf;
;                     *(u32x4*)(KTZ + (size_t)(256 + r) * NT + t0) = wb;
	v_mov_b32_e32 v22, v16
	v_mov_b32_e32 v12, v9
	v_mov_b32_e32 v24, v17
	v_mov_b32_e32 v9, v14
	v_mov_b32_e32 v26, v18
	v_mov_b32_e32 v14, v11
	v_mov_b32_e32 v28, v19
	v_pk_mul_f32 v[10:11], v[20:21], v[22:23]
	v_pk_mul_f32 v[12:13], v[12:13], v[24:25]
	v_pk_mul_f32 v[8:9], v[8:9], v[26:27]
	v_pk_mul_f32 v[14:15], v[14:15], v[28:29]
	v_add_f32_e32 v16, v10, v11
	v_add_f32_e32 v17, v12, v13
	v_add_f32_e32 v8, v8, v9
	v_add_f32_e32 v9, v14, v15
	v_mul_f32_e32 v10, v63, v30
	v_mul_f32_e32 v11, v75, v31
	v_cvt_pk_bf16_f32 v10, v10, v11
	v_mul_f32_e32 v11, v84, v32
	v_mul_f32_e32 v12, v86, v33
	v_cvt_pk_bf16_f32 v11, v11, v12
	v_mul_f32_e32 v12, v85, v16
	v_mul_f32_e32 v13, v88, v17
	v_cvt_pk_bf16_f32 v12, v12, v13
	v_mul_f32_e32 v13, v87, v8
	v_mul_f32_e32 v14, v71, v9
	v_cvt_pk_bf16_f32 v13, v13, v14
	v_mul_f32_e32 v14, v64, v30
	v_mul_f32_e32 v15, v60, v31
	v_cvt_pk_bf16_f32 v14, v14, v15
	v_mul_f32_e32 v15, v66, v32
	v_mul_f32_e32 v18, v68, v33
	v_cvt_pk_bf16_f32 v15, v15, v18
	v_add_co_u32_e64 v18, s[4:5], s63, v120
	v_mul_f32_e32 v16, v70, v16
	v_mul_f32_e32 v17, v72, v17
	v_addc_co_u32_e64 v19, s[4:5], 0, v121, s[4:5]
	v_cvt_pk_bf16_f32 v16, v16, v17
	v_mul_f32_e32 v8, v65, v8
	v_mul_f32_e32 v9, v67, v9
	v_cvt_pk_bf16_f32 v17, v8, v9
	global_store_dwordx4 v[18:19], v[10:13], off
	v_lshl_add_u64 v[8:9], v[120:121], 0, s[26:27]
	s_nop 0
	v_add_co_u32_e64 v12, s[4:5], s64, v120
	v_lshl_add_u64 v[10:11], v[120:121], 0, s[28:29]
	s_nop 0
	v_addc_co_u32_e64 v13, s[4:5], 0, v121, s[4:5]
	global_store_dwordx4 v[12:13], v[14:17], off
	global_load_dwordx4 v[12:15], v[82:83], off
	s_nop 0
	global_load_dwordx4 v[16:19], v[80:81], off
	ds_bpermute_b32 v34, v177, v4
	ds_bpermute_b32 v32, v177, v5
	ds_bpermute_b32 v33, v177, v6
	ds_bpermute_b32 v28, v177, v7
	global_load_dwordx4 v[20:23], v[76:77], off offset:16
	global_load_dwordx4 v[24:27], v[78:79], off offset:16
	s_waitcnt lgkmcnt(0)
	v_cndmask_b32_e64 v29, v28, -v28, vcc
	v_mov_b32_e32 v30, v7
	s_waitcnt vmcnt(3)
	v_mov_b32_e32 v31, v15
	s_waitcnt vmcnt(2)
	v_mov_b32_e32 v28, v19
	v_cndmask_b32_e64 v19, v33, -v33, vcc
	v_mov_b32_e32 v7, v14
	v_cndmask_b32_e64 v15, v32, -v32, vcc
	v_mov_b32_e32 v32, v5
	v_mov_b32_e32 v33, v13
	v_mov_b32_e32 v14, v17
	v_cndmask_b32_e64 v17, v34, -v34, vcc
	v_mov_b32_e32 v5, v12
	ds_bpermute_b32 v13, v177, v0
	v_mov_b32_e32 v12, v0
	ds_bpermute_b32 v34, v177, v1
	ds_bpermute_b32 v35, v177, v2
	v_mov_b32_e32 v0, v2
	ds_bpermute_b32 v2, v177, v3
	v_pk_mul_f32 v[28:29], v[30:31], v[28:29]
	v_pk_mul_f32 v[6:7], v[6:7], v[18:19]
	v_pk_mul_f32 v[14:15], v[32:33], v[14:15]
	v_pk_mul_f32 v[4:5], v[4:5], v[16:17]
	v_add_f32_e32 v18, v28, v29
	v_add_f32_e32 v19, v6, v7
	v_add_f32_e32 v28, v14, v15
	v_add_f32_e32 v29, v4, v5
	s_waitcnt lgkmcnt(3)
	v_cndmask_b32_e64 v5, v13, -v13, vcc
	s_waitcnt lgkmcnt(2)
	v_cndmask_b32_e64 v7, v34, -v34, vcc
	s_waitcnt lgkmcnt(1)
	v_cndmask_b32_e64 v15, v35, -v35, vcc
	s_waitcnt lgkmcnt(0)
	v_cndmask_b32_e64 v17, v2, -v2, vcc
	s_waitcnt vmcnt(1)
	v_mov_b32_e32 v13, v20
	s_waitcnt vmcnt(0)
	v_mov_b32_e32 v4, v24
	v_mov_b32_e32 v20, v1
	v_mov_b32_e32 v6, v25
	v_mov_b32_e32 v1, v22
	v_mov_b32_e32 v14, v26
	v_mov_b32_e32 v22, v3
	v_mov_b32_e32 v16, v27
	v_pk_mul_f32 v[2:3], v[12:13], v[4:5]
	v_pk_mul_f32 v[4:5], v[20:21], v[6:7]
	v_pk_mul_f32 v[0:1], v[0:1], v[14:15]
	v_pk_mul_f32 v[6:7], v[22:23], v[16:17]
	v_add_f32_e32 v12, v2, v3
	v_add_f32_e32 v13, v4, v5
	v_add_f32_e32 v14, v0, v1
	v_add_f32_e32 v7, v6, v7
	v_mul_f32_e32 v0, v63, v29
	v_mul_f32_e32 v1, v75, v28
	v_cvt_pk_bf16_f32 v0, v0, v1
	v_mul_f32_e32 v1, v84, v19
	v_mul_f32_e32 v2, v86, v18
	v_cvt_pk_bf16_f32 v1, v1, v2
	v_mul_f32_e32 v2, v85, v12
	v_mul_f32_e32 v3, v88, v13
	v_cvt_pk_bf16_f32 v2, v2, v3
	v_mul_f32_e32 v3, v87, v14
	v_mul_f32_e32 v4, v71, v7
	v_cvt_pk_bf16_f32 v3, v3, v4
	v_mul_f32_e32 v4, v64, v29
	v_mul_f32_e32 v5, v60, v28
	v_cvt_pk_bf16_f32 v4, v4, v5
	v_mul_f32_e32 v5, v66, v19
	v_mul_f32_e32 v6, v68, v18
	v_cvt_pk_bf16_f32 v5, v5, v6
	v_mul_f32_e32 v6, v70, v12
	v_mul_f32_e32 v12, v72, v13
	v_mul_f32_e32 v7, v67, v7
	v_cvt_pk_bf16_f32 v6, v6, v12
	v_mul_f32_e32 v12, v65, v14
	v_cvt_pk_bf16_f32 v7, v12, v7
	global_store_dwordx4 v[8:9], v[0:3], off offset:256
	global_store_dwordx4 v[10:11], v[4:7], off offset:256
	s_and_b64 vcc, exec, s[2:3]
	s_mov_b32 s33, s30
	s_mov_b64 s[4:5], s[38:39]
	s_mov_b64 s[0:1], s[36:37]
	s_cbranch_vccz .LBB0_606
	s_waitcnt vmcnt(0)
	s_cmpk_gt_u32 s42, 0xff
	s_cbranch_scc1 .LBB0_617
	s_barrier

; #define PG8_STAGE(bufoff, gbase, voff) do { _Pragma("unroll") for (int _i = 0; _i < 2; ++_i) \
;         __builtin_amdgcn_global_load_lds((const unsigned*)((const char*)(gbase) + (voff)[_i]), (LAS unsigned*)(lds + (bufoff) + ldsw + _i * 8192), 16, 0, 0); } while (0)
; #define PG8_LDA(dst, b, h) do { _Pragma("unroll") for (int m = 0; m < 4; ++m) _Pragma("unroll") for (int k = 0; k < 2; ++k) dst[m][k] = *(const LAS bf16x8*)(lds + PG8_SA(b, h) + aoff + m * 2048 + k * 1024); } while (0)
; #define PG8_LDB(dst, b, h) do { _Pragma("unroll") for (int n = 0; n < 2; ++n) _Pragma("unroll") for (int k = 0; k < 2; ++k) dst[n][k] = *(const LAS bf16x8*)(lds + PG8_SB(b, h) + boff + n * 2048 + k * 1024); } while (0)
; #define PG8_WAIT_V(n) asm volatile("s_waitcnt vmcnt(" #n ")" ::: "memory")
; #define PG8_BAR __builtin_amdgcn_s_barrier()
; template <class Epi, class Sched>
; __device__ __forceinline__ void gemm_phase(LAS unsigned char* lds, const Gemm g, const Sched& S, const Epi& E) {
;     ...
;         const bool has_next = S.next(ui + 1, nxt);
;         const char* nA = has_next ? (const char*)g.A + (size_t)nxt.pm * tstep : cA; const char* nB = has_next ? (const char*)g.Bt + (size_t)nxt.pn * tstep : cB;
;         for (int t = 0; t < nt; t += 2) {
;             const bool last = (t == nt - 2);
;             const char* a1 = cA + (size_t)(t + 1) * kstep;
;             const char* a2 = last ? nA : cA + (size_t)(t + 2) * kstep; const char* b2 = last ? nB : cB + (size_t)(t + 2) * kstep;
;             const char* a3 = a2 + kstep; const char* b3 = b2 + kstep;
;             PG8_LDB(B0, 0, 0); PG8_SCHED; PG8_LDA(At, 0, 0); PG8_STAGE(PG8_SA(1, 1), a1 + hstep, voffA);
;             PG8_WAIT_L(8); PG8_BAR; PG8_WAIT_L(0); PG8_MMA(0, 0, At, B0); PG8_BAR; PG8_SCHED;
;             PG8_LDB(B1, 0, 1); PG8_STAGE(PG8_SB(0, 0), b2, voffB);
;             PG8_BAR; PG8_WAIT_L(0); PG8_MMA(0, 1, At, B1); PG8_BAR;
;             PG8_LDA(At, 0, 1); PG8_STAGE(PG8_SA(0, 0), a2, voffA);
;             PG8_BAR; PG8_WAIT_L(0); PG8_MMA(1, 0, At, B0); PG8_BAR; PG8_SCHED;
;             PG8_STAGE(PG8_SB(0, 1), b2 + hstep, voffB);
;             PG8_WAIT_V(6); PG8_BAR; PG8_MMA(1, 1, At, B1); PG8_BAR;
;             PG8_LDB(B0, 1, 0); PG8_SCHED; PG8_LDA(At, 1, 0); PG8_STAGE(PG8_SA(0, 1), a2 + hstep, voffA);
;             PG8_WAIT_L(8); PG8_BAR; PG8_WAIT_L(0); PG8_MMA(0, 0, At, B0); PG8_BAR; PG8_SCHED;
.LBB0_632:
	s_ashr_i32 s23, s22, 31
	v_cmp_lt_i64_e32 vcc, s[24:25], v[140:141]
	s_lshl_b64 s[24:25], s[22:23], 19
	s_add_u32 s24, s38, s24
	s_addc_u32 s25, s39, s25
	s_and_b64 s[26:27], vcc, exec
	s_cselect_b32 s23, s25, s31
	s_cselect_b32 s61, s24, s30
	s_ashr_i32 s21, s20, 31
	s_lshl_b64 s[26:27], s[20:21], 19
	s_add_u32 s26, s96, s26
	s_addc_u32 s27, s97, s27
	s_and_b64 s[36:37], vcc, exec
	s_cselect_b32 s21, s27, s35
	s_cselect_b32 s62, s26, s34
	s_add_u32 s30, s30, 0x40080
	s_addc_u32 s31, s31, 0
	s_add_u32 s63, s34, 0x100
	s_addc_u32 s64, s35, 0
	s_mov_b32 s65, -2
	s_waitcnt lgkmcnt(0)
	ds_read_b128 v[150:153], v147
	ds_read_b128 v[154:157], v147 offset:1024
	ds_read_b128 v[158:161], v147 offset:2048
	ds_read_b128 v[162:165], v147 offset:3072
	s_add_u32 s34, s30, 0xfffc0080
	s_addc_u32 s35, s31, -1
	s_cmp_eq_u32 s65, 12
	s_cselect_b32 s37, s23, s35
	s_cselect_b32 s36, s61, s34
	s_cselect_b32 s35, s21, s64
	s_cselect_b32 s34, s62, s63
	s_add_i32 m0, s29, 0xc000
	ds_read_b128 v[166:169], v148
	ds_read_b128 v[170:173], v148 offset:1024
	ds_read_b128 v[174:177], v148 offset:2048
	ds_read_b128 v[178:181], v148 offset:3072
	ds_read_b128 v[182:185], v148 offset:4096
	ds_read_b128 v[186:189], v148 offset:5120
	ds_read_b128 v[190:193], v148 offset:6144
	ds_read_b128 v[194:197], v148 offset:7168
	global_load_lds_dwordx4 v136, s[30:31]
	s_add_i32 m0, s29, 0xe000
	s_nop 0
	global_load_lds_dwordx4 v138, s[30:31]
	s_waitcnt lgkmcnt(8)
	s_waitcnt vmcnt(8)
	s_setprio 1
	s_barrier
	s_waitcnt lgkmcnt(0)
	s_waitcnt lgkmcnt(0)
	v_mfma_f32_16x16x32_bf16 v[124:127], v[150:153], v[166:169], 0
	v_mfma_f32_16x16x32_bf16 v[120:123], v[158:161], v[166:169], 0
	v_mfma_f32_16x16x32_bf16 v[116:119], v[150:153], v[174:177], 0
	v_mfma_f32_16x16x32_bf16 v[108:111], v[158:161], v[174:177], 0
	v_mfma_f32_16x16x32_bf16 v[100:103], v[150:153], v[182:185], 0
	v_mfma_f32_16x16x32_bf16 v[92:95], v[158:161], v[182:185], 0
	v_mfma_f32_16x16x32_bf16 v[84:87], v[150:153], v[190:193], 0
	v_mfma_f32_16x16x32_bf16 v[76:79], v[158:161], v[190:193], 0
	v_mfma_f32_16x16x32_bf16 v[124:127], v[154:157], v[170:173], v[124:127]
	v_mfma_f32_16x16x32_bf16 v[120:123], v[162:165], v[170:173], v[120:123]
	v_mfma_f32_16x16x32_bf16 v[116:119], v[154:157], v[178:181], v[116:119]
	v_mfma_f32_16x16x32_bf16 v[108:111], v[162:165], v[178:181], v[108:111]
	v_mfma_f32_16x16x32_bf16 v[100:103], v[154:157], v[186:189], v[100:103]
	v_mfma_f32_16x16x32_bf16 v[92:95], v[162:165], v[186:189], v[92:95]
	v_mfma_f32_16x16x32_bf16 v[84:87], v[154:157], v[194:197], v[84:87]
	v_mfma_f32_16x16x32_bf16 v[76:79], v[162:165], v[194:197], v[76:79]
	s_setprio 0
	s_barrier
	s_add_i32 s66, s54, s43
	s_mov_b32 m0, s66
	ds_read_b128 v[202:205], v149
	ds_read_b128 v[206:209], v149 offset:1024
	ds_read_b128 v[210:213], v149 offset:2048
	ds_read_b128 v[214:217], v149 offset:3072
	global_load_lds_dwordx4 v130, s[34:35]
	s_add_i32 m0, s66, 0x2000
	s_nop 0
	global_load_lds_dwordx4 v134, s[34:35]
	s_waitcnt vmcnt(8)
	s_setprio 1
	s_barrier
	s_waitcnt lgkmcnt(0)
	s_waitcnt lgkmcnt(0)
	v_mfma_f32_16x16x32_bf16 v[112:115], v[202:205], v[166:169], 0
	v_mfma_f32_16x16x32_bf16 v[104:107], v[210:213], v[166:169], 0
	v_mfma_f32_16x16x32_bf16 v[96:99], v[202:205], v[174:177], 0
	v_mfma_f32_16x16x32_bf16 v[88:91], v[210:213], v[174:177], 0
	v_mfma_f32_16x16x32_bf16 v[80:83], v[202:205], v[182:185], 0
	v_mfma_f32_16x16x32_bf16 v[72:75], v[210:213], v[182:185], 0
	v_mfma_f32_16x16x32_bf16 v[68:71], v[202:205], v[190:193], 0
	v_mfma_f32_16x16x32_bf16 v[64:67], v[210:213], v[190:193], 0
	v_mfma_f32_16x16x32_bf16 v[112:115], v[206:209], v[170:173], v[112:115]
	v_mfma_f32_16x16x32_bf16 v[104:107], v[214:217], v[170:173], v[104:107]
	v_mfma_f32_16x16x32_bf16 v[96:99], v[206:209], v[178:181], v[96:99]
	v_mfma_f32_16x16x32_bf16 v[88:91], v[214:217], v[178:181], v[88:91]
	v_mfma_f32_16x16x32_bf16 v[80:83], v[206:209], v[186:189], v[80:83]
	v_mfma_f32_16x16x32_bf16 v[72:75], v[214:217], v[186:189], v[72:75]
	v_mfma_f32_16x16x32_bf16 v[68:71], v[206:209], v[194:197], v[68:71]
	v_mfma_f32_16x16x32_bf16 v[64:67], v[214:217], v[194:197], v[64:67]
	s_setprio 0
	s_mov_b32 m0, s29
	v_lshl_add_u64 v[220:221], s[36:37], 0, v[128:129]
	s_barrier
	ds_read_b128 v[166:169], v148 offset:16384
	ds_read_b128 v[170:173], v148 offset:17408
	ds_read_b128 v[174:177], v148 offset:18432
	ds_read_b128 v[178:181], v148 offset:19456
	ds_read_b128 v[182:185], v148 offset:20480
	ds_read_b128 v[186:189], v148 offset:21504
	ds_read_b128 v[190:193], v148 offset:22528
	ds_read_b128 v[194:197], v148 offset:23552
	global_load_lds_dwordx4 v128, s[36:37]
	v_lshl_add_u64 v[222:223], s[36:37], 0, v[132:133]
	s_mov_b32 m0, s44
	s_nop 0
	global_load_lds_dwordx4 v132, s[36:37]
	s_setprio 1
	s_barrier
	s_waitcnt lgkmcnt(0)
	s_waitcnt lgkmcnt(0)
	v_mfma_f32_16x16x32_bf16 v[60:63], v[150:153], v[166:169], 0
	v_mfma_f32_16x16x32_bf16 v[56:59], v[158:161], v[166:169], 0
	v_mfma_f32_16x16x32_bf16 v[52:55], v[150:153], v[174:177], 0
	v_mfma_f32_16x16x32_bf16 v[44:47], v[158:161], v[174:177], 0
	v_mfma_f32_16x16x32_bf16 v[36:39], v[150:153], v[182:185], 0
	v_mfma_f32_16x16x32_bf16 v[28:31], v[158:161], v[182:185], 0
	v_mfma_f32_16x16x32_bf16 v[20:23], v[150:153], v[190:193], 0
	v_mfma_f32_16x16x32_bf16 v[12:15], v[158:161], v[190:193], 0
	v_mfma_f32_16x16x32_bf16 v[60:63], v[154:157], v[170:173], v[60:63]
	v_mfma_f32_16x16x32_bf16 v[56:59], v[162:165], v[170:173], v[56:59]
	v_mfma_f32_16x16x32_bf16 v[52:55], v[154:157], v[178:181], v[52:55]
	v_mfma_f32_16x16x32_bf16 v[44:47], v[162:165], v[178:181], v[44:47]
	v_mfma_f32_16x16x32_bf16 v[36:39], v[154:157], v[186:189], v[36:39]
	v_mfma_f32_16x16x32_bf16 v[28:31], v[162:165], v[186:189], v[28:31]
	v_mfma_f32_16x16x32_bf16 v[20:23], v[154:157], v[194:197], v[20:23]
	v_mfma_f32_16x16x32_bf16 v[12:15], v[162:165], v[194:197], v[12:15]
	s_setprio 0
	s_barrier
; #define PG8_STAGE(bufoff, gbase, voff) do { _Pragma("unroll") for (int _i = 0; _i < 2; ++_i) \
;         __builtin_amdgcn_global_load_lds((const unsigned*)((const char*)(gbase) + (voff)[_i]), (LAS unsigned*)(lds + (bufoff) + ldsw + _i * 8192), 16, 0, 0); } while (0)
; #define PG8_LDA(dst, b, h) do { _Pragma("unroll") for (int m = 0; m < 4; ++m) _Pragma("unroll") for (int k = 0; k < 2; ++k) dst[m][k] = *(const LAS bf16x8*)(lds + PG8_SA(b, h) + aoff + m * 2048 + k * 1024); } while (0)
; #define PG8_LDB(dst, b, h) do { _Pragma("unroll") for (int n = 0; n < 2; ++n) _Pragma("unroll") for (int k = 0; k < 2; ++k) dst[n][k] = *(const LAS bf16x8*)(lds + PG8_SB(b, h) + boff + n * 2048 + k * 1024); } while (0)
; #define PG8_MMA(ai, bj, At, Bt) do { __builtin_amdgcn_s_setprio(1); _Pragma("unroll") for (int m = 0; m < 4; ++m) _Pragma("unroll") for (int n = 0; n < 2; ++n) _Pragma("unroll") for (int k = 0; k < 2; ++k) \
;         acc[ai][bj][m][n] = __builtin_amdgcn_mfma_f32_16x16x32_bf16(Bt[n][k], At[m][k], acc[ai][bj][m][n], 0, 0, 0); __builtin_amdgcn_s_setprio(0); } while (0)
; #define PG8_WAIT_V(n) asm volatile("s_waitcnt vmcnt(" #n ")" ::: "memory")
; #define PG8_WAIT_L(n) asm volatile("s_waitcnt lgkmcnt(" #n ")" ::: "memory")
; #define PG8_BAR __builtin_amdgcn_s_barrier()
; #define PG8_SCHED __builtin_amdgcn_sched_barrier(0)
; template <class Epi, class Sched>
; __device__ __forceinline__ void gemm_phase(LAS unsigned char* lds, const Gemm g, const Sched& S, const Epi& E) {
;     ...
;             PG8_LDA(At, 0, 1); PG8_STAGE(PG8_SA(0, 0), a2, voffA);
;             PG8_BAR; PG8_WAIT_L(0); PG8_MMA(1, 0, At, B0); PG8_BAR; PG8_SCHED;
;             PG8_STAGE(PG8_SB(0, 1), b2 + hstep, voffB);
;             PG8_WAIT_V(6); PG8_BAR; PG8_MMA(1, 1, At, B1); PG8_BAR;
;             PG8_LDB(B0, 1, 0); PG8_SCHED; PG8_LDA(At, 1, 0); PG8_STAGE(PG8_SA(0, 1), a2 + hstep, voffA);
;             PG8_WAIT_L(8); PG8_BAR; PG8_WAIT_L(0); PG8_MMA(0, 0, At, B0); PG8_BAR; PG8_SCHED;
;             PG8_LDB(B1, 1, 1); PG8_STAGE(PG8_SB(1, 0), b3, voffB);
;             PG8_BAR; PG8_WAIT_L(0); PG8_MMA(0, 1, At, B1); PG8_BAR;
;             PG8_LDA(At, 1, 1); PG8_STAGE(PG8_SA(1, 0), a3, voffA);
;             PG8_BAR; PG8_WAIT_L(0); PG8_MMA(1, 0, At, B0); PG8_BAR; PG8_SCHED;
;             PG8_STAGE(PG8_SB(1, 1), b3 + hstep, voffB);
;             PG8_WAIT_V(6); PG8_BAR; PG8_MMA(1, 1, At, B1); PG8_BAR;
	s_add_u32 s66, s34, 0x40000
	s_addc_u32 s67, s35, 0
	s_add_i32 s68, s55, s43
	s_mov_b32 m0, s68
	s_nop 0
	global_load_lds_dwordx4 v130, s[66:67]
	s_add_i32 m0, s68, 0x2000
	s_nop 0
	global_load_lds_dwordx4 v134, s[66:67]
	s_add_u32 s36, s36, 0x40000
	s_addc_u32 s37, s37, 0
	s_mov_b32 m0, s45
	s_nop 0
	global_load_lds_dwordx4 v128, s[36:37]
	s_mov_b32 m0, s46
	s_nop 0
	global_load_lds_dwordx4 v132, s[36:37]
	s_waitcnt vmcnt(10)
	s_setprio 1
	s_barrier
	v_mfma_f32_16x16x32_bf16 v[48:51], v[202:205], v[166:169], 0
	v_mfma_f32_16x16x32_bf16 v[40:43], v[210:213], v[166:169], 0
	v_mfma_f32_16x16x32_bf16 v[32:35], v[202:205], v[174:177], 0
	v_mfma_f32_16x16x32_bf16 v[24:27], v[210:213], v[174:177], 0
	v_mfma_f32_16x16x32_bf16 v[16:19], v[202:205], v[182:185], 0
	v_mfma_f32_16x16x32_bf16 v[8:11], v[210:213], v[182:185], 0
	v_mfma_f32_16x16x32_bf16 v[4:7], v[202:205], v[190:193], 0
	v_mfma_f32_16x16x32_bf16 v[0:3], v[210:213], v[190:193], 0
	v_mfma_f32_16x16x32_bf16 v[48:51], v[206:209], v[170:173], v[48:51]
	v_mfma_f32_16x16x32_bf16 v[40:43], v[214:217], v[170:173], v[40:43]
	v_mfma_f32_16x16x32_bf16 v[32:35], v[206:209], v[178:181], v[32:35]
	v_mfma_f32_16x16x32_bf16 v[24:27], v[214:217], v[178:181], v[24:27]
	v_mfma_f32_16x16x32_bf16 v[16:19], v[206:209], v[186:189], v[16:19]
	v_mfma_f32_16x16x32_bf16 v[8:11], v[214:217], v[186:189], v[8:11]
	v_mfma_f32_16x16x32_bf16 v[4:7], v[206:209], v[194:197], v[4:7]
	v_mfma_f32_16x16x32_bf16 v[0:3], v[214:217], v[194:197], v[0:3]
	s_setprio 0
	s_add_i32 s66, 0, 0x18000
	v_add_u32_e32 v162, s66, v146
	s_barrier
	ds_read_b128 v[150:153], v162
	ds_read_b128 v[154:157], v162 offset:1024
	ds_read_b128 v[158:161], v162 offset:2048
	ds_read_b128 v[162:165], v162 offset:3072
	ds_read_b128 v[166:169], v148 offset:32768
	ds_read_b128 v[170:173], v148 offset:33792
	ds_read_b128 v[174:177], v148 offset:34816
	ds_read_b128 v[178:181], v148 offset:35840
	ds_read_b128 v[182:185], v148 offset:36864
	ds_read_b128 v[186:189], v148 offset:37888
	ds_read_b128 v[190:193], v148 offset:38912
	ds_read_b128 v[194:197], v148 offset:39936
	s_waitcnt lgkmcnt(8)
	s_waitcnt vmcnt(8)
	s_setprio 1
	s_barrier
	s_waitcnt lgkmcnt(0)
	s_waitcnt lgkmcnt(0)
	v_mfma_f32_16x16x32_bf16 v[124:127], v[150:153], v[166:169], v[124:127]
	v_mfma_f32_16x16x32_bf16 v[120:123], v[158:161], v[166:169], v[120:123]
	v_mfma_f32_16x16x32_bf16 v[116:119], v[150:153], v[174:177], v[116:119]
	v_mfma_f32_16x16x32_bf16 v[108:111], v[158:161], v[174:177], v[108:111]
	v_mfma_f32_16x16x32_bf16 v[100:103], v[150:153], v[182:185], v[100:103]
	v_mfma_f32_16x16x32_bf16 v[92:95], v[158:161], v[182:185], v[92:95]
	v_mfma_f32_16x16x32_bf16 v[84:87], v[150:153], v[190:193], v[84:87]
	v_mfma_f32_16x16x32_bf16 v[76:79], v[158:161], v[190:193], v[76:79]
	v_mfma_f32_16x16x32_bf16 v[124:127], v[154:157], v[170:173], v[124:127]
	v_mfma_f32_16x16x32_bf16 v[120:123], v[162:165], v[170:173], v[120:123]
	v_mfma_f32_16x16x32_bf16 v[116:119], v[154:157], v[178:181], v[116:119]
	v_mfma_f32_16x16x32_bf16 v[108:111], v[162:165], v[178:181], v[108:111]
	v_mfma_f32_16x16x32_bf16 v[100:103], v[154:157], v[186:189], v[100:103]
	v_mfma_f32_16x16x32_bf16 v[92:95], v[162:165], v[186:189], v[92:95]
	v_mfma_f32_16x16x32_bf16 v[84:87], v[154:157], v[194:197], v[84:87]
	v_mfma_f32_16x16x32_bf16 v[76:79], v[162:165], v[194:197], v[76:79]
	s_setprio 0
	s_barrier
	s_add_i32 s36, 0, 0x1c000
	s_add_i32 s37, s66, s43
	v_add_u32_e32 v214, s36, v146
	s_add_u32 s4, s34, 0x80
	s_addc_u32 s5, s35, 0
	s_mov_b32 m0, s37
	ds_read_b128 v[202:205], v214
	ds_read_b128 v[206:209], v214 offset:1024
	ds_read_b128 v[210:213], v214 offset:2048
	ds_read_b128 v[214:217], v214 offset:3072
	global_load_lds_dwordx4 v130, s[4:5]
	s_add_i32 m0, s37, 0x2000
	s_nop 0
	global_load_lds_dwordx4 v134, s[4:5]
	s_waitcnt vmcnt(8)
	s_setprio 1
	s_barrier
	s_waitcnt lgkmcnt(0)
	s_waitcnt lgkmcnt(0)
	v_mfma_f32_16x16x32_bf16 v[112:115], v[202:205], v[166:169], v[112:115]
	v_mfma_f32_16x16x32_bf16 v[104:107], v[210:213], v[166:169], v[104:107]
	v_mfma_f32_16x16x32_bf16 v[96:99], v[202:205], v[174:177], v[96:99]
	v_mfma_f32_16x16x32_bf16 v[88:91], v[210:213], v[174:177], v[88:91]
	v_mfma_f32_16x16x32_bf16 v[80:83], v[202:205], v[182:185], v[80:83]
	v_mfma_f32_16x16x32_bf16 v[72:75], v[210:213], v[182:185], v[72:75]
	v_mfma_f32_16x16x32_bf16 v[68:71], v[202:205], v[190:193], v[68:71]
	v_mfma_f32_16x16x32_bf16 v[64:67], v[210:213], v[190:193], v[64:67]
	v_mfma_f32_16x16x32_bf16 v[112:115], v[206:209], v[170:173], v[112:115]
	v_mfma_f32_16x16x32_bf16 v[104:107], v[214:217], v[170:173], v[104:107]
	v_mfma_f32_16x16x32_bf16 v[96:99], v[206:209], v[178:181], v[96:99]
	v_mfma_f32_16x16x32_bf16 v[88:91], v[214:217], v[178:181], v[88:91]
	v_mfma_f32_16x16x32_bf16 v[80:83], v[206:209], v[186:189], v[80:83]
	v_mfma_f32_16x16x32_bf16 v[72:75], v[214:217], v[186:189], v[72:75]
	v_mfma_f32_16x16x32_bf16 v[68:71], v[206:209], v[194:197], v[68:71]
	v_mfma_f32_16x16x32_bf16 v[64:67], v[214:217], v[194:197], v[64:67]
	s_setprio 0
	s_mov_b32 m0, s51
	s_mov_b64 s[4:5], 0x80
	v_lshl_add_u64 v[198:199], v[220:221], 0, s[4:5]
	s_barrier
	ds_read_b128 v[166:169], v148 offset:49152
	ds_read_b128 v[170:173], v148 offset:50176
	ds_read_b128 v[174:177], v148 offset:51200
	ds_read_b128 v[178:181], v148 offset:52224
	ds_read_b128 v[182:185], v148 offset:53248
	ds_read_b128 v[186:189], v148 offset:54272
	ds_read_b128 v[190:193], v148 offset:55296
	ds_read_b128 v[194:197], v148 offset:56320
	global_load_lds_dwordx4 v[198:199], off
	v_lshl_add_u64 v[198:199], v[222:223], 0, s[4:5]
	s_mov_b32 m0, s52
	s_nop 0
	global_load_lds_dwordx4 v[198:199], off
	s_setprio 1
	s_barrier
; #define PG8_STAGE(bufoff, gbase, voff) do { _Pragma("unroll") for (int _i = 0; _i < 2; ++_i) \
;         __builtin_amdgcn_global_load_lds((const unsigned*)((const char*)(gbase) + (voff)[_i]), (LAS unsigned*)(lds + (bufoff) + ldsw + _i * 8192), 16, 0, 0); } while (0)
; #define PG8_LDA(dst, b, h) do { _Pragma("unroll") for (int m = 0; m < 4; ++m) _Pragma("unroll") for (int k = 0; k < 2; ++k) dst[m][k] = *(const LAS bf16x8*)(lds + PG8_SA(b, h) + aoff + m * 2048 + k * 1024); } while (0)
; #define PG8_LDB(dst, b, h) do { _Pragma("unroll") for (int n = 0; n < 2; ++n) _Pragma("unroll") for (int k = 0; k < 2; ++k) dst[n][k] = *(const LAS bf16x8*)(lds + PG8_SB(b, h) + boff + n * 2048 + k * 1024); } while (0)
; #define PG8_WAIT_V(n) asm volatile("s_waitcnt vmcnt(" #n ")" ::: "memory")
; #define PG8_WAIT_L(n) asm volatile("s_waitcnt lgkmcnt(" #n ")" ::: "memory")
; #define PG8_BAR __builtin_amdgcn_s_barrier()
; #define PG8_SCHED __builtin_amdgcn_sched_barrier(0)
; template <class Epi, class Sched>
; __device__ __forceinline__ void gemm_phase(LAS unsigned char* lds, const Gemm g, const Sched& S, const Epi& E) {
;     ...
;             PG8_LDB(B0, 0, 0); PG8_SCHED; PG8_LDA(At, 0, 0); PG8_STAGE(PG8_SA(1, 1), a1 + hstep, voffA);
;             PG8_WAIT_L(8); PG8_BAR; PG8_WAIT_L(0); PG8_MMA(0, 0, At, B0); PG8_BAR; PG8_SCHED;
;             PG8_LDB(B1, 0, 1); PG8_STAGE(PG8_SB(0, 0), b2, voffB);
;             PG8_BAR; PG8_WAIT_L(0); PG8_MMA(0, 1, At, B1); PG8_BAR;
;             PG8_LDA(At, 0, 1); PG8_STAGE(PG8_SA(0, 0), a2, voffA);
;             PG8_BAR; PG8_WAIT_L(0); PG8_MMA(1, 0, At, B0); PG8_BAR; PG8_SCHED;
;             PG8_STAGE(PG8_SB(0, 1), b2 + hstep, voffB);
;             PG8_WAIT_V(6); PG8_BAR; PG8_MMA(1, 1, At, B1); PG8_BAR;
;             PG8_LDB(B0, 1, 0); PG8_SCHED; PG8_LDA(At, 1, 0); PG8_STAGE(PG8_SA(0, 1), a2 + hstep, voffA);
;             PG8_WAIT_L(8); PG8_BAR; PG8_WAIT_L(0); PG8_MMA(0, 0, At, B0); PG8_BAR; PG8_SCHED;
;             PG8_LDB(B1, 1, 1); PG8_STAGE(PG8_SB(1, 0), b3, voffB);
;             PG8_BAR; PG8_WAIT_L(0); PG8_MMA(0, 1, At, B1); PG8_BAR;
;             PG8_LDA(At, 1, 1); PG8_STAGE(PG8_SA(1, 0), a3, voffA);
;             PG8_BAR; PG8_WAIT_L(0); PG8_MMA(1, 0, At, B0); PG8_BAR; PG8_SCHED;
;             PG8_STAGE(PG8_SB(1, 1), b3 + hstep, voffB);
;             PG8_WAIT_V(6); PG8_BAR; PG8_MMA(1, 1, At, B1); PG8_BAR;
	s_waitcnt lgkmcnt(0)
	s_waitcnt lgkmcnt(0)
	v_mfma_f32_16x16x32_bf16 v[60:63], v[150:153], v[166:169], v[60:63]
	v_mfma_f32_16x16x32_bf16 v[56:59], v[158:161], v[166:169], v[56:59]
	v_mfma_f32_16x16x32_bf16 v[52:55], v[150:153], v[174:177], v[52:55]
	v_mfma_f32_16x16x32_bf16 v[44:47], v[158:161], v[174:177], v[44:47]
	v_mfma_f32_16x16x32_bf16 v[36:39], v[150:153], v[182:185], v[36:39]
	v_mfma_f32_16x16x32_bf16 v[28:31], v[158:161], v[182:185], v[28:31]
	v_mfma_f32_16x16x32_bf16 v[20:23], v[150:153], v[190:193], v[20:23]
	v_mfma_f32_16x16x32_bf16 v[12:15], v[158:161], v[190:193], v[12:15]
	v_mfma_f32_16x16x32_bf16 v[60:63], v[154:157], v[170:173], v[60:63]
	v_mfma_f32_16x16x32_bf16 v[56:59], v[162:165], v[170:173], v[56:59]
	v_mfma_f32_16x16x32_bf16 v[52:55], v[154:157], v[178:181], v[52:55]
	v_mfma_f32_16x16x32_bf16 v[44:47], v[162:165], v[178:181], v[44:47]
	v_mfma_f32_16x16x32_bf16 v[36:39], v[154:157], v[186:189], v[36:39]
	v_mfma_f32_16x16x32_bf16 v[28:31], v[162:165], v[186:189], v[28:31]
	v_mfma_f32_16x16x32_bf16 v[20:23], v[154:157], v[194:197], v[20:23]
	v_mfma_f32_16x16x32_bf16 v[12:15], v[162:165], v[194:197], v[12:15]
	s_setprio 0
	s_barrier
	s_add_u32 s34, s34, 0x40080
	s_addc_u32 s35, s35, 0
	s_add_i32 s36, s36, s43
	s_mov_b32 m0, s36
	s_nop 0
	global_load_lds_dwordx4 v130, s[34:35]
	s_add_i32 m0, s36, 0x2000
	s_nop 0
	global_load_lds_dwordx4 v134, s[34:35]
	s_waitcnt vmcnt(8)
	s_setprio 1
	s_barrier
	v_mfma_f32_16x16x32_bf16 v[48:51], v[202:205], v[166:169], v[48:51]
	v_mfma_f32_16x16x32_bf16 v[40:43], v[210:213], v[166:169], v[40:43]
	v_mfma_f32_16x16x32_bf16 v[32:35], v[202:205], v[174:177], v[32:35]
	v_mfma_f32_16x16x32_bf16 v[24:27], v[210:213], v[174:177], v[24:27]
	v_mfma_f32_16x16x32_bf16 v[16:19], v[202:205], v[182:185], v[16:19]
	v_mfma_f32_16x16x32_bf16 v[8:11], v[210:213], v[182:185], v[8:11]
	v_mfma_f32_16x16x32_bf16 v[4:7], v[202:205], v[190:193], v[4:7]
	v_mfma_f32_16x16x32_bf16 v[0:3], v[210:213], v[190:193], v[0:3]
	v_mfma_f32_16x16x32_bf16 v[48:51], v[206:209], v[170:173], v[48:51]
	v_mfma_f32_16x16x32_bf16 v[40:43], v[214:217], v[170:173], v[40:43]
	v_mfma_f32_16x16x32_bf16 v[32:35], v[206:209], v[178:181], v[32:35]
	v_mfma_f32_16x16x32_bf16 v[24:27], v[214:217], v[178:181], v[24:27]
	v_mfma_f32_16x16x32_bf16 v[16:19], v[206:209], v[186:189], v[16:19]
	v_mfma_f32_16x16x32_bf16 v[8:11], v[214:217], v[186:189], v[8:11]
	v_mfma_f32_16x16x32_bf16 v[4:7], v[206:209], v[194:197], v[4:7]
	v_mfma_f32_16x16x32_bf16 v[0:3], v[214:217], v[194:197], v[0:3]
	s_setprio 0
	s_add_i32 s65, s65, 2
	s_add_u32 s30, s30, 0x100
	s_addc_u32 s31, s31, 0
	s_add_u32 s63, s63, 0x100
	s_addc_u32 s64, s64, 0
	s_cmp_gt_u32 s65, 13
	s_barrier
.LBB0_633:
	ds_read_b128 v[150:153], v147
	ds_read_b128 v[154:157], v147 offset:1024
	ds_read_b128 v[158:161], v147 offset:2048
	ds_read_b128 v[162:165], v147 offset:3072
	s_add_u32 s34, s30, 0xfffc0080
	s_addc_u32 s35, s31, -1
	s_cmp_eq_u32 s65, 12
	s_cselect_b32 s37, s23, s35
	s_cselect_b32 s36, s61, s34
	s_cselect_b32 s35, s21, s64
	s_cselect_b32 s34, s62, s63
	s_add_i32 m0, s29, 0xc000
	ds_read_b128 v[166:169], v148
	ds_read_b128 v[170:173], v148 offset:1024
	ds_read_b128 v[174:177], v148 offset:2048
	ds_read_b128 v[178:181], v148 offset:3072
	ds_read_b128 v[182:185], v148 offset:4096
	ds_read_b128 v[186:189], v148 offset:5120
	ds_read_b128 v[190:193], v148 offset:6144
	ds_read_b128 v[194:197], v148 offset:7168
	global_load_lds_dwordx4 v136, s[30:31]
	s_add_i32 m0, s29, 0xe000
	s_nop 0
	global_load_lds_dwordx4 v138, s[30:31]
	s_waitcnt lgkmcnt(8)
	s_waitcnt vmcnt(8)
	s_setprio 1
	s_barrier
	s_waitcnt lgkmcnt(0)
	s_waitcnt lgkmcnt(0)
	v_mfma_f32_16x16x32_bf16 v[124:127], v[150:153], v[166:169], v[124:127]
	v_mfma_f32_16x16x32_bf16 v[120:123], v[158:161], v[166:169], v[120:123]
	v_mfma_f32_16x16x32_bf16 v[116:119], v[150:153], v[174:177], v[116:119]
	v_mfma_f32_16x16x32_bf16 v[108:111], v[158:161], v[174:177], v[108:111]
	v_mfma_f32_16x16x32_bf16 v[100:103], v[150:153], v[182:185], v[100:103]
	v_mfma_f32_16x16x32_bf16 v[92:95], v[158:161], v[182:185], v[92:95]
	v_mfma_f32_16x16x32_bf16 v[84:87], v[150:153], v[190:193], v[84:87]
	v_mfma_f32_16x16x32_bf16 v[76:79], v[158:161], v[190:193], v[76:79]
	v_mfma_f32_16x16x32_bf16 v[124:127], v[154:157], v[170:173], v[124:127]
	v_mfma_f32_16x16x32_bf16 v[120:123], v[162:165], v[170:173], v[120:123]
	v_mfma_f32_16x16x32_bf16 v[116:119], v[154:157], v[178:181], v[116:119]
	v_mfma_f32_16x16x32_bf16 v[108:111], v[162:165], v[178:181], v[108:111]
	v_mfma_f32_16x16x32_bf16 v[100:103], v[154:157], v[186:189], v[100:103]
	v_mfma_f32_16x16x32_bf16 v[92:95], v[162:165], v[186:189], v[92:95]
	v_mfma_f32_16x16x32_bf16 v[84:87], v[154:157], v[194:197], v[84:87]
	v_mfma_f32_16x16x32_bf16 v[76:79], v[162:165], v[194:197], v[76:79]
	s_setprio 0
	s_barrier
	s_add_i32 s66, s54, s43
	s_mov_b32 m0, s66
	ds_read_b128 v[202:205], v149
	ds_read_b128 v[206:209], v149 offset:1024
	ds_read_b128 v[210:213], v149 offset:2048
	ds_read_b128 v[214:217], v149 offset:3072
	global_load_lds_dwordx4 v130, s[34:35]
	s_add_i32 m0, s66, 0x2000
	s_nop 0
	global_load_lds_dwordx4 v134, s[34:35]
	s_waitcnt vmcnt(8)
	s_setprio 1
	s_barrier
; #define PG8_STAGE(bufoff, gbase, voff) do { _Pragma("unroll") for (int _i = 0; _i < 2; ++_i) \
;         __builtin_amdgcn_global_load_lds((const unsigned*)((const char*)(gbase) + (voff)[_i]), (LAS unsigned*)(lds + (bufoff) + ldsw + _i * 8192), 16, 0, 0); } while (0)
; #define PG8_LDA(dst, b, h) do { _Pragma("unroll") for (int m = 0; m < 4; ++m) _Pragma("unroll") for (int k = 0; k < 2; ++k) dst[m][k] = *(const LAS bf16x8*)(lds + PG8_SA(b, h) + aoff + m * 2048 + k * 1024); } while (0)
; #define PG8_LDB(dst, b, h) do { _Pragma("unroll") for (int n = 0; n < 2; ++n) _Pragma("unroll") for (int k = 0; k < 2; ++k) dst[n][k] = *(const LAS bf16x8*)(lds + PG8_SB(b, h) + boff + n * 2048 + k * 1024); } while (0)
; #define PG8_WAIT_V(n) asm volatile("s_waitcnt vmcnt(" #n ")" ::: "memory")
; #define PG8_WAIT_L(n) asm volatile("s_waitcnt lgkmcnt(" #n ")" ::: "memory")
; #define PG8_BAR __builtin_amdgcn_s_barrier()
; #define PG8_SCHED __builtin_amdgcn_sched_barrier(0)
; template <class Epi, class Sched>
; __device__ __forceinline__ void gemm_phase(LAS unsigned char* lds, const Gemm g, const Sched& S, const Epi& E) {
;     ...
;             PG8_LDB(B0, 0, 0); PG8_SCHED; PG8_LDA(At, 0, 0); PG8_STAGE(PG8_SA(1, 1), a1 + hstep, voffA);
;             PG8_WAIT_L(8); PG8_BAR; PG8_WAIT_L(0); PG8_MMA(0, 0, At, B0); PG8_BAR; PG8_SCHED;
;             PG8_LDB(B1, 0, 1); PG8_STAGE(PG8_SB(0, 0), b2, voffB);
;             PG8_BAR; PG8_WAIT_L(0); PG8_MMA(0, 1, At, B1); PG8_BAR;
;             PG8_LDA(At, 0, 1); PG8_STAGE(PG8_SA(0, 0), a2, voffA);
;             PG8_BAR; PG8_WAIT_L(0); PG8_MMA(1, 0, At, B0); PG8_BAR; PG8_SCHED;
;             PG8_STAGE(PG8_SB(0, 1), b2 + hstep, voffB);
;             PG8_WAIT_V(6); PG8_BAR; PG8_MMA(1, 1, At, B1); PG8_BAR;
;             PG8_LDB(B0, 1, 0); PG8_SCHED; PG8_LDA(At, 1, 0); PG8_STAGE(PG8_SA(0, 1), a2 + hstep, voffA);
;             PG8_WAIT_L(8); PG8_BAR; PG8_WAIT_L(0); PG8_MMA(0, 0, At, B0); PG8_BAR; PG8_SCHED;
;             PG8_LDB(B1, 1, 1); PG8_STAGE(PG8_SB(1, 0), b3, voffB);
;             PG8_BAR; PG8_WAIT_L(0); PG8_MMA(0, 1, At, B1); PG8_BAR;
;             PG8_LDA(At, 1, 1); PG8_STAGE(PG8_SA(1, 0), a3, voffA);
;             PG8_BAR; PG8_WAIT_L(0); PG8_MMA(1, 0, At, B0); PG8_BAR; PG8_SCHED;
;             PG8_STAGE(PG8_SB(1, 1), b3 + hstep, voffB);
;             PG8_WAIT_V(6); PG8_BAR; PG8_MMA(1, 1, At, B1); PG8_BAR;
	s_waitcnt lgkmcnt(0)
	s_waitcnt lgkmcnt(0)
	v_mfma_f32_16x16x32_bf16 v[112:115], v[202:205], v[166:169], v[112:115]
	v_mfma_f32_16x16x32_bf16 v[104:107], v[210:213], v[166:169], v[104:107]
	v_mfma_f32_16x16x32_bf16 v[96:99], v[202:205], v[174:177], v[96:99]
	v_mfma_f32_16x16x32_bf16 v[88:91], v[210:213], v[174:177], v[88:91]
	v_mfma_f32_16x16x32_bf16 v[80:83], v[202:205], v[182:185], v[80:83]
	v_mfma_f32_16x16x32_bf16 v[72:75], v[210:213], v[182:185], v[72:75]
	v_mfma_f32_16x16x32_bf16 v[68:71], v[202:205], v[190:193], v[68:71]
	v_mfma_f32_16x16x32_bf16 v[64:67], v[210:213], v[190:193], v[64:67]
	v_mfma_f32_16x16x32_bf16 v[112:115], v[206:209], v[170:173], v[112:115]
	v_mfma_f32_16x16x32_bf16 v[104:107], v[214:217], v[170:173], v[104:107]
	v_mfma_f32_16x16x32_bf16 v[96:99], v[206:209], v[178:181], v[96:99]
	v_mfma_f32_16x16x32_bf16 v[88:91], v[214:217], v[178:181], v[88:91]
	v_mfma_f32_16x16x32_bf16 v[80:83], v[206:209], v[186:189], v[80:83]
	v_mfma_f32_16x16x32_bf16 v[72:75], v[214:217], v[186:189], v[72:75]
	v_mfma_f32_16x16x32_bf16 v[68:71], v[206:209], v[194:197], v[68:71]
	v_mfma_f32_16x16x32_bf16 v[64:67], v[214:217], v[194:197], v[64:67]
	s_setprio 0
	s_mov_b32 m0, s29
	v_lshl_add_u64 v[220:221], s[36:37], 0, v[128:129]
	s_barrier
	ds_read_b128 v[166:169], v148 offset:16384
	ds_read_b128 v[170:173], v148 offset:17408
	ds_read_b128 v[174:177], v148 offset:18432
	ds_read_b128 v[178:181], v148 offset:19456
	ds_read_b128 v[182:185], v148 offset:20480
	ds_read_b128 v[186:189], v148 offset:21504
	ds_read_b128 v[190:193], v148 offset:22528
	ds_read_b128 v[194:197], v148 offset:23552
	global_load_lds_dwordx4 v128, s[36:37]
	v_lshl_add_u64 v[222:223], s[36:37], 0, v[132:133]
	s_mov_b32 m0, s44
	s_nop 0
	global_load_lds_dwordx4 v132, s[36:37]
	s_setprio 1
	s_barrier
	s_waitcnt lgkmcnt(0)
	s_waitcnt lgkmcnt(0)
	v_mfma_f32_16x16x32_bf16 v[60:63], v[150:153], v[166:169], v[60:63]
	v_mfma_f32_16x16x32_bf16 v[56:59], v[158:161], v[166:169], v[56:59]
	v_mfma_f32_16x16x32_bf16 v[52:55], v[150:153], v[174:177], v[52:55]
	v_mfma_f32_16x16x32_bf16 v[44:47], v[158:161], v[174:177], v[44:47]
	v_mfma_f32_16x16x32_bf16 v[36:39], v[150:153], v[182:185], v[36:39]
	v_mfma_f32_16x16x32_bf16 v[28:31], v[158:161], v[182:185], v[28:31]
	v_mfma_f32_16x16x32_bf16 v[20:23], v[150:153], v[190:193], v[20:23]
	v_mfma_f32_16x16x32_bf16 v[12:15], v[158:161], v[190:193], v[12:15]
	v_mfma_f32_16x16x32_bf16 v[60:63], v[154:157], v[170:173], v[60:63]
	v_mfma_f32_16x16x32_bf16 v[56:59], v[162:165], v[170:173], v[56:59]
	v_mfma_f32_16x16x32_bf16 v[52:55], v[154:157], v[178:181], v[52:55]
	v_mfma_f32_16x16x32_bf16 v[44:47], v[162:165], v[178:181], v[44:47]
	v_mfma_f32_16x16x32_bf16 v[36:39], v[154:157], v[186:189], v[36:39]
	v_mfma_f32_16x16x32_bf16 v[28:31], v[162:165], v[186:189], v[28:31]
	v_mfma_f32_16x16x32_bf16 v[20:23], v[154:157], v[194:197], v[20:23]
	v_mfma_f32_16x16x32_bf16 v[12:15], v[162:165], v[194:197], v[12:15]
	s_setprio 0
	s_barrier
	s_add_u32 s66, s34, 0x40000
	s_addc_u32 s67, s35, 0
	s_add_i32 s68, s55, s43
	s_mov_b32 m0, s68
	s_nop 0
	global_load_lds_dwordx4 v130, s[66:67]
	s_add_i32 m0, s68, 0x2000
	s_nop 0
	global_load_lds_dwordx4 v134, s[66:67]
	s_add_u32 s36, s36, 0x40000
	s_addc_u32 s37, s37, 0
	s_mov_b32 m0, s45
	s_nop 0
	global_load_lds_dwordx4 v128, s[36:37]
	s_mov_b32 m0, s46
	s_nop 0
	global_load_lds_dwordx4 v132, s[36:37]
	s_waitcnt vmcnt(10)
	s_setprio 1
	s_barrier
	v_mfma_f32_16x16x32_bf16 v[48:51], v[202:205], v[166:169], v[48:51]
	v_mfma_f32_16x16x32_bf16 v[40:43], v[210:213], v[166:169], v[40:43]
	v_mfma_f32_16x16x32_bf16 v[32:35], v[202:205], v[174:177], v[32:35]
	v_mfma_f32_16x16x32_bf16 v[24:27], v[210:213], v[174:177], v[24:27]
	v_mfma_f32_16x16x32_bf16 v[16:19], v[202:205], v[182:185], v[16:19]
	v_mfma_f32_16x16x32_bf16 v[8:11], v[210:213], v[182:185], v[8:11]
	v_mfma_f32_16x16x32_bf16 v[4:7], v[202:205], v[190:193], v[4:7]
	v_mfma_f32_16x16x32_bf16 v[0:3], v[210:213], v[190:193], v[0:3]
	v_mfma_f32_16x16x32_bf16 v[48:51], v[206:209], v[170:173], v[48:51]
	v_mfma_f32_16x16x32_bf16 v[40:43], v[214:217], v[170:173], v[40:43]
	v_mfma_f32_16x16x32_bf16 v[32:35], v[206:209], v[178:181], v[32:35]
	v_mfma_f32_16x16x32_bf16 v[24:27], v[214:217], v[178:181], v[24:27]
	v_mfma_f32_16x16x32_bf16 v[16:19], v[206:209], v[186:189], v[16:19]
	v_mfma_f32_16x16x32_bf16 v[8:11], v[214:217], v[186:189], v[8:11]
	v_mfma_f32_16x16x32_bf16 v[4:7], v[206:209], v[194:197], v[4:7]
	v_mfma_f32_16x16x32_bf16 v[0:3], v[214:217], v[194:197], v[0:3]
	s_setprio 0
	s_add_i32 s66, 0, 0x18000
	v_add_u32_e32 v162, s66, v146
	s_barrier
	ds_read_b128 v[150:153], v162
	ds_read_b128 v[154:157], v162 offset:1024
	ds_read_b128 v[158:161], v162 offset:2048
	ds_read_b128 v[162:165], v162 offset:3072
	ds_read_b128 v[166:169], v148 offset:32768
	ds_read_b128 v[170:173], v148 offset:33792
	ds_read_b128 v[174:177], v148 offset:34816
	ds_read_b128 v[178:181], v148 offset:35840
	ds_read_b128 v[182:185], v148 offset:36864
	ds_read_b128 v[186:189], v148 offset:37888
	ds_read_b128 v[190:193], v148 offset:38912
	ds_read_b128 v[194:197], v148 offset:39936
	s_waitcnt lgkmcnt(8)
	s_waitcnt vmcnt(8)
	s_setprio 1
	s_barrier
; #define PG8_STAGE(bufoff, gbase, voff) do { _Pragma("unroll") for (int _i = 0; _i < 2; ++_i) \
;         __builtin_amdgcn_global_load_lds((const unsigned*)((const char*)(gbase) + (voff)[_i]), (LAS unsigned*)(lds + (bufoff) + ldsw + _i * 8192), 16, 0, 0); } while (0)
; #define PG8_LDA(dst, b, h) do { _Pragma("unroll") for (int m = 0; m < 4; ++m) _Pragma("unroll") for (int k = 0; k < 2; ++k) dst[m][k] = *(const LAS bf16x8*)(lds + PG8_SA(b, h) + aoff + m * 2048 + k * 1024); } while (0)
; #define PG8_LDB(dst, b, h) do { _Pragma("unroll") for (int n = 0; n < 2; ++n) _Pragma("unroll") for (int k = 0; k < 2; ++k) dst[n][k] = *(const LAS bf16x8*)(lds + PG8_SB(b, h) + boff + n * 2048 + k * 1024); } while (0)
; #define PG8_WAIT_V(n) asm volatile("s_waitcnt vmcnt(" #n ")" ::: "memory")
; #define PG8_WAIT_L(n) asm volatile("s_waitcnt lgkmcnt(" #n ")" ::: "memory")
; #define PG8_BAR __builtin_amdgcn_s_barrier()
; #define PG8_SCHED __builtin_amdgcn_sched_barrier(0)
; template <class Epi, class Sched>
; __device__ __forceinline__ void gemm_phase(LAS unsigned char* lds, const Gemm g, const Sched& S, const Epi& E) {
;     ...
;             PG8_LDB(B0, 0, 0); PG8_SCHED; PG8_LDA(At, 0, 0); PG8_STAGE(PG8_SA(1, 1), a1 + hstep, voffA);
;             PG8_WAIT_L(8); PG8_BAR; PG8_WAIT_L(0); PG8_MMA(0, 0, At, B0); PG8_BAR; PG8_SCHED;
;             PG8_LDB(B1, 0, 1); PG8_STAGE(PG8_SB(0, 0), b2, voffB);
;             PG8_BAR; PG8_WAIT_L(0); PG8_MMA(0, 1, At, B1); PG8_BAR;
;             PG8_LDA(At, 0, 1); PG8_STAGE(PG8_SA(0, 0), a2, voffA);
;             PG8_BAR; PG8_WAIT_L(0); PG8_MMA(1, 0, At, B0); PG8_BAR; PG8_SCHED;
;             PG8_STAGE(PG8_SB(0, 1), b2 + hstep, voffB);
;             PG8_WAIT_V(6); PG8_BAR; PG8_MMA(1, 1, At, B1); PG8_BAR;
;             PG8_LDB(B0, 1, 0); PG8_SCHED; PG8_LDA(At, 1, 0); PG8_STAGE(PG8_SA(0, 1), a2 + hstep, voffA);
;             PG8_WAIT_L(8); PG8_BAR; PG8_WAIT_L(0); PG8_MMA(0, 0, At, B0); PG8_BAR; PG8_SCHED;
;             PG8_LDB(B1, 1, 1); PG8_STAGE(PG8_SB(1, 0), b3, voffB);
;             PG8_BAR; PG8_WAIT_L(0); PG8_MMA(0, 1, At, B1); PG8_BAR;
;             PG8_LDA(At, 1, 1); PG8_STAGE(PG8_SA(1, 0), a3, voffA);
;             PG8_BAR; PG8_WAIT_L(0); PG8_MMA(1, 0, At, B0); PG8_BAR; PG8_SCHED;
;             PG8_STAGE(PG8_SB(1, 1), b3 + hstep, voffB);
;             PG8_WAIT_V(6); PG8_BAR; PG8_MMA(1, 1, At, B1); PG8_BAR;
	s_waitcnt lgkmcnt(0)
	s_waitcnt lgkmcnt(0)
	v_mfma_f32_16x16x32_bf16 v[124:127], v[150:153], v[166:169], v[124:127]
	v_mfma_f32_16x16x32_bf16 v[120:123], v[158:161], v[166:169], v[120:123]
	v_mfma_f32_16x16x32_bf16 v[116:119], v[150:153], v[174:177], v[116:119]
	v_mfma_f32_16x16x32_bf16 v[108:111], v[158:161], v[174:177], v[108:111]
	v_mfma_f32_16x16x32_bf16 v[100:103], v[150:153], v[182:185], v[100:103]
	v_mfma_f32_16x16x32_bf16 v[92:95], v[158:161], v[182:185], v[92:95]
	v_mfma_f32_16x16x32_bf16 v[84:87], v[150:153], v[190:193], v[84:87]
	v_mfma_f32_16x16x32_bf16 v[76:79], v[158:161], v[190:193], v[76:79]
	v_mfma_f32_16x16x32_bf16 v[124:127], v[154:157], v[170:173], v[124:127]
	v_mfma_f32_16x16x32_bf16 v[120:123], v[162:165], v[170:173], v[120:123]
	v_mfma_f32_16x16x32_bf16 v[116:119], v[154:157], v[178:181], v[116:119]
	v_mfma_f32_16x16x32_bf16 v[108:111], v[162:165], v[178:181], v[108:111]
	v_mfma_f32_16x16x32_bf16 v[100:103], v[154:157], v[186:189], v[100:103]
	v_mfma_f32_16x16x32_bf16 v[92:95], v[162:165], v[186:189], v[92:95]
	v_mfma_f32_16x16x32_bf16 v[84:87], v[154:157], v[194:197], v[84:87]
	v_mfma_f32_16x16x32_bf16 v[76:79], v[162:165], v[194:197], v[76:79]
	s_setprio 0
	s_barrier
	s_add_i32 s36, 0, 0x1c000
	s_add_i32 s37, s66, s43
	v_add_u32_e32 v214, s36, v146
	s_add_u32 s4, s34, 0x80
	s_addc_u32 s5, s35, 0
	s_mov_b32 m0, s37
	ds_read_b128 v[202:205], v214
	ds_read_b128 v[206:209], v214 offset:1024
	ds_read_b128 v[210:213], v214 offset:2048
	ds_read_b128 v[214:217], v214 offset:3072
	global_load_lds_dwordx4 v130, s[4:5]
	s_add_i32 m0, s37, 0x2000
	s_nop 0
	global_load_lds_dwordx4 v134, s[4:5]
	s_waitcnt vmcnt(8)
	s_setprio 1
	s_barrier
	s_waitcnt lgkmcnt(0)
	s_waitcnt lgkmcnt(0)
	v_mfma_f32_16x16x32_bf16 v[112:115], v[202:205], v[166:169], v[112:115]
	v_mfma_f32_16x16x32_bf16 v[104:107], v[210:213], v[166:169], v[104:107]
	v_mfma_f32_16x16x32_bf16 v[96:99], v[202:205], v[174:177], v[96:99]
	v_mfma_f32_16x16x32_bf16 v[88:91], v[210:213], v[174:177], v[88:91]
	v_mfma_f32_16x16x32_bf16 v[80:83], v[202:205], v[182:185], v[80:83]
	v_mfma_f32_16x16x32_bf16 v[72:75], v[210:213], v[182:185], v[72:75]
	v_mfma_f32_16x16x32_bf16 v[68:71], v[202:205], v[190:193], v[68:71]
	v_mfma_f32_16x16x32_bf16 v[64:67], v[210:213], v[190:193], v[64:67]
	v_mfma_f32_16x16x32_bf16 v[112:115], v[206:209], v[170:173], v[112:115]
	v_mfma_f32_16x16x32_bf16 v[104:107], v[214:217], v[170:173], v[104:107]
	v_mfma_f32_16x16x32_bf16 v[96:99], v[206:209], v[178:181], v[96:99]
	v_mfma_f32_16x16x32_bf16 v[88:91], v[214:217], v[178:181], v[88:91]
	v_mfma_f32_16x16x32_bf16 v[80:83], v[206:209], v[186:189], v[80:83]
	v_mfma_f32_16x16x32_bf16 v[72:75], v[214:217], v[186:189], v[72:75]
	v_mfma_f32_16x16x32_bf16 v[68:71], v[206:209], v[194:197], v[68:71]
	v_mfma_f32_16x16x32_bf16 v[64:67], v[214:217], v[194:197], v[64:67]
	s_setprio 0
	s_mov_b32 m0, s51
	s_mov_b64 s[4:5], 0x80
	v_lshl_add_u64 v[198:199], v[220:221], 0, s[4:5]
	s_barrier
	ds_read_b128 v[166:169], v148 offset:49152
	ds_read_b128 v[170:173], v148 offset:50176
	ds_read_b128 v[174:177], v148 offset:51200
	ds_read_b128 v[178:181], v148 offset:52224
	ds_read_b128 v[182:185], v148 offset:53248
	ds_read_b128 v[186:189], v148 offset:54272
	ds_read_b128 v[190:193], v148 offset:55296
	ds_read_b128 v[194:197], v148 offset:56320
	global_load_lds_dwordx4 v[198:199], off
	v_lshl_add_u64 v[198:199], v[222:223], 0, s[4:5]
	s_mov_b32 m0, s52
	s_nop 0
	global_load_lds_dwordx4 v[198:199], off
	s_setprio 1
	s_barrier
	s_waitcnt lgkmcnt(0)
	s_waitcnt lgkmcnt(0)
	v_mfma_f32_16x16x32_bf16 v[60:63], v[150:153], v[166:169], v[60:63]
	v_mfma_f32_16x16x32_bf16 v[56:59], v[158:161], v[166:169], v[56:59]
	v_mfma_f32_16x16x32_bf16 v[52:55], v[150:153], v[174:177], v[52:55]
	v_mfma_f32_16x16x32_bf16 v[44:47], v[158:161], v[174:177], v[44:47]
	v_mfma_f32_16x16x32_bf16 v[36:39], v[150:153], v[182:185], v[36:39]
	v_mfma_f32_16x16x32_bf16 v[28:31], v[158:161], v[182:185], v[28:31]
	v_mfma_f32_16x16x32_bf16 v[20:23], v[150:153], v[190:193], v[20:23]
	v_mfma_f32_16x16x32_bf16 v[12:15], v[158:161], v[190:193], v[12:15]
	v_mfma_f32_16x16x32_bf16 v[60:63], v[154:157], v[170:173], v[60:63]
	v_mfma_f32_16x16x32_bf16 v[56:59], v[162:165], v[170:173], v[56:59]
	v_mfma_f32_16x16x32_bf16 v[52:55], v[154:157], v[178:181], v[52:55]
	v_mfma_f32_16x16x32_bf16 v[44:47], v[162:165], v[178:181], v[44:47]
	v_mfma_f32_16x16x32_bf16 v[36:39], v[154:157], v[186:189], v[36:39]
	v_mfma_f32_16x16x32_bf16 v[28:31], v[162:165], v[186:189], v[28:31]
	v_mfma_f32_16x16x32_bf16 v[20:23], v[154:157], v[194:197], v[20:23]
	v_mfma_f32_16x16x32_bf16 v[12:15], v[162:165], v[194:197], v[12:15]
	s_setprio 0
	s_barrier
	s_add_u32 s34, s34, 0x40080
	s_addc_u32 s35, s35, 0
	s_add_i32 s36, s36, s43
	s_mov_b32 m0, s36
	s_nop 0
	global_load_lds_dwordx4 v130, s[34:35]
	s_add_i32 m0, s36, 0x2000
	s_nop 0
	global_load_lds_dwordx4 v134, s[34:35]
	s_waitcnt vmcnt(8)
	s_setprio 1
	s_barrier
; __device__ __forceinline__ unsigned cvt_pk_bf16(float lo, float hi) { unsigned r; asm volatile("v_cvt_pk_bf16_f32 %0, %1, %2" : "=v"(r) : "v"(lo), "v"(hi)); return r; }
;     __device__ __forceinline__ void operator()(const AccT& acc, const Unit& u, int wr, int wc, int fr, int fq) const {
;     ...
;         const int rbase = u.pm * 256 + wr * 64 + fr;
;         const int tb = u.pn * 256 + wc * 32 + 8 * fq;
; #pragma unroll
;         for (int ai = 0; ai < 2; ++ai)
; #pragma unroll
;             for (int m = 0; m < 4; ++m) {
;                 const int r = rbase + ai * 128 + m * 16;
; #pragma unroll
;                 for (int bj = 0; bj < 2; ++bj) {
;                     const int t0 = tb + bj * 128;
;                     const f32x4 v0 = acc[ai][bj][m][0], v1 = acc[ai][bj][m][1];
;                     u32x4 w; w.x = cvt_pk_bf16(v0[0], v0[1]); w.y = cvt_pk_bf16(v0[2], v0[3]); w.z = cvt_pk_bf16(v1[0], v1[1]); w.w = cvt_pk_bf16(v1[2], v1[3]);
;                     *(u32x4*)(VT + (size_t)r * NT + t0) = w;
;                 }
	v_mfma_f32_16x16x32_bf16 v[48:51], v[202:205], v[166:169], v[48:51]
	v_mfma_f32_16x16x32_bf16 v[40:43], v[210:213], v[166:169], v[40:43]
	v_mfma_f32_16x16x32_bf16 v[32:35], v[202:205], v[174:177], v[32:35]
	v_mfma_f32_16x16x32_bf16 v[24:27], v[210:213], v[174:177], v[24:27]
	v_mfma_f32_16x16x32_bf16 v[16:19], v[202:205], v[182:185], v[16:19]
	v_mfma_f32_16x16x32_bf16 v[8:11], v[210:213], v[182:185], v[8:11]
	v_mfma_f32_16x16x32_bf16 v[4:7], v[202:205], v[190:193], v[4:7]
	v_mfma_f32_16x16x32_bf16 v[0:3], v[210:213], v[190:193], v[0:3]
	v_mfma_f32_16x16x32_bf16 v[48:51], v[206:209], v[170:173], v[48:51]
	v_mfma_f32_16x16x32_bf16 v[40:43], v[214:217], v[170:173], v[40:43]
	v_mfma_f32_16x16x32_bf16 v[32:35], v[206:209], v[178:181], v[32:35]
	v_mfma_f32_16x16x32_bf16 v[24:27], v[214:217], v[178:181], v[24:27]
	v_mfma_f32_16x16x32_bf16 v[16:19], v[206:209], v[186:189], v[16:19]
	v_mfma_f32_16x16x32_bf16 v[8:11], v[214:217], v[186:189], v[8:11]
	v_mfma_f32_16x16x32_bf16 v[4:7], v[206:209], v[194:197], v[4:7]
	v_mfma_f32_16x16x32_bf16 v[0:3], v[214:217], v[194:197], v[0:3]
	s_setprio 0
	s_add_i32 s65, s65, 2
	s_add_u32 s30, s30, 0x100
	s_addc_u32 s31, s31, 0
	s_add_u32 s63, s63, 0x100
	s_addc_u32 s64, s64, 0
	s_cmp_gt_u32 s65, 13
	s_barrier
	s_cbranch_scc0 .LBB0_633
	v_mov_b32_e32 v150, v144
	v_mov_b32_e32 v151, v145
	s_lshl_b32 s21, s28, 8
	s_add_i32 s21, s21, s48
	v_add_u32_e32 v150, s21, v150
	s_lshl_b32 s21, s60, 8
	s_or_b32 s21, s21, s49
	v_lshl_add_u32 v152, v151, 3, s21
	v_ashrrev_i32_e32 v151, 31, v150
	v_cvt_pk_bf16_f32 v124, v124, v125
	v_cvt_pk_bf16_f32 v125, v126, v127
	v_cvt_pk_bf16_f32 v126, v120, v121
	v_lshlrev_b64 v[120:121], 17, v[150:151]
	v_lshl_add_u64 v[120:121], s[0:1], 0, v[120:121]
	v_ashrrev_i32_e32 v153, 31, v152
	v_lshl_add_u64 v[120:121], v[152:153], 1, v[120:121]
	s_mov_b32 s21, 0x200000
	v_cvt_pk_bf16_f32 v127, v122, v123
	global_store_dwordx4 v[120:121], v[124:127], off
	v_cvt_pk_bf16_f32 v112, v112, v113
	v_cvt_pk_bf16_f32 v113, v114, v115
	v_cvt_pk_bf16_f32 v114, v104, v105
	v_cvt_pk_bf16_f32 v115, v106, v107
	global_store_dwordx4 v[120:121], v[112:115], off offset:256
	v_cvt_pk_bf16_f32 v104, v116, v117
	v_cvt_pk_bf16_f32 v105, v118, v119
	v_cvt_pk_bf16_f32 v106, v108, v109
	v_cvt_pk_bf16_f32 v107, v110, v111
	s_mov_b64 s[30:31], 0x200000
	v_add_co_u32_e32 v110, vcc, s21, v120
	v_lshl_add_u64 v[108:109], v[120:121], 0, s[30:31]
	s_nop 0
	v_addc_co_u32_e32 v111, vcc, 0, v121, vcc
	s_mov_b32 s21, 0x400000
	global_store_dwordx4 v[110:111], v[104:107], off
	v_cvt_pk_bf16_f32 v96, v96, v97
	v_cvt_pk_bf16_f32 v97, v98, v99
	v_cvt_pk_bf16_f32 v98, v88, v89
	v_cvt_pk_bf16_f32 v99, v90, v91
	global_store_dwordx4 v[108:109], v[96:99], off offset:256
	v_cvt_pk_bf16_f32 v88, v100, v101
	v_cvt_pk_bf16_f32 v89, v102, v103
	v_cvt_pk_bf16_f32 v90, v92, v93
	v_cvt_pk_bf16_f32 v91, v94, v95
	s_mov_b64 s[30:31], 0x400000
	v_add_co_u32_e32 v94, vcc, s21, v120
	v_lshl_add_u64 v[92:93], v[120:121], 0, s[30:31]
	s_nop 0
	v_addc_co_u32_e32 v95, vcc, 0, v121, vcc
	s_mov_b32 s21, 0x600000
	global_store_dwordx4 v[94:95], v[88:91], off
	v_cvt_pk_bf16_f32 v80, v80, v81
	v_cvt_pk_bf16_f32 v81, v82, v83
	v_cvt_pk_bf16_f32 v82, v72, v73
	v_cvt_pk_bf16_f32 v83, v74, v75
	global_store_dwordx4 v[92:93], v[80:83], off offset:256
	v_cvt_pk_bf16_f32 v72, v84, v85
	v_cvt_pk_bf16_f32 v73, v86, v87
	v_cvt_pk_bf16_f32 v74, v76, v77
	v_cvt_pk_bf16_f32 v75, v78, v79
	s_mov_b64 s[30:31], 0x600000
	v_add_co_u32_e32 v78, vcc, s21, v120
	v_lshl_add_u64 v[76:77], v[120:121], 0, s[30:31]
	s_nop 0
	v_addc_co_u32_e32 v79, vcc, 0, v121, vcc
	global_store_dwordx4 v[78:79], v[72:75], off
	v_cvt_pk_bf16_f32 v68, v68, v69
	v_cvt_pk_bf16_f32 v69, v70, v71
	v_cvt_pk_bf16_f32 v70, v64, v65
	v_cvt_pk_bf16_f32 v71, v66, v67
	global_store_dwordx4 v[76:77], v[68:71], off offset:256
	v_cvt_pk_bf16_f32 v60, v60, v61
	v_cvt_pk_bf16_f32 v61, v62, v63
	v_cvt_pk_bf16_f32 v62, v56, v57
	v_cvt_pk_bf16_f32 v63, v58, v59
	s_mov_b64 s[30:31], 0x1000000
	v_add_co_u32_e32 v58, vcc, s56, v120
	v_lshl_add_u64 v[56:57], v[120:121], 0, s[30:31]
	s_nop 0
	v_addc_co_u32_e32 v59, vcc, 0, v121, vcc
	global_store_dwordx4 v[58:59], v[60:63], off
	v_cvt_pk_bf16_f32 v48, v48, v49
	v_cvt_pk_bf16_f32 v49, v50, v51
	v_cvt_pk_bf16_f32 v50, v40, v41
	v_cvt_pk_bf16_f32 v51, v42, v43
	global_store_dwordx4 v[56:57], v[48:51], off offset:256
	v_cvt_pk_bf16_f32 v40, v52, v53
	v_cvt_pk_bf16_f32 v41, v54, v55
	v_cvt_pk_bf16_f32 v42, v44, v45
	v_cvt_pk_bf16_f32 v43, v46, v47
	v_add_co_u32_e32 v46, vcc, s57, v120
	v_lshl_add_u64 v[44:45], v[120:121], 0, s[6:7]
	s_nop 0
	v_addc_co_u32_e32 v47, vcc, 0, v121, vcc
	global_store_dwordx4 v[46:47], v[40:43], off
	v_cvt_pk_bf16_f32 v32, v32, v33
	v_cvt_pk_bf16_f32 v33, v34, v35
	v_cvt_pk_bf16_f32 v34, v24, v25
	v_cvt_pk_bf16_f32 v35, v26, v27
	global_store_dwordx4 v[44:45], v[32:35], off offset:256
	v_cvt_pk_bf16_f32 v24, v36, v37
	v_cvt_pk_bf16_f32 v25, v38, v39
	v_cvt_pk_bf16_f32 v26, v28, v29
	v_cvt_pk_bf16_f32 v27, v30, v31
	v_add_co_u32_e32 v30, vcc, s58, v120
	v_lshl_add_u64 v[28:29], v[120:121], 0, s[8:9]
	s_nop 0
	v_addc_co_u32_e32 v31, vcc, 0, v121, vcc
	global_store_dwordx4 v[30:31], v[24:27], off
	v_cvt_pk_bf16_f32 v16, v16, v17
	v_cvt_pk_bf16_f32 v17, v18, v19
	v_cvt_pk_bf16_f32 v18, v8, v9
	v_cvt_pk_bf16_f32 v19, v10, v11
	global_store_dwordx4 v[28:29], v[16:19], off offset:256
	v_cvt_pk_bf16_f32 v8, v20, v21
	v_cvt_pk_bf16_f32 v9, v22, v23
	v_cvt_pk_bf16_f32 v10, v12, v13
	v_cvt_pk_bf16_f32 v11, v14, v15
	v_add_co_u32_e32 v14, vcc, s59, v120
	v_lshl_add_u64 v[12:13], v[120:121], 0, s[16:17]
	s_nop 0
	v_addc_co_u32_e32 v15, vcc, 0, v121, vcc
	s_and_b64 vcc, exec, s[2:3]
	s_mov_b32 s60, s20
	s_mov_b32 s28, s22
	s_mov_b64 s[34:35], s[26:27]
	s_mov_b64 s[30:31], s[24:25]
	global_store_dwordx4 v[14:15], v[8:11], off
	v_cvt_pk_bf16_f32 v4, v4, v5
	v_cvt_pk_bf16_f32 v5, v6, v7
	v_cvt_pk_bf16_f32 v6, v0, v1
	v_cvt_pk_bf16_f32 v7, v2, v3
	global_store_dwordx4 v[12:13], v[4:7], off offset:256
	s_cbranch_vccz .LBB0_626
	s_waitcnt vmcnt(0)
	s_cmpk_gt_u32 s33, 0xff
	s_cbranch_scc1 .LBB0_637
	s_barrier

; #define PG8_STAGE(bufoff, gbase, voff) do { _Pragma("unroll") for (int _i = 0; _i < 2; ++_i) \
;         __builtin_amdgcn_global_load_lds((const unsigned*)((const char*)(gbase) + (voff)[_i]), (LAS unsigned*)(lds + (bufoff) + ldsw + _i * 8192), 16, 0, 0); } while (0)
; #define PG8_LDA(dst, b, h) do { _Pragma("unroll") for (int m = 0; m < 4; ++m) _Pragma("unroll") for (int k = 0; k < 2; ++k) dst[m][k] = *(const LAS bf16x8*)(lds + PG8_SA(b, h) + aoff + m * 2048 + k * 1024); } while (0)
; #define PG8_LDB(dst, b, h) do { _Pragma("unroll") for (int n = 0; n < 2; ++n) _Pragma("unroll") for (int k = 0; k < 2; ++k) dst[n][k] = *(const LAS bf16x8*)(lds + PG8_SB(b, h) + boff + n * 2048 + k * 1024); } while (0)
; #define PG8_WAIT_V(n) asm volatile("s_waitcnt vmcnt(" #n ")" ::: "memory")
; #define PG8_BAR __builtin_amdgcn_s_barrier()
; template <class Epi, class Sched>
; __device__ __forceinline__ void gemm_phase(LAS unsigned char* lds, const Gemm g, const Sched& S, const Epi& E) {
;     ...
;         const bool has_next = S.next(ui + 1, nxt);
;         const char* nA = has_next ? (const char*)g.A + (size_t)nxt.pm * tstep : cA; const char* nB = has_next ? (const char*)g.Bt + (size_t)nxt.pn * tstep : cB;
;         for (int t = 0; t < nt; t += 2) {
;             const bool last = (t == nt - 2);
;             const char* a1 = cA + (size_t)(t + 1) * kstep;
;             const char* a2 = last ? nA : cA + (size_t)(t + 2) * kstep; const char* b2 = last ? nB : cB + (size_t)(t + 2) * kstep;
;             const char* a3 = a2 + kstep; const char* b3 = b2 + kstep;
;             PG8_LDB(B0, 0, 0); PG8_SCHED; PG8_LDA(At, 0, 0); PG8_STAGE(PG8_SA(1, 1), a1 + hstep, voffA);
;             PG8_WAIT_L(8); PG8_BAR; PG8_WAIT_L(0); PG8_MMA(0, 0, At, B0); PG8_BAR; PG8_SCHED;
;             PG8_LDB(B1, 0, 1); PG8_STAGE(PG8_SB(0, 0), b2, voffB);
;             PG8_BAR; PG8_WAIT_L(0); PG8_MMA(0, 1, At, B1); PG8_BAR;
;             PG8_LDA(At, 0, 1); PG8_STAGE(PG8_SA(0, 0), a2, voffA);
;             PG8_BAR; PG8_WAIT_L(0); PG8_MMA(1, 0, At, B0); PG8_BAR; PG8_SCHED;
;             PG8_STAGE(PG8_SB(0, 1), b2 + hstep, voffB);
;             PG8_WAIT_V(6); PG8_BAR; PG8_MMA(1, 1, At, B1); PG8_BAR;
;             PG8_LDB(B0, 1, 0); PG8_SCHED; PG8_LDA(At, 1, 0); PG8_STAGE(PG8_SA(0, 1), a2 + hstep, voffA);
;             PG8_WAIT_L(8); PG8_BAR; PG8_WAIT_L(0); PG8_MMA(0, 0, At, B0); PG8_BAR; PG8_SCHED;
.LBB0_652:
	s_ashr_i32 s9, s8, 31
	v_cmp_lt_i64_e32 vcc, s[16:17], v[142:143]
	s_lshl_b64 s[16:17], s[8:9], 19
	s_add_u32 s16, s14, s16
	s_addc_u32 s17, s15, s17
	s_and_b64 s[18:19], vcc, exec
	s_cselect_b32 s9, s17, s23
	s_cselect_b32 s48, s16, s22
	s_ashr_i32 s7, s6, 31
	s_lshl_b64 s[18:19], s[6:7], 19
	s_add_u32 s18, s12, s18
	s_addc_u32 s19, s13, s19
	s_and_b64 s[26:27], vcc, exec
	s_cselect_b32 s7, s19, s25
	s_cselect_b32 s49, s18, s24
	s_add_u32 s22, s22, 0x40080
	s_addc_u32 s23, s23, 0
	s_add_u32 s51, s24, 0x100
	s_addc_u32 s52, s25, 0
	s_mov_b32 s53, -2
	s_waitcnt lgkmcnt(0)
	ds_read_b128 v[152:155], v149
	ds_read_b128 v[156:159], v149 offset:1024
	ds_read_b128 v[160:163], v149 offset:2048
	ds_read_b128 v[164:167], v149 offset:3072
	s_add_u32 s24, s22, 0xfffc0080
	s_addc_u32 s25, s23, -1
	s_cmp_eq_u32 s53, 12
	s_cselect_b32 s27, s9, s25
	s_cselect_b32 s26, s48, s24
	s_cselect_b32 s25, s7, s52
	s_cselect_b32 s24, s49, s51
	s_add_i32 m0, s21, 0xc000
	ds_read_b128 v[168:171], v150
	ds_read_b128 v[172:175], v150 offset:1024
	ds_read_b128 v[176:179], v150 offset:2048
	ds_read_b128 v[180:183], v150 offset:3072
	ds_read_b128 v[184:187], v150 offset:4096
	ds_read_b128 v[188:191], v150 offset:5120
	ds_read_b128 v[192:195], v150 offset:6144
	ds_read_b128 v[196:199], v150 offset:7168
	global_load_lds_dwordx4 v138, s[22:23]
	s_add_i32 m0, s21, 0xe000
	s_nop 0
	global_load_lds_dwordx4 v140, s[22:23]
	s_waitcnt lgkmcnt(8)
	s_waitcnt vmcnt(8)
	s_setprio 1
	s_barrier
	s_waitcnt lgkmcnt(0)
	s_waitcnt lgkmcnt(0)
	v_mfma_f32_16x16x32_bf16 v[124:127], v[152:155], v[168:171], 0
	v_mfma_f32_16x16x32_bf16 v[120:123], v[160:163], v[168:171], 0
	v_mfma_f32_16x16x32_bf16 v[112:115], v[152:155], v[176:179], 0
	v_mfma_f32_16x16x32_bf16 v[104:107], v[160:163], v[176:179], 0
	v_mfma_f32_16x16x32_bf16 v[96:99], v[152:155], v[184:187], 0
	v_mfma_f32_16x16x32_bf16 v[88:91], v[160:163], v[184:187], 0
	v_mfma_f32_16x16x32_bf16 v[80:83], v[152:155], v[192:195], 0
	v_mfma_f32_16x16x32_bf16 v[72:75], v[160:163], v[192:195], 0
	v_mfma_f32_16x16x32_bf16 v[124:127], v[156:159], v[172:175], v[124:127]
	v_mfma_f32_16x16x32_bf16 v[120:123], v[164:167], v[172:175], v[120:123]
	v_mfma_f32_16x16x32_bf16 v[112:115], v[156:159], v[180:183], v[112:115]
	v_mfma_f32_16x16x32_bf16 v[104:107], v[164:167], v[180:183], v[104:107]
	v_mfma_f32_16x16x32_bf16 v[96:99], v[156:159], v[188:191], v[96:99]
	v_mfma_f32_16x16x32_bf16 v[88:91], v[164:167], v[188:191], v[88:91]
	v_mfma_f32_16x16x32_bf16 v[80:83], v[156:159], v[196:199], v[80:83]
	v_mfma_f32_16x16x32_bf16 v[72:75], v[164:167], v[196:199], v[72:75]
	s_setprio 0
	s_barrier
	s_add_i32 s54, s45, s30
	s_mov_b32 m0, s54
	ds_read_b128 v[202:205], v151
	ds_read_b128 v[206:209], v151 offset:1024
	ds_read_b128 v[210:213], v151 offset:2048
	ds_read_b128 v[214:217], v151 offset:3072
	global_load_lds_dwordx4 v130, s[24:25]
	s_add_i32 m0, s54, 0x2000
	s_nop 0
	global_load_lds_dwordx4 v134, s[24:25]
	s_waitcnt vmcnt(8)
	s_setprio 1
	s_barrier
	s_waitcnt lgkmcnt(0)
	s_waitcnt lgkmcnt(0)
	v_mfma_f32_16x16x32_bf16 v[116:119], v[202:205], v[168:171], 0
	v_mfma_f32_16x16x32_bf16 v[108:111], v[210:213], v[168:171], 0
	v_mfma_f32_16x16x32_bf16 v[100:103], v[202:205], v[176:179], 0
	v_mfma_f32_16x16x32_bf16 v[92:95], v[210:213], v[176:179], 0
	v_mfma_f32_16x16x32_bf16 v[84:87], v[202:205], v[184:187], 0
	v_mfma_f32_16x16x32_bf16 v[76:79], v[210:213], v[184:187], 0
	v_mfma_f32_16x16x32_bf16 v[68:71], v[202:205], v[192:195], 0
	v_mfma_f32_16x16x32_bf16 v[64:67], v[210:213], v[192:195], 0
	v_mfma_f32_16x16x32_bf16 v[116:119], v[206:209], v[172:175], v[116:119]
	v_mfma_f32_16x16x32_bf16 v[108:111], v[214:217], v[172:175], v[108:111]
	v_mfma_f32_16x16x32_bf16 v[100:103], v[206:209], v[180:183], v[100:103]
	v_mfma_f32_16x16x32_bf16 v[92:95], v[214:217], v[180:183], v[92:95]
	v_mfma_f32_16x16x32_bf16 v[84:87], v[206:209], v[188:191], v[84:87]
	v_mfma_f32_16x16x32_bf16 v[76:79], v[214:217], v[188:191], v[76:79]
	v_mfma_f32_16x16x32_bf16 v[68:71], v[206:209], v[196:199], v[68:71]
	v_mfma_f32_16x16x32_bf16 v[64:67], v[214:217], v[196:199], v[64:67]
	s_setprio 0
	s_mov_b32 m0, s21
	v_lshl_add_u64 v[222:223], s[26:27], 0, v[128:129]
	s_barrier
	ds_read_b128 v[168:171], v150 offset:16384
	ds_read_b128 v[172:175], v150 offset:17408
	ds_read_b128 v[176:179], v150 offset:18432
	ds_read_b128 v[180:183], v150 offset:19456
	ds_read_b128 v[184:187], v150 offset:20480
	ds_read_b128 v[188:191], v150 offset:21504
	ds_read_b128 v[192:195], v150 offset:22528
	ds_read_b128 v[196:199], v150 offset:23552
	global_load_lds_dwordx4 v128, s[26:27]
	v_lshl_add_u64 v[224:225], s[26:27], 0, v[132:133]
	s_mov_b32 m0, s31
	s_nop 0
	global_load_lds_dwordx4 v132, s[26:27]
	s_setprio 1
	s_barrier
	s_waitcnt lgkmcnt(0)
	s_waitcnt lgkmcnt(0)
	v_mfma_f32_16x16x32_bf16 v[60:63], v[152:155], v[168:171], 0
	v_mfma_f32_16x16x32_bf16 v[56:59], v[160:163], v[168:171], 0
	v_mfma_f32_16x16x32_bf16 v[48:51], v[152:155], v[176:179], 0
	v_mfma_f32_16x16x32_bf16 v[40:43], v[160:163], v[176:179], 0
	v_mfma_f32_16x16x32_bf16 v[32:35], v[152:155], v[184:187], 0
	v_mfma_f32_16x16x32_bf16 v[24:27], v[160:163], v[184:187], 0
	v_mfma_f32_16x16x32_bf16 v[16:19], v[152:155], v[192:195], 0
	v_mfma_f32_16x16x32_bf16 v[8:11], v[160:163], v[192:195], 0
	v_mfma_f32_16x16x32_bf16 v[60:63], v[156:159], v[172:175], v[60:63]
	v_mfma_f32_16x16x32_bf16 v[56:59], v[164:167], v[172:175], v[56:59]
	v_mfma_f32_16x16x32_bf16 v[48:51], v[156:159], v[180:183], v[48:51]
	v_mfma_f32_16x16x32_bf16 v[40:43], v[164:167], v[180:183], v[40:43]
	v_mfma_f32_16x16x32_bf16 v[32:35], v[156:159], v[188:191], v[32:35]
	v_mfma_f32_16x16x32_bf16 v[24:27], v[164:167], v[188:191], v[24:27]
	v_mfma_f32_16x16x32_bf16 v[16:19], v[156:159], v[196:199], v[16:19]
	v_mfma_f32_16x16x32_bf16 v[8:11], v[164:167], v[196:199], v[8:11]
	s_setprio 0
	s_barrier
; #define PG8_STAGE(bufoff, gbase, voff) do { _Pragma("unroll") for (int _i = 0; _i < 2; ++_i) \
;         __builtin_amdgcn_global_load_lds((const unsigned*)((const char*)(gbase) + (voff)[_i]), (LAS unsigned*)(lds + (bufoff) + ldsw + _i * 8192), 16, 0, 0); } while (0)
; #define PG8_LDA(dst, b, h) do { _Pragma("unroll") for (int m = 0; m < 4; ++m) _Pragma("unroll") for (int k = 0; k < 2; ++k) dst[m][k] = *(const LAS bf16x8*)(lds + PG8_SA(b, h) + aoff + m * 2048 + k * 1024); } while (0)
; #define PG8_LDB(dst, b, h) do { _Pragma("unroll") for (int n = 0; n < 2; ++n) _Pragma("unroll") for (int k = 0; k < 2; ++k) dst[n][k] = *(const LAS bf16x8*)(lds + PG8_SB(b, h) + boff + n * 2048 + k * 1024); } while (0)
; #define PG8_MMA(ai, bj, At, Bt) do { __builtin_amdgcn_s_setprio(1); _Pragma("unroll") for (int m = 0; m < 4; ++m) _Pragma("unroll") for (int n = 0; n < 2; ++n) _Pragma("unroll") for (int k = 0; k < 2; ++k) \
;         acc[ai][bj][m][n] = __builtin_amdgcn_mfma_f32_16x16x32_bf16(Bt[n][k], At[m][k], acc[ai][bj][m][n], 0, 0, 0); __builtin_amdgcn_s_setprio(0); } while (0)
; #define PG8_WAIT_V(n) asm volatile("s_waitcnt vmcnt(" #n ")" ::: "memory")
; #define PG8_WAIT_L(n) asm volatile("s_waitcnt lgkmcnt(" #n ")" ::: "memory")
; #define PG8_BAR __builtin_amdgcn_s_barrier()
; #define PG8_SCHED __builtin_amdgcn_sched_barrier(0)
; template <class Epi, class Sched>
; __device__ __forceinline__ void gemm_phase(LAS unsigned char* lds, const Gemm g, const Sched& S, const Epi& E) {
;     ...
;             PG8_LDA(At, 0, 1); PG8_STAGE(PG8_SA(0, 0), a2, voffA);
;             PG8_BAR; PG8_WAIT_L(0); PG8_MMA(1, 0, At, B0); PG8_BAR; PG8_SCHED;
;             PG8_STAGE(PG8_SB(0, 1), b2 + hstep, voffB);
;             PG8_WAIT_V(6); PG8_BAR; PG8_MMA(1, 1, At, B1); PG8_BAR;
;             PG8_LDB(B0, 1, 0); PG8_SCHED; PG8_LDA(At, 1, 0); PG8_STAGE(PG8_SA(0, 1), a2 + hstep, voffA);
;             PG8_WAIT_L(8); PG8_BAR; PG8_WAIT_L(0); PG8_MMA(0, 0, At, B0); PG8_BAR; PG8_SCHED;
;             PG8_LDB(B1, 1, 1); PG8_STAGE(PG8_SB(1, 0), b3, voffB);
;             PG8_BAR; PG8_WAIT_L(0); PG8_MMA(0, 1, At, B1); PG8_BAR;
;             PG8_LDA(At, 1, 1); PG8_STAGE(PG8_SA(1, 0), a3, voffA);
;             PG8_BAR; PG8_WAIT_L(0); PG8_MMA(1, 0, At, B0); PG8_BAR; PG8_SCHED;
;             PG8_STAGE(PG8_SB(1, 1), b3 + hstep, voffB);
;             PG8_WAIT_V(6); PG8_BAR; PG8_MMA(1, 1, At, B1); PG8_BAR;
	s_add_u32 s54, s24, 0x40000
	s_addc_u32 s55, s25, 0
	s_add_i32 s56, s46, s30
	s_mov_b32 m0, s56
	s_nop 0
	global_load_lds_dwordx4 v130, s[54:55]
	s_add_i32 m0, s56, 0x2000
	s_nop 0
	global_load_lds_dwordx4 v134, s[54:55]
	s_add_u32 s26, s26, 0x40000
	s_addc_u32 s27, s27, 0
	s_mov_b32 m0, s33
	s_nop 0
	global_load_lds_dwordx4 v128, s[26:27]
	s_mov_b32 m0, s34
	s_nop 0
	global_load_lds_dwordx4 v132, s[26:27]
	s_waitcnt vmcnt(10)
	s_setprio 1
	s_barrier
	v_mfma_f32_16x16x32_bf16 v[52:55], v[202:205], v[168:171], 0
	v_mfma_f32_16x16x32_bf16 v[44:47], v[210:213], v[168:171], 0
	v_mfma_f32_16x16x32_bf16 v[36:39], v[202:205], v[176:179], 0
	v_mfma_f32_16x16x32_bf16 v[28:31], v[210:213], v[176:179], 0
	v_mfma_f32_16x16x32_bf16 v[20:23], v[202:205], v[184:187], 0
	v_mfma_f32_16x16x32_bf16 v[12:15], v[210:213], v[184:187], 0
	v_mfma_f32_16x16x32_bf16 v[4:7], v[202:205], v[192:195], 0
	v_mfma_f32_16x16x32_bf16 v[0:3], v[210:213], v[192:195], 0
	v_mfma_f32_16x16x32_bf16 v[52:55], v[206:209], v[172:175], v[52:55]
	v_mfma_f32_16x16x32_bf16 v[44:47], v[214:217], v[172:175], v[44:47]
	v_mfma_f32_16x16x32_bf16 v[36:39], v[206:209], v[180:183], v[36:39]
	v_mfma_f32_16x16x32_bf16 v[28:31], v[214:217], v[180:183], v[28:31]
	v_mfma_f32_16x16x32_bf16 v[20:23], v[206:209], v[188:191], v[20:23]
	v_mfma_f32_16x16x32_bf16 v[12:15], v[214:217], v[188:191], v[12:15]
	v_mfma_f32_16x16x32_bf16 v[4:7], v[206:209], v[196:199], v[4:7]
	v_mfma_f32_16x16x32_bf16 v[0:3], v[214:217], v[196:199], v[0:3]
	s_setprio 0
	s_add_i32 s54, 0, 0x18000
	v_add_u32_e32 v136, s54, v148
	s_barrier
	ds_read_b128 v[152:155], v136
	ds_read_b128 v[156:159], v136 offset:1024
	ds_read_b128 v[160:163], v136 offset:2048
	ds_read_b128 v[164:167], v136 offset:3072
	ds_read_b128 v[168:171], v150 offset:32768
	ds_read_b128 v[172:175], v150 offset:33792
	ds_read_b128 v[176:179], v150 offset:34816
	ds_read_b128 v[180:183], v150 offset:35840
	ds_read_b128 v[184:187], v150 offset:36864
	ds_read_b128 v[188:191], v150 offset:37888
	ds_read_b128 v[192:195], v150 offset:38912
	ds_read_b128 v[196:199], v150 offset:39936
	s_waitcnt lgkmcnt(8)
	s_waitcnt vmcnt(8)
	s_setprio 1
	s_barrier
	s_waitcnt lgkmcnt(0)
	s_waitcnt lgkmcnt(0)
	v_mfma_f32_16x16x32_bf16 v[124:127], v[152:155], v[168:171], v[124:127]
	v_mfma_f32_16x16x32_bf16 v[120:123], v[160:163], v[168:171], v[120:123]
	v_mfma_f32_16x16x32_bf16 v[112:115], v[152:155], v[176:179], v[112:115]
	v_mfma_f32_16x16x32_bf16 v[104:107], v[160:163], v[176:179], v[104:107]
	v_mfma_f32_16x16x32_bf16 v[96:99], v[152:155], v[184:187], v[96:99]
	v_mfma_f32_16x16x32_bf16 v[88:91], v[160:163], v[184:187], v[88:91]
	v_mfma_f32_16x16x32_bf16 v[80:83], v[152:155], v[192:195], v[80:83]
	v_mfma_f32_16x16x32_bf16 v[72:75], v[160:163], v[192:195], v[72:75]
	v_mfma_f32_16x16x32_bf16 v[124:127], v[156:159], v[172:175], v[124:127]
	v_mfma_f32_16x16x32_bf16 v[120:123], v[164:167], v[172:175], v[120:123]
	v_mfma_f32_16x16x32_bf16 v[112:115], v[156:159], v[180:183], v[112:115]
	v_mfma_f32_16x16x32_bf16 v[104:107], v[164:167], v[180:183], v[104:107]
	v_mfma_f32_16x16x32_bf16 v[96:99], v[156:159], v[188:191], v[96:99]
	v_mfma_f32_16x16x32_bf16 v[88:91], v[164:167], v[188:191], v[88:91]
	v_mfma_f32_16x16x32_bf16 v[80:83], v[156:159], v[196:199], v[80:83]
	v_mfma_f32_16x16x32_bf16 v[72:75], v[164:167], v[196:199], v[72:75]
	s_setprio 0
	s_barrier
	s_add_i32 s26, 0, 0x1c000
	s_add_i32 s27, s54, s30
	v_add_u32_e32 v136, s26, v148
	s_add_u32 s0, s24, 0x80
	s_addc_u32 s1, s25, 0
	s_mov_b32 m0, s27
	ds_read_b128 v[202:205], v136
	ds_read_b128 v[206:209], v136 offset:1024
	ds_read_b128 v[210:213], v136 offset:2048
	ds_read_b128 v[214:217], v136 offset:3072
	global_load_lds_dwordx4 v130, s[0:1]
	s_add_i32 m0, s27, 0x2000
	s_nop 0
	global_load_lds_dwordx4 v134, s[0:1]
	s_waitcnt vmcnt(8)
	s_setprio 1
	s_barrier
	s_waitcnt lgkmcnt(0)
	s_waitcnt lgkmcnt(0)
	v_mfma_f32_16x16x32_bf16 v[116:119], v[202:205], v[168:171], v[116:119]
	v_mfma_f32_16x16x32_bf16 v[108:111], v[210:213], v[168:171], v[108:111]
	v_mfma_f32_16x16x32_bf16 v[100:103], v[202:205], v[176:179], v[100:103]
	v_mfma_f32_16x16x32_bf16 v[92:95], v[210:213], v[176:179], v[92:95]
	v_mfma_f32_16x16x32_bf16 v[84:87], v[202:205], v[184:187], v[84:87]
	v_mfma_f32_16x16x32_bf16 v[76:79], v[210:213], v[184:187], v[76:79]
	v_mfma_f32_16x16x32_bf16 v[68:71], v[202:205], v[192:195], v[68:71]
	v_mfma_f32_16x16x32_bf16 v[64:67], v[210:213], v[192:195], v[64:67]
	v_mfma_f32_16x16x32_bf16 v[116:119], v[206:209], v[172:175], v[116:119]
	v_mfma_f32_16x16x32_bf16 v[108:111], v[214:217], v[172:175], v[108:111]
	v_mfma_f32_16x16x32_bf16 v[100:103], v[206:209], v[180:183], v[100:103]
	v_mfma_f32_16x16x32_bf16 v[92:95], v[214:217], v[180:183], v[92:95]
	v_mfma_f32_16x16x32_bf16 v[84:87], v[206:209], v[188:191], v[84:87]
	v_mfma_f32_16x16x32_bf16 v[76:79], v[214:217], v[188:191], v[76:79]
	v_mfma_f32_16x16x32_bf16 v[68:71], v[206:209], v[196:199], v[68:71]
	v_mfma_f32_16x16x32_bf16 v[64:67], v[214:217], v[196:199], v[64:67]
	s_setprio 0
	s_mov_b32 m0, s42
	s_mov_b64 s[0:1], 0x80
	v_lshl_add_u64 v[218:219], v[222:223], 0, s[0:1]
	s_barrier
	ds_read_b128 v[168:171], v150 offset:49152
	ds_read_b128 v[172:175], v150 offset:50176
	ds_read_b128 v[176:179], v150 offset:51200
	ds_read_b128 v[180:183], v150 offset:52224
	ds_read_b128 v[184:187], v150 offset:53248
	ds_read_b128 v[188:191], v150 offset:54272
	ds_read_b128 v[192:195], v150 offset:55296
	ds_read_b128 v[196:199], v150 offset:56320
	global_load_lds_dwordx4 v[218:219], off
	v_lshl_add_u64 v[218:219], v[224:225], 0, s[0:1]
	s_mov_b32 m0, s43
	s_nop 0
	global_load_lds_dwordx4 v[218:219], off
	s_setprio 1
	s_barrier
; #define PG8_STAGE(bufoff, gbase, voff) do { _Pragma("unroll") for (int _i = 0; _i < 2; ++_i) \
;         __builtin_amdgcn_global_load_lds((const unsigned*)((const char*)(gbase) + (voff)[_i]), (LAS unsigned*)(lds + (bufoff) + ldsw + _i * 8192), 16, 0, 0); } while (0)
; #define PG8_LDA(dst, b, h) do { _Pragma("unroll") for (int m = 0; m < 4; ++m) _Pragma("unroll") for (int k = 0; k < 2; ++k) dst[m][k] = *(const LAS bf16x8*)(lds + PG8_SA(b, h) + aoff + m * 2048 + k * 1024); } while (0)
; #define PG8_LDB(dst, b, h) do { _Pragma("unroll") for (int n = 0; n < 2; ++n) _Pragma("unroll") for (int k = 0; k < 2; ++k) dst[n][k] = *(const LAS bf16x8*)(lds + PG8_SB(b, h) + boff + n * 2048 + k * 1024); } while (0)
; #define PG8_WAIT_V(n) asm volatile("s_waitcnt vmcnt(" #n ")" ::: "memory")
; #define PG8_WAIT_L(n) asm volatile("s_waitcnt lgkmcnt(" #n ")" ::: "memory")
; #define PG8_BAR __builtin_amdgcn_s_barrier()
; #define PG8_SCHED __builtin_amdgcn_sched_barrier(0)
; template <class Epi, class Sched>
; __device__ __forceinline__ void gemm_phase(LAS unsigned char* lds, const Gemm g, const Sched& S, const Epi& E) {
;     ...
;             PG8_LDB(B0, 0, 0); PG8_SCHED; PG8_LDA(At, 0, 0); PG8_STAGE(PG8_SA(1, 1), a1 + hstep, voffA);
;             PG8_WAIT_L(8); PG8_BAR; PG8_WAIT_L(0); PG8_MMA(0, 0, At, B0); PG8_BAR; PG8_SCHED;
;             PG8_LDB(B1, 0, 1); PG8_STAGE(PG8_SB(0, 0), b2, voffB);
;             PG8_BAR; PG8_WAIT_L(0); PG8_MMA(0, 1, At, B1); PG8_BAR;
;             PG8_LDA(At, 0, 1); PG8_STAGE(PG8_SA(0, 0), a2, voffA);
;             PG8_BAR; PG8_WAIT_L(0); PG8_MMA(1, 0, At, B0); PG8_BAR; PG8_SCHED;
;             PG8_STAGE(PG8_SB(0, 1), b2 + hstep, voffB);
;             PG8_WAIT_V(6); PG8_BAR; PG8_MMA(1, 1, At, B1); PG8_BAR;
;             PG8_LDB(B0, 1, 0); PG8_SCHED; PG8_LDA(At, 1, 0); PG8_STAGE(PG8_SA(0, 1), a2 + hstep, voffA);
;             PG8_WAIT_L(8); PG8_BAR; PG8_WAIT_L(0); PG8_MMA(0, 0, At, B0); PG8_BAR; PG8_SCHED;
;             PG8_LDB(B1, 1, 1); PG8_STAGE(PG8_SB(1, 0), b3, voffB);
;             PG8_BAR; PG8_WAIT_L(0); PG8_MMA(0, 1, At, B1); PG8_BAR;
;             PG8_LDA(At, 1, 1); PG8_STAGE(PG8_SA(1, 0), a3, voffA);
;             PG8_BAR; PG8_WAIT_L(0); PG8_MMA(1, 0, At, B0); PG8_BAR; PG8_SCHED;
;             PG8_STAGE(PG8_SB(1, 1), b3 + hstep, voffB);
;             PG8_WAIT_V(6); PG8_BAR; PG8_MMA(1, 1, At, B1); PG8_BAR;
	s_waitcnt lgkmcnt(0)
	s_waitcnt lgkmcnt(0)
	v_mfma_f32_16x16x32_bf16 v[60:63], v[152:155], v[168:171], v[60:63]
	v_mfma_f32_16x16x32_bf16 v[56:59], v[160:163], v[168:171], v[56:59]
	v_mfma_f32_16x16x32_bf16 v[48:51], v[152:155], v[176:179], v[48:51]
	v_mfma_f32_16x16x32_bf16 v[40:43], v[160:163], v[176:179], v[40:43]
	v_mfma_f32_16x16x32_bf16 v[32:35], v[152:155], v[184:187], v[32:35]
	v_mfma_f32_16x16x32_bf16 v[24:27], v[160:163], v[184:187], v[24:27]
	v_mfma_f32_16x16x32_bf16 v[16:19], v[152:155], v[192:195], v[16:19]
	v_mfma_f32_16x16x32_bf16 v[8:11], v[160:163], v[192:195], v[8:11]
	v_mfma_f32_16x16x32_bf16 v[60:63], v[156:159], v[172:175], v[60:63]
	v_mfma_f32_16x16x32_bf16 v[56:59], v[164:167], v[172:175], v[56:59]
	v_mfma_f32_16x16x32_bf16 v[48:51], v[156:159], v[180:183], v[48:51]
	v_mfma_f32_16x16x32_bf16 v[40:43], v[164:167], v[180:183], v[40:43]
	v_mfma_f32_16x16x32_bf16 v[32:35], v[156:159], v[188:191], v[32:35]
	v_mfma_f32_16x16x32_bf16 v[24:27], v[164:167], v[188:191], v[24:27]
	v_mfma_f32_16x16x32_bf16 v[16:19], v[156:159], v[196:199], v[16:19]
	v_mfma_f32_16x16x32_bf16 v[8:11], v[164:167], v[196:199], v[8:11]
	s_setprio 0
	s_barrier
	s_add_u32 s24, s24, 0x40080
	s_addc_u32 s25, s25, 0
	s_add_i32 s26, s26, s30
	s_mov_b32 m0, s26
	s_nop 0
	global_load_lds_dwordx4 v130, s[24:25]
	s_add_i32 m0, s26, 0x2000
	s_nop 0
	global_load_lds_dwordx4 v134, s[24:25]
	s_waitcnt vmcnt(8)
	s_setprio 1
	s_barrier
	v_mfma_f32_16x16x32_bf16 v[52:55], v[202:205], v[168:171], v[52:55]
	v_mfma_f32_16x16x32_bf16 v[44:47], v[210:213], v[168:171], v[44:47]
	v_mfma_f32_16x16x32_bf16 v[36:39], v[202:205], v[176:179], v[36:39]
	v_mfma_f32_16x16x32_bf16 v[28:31], v[210:213], v[176:179], v[28:31]
	v_mfma_f32_16x16x32_bf16 v[20:23], v[202:205], v[184:187], v[20:23]
	v_mfma_f32_16x16x32_bf16 v[12:15], v[210:213], v[184:187], v[12:15]
	v_mfma_f32_16x16x32_bf16 v[4:7], v[202:205], v[192:195], v[4:7]
	v_mfma_f32_16x16x32_bf16 v[0:3], v[210:213], v[192:195], v[0:3]
	v_mfma_f32_16x16x32_bf16 v[52:55], v[206:209], v[172:175], v[52:55]
	v_mfma_f32_16x16x32_bf16 v[44:47], v[214:217], v[172:175], v[44:47]
	v_mfma_f32_16x16x32_bf16 v[36:39], v[206:209], v[180:183], v[36:39]
	v_mfma_f32_16x16x32_bf16 v[28:31], v[214:217], v[180:183], v[28:31]
	v_mfma_f32_16x16x32_bf16 v[20:23], v[206:209], v[188:191], v[20:23]
	v_mfma_f32_16x16x32_bf16 v[12:15], v[214:217], v[188:191], v[12:15]
	v_mfma_f32_16x16x32_bf16 v[4:7], v[206:209], v[196:199], v[4:7]
	v_mfma_f32_16x16x32_bf16 v[0:3], v[214:217], v[196:199], v[0:3]
	s_setprio 0
	s_add_i32 s53, s53, 2
	s_add_u32 s22, s22, 0x100
	s_addc_u32 s23, s23, 0
	s_add_u32 s51, s51, 0x100
	s_addc_u32 s52, s52, 0
	s_cmp_gt_u32 s53, 13
	s_barrier
.LBB0_653:
	ds_read_b128 v[152:155], v149
	ds_read_b128 v[156:159], v149 offset:1024
	ds_read_b128 v[160:163], v149 offset:2048
	ds_read_b128 v[164:167], v149 offset:3072
	s_add_u32 s24, s22, 0xfffc0080
	s_addc_u32 s25, s23, -1
	s_cmp_eq_u32 s53, 12
	s_cselect_b32 s27, s9, s25
	s_cselect_b32 s26, s48, s24
	s_cselect_b32 s25, s7, s52
	s_cselect_b32 s24, s49, s51
	s_add_i32 m0, s21, 0xc000
	ds_read_b128 v[168:171], v150
	ds_read_b128 v[172:175], v150 offset:1024
	ds_read_b128 v[176:179], v150 offset:2048
	ds_read_b128 v[180:183], v150 offset:3072
	ds_read_b128 v[184:187], v150 offset:4096
	ds_read_b128 v[188:191], v150 offset:5120
	ds_read_b128 v[192:195], v150 offset:6144
	ds_read_b128 v[196:199], v150 offset:7168
	global_load_lds_dwordx4 v138, s[22:23]
	s_add_i32 m0, s21, 0xe000
	s_nop 0
	global_load_lds_dwordx4 v140, s[22:23]
	s_waitcnt lgkmcnt(8)
	s_waitcnt vmcnt(8)
	s_setprio 1
	s_barrier
	s_waitcnt lgkmcnt(0)
	s_waitcnt lgkmcnt(0)
	v_mfma_f32_16x16x32_bf16 v[124:127], v[152:155], v[168:171], v[124:127]
	v_mfma_f32_16x16x32_bf16 v[120:123], v[160:163], v[168:171], v[120:123]
	v_mfma_f32_16x16x32_bf16 v[112:115], v[152:155], v[176:179], v[112:115]
	v_mfma_f32_16x16x32_bf16 v[104:107], v[160:163], v[176:179], v[104:107]
	v_mfma_f32_16x16x32_bf16 v[96:99], v[152:155], v[184:187], v[96:99]
	v_mfma_f32_16x16x32_bf16 v[88:91], v[160:163], v[184:187], v[88:91]
	v_mfma_f32_16x16x32_bf16 v[80:83], v[152:155], v[192:195], v[80:83]
	v_mfma_f32_16x16x32_bf16 v[72:75], v[160:163], v[192:195], v[72:75]
	v_mfma_f32_16x16x32_bf16 v[124:127], v[156:159], v[172:175], v[124:127]
	v_mfma_f32_16x16x32_bf16 v[120:123], v[164:167], v[172:175], v[120:123]
	v_mfma_f32_16x16x32_bf16 v[112:115], v[156:159], v[180:183], v[112:115]
	v_mfma_f32_16x16x32_bf16 v[104:107], v[164:167], v[180:183], v[104:107]
	v_mfma_f32_16x16x32_bf16 v[96:99], v[156:159], v[188:191], v[96:99]
	v_mfma_f32_16x16x32_bf16 v[88:91], v[164:167], v[188:191], v[88:91]
	v_mfma_f32_16x16x32_bf16 v[80:83], v[156:159], v[196:199], v[80:83]
	v_mfma_f32_16x16x32_bf16 v[72:75], v[164:167], v[196:199], v[72:75]
	s_setprio 0
	s_barrier
	s_add_i32 s54, s45, s30
	s_mov_b32 m0, s54
	ds_read_b128 v[202:205], v151
	ds_read_b128 v[206:209], v151 offset:1024
	ds_read_b128 v[210:213], v151 offset:2048
	ds_read_b128 v[214:217], v151 offset:3072
	global_load_lds_dwordx4 v130, s[24:25]
	s_add_i32 m0, s54, 0x2000
	s_nop 0
	global_load_lds_dwordx4 v134, s[24:25]
	s_waitcnt vmcnt(8)
	s_setprio 1
	s_barrier
; #define PG8_STAGE(bufoff, gbase, voff) do { _Pragma("unroll") for (int _i = 0; _i < 2; ++_i) \
;         __builtin_amdgcn_global_load_lds((const unsigned*)((const char*)(gbase) + (voff)[_i]), (LAS unsigned*)(lds + (bufoff) + ldsw + _i * 8192), 16, 0, 0); } while (0)
; #define PG8_LDA(dst, b, h) do { _Pragma("unroll") for (int m = 0; m < 4; ++m) _Pragma("unroll") for (int k = 0; k < 2; ++k) dst[m][k] = *(const LAS bf16x8*)(lds + PG8_SA(b, h) + aoff + m * 2048 + k * 1024); } while (0)
; #define PG8_LDB(dst, b, h) do { _Pragma("unroll") for (int n = 0; n < 2; ++n) _Pragma("unroll") for (int k = 0; k < 2; ++k) dst[n][k] = *(const LAS bf16x8*)(lds + PG8_SB(b, h) + boff + n * 2048 + k * 1024); } while (0)
; #define PG8_WAIT_V(n) asm volatile("s_waitcnt vmcnt(" #n ")" ::: "memory")
; #define PG8_WAIT_L(n) asm volatile("s_waitcnt lgkmcnt(" #n ")" ::: "memory")
; #define PG8_BAR __builtin_amdgcn_s_barrier()
; #define PG8_SCHED __builtin_amdgcn_sched_barrier(0)
; template <class Epi, class Sched>
; __device__ __forceinline__ void gemm_phase(LAS unsigned char* lds, const Gemm g, const Sched& S, const Epi& E) {
;     ...
;             PG8_LDB(B0, 0, 0); PG8_SCHED; PG8_LDA(At, 0, 0); PG8_STAGE(PG8_SA(1, 1), a1 + hstep, voffA);
;             PG8_WAIT_L(8); PG8_BAR; PG8_WAIT_L(0); PG8_MMA(0, 0, At, B0); PG8_BAR; PG8_SCHED;
;             PG8_LDB(B1, 0, 1); PG8_STAGE(PG8_SB(0, 0), b2, voffB);
;             PG8_BAR; PG8_WAIT_L(0); PG8_MMA(0, 1, At, B1); PG8_BAR;
;             PG8_LDA(At, 0, 1); PG8_STAGE(PG8_SA(0, 0), a2, voffA);
;             PG8_BAR; PG8_WAIT_L(0); PG8_MMA(1, 0, At, B0); PG8_BAR; PG8_SCHED;
;             PG8_STAGE(PG8_SB(0, 1), b2 + hstep, voffB);
;             PG8_WAIT_V(6); PG8_BAR; PG8_MMA(1, 1, At, B1); PG8_BAR;
;             PG8_LDB(B0, 1, 0); PG8_SCHED; PG8_LDA(At, 1, 0); PG8_STAGE(PG8_SA(0, 1), a2 + hstep, voffA);
;             PG8_WAIT_L(8); PG8_BAR; PG8_WAIT_L(0); PG8_MMA(0, 0, At, B0); PG8_BAR; PG8_SCHED;
;             PG8_LDB(B1, 1, 1); PG8_STAGE(PG8_SB(1, 0), b3, voffB);
;             PG8_BAR; PG8_WAIT_L(0); PG8_MMA(0, 1, At, B1); PG8_BAR;
;             PG8_LDA(At, 1, 1); PG8_STAGE(PG8_SA(1, 0), a3, voffA);
;             PG8_BAR; PG8_WAIT_L(0); PG8_MMA(1, 0, At, B0); PG8_BAR; PG8_SCHED;
;             PG8_STAGE(PG8_SB(1, 1), b3 + hstep, voffB);
;             PG8_WAIT_V(6); PG8_BAR; PG8_MMA(1, 1, At, B1); PG8_BAR;
	s_waitcnt lgkmcnt(0)
	s_waitcnt lgkmcnt(0)
	v_mfma_f32_16x16x32_bf16 v[116:119], v[202:205], v[168:171], v[116:119]
	v_mfma_f32_16x16x32_bf16 v[108:111], v[210:213], v[168:171], v[108:111]
	v_mfma_f32_16x16x32_bf16 v[100:103], v[202:205], v[176:179], v[100:103]
	v_mfma_f32_16x16x32_bf16 v[92:95], v[210:213], v[176:179], v[92:95]
	v_mfma_f32_16x16x32_bf16 v[84:87], v[202:205], v[184:187], v[84:87]
	v_mfma_f32_16x16x32_bf16 v[76:79], v[210:213], v[184:187], v[76:79]
	v_mfma_f32_16x16x32_bf16 v[68:71], v[202:205], v[192:195], v[68:71]
	v_mfma_f32_16x16x32_bf16 v[64:67], v[210:213], v[192:195], v[64:67]
	v_mfma_f32_16x16x32_bf16 v[116:119], v[206:209], v[172:175], v[116:119]
	v_mfma_f32_16x16x32_bf16 v[108:111], v[214:217], v[172:175], v[108:111]
	v_mfma_f32_16x16x32_bf16 v[100:103], v[206:209], v[180:183], v[100:103]
	v_mfma_f32_16x16x32_bf16 v[92:95], v[214:217], v[180:183], v[92:95]
	v_mfma_f32_16x16x32_bf16 v[84:87], v[206:209], v[188:191], v[84:87]
	v_mfma_f32_16x16x32_bf16 v[76:79], v[214:217], v[188:191], v[76:79]
	v_mfma_f32_16x16x32_bf16 v[68:71], v[206:209], v[196:199], v[68:71]
	v_mfma_f32_16x16x32_bf16 v[64:67], v[214:217], v[196:199], v[64:67]
	s_setprio 0
	s_mov_b32 m0, s21
	v_lshl_add_u64 v[222:223], s[26:27], 0, v[128:129]
	s_barrier
	ds_read_b128 v[168:171], v150 offset:16384
	ds_read_b128 v[172:175], v150 offset:17408
	ds_read_b128 v[176:179], v150 offset:18432
	ds_read_b128 v[180:183], v150 offset:19456
	ds_read_b128 v[184:187], v150 offset:20480
	ds_read_b128 v[188:191], v150 offset:21504
	ds_read_b128 v[192:195], v150 offset:22528
	ds_read_b128 v[196:199], v150 offset:23552
	global_load_lds_dwordx4 v128, s[26:27]
	v_lshl_add_u64 v[224:225], s[26:27], 0, v[132:133]
	s_mov_b32 m0, s31
	s_nop 0
	global_load_lds_dwordx4 v132, s[26:27]
	s_setprio 1
	s_barrier
	s_waitcnt lgkmcnt(0)
	s_waitcnt lgkmcnt(0)
	v_mfma_f32_16x16x32_bf16 v[60:63], v[152:155], v[168:171], v[60:63]
	v_mfma_f32_16x16x32_bf16 v[56:59], v[160:163], v[168:171], v[56:59]
	v_mfma_f32_16x16x32_bf16 v[48:51], v[152:155], v[176:179], v[48:51]
	v_mfma_f32_16x16x32_bf16 v[40:43], v[160:163], v[176:179], v[40:43]
	v_mfma_f32_16x16x32_bf16 v[32:35], v[152:155], v[184:187], v[32:35]
	v_mfma_f32_16x16x32_bf16 v[24:27], v[160:163], v[184:187], v[24:27]
	v_mfma_f32_16x16x32_bf16 v[16:19], v[152:155], v[192:195], v[16:19]
	v_mfma_f32_16x16x32_bf16 v[8:11], v[160:163], v[192:195], v[8:11]
	v_mfma_f32_16x16x32_bf16 v[60:63], v[156:159], v[172:175], v[60:63]
	v_mfma_f32_16x16x32_bf16 v[56:59], v[164:167], v[172:175], v[56:59]
	v_mfma_f32_16x16x32_bf16 v[48:51], v[156:159], v[180:183], v[48:51]
	v_mfma_f32_16x16x32_bf16 v[40:43], v[164:167], v[180:183], v[40:43]
	v_mfma_f32_16x16x32_bf16 v[32:35], v[156:159], v[188:191], v[32:35]
	v_mfma_f32_16x16x32_bf16 v[24:27], v[164:167], v[188:191], v[24:27]
	v_mfma_f32_16x16x32_bf16 v[16:19], v[156:159], v[196:199], v[16:19]
	v_mfma_f32_16x16x32_bf16 v[8:11], v[164:167], v[196:199], v[8:11]
	s_setprio 0
	s_barrier
	s_add_u32 s54, s24, 0x40000
	s_addc_u32 s55, s25, 0
	s_add_i32 s56, s46, s30
	s_mov_b32 m0, s56
	s_nop 0
	global_load_lds_dwordx4 v130, s[54:55]
	s_add_i32 m0, s56, 0x2000
	s_nop 0
	global_load_lds_dwordx4 v134, s[54:55]
	s_add_u32 s26, s26, 0x40000
	s_addc_u32 s27, s27, 0
	s_mov_b32 m0, s33
	s_nop 0
	global_load_lds_dwordx4 v128, s[26:27]
	s_mov_b32 m0, s34
	s_nop 0
	global_load_lds_dwordx4 v132, s[26:27]
	s_waitcnt vmcnt(10)
	s_setprio 1
	s_barrier
	v_mfma_f32_16x16x32_bf16 v[52:55], v[202:205], v[168:171], v[52:55]
	v_mfma_f32_16x16x32_bf16 v[44:47], v[210:213], v[168:171], v[44:47]
	v_mfma_f32_16x16x32_bf16 v[36:39], v[202:205], v[176:179], v[36:39]
	v_mfma_f32_16x16x32_bf16 v[28:31], v[210:213], v[176:179], v[28:31]
	v_mfma_f32_16x16x32_bf16 v[20:23], v[202:205], v[184:187], v[20:23]
	v_mfma_f32_16x16x32_bf16 v[12:15], v[210:213], v[184:187], v[12:15]
	v_mfma_f32_16x16x32_bf16 v[4:7], v[202:205], v[192:195], v[4:7]
	v_mfma_f32_16x16x32_bf16 v[0:3], v[210:213], v[192:195], v[0:3]
	v_mfma_f32_16x16x32_bf16 v[52:55], v[206:209], v[172:175], v[52:55]
	v_mfma_f32_16x16x32_bf16 v[44:47], v[214:217], v[172:175], v[44:47]
	v_mfma_f32_16x16x32_bf16 v[36:39], v[206:209], v[180:183], v[36:39]
	v_mfma_f32_16x16x32_bf16 v[28:31], v[214:217], v[180:183], v[28:31]
	v_mfma_f32_16x16x32_bf16 v[20:23], v[206:209], v[188:191], v[20:23]
	v_mfma_f32_16x16x32_bf16 v[12:15], v[214:217], v[188:191], v[12:15]
	v_mfma_f32_16x16x32_bf16 v[4:7], v[206:209], v[196:199], v[4:7]
	v_mfma_f32_16x16x32_bf16 v[0:3], v[214:217], v[196:199], v[0:3]
	s_setprio 0
	s_add_i32 s54, 0, 0x18000
	v_add_u32_e32 v136, s54, v148
	s_barrier
	ds_read_b128 v[152:155], v136
	ds_read_b128 v[156:159], v136 offset:1024
	ds_read_b128 v[160:163], v136 offset:2048
	ds_read_b128 v[164:167], v136 offset:3072
	ds_read_b128 v[168:171], v150 offset:32768
	ds_read_b128 v[172:175], v150 offset:33792
	ds_read_b128 v[176:179], v150 offset:34816
	ds_read_b128 v[180:183], v150 offset:35840
	ds_read_b128 v[184:187], v150 offset:36864
	ds_read_b128 v[188:191], v150 offset:37888
	ds_read_b128 v[192:195], v150 offset:38912
	ds_read_b128 v[196:199], v150 offset:39936
	s_waitcnt lgkmcnt(8)
	s_waitcnt vmcnt(8)
	s_setprio 1
	s_barrier
; #define PG8_STAGE(bufoff, gbase, voff) do { _Pragma("unroll") for (int _i = 0; _i < 2; ++_i) \
;         __builtin_amdgcn_global_load_lds((const unsigned*)((const char*)(gbase) + (voff)[_i]), (LAS unsigned*)(lds + (bufoff) + ldsw + _i * 8192), 16, 0, 0); } while (0)
; #define PG8_LDA(dst, b, h) do { _Pragma("unroll") for (int m = 0; m < 4; ++m) _Pragma("unroll") for (int k = 0; k < 2; ++k) dst[m][k] = *(const LAS bf16x8*)(lds + PG8_SA(b, h) + aoff + m * 2048 + k * 1024); } while (0)
; #define PG8_LDB(dst, b, h) do { _Pragma("unroll") for (int n = 0; n < 2; ++n) _Pragma("unroll") for (int k = 0; k < 2; ++k) dst[n][k] = *(const LAS bf16x8*)(lds + PG8_SB(b, h) + boff + n * 2048 + k * 1024); } while (0)
; #define PG8_WAIT_V(n) asm volatile("s_waitcnt vmcnt(" #n ")" ::: "memory")
; #define PG8_WAIT_L(n) asm volatile("s_waitcnt lgkmcnt(" #n ")" ::: "memory")
; #define PG8_BAR __builtin_amdgcn_s_barrier()
; #define PG8_SCHED __builtin_amdgcn_sched_barrier(0)
; template <class Epi, class Sched>
; __device__ __forceinline__ void gemm_phase(LAS unsigned char* lds, const Gemm g, const Sched& S, const Epi& E) {
;     ...
;             PG8_LDB(B0, 0, 0); PG8_SCHED; PG8_LDA(At, 0, 0); PG8_STAGE(PG8_SA(1, 1), a1 + hstep, voffA);
;             PG8_WAIT_L(8); PG8_BAR; PG8_WAIT_L(0); PG8_MMA(0, 0, At, B0); PG8_BAR; PG8_SCHED;
;             PG8_LDB(B1, 0, 1); PG8_STAGE(PG8_SB(0, 0), b2, voffB);
;             PG8_BAR; PG8_WAIT_L(0); PG8_MMA(0, 1, At, B1); PG8_BAR;
;             PG8_LDA(At, 0, 1); PG8_STAGE(PG8_SA(0, 0), a2, voffA);
;             PG8_BAR; PG8_WAIT_L(0); PG8_MMA(1, 0, At, B0); PG8_BAR; PG8_SCHED;
;             PG8_STAGE(PG8_SB(0, 1), b2 + hstep, voffB);
;             PG8_WAIT_V(6); PG8_BAR; PG8_MMA(1, 1, At, B1); PG8_BAR;
;             PG8_LDB(B0, 1, 0); PG8_SCHED; PG8_LDA(At, 1, 0); PG8_STAGE(PG8_SA(0, 1), a2 + hstep, voffA);
;             PG8_WAIT_L(8); PG8_BAR; PG8_WAIT_L(0); PG8_MMA(0, 0, At, B0); PG8_BAR; PG8_SCHED;
;             PG8_LDB(B1, 1, 1); PG8_STAGE(PG8_SB(1, 0), b3, voffB);
;             PG8_BAR; PG8_WAIT_L(0); PG8_MMA(0, 1, At, B1); PG8_BAR;
;             PG8_LDA(At, 1, 1); PG8_STAGE(PG8_SA(1, 0), a3, voffA);
;             PG8_BAR; PG8_WAIT_L(0); PG8_MMA(1, 0, At, B0); PG8_BAR; PG8_SCHED;
;             PG8_STAGE(PG8_SB(1, 1), b3 + hstep, voffB);
;             PG8_WAIT_V(6); PG8_BAR; PG8_MMA(1, 1, At, B1); PG8_BAR;
	s_waitcnt lgkmcnt(0)
	s_waitcnt lgkmcnt(0)
	v_mfma_f32_16x16x32_bf16 v[124:127], v[152:155], v[168:171], v[124:127]
	v_mfma_f32_16x16x32_bf16 v[120:123], v[160:163], v[168:171], v[120:123]
	v_mfma_f32_16x16x32_bf16 v[112:115], v[152:155], v[176:179], v[112:115]
	v_mfma_f32_16x16x32_bf16 v[104:107], v[160:163], v[176:179], v[104:107]
	v_mfma_f32_16x16x32_bf16 v[96:99], v[152:155], v[184:187], v[96:99]
	v_mfma_f32_16x16x32_bf16 v[88:91], v[160:163], v[184:187], v[88:91]
	v_mfma_f32_16x16x32_bf16 v[80:83], v[152:155], v[192:195], v[80:83]
	v_mfma_f32_16x16x32_bf16 v[72:75], v[160:163], v[192:195], v[72:75]
	v_mfma_f32_16x16x32_bf16 v[124:127], v[156:159], v[172:175], v[124:127]
	v_mfma_f32_16x16x32_bf16 v[120:123], v[164:167], v[172:175], v[120:123]
	v_mfma_f32_16x16x32_bf16 v[112:115], v[156:159], v[180:183], v[112:115]
	v_mfma_f32_16x16x32_bf16 v[104:107], v[164:167], v[180:183], v[104:107]
	v_mfma_f32_16x16x32_bf16 v[96:99], v[156:159], v[188:191], v[96:99]
	v_mfma_f32_16x16x32_bf16 v[88:91], v[164:167], v[188:191], v[88:91]
	v_mfma_f32_16x16x32_bf16 v[80:83], v[156:159], v[196:199], v[80:83]
	v_mfma_f32_16x16x32_bf16 v[72:75], v[164:167], v[196:199], v[72:75]
	s_setprio 0
	s_barrier
	s_add_i32 s26, 0, 0x1c000
	s_add_i32 s27, s54, s30
	v_add_u32_e32 v136, s26, v148
	s_add_u32 s0, s24, 0x80
	s_addc_u32 s1, s25, 0
	s_mov_b32 m0, s27
	ds_read_b128 v[202:205], v136
	ds_read_b128 v[206:209], v136 offset:1024
	ds_read_b128 v[210:213], v136 offset:2048
	ds_read_b128 v[214:217], v136 offset:3072
	global_load_lds_dwordx4 v130, s[0:1]
	s_add_i32 m0, s27, 0x2000
	s_nop 0
	global_load_lds_dwordx4 v134, s[0:1]
	s_waitcnt vmcnt(8)
	s_setprio 1
	s_barrier
	s_waitcnt lgkmcnt(0)
	s_waitcnt lgkmcnt(0)
	v_mfma_f32_16x16x32_bf16 v[116:119], v[202:205], v[168:171], v[116:119]
	v_mfma_f32_16x16x32_bf16 v[108:111], v[210:213], v[168:171], v[108:111]
	v_mfma_f32_16x16x32_bf16 v[100:103], v[202:205], v[176:179], v[100:103]
	v_mfma_f32_16x16x32_bf16 v[92:95], v[210:213], v[176:179], v[92:95]
	v_mfma_f32_16x16x32_bf16 v[84:87], v[202:205], v[184:187], v[84:87]
	v_mfma_f32_16x16x32_bf16 v[76:79], v[210:213], v[184:187], v[76:79]
	v_mfma_f32_16x16x32_bf16 v[68:71], v[202:205], v[192:195], v[68:71]
	v_mfma_f32_16x16x32_bf16 v[64:67], v[210:213], v[192:195], v[64:67]
	v_mfma_f32_16x16x32_bf16 v[116:119], v[206:209], v[172:175], v[116:119]
	v_mfma_f32_16x16x32_bf16 v[108:111], v[214:217], v[172:175], v[108:111]
	v_mfma_f32_16x16x32_bf16 v[100:103], v[206:209], v[180:183], v[100:103]
	v_mfma_f32_16x16x32_bf16 v[92:95], v[214:217], v[180:183], v[92:95]
	v_mfma_f32_16x16x32_bf16 v[84:87], v[206:209], v[188:191], v[84:87]
	v_mfma_f32_16x16x32_bf16 v[76:79], v[214:217], v[188:191], v[76:79]
	v_mfma_f32_16x16x32_bf16 v[68:71], v[206:209], v[196:199], v[68:71]
	v_mfma_f32_16x16x32_bf16 v[64:67], v[214:217], v[196:199], v[64:67]
	s_setprio 0
	s_mov_b32 m0, s42
	s_mov_b64 s[0:1], 0x80
	v_lshl_add_u64 v[218:219], v[222:223], 0, s[0:1]
	s_barrier
	ds_read_b128 v[168:171], v150 offset:49152
	ds_read_b128 v[172:175], v150 offset:50176
	ds_read_b128 v[176:179], v150 offset:51200
	ds_read_b128 v[180:183], v150 offset:52224
	ds_read_b128 v[184:187], v150 offset:53248
	ds_read_b128 v[188:191], v150 offset:54272
	ds_read_b128 v[192:195], v150 offset:55296
	ds_read_b128 v[196:199], v150 offset:56320
	global_load_lds_dwordx4 v[218:219], off
	v_lshl_add_u64 v[218:219], v[224:225], 0, s[0:1]
	s_mov_b32 m0, s43
	s_nop 0
	global_load_lds_dwordx4 v[218:219], off
	s_setprio 1
	s_barrier
	s_waitcnt lgkmcnt(0)
	s_waitcnt lgkmcnt(0)
	v_mfma_f32_16x16x32_bf16 v[60:63], v[152:155], v[168:171], v[60:63]
	v_mfma_f32_16x16x32_bf16 v[56:59], v[160:163], v[168:171], v[56:59]
	v_mfma_f32_16x16x32_bf16 v[48:51], v[152:155], v[176:179], v[48:51]
	v_mfma_f32_16x16x32_bf16 v[40:43], v[160:163], v[176:179], v[40:43]
	v_mfma_f32_16x16x32_bf16 v[32:35], v[152:155], v[184:187], v[32:35]
	v_mfma_f32_16x16x32_bf16 v[24:27], v[160:163], v[184:187], v[24:27]
	v_mfma_f32_16x16x32_bf16 v[16:19], v[152:155], v[192:195], v[16:19]
	v_mfma_f32_16x16x32_bf16 v[8:11], v[160:163], v[192:195], v[8:11]
	v_mfma_f32_16x16x32_bf16 v[60:63], v[156:159], v[172:175], v[60:63]
	v_mfma_f32_16x16x32_bf16 v[56:59], v[164:167], v[172:175], v[56:59]
	v_mfma_f32_16x16x32_bf16 v[48:51], v[156:159], v[180:183], v[48:51]
	v_mfma_f32_16x16x32_bf16 v[40:43], v[164:167], v[180:183], v[40:43]
	v_mfma_f32_16x16x32_bf16 v[32:35], v[156:159], v[188:191], v[32:35]
	v_mfma_f32_16x16x32_bf16 v[24:27], v[164:167], v[188:191], v[24:27]
	v_mfma_f32_16x16x32_bf16 v[16:19], v[156:159], v[196:199], v[16:19]
	v_mfma_f32_16x16x32_bf16 v[8:11], v[164:167], v[196:199], v[8:11]
	s_setprio 0
	s_barrier
	s_add_u32 s24, s24, 0x40080
	s_addc_u32 s25, s25, 0
	s_add_i32 s26, s26, s30
	s_mov_b32 m0, s26
	s_nop 0
	global_load_lds_dwordx4 v130, s[24:25]
	s_add_i32 m0, s26, 0x2000
	s_nop 0
	global_load_lds_dwordx4 v134, s[24:25]
	s_waitcnt vmcnt(8)
	s_setprio 1
	s_barrier
	v_mfma_f32_16x16x32_bf16 v[52:55], v[202:205], v[168:171], v[52:55]
	v_mfma_f32_16x16x32_bf16 v[44:47], v[210:213], v[168:171], v[44:47]
	v_mfma_f32_16x16x32_bf16 v[36:39], v[202:205], v[176:179], v[36:39]
	v_mfma_f32_16x16x32_bf16 v[28:31], v[210:213], v[176:179], v[28:31]
	v_mfma_f32_16x16x32_bf16 v[20:23], v[202:205], v[184:187], v[20:23]
	v_mfma_f32_16x16x32_bf16 v[12:15], v[210:213], v[184:187], v[12:15]
	v_mfma_f32_16x16x32_bf16 v[4:7], v[202:205], v[192:195], v[4:7]
	v_mfma_f32_16x16x32_bf16 v[0:3], v[210:213], v[192:195], v[0:3]
	v_mfma_f32_16x16x32_bf16 v[52:55], v[206:209], v[172:175], v[52:55]
	v_mfma_f32_16x16x32_bf16 v[44:47], v[214:217], v[172:175], v[44:47]
	v_mfma_f32_16x16x32_bf16 v[36:39], v[206:209], v[180:183], v[36:39]
	v_mfma_f32_16x16x32_bf16 v[28:31], v[214:217], v[180:183], v[28:31]
	v_mfma_f32_16x16x32_bf16 v[20:23], v[206:209], v[188:191], v[20:23]
	v_mfma_f32_16x16x32_bf16 v[12:15], v[214:217], v[188:191], v[12:15]
	v_mfma_f32_16x16x32_bf16 v[4:7], v[206:209], v[196:199], v[4:7]
	v_mfma_f32_16x16x32_bf16 v[0:3], v[214:217], v[196:199], v[0:3]
	s_setprio 0
	s_add_i32 s53, s53, 2
	s_add_u32 s22, s22, 0x100
	s_addc_u32 s23, s23, 0
	s_add_u32 s51, s51, 0x100
	s_addc_u32 s52, s52, 0
	s_cmp_gt_u32 s53, 13
	s_barrier
; __device__ __forceinline__ unsigned cvt_pk_bf16(float lo, float hi) { unsigned r; asm volatile("v_cvt_pk_bf16_f32 %0, %1, %2" : "=v"(r) : "v"(lo), "v"(hi)); return r; }
;     __device__ __forceinline__ void operator()(const AccT& acc, const Unit& u, int wr, int wc, int fr, int fq) const {
;     ...
;         const int rbase = u.pm * 256 + wr * 64 + fr;
;         const int tb = u.pn * 256 + wc * 32 + 8 * fq;
; #pragma unroll
;         for (int ai = 0; ai < 2; ++ai)
; #pragma unroll
;             for (int m = 0; m < 4; ++m) {
;                 const int gm = rbase + ai * 128 + m * 16;
; #pragma unroll
;                 for (int bj = 0; bj < 2; ++bj) {
;                     const int t0 = tb + bj * 128;
;                     const f32x4 v0 = acc[ai][bj][m][0], v1 = acc[ai][bj][m][1];
;                     u32x4 w; w.x = cvt_pk_bf16(v0[0], v0[1]); w.y = cvt_pk_bf16(v0[2], v0[3]); w.z = cvt_pk_bf16(v1[0], v1[1]); w.w = cvt_pk_bf16(v1[2], v1[3]);
;                     *(u32x4*)(YT + ((size_t)((t0 >> 10) * 512 + gm)) * 2048 + part * 1024 + (t0 & 1023)) = w;
;                 }
;             }
	s_cbranch_scc0 .LBB0_653
	v_mov_b32_e32 v136, v147
	v_mov_b32_e32 v152, v146
	s_lshl_b32 s7, s20, 8
	s_add_i32 s7, s7, s36
	v_add_u32_e32 v152, s7, v152
	s_lshl_b32 s7, s47, 8
	s_or_b32 s7, s7, s37
	v_lshl_add_u32 v153, v136, 3, s7
	v_cvt_pk_bf16_f32 v124, v124, v125
	v_cvt_pk_bf16_f32 v125, v126, v127
	v_cvt_pk_bf16_f32 v126, v120, v121
	v_ashrrev_i32_e32 v120, 1, v153
	v_cvt_pk_bf16_f32 v127, v122, v123
	v_and_b32_e32 v122, 0xfffffe00, v120
	v_add_u32_e32 v120, v122, v152
	v_ashrrev_i32_e32 v121, 31, v120
	v_lshlrev_b64 v[120:121], 12, v[120:121]
	v_and_b32_e32 v123, 0x3f8, v153
	v_lshl_add_u64 v[120:121], s[68:69], 0, v[120:121]
	v_lshlrev_b32_e32 v136, 1, v123
	v_lshl_add_u64 v[120:121], v[120:121], 0, v[136:137]
	global_store_dwordx4 v[120:121], v[124:127], off
	v_add_u32_e32 v120, 0x80, v153
	v_cvt_pk_bf16_f32 v116, v116, v117
	v_cvt_pk_bf16_f32 v117, v118, v119
	v_cvt_pk_bf16_f32 v118, v108, v109
	v_ashrrev_i32_e32 v108, 1, v120
	v_and_b32_e32 v121, 0xfffffe00, v108
	v_add_u32_e32 v108, v121, v152
	v_ashrrev_i32_e32 v109, 31, v108
	v_lshlrev_b64 v[108:109], 12, v[108:109]
	v_cvt_pk_bf16_f32 v119, v110, v111
	v_lshl_add_u64 v[110:111], s[68:69], 0, v[108:109]
	v_and_b32_e32 v108, 0x3f8, v120
	v_lshlrev_b32_e32 v108, 1, v108
	v_mov_b32_e32 v109, v137
	v_lshl_add_u64 v[110:111], v[110:111], 0, v[108:109]
	global_store_dwordx4 v[110:111], v[116:119], off
	v_cvt_pk_bf16_f32 v110, v112, v113
	v_cvt_pk_bf16_f32 v111, v114, v115
	v_cvt_pk_bf16_f32 v112, v104, v105
	v_cvt_pk_bf16_f32 v113, v106, v107
	s_and_b64 vcc, exec, s[4:5]
	s_nop 0
	v_add_u32_e32 v116, 16, v152
	v_add_u32_e32 v104, v122, v116
	v_ashrrev_i32_e32 v105, 31, v104
	v_lshlrev_b64 v[104:105], 12, v[104:105]
	v_lshl_add_u64 v[104:105], s[68:69], 0, v[104:105]
	v_lshl_add_u64 v[104:105], v[104:105], 0, v[136:137]
	global_store_dwordx4 v[104:105], v[110:113], off
	v_cvt_pk_bf16_f32 v100, v100, v101
	v_cvt_pk_bf16_f32 v101, v102, v103
	v_cvt_pk_bf16_f32 v102, v92, v93
	v_add_u32_e32 v92, v121, v116
	v_ashrrev_i32_e32 v93, 31, v92
	v_lshlrev_b64 v[92:93], 12, v[92:93]
	v_lshl_add_u64 v[92:93], s[68:69], 0, v[92:93]
	v_lshl_add_u64 v[92:93], v[92:93], 0, v[108:109]
	v_cvt_pk_bf16_f32 v103, v94, v95
	global_store_dwordx4 v[92:93], v[100:103], off
	v_cvt_pk_bf16_f32 v92, v96, v97
	v_cvt_pk_bf16_f32 v93, v98, v99
	v_cvt_pk_bf16_f32 v94, v88, v89
	v_cvt_pk_bf16_f32 v95, v90, v91
	s_mov_b32 s47, s6
	s_nop 0
	v_add_u32_e32 v100, 32, v152
	v_add_u32_e32 v88, v122, v100
	v_ashrrev_i32_e32 v89, 31, v88
	v_lshlrev_b64 v[88:89], 12, v[88:89]
	v_lshl_add_u64 v[88:89], s[68:69], 0, v[88:89]
	v_lshl_add_u64 v[88:89], v[88:89], 0, v[136:137]
	global_store_dwordx4 v[88:89], v[92:95], off
	v_cvt_pk_bf16_f32 v84, v84, v85
	v_cvt_pk_bf16_f32 v85, v86, v87
	v_cvt_pk_bf16_f32 v86, v76, v77
	v_add_u32_e32 v76, v121, v100
	v_ashrrev_i32_e32 v77, 31, v76
	v_lshlrev_b64 v[76:77], 12, v[76:77]
	v_lshl_add_u64 v[76:77], s[68:69], 0, v[76:77]
	v_lshl_add_u64 v[76:77], v[76:77], 0, v[108:109]
	v_cvt_pk_bf16_f32 v87, v78, v79
	global_store_dwordx4 v[76:77], v[84:87], off
	v_cvt_pk_bf16_f32 v76, v80, v81
	v_cvt_pk_bf16_f32 v77, v82, v83
	v_cvt_pk_bf16_f32 v78, v72, v73
	v_cvt_pk_bf16_f32 v79, v74, v75
	s_mov_b32 s20, s8
	s_nop 0
	v_add_u32_e32 v84, 48, v152
	v_add_u32_e32 v72, v122, v84
	v_ashrrev_i32_e32 v73, 31, v72
	v_lshlrev_b64 v[72:73], 12, v[72:73]
	v_lshl_add_u64 v[72:73], s[68:69], 0, v[72:73]
	v_lshl_add_u64 v[72:73], v[72:73], 0, v[136:137]
	global_store_dwordx4 v[72:73], v[76:79], off
	v_cvt_pk_bf16_f32 v68, v68, v69
	v_cvt_pk_bf16_f32 v69, v70, v71
; __device__ __forceinline__ unsigned cvt_pk_bf16(float lo, float hi) { unsigned r; asm volatile("v_cvt_pk_bf16_f32 %0, %1, %2" : "=v"(r) : "v"(lo), "v"(hi)); return r; }
; #define PG8_WAIT_V(n) asm volatile("s_waitcnt vmcnt(" #n ")" ::: "memory")
; #define PG8_BAR __builtin_amdgcn_s_barrier()
; template <class Epi, class Sched>
; __device__ __forceinline__ void gemm_phase(LAS unsigned char* lds, const Gemm g, const Sched& S, const Epi& E) {
;     ...
;     PG8_WAIT_V(0);
;     if (wr == 0) PG8_BAR;
;     PG8_BAR;
;     __device__ __forceinline__ void operator()(const AccT& acc, const Unit& u, int wr, int wc, int fr, int fq) const {
;     ...
;                 const int gm = rbase + ai * 128 + m * 16;
; #pragma unroll
;                 for (int bj = 0; bj < 2; ++bj) {
;                     const int t0 = tb + bj * 128;
;                     const f32x4 v0 = acc[ai][bj][m][0], v1 = acc[ai][bj][m][1];
;                     u32x4 w; w.x = cvt_pk_bf16(v0[0], v0[1]); w.y = cvt_pk_bf16(v0[2], v0[3]); w.z = cvt_pk_bf16(v1[0], v1[1]); w.w = cvt_pk_bf16(v1[2], v1[3]);
;                     *(u32x4*)(YT + ((size_t)((t0 >> 10) * 512 + gm)) * 2048 + part * 1024 + (t0 & 1023)) = w;
;                 }
;             }
	v_cvt_pk_bf16_f32 v70, v64, v65
	v_add_u32_e32 v64, v121, v84
	v_ashrrev_i32_e32 v65, 31, v64
	v_lshlrev_b64 v[64:65], 12, v[64:65]
	v_lshl_add_u64 v[64:65], s[68:69], 0, v[64:65]
	v_lshl_add_u64 v[64:65], v[64:65], 0, v[108:109]
	v_cvt_pk_bf16_f32 v71, v66, v67
	global_store_dwordx4 v[64:65], v[68:71], off
	v_add_u32_e32 v64, 0x80, v152
	v_cvt_pk_bf16_f32 v60, v60, v61
	v_cvt_pk_bf16_f32 v61, v62, v63
	v_cvt_pk_bf16_f32 v62, v56, v57
	v_add_u32_e32 v56, v122, v64
	v_ashrrev_i32_e32 v57, 31, v56
	v_lshlrev_b64 v[56:57], 12, v[56:57]
	v_lshl_add_u64 v[56:57], s[68:69], 0, v[56:57]
	v_lshl_add_u64 v[56:57], v[56:57], 0, v[136:137]
	v_cvt_pk_bf16_f32 v63, v58, v59
	global_store_dwordx4 v[56:57], v[60:63], off
	v_cvt_pk_bf16_f32 v52, v52, v53
	v_cvt_pk_bf16_f32 v53, v54, v55
	v_cvt_pk_bf16_f32 v54, v44, v45
	v_add_u32_e32 v44, v121, v64
	v_ashrrev_i32_e32 v45, 31, v44
	v_lshlrev_b64 v[44:45], 12, v[44:45]
	v_lshl_add_u64 v[44:45], s[68:69], 0, v[44:45]
	v_lshl_add_u64 v[44:45], v[44:45], 0, v[108:109]
	v_cvt_pk_bf16_f32 v55, v46, v47
	global_store_dwordx4 v[44:45], v[52:55], off
	v_cvt_pk_bf16_f32 v44, v48, v49
	v_cvt_pk_bf16_f32 v45, v50, v51
	v_cvt_pk_bf16_f32 v46, v40, v41
	v_cvt_pk_bf16_f32 v47, v42, v43
	s_mov_b64 s[24:25], s[18:19]
	s_nop 0
	v_add_u32_e32 v52, 0x90, v152
	v_add_u32_e32 v40, v122, v52
	v_ashrrev_i32_e32 v41, 31, v40
	v_lshlrev_b64 v[40:41], 12, v[40:41]
	v_lshl_add_u64 v[40:41], s[68:69], 0, v[40:41]
	v_lshl_add_u64 v[40:41], v[40:41], 0, v[136:137]
	global_store_dwordx4 v[40:41], v[44:47], off
	v_cvt_pk_bf16_f32 v36, v36, v37
	v_cvt_pk_bf16_f32 v37, v38, v39
	v_cvt_pk_bf16_f32 v38, v28, v29
	v_add_u32_e32 v28, v121, v52
	v_ashrrev_i32_e32 v29, 31, v28
	v_lshlrev_b64 v[28:29], 12, v[28:29]
	v_lshl_add_u64 v[28:29], s[68:69], 0, v[28:29]
	v_lshl_add_u64 v[28:29], v[28:29], 0, v[108:109]
	v_cvt_pk_bf16_f32 v39, v30, v31
	global_store_dwordx4 v[28:29], v[36:39], off
	v_cvt_pk_bf16_f32 v28, v32, v33
	v_cvt_pk_bf16_f32 v29, v34, v35
	v_cvt_pk_bf16_f32 v30, v24, v25
	v_cvt_pk_bf16_f32 v31, v26, v27
	s_mov_b64 s[22:23], s[16:17]
	s_nop 0
	v_add_u32_e32 v36, 0xa0, v152
	v_add_u32_e32 v24, v122, v36
	v_ashrrev_i32_e32 v25, 31, v24
	v_lshlrev_b64 v[24:25], 12, v[24:25]
	v_lshl_add_u64 v[24:25], s[68:69], 0, v[24:25]
	v_lshl_add_u64 v[24:25], v[24:25], 0, v[136:137]
	global_store_dwordx4 v[24:25], v[28:31], off
	v_cvt_pk_bf16_f32 v20, v20, v21
	v_cvt_pk_bf16_f32 v21, v22, v23
	v_cvt_pk_bf16_f32 v22, v12, v13
	v_add_u32_e32 v12, v121, v36
	v_ashrrev_i32_e32 v13, 31, v12
	v_lshlrev_b64 v[12:13], 12, v[12:13]
	v_lshl_add_u64 v[12:13], s[68:69], 0, v[12:13]
	v_lshl_add_u64 v[12:13], v[12:13], 0, v[108:109]
	v_cvt_pk_bf16_f32 v23, v14, v15
	global_store_dwordx4 v[12:13], v[20:23], off
	v_cvt_pk_bf16_f32 v12, v16, v17
	v_cvt_pk_bf16_f32 v13, v18, v19
	v_cvt_pk_bf16_f32 v14, v8, v9
	v_cvt_pk_bf16_f32 v15, v10, v11
	s_nop 1
	v_add_u32_e32 v20, 0xb0, v152
	v_add_u32_e32 v8, v122, v20
	v_ashrrev_i32_e32 v9, 31, v8
	v_lshlrev_b64 v[8:9], 12, v[8:9]
	v_lshl_add_u64 v[8:9], s[68:69], 0, v[8:9]
	v_lshl_add_u64 v[8:9], v[8:9], 0, v[136:137]
	global_store_dwordx4 v[8:9], v[12:15], off
	v_cvt_pk_bf16_f32 v4, v4, v5
	v_cvt_pk_bf16_f32 v5, v6, v7
	v_cvt_pk_bf16_f32 v6, v0, v1
	v_add_u32_e32 v0, v121, v20
	v_ashrrev_i32_e32 v1, 31, v0
	v_lshlrev_b64 v[0:1], 12, v[0:1]
	v_lshl_add_u64 v[0:1], s[68:69], 0, v[0:1]
	v_lshl_add_u64 v[0:1], v[0:1], 0, v[108:109]
	v_cvt_pk_bf16_f32 v7, v2, v3
	global_store_dwordx4 v[0:1], v[4:7], off
	s_cbranch_vccz .LBB0_646
	s_waitcnt vmcnt(0)
	s_cmpk_gt_u32 s28, 0xff
	s_cbranch_scc1 .LBB0_657
	s_barrier

; #define PG8_STAGE(bufoff, gbase, voff) do { _Pragma("unroll") for (int _i = 0; _i < 2; ++_i) \
;         __builtin_amdgcn_global_load_lds((const unsigned*)((const char*)(gbase) + (voff)[_i]), (LAS unsigned*)(lds + (bufoff) + ldsw + _i * 8192), 16, 0, 0); } while (0)
; #define PG8_LDA(dst, b, h) do { _Pragma("unroll") for (int m = 0; m < 4; ++m) _Pragma("unroll") for (int k = 0; k < 2; ++k) dst[m][k] = *(const LAS bf16x8*)(lds + PG8_SA(b, h) + aoff + m * 2048 + k * 1024); } while (0)
; #define PG8_LDB(dst, b, h) do { _Pragma("unroll") for (int n = 0; n < 2; ++n) _Pragma("unroll") for (int k = 0; k < 2; ++k) dst[n][k] = *(const LAS bf16x8*)(lds + PG8_SB(b, h) + boff + n * 2048 + k * 1024); } while (0)
; #define PG8_WAIT_V(n) asm volatile("s_waitcnt vmcnt(" #n ")" ::: "memory")
; #define PG8_WAIT_L(n) asm volatile("s_waitcnt lgkmcnt(" #n ")" ::: "memory")
; #define PG8_BAR __builtin_amdgcn_s_barrier()
; #define PG8_SCHED __builtin_amdgcn_sched_barrier(0)
; template <class Epi, class Sched>
; __device__ __forceinline__ void gemm_phase(LAS unsigned char* lds, const Gemm g, const Sched& S, const Epi& E) {
;     ...
;     for (;;) {
;         const bool has_next = S.next(ui + 1, nxt);
;         const char* nA = has_next ? (const char*)g.A + (size_t)nxt.pm * tstep : cA; const char* nB = has_next ? (const char*)g.Bt + (size_t)nxt.pn * tstep : cB;
;         for (int t = 0; t < nt; t += 2) {
;             const bool last = (t == nt - 2);
;             const char* a1 = cA + (size_t)(t + 1) * kstep;
;             const char* a2 = last ? nA : cA + (size_t)(t + 2) * kstep; const char* b2 = last ? nB : cB + (size_t)(t + 2) * kstep;
;             const char* a3 = a2 + kstep; const char* b3 = b2 + kstep;
;             PG8_LDB(B0, 0, 0); PG8_SCHED; PG8_LDA(At, 0, 0); PG8_STAGE(PG8_SA(1, 1), a1 + hstep, voffA);
;             PG8_WAIT_L(8); PG8_BAR; PG8_WAIT_L(0); PG8_MMA(0, 0, At, B0); PG8_BAR; PG8_SCHED;
;             PG8_LDB(B1, 0, 1); PG8_STAGE(PG8_SB(0, 0), b2, voffB);
;             PG8_BAR; PG8_WAIT_L(0); PG8_MMA(0, 1, At, B1); PG8_BAR;
;             PG8_LDA(At, 0, 1); PG8_STAGE(PG8_SA(0, 0), a2, voffA);
;             PG8_BAR; PG8_WAIT_L(0); PG8_MMA(1, 0, At, B0); PG8_BAR; PG8_SCHED;
;             PG8_STAGE(PG8_SB(0, 1), b2 + hstep, voffB);
;             PG8_WAIT_V(6); PG8_BAR; PG8_MMA(1, 1, At, B1); PG8_BAR;
.LBB0_672:
	s_ashr_i32 s9, s8, 31
	v_cmp_lt_i64_e32 vcc, s[12:13], v[142:143]
	s_lshl_b64 s[12:13], s[8:9], 19
	s_add_u32 s12, s26, s12
	s_addc_u32 s13, s27, s13
	s_and_b64 s[14:15], vcc, exec
	s_cselect_b32 s9, s13, s19
	s_cselect_b32 s46, s12, s18
	s_ashr_i32 s7, s6, 31
	s_lshl_b64 s[14:15], s[6:7], 19
	s_add_u32 s14, s10, s14
	s_addc_u32 s15, s11, s15
	s_and_b64 s[22:23], vcc, exec
	s_cselect_b32 s7, s15, s21
	s_cselect_b32 s47, s14, s20
	s_add_u32 s18, s18, 0x40080
	s_addc_u32 s19, s19, 0
	s_add_u32 s48, s20, 0x100
	s_addc_u32 s49, s21, 0
	s_mov_b32 s51, -2
	s_waitcnt lgkmcnt(0)
	ds_read_b128 v[152:155], v149
	ds_read_b128 v[156:159], v149 offset:1024
	ds_read_b128 v[160:163], v149 offset:2048
	ds_read_b128 v[164:167], v149 offset:3072
	s_add_u32 s20, s18, 0xfffc0080
	s_addc_u32 s21, s19, -1
	s_cmp_eq_u32 s51, 12
	s_cselect_b32 s23, s9, s21
	s_cselect_b32 s22, s46, s20
	s_cselect_b32 s21, s7, s49
	s_cselect_b32 s20, s47, s48
	s_add_i32 m0, s17, 0xc000
	ds_read_b128 v[168:171], v150
	ds_read_b128 v[172:175], v150 offset:1024
	ds_read_b128 v[176:179], v150 offset:2048
	ds_read_b128 v[180:183], v150 offset:3072
	ds_read_b128 v[184:187], v150 offset:4096
	ds_read_b128 v[188:191], v150 offset:5120
	ds_read_b128 v[192:195], v150 offset:6144
	ds_read_b128 v[196:199], v150 offset:7168
	global_load_lds_dwordx4 v138, s[18:19]
	s_add_i32 m0, s17, 0xe000
	s_nop 0
	global_load_lds_dwordx4 v140, s[18:19]
	s_waitcnt lgkmcnt(8)
	s_waitcnt vmcnt(8)
	s_setprio 1
	s_barrier
	s_waitcnt lgkmcnt(0)
	s_waitcnt lgkmcnt(0)
	v_mfma_f32_16x16x32_bf16 v[124:127], v[152:155], v[168:171], 0
	v_mfma_f32_16x16x32_bf16 v[120:123], v[160:163], v[168:171], 0
	v_mfma_f32_16x16x32_bf16 v[112:115], v[152:155], v[176:179], 0
	v_mfma_f32_16x16x32_bf16 v[104:107], v[160:163], v[176:179], 0
	v_mfma_f32_16x16x32_bf16 v[96:99], v[152:155], v[184:187], 0
	v_mfma_f32_16x16x32_bf16 v[88:91], v[160:163], v[184:187], 0
	v_mfma_f32_16x16x32_bf16 v[80:83], v[152:155], v[192:195], 0
	v_mfma_f32_16x16x32_bf16 v[72:75], v[160:163], v[192:195], 0
	v_mfma_f32_16x16x32_bf16 v[124:127], v[156:159], v[172:175], v[124:127]
	v_mfma_f32_16x16x32_bf16 v[120:123], v[164:167], v[172:175], v[120:123]
	v_mfma_f32_16x16x32_bf16 v[112:115], v[156:159], v[180:183], v[112:115]
	v_mfma_f32_16x16x32_bf16 v[104:107], v[164:167], v[180:183], v[104:107]
	v_mfma_f32_16x16x32_bf16 v[96:99], v[156:159], v[188:191], v[96:99]
	v_mfma_f32_16x16x32_bf16 v[88:91], v[164:167], v[188:191], v[88:91]
	v_mfma_f32_16x16x32_bf16 v[80:83], v[156:159], v[196:199], v[80:83]
	v_mfma_f32_16x16x32_bf16 v[72:75], v[164:167], v[196:199], v[72:75]
	s_setprio 0
	s_barrier
	s_add_i32 s52, s43, s28
	s_mov_b32 m0, s52
	ds_read_b128 v[202:205], v151
	ds_read_b128 v[206:209], v151 offset:1024
	ds_read_b128 v[210:213], v151 offset:2048
	ds_read_b128 v[214:217], v151 offset:3072
	global_load_lds_dwordx4 v130, s[20:21]
	s_add_i32 m0, s52, 0x2000
	s_nop 0
	global_load_lds_dwordx4 v134, s[20:21]
	s_waitcnt vmcnt(8)
	s_setprio 1
	s_barrier
	s_waitcnt lgkmcnt(0)
	s_waitcnt lgkmcnt(0)
	v_mfma_f32_16x16x32_bf16 v[116:119], v[202:205], v[168:171], 0
	v_mfma_f32_16x16x32_bf16 v[108:111], v[210:213], v[168:171], 0
	v_mfma_f32_16x16x32_bf16 v[100:103], v[202:205], v[176:179], 0
	v_mfma_f32_16x16x32_bf16 v[92:95], v[210:213], v[176:179], 0
	v_mfma_f32_16x16x32_bf16 v[84:87], v[202:205], v[184:187], 0
	v_mfma_f32_16x16x32_bf16 v[76:79], v[210:213], v[184:187], 0
	v_mfma_f32_16x16x32_bf16 v[68:71], v[202:205], v[192:195], 0
	v_mfma_f32_16x16x32_bf16 v[64:67], v[210:213], v[192:195], 0
	v_mfma_f32_16x16x32_bf16 v[116:119], v[206:209], v[172:175], v[116:119]
	v_mfma_f32_16x16x32_bf16 v[108:111], v[214:217], v[172:175], v[108:111]
	v_mfma_f32_16x16x32_bf16 v[100:103], v[206:209], v[180:183], v[100:103]
	v_mfma_f32_16x16x32_bf16 v[92:95], v[214:217], v[180:183], v[92:95]
	v_mfma_f32_16x16x32_bf16 v[84:87], v[206:209], v[188:191], v[84:87]
	v_mfma_f32_16x16x32_bf16 v[76:79], v[214:217], v[188:191], v[76:79]
	v_mfma_f32_16x16x32_bf16 v[68:71], v[206:209], v[196:199], v[68:71]
	v_mfma_f32_16x16x32_bf16 v[64:67], v[214:217], v[196:199], v[64:67]
	s_setprio 0
	s_mov_b32 m0, s17
	v_lshl_add_u64 v[222:223], s[22:23], 0, v[128:129]
	s_barrier
	ds_read_b128 v[168:171], v150 offset:16384
	ds_read_b128 v[172:175], v150 offset:17408
	ds_read_b128 v[176:179], v150 offset:18432
	ds_read_b128 v[180:183], v150 offset:19456
	ds_read_b128 v[184:187], v150 offset:20480
	ds_read_b128 v[188:191], v150 offset:21504
	ds_read_b128 v[192:195], v150 offset:22528
	ds_read_b128 v[196:199], v150 offset:23552
	global_load_lds_dwordx4 v128, s[22:23]
	v_lshl_add_u64 v[224:225], s[22:23], 0, v[132:133]
	s_mov_b32 m0, s29
	s_nop 0
	global_load_lds_dwordx4 v132, s[22:23]
	s_setprio 1
	s_barrier
	s_waitcnt lgkmcnt(0)
	s_waitcnt lgkmcnt(0)
	v_mfma_f32_16x16x32_bf16 v[60:63], v[152:155], v[168:171], 0
	v_mfma_f32_16x16x32_bf16 v[56:59], v[160:163], v[168:171], 0
	v_mfma_f32_16x16x32_bf16 v[48:51], v[152:155], v[176:179], 0
	v_mfma_f32_16x16x32_bf16 v[40:43], v[160:163], v[176:179], 0
	v_mfma_f32_16x16x32_bf16 v[32:35], v[152:155], v[184:187], 0
	v_mfma_f32_16x16x32_bf16 v[24:27], v[160:163], v[184:187], 0
	v_mfma_f32_16x16x32_bf16 v[16:19], v[152:155], v[192:195], 0
	v_mfma_f32_16x16x32_bf16 v[8:11], v[160:163], v[192:195], 0
	v_mfma_f32_16x16x32_bf16 v[60:63], v[156:159], v[172:175], v[60:63]
	v_mfma_f32_16x16x32_bf16 v[56:59], v[164:167], v[172:175], v[56:59]
	v_mfma_f32_16x16x32_bf16 v[48:51], v[156:159], v[180:183], v[48:51]
	v_mfma_f32_16x16x32_bf16 v[40:43], v[164:167], v[180:183], v[40:43]
	v_mfma_f32_16x16x32_bf16 v[32:35], v[156:159], v[188:191], v[32:35]
	v_mfma_f32_16x16x32_bf16 v[24:27], v[164:167], v[188:191], v[24:27]
	v_mfma_f32_16x16x32_bf16 v[16:19], v[156:159], v[196:199], v[16:19]
	v_mfma_f32_16x16x32_bf16 v[8:11], v[164:167], v[196:199], v[8:11]
	s_setprio 0
	s_barrier
; #define PG8_STAGE(bufoff, gbase, voff) do { _Pragma("unroll") for (int _i = 0; _i < 2; ++_i) \
;         __builtin_amdgcn_global_load_lds((const unsigned*)((const char*)(gbase) + (voff)[_i]), (LAS unsigned*)(lds + (bufoff) + ldsw + _i * 8192), 16, 0, 0); } while (0)
; #define PG8_LDA(dst, b, h) do { _Pragma("unroll") for (int m = 0; m < 4; ++m) _Pragma("unroll") for (int k = 0; k < 2; ++k) dst[m][k] = *(const LAS bf16x8*)(lds + PG8_SA(b, h) + aoff + m * 2048 + k * 1024); } while (0)
; #define PG8_LDB(dst, b, h) do { _Pragma("unroll") for (int n = 0; n < 2; ++n) _Pragma("unroll") for (int k = 0; k < 2; ++k) dst[n][k] = *(const LAS bf16x8*)(lds + PG8_SB(b, h) + boff + n * 2048 + k * 1024); } while (0)
; #define PG8_MMA(ai, bj, At, Bt) do { __builtin_amdgcn_s_setprio(1); _Pragma("unroll") for (int m = 0; m < 4; ++m) _Pragma("unroll") for (int n = 0; n < 2; ++n) _Pragma("unroll") for (int k = 0; k < 2; ++k) \
;         acc[ai][bj][m][n] = __builtin_amdgcn_mfma_f32_16x16x32_bf16(Bt[n][k], At[m][k], acc[ai][bj][m][n], 0, 0, 0); __builtin_amdgcn_s_setprio(0); } while (0)
; #define PG8_WAIT_V(n) asm volatile("s_waitcnt vmcnt(" #n ")" ::: "memory")
; #define PG8_WAIT_L(n) asm volatile("s_waitcnt lgkmcnt(" #n ")" ::: "memory")
; #define PG8_BAR __builtin_amdgcn_s_barrier()
; #define PG8_SCHED __builtin_amdgcn_sched_barrier(0)
; template <class Epi, class Sched>
; __device__ __forceinline__ void gemm_phase(LAS unsigned char* lds, const Gemm g, const Sched& S, const Epi& E) {
;     ...
;             PG8_BAR; PG8_WAIT_L(0); PG8_MMA(1, 0, At, B0); PG8_BAR; PG8_SCHED;
;             PG8_STAGE(PG8_SB(0, 1), b2 + hstep, voffB);
;             PG8_WAIT_V(6); PG8_BAR; PG8_MMA(1, 1, At, B1); PG8_BAR;
;             PG8_LDB(B0, 1, 0); PG8_SCHED; PG8_LDA(At, 1, 0); PG8_STAGE(PG8_SA(0, 1), a2 + hstep, voffA);
;             PG8_WAIT_L(8); PG8_BAR; PG8_WAIT_L(0); PG8_MMA(0, 0, At, B0); PG8_BAR; PG8_SCHED;
;             PG8_LDB(B1, 1, 1); PG8_STAGE(PG8_SB(1, 0), b3, voffB);
;             PG8_BAR; PG8_WAIT_L(0); PG8_MMA(0, 1, At, B1); PG8_BAR;
;             PG8_LDA(At, 1, 1); PG8_STAGE(PG8_SA(1, 0), a3, voffA);
;             PG8_BAR; PG8_WAIT_L(0); PG8_MMA(1, 0, At, B0); PG8_BAR; PG8_SCHED;
;             PG8_STAGE(PG8_SB(1, 1), b3 + hstep, voffB);
;             PG8_WAIT_V(6); PG8_BAR; PG8_MMA(1, 1, At, B1); PG8_BAR;
	s_add_u32 s52, s20, 0x40000
	s_addc_u32 s53, s21, 0
	s_add_i32 s54, s44, s28
	s_mov_b32 m0, s54
	s_nop 0
	global_load_lds_dwordx4 v130, s[52:53]
	s_add_i32 m0, s54, 0x2000
	s_nop 0
	global_load_lds_dwordx4 v134, s[52:53]
	s_add_u32 s22, s22, 0x40000
	s_addc_u32 s23, s23, 0
	s_mov_b32 m0, s30
	s_nop 0
	global_load_lds_dwordx4 v128, s[22:23]
	s_mov_b32 m0, s31
	s_nop 0
	global_load_lds_dwordx4 v132, s[22:23]
	s_waitcnt vmcnt(10)
	s_setprio 1
	s_barrier
	v_mfma_f32_16x16x32_bf16 v[52:55], v[202:205], v[168:171], 0
	v_mfma_f32_16x16x32_bf16 v[44:47], v[210:213], v[168:171], 0
	v_mfma_f32_16x16x32_bf16 v[36:39], v[202:205], v[176:179], 0
	v_mfma_f32_16x16x32_bf16 v[28:31], v[210:213], v[176:179], 0
	v_mfma_f32_16x16x32_bf16 v[20:23], v[202:205], v[184:187], 0
	v_mfma_f32_16x16x32_bf16 v[12:15], v[210:213], v[184:187], 0
	v_mfma_f32_16x16x32_bf16 v[4:7], v[202:205], v[192:195], 0
	v_mfma_f32_16x16x32_bf16 v[0:3], v[210:213], v[192:195], 0
	v_mfma_f32_16x16x32_bf16 v[52:55], v[206:209], v[172:175], v[52:55]
	v_mfma_f32_16x16x32_bf16 v[44:47], v[214:217], v[172:175], v[44:47]
	v_mfma_f32_16x16x32_bf16 v[36:39], v[206:209], v[180:183], v[36:39]
	v_mfma_f32_16x16x32_bf16 v[28:31], v[214:217], v[180:183], v[28:31]
	v_mfma_f32_16x16x32_bf16 v[20:23], v[206:209], v[188:191], v[20:23]
	v_mfma_f32_16x16x32_bf16 v[12:15], v[214:217], v[188:191], v[12:15]
	v_mfma_f32_16x16x32_bf16 v[4:7], v[206:209], v[196:199], v[4:7]
	v_mfma_f32_16x16x32_bf16 v[0:3], v[214:217], v[196:199], v[0:3]
	s_setprio 0
	s_add_i32 s52, 0, 0x18000
	v_add_u32_e32 v136, s52, v148
	s_barrier
	ds_read_b128 v[152:155], v136
	ds_read_b128 v[156:159], v136 offset:1024
	ds_read_b128 v[160:163], v136 offset:2048
	ds_read_b128 v[164:167], v136 offset:3072
	ds_read_b128 v[168:171], v150 offset:32768
	ds_read_b128 v[172:175], v150 offset:33792
	ds_read_b128 v[176:179], v150 offset:34816
	ds_read_b128 v[180:183], v150 offset:35840
	ds_read_b128 v[184:187], v150 offset:36864
	ds_read_b128 v[188:191], v150 offset:37888
	ds_read_b128 v[192:195], v150 offset:38912
	ds_read_b128 v[196:199], v150 offset:39936
	s_waitcnt lgkmcnt(8)
	s_waitcnt vmcnt(8)
	s_setprio 1
	s_barrier
	s_waitcnt lgkmcnt(0)
	s_waitcnt lgkmcnt(0)
	v_mfma_f32_16x16x32_bf16 v[124:127], v[152:155], v[168:171], v[124:127]
	v_mfma_f32_16x16x32_bf16 v[120:123], v[160:163], v[168:171], v[120:123]
	v_mfma_f32_16x16x32_bf16 v[112:115], v[152:155], v[176:179], v[112:115]
	v_mfma_f32_16x16x32_bf16 v[104:107], v[160:163], v[176:179], v[104:107]
	v_mfma_f32_16x16x32_bf16 v[96:99], v[152:155], v[184:187], v[96:99]
	v_mfma_f32_16x16x32_bf16 v[88:91], v[160:163], v[184:187], v[88:91]
	v_mfma_f32_16x16x32_bf16 v[80:83], v[152:155], v[192:195], v[80:83]
	v_mfma_f32_16x16x32_bf16 v[72:75], v[160:163], v[192:195], v[72:75]
	v_mfma_f32_16x16x32_bf16 v[124:127], v[156:159], v[172:175], v[124:127]
	v_mfma_f32_16x16x32_bf16 v[120:123], v[164:167], v[172:175], v[120:123]
	v_mfma_f32_16x16x32_bf16 v[112:115], v[156:159], v[180:183], v[112:115]
	v_mfma_f32_16x16x32_bf16 v[104:107], v[164:167], v[180:183], v[104:107]
	v_mfma_f32_16x16x32_bf16 v[96:99], v[156:159], v[188:191], v[96:99]
	v_mfma_f32_16x16x32_bf16 v[88:91], v[164:167], v[188:191], v[88:91]
	v_mfma_f32_16x16x32_bf16 v[80:83], v[156:159], v[196:199], v[80:83]
	v_mfma_f32_16x16x32_bf16 v[72:75], v[164:167], v[196:199], v[72:75]
	s_setprio 0
	s_barrier
	s_add_i32 s22, 0, 0x1c000
	s_add_i32 s23, s52, s28
	v_add_u32_e32 v136, s22, v148
	s_add_u32 s0, s20, 0x80
	s_addc_u32 s1, s21, 0
	s_mov_b32 m0, s23
	ds_read_b128 v[202:205], v136
	ds_read_b128 v[206:209], v136 offset:1024
	ds_read_b128 v[210:213], v136 offset:2048
	ds_read_b128 v[214:217], v136 offset:3072
	global_load_lds_dwordx4 v130, s[0:1]
	s_add_i32 m0, s23, 0x2000
	s_nop 0
	global_load_lds_dwordx4 v134, s[0:1]
	s_waitcnt vmcnt(8)
	s_setprio 1
	s_barrier
	s_waitcnt lgkmcnt(0)
	s_waitcnt lgkmcnt(0)
	v_mfma_f32_16x16x32_bf16 v[116:119], v[202:205], v[168:171], v[116:119]
	v_mfma_f32_16x16x32_bf16 v[108:111], v[210:213], v[168:171], v[108:111]
	v_mfma_f32_16x16x32_bf16 v[100:103], v[202:205], v[176:179], v[100:103]
	v_mfma_f32_16x16x32_bf16 v[92:95], v[210:213], v[176:179], v[92:95]
	v_mfma_f32_16x16x32_bf16 v[84:87], v[202:205], v[184:187], v[84:87]
	v_mfma_f32_16x16x32_bf16 v[76:79], v[210:213], v[184:187], v[76:79]
	v_mfma_f32_16x16x32_bf16 v[68:71], v[202:205], v[192:195], v[68:71]
	v_mfma_f32_16x16x32_bf16 v[64:67], v[210:213], v[192:195], v[64:67]
	v_mfma_f32_16x16x32_bf16 v[116:119], v[206:209], v[172:175], v[116:119]
	v_mfma_f32_16x16x32_bf16 v[108:111], v[214:217], v[172:175], v[108:111]
	v_mfma_f32_16x16x32_bf16 v[100:103], v[206:209], v[180:183], v[100:103]
	v_mfma_f32_16x16x32_bf16 v[92:95], v[214:217], v[180:183], v[92:95]
	v_mfma_f32_16x16x32_bf16 v[84:87], v[206:209], v[188:191], v[84:87]
	v_mfma_f32_16x16x32_bf16 v[76:79], v[214:217], v[188:191], v[76:79]
	v_mfma_f32_16x16x32_bf16 v[68:71], v[206:209], v[196:199], v[68:71]
	v_mfma_f32_16x16x32_bf16 v[64:67], v[214:217], v[196:199], v[64:67]
	s_setprio 0
	s_mov_b32 m0, s36
	s_mov_b64 s[0:1], 0x80
	v_lshl_add_u64 v[218:219], v[222:223], 0, s[0:1]
	s_barrier
	ds_read_b128 v[168:171], v150 offset:49152
	ds_read_b128 v[172:175], v150 offset:50176
	ds_read_b128 v[176:179], v150 offset:51200
	ds_read_b128 v[180:183], v150 offset:52224
	ds_read_b128 v[184:187], v150 offset:53248
	ds_read_b128 v[188:191], v150 offset:54272
	ds_read_b128 v[192:195], v150 offset:55296
	ds_read_b128 v[196:199], v150 offset:56320
	global_load_lds_dwordx4 v[218:219], off
	v_lshl_add_u64 v[218:219], v[224:225], 0, s[0:1]
	s_mov_b32 m0, s37
	s_nop 0
	global_load_lds_dwordx4 v[218:219], off
	s_setprio 1
	s_barrier
; #define PG8_STAGE(bufoff, gbase, voff) do { _Pragma("unroll") for (int _i = 0; _i < 2; ++_i) \
;         __builtin_amdgcn_global_load_lds((const unsigned*)((const char*)(gbase) + (voff)[_i]), (LAS unsigned*)(lds + (bufoff) + ldsw + _i * 8192), 16, 0, 0); } while (0)
; #define PG8_LDA(dst, b, h) do { _Pragma("unroll") for (int m = 0; m < 4; ++m) _Pragma("unroll") for (int k = 0; k < 2; ++k) dst[m][k] = *(const LAS bf16x8*)(lds + PG8_SA(b, h) + aoff + m * 2048 + k * 1024); } while (0)
; #define PG8_WAIT_V(n) asm volatile("s_waitcnt vmcnt(" #n ")" ::: "memory")
; #define PG8_WAIT_L(n) asm volatile("s_waitcnt lgkmcnt(" #n ")" ::: "memory")
; template <class Epi, class Sched>
; __device__ __forceinline__ void gemm_phase(LAS unsigned char* lds, const Gemm g, const Sched& S, const Epi& E) {
;     ...
;         for (int t = 0; t < nt; t += 2) {
;             const bool last = (t == nt - 2);
;             const char* a1 = cA + (size_t)(t + 1) * kstep;
;             const char* a2 = last ? nA : cA + (size_t)(t + 2) * kstep; const char* b2 = last ? nB : cB + (size_t)(t + 2) * kstep;
;             const char* a3 = a2 + kstep; const char* b3 = b2 + kstep;
;             PG8_LDB(B0, 0, 0); PG8_SCHED; PG8_LDA(At, 0, 0); PG8_STAGE(PG8_SA(1, 1), a1 + hstep, voffA);
;             PG8_WAIT_L(8); PG8_BAR; PG8_WAIT_L(0); PG8_MMA(0, 0, At, B0); PG8_BAR; PG8_SCHED;
;             PG8_LDB(B1, 0, 1); PG8_STAGE(PG8_SB(0, 0), b2, voffB);
;             PG8_BAR; PG8_WAIT_L(0); PG8_MMA(0, 1, At, B1); PG8_BAR;
;             PG8_LDA(At, 0, 1); PG8_STAGE(PG8_SA(0, 0), a2, voffA);
;             PG8_BAR; PG8_WAIT_L(0); PG8_MMA(1, 0, At, B0); PG8_BAR; PG8_SCHED;
;             PG8_STAGE(PG8_SB(0, 1), b2 + hstep, voffB);
;             PG8_WAIT_V(6); PG8_BAR; PG8_MMA(1, 1, At, B1); PG8_BAR;
;             PG8_LDB(B0, 1, 0); PG8_SCHED; PG8_LDA(At, 1, 0); PG8_STAGE(PG8_SA(0, 1), a2 + hstep, voffA);
;             PG8_WAIT_L(8); PG8_BAR; PG8_WAIT_L(0); PG8_MMA(0, 0, At, B0); PG8_BAR; PG8_SCHED;
;             PG8_LDB(B1, 1, 1); PG8_STAGE(PG8_SB(1, 0), b3, voffB);
;             PG8_BAR; PG8_WAIT_L(0); PG8_MMA(0, 1, At, B1); PG8_BAR;
;             PG8_LDA(At, 1, 1); PG8_STAGE(PG8_SA(1, 0), a3, voffA);
;             PG8_BAR; PG8_WAIT_L(0); PG8_MMA(1, 0, At, B0); PG8_BAR; PG8_SCHED;
;             PG8_STAGE(PG8_SB(1, 1), b3 + hstep, voffB);
;             PG8_WAIT_V(6); PG8_BAR; PG8_MMA(1, 1, At, B1); PG8_BAR;
	s_waitcnt lgkmcnt(0)
	s_waitcnt lgkmcnt(0)
	v_mfma_f32_16x16x32_bf16 v[60:63], v[152:155], v[168:171], v[60:63]
	v_mfma_f32_16x16x32_bf16 v[56:59], v[160:163], v[168:171], v[56:59]
	v_mfma_f32_16x16x32_bf16 v[48:51], v[152:155], v[176:179], v[48:51]
	v_mfma_f32_16x16x32_bf16 v[40:43], v[160:163], v[176:179], v[40:43]
	v_mfma_f32_16x16x32_bf16 v[32:35], v[152:155], v[184:187], v[32:35]
	v_mfma_f32_16x16x32_bf16 v[24:27], v[160:163], v[184:187], v[24:27]
	v_mfma_f32_16x16x32_bf16 v[16:19], v[152:155], v[192:195], v[16:19]
	v_mfma_f32_16x16x32_bf16 v[8:11], v[160:163], v[192:195], v[8:11]
	v_mfma_f32_16x16x32_bf16 v[60:63], v[156:159], v[172:175], v[60:63]
	v_mfma_f32_16x16x32_bf16 v[56:59], v[164:167], v[172:175], v[56:59]
	v_mfma_f32_16x16x32_bf16 v[48:51], v[156:159], v[180:183], v[48:51]
	v_mfma_f32_16x16x32_bf16 v[40:43], v[164:167], v[180:183], v[40:43]
	v_mfma_f32_16x16x32_bf16 v[32:35], v[156:159], v[188:191], v[32:35]
	v_mfma_f32_16x16x32_bf16 v[24:27], v[164:167], v[188:191], v[24:27]
	v_mfma_f32_16x16x32_bf16 v[16:19], v[156:159], v[196:199], v[16:19]
	v_mfma_f32_16x16x32_bf16 v[8:11], v[164:167], v[196:199], v[8:11]
	s_setprio 0
	s_barrier
	s_add_u32 s20, s20, 0x40080
	s_addc_u32 s21, s21, 0
	s_add_i32 s22, s22, s28
	s_mov_b32 m0, s22
	s_nop 0
	global_load_lds_dwordx4 v130, s[20:21]
	s_add_i32 m0, s22, 0x2000
	s_nop 0
	global_load_lds_dwordx4 v134, s[20:21]
	s_waitcnt vmcnt(8)
	s_setprio 1
	s_barrier
	v_mfma_f32_16x16x32_bf16 v[52:55], v[202:205], v[168:171], v[52:55]
	v_mfma_f32_16x16x32_bf16 v[44:47], v[210:213], v[168:171], v[44:47]
	v_mfma_f32_16x16x32_bf16 v[36:39], v[202:205], v[176:179], v[36:39]
	v_mfma_f32_16x16x32_bf16 v[28:31], v[210:213], v[176:179], v[28:31]
	v_mfma_f32_16x16x32_bf16 v[20:23], v[202:205], v[184:187], v[20:23]
	v_mfma_f32_16x16x32_bf16 v[12:15], v[210:213], v[184:187], v[12:15]
	v_mfma_f32_16x16x32_bf16 v[4:7], v[202:205], v[192:195], v[4:7]
	v_mfma_f32_16x16x32_bf16 v[0:3], v[210:213], v[192:195], v[0:3]
	v_mfma_f32_16x16x32_bf16 v[52:55], v[206:209], v[172:175], v[52:55]
	v_mfma_f32_16x16x32_bf16 v[44:47], v[214:217], v[172:175], v[44:47]
	v_mfma_f32_16x16x32_bf16 v[36:39], v[206:209], v[180:183], v[36:39]
	v_mfma_f32_16x16x32_bf16 v[28:31], v[214:217], v[180:183], v[28:31]
	v_mfma_f32_16x16x32_bf16 v[20:23], v[206:209], v[188:191], v[20:23]
	v_mfma_f32_16x16x32_bf16 v[12:15], v[214:217], v[188:191], v[12:15]
	v_mfma_f32_16x16x32_bf16 v[4:7], v[206:209], v[196:199], v[4:7]
	v_mfma_f32_16x16x32_bf16 v[0:3], v[214:217], v[196:199], v[0:3]
	s_setprio 0
	s_add_i32 s51, s51, 2
	s_add_u32 s18, s18, 0x100
	s_addc_u32 s19, s19, 0
	s_add_u32 s48, s48, 0x100
	s_addc_u32 s49, s49, 0
	s_cmp_gt_u32 s51, 13
	s_barrier
.LBB0_673:
	ds_read_b128 v[152:155], v149
	ds_read_b128 v[156:159], v149 offset:1024
	ds_read_b128 v[160:163], v149 offset:2048
	ds_read_b128 v[164:167], v149 offset:3072
	s_add_u32 s20, s18, 0xfffc0080
	s_addc_u32 s21, s19, -1
	s_cmp_eq_u32 s51, 12
	s_cselect_b32 s23, s9, s21
	s_cselect_b32 s22, s46, s20
	s_cselect_b32 s21, s7, s49
	s_cselect_b32 s20, s47, s48
	s_add_i32 m0, s17, 0xc000
	ds_read_b128 v[168:171], v150
	ds_read_b128 v[172:175], v150 offset:1024
	ds_read_b128 v[176:179], v150 offset:2048
	ds_read_b128 v[180:183], v150 offset:3072
	ds_read_b128 v[184:187], v150 offset:4096
	ds_read_b128 v[188:191], v150 offset:5120
	ds_read_b128 v[192:195], v150 offset:6144
	ds_read_b128 v[196:199], v150 offset:7168
	global_load_lds_dwordx4 v138, s[18:19]
	s_add_i32 m0, s17, 0xe000
	s_nop 0
	global_load_lds_dwordx4 v140, s[18:19]
	s_waitcnt lgkmcnt(8)
	s_waitcnt vmcnt(8)
	s_setprio 1
	s_barrier
	s_waitcnt lgkmcnt(0)
	s_waitcnt lgkmcnt(0)
	v_mfma_f32_16x16x32_bf16 v[124:127], v[152:155], v[168:171], v[124:127]
	v_mfma_f32_16x16x32_bf16 v[120:123], v[160:163], v[168:171], v[120:123]
	v_mfma_f32_16x16x32_bf16 v[112:115], v[152:155], v[176:179], v[112:115]
	v_mfma_f32_16x16x32_bf16 v[104:107], v[160:163], v[176:179], v[104:107]
	v_mfma_f32_16x16x32_bf16 v[96:99], v[152:155], v[184:187], v[96:99]
	v_mfma_f32_16x16x32_bf16 v[88:91], v[160:163], v[184:187], v[88:91]
	v_mfma_f32_16x16x32_bf16 v[80:83], v[152:155], v[192:195], v[80:83]
	v_mfma_f32_16x16x32_bf16 v[72:75], v[160:163], v[192:195], v[72:75]
	v_mfma_f32_16x16x32_bf16 v[124:127], v[156:159], v[172:175], v[124:127]
	v_mfma_f32_16x16x32_bf16 v[120:123], v[164:167], v[172:175], v[120:123]
	v_mfma_f32_16x16x32_bf16 v[112:115], v[156:159], v[180:183], v[112:115]
	v_mfma_f32_16x16x32_bf16 v[104:107], v[164:167], v[180:183], v[104:107]
	v_mfma_f32_16x16x32_bf16 v[96:99], v[156:159], v[188:191], v[96:99]
	v_mfma_f32_16x16x32_bf16 v[88:91], v[164:167], v[188:191], v[88:91]
	v_mfma_f32_16x16x32_bf16 v[80:83], v[156:159], v[196:199], v[80:83]
	v_mfma_f32_16x16x32_bf16 v[72:75], v[164:167], v[196:199], v[72:75]
	s_setprio 0
	s_barrier
	s_add_i32 s52, s43, s28
	s_mov_b32 m0, s52
	ds_read_b128 v[202:205], v151
	ds_read_b128 v[206:209], v151 offset:1024
	ds_read_b128 v[210:213], v151 offset:2048
	ds_read_b128 v[214:217], v151 offset:3072
	global_load_lds_dwordx4 v130, s[20:21]
	s_add_i32 m0, s52, 0x2000
	s_nop 0
	global_load_lds_dwordx4 v134, s[20:21]
	s_waitcnt vmcnt(8)
	s_setprio 1
	s_barrier
; #define PG8_STAGE(bufoff, gbase, voff) do { _Pragma("unroll") for (int _i = 0; _i < 2; ++_i) \
;         __builtin_amdgcn_global_load_lds((const unsigned*)((const char*)(gbase) + (voff)[_i]), (LAS unsigned*)(lds + (bufoff) + ldsw + _i * 8192), 16, 0, 0); } while (0)
; #define PG8_LDA(dst, b, h) do { _Pragma("unroll") for (int m = 0; m < 4; ++m) _Pragma("unroll") for (int k = 0; k < 2; ++k) dst[m][k] = *(const LAS bf16x8*)(lds + PG8_SA(b, h) + aoff + m * 2048 + k * 1024); } while (0)
; #define PG8_LDB(dst, b, h) do { _Pragma("unroll") for (int n = 0; n < 2; ++n) _Pragma("unroll") for (int k = 0; k < 2; ++k) dst[n][k] = *(const LAS bf16x8*)(lds + PG8_SB(b, h) + boff + n * 2048 + k * 1024); } while (0)
; #define PG8_WAIT_V(n) asm volatile("s_waitcnt vmcnt(" #n ")" ::: "memory")
; #define PG8_WAIT_L(n) asm volatile("s_waitcnt lgkmcnt(" #n ")" ::: "memory")
; #define PG8_BAR __builtin_amdgcn_s_barrier()
; #define PG8_SCHED __builtin_amdgcn_sched_barrier(0)
; template <class Epi, class Sched>
; __device__ __forceinline__ void gemm_phase(LAS unsigned char* lds, const Gemm g, const Sched& S, const Epi& E) {
;     ...
;             PG8_LDB(B0, 0, 0); PG8_SCHED; PG8_LDA(At, 0, 0); PG8_STAGE(PG8_SA(1, 1), a1 + hstep, voffA);
;             PG8_WAIT_L(8); PG8_BAR; PG8_WAIT_L(0); PG8_MMA(0, 0, At, B0); PG8_BAR; PG8_SCHED;
;             PG8_LDB(B1, 0, 1); PG8_STAGE(PG8_SB(0, 0), b2, voffB);
;             PG8_BAR; PG8_WAIT_L(0); PG8_MMA(0, 1, At, B1); PG8_BAR;
;             PG8_LDA(At, 0, 1); PG8_STAGE(PG8_SA(0, 0), a2, voffA);
;             PG8_BAR; PG8_WAIT_L(0); PG8_MMA(1, 0, At, B0); PG8_BAR; PG8_SCHED;
;             PG8_STAGE(PG8_SB(0, 1), b2 + hstep, voffB);
;             PG8_WAIT_V(6); PG8_BAR; PG8_MMA(1, 1, At, B1); PG8_BAR;
;             PG8_LDB(B0, 1, 0); PG8_SCHED; PG8_LDA(At, 1, 0); PG8_STAGE(PG8_SA(0, 1), a2 + hstep, voffA);
;             PG8_WAIT_L(8); PG8_BAR; PG8_WAIT_L(0); PG8_MMA(0, 0, At, B0); PG8_BAR; PG8_SCHED;
;             PG8_LDB(B1, 1, 1); PG8_STAGE(PG8_SB(1, 0), b3, voffB);
;             PG8_BAR; PG8_WAIT_L(0); PG8_MMA(0, 1, At, B1); PG8_BAR;
;             PG8_LDA(At, 1, 1); PG8_STAGE(PG8_SA(1, 0), a3, voffA);
;             PG8_BAR; PG8_WAIT_L(0); PG8_MMA(1, 0, At, B0); PG8_BAR; PG8_SCHED;
;             PG8_STAGE(PG8_SB(1, 1), b3 + hstep, voffB);
;             PG8_WAIT_V(6); PG8_BAR; PG8_MMA(1, 1, At, B1); PG8_BAR;
	s_waitcnt lgkmcnt(0)
	s_waitcnt lgkmcnt(0)
	v_mfma_f32_16x16x32_bf16 v[116:119], v[202:205], v[168:171], v[116:119]
	v_mfma_f32_16x16x32_bf16 v[108:111], v[210:213], v[168:171], v[108:111]
	v_mfma_f32_16x16x32_bf16 v[100:103], v[202:205], v[176:179], v[100:103]
	v_mfma_f32_16x16x32_bf16 v[92:95], v[210:213], v[176:179], v[92:95]
	v_mfma_f32_16x16x32_bf16 v[84:87], v[202:205], v[184:187], v[84:87]
	v_mfma_f32_16x16x32_bf16 v[76:79], v[210:213], v[184:187], v[76:79]
	v_mfma_f32_16x16x32_bf16 v[68:71], v[202:205], v[192:195], v[68:71]
	v_mfma_f32_16x16x32_bf16 v[64:67], v[210:213], v[192:195], v[64:67]
	v_mfma_f32_16x16x32_bf16 v[116:119], v[206:209], v[172:175], v[116:119]
	v_mfma_f32_16x16x32_bf16 v[108:111], v[214:217], v[172:175], v[108:111]
	v_mfma_f32_16x16x32_bf16 v[100:103], v[206:209], v[180:183], v[100:103]
	v_mfma_f32_16x16x32_bf16 v[92:95], v[214:217], v[180:183], v[92:95]
	v_mfma_f32_16x16x32_bf16 v[84:87], v[206:209], v[188:191], v[84:87]
	v_mfma_f32_16x16x32_bf16 v[76:79], v[214:217], v[188:191], v[76:79]
	v_mfma_f32_16x16x32_bf16 v[68:71], v[206:209], v[196:199], v[68:71]
	v_mfma_f32_16x16x32_bf16 v[64:67], v[214:217], v[196:199], v[64:67]
	s_setprio 0
	s_mov_b32 m0, s17
	v_lshl_add_u64 v[222:223], s[22:23], 0, v[128:129]
	s_barrier
	ds_read_b128 v[168:171], v150 offset:16384
	ds_read_b128 v[172:175], v150 offset:17408
	ds_read_b128 v[176:179], v150 offset:18432
	ds_read_b128 v[180:183], v150 offset:19456
	ds_read_b128 v[184:187], v150 offset:20480
	ds_read_b128 v[188:191], v150 offset:21504
	ds_read_b128 v[192:195], v150 offset:22528
	ds_read_b128 v[196:199], v150 offset:23552
	global_load_lds_dwordx4 v128, s[22:23]
	v_lshl_add_u64 v[224:225], s[22:23], 0, v[132:133]
	s_mov_b32 m0, s29
	s_nop 0
	global_load_lds_dwordx4 v132, s[22:23]
	s_setprio 1
	s_barrier
	s_waitcnt lgkmcnt(0)
	s_waitcnt lgkmcnt(0)
	v_mfma_f32_16x16x32_bf16 v[60:63], v[152:155], v[168:171], v[60:63]
	v_mfma_f32_16x16x32_bf16 v[56:59], v[160:163], v[168:171], v[56:59]
	v_mfma_f32_16x16x32_bf16 v[48:51], v[152:155], v[176:179], v[48:51]
	v_mfma_f32_16x16x32_bf16 v[40:43], v[160:163], v[176:179], v[40:43]
	v_mfma_f32_16x16x32_bf16 v[32:35], v[152:155], v[184:187], v[32:35]
	v_mfma_f32_16x16x32_bf16 v[24:27], v[160:163], v[184:187], v[24:27]
	v_mfma_f32_16x16x32_bf16 v[16:19], v[152:155], v[192:195], v[16:19]
	v_mfma_f32_16x16x32_bf16 v[8:11], v[160:163], v[192:195], v[8:11]
	v_mfma_f32_16x16x32_bf16 v[60:63], v[156:159], v[172:175], v[60:63]
	v_mfma_f32_16x16x32_bf16 v[56:59], v[164:167], v[172:175], v[56:59]
	v_mfma_f32_16x16x32_bf16 v[48:51], v[156:159], v[180:183], v[48:51]
	v_mfma_f32_16x16x32_bf16 v[40:43], v[164:167], v[180:183], v[40:43]
	v_mfma_f32_16x16x32_bf16 v[32:35], v[156:159], v[188:191], v[32:35]
	v_mfma_f32_16x16x32_bf16 v[24:27], v[164:167], v[188:191], v[24:27]
	v_mfma_f32_16x16x32_bf16 v[16:19], v[156:159], v[196:199], v[16:19]
	v_mfma_f32_16x16x32_bf16 v[8:11], v[164:167], v[196:199], v[8:11]
	s_setprio 0
	s_barrier
	s_add_u32 s52, s20, 0x40000
	s_addc_u32 s53, s21, 0
	s_add_i32 s54, s44, s28
	s_mov_b32 m0, s54
	s_nop 0
	global_load_lds_dwordx4 v130, s[52:53]
	s_add_i32 m0, s54, 0x2000
	s_nop 0
	global_load_lds_dwordx4 v134, s[52:53]
	s_add_u32 s22, s22, 0x40000
	s_addc_u32 s23, s23, 0
	s_mov_b32 m0, s30
	s_nop 0
	global_load_lds_dwordx4 v128, s[22:23]
	s_mov_b32 m0, s31
	s_nop 0
	global_load_lds_dwordx4 v132, s[22:23]
	s_waitcnt vmcnt(10)
	s_setprio 1
	s_barrier
	v_mfma_f32_16x16x32_bf16 v[52:55], v[202:205], v[168:171], v[52:55]
	v_mfma_f32_16x16x32_bf16 v[44:47], v[210:213], v[168:171], v[44:47]
	v_mfma_f32_16x16x32_bf16 v[36:39], v[202:205], v[176:179], v[36:39]
	v_mfma_f32_16x16x32_bf16 v[28:31], v[210:213], v[176:179], v[28:31]
	v_mfma_f32_16x16x32_bf16 v[20:23], v[202:205], v[184:187], v[20:23]
	v_mfma_f32_16x16x32_bf16 v[12:15], v[210:213], v[184:187], v[12:15]
	v_mfma_f32_16x16x32_bf16 v[4:7], v[202:205], v[192:195], v[4:7]
	v_mfma_f32_16x16x32_bf16 v[0:3], v[210:213], v[192:195], v[0:3]
	v_mfma_f32_16x16x32_bf16 v[52:55], v[206:209], v[172:175], v[52:55]
	v_mfma_f32_16x16x32_bf16 v[44:47], v[214:217], v[172:175], v[44:47]
	v_mfma_f32_16x16x32_bf16 v[36:39], v[206:209], v[180:183], v[36:39]
	v_mfma_f32_16x16x32_bf16 v[28:31], v[214:217], v[180:183], v[28:31]
	v_mfma_f32_16x16x32_bf16 v[20:23], v[206:209], v[188:191], v[20:23]
	v_mfma_f32_16x16x32_bf16 v[12:15], v[214:217], v[188:191], v[12:15]
	v_mfma_f32_16x16x32_bf16 v[4:7], v[206:209], v[196:199], v[4:7]
	v_mfma_f32_16x16x32_bf16 v[0:3], v[214:217], v[196:199], v[0:3]
	s_setprio 0
	s_add_i32 s52, 0, 0x18000
	v_add_u32_e32 v136, s52, v148
	s_barrier
	ds_read_b128 v[152:155], v136
	ds_read_b128 v[156:159], v136 offset:1024
	ds_read_b128 v[160:163], v136 offset:2048
	ds_read_b128 v[164:167], v136 offset:3072
	ds_read_b128 v[168:171], v150 offset:32768
	ds_read_b128 v[172:175], v150 offset:33792
	ds_read_b128 v[176:179], v150 offset:34816
	ds_read_b128 v[180:183], v150 offset:35840
	ds_read_b128 v[184:187], v150 offset:36864
	ds_read_b128 v[188:191], v150 offset:37888
	ds_read_b128 v[192:195], v150 offset:38912
	ds_read_b128 v[196:199], v150 offset:39936
	s_waitcnt lgkmcnt(8)
	s_waitcnt vmcnt(8)
	s_setprio 1
	s_barrier
; #define PG8_STAGE(bufoff, gbase, voff) do { _Pragma("unroll") for (int _i = 0; _i < 2; ++_i) \
;         __builtin_amdgcn_global_load_lds((const unsigned*)((const char*)(gbase) + (voff)[_i]), (LAS unsigned*)(lds + (bufoff) + ldsw + _i * 8192), 16, 0, 0); } while (0)
; #define PG8_LDA(dst, b, h) do { _Pragma("unroll") for (int m = 0; m < 4; ++m) _Pragma("unroll") for (int k = 0; k < 2; ++k) dst[m][k] = *(const LAS bf16x8*)(lds + PG8_SA(b, h) + aoff + m * 2048 + k * 1024); } while (0)
; #define PG8_LDB(dst, b, h) do { _Pragma("unroll") for (int n = 0; n < 2; ++n) _Pragma("unroll") for (int k = 0; k < 2; ++k) dst[n][k] = *(const LAS bf16x8*)(lds + PG8_SB(b, h) + boff + n * 2048 + k * 1024); } while (0)
; #define PG8_MMA(ai, bj, At, Bt) do { __builtin_amdgcn_s_setprio(1); _Pragma("unroll") for (int m = 0; m < 4; ++m) _Pragma("unroll") for (int n = 0; n < 2; ++n) _Pragma("unroll") for (int k = 0; k < 2; ++k) \
;         acc[ai][bj][m][n] = __builtin_amdgcn_mfma_f32_16x16x32_bf16(Bt[n][k], At[m][k], acc[ai][bj][m][n], 0, 0, 0); __builtin_amdgcn_s_setprio(0); } while (0)
; #define PG8_WAIT_V(n) asm volatile("s_waitcnt vmcnt(" #n ")" ::: "memory")
; #define PG8_WAIT_L(n) asm volatile("s_waitcnt lgkmcnt(" #n ")" ::: "memory")
; #define PG8_BAR __builtin_amdgcn_s_barrier()
; #define PG8_SCHED __builtin_amdgcn_sched_barrier(0)
; template <class Epi, class Sched>
; __device__ __forceinline__ void gemm_phase(LAS unsigned char* lds, const Gemm g, const Sched& S, const Epi& E) {
;     ...
;             PG8_BAR; PG8_WAIT_L(0); PG8_MMA(1, 0, At, B0); PG8_BAR; PG8_SCHED;
;             PG8_STAGE(PG8_SB(0, 1), b2 + hstep, voffB);
;             PG8_WAIT_V(6); PG8_BAR; PG8_MMA(1, 1, At, B1); PG8_BAR;
;             PG8_LDB(B0, 1, 0); PG8_SCHED; PG8_LDA(At, 1, 0); PG8_STAGE(PG8_SA(0, 1), a2 + hstep, voffA);
;             PG8_WAIT_L(8); PG8_BAR; PG8_WAIT_L(0); PG8_MMA(0, 0, At, B0); PG8_BAR; PG8_SCHED;
;             PG8_LDB(B1, 1, 1); PG8_STAGE(PG8_SB(1, 0), b3, voffB);
;             PG8_BAR; PG8_WAIT_L(0); PG8_MMA(0, 1, At, B1); PG8_BAR;
;             PG8_LDA(At, 1, 1); PG8_STAGE(PG8_SA(1, 0), a3, voffA);
;             PG8_BAR; PG8_WAIT_L(0); PG8_MMA(1, 0, At, B0); PG8_BAR; PG8_SCHED;
;             PG8_STAGE(PG8_SB(1, 1), b3 + hstep, voffB);
;             PG8_WAIT_V(6); PG8_BAR; PG8_MMA(1, 1, At, B1); PG8_BAR;
	s_waitcnt lgkmcnt(0)
	s_waitcnt lgkmcnt(0)
	v_mfma_f32_16x16x32_bf16 v[124:127], v[152:155], v[168:171], v[124:127]
	v_mfma_f32_16x16x32_bf16 v[120:123], v[160:163], v[168:171], v[120:123]
	v_mfma_f32_16x16x32_bf16 v[112:115], v[152:155], v[176:179], v[112:115]
	v_mfma_f32_16x16x32_bf16 v[104:107], v[160:163], v[176:179], v[104:107]
	v_mfma_f32_16x16x32_bf16 v[96:99], v[152:155], v[184:187], v[96:99]
	v_mfma_f32_16x16x32_bf16 v[88:91], v[160:163], v[184:187], v[88:91]
	v_mfma_f32_16x16x32_bf16 v[80:83], v[152:155], v[192:195], v[80:83]
	v_mfma_f32_16x16x32_bf16 v[72:75], v[160:163], v[192:195], v[72:75]
	v_mfma_f32_16x16x32_bf16 v[124:127], v[156:159], v[172:175], v[124:127]
	v_mfma_f32_16x16x32_bf16 v[120:123], v[164:167], v[172:175], v[120:123]
	v_mfma_f32_16x16x32_bf16 v[112:115], v[156:159], v[180:183], v[112:115]
	v_mfma_f32_16x16x32_bf16 v[104:107], v[164:167], v[180:183], v[104:107]
	v_mfma_f32_16x16x32_bf16 v[96:99], v[156:159], v[188:191], v[96:99]
	v_mfma_f32_16x16x32_bf16 v[88:91], v[164:167], v[188:191], v[88:91]
	v_mfma_f32_16x16x32_bf16 v[80:83], v[156:159], v[196:199], v[80:83]
	v_mfma_f32_16x16x32_bf16 v[72:75], v[164:167], v[196:199], v[72:75]
	s_setprio 0
	s_barrier
	s_add_i32 s22, 0, 0x1c000
	s_add_i32 s23, s52, s28
	v_add_u32_e32 v136, s22, v148
	s_add_u32 s0, s20, 0x80
	s_addc_u32 s1, s21, 0
	s_mov_b32 m0, s23
	ds_read_b128 v[202:205], v136
	ds_read_b128 v[206:209], v136 offset:1024
	ds_read_b128 v[210:213], v136 offset:2048
	ds_read_b128 v[214:217], v136 offset:3072
	global_load_lds_dwordx4 v130, s[0:1]
	s_add_i32 m0, s23, 0x2000
	s_nop 0
	global_load_lds_dwordx4 v134, s[0:1]
	s_waitcnt vmcnt(8)
	s_setprio 1
	s_barrier
	s_waitcnt lgkmcnt(0)
	s_waitcnt lgkmcnt(0)
	v_mfma_f32_16x16x32_bf16 v[116:119], v[202:205], v[168:171], v[116:119]
	v_mfma_f32_16x16x32_bf16 v[108:111], v[210:213], v[168:171], v[108:111]
	v_mfma_f32_16x16x32_bf16 v[100:103], v[202:205], v[176:179], v[100:103]
	v_mfma_f32_16x16x32_bf16 v[92:95], v[210:213], v[176:179], v[92:95]
	v_mfma_f32_16x16x32_bf16 v[84:87], v[202:205], v[184:187], v[84:87]
	v_mfma_f32_16x16x32_bf16 v[76:79], v[210:213], v[184:187], v[76:79]
	v_mfma_f32_16x16x32_bf16 v[68:71], v[202:205], v[192:195], v[68:71]
	v_mfma_f32_16x16x32_bf16 v[64:67], v[210:213], v[192:195], v[64:67]
	v_mfma_f32_16x16x32_bf16 v[116:119], v[206:209], v[172:175], v[116:119]
	v_mfma_f32_16x16x32_bf16 v[108:111], v[214:217], v[172:175], v[108:111]
	v_mfma_f32_16x16x32_bf16 v[100:103], v[206:209], v[180:183], v[100:103]
	v_mfma_f32_16x16x32_bf16 v[92:95], v[214:217], v[180:183], v[92:95]
	v_mfma_f32_16x16x32_bf16 v[84:87], v[206:209], v[188:191], v[84:87]
	v_mfma_f32_16x16x32_bf16 v[76:79], v[214:217], v[188:191], v[76:79]
	v_mfma_f32_16x16x32_bf16 v[68:71], v[206:209], v[196:199], v[68:71]
	v_mfma_f32_16x16x32_bf16 v[64:67], v[214:217], v[196:199], v[64:67]
	s_setprio 0
	s_mov_b32 m0, s36
	s_mov_b64 s[0:1], 0x80
	v_lshl_add_u64 v[218:219], v[222:223], 0, s[0:1]
	s_barrier
	ds_read_b128 v[168:171], v150 offset:49152
	ds_read_b128 v[172:175], v150 offset:50176
	ds_read_b128 v[176:179], v150 offset:51200
	ds_read_b128 v[180:183], v150 offset:52224
	ds_read_b128 v[184:187], v150 offset:53248
	ds_read_b128 v[188:191], v150 offset:54272
	ds_read_b128 v[192:195], v150 offset:55296
	ds_read_b128 v[196:199], v150 offset:56320
	global_load_lds_dwordx4 v[218:219], off
	v_lshl_add_u64 v[218:219], v[224:225], 0, s[0:1]
	s_mov_b32 m0, s37
	s_nop 0
	global_load_lds_dwordx4 v[218:219], off
	s_setprio 1
	s_barrier
	s_waitcnt lgkmcnt(0)
	s_waitcnt lgkmcnt(0)
	v_mfma_f32_16x16x32_bf16 v[60:63], v[152:155], v[168:171], v[60:63]
	v_mfma_f32_16x16x32_bf16 v[56:59], v[160:163], v[168:171], v[56:59]
	v_mfma_f32_16x16x32_bf16 v[48:51], v[152:155], v[176:179], v[48:51]
	v_mfma_f32_16x16x32_bf16 v[40:43], v[160:163], v[176:179], v[40:43]
	v_mfma_f32_16x16x32_bf16 v[32:35], v[152:155], v[184:187], v[32:35]
	v_mfma_f32_16x16x32_bf16 v[24:27], v[160:163], v[184:187], v[24:27]
	v_mfma_f32_16x16x32_bf16 v[16:19], v[152:155], v[192:195], v[16:19]
	v_mfma_f32_16x16x32_bf16 v[8:11], v[160:163], v[192:195], v[8:11]
	v_mfma_f32_16x16x32_bf16 v[60:63], v[156:159], v[172:175], v[60:63]
	v_mfma_f32_16x16x32_bf16 v[56:59], v[164:167], v[172:175], v[56:59]
	v_mfma_f32_16x16x32_bf16 v[48:51], v[156:159], v[180:183], v[48:51]
	v_mfma_f32_16x16x32_bf16 v[40:43], v[164:167], v[180:183], v[40:43]
	v_mfma_f32_16x16x32_bf16 v[32:35], v[156:159], v[188:191], v[32:35]
	v_mfma_f32_16x16x32_bf16 v[24:27], v[164:167], v[188:191], v[24:27]
	v_mfma_f32_16x16x32_bf16 v[16:19], v[156:159], v[196:199], v[16:19]
	v_mfma_f32_16x16x32_bf16 v[8:11], v[164:167], v[196:199], v[8:11]
	s_setprio 0
	s_barrier
	s_add_u32 s20, s20, 0x40080
	s_addc_u32 s21, s21, 0
	s_add_i32 s22, s22, s28
	s_mov_b32 m0, s22
	s_nop 0
	global_load_lds_dwordx4 v130, s[20:21]
	s_add_i32 m0, s22, 0x2000
	s_nop 0
	global_load_lds_dwordx4 v134, s[20:21]
	s_waitcnt vmcnt(8)
	s_setprio 1
	s_barrier
	v_mfma_f32_16x16x32_bf16 v[52:55], v[202:205], v[168:171], v[52:55]
	v_mfma_f32_16x16x32_bf16 v[44:47], v[210:213], v[168:171], v[44:47]
	v_mfma_f32_16x16x32_bf16 v[36:39], v[202:205], v[176:179], v[36:39]
	v_mfma_f32_16x16x32_bf16 v[28:31], v[210:213], v[176:179], v[28:31]
	v_mfma_f32_16x16x32_bf16 v[20:23], v[202:205], v[184:187], v[20:23]
	v_mfma_f32_16x16x32_bf16 v[12:15], v[210:213], v[184:187], v[12:15]
	v_mfma_f32_16x16x32_bf16 v[4:7], v[202:205], v[192:195], v[4:7]
	v_mfma_f32_16x16x32_bf16 v[0:3], v[210:213], v[192:195], v[0:3]
	v_mfma_f32_16x16x32_bf16 v[52:55], v[206:209], v[172:175], v[52:55]
	v_mfma_f32_16x16x32_bf16 v[44:47], v[214:217], v[172:175], v[44:47]
	v_mfma_f32_16x16x32_bf16 v[36:39], v[206:209], v[180:183], v[36:39]
	v_mfma_f32_16x16x32_bf16 v[28:31], v[214:217], v[180:183], v[28:31]
	v_mfma_f32_16x16x32_bf16 v[20:23], v[206:209], v[188:191], v[20:23]
	v_mfma_f32_16x16x32_bf16 v[12:15], v[214:217], v[188:191], v[12:15]
	v_mfma_f32_16x16x32_bf16 v[4:7], v[206:209], v[196:199], v[4:7]
	v_mfma_f32_16x16x32_bf16 v[0:3], v[214:217], v[196:199], v[0:3]
	s_setprio 0
	s_add_i32 s51, s51, 2
	s_add_u32 s18, s18, 0x100
	s_addc_u32 s19, s19, 0
	s_add_u32 s48, s48, 0x100
	s_addc_u32 s49, s49, 0
	s_cmp_gt_u32 s51, 13
	s_barrier
; __device__ __forceinline__ unsigned cvt_pk_bf16(float lo, float hi) { unsigned r; asm volatile("v_cvt_pk_bf16_f32 %0, %1, %2" : "=v"(r) : "v"(lo), "v"(hi)); return r; }
;     __device__ __forceinline__ void operator()(const AccT& acc, const Unit& u, int wr, int wc, int fr, int fq) const {
;     ...
;         const int rbase = u.pm * 256 + wr * 64 + fr;
;         const int tb = u.pn * 256 + wc * 32 + 8 * fq;
; #pragma unroll
;         for (int ai = 0; ai < 2; ++ai)
; #pragma unroll
;             for (int m = 0; m < 4; ++m) {
;                 const int gm = rbase + ai * 128 + m * 16;
; #pragma unroll
;                 for (int bj = 0; bj < 2; ++bj) {
;                     const int t0 = tb + bj * 128;
;                     const f32x4 v0 = acc[ai][bj][m][0], v1 = acc[ai][bj][m][1];
;                     u32x4 w; w.x = cvt_pk_bf16(v0[0], v0[1]); w.y = cvt_pk_bf16(v0[2], v0[3]); w.z = cvt_pk_bf16(v1[0], v1[1]); w.w = cvt_pk_bf16(v1[2], v1[3]);
;                     *(u32x4*)(YT + ((size_t)((t0 >> 10) * 512 + gm)) * 2048 + part * 1024 + (t0 & 1023)) = w;
;                 }
;             }
	s_cbranch_scc0 .LBB0_673
	v_mov_b32_e32 v136, v147
	v_mov_b32_e32 v152, v146
	s_lshl_b32 s7, s16, 8
	s_add_i32 s7, s7, s34
	v_add_u32_e32 v152, s7, v152
	s_lshl_b32 s7, s45, 8
	s_or_b32 s7, s7, s35
	v_lshl_add_u32 v153, v136, 3, s7
	v_cvt_pk_bf16_f32 v124, v124, v125
	v_cvt_pk_bf16_f32 v125, v126, v127
	v_cvt_pk_bf16_f32 v126, v120, v121
	v_ashrrev_i32_e32 v120, 1, v153
	v_cvt_pk_bf16_f32 v127, v122, v123
	v_and_b32_e32 v122, 0xfffffe00, v120
	v_add_u32_e32 v120, v122, v152
	v_ashrrev_i32_e32 v121, 31, v120
	v_lshlrev_b64 v[120:121], 12, v[120:121]
	v_and_b32_e32 v123, 0x3f8, v153
	v_lshl_add_u64 v[120:121], s[4:5], 0, v[120:121]
	v_lshlrev_b32_e32 v136, 1, v123
	v_lshl_add_u64 v[120:121], v[120:121], 0, v[136:137]
	global_store_dwordx4 v[120:121], v[124:127], off
	v_add_u32_e32 v120, 0x80, v153
	v_cvt_pk_bf16_f32 v116, v116, v117
	v_cvt_pk_bf16_f32 v117, v118, v119
	v_cvt_pk_bf16_f32 v118, v108, v109
	v_ashrrev_i32_e32 v108, 1, v120
	v_and_b32_e32 v121, 0xfffffe00, v108
	v_add_u32_e32 v108, v121, v152
	v_ashrrev_i32_e32 v109, 31, v108
	v_lshlrev_b64 v[108:109], 12, v[108:109]
	v_cvt_pk_bf16_f32 v119, v110, v111
	v_lshl_add_u64 v[110:111], s[4:5], 0, v[108:109]
	v_and_b32_e32 v108, 0x3f8, v120
	v_lshlrev_b32_e32 v108, 1, v108
	v_mov_b32_e32 v109, v137
	v_lshl_add_u64 v[110:111], v[110:111], 0, v[108:109]
	global_store_dwordx4 v[110:111], v[116:119], off
	v_cvt_pk_bf16_f32 v110, v112, v113
	v_cvt_pk_bf16_f32 v111, v114, v115
	v_cvt_pk_bf16_f32 v112, v104, v105
	v_cvt_pk_bf16_f32 v113, v106, v107
	s_and_b64 vcc, exec, s[2:3]
	s_nop 0
	v_add_u32_e32 v116, 16, v152
	v_add_u32_e32 v104, v122, v116
	v_ashrrev_i32_e32 v105, 31, v104
	v_lshlrev_b64 v[104:105], 12, v[104:105]
	v_lshl_add_u64 v[104:105], s[4:5], 0, v[104:105]
	v_lshl_add_u64 v[104:105], v[104:105], 0, v[136:137]
	global_store_dwordx4 v[104:105], v[110:113], off
	v_cvt_pk_bf16_f32 v100, v100, v101
	v_cvt_pk_bf16_f32 v101, v102, v103
	v_cvt_pk_bf16_f32 v102, v92, v93
	v_add_u32_e32 v92, v121, v116
	v_ashrrev_i32_e32 v93, 31, v92
	v_lshlrev_b64 v[92:93], 12, v[92:93]
	v_lshl_add_u64 v[92:93], s[4:5], 0, v[92:93]
	v_lshl_add_u64 v[92:93], v[92:93], 0, v[108:109]
	v_cvt_pk_bf16_f32 v103, v94, v95
	global_store_dwordx4 v[92:93], v[100:103], off
	v_cvt_pk_bf16_f32 v92, v96, v97
	v_cvt_pk_bf16_f32 v93, v98, v99
	v_cvt_pk_bf16_f32 v94, v88, v89
	v_cvt_pk_bf16_f32 v95, v90, v91
	s_mov_b32 s45, s6
	s_nop 0
	v_add_u32_e32 v100, 32, v152
	v_add_u32_e32 v88, v122, v100
	v_ashrrev_i32_e32 v89, 31, v88
	v_lshlrev_b64 v[88:89], 12, v[88:89]
	v_lshl_add_u64 v[88:89], s[4:5], 0, v[88:89]
	v_lshl_add_u64 v[88:89], v[88:89], 0, v[136:137]
	global_store_dwordx4 v[88:89], v[92:95], off
	v_cvt_pk_bf16_f32 v84, v84, v85
	v_cvt_pk_bf16_f32 v85, v86, v87
	v_cvt_pk_bf16_f32 v86, v76, v77
	v_add_u32_e32 v76, v121, v100
	v_ashrrev_i32_e32 v77, 31, v76
	v_lshlrev_b64 v[76:77], 12, v[76:77]
	v_lshl_add_u64 v[76:77], s[4:5], 0, v[76:77]
	v_lshl_add_u64 v[76:77], v[76:77], 0, v[108:109]
	v_cvt_pk_bf16_f32 v87, v78, v79
	global_store_dwordx4 v[76:77], v[84:87], off
	v_cvt_pk_bf16_f32 v76, v80, v81
	v_cvt_pk_bf16_f32 v77, v82, v83
	v_cvt_pk_bf16_f32 v78, v72, v73
	v_cvt_pk_bf16_f32 v79, v74, v75
	s_mov_b32 s16, s8
	s_nop 0
	v_add_u32_e32 v84, 48, v152
	v_add_u32_e32 v72, v122, v84
	v_ashrrev_i32_e32 v73, 31, v72
	v_lshlrev_b64 v[72:73], 12, v[72:73]
	v_lshl_add_u64 v[72:73], s[4:5], 0, v[72:73]
	v_lshl_add_u64 v[72:73], v[72:73], 0, v[136:137]
	global_store_dwordx4 v[72:73], v[76:79], off
	v_cvt_pk_bf16_f32 v68, v68, v69
	v_cvt_pk_bf16_f32 v69, v70, v71
	v_cvt_pk_bf16_f32 v70, v64, v65
	v_add_u32_e32 v64, v121, v84
	v_ashrrev_i32_e32 v65, 31, v64
	v_lshlrev_b64 v[64:65], 12, v[64:65]
	v_lshl_add_u64 v[64:65], s[4:5], 0, v[64:65]
	v_lshl_add_u64 v[64:65], v[64:65], 0, v[108:109]
	v_cvt_pk_bf16_f32 v71, v66, v67
	global_store_dwordx4 v[64:65], v[68:71], off
	v_add_u32_e32 v64, 0x80, v152
	v_cvt_pk_bf16_f32 v60, v60, v61
	v_cvt_pk_bf16_f32 v61, v62, v63
	v_cvt_pk_bf16_f32 v62, v56, v57
	v_add_u32_e32 v56, v122, v64
	v_ashrrev_i32_e32 v57, 31, v56
	v_lshlrev_b64 v[56:57], 12, v[56:57]
	v_lshl_add_u64 v[56:57], s[4:5], 0, v[56:57]
	v_lshl_add_u64 v[56:57], v[56:57], 0, v[136:137]
	v_cvt_pk_bf16_f32 v63, v58, v59
	global_store_dwordx4 v[56:57], v[60:63], off
	v_cvt_pk_bf16_f32 v52, v52, v53
	v_cvt_pk_bf16_f32 v53, v54, v55
	v_cvt_pk_bf16_f32 v54, v44, v45
	v_add_u32_e32 v44, v121, v64
	v_ashrrev_i32_e32 v45, 31, v44
	v_lshlrev_b64 v[44:45], 12, v[44:45]
	v_lshl_add_u64 v[44:45], s[4:5], 0, v[44:45]
	v_lshl_add_u64 v[44:45], v[44:45], 0, v[108:109]
	v_cvt_pk_bf16_f32 v55, v46, v47
	global_store_dwordx4 v[44:45], v[52:55], off
	v_cvt_pk_bf16_f32 v44, v48, v49
	v_cvt_pk_bf16_f32 v45, v50, v51
	v_cvt_pk_bf16_f32 v46, v40, v41
	v_cvt_pk_bf16_f32 v47, v42, v43
	s_mov_b64 s[20:21], s[14:15]
	s_nop 0
	v_add_u32_e32 v52, 0x90, v152
	v_add_u32_e32 v40, v122, v52
	v_ashrrev_i32_e32 v41, 31, v40
	v_lshlrev_b64 v[40:41], 12, v[40:41]
	v_lshl_add_u64 v[40:41], s[4:5], 0, v[40:41]
	v_lshl_add_u64 v[40:41], v[40:41], 0, v[136:137]
	global_store_dwordx4 v[40:41], v[44:47], off
	v_cvt_pk_bf16_f32 v36, v36, v37
	v_cvt_pk_bf16_f32 v37, v38, v39
	v_cvt_pk_bf16_f32 v38, v28, v29
	v_add_u32_e32 v28, v121, v52
	v_ashrrev_i32_e32 v29, 31, v28
	v_lshlrev_b64 v[28:29], 12, v[28:29]
	v_lshl_add_u64 v[28:29], s[4:5], 0, v[28:29]
	v_lshl_add_u64 v[28:29], v[28:29], 0, v[108:109]
	v_cvt_pk_bf16_f32 v39, v30, v31
	global_store_dwordx4 v[28:29], v[36:39], off
	v_cvt_pk_bf16_f32 v28, v32, v33
	v_cvt_pk_bf16_f32 v29, v34, v35
	v_cvt_pk_bf16_f32 v30, v24, v25
	v_cvt_pk_bf16_f32 v31, v26, v27
	s_mov_b64 s[18:19], s[12:13]
	s_nop 0
	v_add_u32_e32 v36, 0xa0, v152
	v_add_u32_e32 v24, v122, v36
	v_ashrrev_i32_e32 v25, 31, v24
	v_lshlrev_b64 v[24:25], 12, v[24:25]
	v_lshl_add_u64 v[24:25], s[4:5], 0, v[24:25]
	v_lshl_add_u64 v[24:25], v[24:25], 0, v[136:137]
	global_store_dwordx4 v[24:25], v[28:31], off
	v_cvt_pk_bf16_f32 v20, v20, v21
	v_cvt_pk_bf16_f32 v21, v22, v23
	v_cvt_pk_bf16_f32 v22, v12, v13
	v_add_u32_e32 v12, v121, v36
	v_ashrrev_i32_e32 v13, 31, v12
	v_lshlrev_b64 v[12:13], 12, v[12:13]
	v_lshl_add_u64 v[12:13], s[4:5], 0, v[12:13]
	v_lshl_add_u64 v[12:13], v[12:13], 0, v[108:109]
	v_cvt_pk_bf16_f32 v23, v14, v15
	global_store_dwordx4 v[12:13], v[20:23], off
	v_cvt_pk_bf16_f32 v12, v16, v17
	v_cvt_pk_bf16_f32 v13, v18, v19
	v_cvt_pk_bf16_f32 v14, v8, v9
	v_cvt_pk_bf16_f32 v15, v10, v11
	s_nop 1
	v_add_u32_e32 v20, 0xb0, v152
	v_add_u32_e32 v8, v122, v20
	v_ashrrev_i32_e32 v9, 31, v8
	v_lshlrev_b64 v[8:9], 12, v[8:9]
	v_lshl_add_u64 v[8:9], s[4:5], 0, v[8:9]
	v_lshl_add_u64 v[8:9], v[8:9], 0, v[136:137]
	global_store_dwordx4 v[8:9], v[12:15], off
	v_cvt_pk_bf16_f32 v4, v4, v5
	v_cvt_pk_bf16_f32 v5, v6, v7
	v_cvt_pk_bf16_f32 v6, v0, v1
	v_add_u32_e32 v0, v121, v20
	v_ashrrev_i32_e32 v1, 31, v0
	v_lshlrev_b64 v[0:1], 12, v[0:1]
	v_lshl_add_u64 v[0:1], s[4:5], 0, v[0:1]
	v_lshl_add_u64 v[0:1], v[0:1], 0, v[108:109]
	v_cvt_pk_bf16_f32 v7, v2, v3
	global_store_dwordx4 v[0:1], v[4:7], off
	s_cbranch_vccz .LBB0_666
; #define PG8_WAIT_V(n) asm volatile("s_waitcnt vmcnt(" #n ")" ::: "memory")
; #define PG8_BAR __builtin_amdgcn_s_barrier()
; template <class Epi, class Sched>
; __device__ __forceinline__ void gemm_phase(LAS unsigned char* lds, const Gemm g, const Sched& S, const Epi& E) {
;     ...
;     PG8_WAIT_V(0);
;     if (wr == 0) PG8_BAR;
;     PG8_BAR;
	s_waitcnt vmcnt(0)
	s_cmpk_gt_u32 s24, 0xff
	s_cbranch_scc1 .LBB0_677
	s_barrier

; #define PG8_STAGE(bufoff, gbase, voff) do { _Pragma("unroll") for (int _i = 0; _i < 2; ++_i) \
;         __builtin_amdgcn_global_load_lds((const unsigned*)((const char*)(gbase) + (voff)[_i]), (LAS unsigned*)(lds + (bufoff) + ldsw + _i * 8192), 16, 0, 0); } while (0)
; #define PG8_LDA(dst, b, h) do { _Pragma("unroll") for (int m = 0; m < 4; ++m) _Pragma("unroll") for (int k = 0; k < 2; ++k) dst[m][k] = *(const LAS bf16x8*)(lds + PG8_SA(b, h) + aoff + m * 2048 + k * 1024); } while (0)
; #define PG8_LDB(dst, b, h) do { _Pragma("unroll") for (int n = 0; n < 2; ++n) _Pragma("unroll") for (int k = 0; k < 2; ++k) dst[n][k] = *(const LAS bf16x8*)(lds + PG8_SB(b, h) + boff + n * 2048 + k * 1024); } while (0)
; #define PG8_WAIT_V(n) asm volatile("s_waitcnt vmcnt(" #n ")" ::: "memory")
; #define PG8_WAIT_L(n) asm volatile("s_waitcnt lgkmcnt(" #n ")" ::: "memory")
; #define PG8_BAR __builtin_amdgcn_s_barrier()
; #define PG8_SCHED __builtin_amdgcn_sched_barrier(0)
; template <class Epi, class Sched>
; __device__ __forceinline__ void gemm_phase(LAS unsigned char* lds, const Gemm g, const Sched& S, const Epi& E) {
;     ...
;     for (;;) {
;         const bool has_next = S.next(ui + 1, nxt);
;         const char* nA = has_next ? (const char*)g.A + (size_t)nxt.pm * tstep : cA; const char* nB = has_next ? (const char*)g.Bt + (size_t)nxt.pn * tstep : cB;
;         for (int t = 0; t < nt; t += 2) {
;             const bool last = (t == nt - 2);
;             const char* a1 = cA + (size_t)(t + 1) * kstep;
;             const char* a2 = last ? nA : cA + (size_t)(t + 2) * kstep; const char* b2 = last ? nB : cB + (size_t)(t + 2) * kstep;
;             const char* a3 = a2 + kstep; const char* b3 = b2 + kstep;
;             PG8_LDB(B0, 0, 0); PG8_SCHED; PG8_LDA(At, 0, 0); PG8_STAGE(PG8_SA(1, 1), a1 + hstep, voffA);
;             PG8_WAIT_L(8); PG8_BAR; PG8_WAIT_L(0); PG8_MMA(0, 0, At, B0); PG8_BAR; PG8_SCHED;
;             PG8_LDB(B1, 0, 1); PG8_STAGE(PG8_SB(0, 0), b2, voffB);
;             PG8_BAR; PG8_WAIT_L(0); PG8_MMA(0, 1, At, B1); PG8_BAR;
;             PG8_LDA(At, 0, 1); PG8_STAGE(PG8_SA(0, 0), a2, voffA);
;             PG8_BAR; PG8_WAIT_L(0); PG8_MMA(1, 0, At, B0); PG8_BAR; PG8_SCHED;
;             PG8_STAGE(PG8_SB(0, 1), b2 + hstep, voffB);
;             PG8_WAIT_V(6); PG8_BAR; PG8_MMA(1, 1, At, B1); PG8_BAR;
.LBB0_692:
	s_ashr_i32 s19, s18, 31
	v_cmp_lt_i64_e64 s[24:25], s[20:21], 32
	s_lshl_b64 s[20:21], s[18:19], 19
	s_add_u32 s20, s40, s20
	s_addc_u32 s21, s41, s21
	s_and_b64 s[22:23], s[24:25], exec
	s_cselect_b32 s19, s21, s3
	s_cselect_b32 s57, s20, s2
	s_ashr_i32 s17, s16, 31
	s_lshl_b64 s[22:23], s[16:17], 19
	s_add_u32 s22, s28, s22
	s_addc_u32 s23, s29, s23
	s_and_b64 s[24:25], s[24:25], exec
	s_cselect_b32 s17, s23, s5
	s_cselect_b32 s58, s22, s4
	s_add_u32 s2, s2, 0x40080
	s_addc_u32 s3, s3, 0
	s_add_u32 s59, s4, 0x100
	s_addc_u32 s60, s5, 0
	s_mov_b32 s61, -2
	s_waitcnt lgkmcnt(0)
	ds_read_b128 v[140:143], v149
	ds_read_b128 v[154:157], v149 offset:1024
	ds_read_b128 v[158:161], v149 offset:2048
	ds_read_b128 v[162:165], v149 offset:3072
	s_add_u32 s4, s2, 0xfffc0080
	s_addc_u32 s5, s3, -1
	s_cmp_eq_u32 s61, 12
	s_cselect_b32 s25, s19, s5
	s_cselect_b32 s24, s57, s4
	s_cselect_b32 s5, s17, s60
	s_cselect_b32 s4, s58, s59
	s_add_i32 m0, s33, 0xc000
	ds_read_b128 v[166:169], v150
	ds_read_b128 v[170:173], v150 offset:1024
	ds_read_b128 v[174:177], v150 offset:2048
	ds_read_b128 v[178:181], v150 offset:3072
	ds_read_b128 v[182:185], v150 offset:4096
	ds_read_b128 v[186:189], v150 offset:5120
	ds_read_b128 v[190:193], v150 offset:6144
	ds_read_b128 v[194:197], v150 offset:7168
	global_load_lds_dwordx4 v136, s[2:3]
	s_add_i32 m0, s33, 0xe000
	s_nop 0
	global_load_lds_dwordx4 v138, s[2:3]
	s_waitcnt lgkmcnt(8)
	s_waitcnt vmcnt(8)
	s_setprio 1
	s_barrier
	s_waitcnt lgkmcnt(0)
	s_waitcnt lgkmcnt(0)
	v_mfma_f32_16x16x32_bf16 v[124:127], v[140:143], v[166:169], 0
	v_mfma_f32_16x16x32_bf16 v[120:123], v[158:161], v[166:169], 0
	v_mfma_f32_16x16x32_bf16 v[108:111], v[140:143], v[174:177], 0
	v_mfma_f32_16x16x32_bf16 v[104:107], v[158:161], v[174:177], 0
	v_mfma_f32_16x16x32_bf16 v[92:95], v[140:143], v[182:185], 0
	v_mfma_f32_16x16x32_bf16 v[88:91], v[158:161], v[182:185], 0
	v_mfma_f32_16x16x32_bf16 v[76:79], v[140:143], v[190:193], 0
	v_mfma_f32_16x16x32_bf16 v[72:75], v[158:161], v[190:193], 0
	v_mfma_f32_16x16x32_bf16 v[124:127], v[154:157], v[170:173], v[124:127]
	v_mfma_f32_16x16x32_bf16 v[120:123], v[162:165], v[170:173], v[120:123]
	v_mfma_f32_16x16x32_bf16 v[108:111], v[154:157], v[178:181], v[108:111]
	v_mfma_f32_16x16x32_bf16 v[104:107], v[162:165], v[178:181], v[104:107]
	v_mfma_f32_16x16x32_bf16 v[92:95], v[154:157], v[186:189], v[92:95]
	v_mfma_f32_16x16x32_bf16 v[88:91], v[162:165], v[186:189], v[88:91]
	v_mfma_f32_16x16x32_bf16 v[76:79], v[154:157], v[194:197], v[76:79]
	v_mfma_f32_16x16x32_bf16 v[72:75], v[162:165], v[194:197], v[72:75]
	s_setprio 0
	s_barrier
	s_add_i32 s62, s47, s31
	s_mov_b32 m0, s62
	ds_read_b128 v[202:205], v151
	ds_read_b128 v[206:209], v151 offset:1024
	ds_read_b128 v[210:213], v151 offset:2048
	ds_read_b128 v[214:217], v151 offset:3072
	global_load_lds_dwordx4 v130, s[4:5]
	s_add_i32 m0, s62, 0x2000
	s_nop 0
	global_load_lds_dwordx4 v134, s[4:5]
	s_waitcnt vmcnt(8)
	s_setprio 1
	s_barrier
	s_waitcnt lgkmcnt(0)
	s_waitcnt lgkmcnt(0)
	v_mfma_f32_16x16x32_bf16 v[116:119], v[202:205], v[166:169], 0
	v_mfma_f32_16x16x32_bf16 v[112:115], v[210:213], v[166:169], 0
	v_mfma_f32_16x16x32_bf16 v[100:103], v[202:205], v[174:177], 0
	v_mfma_f32_16x16x32_bf16 v[96:99], v[210:213], v[174:177], 0
	v_mfma_f32_16x16x32_bf16 v[84:87], v[202:205], v[182:185], 0
	v_mfma_f32_16x16x32_bf16 v[80:83], v[210:213], v[182:185], 0
	v_mfma_f32_16x16x32_bf16 v[68:71], v[202:205], v[190:193], 0
	v_mfma_f32_16x16x32_bf16 v[64:67], v[210:213], v[190:193], 0
	v_mfma_f32_16x16x32_bf16 v[116:119], v[206:209], v[170:173], v[116:119]
	v_mfma_f32_16x16x32_bf16 v[112:115], v[214:217], v[170:173], v[112:115]
	v_mfma_f32_16x16x32_bf16 v[100:103], v[206:209], v[178:181], v[100:103]
	v_mfma_f32_16x16x32_bf16 v[96:99], v[214:217], v[178:181], v[96:99]
	v_mfma_f32_16x16x32_bf16 v[84:87], v[206:209], v[186:189], v[84:87]
	v_mfma_f32_16x16x32_bf16 v[80:83], v[214:217], v[186:189], v[80:83]
	v_mfma_f32_16x16x32_bf16 v[68:71], v[206:209], v[194:197], v[68:71]
	v_mfma_f32_16x16x32_bf16 v[64:67], v[214:217], v[194:197], v[64:67]
	s_setprio 0
	s_mov_b32 m0, s33
	v_lshl_add_u64 v[218:219], s[24:25], 0, v[128:129]
	s_barrier
	ds_read_b128 v[166:169], v150 offset:16384
	ds_read_b128 v[170:173], v150 offset:17408
	ds_read_b128 v[174:177], v150 offset:18432
	ds_read_b128 v[178:181], v150 offset:19456
	ds_read_b128 v[182:185], v150 offset:20480
	ds_read_b128 v[186:189], v150 offset:21504
	ds_read_b128 v[190:193], v150 offset:22528
	ds_read_b128 v[194:197], v150 offset:23552
	global_load_lds_dwordx4 v128, s[24:25]
	v_lshl_add_u64 v[220:221], s[24:25], 0, v[132:133]
	s_mov_b32 m0, s34
	s_nop 0
	global_load_lds_dwordx4 v132, s[24:25]
	s_setprio 1
	s_barrier
	s_waitcnt lgkmcnt(0)
	s_waitcnt lgkmcnt(0)
	v_mfma_f32_16x16x32_bf16 v[60:63], v[140:143], v[166:169], 0
	v_mfma_f32_16x16x32_bf16 v[56:59], v[158:161], v[166:169], 0
	v_mfma_f32_16x16x32_bf16 v[44:47], v[140:143], v[174:177], 0
	v_mfma_f32_16x16x32_bf16 v[40:43], v[158:161], v[174:177], 0
	v_mfma_f32_16x16x32_bf16 v[28:31], v[140:143], v[182:185], 0
	v_mfma_f32_16x16x32_bf16 v[24:27], v[158:161], v[182:185], 0
	v_mfma_f32_16x16x32_bf16 v[12:15], v[140:143], v[190:193], 0
	v_mfma_f32_16x16x32_bf16 v[8:11], v[158:161], v[190:193], 0
	v_mfma_f32_16x16x32_bf16 v[60:63], v[154:157], v[170:173], v[60:63]
	v_mfma_f32_16x16x32_bf16 v[56:59], v[162:165], v[170:173], v[56:59]
	v_mfma_f32_16x16x32_bf16 v[44:47], v[154:157], v[178:181], v[44:47]
	v_mfma_f32_16x16x32_bf16 v[40:43], v[162:165], v[178:181], v[40:43]
	v_mfma_f32_16x16x32_bf16 v[28:31], v[154:157], v[186:189], v[28:31]
	v_mfma_f32_16x16x32_bf16 v[24:27], v[162:165], v[186:189], v[24:27]
	v_mfma_f32_16x16x32_bf16 v[12:15], v[154:157], v[194:197], v[12:15]
	v_mfma_f32_16x16x32_bf16 v[8:11], v[162:165], v[194:197], v[8:11]
	s_setprio 0
	s_barrier
; #define PG8_STAGE(bufoff, gbase, voff) do { _Pragma("unroll") for (int _i = 0; _i < 2; ++_i) \
;         __builtin_amdgcn_global_load_lds((const unsigned*)((const char*)(gbase) + (voff)[_i]), (LAS unsigned*)(lds + (bufoff) + ldsw + _i * 8192), 16, 0, 0); } while (0)
; #define PG8_LDA(dst, b, h) do { _Pragma("unroll") for (int m = 0; m < 4; ++m) _Pragma("unroll") for (int k = 0; k < 2; ++k) dst[m][k] = *(const LAS bf16x8*)(lds + PG8_SA(b, h) + aoff + m * 2048 + k * 1024); } while (0)
; #define PG8_LDB(dst, b, h) do { _Pragma("unroll") for (int n = 0; n < 2; ++n) _Pragma("unroll") for (int k = 0; k < 2; ++k) dst[n][k] = *(const LAS bf16x8*)(lds + PG8_SB(b, h) + boff + n * 2048 + k * 1024); } while (0)
; #define PG8_MMA(ai, bj, At, Bt) do { __builtin_amdgcn_s_setprio(1); _Pragma("unroll") for (int m = 0; m < 4; ++m) _Pragma("unroll") for (int n = 0; n < 2; ++n) _Pragma("unroll") for (int k = 0; k < 2; ++k) \
;         acc[ai][bj][m][n] = __builtin_amdgcn_mfma_f32_16x16x32_bf16(Bt[n][k], At[m][k], acc[ai][bj][m][n], 0, 0, 0); __builtin_amdgcn_s_setprio(0); } while (0)
; #define PG8_WAIT_V(n) asm volatile("s_waitcnt vmcnt(" #n ")" ::: "memory")
; #define PG8_WAIT_L(n) asm volatile("s_waitcnt lgkmcnt(" #n ")" ::: "memory")
; #define PG8_BAR __builtin_amdgcn_s_barrier()
; #define PG8_SCHED __builtin_amdgcn_sched_barrier(0)
; template <class Epi, class Sched>
; __device__ __forceinline__ void gemm_phase(LAS unsigned char* lds, const Gemm g, const Sched& S, const Epi& E) {
;     ...
;             PG8_BAR; PG8_WAIT_L(0); PG8_MMA(1, 0, At, B0); PG8_BAR; PG8_SCHED;
;             PG8_STAGE(PG8_SB(0, 1), b2 + hstep, voffB);
;             PG8_WAIT_V(6); PG8_BAR; PG8_MMA(1, 1, At, B1); PG8_BAR;
;             PG8_LDB(B0, 1, 0); PG8_SCHED; PG8_LDA(At, 1, 0); PG8_STAGE(PG8_SA(0, 1), a2 + hstep, voffA);
;             PG8_WAIT_L(8); PG8_BAR; PG8_WAIT_L(0); PG8_MMA(0, 0, At, B0); PG8_BAR; PG8_SCHED;
;             PG8_LDB(B1, 1, 1); PG8_STAGE(PG8_SB(1, 0), b3, voffB);
;             PG8_BAR; PG8_WAIT_L(0); PG8_MMA(0, 1, At, B1); PG8_BAR;
;             PG8_LDA(At, 1, 1); PG8_STAGE(PG8_SA(1, 0), a3, voffA);
;             PG8_BAR; PG8_WAIT_L(0); PG8_MMA(1, 0, At, B0); PG8_BAR; PG8_SCHED;
;             PG8_STAGE(PG8_SB(1, 1), b3 + hstep, voffB);
;             PG8_WAIT_V(6); PG8_BAR; PG8_MMA(1, 1, At, B1); PG8_BAR;
	s_add_u32 s62, s4, 0x40000
	s_addc_u32 s63, s5, 0
	s_add_i32 s64, s48, s31
	s_mov_b32 m0, s64
	s_nop 0
	global_load_lds_dwordx4 v130, s[62:63]
	s_add_i32 m0, s64, 0x2000
	s_nop 0
	global_load_lds_dwordx4 v134, s[62:63]
	s_add_u32 s24, s24, 0x40000
	s_addc_u32 s25, s25, 0
	s_mov_b32 m0, s35
	s_nop 0
	global_load_lds_dwordx4 v128, s[24:25]
	s_mov_b32 m0, s36
	s_nop 0
	global_load_lds_dwordx4 v132, s[24:25]
	s_waitcnt vmcnt(10)
	s_setprio 1
	s_barrier
	v_mfma_f32_16x16x32_bf16 v[52:55], v[202:205], v[166:169], 0
	v_mfma_f32_16x16x32_bf16 v[48:51], v[210:213], v[166:169], 0
	v_mfma_f32_16x16x32_bf16 v[36:39], v[202:205], v[174:177], 0
	v_mfma_f32_16x16x32_bf16 v[32:35], v[210:213], v[174:177], 0
	v_mfma_f32_16x16x32_bf16 v[20:23], v[202:205], v[182:185], 0
	v_mfma_f32_16x16x32_bf16 v[16:19], v[210:213], v[182:185], 0
	v_mfma_f32_16x16x32_bf16 v[4:7], v[202:205], v[190:193], 0
	v_mfma_f32_16x16x32_bf16 v[0:3], v[210:213], v[190:193], 0
	v_mfma_f32_16x16x32_bf16 v[52:55], v[206:209], v[170:173], v[52:55]
	v_mfma_f32_16x16x32_bf16 v[48:51], v[214:217], v[170:173], v[48:51]
	v_mfma_f32_16x16x32_bf16 v[36:39], v[206:209], v[178:181], v[36:39]
	v_mfma_f32_16x16x32_bf16 v[32:35], v[214:217], v[178:181], v[32:35]
	v_mfma_f32_16x16x32_bf16 v[20:23], v[206:209], v[186:189], v[20:23]
	v_mfma_f32_16x16x32_bf16 v[16:19], v[214:217], v[186:189], v[16:19]
	v_mfma_f32_16x16x32_bf16 v[4:7], v[206:209], v[194:197], v[4:7]
	v_mfma_f32_16x16x32_bf16 v[0:3], v[214:217], v[194:197], v[0:3]
	s_setprio 0
	s_add_i32 s62, 0, 0x18000
	v_add_u32_e32 v162, s62, v148
	s_barrier
	ds_read_b128 v[140:143], v162
	ds_read_b128 v[154:157], v162 offset:1024
	ds_read_b128 v[158:161], v162 offset:2048
	ds_read_b128 v[162:165], v162 offset:3072
	ds_read_b128 v[166:169], v150 offset:32768
	ds_read_b128 v[170:173], v150 offset:33792
	ds_read_b128 v[174:177], v150 offset:34816
	ds_read_b128 v[178:181], v150 offset:35840
	ds_read_b128 v[182:185], v150 offset:36864
	ds_read_b128 v[186:189], v150 offset:37888
	ds_read_b128 v[190:193], v150 offset:38912
	ds_read_b128 v[194:197], v150 offset:39936
	s_waitcnt lgkmcnt(8)
	s_waitcnt vmcnt(8)
	s_setprio 1
	s_barrier
	s_waitcnt lgkmcnt(0)
	s_waitcnt lgkmcnt(0)
	v_mfma_f32_16x16x32_bf16 v[124:127], v[140:143], v[166:169], v[124:127]
	v_mfma_f32_16x16x32_bf16 v[120:123], v[158:161], v[166:169], v[120:123]
	v_mfma_f32_16x16x32_bf16 v[108:111], v[140:143], v[174:177], v[108:111]
	v_mfma_f32_16x16x32_bf16 v[104:107], v[158:161], v[174:177], v[104:107]
	v_mfma_f32_16x16x32_bf16 v[92:95], v[140:143], v[182:185], v[92:95]
	v_mfma_f32_16x16x32_bf16 v[88:91], v[158:161], v[182:185], v[88:91]
	v_mfma_f32_16x16x32_bf16 v[76:79], v[140:143], v[190:193], v[76:79]
	v_mfma_f32_16x16x32_bf16 v[72:75], v[158:161], v[190:193], v[72:75]
	v_mfma_f32_16x16x32_bf16 v[124:127], v[154:157], v[170:173], v[124:127]
	v_mfma_f32_16x16x32_bf16 v[120:123], v[162:165], v[170:173], v[120:123]
	v_mfma_f32_16x16x32_bf16 v[108:111], v[154:157], v[178:181], v[108:111]
	v_mfma_f32_16x16x32_bf16 v[104:107], v[162:165], v[178:181], v[104:107]
	v_mfma_f32_16x16x32_bf16 v[92:95], v[154:157], v[186:189], v[92:95]
	v_mfma_f32_16x16x32_bf16 v[88:91], v[162:165], v[186:189], v[88:91]
	v_mfma_f32_16x16x32_bf16 v[76:79], v[154:157], v[194:197], v[76:79]
	v_mfma_f32_16x16x32_bf16 v[72:75], v[162:165], v[194:197], v[72:75]
	s_setprio 0
	s_barrier
	s_add_i32 s24, 0, 0x1c000
	s_add_i32 s25, s62, s31
	v_add_u32_e32 v214, s24, v148
	s_add_u32 s0, s4, 0x80
	s_addc_u32 s1, s5, 0
	s_mov_b32 m0, s25
	ds_read_b128 v[202:205], v214
	ds_read_b128 v[206:209], v214 offset:1024
	ds_read_b128 v[210:213], v214 offset:2048
	ds_read_b128 v[214:217], v214 offset:3072
	global_load_lds_dwordx4 v130, s[0:1]
	s_add_i32 m0, s25, 0x2000
	s_nop 0
	global_load_lds_dwordx4 v134, s[0:1]
	s_waitcnt vmcnt(8)
	s_setprio 1
	s_barrier
	s_waitcnt lgkmcnt(0)
	s_waitcnt lgkmcnt(0)
	v_mfma_f32_16x16x32_bf16 v[116:119], v[202:205], v[166:169], v[116:119]
	v_mfma_f32_16x16x32_bf16 v[112:115], v[210:213], v[166:169], v[112:115]
	v_mfma_f32_16x16x32_bf16 v[100:103], v[202:205], v[174:177], v[100:103]
	v_mfma_f32_16x16x32_bf16 v[96:99], v[210:213], v[174:177], v[96:99]
	v_mfma_f32_16x16x32_bf16 v[84:87], v[202:205], v[182:185], v[84:87]
	v_mfma_f32_16x16x32_bf16 v[80:83], v[210:213], v[182:185], v[80:83]
	v_mfma_f32_16x16x32_bf16 v[68:71], v[202:205], v[190:193], v[68:71]
	v_mfma_f32_16x16x32_bf16 v[64:67], v[210:213], v[190:193], v[64:67]
	v_mfma_f32_16x16x32_bf16 v[116:119], v[206:209], v[170:173], v[116:119]
	v_mfma_f32_16x16x32_bf16 v[112:115], v[214:217], v[170:173], v[112:115]
	v_mfma_f32_16x16x32_bf16 v[100:103], v[206:209], v[178:181], v[100:103]
	v_mfma_f32_16x16x32_bf16 v[96:99], v[214:217], v[178:181], v[96:99]
	v_mfma_f32_16x16x32_bf16 v[84:87], v[206:209], v[186:189], v[84:87]
	v_mfma_f32_16x16x32_bf16 v[80:83], v[214:217], v[186:189], v[80:83]
	v_mfma_f32_16x16x32_bf16 v[68:71], v[206:209], v[194:197], v[68:71]
	v_mfma_f32_16x16x32_bf16 v[64:67], v[214:217], v[194:197], v[64:67]
	s_setprio 0
	s_mov_b32 m0, s44
	s_mov_b64 s[0:1], 0x80
	v_lshl_add_u64 v[144:145], v[218:219], 0, s[0:1]
	s_barrier
	ds_read_b128 v[166:169], v150 offset:49152
	ds_read_b128 v[170:173], v150 offset:50176
	ds_read_b128 v[174:177], v150 offset:51200
	ds_read_b128 v[178:181], v150 offset:52224
	ds_read_b128 v[182:185], v150 offset:53248
	ds_read_b128 v[186:189], v150 offset:54272
	ds_read_b128 v[190:193], v150 offset:55296
	ds_read_b128 v[194:197], v150 offset:56320
	global_load_lds_dwordx4 v[144:145], off
	v_lshl_add_u64 v[144:145], v[220:221], 0, s[0:1]
	s_mov_b32 m0, s45
	s_nop 0
	global_load_lds_dwordx4 v[144:145], off
	s_setprio 1
	s_barrier
; #define PG8_STAGE(bufoff, gbase, voff) do { _Pragma("unroll") for (int _i = 0; _i < 2; ++_i) \
;         __builtin_amdgcn_global_load_lds((const unsigned*)((const char*)(gbase) + (voff)[_i]), (LAS unsigned*)(lds + (bufoff) + ldsw + _i * 8192), 16, 0, 0); } while (0)
; #define PG8_LDA(dst, b, h) do { _Pragma("unroll") for (int m = 0; m < 4; ++m) _Pragma("unroll") for (int k = 0; k < 2; ++k) dst[m][k] = *(const LAS bf16x8*)(lds + PG8_SA(b, h) + aoff + m * 2048 + k * 1024); } while (0)
; #define PG8_WAIT_V(n) asm volatile("s_waitcnt vmcnt(" #n ")" ::: "memory")
; #define PG8_WAIT_L(n) asm volatile("s_waitcnt lgkmcnt(" #n ")" ::: "memory")
; template <class Epi, class Sched>
; __device__ __forceinline__ void gemm_phase(LAS unsigned char* lds, const Gemm g, const Sched& S, const Epi& E) {
;     ...
;         for (int t = 0; t < nt; t += 2) {
;             const bool last = (t == nt - 2);
;             const char* a1 = cA + (size_t)(t + 1) * kstep;
;             const char* a2 = last ? nA : cA + (size_t)(t + 2) * kstep; const char* b2 = last ? nB : cB + (size_t)(t + 2) * kstep;
;             const char* a3 = a2 + kstep; const char* b3 = b2 + kstep;
;             PG8_LDB(B0, 0, 0); PG8_SCHED; PG8_LDA(At, 0, 0); PG8_STAGE(PG8_SA(1, 1), a1 + hstep, voffA);
;             PG8_WAIT_L(8); PG8_BAR; PG8_WAIT_L(0); PG8_MMA(0, 0, At, B0); PG8_BAR; PG8_SCHED;
;             PG8_LDB(B1, 0, 1); PG8_STAGE(PG8_SB(0, 0), b2, voffB);
;             PG8_BAR; PG8_WAIT_L(0); PG8_MMA(0, 1, At, B1); PG8_BAR;
;             PG8_LDA(At, 0, 1); PG8_STAGE(PG8_SA(0, 0), a2, voffA);
;             PG8_BAR; PG8_WAIT_L(0); PG8_MMA(1, 0, At, B0); PG8_BAR; PG8_SCHED;
;             PG8_STAGE(PG8_SB(0, 1), b2 + hstep, voffB);
;             PG8_WAIT_V(6); PG8_BAR; PG8_MMA(1, 1, At, B1); PG8_BAR;
;             PG8_LDB(B0, 1, 0); PG8_SCHED; PG8_LDA(At, 1, 0); PG8_STAGE(PG8_SA(0, 1), a2 + hstep, voffA);
;             PG8_WAIT_L(8); PG8_BAR; PG8_WAIT_L(0); PG8_MMA(0, 0, At, B0); PG8_BAR; PG8_SCHED;
;             PG8_LDB(B1, 1, 1); PG8_STAGE(PG8_SB(1, 0), b3, voffB);
;             PG8_BAR; PG8_WAIT_L(0); PG8_MMA(0, 1, At, B1); PG8_BAR;
;             PG8_LDA(At, 1, 1); PG8_STAGE(PG8_SA(1, 0), a3, voffA);
;             PG8_BAR; PG8_WAIT_L(0); PG8_MMA(1, 0, At, B0); PG8_BAR; PG8_SCHED;
;             PG8_STAGE(PG8_SB(1, 1), b3 + hstep, voffB);
;             PG8_WAIT_V(6); PG8_BAR; PG8_MMA(1, 1, At, B1); PG8_BAR;
	s_waitcnt lgkmcnt(0)
	s_waitcnt lgkmcnt(0)
	v_mfma_f32_16x16x32_bf16 v[60:63], v[140:143], v[166:169], v[60:63]
	v_mfma_f32_16x16x32_bf16 v[56:59], v[158:161], v[166:169], v[56:59]
	v_mfma_f32_16x16x32_bf16 v[44:47], v[140:143], v[174:177], v[44:47]
	v_mfma_f32_16x16x32_bf16 v[40:43], v[158:161], v[174:177], v[40:43]
	v_mfma_f32_16x16x32_bf16 v[28:31], v[140:143], v[182:185], v[28:31]
	v_mfma_f32_16x16x32_bf16 v[24:27], v[158:161], v[182:185], v[24:27]
	v_mfma_f32_16x16x32_bf16 v[12:15], v[140:143], v[190:193], v[12:15]
	v_mfma_f32_16x16x32_bf16 v[8:11], v[158:161], v[190:193], v[8:11]
	v_mfma_f32_16x16x32_bf16 v[60:63], v[154:157], v[170:173], v[60:63]
	v_mfma_f32_16x16x32_bf16 v[56:59], v[162:165], v[170:173], v[56:59]
	v_mfma_f32_16x16x32_bf16 v[44:47], v[154:157], v[178:181], v[44:47]
	v_mfma_f32_16x16x32_bf16 v[40:43], v[162:165], v[178:181], v[40:43]
	v_mfma_f32_16x16x32_bf16 v[28:31], v[154:157], v[186:189], v[28:31]
	v_mfma_f32_16x16x32_bf16 v[24:27], v[162:165], v[186:189], v[24:27]
	v_mfma_f32_16x16x32_bf16 v[12:15], v[154:157], v[194:197], v[12:15]
	v_mfma_f32_16x16x32_bf16 v[8:11], v[162:165], v[194:197], v[8:11]
	s_setprio 0
	s_barrier
	s_add_u32 s4, s4, 0x40080
	s_addc_u32 s5, s5, 0
	s_add_i32 s24, s24, s31
	s_mov_b32 m0, s24
	s_nop 0
	global_load_lds_dwordx4 v130, s[4:5]
	s_add_i32 m0, s24, 0x2000
	s_nop 0
	global_load_lds_dwordx4 v134, s[4:5]
	s_waitcnt vmcnt(8)
	s_setprio 1
	s_barrier
	v_mfma_f32_16x16x32_bf16 v[52:55], v[202:205], v[166:169], v[52:55]
	v_mfma_f32_16x16x32_bf16 v[48:51], v[210:213], v[166:169], v[48:51]
	v_mfma_f32_16x16x32_bf16 v[36:39], v[202:205], v[174:177], v[36:39]
	v_mfma_f32_16x16x32_bf16 v[32:35], v[210:213], v[174:177], v[32:35]
	v_mfma_f32_16x16x32_bf16 v[20:23], v[202:205], v[182:185], v[20:23]
	v_mfma_f32_16x16x32_bf16 v[16:19], v[210:213], v[182:185], v[16:19]
	v_mfma_f32_16x16x32_bf16 v[4:7], v[202:205], v[190:193], v[4:7]
	v_mfma_f32_16x16x32_bf16 v[0:3], v[210:213], v[190:193], v[0:3]
	v_mfma_f32_16x16x32_bf16 v[52:55], v[206:209], v[170:173], v[52:55]
	v_mfma_f32_16x16x32_bf16 v[48:51], v[214:217], v[170:173], v[48:51]
	v_mfma_f32_16x16x32_bf16 v[36:39], v[206:209], v[178:181], v[36:39]
	v_mfma_f32_16x16x32_bf16 v[32:35], v[214:217], v[178:181], v[32:35]
	v_mfma_f32_16x16x32_bf16 v[20:23], v[206:209], v[186:189], v[20:23]
	v_mfma_f32_16x16x32_bf16 v[16:19], v[214:217], v[186:189], v[16:19]
	v_mfma_f32_16x16x32_bf16 v[4:7], v[206:209], v[194:197], v[4:7]
	v_mfma_f32_16x16x32_bf16 v[0:3], v[214:217], v[194:197], v[0:3]
	s_setprio 0
	s_add_i32 s61, s61, 2
	s_add_u32 s2, s2, 0x100
	s_addc_u32 s3, s3, 0
	s_add_u32 s59, s59, 0x100
	s_addc_u32 s60, s60, 0
	s_cmp_gt_u32 s61, 13
	s_barrier
.LBB0_693:
	ds_read_b128 v[140:143], v149
	ds_read_b128 v[154:157], v149 offset:1024
	ds_read_b128 v[158:161], v149 offset:2048
	ds_read_b128 v[162:165], v149 offset:3072
	s_add_u32 s4, s2, 0xfffc0080
	s_addc_u32 s5, s3, -1
	s_cmp_eq_u32 s61, 12
	s_cselect_b32 s25, s19, s5
	s_cselect_b32 s24, s57, s4
	s_cselect_b32 s5, s17, s60
	s_cselect_b32 s4, s58, s59
	s_add_i32 m0, s33, 0xc000
	ds_read_b128 v[166:169], v150
	ds_read_b128 v[170:173], v150 offset:1024
	ds_read_b128 v[174:177], v150 offset:2048
	ds_read_b128 v[178:181], v150 offset:3072
	ds_read_b128 v[182:185], v150 offset:4096
	ds_read_b128 v[186:189], v150 offset:5120
	ds_read_b128 v[190:193], v150 offset:6144
	ds_read_b128 v[194:197], v150 offset:7168
	global_load_lds_dwordx4 v136, s[2:3]
	s_add_i32 m0, s33, 0xe000
	s_nop 0
	global_load_lds_dwordx4 v138, s[2:3]
	s_waitcnt lgkmcnt(8)
	s_waitcnt vmcnt(8)
	s_setprio 1
	s_barrier
	s_waitcnt lgkmcnt(0)
	s_waitcnt lgkmcnt(0)
	v_mfma_f32_16x16x32_bf16 v[124:127], v[140:143], v[166:169], v[124:127]
	v_mfma_f32_16x16x32_bf16 v[120:123], v[158:161], v[166:169], v[120:123]
	v_mfma_f32_16x16x32_bf16 v[108:111], v[140:143], v[174:177], v[108:111]
	v_mfma_f32_16x16x32_bf16 v[104:107], v[158:161], v[174:177], v[104:107]
	v_mfma_f32_16x16x32_bf16 v[92:95], v[140:143], v[182:185], v[92:95]
	v_mfma_f32_16x16x32_bf16 v[88:91], v[158:161], v[182:185], v[88:91]
	v_mfma_f32_16x16x32_bf16 v[76:79], v[140:143], v[190:193], v[76:79]
	v_mfma_f32_16x16x32_bf16 v[72:75], v[158:161], v[190:193], v[72:75]
	v_mfma_f32_16x16x32_bf16 v[124:127], v[154:157], v[170:173], v[124:127]
	v_mfma_f32_16x16x32_bf16 v[120:123], v[162:165], v[170:173], v[120:123]
	v_mfma_f32_16x16x32_bf16 v[108:111], v[154:157], v[178:181], v[108:111]
	v_mfma_f32_16x16x32_bf16 v[104:107], v[162:165], v[178:181], v[104:107]
	v_mfma_f32_16x16x32_bf16 v[92:95], v[154:157], v[186:189], v[92:95]
	v_mfma_f32_16x16x32_bf16 v[88:91], v[162:165], v[186:189], v[88:91]
	v_mfma_f32_16x16x32_bf16 v[76:79], v[154:157], v[194:197], v[76:79]
	v_mfma_f32_16x16x32_bf16 v[72:75], v[162:165], v[194:197], v[72:75]
	s_setprio 0
	s_barrier
	s_add_i32 s62, s47, s31
	s_mov_b32 m0, s62
	ds_read_b128 v[202:205], v151
	ds_read_b128 v[206:209], v151 offset:1024
	ds_read_b128 v[210:213], v151 offset:2048
	ds_read_b128 v[214:217], v151 offset:3072
	global_load_lds_dwordx4 v130, s[4:5]
	s_add_i32 m0, s62, 0x2000
	s_nop 0
	global_load_lds_dwordx4 v134, s[4:5]
	s_waitcnt vmcnt(8)
	s_setprio 1
	s_barrier
; #define PG8_STAGE(bufoff, gbase, voff) do { _Pragma("unroll") for (int _i = 0; _i < 2; ++_i) \
;         __builtin_amdgcn_global_load_lds((const unsigned*)((const char*)(gbase) + (voff)[_i]), (LAS unsigned*)(lds + (bufoff) + ldsw + _i * 8192), 16, 0, 0); } while (0)
; #define PG8_LDA(dst, b, h) do { _Pragma("unroll") for (int m = 0; m < 4; ++m) _Pragma("unroll") for (int k = 0; k < 2; ++k) dst[m][k] = *(const LAS bf16x8*)(lds + PG8_SA(b, h) + aoff + m * 2048 + k * 1024); } while (0)
; #define PG8_LDB(dst, b, h) do { _Pragma("unroll") for (int n = 0; n < 2; ++n) _Pragma("unroll") for (int k = 0; k < 2; ++k) dst[n][k] = *(const LAS bf16x8*)(lds + PG8_SB(b, h) + boff + n * 2048 + k * 1024); } while (0)
; #define PG8_WAIT_V(n) asm volatile("s_waitcnt vmcnt(" #n ")" ::: "memory")
; #define PG8_WAIT_L(n) asm volatile("s_waitcnt lgkmcnt(" #n ")" ::: "memory")
; #define PG8_BAR __builtin_amdgcn_s_barrier()
; #define PG8_SCHED __builtin_amdgcn_sched_barrier(0)
; template <class Epi, class Sched>
; __device__ __forceinline__ void gemm_phase(LAS unsigned char* lds, const Gemm g, const Sched& S, const Epi& E) {
;     ...
;             PG8_LDB(B0, 0, 0); PG8_SCHED; PG8_LDA(At, 0, 0); PG8_STAGE(PG8_SA(1, 1), a1 + hstep, voffA);
;             PG8_WAIT_L(8); PG8_BAR; PG8_WAIT_L(0); PG8_MMA(0, 0, At, B0); PG8_BAR; PG8_SCHED;
;             PG8_LDB(B1, 0, 1); PG8_STAGE(PG8_SB(0, 0), b2, voffB);
;             PG8_BAR; PG8_WAIT_L(0); PG8_MMA(0, 1, At, B1); PG8_BAR;
;             PG8_LDA(At, 0, 1); PG8_STAGE(PG8_SA(0, 0), a2, voffA);
;             PG8_BAR; PG8_WAIT_L(0); PG8_MMA(1, 0, At, B0); PG8_BAR; PG8_SCHED;
;             PG8_STAGE(PG8_SB(0, 1), b2 + hstep, voffB);
;             PG8_WAIT_V(6); PG8_BAR; PG8_MMA(1, 1, At, B1); PG8_BAR;
;             PG8_LDB(B0, 1, 0); PG8_SCHED; PG8_LDA(At, 1, 0); PG8_STAGE(PG8_SA(0, 1), a2 + hstep, voffA);
;             PG8_WAIT_L(8); PG8_BAR; PG8_WAIT_L(0); PG8_MMA(0, 0, At, B0); PG8_BAR; PG8_SCHED;
;             PG8_LDB(B1, 1, 1); PG8_STAGE(PG8_SB(1, 0), b3, voffB);
;             PG8_BAR; PG8_WAIT_L(0); PG8_MMA(0, 1, At, B1); PG8_BAR;
;             PG8_LDA(At, 1, 1); PG8_STAGE(PG8_SA(1, 0), a3, voffA);
;             PG8_BAR; PG8_WAIT_L(0); PG8_MMA(1, 0, At, B0); PG8_BAR; PG8_SCHED;
;             PG8_STAGE(PG8_SB(1, 1), b3 + hstep, voffB);
;             PG8_WAIT_V(6); PG8_BAR; PG8_MMA(1, 1, At, B1); PG8_BAR;
	s_waitcnt lgkmcnt(0)
	s_waitcnt lgkmcnt(0)
	v_mfma_f32_16x16x32_bf16 v[116:119], v[202:205], v[166:169], v[116:119]
	v_mfma_f32_16x16x32_bf16 v[112:115], v[210:213], v[166:169], v[112:115]
	v_mfma_f32_16x16x32_bf16 v[100:103], v[202:205], v[174:177], v[100:103]
	v_mfma_f32_16x16x32_bf16 v[96:99], v[210:213], v[174:177], v[96:99]
	v_mfma_f32_16x16x32_bf16 v[84:87], v[202:205], v[182:185], v[84:87]
	v_mfma_f32_16x16x32_bf16 v[80:83], v[210:213], v[182:185], v[80:83]
	v_mfma_f32_16x16x32_bf16 v[68:71], v[202:205], v[190:193], v[68:71]
	v_mfma_f32_16x16x32_bf16 v[64:67], v[210:213], v[190:193], v[64:67]
	v_mfma_f32_16x16x32_bf16 v[116:119], v[206:209], v[170:173], v[116:119]
	v_mfma_f32_16x16x32_bf16 v[112:115], v[214:217], v[170:173], v[112:115]
	v_mfma_f32_16x16x32_bf16 v[100:103], v[206:209], v[178:181], v[100:103]
	v_mfma_f32_16x16x32_bf16 v[96:99], v[214:217], v[178:181], v[96:99]
	v_mfma_f32_16x16x32_bf16 v[84:87], v[206:209], v[186:189], v[84:87]
	v_mfma_f32_16x16x32_bf16 v[80:83], v[214:217], v[186:189], v[80:83]
	v_mfma_f32_16x16x32_bf16 v[68:71], v[206:209], v[194:197], v[68:71]
	v_mfma_f32_16x16x32_bf16 v[64:67], v[214:217], v[194:197], v[64:67]
	s_setprio 0
	s_mov_b32 m0, s33
	v_lshl_add_u64 v[218:219], s[24:25], 0, v[128:129]
	s_barrier
	ds_read_b128 v[166:169], v150 offset:16384
	ds_read_b128 v[170:173], v150 offset:17408
	ds_read_b128 v[174:177], v150 offset:18432
	ds_read_b128 v[178:181], v150 offset:19456
	ds_read_b128 v[182:185], v150 offset:20480
	ds_read_b128 v[186:189], v150 offset:21504
	ds_read_b128 v[190:193], v150 offset:22528
	ds_read_b128 v[194:197], v150 offset:23552
	global_load_lds_dwordx4 v128, s[24:25]
	v_lshl_add_u64 v[220:221], s[24:25], 0, v[132:133]
	s_mov_b32 m0, s34
	s_nop 0
	global_load_lds_dwordx4 v132, s[24:25]
	s_setprio 1
	s_barrier
	s_waitcnt lgkmcnt(0)
	s_waitcnt lgkmcnt(0)
	v_mfma_f32_16x16x32_bf16 v[60:63], v[140:143], v[166:169], v[60:63]
	v_mfma_f32_16x16x32_bf16 v[56:59], v[158:161], v[166:169], v[56:59]
	v_mfma_f32_16x16x32_bf16 v[44:47], v[140:143], v[174:177], v[44:47]
	v_mfma_f32_16x16x32_bf16 v[40:43], v[158:161], v[174:177], v[40:43]
	v_mfma_f32_16x16x32_bf16 v[28:31], v[140:143], v[182:185], v[28:31]
	v_mfma_f32_16x16x32_bf16 v[24:27], v[158:161], v[182:185], v[24:27]
	v_mfma_f32_16x16x32_bf16 v[12:15], v[140:143], v[190:193], v[12:15]
	v_mfma_f32_16x16x32_bf16 v[8:11], v[158:161], v[190:193], v[8:11]
	v_mfma_f32_16x16x32_bf16 v[60:63], v[154:157], v[170:173], v[60:63]
	v_mfma_f32_16x16x32_bf16 v[56:59], v[162:165], v[170:173], v[56:59]
	v_mfma_f32_16x16x32_bf16 v[44:47], v[154:157], v[178:181], v[44:47]
	v_mfma_f32_16x16x32_bf16 v[40:43], v[162:165], v[178:181], v[40:43]
	v_mfma_f32_16x16x32_bf16 v[28:31], v[154:157], v[186:189], v[28:31]
	v_mfma_f32_16x16x32_bf16 v[24:27], v[162:165], v[186:189], v[24:27]
	v_mfma_f32_16x16x32_bf16 v[12:15], v[154:157], v[194:197], v[12:15]
	v_mfma_f32_16x16x32_bf16 v[8:11], v[162:165], v[194:197], v[8:11]
	s_setprio 0
	s_barrier
	s_add_u32 s62, s4, 0x40000
	s_addc_u32 s63, s5, 0
	s_add_i32 s64, s48, s31
	s_mov_b32 m0, s64
	s_nop 0
	global_load_lds_dwordx4 v130, s[62:63]
	s_add_i32 m0, s64, 0x2000
	s_nop 0
	global_load_lds_dwordx4 v134, s[62:63]
	s_add_u32 s24, s24, 0x40000
	s_addc_u32 s25, s25, 0
	s_mov_b32 m0, s35
	s_nop 0
	global_load_lds_dwordx4 v128, s[24:25]
	s_mov_b32 m0, s36
	s_nop 0
	global_load_lds_dwordx4 v132, s[24:25]
	s_waitcnt vmcnt(10)
	s_setprio 1
	s_barrier
	v_mfma_f32_16x16x32_bf16 v[52:55], v[202:205], v[166:169], v[52:55]
	v_mfma_f32_16x16x32_bf16 v[48:51], v[210:213], v[166:169], v[48:51]
	v_mfma_f32_16x16x32_bf16 v[36:39], v[202:205], v[174:177], v[36:39]
	v_mfma_f32_16x16x32_bf16 v[32:35], v[210:213], v[174:177], v[32:35]
	v_mfma_f32_16x16x32_bf16 v[20:23], v[202:205], v[182:185], v[20:23]
	v_mfma_f32_16x16x32_bf16 v[16:19], v[210:213], v[182:185], v[16:19]
	v_mfma_f32_16x16x32_bf16 v[4:7], v[202:205], v[190:193], v[4:7]
	v_mfma_f32_16x16x32_bf16 v[0:3], v[210:213], v[190:193], v[0:3]
	v_mfma_f32_16x16x32_bf16 v[52:55], v[206:209], v[170:173], v[52:55]
	v_mfma_f32_16x16x32_bf16 v[48:51], v[214:217], v[170:173], v[48:51]
	v_mfma_f32_16x16x32_bf16 v[36:39], v[206:209], v[178:181], v[36:39]
	v_mfma_f32_16x16x32_bf16 v[32:35], v[214:217], v[178:181], v[32:35]
	v_mfma_f32_16x16x32_bf16 v[20:23], v[206:209], v[186:189], v[20:23]
	v_mfma_f32_16x16x32_bf16 v[16:19], v[214:217], v[186:189], v[16:19]
	v_mfma_f32_16x16x32_bf16 v[4:7], v[206:209], v[194:197], v[4:7]
	v_mfma_f32_16x16x32_bf16 v[0:3], v[214:217], v[194:197], v[0:3]
	s_setprio 0
	s_add_i32 s62, 0, 0x18000
	v_add_u32_e32 v162, s62, v148
	s_barrier
	ds_read_b128 v[140:143], v162
	ds_read_b128 v[154:157], v162 offset:1024
	ds_read_b128 v[158:161], v162 offset:2048
	ds_read_b128 v[162:165], v162 offset:3072
	ds_read_b128 v[166:169], v150 offset:32768
	ds_read_b128 v[170:173], v150 offset:33792
	ds_read_b128 v[174:177], v150 offset:34816
	ds_read_b128 v[178:181], v150 offset:35840
	ds_read_b128 v[182:185], v150 offset:36864
	ds_read_b128 v[186:189], v150 offset:37888
	ds_read_b128 v[190:193], v150 offset:38912
	ds_read_b128 v[194:197], v150 offset:39936
	s_waitcnt lgkmcnt(8)
	s_waitcnt vmcnt(8)
	s_setprio 1
	s_barrier
; #define PG8_STAGE(bufoff, gbase, voff) do { _Pragma("unroll") for (int _i = 0; _i < 2; ++_i) \
;         __builtin_amdgcn_global_load_lds((const unsigned*)((const char*)(gbase) + (voff)[_i]), (LAS unsigned*)(lds + (bufoff) + ldsw + _i * 8192), 16, 0, 0); } while (0)
; #define PG8_LDA(dst, b, h) do { _Pragma("unroll") for (int m = 0; m < 4; ++m) _Pragma("unroll") for (int k = 0; k < 2; ++k) dst[m][k] = *(const LAS bf16x8*)(lds + PG8_SA(b, h) + aoff + m * 2048 + k * 1024); } while (0)
; #define PG8_LDB(dst, b, h) do { _Pragma("unroll") for (int n = 0; n < 2; ++n) _Pragma("unroll") for (int k = 0; k < 2; ++k) dst[n][k] = *(const LAS bf16x8*)(lds + PG8_SB(b, h) + boff + n * 2048 + k * 1024); } while (0)
; #define PG8_MMA(ai, bj, At, Bt) do { __builtin_amdgcn_s_setprio(1); _Pragma("unroll") for (int m = 0; m < 4; ++m) _Pragma("unroll") for (int n = 0; n < 2; ++n) _Pragma("unroll") for (int k = 0; k < 2; ++k) \
;         acc[ai][bj][m][n] = __builtin_amdgcn_mfma_f32_16x16x32_bf16(Bt[n][k], At[m][k], acc[ai][bj][m][n], 0, 0, 0); __builtin_amdgcn_s_setprio(0); } while (0)
; #define PG8_WAIT_V(n) asm volatile("s_waitcnt vmcnt(" #n ")" ::: "memory")
; #define PG8_WAIT_L(n) asm volatile("s_waitcnt lgkmcnt(" #n ")" ::: "memory")
; #define PG8_BAR __builtin_amdgcn_s_barrier()
; #define PG8_SCHED __builtin_amdgcn_sched_barrier(0)
; template <class Epi, class Sched>
; __device__ __forceinline__ void gemm_phase(LAS unsigned char* lds, const Gemm g, const Sched& S, const Epi& E) {
;     ...
;             PG8_BAR; PG8_WAIT_L(0); PG8_MMA(1, 0, At, B0); PG8_BAR; PG8_SCHED;
;             PG8_STAGE(PG8_SB(0, 1), b2 + hstep, voffB);
;             PG8_WAIT_V(6); PG8_BAR; PG8_MMA(1, 1, At, B1); PG8_BAR;
;             PG8_LDB(B0, 1, 0); PG8_SCHED; PG8_LDA(At, 1, 0); PG8_STAGE(PG8_SA(0, 1), a2 + hstep, voffA);
;             PG8_WAIT_L(8); PG8_BAR; PG8_WAIT_L(0); PG8_MMA(0, 0, At, B0); PG8_BAR; PG8_SCHED;
;             PG8_LDB(B1, 1, 1); PG8_STAGE(PG8_SB(1, 0), b3, voffB);
;             PG8_BAR; PG8_WAIT_L(0); PG8_MMA(0, 1, At, B1); PG8_BAR;
;             PG8_LDA(At, 1, 1); PG8_STAGE(PG8_SA(1, 0), a3, voffA);
;             PG8_BAR; PG8_WAIT_L(0); PG8_MMA(1, 0, At, B0); PG8_BAR; PG8_SCHED;
;             PG8_STAGE(PG8_SB(1, 1), b3 + hstep, voffB);
;             PG8_WAIT_V(6); PG8_BAR; PG8_MMA(1, 1, At, B1); PG8_BAR;
	s_waitcnt lgkmcnt(0)
	s_waitcnt lgkmcnt(0)
	v_mfma_f32_16x16x32_bf16 v[124:127], v[140:143], v[166:169], v[124:127]
	v_mfma_f32_16x16x32_bf16 v[120:123], v[158:161], v[166:169], v[120:123]
	v_mfma_f32_16x16x32_bf16 v[108:111], v[140:143], v[174:177], v[108:111]
	v_mfma_f32_16x16x32_bf16 v[104:107], v[158:161], v[174:177], v[104:107]
	v_mfma_f32_16x16x32_bf16 v[92:95], v[140:143], v[182:185], v[92:95]
	v_mfma_f32_16x16x32_bf16 v[88:91], v[158:161], v[182:185], v[88:91]
	v_mfma_f32_16x16x32_bf16 v[76:79], v[140:143], v[190:193], v[76:79]
	v_mfma_f32_16x16x32_bf16 v[72:75], v[158:161], v[190:193], v[72:75]
	v_mfma_f32_16x16x32_bf16 v[124:127], v[154:157], v[170:173], v[124:127]
	v_mfma_f32_16x16x32_bf16 v[120:123], v[162:165], v[170:173], v[120:123]
	v_mfma_f32_16x16x32_bf16 v[108:111], v[154:157], v[178:181], v[108:111]
	v_mfma_f32_16x16x32_bf16 v[104:107], v[162:165], v[178:181], v[104:107]
	v_mfma_f32_16x16x32_bf16 v[92:95], v[154:157], v[186:189], v[92:95]
	v_mfma_f32_16x16x32_bf16 v[88:91], v[162:165], v[186:189], v[88:91]
	v_mfma_f32_16x16x32_bf16 v[76:79], v[154:157], v[194:197], v[76:79]
	v_mfma_f32_16x16x32_bf16 v[72:75], v[162:165], v[194:197], v[72:75]
	s_setprio 0
	s_barrier
	s_add_i32 s24, 0, 0x1c000
	s_add_i32 s25, s62, s31
	v_add_u32_e32 v214, s24, v148
	s_add_u32 s0, s4, 0x80
	s_addc_u32 s1, s5, 0
	s_mov_b32 m0, s25
	ds_read_b128 v[202:205], v214
	ds_read_b128 v[206:209], v214 offset:1024
	ds_read_b128 v[210:213], v214 offset:2048
	ds_read_b128 v[214:217], v214 offset:3072
	global_load_lds_dwordx4 v130, s[0:1]
	s_add_i32 m0, s25, 0x2000
	s_nop 0
	global_load_lds_dwordx4 v134, s[0:1]
	s_waitcnt vmcnt(8)
	s_setprio 1
	s_barrier
	s_waitcnt lgkmcnt(0)
	s_waitcnt lgkmcnt(0)
	v_mfma_f32_16x16x32_bf16 v[116:119], v[202:205], v[166:169], v[116:119]
	v_mfma_f32_16x16x32_bf16 v[112:115], v[210:213], v[166:169], v[112:115]
	v_mfma_f32_16x16x32_bf16 v[100:103], v[202:205], v[174:177], v[100:103]
	v_mfma_f32_16x16x32_bf16 v[96:99], v[210:213], v[174:177], v[96:99]
	v_mfma_f32_16x16x32_bf16 v[84:87], v[202:205], v[182:185], v[84:87]
	v_mfma_f32_16x16x32_bf16 v[80:83], v[210:213], v[182:185], v[80:83]
	v_mfma_f32_16x16x32_bf16 v[68:71], v[202:205], v[190:193], v[68:71]
	v_mfma_f32_16x16x32_bf16 v[64:67], v[210:213], v[190:193], v[64:67]
	v_mfma_f32_16x16x32_bf16 v[116:119], v[206:209], v[170:173], v[116:119]
	v_mfma_f32_16x16x32_bf16 v[112:115], v[214:217], v[170:173], v[112:115]
	v_mfma_f32_16x16x32_bf16 v[100:103], v[206:209], v[178:181], v[100:103]
	v_mfma_f32_16x16x32_bf16 v[96:99], v[214:217], v[178:181], v[96:99]
	v_mfma_f32_16x16x32_bf16 v[84:87], v[206:209], v[186:189], v[84:87]
	v_mfma_f32_16x16x32_bf16 v[80:83], v[214:217], v[186:189], v[80:83]
	v_mfma_f32_16x16x32_bf16 v[68:71], v[206:209], v[194:197], v[68:71]
	v_mfma_f32_16x16x32_bf16 v[64:67], v[214:217], v[194:197], v[64:67]
	s_setprio 0
	s_mov_b32 m0, s44
	s_mov_b64 s[0:1], 0x80
	v_lshl_add_u64 v[144:145], v[218:219], 0, s[0:1]
	s_barrier
	ds_read_b128 v[166:169], v150 offset:49152
	ds_read_b128 v[170:173], v150 offset:50176
	ds_read_b128 v[174:177], v150 offset:51200
	ds_read_b128 v[178:181], v150 offset:52224
	ds_read_b128 v[182:185], v150 offset:53248
	ds_read_b128 v[186:189], v150 offset:54272
	ds_read_b128 v[190:193], v150 offset:55296
	ds_read_b128 v[194:197], v150 offset:56320
	global_load_lds_dwordx4 v[144:145], off
	v_lshl_add_u64 v[144:145], v[220:221], 0, s[0:1]
	s_mov_b32 m0, s45
	s_nop 0
	global_load_lds_dwordx4 v[144:145], off
	s_setprio 1
	s_barrier
	s_waitcnt lgkmcnt(0)
	s_waitcnt lgkmcnt(0)
	v_mfma_f32_16x16x32_bf16 v[60:63], v[140:143], v[166:169], v[60:63]
	v_mfma_f32_16x16x32_bf16 v[56:59], v[158:161], v[166:169], v[56:59]
	v_mfma_f32_16x16x32_bf16 v[44:47], v[140:143], v[174:177], v[44:47]
	v_mfma_f32_16x16x32_bf16 v[40:43], v[158:161], v[174:177], v[40:43]
	v_mfma_f32_16x16x32_bf16 v[28:31], v[140:143], v[182:185], v[28:31]
	v_mfma_f32_16x16x32_bf16 v[24:27], v[158:161], v[182:185], v[24:27]
	v_mfma_f32_16x16x32_bf16 v[12:15], v[140:143], v[190:193], v[12:15]
	v_mfma_f32_16x16x32_bf16 v[8:11], v[158:161], v[190:193], v[8:11]
	v_mfma_f32_16x16x32_bf16 v[60:63], v[154:157], v[170:173], v[60:63]
	v_mfma_f32_16x16x32_bf16 v[56:59], v[162:165], v[170:173], v[56:59]
	v_mfma_f32_16x16x32_bf16 v[44:47], v[154:157], v[178:181], v[44:47]
	v_mfma_f32_16x16x32_bf16 v[40:43], v[162:165], v[178:181], v[40:43]
	v_mfma_f32_16x16x32_bf16 v[28:31], v[154:157], v[186:189], v[28:31]
	v_mfma_f32_16x16x32_bf16 v[24:27], v[162:165], v[186:189], v[24:27]
	v_mfma_f32_16x16x32_bf16 v[12:15], v[154:157], v[194:197], v[12:15]
	v_mfma_f32_16x16x32_bf16 v[8:11], v[162:165], v[194:197], v[8:11]
	s_setprio 0
	s_barrier
	s_add_u32 s4, s4, 0x40080
	s_addc_u32 s5, s5, 0
	s_add_i32 s24, s24, s31
	s_mov_b32 m0, s24
	s_nop 0
	global_load_lds_dwordx4 v130, s[4:5]
	s_add_i32 m0, s24, 0x2000
	s_nop 0
	global_load_lds_dwordx4 v134, s[4:5]
	s_waitcnt vmcnt(8)
	s_setprio 1
	s_barrier
	v_mfma_f32_16x16x32_bf16 v[52:55], v[202:205], v[166:169], v[52:55]
	v_mfma_f32_16x16x32_bf16 v[48:51], v[210:213], v[166:169], v[48:51]
	v_mfma_f32_16x16x32_bf16 v[36:39], v[202:205], v[174:177], v[36:39]
	v_mfma_f32_16x16x32_bf16 v[32:35], v[210:213], v[174:177], v[32:35]
	v_mfma_f32_16x16x32_bf16 v[20:23], v[202:205], v[182:185], v[20:23]
	v_mfma_f32_16x16x32_bf16 v[16:19], v[210:213], v[182:185], v[16:19]
	v_mfma_f32_16x16x32_bf16 v[4:7], v[202:205], v[190:193], v[4:7]
	v_mfma_f32_16x16x32_bf16 v[0:3], v[210:213], v[190:193], v[0:3]
	v_mfma_f32_16x16x32_bf16 v[52:55], v[206:209], v[170:173], v[52:55]
	v_mfma_f32_16x16x32_bf16 v[48:51], v[214:217], v[170:173], v[48:51]
	v_mfma_f32_16x16x32_bf16 v[36:39], v[206:209], v[178:181], v[36:39]
	v_mfma_f32_16x16x32_bf16 v[32:35], v[214:217], v[178:181], v[32:35]
	v_mfma_f32_16x16x32_bf16 v[20:23], v[206:209], v[186:189], v[20:23]
	v_mfma_f32_16x16x32_bf16 v[16:19], v[214:217], v[186:189], v[16:19]
	v_mfma_f32_16x16x32_bf16 v[4:7], v[206:209], v[194:197], v[4:7]
	v_mfma_f32_16x16x32_bf16 v[0:3], v[214:217], v[194:197], v[0:3]
	s_setprio 0
	s_add_i32 s61, s61, 2
	s_add_u32 s2, s2, 0x100
	s_addc_u32 s3, s3, 0
	s_add_u32 s59, s59, 0x100
	s_addc_u32 s60, s60, 0
	s_cmp_gt_u32 s61, 13
	s_barrier
;     __device__ __forceinline__ void operator()(const AccT& acc, const Unit& u, int wr, int wc, int fr, int fq) const {
;     ...
;         const int rbase = wr * 64 + fr;
;         const int tb = u.pn * 256 + wc * 32 + 8 * fq;
;         const int o0 = wc * 32 + 8 * fq;
;         const int j = fr & 3; const float sgn = ((fr >> 2) & 1) ? 1.0f : -1.0f;
; #pragma unroll
;         for (int ai = 0; ai < 2; ++ai) {
;             const int hh = 2 * ai + wr;
;             const float l2f = lgd[hh] * 1.4426950408889634f, l2b = lgd[4 + hh] * 1.4426950408889634f;
;             const float zf0 = exp2f((float)(127 - o0) * l2f), zfs = exp2f(-l2f), zb0 = exp2f((float)o0 * l2b), zbs = exp2f(l2b);
; #pragma unroll
;             for (int m = 0; m < 4; ++m) {
;                 const int r = rbase + ai * 128 + m * 16;
;                 const int d = 4 * (2 * m + (fr >> 3)) + j;
; #pragma unroll
;                 for (int bj = 0; bj < 2; ++bj) {
;                     const int t0 = tb + bj * 128;
;                     float v[8];
; #pragma unroll
;                     for (int jj = 0; jj < 4; ++jj) { v[jj] = acc[ai][bj][m][0][jj]; v[4 + jj] = acc[ai][bj][m][1][jj]; }
;                     if constexpr (ROPE) {
;                         const int t = t0 & 2047;
; #pragma unroll
;                         for (int hf = 0; hf < 2; ++hf) {
;                             f32x4 cs, sn;
;                             if (m < 2) { const float c1 = ropeA[(t >> 6) * 16 + d], s1 = ropeA[1024 + (t >> 6) * 16 + d]; cs = (f32x4){c1, c1, c1, c1}; sn = (f32x4){s1, s1, s1, s1}; }
;                             else { const float* cb = ropeA + 2048 + (d - 16) * 64 + (t & 63) + 4 * hf; cs = *(const f32x4*)(cb); sn = *(const f32x4*)(cb + 1024); }
; #pragma unroll
;                             for (int jj = 0; jj < 4; ++jj) { const float pr = __shfl_xor(v[4 * hf + jj], 4); v[4 * hf + jj] = v[4 * hf + jj] * cs[jj] + sgn * pr * sn[jj]; }
;                             __builtin_amdgcn_sched_barrier(0);
;                         }
;                     }
;                     float zf[8], zb[8]; zf[0] = zf0; zb[0] = zb0;
; #pragma unroll
;                     for (int jj = 1; jj < 8; ++jj) { zf[jj] = zf[jj - 1] * zfs; zb[jj] = zb[jj - 1] * zbs; }
;                     u32x4 wf, wb;
	s_cbranch_scc0 .LBB0_693
	v_mov_b32_e32 v141, v147
	v_mov_b32_e32 v140, v146
	global_load_dword v156, v131, s[6:7]
	global_load_dword v157, v131, s[6:7] offset:16
	s_lshl_b32 s2, s56, 8
	s_or_b32 s2, s2, s43
	v_add_u32_e32 v140, s42, v140
	v_lshlrev_b32_e32 v141, 3, v141
	v_add_u32_e32 v142, s2, v141
	v_add_u32_e32 v143, s43, v141
	v_ashrrev_i32_e32 v141, 31, v140
	v_sub_u32_e32 v144, 0x7f, v143
	v_lshlrev_b64 v[140:141], 14, v[140:141]
	v_cvt_f32_i32_e32 v154, v143
	v_ashrrev_i32_e32 v143, 31, v142
	v_cvt_f32_i32_e32 v155, v144
	v_lshl_add_u64 v[140:141], s[70:71], 0, v[140:141]
	s_mov_b32 s3, 0x400000
	v_lshl_add_u64 v[140:141], v[142:143], 1, v[140:141]
	v_add_co_u32_e32 v144, vcc, s3, v140
	s_mov_b64 s[4:5], 0x400000
	s_nop 0
	v_addc_co_u32_e32 v145, vcc, 0, v141, vcc
	v_lshl_add_u64 v[142:143], v[140:141], 0, s[4:5]
	s_waitcnt vmcnt(0)
	v_mul_f32_e32 v158, 0x3fb8aa3b, v156
	v_mul_f32_e32 v159, 0x3fb8aa3b, v157
	v_mul_f32_e32 v160, v158, v155
	v_cmp_lt_f32_e32 vcc, s51, v158
	v_mul_f32_e32 v162, v159, v154
	v_cmp_gt_f32_e64 s[2:3], s49, v159
	v_cndmask_b32_e32 v161, 0, v153, vcc
	v_cmp_gt_f32_e64 s[4:5], s49, v160
	v_cndmask_b32_e64 v163, 0, v153, s[2:3]
	s_and_b64 s[24:25], vcc, exec
	v_cmp_gt_f32_e32 vcc, s49, v162
	v_fmac_f32_e32 v163, 0x3fb8aa3b, v157
	v_cndmask_b32_e64 v157, 0, v153, s[4:5]
	v_cndmask_b32_e32 v162, 0, v153, vcc
	v_fmac_f32_e32 v161, 0xbfb8aa3b, v156
	v_fmac_f32_e32 v157, v158, v155
	v_fmac_f32_e32 v162, v159, v154
	v_exp_f32_e32 v161, v161
	v_exp_f32_e32 v163, v163
	v_exp_f32_e32 v157, v157
	v_exp_f32_e32 v158, v162
	v_cndmask_b32_e64 v160, 0, v152, s[4:5]
	s_cselect_b32 s4, 0xffffffc0, 0
	s_and_b64 s[2:3], s[2:3], exec
	v_cndmask_b32_e32 v156, 0, v152, vcc
	s_cselect_b32 s2, 0xffffffc0, 0
	v_ldexp_f32 v161, v161, s4
	v_ldexp_f32 v162, v163, s2
	v_ldexp_f32 v163, v157, v160
	v_ldexp_f32 v156, v158, v156
	v_mul_f32_e32 v164, v161, v163
	v_mul_f32_e32 v157, v162, v156
	v_mul_f32_e32 v158, v124, v163
	v_mul_f32_e32 v165, v124, v156
	v_mul_f32_e32 v166, v161, v164
	v_mul_f32_e32 v124, v162, v157
	v_mul_f32_e32 v159, v125, v164
	v_mul_f32_e32 v167, v125, v157
	v_mul_f32_e32 v168, v161, v166
	v_mul_f32_e32 v125, v162, v124
	v_cvt_pk_bf16_f32 v158, v158, v159
	v_mul_f32_e32 v159, v126, v166
	v_mul_f32_e32 v169, v126, v124
	v_mul_f32_e32 v170, v161, v168
	v_mul_f32_e32 v126, v162, v125
	v_mul_f32_e32 v171, v161, v170
	v_mul_f32_e32 v172, v162, v126
	v_mul_f32_e32 v160, v127, v168
	v_mul_f32_e32 v174, v161, v171
	v_mul_f32_e32 v175, v162, v172
	v_cvt_pk_bf16_f32 v159, v159, v160
	v_mul_f32_e32 v160, v120, v170
	v_mul_f32_e32 v173, v120, v126
	v_mul_f32_e32 v120, v121, v171
	v_mul_f32_e32 v177, v161, v174
	v_mul_f32_e32 v162, v162, v175
	v_mul_f32_e32 v176, v121, v172
	v_cvt_pk_bf16_f32 v160, v160, v120
	v_mul_f32_e32 v120, v122, v174
	v_mul_f32_e32 v121, v123, v177
	v_mul_f32_e32 v123, v123, v162
	v_cvt_pk_bf16_f32 v161, v120, v121
	v_mul_f32_e32 v127, v127, v125
	v_mul_f32_e32 v178, v122, v175
	v_cvt_pk_bf16_f32 v120, v165, v167
	v_cvt_pk_bf16_f32 v121, v169, v127
	v_cvt_pk_bf16_f32 v122, v173, v176
	v_cvt_pk_bf16_f32 v123, v178, v123
	global_store_dwordx4 v[140:141], v[158:161], off
	global_store_dwordx4 v[144:145], v[120:123], off
	s_nop 1
	v_mul_f32_e32 v120, v116, v163
	v_mul_f32_e32 v121, v117, v164
	v_cvt_pk_bf16_f32 v120, v120, v121
	v_mul_f32_e32 v121, v118, v166
	v_mul_f32_e32 v122, v119, v168
	v_cvt_pk_bf16_f32 v121, v121, v122
	v_mul_f32_e32 v122, v112, v170
	v_mul_f32_e32 v123, v113, v171
	v_cvt_pk_bf16_f32 v122, v122, v123
	v_mul_f32_e32 v123, v114, v174
	v_mul_f32_e32 v116, v116, v156
	v_mul_f32_e32 v117, v117, v157
	v_mul_f32_e32 v127, v115, v177
	v_cvt_pk_bf16_f32 v123, v123, v127
	v_cvt_pk_bf16_f32 v116, v116, v117
	v_mul_f32_e32 v117, v118, v124
	v_mul_f32_e32 v118, v119, v125
	v_mul_f32_e32 v112, v112, v126
	v_mul_f32_e32 v113, v113, v172
	v_cvt_pk_bf16_f32 v117, v117, v118
	v_cvt_pk_bf16_f32 v118, v112, v113
	v_mul_f32_e32 v112, v114, v175
	v_mul_f32_e32 v113, v115, v162
	v_cvt_pk_bf16_f32 v119, v112, v113
	global_store_dwordx4 v[140:141], v[120:123], off offset:256
	global_store_dwordx4 v[142:143], v[116:119], off offset:256
	v_mul_f32_e32 v112, v108, v163
	v_mul_f32_e32 v113, v109, v164
	v_cvt_pk_bf16_f32 v112, v112, v113
	v_mul_f32_e32 v113, v110, v166
	v_mul_f32_e32 v114, v111, v168
	v_cvt_pk_bf16_f32 v113, v113, v114
	v_mul_f32_e32 v114, v104, v170
	v_mul_f32_e32 v115, v105, v171
	v_cvt_pk_bf16_f32 v114, v114, v115
	v_mul_f32_e32 v115, v106, v174
	v_mul_f32_e32 v108, v108, v156
	v_mul_f32_e32 v109, v109, v157
	v_mul_f32_e32 v116, v107, v177
	v_cvt_pk_bf16_f32 v115, v115, v116
	v_cvt_pk_bf16_f32 v108, v108, v109
	v_mul_f32_e32 v109, v110, v124
	v_mul_f32_e32 v110, v111, v125
	v_mul_f32_e32 v104, v104, v126
	s_mov_b64 s[2:3], 0x40000
	v_cvt_pk_bf16_f32 v109, v109, v110
	v_mul_f32_e32 v105, v105, v172
	v_cvt_pk_bf16_f32 v110, v104, v105
	v_mul_f32_e32 v104, v106, v175
	v_lshl_add_u64 v[116:117], v[140:141], 0, s[2:3]
	s_mov_b32 s2, 0x40000
	v_mul_f32_e32 v105, v107, v162
	v_cvt_pk_bf16_f32 v111, v104, v105
	v_add_co_u32_e32 v104, vcc, s2, v140
	s_mov_b64 s[2:3], 0x440000
	s_nop 0
	v_addc_co_u32_e32 v105, vcc, 0, v141, vcc
	global_store_dwordx4 v[104:105], v[112:115], off
	s_nop 1
	v_lshl_add_u64 v[112:113], v[140:141], 0, s[2:3]
	s_mov_b32 s2, 0x440000
	v_add_co_u32_e32 v104, vcc, s2, v140
	s_nop 1
	v_addc_co_u32_e32 v105, vcc, 0, v141, vcc
	global_store_dwordx4 v[104:105], v[108:111], off
	v_mul_f32_e32 v104, v100, v163
	v_mul_f32_e32 v105, v101, v164
	v_cvt_pk_bf16_f32 v104, v104, v105
	v_mul_f32_e32 v105, v102, v166
	v_mul_f32_e32 v106, v103, v168
	v_cvt_pk_bf16_f32 v105, v105, v106
; __device__ __forceinline__ unsigned cvt_pk_bf16(float lo, float hi) { unsigned r; asm volatile("v_cvt_pk_bf16_f32 %0, %1, %2" : "=v"(r) : "v"(lo), "v"(hi)); return r; }
;     __device__ __forceinline__ void operator()(const AccT& acc, const Unit& u, int wr, int wc, int fr, int fq) const {
;     ...
;             const int hh = 2 * ai + wr;
;             const float l2f = lgd[hh] * 1.4426950408889634f, l2b = lgd[4 + hh] * 1.4426950408889634f;
;             const float zf0 = exp2f((float)(127 - o0) * l2f), zfs = exp2f(-l2f), zb0 = exp2f((float)o0 * l2b), zbs = exp2f(l2b);
;     ...
;                     float zf[8], zb[8]; zf[0] = zf0; zb[0] = zb0;
; #pragma unroll
;                     for (int jj = 1; jj < 8; ++jj) { zf[jj] = zf[jj - 1] * zfs; zb[jj] = zb[jj - 1] * zbs; }
;                     u32x4 wf, wb;
;                     wf.x = cvt_pk_bf16(v[0] * zf[0], v[1] * zf[1]); wf.y = cvt_pk_bf16(v[2] * zf[2], v[3] * zf[3]); wf.z = cvt_pk_bf16(v[4] * zf[4], v[5] * zf[5]); wf.w = cvt_pk_bf16(v[6] * zf[6], v[7] * zf[7]);
;                     wb.x = cvt_pk_bf16(v[0] * zb[0], v[1] * zb[1]); wb.y = cvt_pk_bf16(v[2] * zb[2], v[3] * zb[3]); wb.z = cvt_pk_bf16(v[4] * zb[4], v[5] * zb[5]); wb.w = cvt_pk_bf16(v[6] * zb[6], v[7] * zb[7]);
;                     *(u32x4*)(KTZ + (size_t)r * NT + t0) = wf;
;                     *(u32x4*)(KTZ + (size_t)(256 + r) * NT + t0) = wb;
	v_mul_f32_e32 v106, v96, v170
	v_mul_f32_e32 v107, v97, v171
	v_cvt_pk_bf16_f32 v106, v106, v107
	v_mul_f32_e32 v107, v98, v174
	v_mul_f32_e32 v100, v100, v156
	v_mul_f32_e32 v101, v101, v157
	v_mul_f32_e32 v108, v99, v177
	v_cvt_pk_bf16_f32 v107, v107, v108
	v_cvt_pk_bf16_f32 v100, v100, v101
	v_mul_f32_e32 v101, v102, v124
	v_mul_f32_e32 v102, v103, v125
	v_mul_f32_e32 v96, v96, v126
	v_mul_f32_e32 v97, v97, v172
	v_cvt_pk_bf16_f32 v101, v101, v102
	v_cvt_pk_bf16_f32 v102, v96, v97
	v_mul_f32_e32 v96, v98, v175
	v_mul_f32_e32 v97, v99, v162
	v_cvt_pk_bf16_f32 v103, v96, v97
	global_store_dwordx4 v[116:117], v[104:107], off offset:256
	global_store_dwordx4 v[112:113], v[100:103], off offset:256
	v_mul_f32_e32 v96, v92, v163
	v_mul_f32_e32 v97, v93, v164
	v_cvt_pk_bf16_f32 v96, v96, v97
	v_mul_f32_e32 v97, v94, v166
	v_mul_f32_e32 v98, v95, v168
	v_cvt_pk_bf16_f32 v97, v97, v98
	v_mul_f32_e32 v98, v88, v170
	v_mul_f32_e32 v99, v89, v171
	v_cvt_pk_bf16_f32 v98, v98, v99
	v_mul_f32_e32 v99, v90, v174
	v_mul_f32_e32 v92, v92, v156
	v_mul_f32_e32 v93, v93, v157
	v_mul_f32_e32 v100, v91, v177
	v_cvt_pk_bf16_f32 v99, v99, v100
	v_cvt_pk_bf16_f32 v92, v92, v93
	v_mul_f32_e32 v93, v94, v124
	v_mul_f32_e32 v94, v95, v125
	v_mul_f32_e32 v88, v88, v126
	s_mov_b64 s[2:3], 0x80000
	v_cvt_pk_bf16_f32 v93, v93, v94
	v_mul_f32_e32 v89, v89, v172
	v_cvt_pk_bf16_f32 v94, v88, v89
	v_mul_f32_e32 v88, v90, v175
	v_lshl_add_u64 v[100:101], v[140:141], 0, s[2:3]
	s_mov_b32 s2, 0x80000
	v_mul_f32_e32 v89, v91, v162
	v_cvt_pk_bf16_f32 v95, v88, v89
	v_add_co_u32_e32 v88, vcc, s2, v140
	s_mov_b64 s[2:3], 0x480000
	s_nop 0
	v_addc_co_u32_e32 v89, vcc, 0, v141, vcc
	global_store_dwordx4 v[88:89], v[96:99], off
	s_nop 1
	v_lshl_add_u64 v[96:97], v[140:141], 0, s[2:3]
	s_mov_b32 s2, 0x480000
	v_add_co_u32_e32 v88, vcc, s2, v140
	s_nop 1
	v_addc_co_u32_e32 v89, vcc, 0, v141, vcc
	global_store_dwordx4 v[88:89], v[92:95], off
	v_mul_f32_e32 v88, v84, v163
	v_mul_f32_e32 v89, v85, v164
	v_cvt_pk_bf16_f32 v88, v88, v89
	v_mul_f32_e32 v89, v86, v166
	v_mul_f32_e32 v90, v87, v168
	v_cvt_pk_bf16_f32 v89, v89, v90
	v_mul_f32_e32 v90, v80, v170
	v_mul_f32_e32 v91, v81, v171
	v_cvt_pk_bf16_f32 v90, v90, v91
	v_mul_f32_e32 v91, v82, v174
	v_mul_f32_e32 v84, v84, v156
	v_mul_f32_e32 v85, v85, v157
	v_mul_f32_e32 v92, v83, v177
	v_cvt_pk_bf16_f32 v91, v91, v92
	v_cvt_pk_bf16_f32 v84, v84, v85
	v_mul_f32_e32 v85, v86, v124
	v_mul_f32_e32 v86, v87, v125
	v_mul_f32_e32 v80, v80, v126
	v_mul_f32_e32 v81, v81, v172
	v_cvt_pk_bf16_f32 v85, v85, v86
	v_cvt_pk_bf16_f32 v86, v80, v81
	v_mul_f32_e32 v80, v82, v175
	v_mul_f32_e32 v81, v83, v162
	v_cvt_pk_bf16_f32 v87, v80, v81
	global_store_dwordx4 v[100:101], v[88:91], off offset:256
	global_store_dwordx4 v[96:97], v[84:87], off offset:256
	v_mul_f32_e32 v80, v76, v163
	v_mul_f32_e32 v81, v77, v164
	v_cvt_pk_bf16_f32 v80, v80, v81
	v_mul_f32_e32 v81, v78, v166
	v_mul_f32_e32 v82, v79, v168
	v_cvt_pk_bf16_f32 v81, v81, v82
	v_mul_f32_e32 v82, v72, v170
	v_mul_f32_e32 v83, v73, v171
	v_cvt_pk_bf16_f32 v82, v82, v83
	v_mul_f32_e32 v83, v74, v174
	v_mul_f32_e32 v76, v76, v156
	v_mul_f32_e32 v77, v77, v157
	v_mul_f32_e32 v84, v75, v177
	v_cvt_pk_bf16_f32 v83, v83, v84
	v_cvt_pk_bf16_f32 v76, v76, v77
	v_mul_f32_e32 v77, v78, v124
	v_mul_f32_e32 v78, v79, v125
	v_mul_f32_e32 v72, v72, v126
	s_mov_b64 s[2:3], 0xc0000
	v_cvt_pk_bf16_f32 v77, v77, v78
	v_mul_f32_e32 v73, v73, v172
	v_cvt_pk_bf16_f32 v78, v72, v73
	v_mul_f32_e32 v72, v74, v175
	v_lshl_add_u64 v[84:85], v[140:141], 0, s[2:3]
	s_mov_b32 s2, 0xc0000
	v_mul_f32_e32 v73, v75, v162
	v_cvt_pk_bf16_f32 v79, v72, v73
	v_add_co_u32_e32 v72, vcc, s2, v140
	s_mov_b64 s[2:3], 0x4c0000
	s_nop 0
	v_addc_co_u32_e32 v73, vcc, 0, v141, vcc
	global_store_dwordx4 v[72:73], v[80:83], off
	s_nop 1
	v_lshl_add_u64 v[80:81], v[140:141], 0, s[2:3]
	s_mov_b32 s2, 0x4c0000
	v_add_co_u32_e32 v72, vcc, s2, v140
	s_nop 1
	v_addc_co_u32_e32 v73, vcc, 0, v141, vcc
	global_store_dwordx4 v[72:73], v[76:79], off
	v_mul_f32_e32 v72, v68, v163
	v_mul_f32_e32 v73, v69, v164
	v_cvt_pk_bf16_f32 v72, v72, v73
	v_mul_f32_e32 v73, v70, v166
	v_mul_f32_e32 v74, v71, v168
	v_cvt_pk_bf16_f32 v73, v73, v74
	v_mul_f32_e32 v74, v64, v170
	v_mul_f32_e32 v75, v65, v171
	v_cvt_pk_bf16_f32 v74, v74, v75
	v_mul_f32_e32 v75, v66, v174
	v_mul_f32_e32 v68, v68, v156
	v_mul_f32_e32 v69, v69, v157
	v_mul_f32_e32 v76, v67, v177
	v_cvt_pk_bf16_f32 v75, v75, v76
	v_cvt_pk_bf16_f32 v68, v68, v69
	v_mul_f32_e32 v69, v70, v124
	v_mul_f32_e32 v70, v71, v125
	v_mul_f32_e32 v64, v64, v126
	v_mul_f32_e32 v65, v65, v172
	v_cvt_pk_bf16_f32 v69, v69, v70
	v_cvt_pk_bf16_f32 v70, v64, v65
	v_mul_f32_e32 v64, v66, v175
	v_mul_f32_e32 v65, v67, v162
	v_cvt_pk_bf16_f32 v71, v64, v65
	global_store_dwordx4 v[84:85], v[72:75], off offset:256
	global_store_dwordx4 v[80:81], v[68:71], off offset:256
	global_load_dword v70, v131, s[6:7] offset:8
	s_nop 0
	global_load_dword v71, v131, s[6:7] offset:24
	s_mov_b32 s17, 0x200000
	v_add_co_u32_e32 v76, vcc, s17, v140
	s_mov_b32 s19, 0x600000
	s_nop 0
	v_addc_co_u32_e32 v77, vcc, 0, v141, vcc
	v_add_co_u32_e32 v68, vcc, s19, v140
	s_mov_b64 s[2:3], 0x200000
	s_nop 0
	v_addc_co_u32_e32 v69, vcc, 0, v141, vcc
	s_mov_b64 s[4:5], 0x600000
	v_lshl_add_u64 v[64:65], v[140:141], 0, s[2:3]
	v_lshl_add_u64 v[66:67], v[140:141], 0, s[4:5]
	s_waitcnt vmcnt(0)
;     __device__ __forceinline__ void operator()(const AccT& acc, const Unit& u, int wr, int wc, int fr, int fq) const {
;     ...
;             const float l2f = lgd[hh] * 1.4426950408889634f, l2b = lgd[4 + hh] * 1.4426950408889634f;
;             const float zf0 = exp2f((float)(127 - o0) * l2f), zfs = exp2f(-l2f), zb0 = exp2f((float)o0 * l2b), zbs = exp2f(l2b);
; #pragma unroll
;             for (int m = 0; m < 4; ++m) {
;                 const int r = rbase + ai * 128 + m * 16;
;                 const int d = 4 * (2 * m + (fr >> 3)) + j;
; #pragma unroll
;                 for (int bj = 0; bj < 2; ++bj) {
;                     const int t0 = tb + bj * 128;
;                     float v[8];
; #pragma unroll
;                     for (int jj = 0; jj < 4; ++jj) { v[jj] = acc[ai][bj][m][0][jj]; v[4 + jj] = acc[ai][bj][m][1][jj]; }
;                     if constexpr (ROPE) {
;                         const int t = t0 & 2047;
; #pragma unroll
;                         for (int hf = 0; hf < 2; ++hf) {
;                             f32x4 cs, sn;
;                             if (m < 2) { const float c1 = ropeA[(t >> 6) * 16 + d], s1 = ropeA[1024 + (t >> 6) * 16 + d]; cs = (f32x4){c1, c1, c1, c1}; sn = (f32x4){s1, s1, s1, s1}; }
;                             else { const float* cb = ropeA + 2048 + (d - 16) * 64 + (t & 63) + 4 * hf; cs = *(const f32x4*)(cb); sn = *(const f32x4*)(cb + 1024); }
; #pragma unroll
;                             for (int jj = 0; jj < 4; ++jj) { const float pr = __shfl_xor(v[4 * hf + jj], 4); v[4 * hf + jj] = v[4 * hf + jj] * cs[jj] + sgn * pr * sn[jj]; }
;                             __builtin_amdgcn_sched_barrier(0);
;                         }
;                     }
;                     float zf[8], zb[8]; zf[0] = zf0; zb[0] = zb0;
; #pragma unroll
;                     for (int jj = 1; jj < 8; ++jj) { zf[jj] = zf[jj - 1] * zfs; zb[jj] = zb[jj - 1] * zbs; }
;                     u32x4 wf, wb;
;                     wf.x = cvt_pk_bf16(v[0] * zf[0], v[1] * zf[1]); wf.y = cvt_pk_bf16(v[2] * zf[2], v[3] * zf[3]); wf.z = cvt_pk_bf16(v[4] * zf[4], v[5] * zf[5]); wf.w = cvt_pk_bf16(v[6] * zf[6], v[7] * zf[7]);
;                     wb.x = cvt_pk_bf16(v[0] * zb[0], v[1] * zb[1]); wb.y = cvt_pk_bf16(v[2] * zb[2], v[3] * zb[3]); wb.z = cvt_pk_bf16(v[4] * zb[4], v[5] * zb[5]); wb.w = cvt_pk_bf16(v[6] * zb[6], v[7] * zb[7]);
	v_mul_f32_e32 v72, 0x3fb8aa3b, v70
	v_mul_f32_e32 v73, 0x3fb8aa3b, v71
	v_mul_f32_e32 v74, v72, v155
	v_cmp_lt_f32_e32 vcc, s51, v72
	v_mul_f32_e32 v78, v73, v154
	v_cmp_gt_f32_e64 s[2:3], s49, v73
	v_cndmask_b32_e32 v75, 0, v153, vcc
	v_cmp_gt_f32_e64 s[4:5], s49, v74
	v_cndmask_b32_e64 v79, 0, v153, s[2:3]
	s_and_b64 s[24:25], vcc, exec
	v_cmp_gt_f32_e32 vcc, s49, v78
	v_fmac_f32_e32 v79, 0x3fb8aa3b, v71
	v_cndmask_b32_e64 v71, 0, v153, s[4:5]
	v_cndmask_b32_e32 v78, 0, v153, vcc
	v_fmac_f32_e32 v75, 0xbfb8aa3b, v70
	v_fmac_f32_e32 v71, v72, v155
	v_fmac_f32_e32 v78, v73, v154
	v_exp_f32_e32 v75, v75
	v_exp_f32_e32 v79, v79
	v_exp_f32_e32 v71, v71
	v_exp_f32_e32 v72, v78
	v_cndmask_b32_e64 v74, 0, v152, s[4:5]
	s_cselect_b32 s4, 0xffffffc0, 0
	s_and_b64 s[2:3], s[2:3], exec
	v_cndmask_b32_e32 v70, 0, v152, vcc
	s_cselect_b32 s2, 0xffffffc0, 0
	v_ldexp_f32 v75, v75, s4
	v_ldexp_f32 v78, v79, s2
	v_ldexp_f32 v79, v71, v74
	v_ldexp_f32 v70, v72, v70
	v_mul_f32_e32 v80, v75, v79
	v_mul_f32_e32 v71, v78, v70
	v_mul_f32_e32 v72, v60, v79
	v_mul_f32_e32 v81, v60, v70
	v_mul_f32_e32 v82, v75, v80
	v_mul_f32_e32 v60, v78, v71
	v_mul_f32_e32 v83, v75, v82
	v_mul_f32_e32 v84, v78, v60
	v_mul_f32_e32 v85, v75, v83
	v_mul_f32_e32 v86, v78, v84
	v_mul_f32_e32 v73, v61, v80
	v_mul_f32_e32 v87, v75, v85
	v_mul_f32_e32 v88, v78, v86
	v_cvt_pk_bf16_f32 v72, v72, v73
	v_mul_f32_e32 v73, v62, v82
	v_mul_f32_e32 v74, v63, v83
	v_mul_f32_e32 v90, v75, v87
	v_mul_f32_e32 v91, v78, v88
	v_cvt_pk_bf16_f32 v73, v73, v74
	v_mul_f32_e32 v74, v56, v85
	v_mul_f32_e32 v89, v56, v86
	v_mul_f32_e32 v56, v57, v87
	v_mul_f32_e32 v93, v75, v90
	v_mul_f32_e32 v78, v78, v91
	v_mul_f32_e32 v92, v57, v88
	v_cvt_pk_bf16_f32 v74, v74, v56
	v_mul_f32_e32 v56, v58, v90
	v_mul_f32_e32 v57, v59, v93
	v_mul_f32_e32 v59, v59, v78
	v_cvt_pk_bf16_f32 v75, v56, v57
	v_mul_f32_e32 v61, v61, v71
	v_mul_f32_e32 v62, v62, v60
	v_mul_f32_e32 v63, v63, v84
	v_mul_f32_e32 v94, v58, v91
	v_cvt_pk_bf16_f32 v56, v81, v61
	v_cvt_pk_bf16_f32 v57, v62, v63
	v_cvt_pk_bf16_f32 v58, v89, v92
	v_cvt_pk_bf16_f32 v59, v94, v59
	global_store_dwordx4 v[76:77], v[72:75], off
	global_store_dwordx4 v[68:69], v[56:59], off
	s_nop 1
	v_mul_f32_e32 v56, v52, v79
	v_mul_f32_e32 v57, v53, v80
	v_cvt_pk_bf16_f32 v56, v56, v57
	v_mul_f32_e32 v57, v54, v82
	v_mul_f32_e32 v58, v55, v83
	v_cvt_pk_bf16_f32 v57, v57, v58
	v_mul_f32_e32 v58, v48, v85
	v_mul_f32_e32 v59, v49, v87
	v_cvt_pk_bf16_f32 v58, v58, v59
	v_mul_f32_e32 v59, v50, v90
	v_mul_f32_e32 v52, v52, v70
	v_mul_f32_e32 v53, v53, v71
	v_mul_f32_e32 v61, v51, v93
	v_cvt_pk_bf16_f32 v59, v59, v61
	v_cvt_pk_bf16_f32 v52, v52, v53
	v_mul_f32_e32 v53, v54, v60
	v_mul_f32_e32 v54, v55, v84
	v_mul_f32_e32 v48, v48, v86
	v_mul_f32_e32 v49, v49, v88
	v_cvt_pk_bf16_f32 v53, v53, v54
	v_cvt_pk_bf16_f32 v54, v48, v49
	v_mul_f32_e32 v48, v50, v91
	v_mul_f32_e32 v49, v51, v78
	v_cvt_pk_bf16_f32 v55, v48, v49
	global_store_dwordx4 v[64:65], v[56:59], off offset:256
	global_store_dwordx4 v[66:67], v[52:55], off offset:256
	v_mul_f32_e32 v48, v44, v79
	v_mul_f32_e32 v49, v45, v80
	v_cvt_pk_bf16_f32 v48, v48, v49
	v_mul_f32_e32 v49, v46, v82
	v_mul_f32_e32 v50, v47, v83
	v_cvt_pk_bf16_f32 v49, v49, v50
	v_mul_f32_e32 v50, v40, v85
	v_mul_f32_e32 v51, v41, v87
	v_cvt_pk_bf16_f32 v50, v50, v51
	v_mul_f32_e32 v51, v42, v90
	v_mul_f32_e32 v44, v44, v70
	v_mul_f32_e32 v45, v45, v71
	v_mul_f32_e32 v52, v43, v93
	v_cvt_pk_bf16_f32 v51, v51, v52
	v_cvt_pk_bf16_f32 v44, v44, v45
	v_mul_f32_e32 v45, v46, v60
	v_mul_f32_e32 v46, v47, v84
	v_mul_f32_e32 v40, v40, v86
	s_mov_b64 s[2:3], 0x240000
	v_cvt_pk_bf16_f32 v45, v45, v46
	v_mul_f32_e32 v41, v41, v88
	v_cvt_pk_bf16_f32 v46, v40, v41
	v_mul_f32_e32 v40, v42, v91
	v_lshl_add_u64 v[52:53], v[140:141], 0, s[2:3]
	s_mov_b32 s2, 0x240000
	v_mul_f32_e32 v41, v43, v78
	v_cvt_pk_bf16_f32 v47, v40, v41
	v_add_co_u32_e32 v40, vcc, s2, v140
	s_mov_b64 s[2:3], 0x640000
	s_nop 0
	v_addc_co_u32_e32 v41, vcc, 0, v141, vcc
	global_store_dwordx4 v[40:41], v[48:51], off
	s_nop 1
	v_lshl_add_u64 v[48:49], v[140:141], 0, s[2:3]
	s_mov_b32 s2, 0x640000
	v_add_co_u32_e32 v40, vcc, s2, v140
	s_nop 1
	v_addc_co_u32_e32 v41, vcc, 0, v141, vcc
	global_store_dwordx4 v[40:41], v[44:47], off
	v_mul_f32_e32 v40, v36, v79
	v_mul_f32_e32 v41, v37, v80
	v_cvt_pk_bf16_f32 v40, v40, v41
	v_mul_f32_e32 v41, v38, v82
	v_mul_f32_e32 v42, v39, v83
	v_cvt_pk_bf16_f32 v41, v41, v42
	v_mul_f32_e32 v42, v32, v85
	v_mul_f32_e32 v43, v33, v87
	v_cvt_pk_bf16_f32 v42, v42, v43
	v_mul_f32_e32 v43, v34, v90
	v_mul_f32_e32 v36, v36, v70
; __device__ __forceinline__ unsigned cvt_pk_bf16(float lo, float hi) { unsigned r; asm volatile("v_cvt_pk_bf16_f32 %0, %1, %2" : "=v"(r) : "v"(lo), "v"(hi)); return r; }
; #define PG8_WAIT_V(n) asm volatile("s_waitcnt vmcnt(" #n ")" ::: "memory")
; #define PG8_BAR __builtin_amdgcn_s_barrier()
; template <class Epi, class Sched>
; __device__ __forceinline__ void gemm_phase(LAS unsigned char* lds, const Gemm g, const Sched& S, const Epi& E) {
;     ...
;     PG8_WAIT_V(0);
;     if (wr == 0) PG8_BAR;
;     PG8_BAR;
;     __device__ __forceinline__ void operator()(const AccT& acc, const Unit& u, int wr, int wc, int fr, int fq) const {
;     ...
;                     float zf[8], zb[8]; zf[0] = zf0; zb[0] = zb0;
; #pragma unroll
;                     for (int jj = 1; jj < 8; ++jj) { zf[jj] = zf[jj - 1] * zfs; zb[jj] = zb[jj - 1] * zbs; }
;                     u32x4 wf, wb;
;                     wf.x = cvt_pk_bf16(v[0] * zf[0], v[1] * zf[1]); wf.y = cvt_pk_bf16(v[2] * zf[2], v[3] * zf[3]); wf.z = cvt_pk_bf16(v[4] * zf[4], v[5] * zf[5]); wf.w = cvt_pk_bf16(v[6] * zf[6], v[7] * zf[7]);
;                     wb.x = cvt_pk_bf16(v[0] * zb[0], v[1] * zb[1]); wb.y = cvt_pk_bf16(v[2] * zb[2], v[3] * zb[3]); wb.z = cvt_pk_bf16(v[4] * zb[4], v[5] * zb[5]); wb.w = cvt_pk_bf16(v[6] * zb[6], v[7] * zb[7]);
;                     *(u32x4*)(KTZ + (size_t)r * NT + t0) = wf;
;                     *(u32x4*)(KTZ + (size_t)(256 + r) * NT + t0) = wb;
;                     __builtin_amdgcn_sched_barrier(0);
;                 }
;             }
;         }
	v_mul_f32_e32 v37, v37, v71
	v_mul_f32_e32 v44, v35, v93
	v_cvt_pk_bf16_f32 v43, v43, v44
	v_cvt_pk_bf16_f32 v36, v36, v37
	v_mul_f32_e32 v37, v38, v60
	v_mul_f32_e32 v38, v39, v84
	v_mul_f32_e32 v32, v32, v86
	v_mul_f32_e32 v33, v33, v88
	v_cvt_pk_bf16_f32 v37, v37, v38
	v_cvt_pk_bf16_f32 v38, v32, v33
	v_mul_f32_e32 v32, v34, v91
	v_mul_f32_e32 v33, v35, v78
	v_cvt_pk_bf16_f32 v39, v32, v33
	global_store_dwordx4 v[52:53], v[40:43], off offset:256
	global_store_dwordx4 v[48:49], v[36:39], off offset:256
	v_mul_f32_e32 v32, v28, v79
	v_mul_f32_e32 v33, v29, v80
	v_cvt_pk_bf16_f32 v32, v32, v33
	v_mul_f32_e32 v33, v30, v82
	v_mul_f32_e32 v34, v31, v83
	v_cvt_pk_bf16_f32 v33, v33, v34
	v_mul_f32_e32 v34, v24, v85
	v_mul_f32_e32 v35, v25, v87
	v_cvt_pk_bf16_f32 v34, v34, v35
	v_mul_f32_e32 v35, v26, v90
	v_mul_f32_e32 v28, v28, v70
	v_mul_f32_e32 v29, v29, v71
	v_mul_f32_e32 v36, v27, v93
	v_cvt_pk_bf16_f32 v35, v35, v36
	v_cvt_pk_bf16_f32 v28, v28, v29
	v_mul_f32_e32 v29, v30, v60
	v_mul_f32_e32 v30, v31, v84
	v_mul_f32_e32 v24, v24, v86
	v_cvt_pk_bf16_f32 v29, v29, v30
	v_mul_f32_e32 v25, v25, v88
	v_cvt_pk_bf16_f32 v30, v24, v25
	v_mul_f32_e32 v24, v26, v91
	v_mul_f32_e32 v25, v27, v78
	v_cvt_pk_bf16_f32 v31, v24, v25
	v_add_co_u32_e32 v24, vcc, s52, v140
	s_mov_b64 s[2:3], 0x280000
	s_nop 0
	v_addc_co_u32_e32 v25, vcc, 0, v141, vcc
	global_store_dwordx4 v[24:25], v[32:35], off
	v_add_co_u32_e32 v24, vcc, s53, v140
	v_lshl_add_u64 v[36:37], v[140:141], 0, s[2:3]
	s_nop 0
	v_addc_co_u32_e32 v25, vcc, 0, v141, vcc
	v_lshl_add_u64 v[32:33], v[140:141], 0, s[8:9]
	global_store_dwordx4 v[24:25], v[28:31], off
	v_mul_f32_e32 v24, v20, v79
	v_mul_f32_e32 v25, v21, v80
	v_cvt_pk_bf16_f32 v24, v24, v25
	v_mul_f32_e32 v25, v22, v82
	v_mul_f32_e32 v26, v23, v83
	v_cvt_pk_bf16_f32 v25, v25, v26
	v_mul_f32_e32 v26, v16, v85
	v_mul_f32_e32 v27, v17, v87
	v_cvt_pk_bf16_f32 v26, v26, v27
	v_mul_f32_e32 v27, v18, v90
	v_mul_f32_e32 v20, v20, v70
	v_mul_f32_e32 v21, v21, v71
	v_mul_f32_e32 v28, v19, v93
	v_cvt_pk_bf16_f32 v27, v27, v28
	v_cvt_pk_bf16_f32 v20, v20, v21
	v_mul_f32_e32 v21, v22, v60
	v_mul_f32_e32 v22, v23, v84
	v_mul_f32_e32 v16, v16, v86
	v_mul_f32_e32 v17, v17, v88
	v_cvt_pk_bf16_f32 v21, v21, v22
	v_cvt_pk_bf16_f32 v22, v16, v17
	v_mul_f32_e32 v16, v18, v91
	v_mul_f32_e32 v17, v19, v78
	v_cvt_pk_bf16_f32 v23, v16, v17
	global_store_dwordx4 v[36:37], v[24:27], off offset:256
	global_store_dwordx4 v[32:33], v[20:23], off offset:256
	v_mul_f32_e32 v16, v12, v79
	v_mul_f32_e32 v17, v13, v80
	v_cvt_pk_bf16_f32 v16, v16, v17
	v_mul_f32_e32 v17, v14, v82
	v_mul_f32_e32 v18, v15, v83
	v_cvt_pk_bf16_f32 v17, v17, v18
	v_mul_f32_e32 v18, v8, v85
	v_mul_f32_e32 v19, v9, v87
	v_cvt_pk_bf16_f32 v18, v18, v19
	v_mul_f32_e32 v19, v10, v90
	v_mul_f32_e32 v12, v12, v70
	v_mul_f32_e32 v13, v13, v71
	v_mul_f32_e32 v20, v11, v93
	v_cvt_pk_bf16_f32 v19, v19, v20
	v_cvt_pk_bf16_f32 v12, v12, v13
	v_mul_f32_e32 v13, v14, v60
	v_mul_f32_e32 v14, v15, v84
	v_mul_f32_e32 v8, v8, v86
	v_cvt_pk_bf16_f32 v13, v13, v14
	v_mul_f32_e32 v9, v9, v88
	v_cvt_pk_bf16_f32 v14, v8, v9
	v_mul_f32_e32 v8, v10, v91
	v_mul_f32_e32 v9, v11, v78
	v_cvt_pk_bf16_f32 v15, v8, v9
	v_add_co_u32_e32 v8, vcc, s54, v140
	v_lshl_add_u64 v[20:21], v[140:141], 0, s[10:11]
	s_nop 0
	v_addc_co_u32_e32 v9, vcc, 0, v141, vcc
	global_store_dwordx4 v[8:9], v[16:19], off
	v_add_co_u32_e32 v8, vcc, s55, v140
	s_nop 0
	v_lshl_add_u64 v[16:17], v[140:141], 0, s[12:13]
	v_addc_co_u32_e32 v9, vcc, 0, v141, vcc
	global_store_dwordx4 v[8:9], v[12:15], off
	v_mul_f32_e32 v8, v4, v79
	v_mul_f32_e32 v9, v5, v80
	v_cvt_pk_bf16_f32 v8, v8, v9
	v_mul_f32_e32 v9, v6, v82
	v_mul_f32_e32 v10, v7, v83
	v_cvt_pk_bf16_f32 v9, v9, v10
	v_mul_f32_e32 v10, v0, v85
	v_mul_f32_e32 v11, v1, v87
	v_cvt_pk_bf16_f32 v10, v10, v11
	v_mul_f32_e32 v11, v2, v90
	v_mul_f32_e32 v4, v4, v70
	v_mul_f32_e32 v5, v5, v71
	v_mul_f32_e32 v12, v3, v93
	v_cvt_pk_bf16_f32 v11, v11, v12
	v_cvt_pk_bf16_f32 v4, v4, v5
	v_mul_f32_e32 v5, v6, v60
	v_mul_f32_e32 v6, v7, v84
	v_mul_f32_e32 v0, v0, v86
	v_mul_f32_e32 v1, v1, v88
	v_cvt_pk_bf16_f32 v5, v5, v6
	v_cvt_pk_bf16_f32 v6, v0, v1
	v_mul_f32_e32 v0, v2, v91
	v_mul_f32_e32 v1, v3, v78
	v_cvt_pk_bf16_f32 v7, v0, v1
	global_store_dwordx4 v[20:21], v[8:11], off offset:256
	global_store_dwordx4 v[16:17], v[4:7], off offset:256
	s_and_b64 vcc, exec, s[14:15]
	s_mov_b32 s56, s16
	s_mov_b64 s[4:5], s[22:23]
	s_mov_b64 s[2:3], s[20:21]
	s_cbranch_vccz .LBB0_686
	s_waitcnt vmcnt(0)
	s_cmpk_gt_u32 s27, 0xff
	s_cbranch_scc1 .LBB0_697
	s_barrier

; #define PG8_STAGE(bufoff, gbase, voff) do { _Pragma("unroll") for (int _i = 0; _i < 2; ++_i) \
;         __builtin_amdgcn_global_load_lds((const unsigned*)((const char*)(gbase) + (voff)[_i]), (LAS unsigned*)(lds + (bufoff) + ldsw + _i * 8192), 16, 0, 0); } while (0)
; #define PG8_LDA(dst, b, h) do { _Pragma("unroll") for (int m = 0; m < 4; ++m) _Pragma("unroll") for (int k = 0; k < 2; ++k) dst[m][k] = *(const LAS bf16x8*)(lds + PG8_SA(b, h) + aoff + m * 2048 + k * 1024); } while (0)
; #define PG8_LDB(dst, b, h) do { _Pragma("unroll") for (int n = 0; n < 2; ++n) _Pragma("unroll") for (int k = 0; k < 2; ++k) dst[n][k] = *(const LAS bf16x8*)(lds + PG8_SB(b, h) + boff + n * 2048 + k * 1024); } while (0)
; #define PG8_WAIT_V(n) asm volatile("s_waitcnt vmcnt(" #n ")" ::: "memory")
; #define PG8_WAIT_L(n) asm volatile("s_waitcnt lgkmcnt(" #n ")" ::: "memory")
; #define PG8_BAR __builtin_amdgcn_s_barrier()
; #define PG8_SCHED __builtin_amdgcn_sched_barrier(0)
; template <class Epi, class Sched>
; __device__ __forceinline__ void gemm_phase(LAS unsigned char* lds, const Gemm g, const Sched& S, const Epi& E) {
;     ...
;     for (;;) {
;         const bool has_next = S.next(ui + 1, nxt);
;         const char* nA = has_next ? (const char*)g.A + (size_t)nxt.pm * tstep : cA; const char* nB = has_next ? (const char*)g.Bt + (size_t)nxt.pn * tstep : cB;
;         for (int t = 0; t < nt; t += 2) {
;             const bool last = (t == nt - 2);
;             const char* a1 = cA + (size_t)(t + 1) * kstep;
;             const char* a2 = last ? nA : cA + (size_t)(t + 2) * kstep; const char* b2 = last ? nB : cB + (size_t)(t + 2) * kstep;
;             const char* a3 = a2 + kstep; const char* b3 = b2 + kstep;
;             PG8_LDB(B0, 0, 0); PG8_SCHED; PG8_LDA(At, 0, 0); PG8_STAGE(PG8_SA(1, 1), a1 + hstep, voffA);
;             PG8_WAIT_L(8); PG8_BAR; PG8_WAIT_L(0); PG8_MMA(0, 0, At, B0); PG8_BAR; PG8_SCHED;
;             PG8_LDB(B1, 0, 1); PG8_STAGE(PG8_SB(0, 0), b2, voffB);
;             PG8_BAR; PG8_WAIT_L(0); PG8_MMA(0, 1, At, B1); PG8_BAR;
;             PG8_LDA(At, 0, 1); PG8_STAGE(PG8_SA(0, 0), a2, voffA);
;             PG8_BAR; PG8_WAIT_L(0); PG8_MMA(1, 0, At, B0); PG8_BAR; PG8_SCHED;
;             PG8_STAGE(PG8_SB(0, 1), b2 + hstep, voffB);
;             PG8_WAIT_V(6); PG8_BAR; PG8_MMA(1, 1, At, B1); PG8_BAR;
.LBB0_712:
	s_ashr_i32 s15, s14, 31
	v_cmp_lt_i64_e64 s[26:27], s[16:17], 64
	s_lshl_b64 s[16:17], s[14:15], 19
	s_add_u32 s16, s38, s16
	s_addc_u32 s17, s39, s17
	s_and_b64 s[18:19], s[26:27], exec
	s_cselect_b32 s15, s17, s23
	s_cselect_b32 s54, s16, s22
	s_ashr_i32 s13, s12, 31
	s_lshl_b64 s[18:19], s[12:13], 19
	s_add_u32 s18, s28, s18
	s_addc_u32 s19, s29, s19
	s_and_b64 s[26:27], s[26:27], exec
	s_cselect_b32 s13, s19, s25
	s_cselect_b32 s55, s18, s24
	s_add_u32 s22, s22, 0x40080
	s_addc_u32 s23, s23, 0
	s_add_u32 s56, s24, 0x100
	s_addc_u32 s57, s25, 0
	s_mov_b32 s58, -2
	s_waitcnt lgkmcnt(0)
	ds_read_b128 v[146:149], v143
	ds_read_b128 v[150:153], v143 offset:1024
	ds_read_b128 v[154:157], v143 offset:2048
	ds_read_b128 v[158:161], v143 offset:3072
	s_add_u32 s24, s22, 0xfffc0080
	s_addc_u32 s25, s23, -1
	s_cmp_eq_u32 s58, 12
	s_cselect_b32 s27, s15, s25
	s_cselect_b32 s26, s54, s24
	s_cselect_b32 s25, s13, s57
	s_cselect_b32 s24, s55, s56
	s_add_i32 m0, s21, 0xc000
	ds_read_b128 v[162:165], v144
	ds_read_b128 v[166:169], v144 offset:1024
	ds_read_b128 v[170:173], v144 offset:2048
	ds_read_b128 v[174:177], v144 offset:3072
	ds_read_b128 v[178:181], v144 offset:4096
	ds_read_b128 v[182:185], v144 offset:5120
	ds_read_b128 v[186:189], v144 offset:6144
	ds_read_b128 v[190:193], v144 offset:7168
	global_load_lds_dwordx4 v136, s[22:23]
	s_add_i32 m0, s21, 0xe000
	s_nop 0
	global_load_lds_dwordx4 v138, s[22:23]
	s_waitcnt lgkmcnt(8)
	s_waitcnt vmcnt(8)
	s_setprio 1
	s_barrier
	s_waitcnt lgkmcnt(0)
	s_waitcnt lgkmcnt(0)
	v_mfma_f32_16x16x32_bf16 v[124:127], v[146:149], v[162:165], 0
	v_mfma_f32_16x16x32_bf16 v[120:123], v[154:157], v[162:165], 0
	v_mfma_f32_16x16x32_bf16 v[116:119], v[146:149], v[170:173], 0
	v_mfma_f32_16x16x32_bf16 v[108:111], v[154:157], v[170:173], 0
	v_mfma_f32_16x16x32_bf16 v[100:103], v[146:149], v[178:181], 0
	v_mfma_f32_16x16x32_bf16 v[92:95], v[154:157], v[178:181], 0
	v_mfma_f32_16x16x32_bf16 v[84:87], v[146:149], v[186:189], 0
	v_mfma_f32_16x16x32_bf16 v[76:79], v[154:157], v[186:189], 0
	v_mfma_f32_16x16x32_bf16 v[124:127], v[150:153], v[166:169], v[124:127]
	v_mfma_f32_16x16x32_bf16 v[120:123], v[158:161], v[166:169], v[120:123]
	v_mfma_f32_16x16x32_bf16 v[116:119], v[150:153], v[174:177], v[116:119]
	v_mfma_f32_16x16x32_bf16 v[108:111], v[158:161], v[174:177], v[108:111]
	v_mfma_f32_16x16x32_bf16 v[100:103], v[150:153], v[182:185], v[100:103]
	v_mfma_f32_16x16x32_bf16 v[92:95], v[158:161], v[182:185], v[92:95]
	v_mfma_f32_16x16x32_bf16 v[84:87], v[150:153], v[190:193], v[84:87]
	v_mfma_f32_16x16x32_bf16 v[76:79], v[158:161], v[190:193], v[76:79]
	s_setprio 0
	s_barrier
	s_add_i32 s59, s46, s34
	s_mov_b32 m0, s59
	ds_read_b128 v[194:197], v145
	ds_read_b128 v[202:205], v145 offset:1024
	ds_read_b128 v[206:209], v145 offset:2048
	ds_read_b128 v[210:213], v145 offset:3072
	global_load_lds_dwordx4 v130, s[24:25]
	s_add_i32 m0, s59, 0x2000
	s_nop 0
	global_load_lds_dwordx4 v134, s[24:25]
	s_waitcnt vmcnt(8)
	s_setprio 1
	s_barrier
	s_waitcnt lgkmcnt(0)
	s_waitcnt lgkmcnt(0)
	v_mfma_f32_16x16x32_bf16 v[112:115], v[194:197], v[162:165], 0
	v_mfma_f32_16x16x32_bf16 v[104:107], v[206:209], v[162:165], 0
	v_mfma_f32_16x16x32_bf16 v[96:99], v[194:197], v[170:173], 0
	v_mfma_f32_16x16x32_bf16 v[88:91], v[206:209], v[170:173], 0
	v_mfma_f32_16x16x32_bf16 v[80:83], v[194:197], v[178:181], 0
	v_mfma_f32_16x16x32_bf16 v[72:75], v[206:209], v[178:181], 0
	v_mfma_f32_16x16x32_bf16 v[68:71], v[194:197], v[186:189], 0
	v_mfma_f32_16x16x32_bf16 v[64:67], v[206:209], v[186:189], 0
	v_mfma_f32_16x16x32_bf16 v[112:115], v[202:205], v[166:169], v[112:115]
	v_mfma_f32_16x16x32_bf16 v[104:107], v[210:213], v[166:169], v[104:107]
	v_mfma_f32_16x16x32_bf16 v[96:99], v[202:205], v[174:177], v[96:99]
	v_mfma_f32_16x16x32_bf16 v[88:91], v[210:213], v[174:177], v[88:91]
	v_mfma_f32_16x16x32_bf16 v[80:83], v[202:205], v[182:185], v[80:83]
	v_mfma_f32_16x16x32_bf16 v[72:75], v[210:213], v[182:185], v[72:75]
	v_mfma_f32_16x16x32_bf16 v[68:71], v[202:205], v[190:193], v[68:71]
	v_mfma_f32_16x16x32_bf16 v[64:67], v[210:213], v[190:193], v[64:67]
	s_setprio 0
	s_mov_b32 m0, s21
	v_lshl_add_u64 v[216:217], s[26:27], 0, v[128:129]
	s_barrier
	ds_read_b128 v[162:165], v144 offset:16384
	ds_read_b128 v[166:169], v144 offset:17408
	ds_read_b128 v[170:173], v144 offset:18432
	ds_read_b128 v[174:177], v144 offset:19456
	ds_read_b128 v[178:181], v144 offset:20480
	ds_read_b128 v[182:185], v144 offset:21504
	ds_read_b128 v[186:189], v144 offset:22528
	ds_read_b128 v[190:193], v144 offset:23552
	global_load_lds_dwordx4 v128, s[26:27]
	v_lshl_add_u64 v[218:219], s[26:27], 0, v[132:133]
	s_mov_b32 m0, s35
	s_nop 0
	global_load_lds_dwordx4 v132, s[26:27]
	s_setprio 1
	s_barrier
	s_waitcnt lgkmcnt(0)
	s_waitcnt lgkmcnt(0)
	v_mfma_f32_16x16x32_bf16 v[60:63], v[146:149], v[162:165], 0
	v_mfma_f32_16x16x32_bf16 v[56:59], v[154:157], v[162:165], 0
	v_mfma_f32_16x16x32_bf16 v[52:55], v[146:149], v[170:173], 0
	v_mfma_f32_16x16x32_bf16 v[44:47], v[154:157], v[170:173], 0
	v_mfma_f32_16x16x32_bf16 v[36:39], v[146:149], v[178:181], 0
	v_mfma_f32_16x16x32_bf16 v[28:31], v[154:157], v[178:181], 0
	v_mfma_f32_16x16x32_bf16 v[20:23], v[146:149], v[186:189], 0
	v_mfma_f32_16x16x32_bf16 v[12:15], v[154:157], v[186:189], 0
	v_mfma_f32_16x16x32_bf16 v[60:63], v[150:153], v[166:169], v[60:63]
	v_mfma_f32_16x16x32_bf16 v[56:59], v[158:161], v[166:169], v[56:59]
	v_mfma_f32_16x16x32_bf16 v[52:55], v[150:153], v[174:177], v[52:55]
	v_mfma_f32_16x16x32_bf16 v[44:47], v[158:161], v[174:177], v[44:47]
	v_mfma_f32_16x16x32_bf16 v[36:39], v[150:153], v[182:185], v[36:39]
	v_mfma_f32_16x16x32_bf16 v[28:31], v[158:161], v[182:185], v[28:31]
	v_mfma_f32_16x16x32_bf16 v[20:23], v[150:153], v[190:193], v[20:23]
	v_mfma_f32_16x16x32_bf16 v[12:15], v[158:161], v[190:193], v[12:15]
	s_setprio 0
	s_barrier
; #define PG8_STAGE(bufoff, gbase, voff) do { _Pragma("unroll") for (int _i = 0; _i < 2; ++_i) \
;         __builtin_amdgcn_global_load_lds((const unsigned*)((const char*)(gbase) + (voff)[_i]), (LAS unsigned*)(lds + (bufoff) + ldsw + _i * 8192), 16, 0, 0); } while (0)
; #define PG8_LDA(dst, b, h) do { _Pragma("unroll") for (int m = 0; m < 4; ++m) _Pragma("unroll") for (int k = 0; k < 2; ++k) dst[m][k] = *(const LAS bf16x8*)(lds + PG8_SA(b, h) + aoff + m * 2048 + k * 1024); } while (0)
; #define PG8_LDB(dst, b, h) do { _Pragma("unroll") for (int n = 0; n < 2; ++n) _Pragma("unroll") for (int k = 0; k < 2; ++k) dst[n][k] = *(const LAS bf16x8*)(lds + PG8_SB(b, h) + boff + n * 2048 + k * 1024); } while (0)
; #define PG8_MMA(ai, bj, At, Bt) do { __builtin_amdgcn_s_setprio(1); _Pragma("unroll") for (int m = 0; m < 4; ++m) _Pragma("unroll") for (int n = 0; n < 2; ++n) _Pragma("unroll") for (int k = 0; k < 2; ++k) \
;         acc[ai][bj][m][n] = __builtin_amdgcn_mfma_f32_16x16x32_bf16(Bt[n][k], At[m][k], acc[ai][bj][m][n], 0, 0, 0); __builtin_amdgcn_s_setprio(0); } while (0)
; #define PG8_WAIT_V(n) asm volatile("s_waitcnt vmcnt(" #n ")" ::: "memory")
; #define PG8_WAIT_L(n) asm volatile("s_waitcnt lgkmcnt(" #n ")" ::: "memory")
; #define PG8_BAR __builtin_amdgcn_s_barrier()
; #define PG8_SCHED __builtin_amdgcn_sched_barrier(0)
; template <class Epi, class Sched>
; __device__ __forceinline__ void gemm_phase(LAS unsigned char* lds, const Gemm g, const Sched& S, const Epi& E) {
;     ...
;             PG8_BAR; PG8_WAIT_L(0); PG8_MMA(1, 0, At, B0); PG8_BAR; PG8_SCHED;
;             PG8_STAGE(PG8_SB(0, 1), b2 + hstep, voffB);
;             PG8_WAIT_V(6); PG8_BAR; PG8_MMA(1, 1, At, B1); PG8_BAR;
;             PG8_LDB(B0, 1, 0); PG8_SCHED; PG8_LDA(At, 1, 0); PG8_STAGE(PG8_SA(0, 1), a2 + hstep, voffA);
;             PG8_WAIT_L(8); PG8_BAR; PG8_WAIT_L(0); PG8_MMA(0, 0, At, B0); PG8_BAR; PG8_SCHED;
;             PG8_LDB(B1, 1, 1); PG8_STAGE(PG8_SB(1, 0), b3, voffB);
;             PG8_BAR; PG8_WAIT_L(0); PG8_MMA(0, 1, At, B1); PG8_BAR;
;             PG8_LDA(At, 1, 1); PG8_STAGE(PG8_SA(1, 0), a3, voffA);
;             PG8_BAR; PG8_WAIT_L(0); PG8_MMA(1, 0, At, B0); PG8_BAR; PG8_SCHED;
;             PG8_STAGE(PG8_SB(1, 1), b3 + hstep, voffB);
;             PG8_WAIT_V(6); PG8_BAR; PG8_MMA(1, 1, At, B1); PG8_BAR;
	s_add_u32 s60, s24, 0x40000
	s_addc_u32 s61, s25, 0
	s_add_i32 s59, s47, s34
	s_mov_b32 m0, s59
	s_nop 0
	global_load_lds_dwordx4 v130, s[60:61]
	s_add_i32 m0, s59, 0x2000
	s_nop 0
	global_load_lds_dwordx4 v134, s[60:61]
	s_add_u32 s26, s26, 0x40000
	s_addc_u32 s27, s27, 0
	s_mov_b32 m0, s36
	s_nop 0
	global_load_lds_dwordx4 v128, s[26:27]
	s_mov_b32 m0, s37
	s_nop 0
	global_load_lds_dwordx4 v132, s[26:27]
	s_waitcnt vmcnt(10)
	s_setprio 1
	s_barrier
	v_mfma_f32_16x16x32_bf16 v[48:51], v[194:197], v[162:165], 0
	v_mfma_f32_16x16x32_bf16 v[40:43], v[206:209], v[162:165], 0
	v_mfma_f32_16x16x32_bf16 v[32:35], v[194:197], v[170:173], 0
	v_mfma_f32_16x16x32_bf16 v[24:27], v[206:209], v[170:173], 0
	v_mfma_f32_16x16x32_bf16 v[16:19], v[194:197], v[178:181], 0
	v_mfma_f32_16x16x32_bf16 v[8:11], v[206:209], v[178:181], 0
	v_mfma_f32_16x16x32_bf16 v[4:7], v[194:197], v[186:189], 0
	v_mfma_f32_16x16x32_bf16 v[0:3], v[206:209], v[186:189], 0
	v_mfma_f32_16x16x32_bf16 v[48:51], v[202:205], v[166:169], v[48:51]
	v_mfma_f32_16x16x32_bf16 v[40:43], v[210:213], v[166:169], v[40:43]
	v_mfma_f32_16x16x32_bf16 v[32:35], v[202:205], v[174:177], v[32:35]
	v_mfma_f32_16x16x32_bf16 v[24:27], v[210:213], v[174:177], v[24:27]
	v_mfma_f32_16x16x32_bf16 v[16:19], v[202:205], v[182:185], v[16:19]
	v_mfma_f32_16x16x32_bf16 v[8:11], v[210:213], v[182:185], v[8:11]
	v_mfma_f32_16x16x32_bf16 v[4:7], v[202:205], v[190:193], v[4:7]
	v_mfma_f32_16x16x32_bf16 v[0:3], v[210:213], v[190:193], v[0:3]
	s_setprio 0
	s_add_i32 s59, 0, 0x18000
	v_add_u32_e32 v158, s59, v142
	s_barrier
	ds_read_b128 v[146:149], v158
	ds_read_b128 v[150:153], v158 offset:1024
	ds_read_b128 v[154:157], v158 offset:2048
	ds_read_b128 v[158:161], v158 offset:3072
	ds_read_b128 v[162:165], v144 offset:32768
	ds_read_b128 v[166:169], v144 offset:33792
	ds_read_b128 v[170:173], v144 offset:34816
	ds_read_b128 v[174:177], v144 offset:35840
	ds_read_b128 v[178:181], v144 offset:36864
	ds_read_b128 v[182:185], v144 offset:37888
	ds_read_b128 v[186:189], v144 offset:38912
	ds_read_b128 v[190:193], v144 offset:39936
	s_waitcnt lgkmcnt(8)
	s_waitcnt vmcnt(8)
	s_setprio 1
	s_barrier
	s_waitcnt lgkmcnt(0)
	s_waitcnt lgkmcnt(0)
	v_mfma_f32_16x16x32_bf16 v[124:127], v[146:149], v[162:165], v[124:127]
	v_mfma_f32_16x16x32_bf16 v[120:123], v[154:157], v[162:165], v[120:123]
	v_mfma_f32_16x16x32_bf16 v[116:119], v[146:149], v[170:173], v[116:119]
	v_mfma_f32_16x16x32_bf16 v[108:111], v[154:157], v[170:173], v[108:111]
	v_mfma_f32_16x16x32_bf16 v[100:103], v[146:149], v[178:181], v[100:103]
	v_mfma_f32_16x16x32_bf16 v[92:95], v[154:157], v[178:181], v[92:95]
	v_mfma_f32_16x16x32_bf16 v[84:87], v[146:149], v[186:189], v[84:87]
	v_mfma_f32_16x16x32_bf16 v[76:79], v[154:157], v[186:189], v[76:79]
	v_mfma_f32_16x16x32_bf16 v[124:127], v[150:153], v[166:169], v[124:127]
	v_mfma_f32_16x16x32_bf16 v[120:123], v[158:161], v[166:169], v[120:123]
	v_mfma_f32_16x16x32_bf16 v[116:119], v[150:153], v[174:177], v[116:119]
	v_mfma_f32_16x16x32_bf16 v[108:111], v[158:161], v[174:177], v[108:111]
	v_mfma_f32_16x16x32_bf16 v[100:103], v[150:153], v[182:185], v[100:103]
	v_mfma_f32_16x16x32_bf16 v[92:95], v[158:161], v[182:185], v[92:95]
	v_mfma_f32_16x16x32_bf16 v[84:87], v[150:153], v[190:193], v[84:87]
	v_mfma_f32_16x16x32_bf16 v[76:79], v[158:161], v[190:193], v[76:79]
	s_setprio 0
	s_barrier
	s_add_i32 s26, 0, 0x1c000
	s_add_i32 s27, s59, s34
	v_add_u32_e32 v210, s26, v142
	s_add_u32 s0, s24, 0x80
	s_addc_u32 s1, s25, 0
	s_mov_b32 m0, s27
	ds_read_b128 v[194:197], v210
	ds_read_b128 v[202:205], v210 offset:1024
	ds_read_b128 v[206:209], v210 offset:2048
	ds_read_b128 v[210:213], v210 offset:3072
	global_load_lds_dwordx4 v130, s[0:1]
	s_add_i32 m0, s27, 0x2000
	s_nop 0
	global_load_lds_dwordx4 v134, s[0:1]
	s_waitcnt vmcnt(8)
	s_setprio 1
	s_barrier
	s_waitcnt lgkmcnt(0)
	s_waitcnt lgkmcnt(0)
	v_mfma_f32_16x16x32_bf16 v[112:115], v[194:197], v[162:165], v[112:115]
	v_mfma_f32_16x16x32_bf16 v[104:107], v[206:209], v[162:165], v[104:107]
	v_mfma_f32_16x16x32_bf16 v[96:99], v[194:197], v[170:173], v[96:99]
	v_mfma_f32_16x16x32_bf16 v[88:91], v[206:209], v[170:173], v[88:91]
	v_mfma_f32_16x16x32_bf16 v[80:83], v[194:197], v[178:181], v[80:83]
	v_mfma_f32_16x16x32_bf16 v[72:75], v[206:209], v[178:181], v[72:75]
	v_mfma_f32_16x16x32_bf16 v[68:71], v[194:197], v[186:189], v[68:71]
	v_mfma_f32_16x16x32_bf16 v[64:67], v[206:209], v[186:189], v[64:67]
	v_mfma_f32_16x16x32_bf16 v[112:115], v[202:205], v[166:169], v[112:115]
	v_mfma_f32_16x16x32_bf16 v[104:107], v[210:213], v[166:169], v[104:107]
	v_mfma_f32_16x16x32_bf16 v[96:99], v[202:205], v[174:177], v[96:99]
	v_mfma_f32_16x16x32_bf16 v[88:91], v[210:213], v[174:177], v[88:91]
	v_mfma_f32_16x16x32_bf16 v[80:83], v[202:205], v[182:185], v[80:83]
	v_mfma_f32_16x16x32_bf16 v[72:75], v[210:213], v[182:185], v[72:75]
	v_mfma_f32_16x16x32_bf16 v[68:71], v[202:205], v[190:193], v[68:71]
	v_mfma_f32_16x16x32_bf16 v[64:67], v[210:213], v[190:193], v[64:67]
	s_setprio 0
	s_mov_b32 m0, s43
	s_mov_b64 s[0:1], 0x80
	v_lshl_add_u64 v[198:199], v[216:217], 0, s[0:1]
	s_barrier
	ds_read_b128 v[162:165], v144 offset:49152
	ds_read_b128 v[166:169], v144 offset:50176
	ds_read_b128 v[170:173], v144 offset:51200
	ds_read_b128 v[174:177], v144 offset:52224
	ds_read_b128 v[178:181], v144 offset:53248
	ds_read_b128 v[182:185], v144 offset:54272
	ds_read_b128 v[186:189], v144 offset:55296
	ds_read_b128 v[190:193], v144 offset:56320
	global_load_lds_dwordx4 v[198:199], off
	v_lshl_add_u64 v[198:199], v[218:219], 0, s[0:1]
	s_mov_b32 m0, s44
	s_nop 0
	global_load_lds_dwordx4 v[198:199], off
	s_setprio 1
	s_barrier
; #define PG8_STAGE(bufoff, gbase, voff) do { _Pragma("unroll") for (int _i = 0; _i < 2; ++_i) \
;         __builtin_amdgcn_global_load_lds((const unsigned*)((const char*)(gbase) + (voff)[_i]), (LAS unsigned*)(lds + (bufoff) + ldsw + _i * 8192), 16, 0, 0); } while (0)
; #define PG8_LDA(dst, b, h) do { _Pragma("unroll") for (int m = 0; m < 4; ++m) _Pragma("unroll") for (int k = 0; k < 2; ++k) dst[m][k] = *(const LAS bf16x8*)(lds + PG8_SA(b, h) + aoff + m * 2048 + k * 1024); } while (0)
; #define PG8_WAIT_V(n) asm volatile("s_waitcnt vmcnt(" #n ")" ::: "memory")
; #define PG8_WAIT_L(n) asm volatile("s_waitcnt lgkmcnt(" #n ")" ::: "memory")
; template <class Epi, class Sched>
; __device__ __forceinline__ void gemm_phase(LAS unsigned char* lds, const Gemm g, const Sched& S, const Epi& E) {
;     ...
;         for (int t = 0; t < nt; t += 2) {
;             const bool last = (t == nt - 2);
;             const char* a1 = cA + (size_t)(t + 1) * kstep;
;             const char* a2 = last ? nA : cA + (size_t)(t + 2) * kstep; const char* b2 = last ? nB : cB + (size_t)(t + 2) * kstep;
;             const char* a3 = a2 + kstep; const char* b3 = b2 + kstep;
;             PG8_LDB(B0, 0, 0); PG8_SCHED; PG8_LDA(At, 0, 0); PG8_STAGE(PG8_SA(1, 1), a1 + hstep, voffA);
;             PG8_WAIT_L(8); PG8_BAR; PG8_WAIT_L(0); PG8_MMA(0, 0, At, B0); PG8_BAR; PG8_SCHED;
;             PG8_LDB(B1, 0, 1); PG8_STAGE(PG8_SB(0, 0), b2, voffB);
;             PG8_BAR; PG8_WAIT_L(0); PG8_MMA(0, 1, At, B1); PG8_BAR;
;             PG8_LDA(At, 0, 1); PG8_STAGE(PG8_SA(0, 0), a2, voffA);
;             PG8_BAR; PG8_WAIT_L(0); PG8_MMA(1, 0, At, B0); PG8_BAR; PG8_SCHED;
;             PG8_STAGE(PG8_SB(0, 1), b2 + hstep, voffB);
;             PG8_WAIT_V(6); PG8_BAR; PG8_MMA(1, 1, At, B1); PG8_BAR;
;             PG8_LDB(B0, 1, 0); PG8_SCHED; PG8_LDA(At, 1, 0); PG8_STAGE(PG8_SA(0, 1), a2 + hstep, voffA);
;             PG8_WAIT_L(8); PG8_BAR; PG8_WAIT_L(0); PG8_MMA(0, 0, At, B0); PG8_BAR; PG8_SCHED;
;             PG8_LDB(B1, 1, 1); PG8_STAGE(PG8_SB(1, 0), b3, voffB);
;             PG8_BAR; PG8_WAIT_L(0); PG8_MMA(0, 1, At, B1); PG8_BAR;
;             PG8_LDA(At, 1, 1); PG8_STAGE(PG8_SA(1, 0), a3, voffA);
;             PG8_BAR; PG8_WAIT_L(0); PG8_MMA(1, 0, At, B0); PG8_BAR; PG8_SCHED;
;             PG8_STAGE(PG8_SB(1, 1), b3 + hstep, voffB);
;             PG8_WAIT_V(6); PG8_BAR; PG8_MMA(1, 1, At, B1); PG8_BAR;
	s_waitcnt lgkmcnt(0)
	s_waitcnt lgkmcnt(0)
	v_mfma_f32_16x16x32_bf16 v[60:63], v[146:149], v[162:165], v[60:63]
	v_mfma_f32_16x16x32_bf16 v[56:59], v[154:157], v[162:165], v[56:59]
	v_mfma_f32_16x16x32_bf16 v[52:55], v[146:149], v[170:173], v[52:55]
	v_mfma_f32_16x16x32_bf16 v[44:47], v[154:157], v[170:173], v[44:47]
	v_mfma_f32_16x16x32_bf16 v[36:39], v[146:149], v[178:181], v[36:39]
	v_mfma_f32_16x16x32_bf16 v[28:31], v[154:157], v[178:181], v[28:31]
	v_mfma_f32_16x16x32_bf16 v[20:23], v[146:149], v[186:189], v[20:23]
	v_mfma_f32_16x16x32_bf16 v[12:15], v[154:157], v[186:189], v[12:15]
	v_mfma_f32_16x16x32_bf16 v[60:63], v[150:153], v[166:169], v[60:63]
	v_mfma_f32_16x16x32_bf16 v[56:59], v[158:161], v[166:169], v[56:59]
	v_mfma_f32_16x16x32_bf16 v[52:55], v[150:153], v[174:177], v[52:55]
	v_mfma_f32_16x16x32_bf16 v[44:47], v[158:161], v[174:177], v[44:47]
	v_mfma_f32_16x16x32_bf16 v[36:39], v[150:153], v[182:185], v[36:39]
	v_mfma_f32_16x16x32_bf16 v[28:31], v[158:161], v[182:185], v[28:31]
	v_mfma_f32_16x16x32_bf16 v[20:23], v[150:153], v[190:193], v[20:23]
	v_mfma_f32_16x16x32_bf16 v[12:15], v[158:161], v[190:193], v[12:15]
	s_setprio 0
	s_barrier
	s_add_u32 s24, s24, 0x40080
	s_addc_u32 s25, s25, 0
	s_add_i32 s26, s26, s34
	s_mov_b32 m0, s26
	s_nop 0
	global_load_lds_dwordx4 v130, s[24:25]
	s_add_i32 m0, s26, 0x2000
	s_nop 0
	global_load_lds_dwordx4 v134, s[24:25]
	s_waitcnt vmcnt(8)
	s_setprio 1
	s_barrier
	v_mfma_f32_16x16x32_bf16 v[48:51], v[194:197], v[162:165], v[48:51]
	v_mfma_f32_16x16x32_bf16 v[40:43], v[206:209], v[162:165], v[40:43]
	v_mfma_f32_16x16x32_bf16 v[32:35], v[194:197], v[170:173], v[32:35]
	v_mfma_f32_16x16x32_bf16 v[24:27], v[206:209], v[170:173], v[24:27]
	v_mfma_f32_16x16x32_bf16 v[16:19], v[194:197], v[178:181], v[16:19]
	v_mfma_f32_16x16x32_bf16 v[8:11], v[206:209], v[178:181], v[8:11]
	v_mfma_f32_16x16x32_bf16 v[4:7], v[194:197], v[186:189], v[4:7]
	v_mfma_f32_16x16x32_bf16 v[0:3], v[206:209], v[186:189], v[0:3]
	v_mfma_f32_16x16x32_bf16 v[48:51], v[202:205], v[166:169], v[48:51]
	v_mfma_f32_16x16x32_bf16 v[40:43], v[210:213], v[166:169], v[40:43]
	v_mfma_f32_16x16x32_bf16 v[32:35], v[202:205], v[174:177], v[32:35]
	v_mfma_f32_16x16x32_bf16 v[24:27], v[210:213], v[174:177], v[24:27]
	v_mfma_f32_16x16x32_bf16 v[16:19], v[202:205], v[182:185], v[16:19]
	v_mfma_f32_16x16x32_bf16 v[8:11], v[210:213], v[182:185], v[8:11]
	v_mfma_f32_16x16x32_bf16 v[4:7], v[202:205], v[190:193], v[4:7]
	v_mfma_f32_16x16x32_bf16 v[0:3], v[210:213], v[190:193], v[0:3]
	s_setprio 0
	s_add_i32 s58, s58, 2
	s_add_u32 s22, s22, 0x100
	s_addc_u32 s23, s23, 0
	s_add_u32 s56, s56, 0x100
	s_addc_u32 s57, s57, 0
	s_cmp_gt_u32 s58, 13
	s_barrier
.LBB0_713:
	ds_read_b128 v[146:149], v143
	ds_read_b128 v[150:153], v143 offset:1024
	ds_read_b128 v[154:157], v143 offset:2048
	ds_read_b128 v[158:161], v143 offset:3072
	s_add_u32 s24, s22, 0xfffc0080
	s_addc_u32 s25, s23, -1
	s_cmp_eq_u32 s58, 12
	s_cselect_b32 s27, s15, s25
	s_cselect_b32 s26, s54, s24
	s_cselect_b32 s25, s13, s57
	s_cselect_b32 s24, s55, s56
	s_add_i32 m0, s21, 0xc000
	ds_read_b128 v[162:165], v144
	ds_read_b128 v[166:169], v144 offset:1024
	ds_read_b128 v[170:173], v144 offset:2048
	ds_read_b128 v[174:177], v144 offset:3072
	ds_read_b128 v[178:181], v144 offset:4096
	ds_read_b128 v[182:185], v144 offset:5120
	ds_read_b128 v[186:189], v144 offset:6144
	ds_read_b128 v[190:193], v144 offset:7168
	global_load_lds_dwordx4 v136, s[22:23]
	s_add_i32 m0, s21, 0xe000
	s_nop 0
	global_load_lds_dwordx4 v138, s[22:23]
	s_waitcnt lgkmcnt(8)
	s_waitcnt vmcnt(8)
	s_setprio 1
	s_barrier
	s_waitcnt lgkmcnt(0)
	s_waitcnt lgkmcnt(0)
	v_mfma_f32_16x16x32_bf16 v[124:127], v[146:149], v[162:165], v[124:127]
	v_mfma_f32_16x16x32_bf16 v[120:123], v[154:157], v[162:165], v[120:123]
	v_mfma_f32_16x16x32_bf16 v[116:119], v[146:149], v[170:173], v[116:119]
	v_mfma_f32_16x16x32_bf16 v[108:111], v[154:157], v[170:173], v[108:111]
	v_mfma_f32_16x16x32_bf16 v[100:103], v[146:149], v[178:181], v[100:103]
	v_mfma_f32_16x16x32_bf16 v[92:95], v[154:157], v[178:181], v[92:95]
	v_mfma_f32_16x16x32_bf16 v[84:87], v[146:149], v[186:189], v[84:87]
	v_mfma_f32_16x16x32_bf16 v[76:79], v[154:157], v[186:189], v[76:79]
	v_mfma_f32_16x16x32_bf16 v[124:127], v[150:153], v[166:169], v[124:127]
	v_mfma_f32_16x16x32_bf16 v[120:123], v[158:161], v[166:169], v[120:123]
	v_mfma_f32_16x16x32_bf16 v[116:119], v[150:153], v[174:177], v[116:119]
	v_mfma_f32_16x16x32_bf16 v[108:111], v[158:161], v[174:177], v[108:111]
	v_mfma_f32_16x16x32_bf16 v[100:103], v[150:153], v[182:185], v[100:103]
	v_mfma_f32_16x16x32_bf16 v[92:95], v[158:161], v[182:185], v[92:95]
	v_mfma_f32_16x16x32_bf16 v[84:87], v[150:153], v[190:193], v[84:87]
	v_mfma_f32_16x16x32_bf16 v[76:79], v[158:161], v[190:193], v[76:79]
	s_setprio 0
	s_barrier
	s_add_i32 s59, s46, s34
	s_mov_b32 m0, s59
	ds_read_b128 v[194:197], v145
	ds_read_b128 v[202:205], v145 offset:1024
	ds_read_b128 v[206:209], v145 offset:2048
	ds_read_b128 v[210:213], v145 offset:3072
	global_load_lds_dwordx4 v130, s[24:25]
	s_add_i32 m0, s59, 0x2000
	s_nop 0
	global_load_lds_dwordx4 v134, s[24:25]
	s_waitcnt vmcnt(8)
	s_setprio 1
	s_barrier
; #define PG8_STAGE(bufoff, gbase, voff) do { _Pragma("unroll") for (int _i = 0; _i < 2; ++_i) \
;         __builtin_amdgcn_global_load_lds((const unsigned*)((const char*)(gbase) + (voff)[_i]), (LAS unsigned*)(lds + (bufoff) + ldsw + _i * 8192), 16, 0, 0); } while (0)
; #define PG8_LDA(dst, b, h) do { _Pragma("unroll") for (int m = 0; m < 4; ++m) _Pragma("unroll") for (int k = 0; k < 2; ++k) dst[m][k] = *(const LAS bf16x8*)(lds + PG8_SA(b, h) + aoff + m * 2048 + k * 1024); } while (0)
; #define PG8_LDB(dst, b, h) do { _Pragma("unroll") for (int n = 0; n < 2; ++n) _Pragma("unroll") for (int k = 0; k < 2; ++k) dst[n][k] = *(const LAS bf16x8*)(lds + PG8_SB(b, h) + boff + n * 2048 + k * 1024); } while (0)
; #define PG8_WAIT_V(n) asm volatile("s_waitcnt vmcnt(" #n ")" ::: "memory")
; #define PG8_WAIT_L(n) asm volatile("s_waitcnt lgkmcnt(" #n ")" ::: "memory")
; #define PG8_BAR __builtin_amdgcn_s_barrier()
; #define PG8_SCHED __builtin_amdgcn_sched_barrier(0)
; template <class Epi, class Sched>
; __device__ __forceinline__ void gemm_phase(LAS unsigned char* lds, const Gemm g, const Sched& S, const Epi& E) {
;     ...
;             PG8_LDB(B0, 0, 0); PG8_SCHED; PG8_LDA(At, 0, 0); PG8_STAGE(PG8_SA(1, 1), a1 + hstep, voffA);
;             PG8_WAIT_L(8); PG8_BAR; PG8_WAIT_L(0); PG8_MMA(0, 0, At, B0); PG8_BAR; PG8_SCHED;
;             PG8_LDB(B1, 0, 1); PG8_STAGE(PG8_SB(0, 0), b2, voffB);
;             PG8_BAR; PG8_WAIT_L(0); PG8_MMA(0, 1, At, B1); PG8_BAR;
;             PG8_LDA(At, 0, 1); PG8_STAGE(PG8_SA(0, 0), a2, voffA);
;             PG8_BAR; PG8_WAIT_L(0); PG8_MMA(1, 0, At, B0); PG8_BAR; PG8_SCHED;
;             PG8_STAGE(PG8_SB(0, 1), b2 + hstep, voffB);
;             PG8_WAIT_V(6); PG8_BAR; PG8_MMA(1, 1, At, B1); PG8_BAR;
;             PG8_LDB(B0, 1, 0); PG8_SCHED; PG8_LDA(At, 1, 0); PG8_STAGE(PG8_SA(0, 1), a2 + hstep, voffA);
;             PG8_WAIT_L(8); PG8_BAR; PG8_WAIT_L(0); PG8_MMA(0, 0, At, B0); PG8_BAR; PG8_SCHED;
;             PG8_LDB(B1, 1, 1); PG8_STAGE(PG8_SB(1, 0), b3, voffB);
;             PG8_BAR; PG8_WAIT_L(0); PG8_MMA(0, 1, At, B1); PG8_BAR;
;             PG8_LDA(At, 1, 1); PG8_STAGE(PG8_SA(1, 0), a3, voffA);
;             PG8_BAR; PG8_WAIT_L(0); PG8_MMA(1, 0, At, B0); PG8_BAR; PG8_SCHED;
;             PG8_STAGE(PG8_SB(1, 1), b3 + hstep, voffB);
;             PG8_WAIT_V(6); PG8_BAR; PG8_MMA(1, 1, At, B1); PG8_BAR;
	s_waitcnt lgkmcnt(0)
	s_waitcnt lgkmcnt(0)
	v_mfma_f32_16x16x32_bf16 v[112:115], v[194:197], v[162:165], v[112:115]
	v_mfma_f32_16x16x32_bf16 v[104:107], v[206:209], v[162:165], v[104:107]
	v_mfma_f32_16x16x32_bf16 v[96:99], v[194:197], v[170:173], v[96:99]
	v_mfma_f32_16x16x32_bf16 v[88:91], v[206:209], v[170:173], v[88:91]
	v_mfma_f32_16x16x32_bf16 v[80:83], v[194:197], v[178:181], v[80:83]
	v_mfma_f32_16x16x32_bf16 v[72:75], v[206:209], v[178:181], v[72:75]
	v_mfma_f32_16x16x32_bf16 v[68:71], v[194:197], v[186:189], v[68:71]
	v_mfma_f32_16x16x32_bf16 v[64:67], v[206:209], v[186:189], v[64:67]
	v_mfma_f32_16x16x32_bf16 v[112:115], v[202:205], v[166:169], v[112:115]
	v_mfma_f32_16x16x32_bf16 v[104:107], v[210:213], v[166:169], v[104:107]
	v_mfma_f32_16x16x32_bf16 v[96:99], v[202:205], v[174:177], v[96:99]
	v_mfma_f32_16x16x32_bf16 v[88:91], v[210:213], v[174:177], v[88:91]
	v_mfma_f32_16x16x32_bf16 v[80:83], v[202:205], v[182:185], v[80:83]
	v_mfma_f32_16x16x32_bf16 v[72:75], v[210:213], v[182:185], v[72:75]
	v_mfma_f32_16x16x32_bf16 v[68:71], v[202:205], v[190:193], v[68:71]
	v_mfma_f32_16x16x32_bf16 v[64:67], v[210:213], v[190:193], v[64:67]
	s_setprio 0
	s_mov_b32 m0, s21
	v_lshl_add_u64 v[216:217], s[26:27], 0, v[128:129]
	s_barrier
	ds_read_b128 v[162:165], v144 offset:16384
	ds_read_b128 v[166:169], v144 offset:17408
	ds_read_b128 v[170:173], v144 offset:18432
	ds_read_b128 v[174:177], v144 offset:19456
	ds_read_b128 v[178:181], v144 offset:20480
	ds_read_b128 v[182:185], v144 offset:21504
	ds_read_b128 v[186:189], v144 offset:22528
	ds_read_b128 v[190:193], v144 offset:23552
	global_load_lds_dwordx4 v128, s[26:27]
	v_lshl_add_u64 v[218:219], s[26:27], 0, v[132:133]
	s_mov_b32 m0, s35
	s_nop 0
	global_load_lds_dwordx4 v132, s[26:27]
	s_setprio 1
	s_barrier
	s_waitcnt lgkmcnt(0)
	s_waitcnt lgkmcnt(0)
	v_mfma_f32_16x16x32_bf16 v[60:63], v[146:149], v[162:165], v[60:63]
	v_mfma_f32_16x16x32_bf16 v[56:59], v[154:157], v[162:165], v[56:59]
	v_mfma_f32_16x16x32_bf16 v[52:55], v[146:149], v[170:173], v[52:55]
	v_mfma_f32_16x16x32_bf16 v[44:47], v[154:157], v[170:173], v[44:47]
	v_mfma_f32_16x16x32_bf16 v[36:39], v[146:149], v[178:181], v[36:39]
	v_mfma_f32_16x16x32_bf16 v[28:31], v[154:157], v[178:181], v[28:31]
	v_mfma_f32_16x16x32_bf16 v[20:23], v[146:149], v[186:189], v[20:23]
	v_mfma_f32_16x16x32_bf16 v[12:15], v[154:157], v[186:189], v[12:15]
	v_mfma_f32_16x16x32_bf16 v[60:63], v[150:153], v[166:169], v[60:63]
	v_mfma_f32_16x16x32_bf16 v[56:59], v[158:161], v[166:169], v[56:59]
	v_mfma_f32_16x16x32_bf16 v[52:55], v[150:153], v[174:177], v[52:55]
	v_mfma_f32_16x16x32_bf16 v[44:47], v[158:161], v[174:177], v[44:47]
	v_mfma_f32_16x16x32_bf16 v[36:39], v[150:153], v[182:185], v[36:39]
	v_mfma_f32_16x16x32_bf16 v[28:31], v[158:161], v[182:185], v[28:31]
	v_mfma_f32_16x16x32_bf16 v[20:23], v[150:153], v[190:193], v[20:23]
	v_mfma_f32_16x16x32_bf16 v[12:15], v[158:161], v[190:193], v[12:15]
	s_setprio 0
	s_barrier
	s_add_u32 s60, s24, 0x40000
	s_addc_u32 s61, s25, 0
	s_add_i32 s59, s47, s34
	s_mov_b32 m0, s59
	s_nop 0
	global_load_lds_dwordx4 v130, s[60:61]
	s_add_i32 m0, s59, 0x2000
	s_nop 0
	global_load_lds_dwordx4 v134, s[60:61]
	s_add_u32 s26, s26, 0x40000
	s_addc_u32 s27, s27, 0
	s_mov_b32 m0, s36
	s_nop 0
	global_load_lds_dwordx4 v128, s[26:27]
	s_mov_b32 m0, s37
	s_nop 0
	global_load_lds_dwordx4 v132, s[26:27]
	s_waitcnt vmcnt(10)
	s_setprio 1
	s_barrier
	v_mfma_f32_16x16x32_bf16 v[48:51], v[194:197], v[162:165], v[48:51]
	v_mfma_f32_16x16x32_bf16 v[40:43], v[206:209], v[162:165], v[40:43]
	v_mfma_f32_16x16x32_bf16 v[32:35], v[194:197], v[170:173], v[32:35]
	v_mfma_f32_16x16x32_bf16 v[24:27], v[206:209], v[170:173], v[24:27]
	v_mfma_f32_16x16x32_bf16 v[16:19], v[194:197], v[178:181], v[16:19]
	v_mfma_f32_16x16x32_bf16 v[8:11], v[206:209], v[178:181], v[8:11]
	v_mfma_f32_16x16x32_bf16 v[4:7], v[194:197], v[186:189], v[4:7]
	v_mfma_f32_16x16x32_bf16 v[0:3], v[206:209], v[186:189], v[0:3]
	v_mfma_f32_16x16x32_bf16 v[48:51], v[202:205], v[166:169], v[48:51]
	v_mfma_f32_16x16x32_bf16 v[40:43], v[210:213], v[166:169], v[40:43]
	v_mfma_f32_16x16x32_bf16 v[32:35], v[202:205], v[174:177], v[32:35]
	v_mfma_f32_16x16x32_bf16 v[24:27], v[210:213], v[174:177], v[24:27]
	v_mfma_f32_16x16x32_bf16 v[16:19], v[202:205], v[182:185], v[16:19]
	v_mfma_f32_16x16x32_bf16 v[8:11], v[210:213], v[182:185], v[8:11]
	v_mfma_f32_16x16x32_bf16 v[4:7], v[202:205], v[190:193], v[4:7]
	v_mfma_f32_16x16x32_bf16 v[0:3], v[210:213], v[190:193], v[0:3]
	s_setprio 0
	s_add_i32 s59, 0, 0x18000
	v_add_u32_e32 v158, s59, v142
	s_barrier
	ds_read_b128 v[146:149], v158
	ds_read_b128 v[150:153], v158 offset:1024
	ds_read_b128 v[154:157], v158 offset:2048
	ds_read_b128 v[158:161], v158 offset:3072
	ds_read_b128 v[162:165], v144 offset:32768
	ds_read_b128 v[166:169], v144 offset:33792
	ds_read_b128 v[170:173], v144 offset:34816
	ds_read_b128 v[174:177], v144 offset:35840
	ds_read_b128 v[178:181], v144 offset:36864
	ds_read_b128 v[182:185], v144 offset:37888
	ds_read_b128 v[186:189], v144 offset:38912
	ds_read_b128 v[190:193], v144 offset:39936
	s_waitcnt lgkmcnt(8)
	s_waitcnt vmcnt(8)
	s_setprio 1
	s_barrier
; #define PG8_STAGE(bufoff, gbase, voff) do { _Pragma("unroll") for (int _i = 0; _i < 2; ++_i) \
;         __builtin_amdgcn_global_load_lds((const unsigned*)((const char*)(gbase) + (voff)[_i]), (LAS unsigned*)(lds + (bufoff) + ldsw + _i * 8192), 16, 0, 0); } while (0)
; #define PG8_LDA(dst, b, h) do { _Pragma("unroll") for (int m = 0; m < 4; ++m) _Pragma("unroll") for (int k = 0; k < 2; ++k) dst[m][k] = *(const LAS bf16x8*)(lds + PG8_SA(b, h) + aoff + m * 2048 + k * 1024); } while (0)
; #define PG8_LDB(dst, b, h) do { _Pragma("unroll") for (int n = 0; n < 2; ++n) _Pragma("unroll") for (int k = 0; k < 2; ++k) dst[n][k] = *(const LAS bf16x8*)(lds + PG8_SB(b, h) + boff + n * 2048 + k * 1024); } while (0)
; #define PG8_MMA(ai, bj, At, Bt) do { __builtin_amdgcn_s_setprio(1); _Pragma("unroll") for (int m = 0; m < 4; ++m) _Pragma("unroll") for (int n = 0; n < 2; ++n) _Pragma("unroll") for (int k = 0; k < 2; ++k) \
;         acc[ai][bj][m][n] = __builtin_amdgcn_mfma_f32_16x16x32_bf16(Bt[n][k], At[m][k], acc[ai][bj][m][n], 0, 0, 0); __builtin_amdgcn_s_setprio(0); } while (0)
; #define PG8_WAIT_V(n) asm volatile("s_waitcnt vmcnt(" #n ")" ::: "memory")
; #define PG8_WAIT_L(n) asm volatile("s_waitcnt lgkmcnt(" #n ")" ::: "memory")
; #define PG8_BAR __builtin_amdgcn_s_barrier()
; #define PG8_SCHED __builtin_amdgcn_sched_barrier(0)
; template <class Epi, class Sched>
; __device__ __forceinline__ void gemm_phase(LAS unsigned char* lds, const Gemm g, const Sched& S, const Epi& E) {
;     ...
;             PG8_BAR; PG8_WAIT_L(0); PG8_MMA(1, 0, At, B0); PG8_BAR; PG8_SCHED;
;             PG8_STAGE(PG8_SB(0, 1), b2 + hstep, voffB);
;             PG8_WAIT_V(6); PG8_BAR; PG8_MMA(1, 1, At, B1); PG8_BAR;
;             PG8_LDB(B0, 1, 0); PG8_SCHED; PG8_LDA(At, 1, 0); PG8_STAGE(PG8_SA(0, 1), a2 + hstep, voffA);
;             PG8_WAIT_L(8); PG8_BAR; PG8_WAIT_L(0); PG8_MMA(0, 0, At, B0); PG8_BAR; PG8_SCHED;
;             PG8_LDB(B1, 1, 1); PG8_STAGE(PG8_SB(1, 0), b3, voffB);
;             PG8_BAR; PG8_WAIT_L(0); PG8_MMA(0, 1, At, B1); PG8_BAR;
;             PG8_LDA(At, 1, 1); PG8_STAGE(PG8_SA(1, 0), a3, voffA);
;             PG8_BAR; PG8_WAIT_L(0); PG8_MMA(1, 0, At, B0); PG8_BAR; PG8_SCHED;
;             PG8_STAGE(PG8_SB(1, 1), b3 + hstep, voffB);
;             PG8_WAIT_V(6); PG8_BAR; PG8_MMA(1, 1, At, B1); PG8_BAR;
	s_waitcnt lgkmcnt(0)
	s_waitcnt lgkmcnt(0)
	v_mfma_f32_16x16x32_bf16 v[124:127], v[146:149], v[162:165], v[124:127]
	v_mfma_f32_16x16x32_bf16 v[120:123], v[154:157], v[162:165], v[120:123]
	v_mfma_f32_16x16x32_bf16 v[116:119], v[146:149], v[170:173], v[116:119]
	v_mfma_f32_16x16x32_bf16 v[108:111], v[154:157], v[170:173], v[108:111]
	v_mfma_f32_16x16x32_bf16 v[100:103], v[146:149], v[178:181], v[100:103]
	v_mfma_f32_16x16x32_bf16 v[92:95], v[154:157], v[178:181], v[92:95]
	v_mfma_f32_16x16x32_bf16 v[84:87], v[146:149], v[186:189], v[84:87]
	v_mfma_f32_16x16x32_bf16 v[76:79], v[154:157], v[186:189], v[76:79]
	v_mfma_f32_16x16x32_bf16 v[124:127], v[150:153], v[166:169], v[124:127]
	v_mfma_f32_16x16x32_bf16 v[120:123], v[158:161], v[166:169], v[120:123]
	v_mfma_f32_16x16x32_bf16 v[116:119], v[150:153], v[174:177], v[116:119]
	v_mfma_f32_16x16x32_bf16 v[108:111], v[158:161], v[174:177], v[108:111]
	v_mfma_f32_16x16x32_bf16 v[100:103], v[150:153], v[182:185], v[100:103]
	v_mfma_f32_16x16x32_bf16 v[92:95], v[158:161], v[182:185], v[92:95]
	v_mfma_f32_16x16x32_bf16 v[84:87], v[150:153], v[190:193], v[84:87]
	v_mfma_f32_16x16x32_bf16 v[76:79], v[158:161], v[190:193], v[76:79]
	s_setprio 0
	s_barrier
	s_add_i32 s26, 0, 0x1c000
	s_add_i32 s27, s59, s34
	v_add_u32_e32 v210, s26, v142
	s_add_u32 s0, s24, 0x80
	s_addc_u32 s1, s25, 0
	s_mov_b32 m0, s27
	ds_read_b128 v[194:197], v210
	ds_read_b128 v[202:205], v210 offset:1024
	ds_read_b128 v[206:209], v210 offset:2048
	ds_read_b128 v[210:213], v210 offset:3072
	global_load_lds_dwordx4 v130, s[0:1]
	s_add_i32 m0, s27, 0x2000
	s_nop 0
	global_load_lds_dwordx4 v134, s[0:1]
	s_waitcnt vmcnt(8)
	s_setprio 1
	s_barrier
	s_waitcnt lgkmcnt(0)
	s_waitcnt lgkmcnt(0)
	v_mfma_f32_16x16x32_bf16 v[112:115], v[194:197], v[162:165], v[112:115]
	v_mfma_f32_16x16x32_bf16 v[104:107], v[206:209], v[162:165], v[104:107]
	v_mfma_f32_16x16x32_bf16 v[96:99], v[194:197], v[170:173], v[96:99]
	v_mfma_f32_16x16x32_bf16 v[88:91], v[206:209], v[170:173], v[88:91]
	v_mfma_f32_16x16x32_bf16 v[80:83], v[194:197], v[178:181], v[80:83]
	v_mfma_f32_16x16x32_bf16 v[72:75], v[206:209], v[178:181], v[72:75]
	v_mfma_f32_16x16x32_bf16 v[68:71], v[194:197], v[186:189], v[68:71]
	v_mfma_f32_16x16x32_bf16 v[64:67], v[206:209], v[186:189], v[64:67]
	v_mfma_f32_16x16x32_bf16 v[112:115], v[202:205], v[166:169], v[112:115]
	v_mfma_f32_16x16x32_bf16 v[104:107], v[210:213], v[166:169], v[104:107]
	v_mfma_f32_16x16x32_bf16 v[96:99], v[202:205], v[174:177], v[96:99]
	v_mfma_f32_16x16x32_bf16 v[88:91], v[210:213], v[174:177], v[88:91]
	v_mfma_f32_16x16x32_bf16 v[80:83], v[202:205], v[182:185], v[80:83]
	v_mfma_f32_16x16x32_bf16 v[72:75], v[210:213], v[182:185], v[72:75]
	v_mfma_f32_16x16x32_bf16 v[68:71], v[202:205], v[190:193], v[68:71]
	v_mfma_f32_16x16x32_bf16 v[64:67], v[210:213], v[190:193], v[64:67]
	s_setprio 0
	s_mov_b32 m0, s43
	s_mov_b64 s[0:1], 0x80
	v_lshl_add_u64 v[198:199], v[216:217], 0, s[0:1]
	s_barrier
	ds_read_b128 v[162:165], v144 offset:49152
	ds_read_b128 v[166:169], v144 offset:50176
	ds_read_b128 v[170:173], v144 offset:51200
	ds_read_b128 v[174:177], v144 offset:52224
	ds_read_b128 v[178:181], v144 offset:53248
	ds_read_b128 v[182:185], v144 offset:54272
	ds_read_b128 v[186:189], v144 offset:55296
	ds_read_b128 v[190:193], v144 offset:56320
	global_load_lds_dwordx4 v[198:199], off
	v_lshl_add_u64 v[198:199], v[218:219], 0, s[0:1]
	s_mov_b32 m0, s44
	s_nop 0
	global_load_lds_dwordx4 v[198:199], off
	s_setprio 1
	s_barrier
	s_waitcnt lgkmcnt(0)
	s_waitcnt lgkmcnt(0)
	v_mfma_f32_16x16x32_bf16 v[60:63], v[146:149], v[162:165], v[60:63]
	v_mfma_f32_16x16x32_bf16 v[56:59], v[154:157], v[162:165], v[56:59]
	v_mfma_f32_16x16x32_bf16 v[52:55], v[146:149], v[170:173], v[52:55]
	v_mfma_f32_16x16x32_bf16 v[44:47], v[154:157], v[170:173], v[44:47]
	v_mfma_f32_16x16x32_bf16 v[36:39], v[146:149], v[178:181], v[36:39]
	v_mfma_f32_16x16x32_bf16 v[28:31], v[154:157], v[178:181], v[28:31]
	v_mfma_f32_16x16x32_bf16 v[20:23], v[146:149], v[186:189], v[20:23]
	v_mfma_f32_16x16x32_bf16 v[12:15], v[154:157], v[186:189], v[12:15]
	v_mfma_f32_16x16x32_bf16 v[60:63], v[150:153], v[166:169], v[60:63]
	v_mfma_f32_16x16x32_bf16 v[56:59], v[158:161], v[166:169], v[56:59]
	v_mfma_f32_16x16x32_bf16 v[52:55], v[150:153], v[174:177], v[52:55]
	v_mfma_f32_16x16x32_bf16 v[44:47], v[158:161], v[174:177], v[44:47]
	v_mfma_f32_16x16x32_bf16 v[36:39], v[150:153], v[182:185], v[36:39]
	v_mfma_f32_16x16x32_bf16 v[28:31], v[158:161], v[182:185], v[28:31]
	v_mfma_f32_16x16x32_bf16 v[20:23], v[150:153], v[190:193], v[20:23]
	v_mfma_f32_16x16x32_bf16 v[12:15], v[158:161], v[190:193], v[12:15]
	s_setprio 0
	s_barrier
	s_add_u32 s24, s24, 0x40080
	s_addc_u32 s25, s25, 0
	s_add_i32 s26, s26, s34
	s_mov_b32 m0, s26
	s_nop 0
	global_load_lds_dwordx4 v130, s[24:25]
	s_add_i32 m0, s26, 0x2000
	s_nop 0
	global_load_lds_dwordx4 v134, s[24:25]
	s_waitcnt vmcnt(8)
	s_setprio 1
	s_barrier
; __device__ __forceinline__ unsigned cvt_pk_bf16(float lo, float hi) { unsigned r; asm volatile("v_cvt_pk_bf16_f32 %0, %1, %2" : "=v"(r) : "v"(lo), "v"(hi)); return r; }
; #define PG8_MMA(ai, bj, At, Bt) do { __builtin_amdgcn_s_setprio(1); _Pragma("unroll") for (int m = 0; m < 4; ++m) _Pragma("unroll") for (int n = 0; n < 2; ++n) _Pragma("unroll") for (int k = 0; k < 2; ++k) \
;         acc[ai][bj][m][n] = __builtin_amdgcn_mfma_f32_16x16x32_bf16(Bt[n][k], At[m][k], acc[ai][bj][m][n], 0, 0, 0); __builtin_amdgcn_s_setprio(0); } while (0)
; #define PG8_WAIT_V(n) asm volatile("s_waitcnt vmcnt(" #n ")" ::: "memory")
; #define PG8_BAR __builtin_amdgcn_s_barrier()
; template <class Epi, class Sched>
; __device__ __forceinline__ void gemm_phase(LAS unsigned char* lds, const Gemm g, const Sched& S, const Epi& E) {
;     ...
;             PG8_WAIT_V(6); PG8_BAR; PG8_MMA(1, 1, At, B1); PG8_BAR;
;         }
;         E(acc, cur, wr, wc, fr, fq);
;         if (!has_next) break;
; #pragma unroll
;         for (int a = 0; a < 2; ++a)
; #pragma unroll
;             for (int b = 0; b < 2; ++b)
; #pragma unroll
;                 for (int m = 0; m < 4; ++m)
; #pragma unroll
;                     for (int n = 0; n < 2; ++n) acc[a][b][m][n] = (f32x4){0.f, 0.f, 0.f, 0.f};
;         cur = nxt; cA = nA; cB = nB; ++ui;
;     }
;     PG8_WAIT_V(0);
;     if (wr == 0) PG8_BAR;
;     PG8_BAR;
;     __device__ __forceinline__ void operator()(const AccT& acc, const Unit& u, int wr, int wc, int fr, int fq) const {
;         asm volatile("" : "+v"(fr), "+v"(fq));
;         const int rbase = u.pm * 256 + wr * 64 + fr;
;         const int tb = u.pn * 256 + wc * 32 + 8 * fq;
; #pragma unroll
;         for (int ai = 0; ai < 2; ++ai)
; #pragma unroll
;             for (int m = 0; m < 4; ++m) {
;                 const int r = rbase + ai * 128 + m * 16;
; #pragma unroll
;                 for (int bj = 0; bj < 2; ++bj) {
;                     const int t0 = tb + bj * 128;
;                     const f32x4 v0 = acc[ai][bj][m][0], v1 = acc[ai][bj][m][1];
;                     u32x4 w; w.x = cvt_pk_bf16(v0[0], v0[1]); w.y = cvt_pk_bf16(v0[2], v0[3]); w.z = cvt_pk_bf16(v1[0], v1[1]); w.w = cvt_pk_bf16(v1[2], v1[3]);
;                     *(u32x4*)(VT + (size_t)r * NT + t0) = w;
;                 }
;             }
;     }
	v_mfma_f32_16x16x32_bf16 v[48:51], v[194:197], v[162:165], v[48:51]
	v_mfma_f32_16x16x32_bf16 v[40:43], v[206:209], v[162:165], v[40:43]
	v_mfma_f32_16x16x32_bf16 v[32:35], v[194:197], v[170:173], v[32:35]
	v_mfma_f32_16x16x32_bf16 v[24:27], v[206:209], v[170:173], v[24:27]
	v_mfma_f32_16x16x32_bf16 v[16:19], v[194:197], v[178:181], v[16:19]
	v_mfma_f32_16x16x32_bf16 v[8:11], v[206:209], v[178:181], v[8:11]
	v_mfma_f32_16x16x32_bf16 v[4:7], v[194:197], v[186:189], v[4:7]
	v_mfma_f32_16x16x32_bf16 v[0:3], v[206:209], v[186:189], v[0:3]
	v_mfma_f32_16x16x32_bf16 v[48:51], v[202:205], v[166:169], v[48:51]
	v_mfma_f32_16x16x32_bf16 v[40:43], v[210:213], v[166:169], v[40:43]
	v_mfma_f32_16x16x32_bf16 v[32:35], v[202:205], v[174:177], v[32:35]
	v_mfma_f32_16x16x32_bf16 v[24:27], v[210:213], v[174:177], v[24:27]
	v_mfma_f32_16x16x32_bf16 v[16:19], v[202:205], v[182:185], v[16:19]
	v_mfma_f32_16x16x32_bf16 v[8:11], v[210:213], v[182:185], v[8:11]
	v_mfma_f32_16x16x32_bf16 v[4:7], v[202:205], v[190:193], v[4:7]
	v_mfma_f32_16x16x32_bf16 v[0:3], v[210:213], v[190:193], v[0:3]
	s_setprio 0
	s_add_i32 s58, s58, 2
	s_add_u32 s22, s22, 0x100
	s_addc_u32 s23, s23, 0
	s_add_u32 s56, s56, 0x100
	s_addc_u32 s57, s57, 0
	s_cmp_gt_u32 s58, 13
	s_barrier
	s_cbranch_scc0 .LBB0_713
	v_mov_b32_e32 v146, v140
	v_mov_b32_e32 v147, v141
	s_lshl_b32 s13, s20, 8
	s_add_i32 s13, s13, s41
	v_add_u32_e32 v146, s13, v146
	s_lshl_b32 s13, s53, 8
	s_or_b32 s13, s13, s42
	v_lshl_add_u32 v148, v147, 3, s13
	v_ashrrev_i32_e32 v147, 31, v146
	v_cvt_pk_bf16_f32 v124, v124, v125
	v_cvt_pk_bf16_f32 v125, v126, v127
	v_cvt_pk_bf16_f32 v126, v120, v121
	v_lshlrev_b64 v[120:121], 14, v[146:147]
	v_lshl_add_u64 v[120:121], s[62:63], 0, v[120:121]
	v_ashrrev_i32_e32 v149, 31, v148
	v_lshl_add_u64 v[120:121], v[148:149], 1, v[120:121]
	s_mov_b32 s13, 0x40000
	v_cvt_pk_bf16_f32 v127, v122, v123
	global_store_dwordx4 v[120:121], v[124:127], off
	v_cvt_pk_bf16_f32 v112, v112, v113
	v_cvt_pk_bf16_f32 v113, v114, v115
	v_cvt_pk_bf16_f32 v114, v104, v105
	v_cvt_pk_bf16_f32 v115, v106, v107
	global_store_dwordx4 v[120:121], v[112:115], off offset:256
	v_cvt_pk_bf16_f32 v104, v116, v117
	v_cvt_pk_bf16_f32 v105, v118, v119
	v_cvt_pk_bf16_f32 v106, v108, v109
	v_cvt_pk_bf16_f32 v107, v110, v111
	s_mov_b64 s[22:23], 0x40000
	v_add_co_u32_e32 v110, vcc, s13, v120
	v_lshl_add_u64 v[108:109], v[120:121], 0, s[22:23]
	s_nop 0
	v_addc_co_u32_e32 v111, vcc, 0, v121, vcc
	s_mov_b32 s13, 0x80000
	global_store_dwordx4 v[110:111], v[104:107], off
	v_cvt_pk_bf16_f32 v96, v96, v97
	v_cvt_pk_bf16_f32 v97, v98, v99
	v_cvt_pk_bf16_f32 v98, v88, v89
	v_cvt_pk_bf16_f32 v99, v90, v91
	global_store_dwordx4 v[108:109], v[96:99], off offset:256
	v_cvt_pk_bf16_f32 v88, v100, v101
	v_cvt_pk_bf16_f32 v89, v102, v103
	v_cvt_pk_bf16_f32 v90, v92, v93
	v_cvt_pk_bf16_f32 v91, v94, v95
	s_mov_b64 s[22:23], 0x80000
	v_add_co_u32_e32 v94, vcc, s13, v120
	v_lshl_add_u64 v[92:93], v[120:121], 0, s[22:23]
	s_nop 0
	v_addc_co_u32_e32 v95, vcc, 0, v121, vcc
	global_store_dwordx4 v[94:95], v[88:91], off
	v_cvt_pk_bf16_f32 v80, v80, v81
	v_cvt_pk_bf16_f32 v81, v82, v83
	v_cvt_pk_bf16_f32 v82, v72, v73
	v_cvt_pk_bf16_f32 v83, v74, v75
	global_store_dwordx4 v[92:93], v[80:83], off offset:256
	v_cvt_pk_bf16_f32 v72, v84, v85
	v_cvt_pk_bf16_f32 v73, v86, v87
	v_cvt_pk_bf16_f32 v74, v76, v77
	v_cvt_pk_bf16_f32 v75, v78, v79
	s_mov_b64 s[22:23], 0xc0000
	v_add_co_u32_e32 v78, vcc, s48, v120
	v_lshl_add_u64 v[76:77], v[120:121], 0, s[22:23]
	s_nop 0
	v_addc_co_u32_e32 v79, vcc, 0, v121, vcc
	global_store_dwordx4 v[78:79], v[72:75], off
	v_cvt_pk_bf16_f32 v68, v68, v69
	v_cvt_pk_bf16_f32 v69, v70, v71
	v_cvt_pk_bf16_f32 v70, v64, v65
	v_cvt_pk_bf16_f32 v71, v66, v67
	global_store_dwordx4 v[76:77], v[68:71], off offset:256
	v_cvt_pk_bf16_f32 v60, v60, v61
	v_cvt_pk_bf16_f32 v61, v62, v63
	v_cvt_pk_bf16_f32 v62, v56, v57
	v_cvt_pk_bf16_f32 v63, v58, v59
	v_add_co_u32_e32 v58, vcc, s49, v120
	v_lshl_add_u64 v[56:57], v[120:121], 0, s[2:3]
	s_nop 0
	v_addc_co_u32_e32 v59, vcc, 0, v121, vcc
	global_store_dwordx4 v[58:59], v[60:63], off
	v_cvt_pk_bf16_f32 v48, v48, v49
	v_cvt_pk_bf16_f32 v49, v50, v51
	v_cvt_pk_bf16_f32 v50, v40, v41
	v_cvt_pk_bf16_f32 v51, v42, v43
	global_store_dwordx4 v[56:57], v[48:51], off offset:256
	v_cvt_pk_bf16_f32 v40, v52, v53
	v_cvt_pk_bf16_f32 v41, v54, v55
	v_cvt_pk_bf16_f32 v42, v44, v45
	v_cvt_pk_bf16_f32 v43, v46, v47
	v_add_co_u32_e32 v46, vcc, s50, v120
	v_lshl_add_u64 v[44:45], v[120:121], 0, s[4:5]
	s_nop 0
	v_addc_co_u32_e32 v47, vcc, 0, v121, vcc
	global_store_dwordx4 v[46:47], v[40:43], off
	v_cvt_pk_bf16_f32 v32, v32, v33
	v_cvt_pk_bf16_f32 v33, v34, v35
	v_cvt_pk_bf16_f32 v34, v24, v25
	v_cvt_pk_bf16_f32 v35, v26, v27
	global_store_dwordx4 v[44:45], v[32:35], off offset:256
	v_cvt_pk_bf16_f32 v24, v36, v37
	v_cvt_pk_bf16_f32 v25, v38, v39
	v_cvt_pk_bf16_f32 v26, v28, v29
	v_cvt_pk_bf16_f32 v27, v30, v31
	v_add_co_u32_e32 v30, vcc, s51, v120
	v_lshl_add_u64 v[28:29], v[120:121], 0, s[6:7]
	s_nop 0
	v_addc_co_u32_e32 v31, vcc, 0, v121, vcc
	global_store_dwordx4 v[30:31], v[24:27], off
	v_cvt_pk_bf16_f32 v16, v16, v17
	v_cvt_pk_bf16_f32 v17, v18, v19
	v_cvt_pk_bf16_f32 v18, v8, v9
	v_cvt_pk_bf16_f32 v19, v10, v11
	global_store_dwordx4 v[28:29], v[16:19], off offset:256
	v_cvt_pk_bf16_f32 v8, v20, v21
	v_cvt_pk_bf16_f32 v9, v22, v23
	v_cvt_pk_bf16_f32 v10, v12, v13
	v_cvt_pk_bf16_f32 v11, v14, v15
	v_add_co_u32_e32 v14, vcc, s52, v120
	v_lshl_add_u64 v[12:13], v[120:121], 0, s[8:9]
	s_nop 0
	v_addc_co_u32_e32 v15, vcc, 0, v121, vcc
	s_and_b64 vcc, exec, s[10:11]
	s_mov_b32 s53, s12
	s_mov_b32 s20, s14
	s_mov_b64 s[24:25], s[18:19]
	s_mov_b64 s[22:23], s[16:17]
	global_store_dwordx4 v[14:15], v[8:11], off
	v_cvt_pk_bf16_f32 v4, v4, v5
	v_cvt_pk_bf16_f32 v5, v6, v7
	v_cvt_pk_bf16_f32 v6, v0, v1
	v_cvt_pk_bf16_f32 v7, v2, v3
	global_store_dwordx4 v[12:13], v[4:7], off offset:256
	s_cbranch_vccz .LBB0_706
	s_waitcnt vmcnt(0)
	s_cmpk_gt_u32 s31, 0xff
	s_cbranch_scc1 .LBB0_717
	s_barrier

; #define PG8_STAGE(bufoff, gbase, voff) do { _Pragma("unroll") for (int _i = 0; _i < 2; ++_i) \
;         __builtin_amdgcn_global_load_lds((const unsigned*)((const char*)(gbase) + (voff)[_i]), (LAS unsigned*)(lds + (bufoff) + ldsw + _i * 8192), 16, 0, 0); } while (0)
; #define PG8_LDA(dst, b, h) do { _Pragma("unroll") for (int m = 0; m < 4; ++m) _Pragma("unroll") for (int k = 0; k < 2; ++k) dst[m][k] = *(const LAS bf16x8*)(lds + PG8_SA(b, h) + aoff + m * 2048 + k * 1024); } while (0)
; #define PG8_LDB(dst, b, h) do { _Pragma("unroll") for (int n = 0; n < 2; ++n) _Pragma("unroll") for (int k = 0; k < 2; ++k) dst[n][k] = *(const LAS bf16x8*)(lds + PG8_SB(b, h) + boff + n * 2048 + k * 1024); } while (0)
; #define PG8_WAIT_V(n) asm volatile("s_waitcnt vmcnt(" #n ")" ::: "memory")
; #define PG8_WAIT_L(n) asm volatile("s_waitcnt lgkmcnt(" #n ")" ::: "memory")
; #define PG8_BAR __builtin_amdgcn_s_barrier()
; #define PG8_SCHED __builtin_amdgcn_sched_barrier(0)
; template <class Epi, class Sched>
; __device__ __forceinline__ void gemm_phase(LAS unsigned char* lds, const Gemm g, const Sched& S, const Epi& E) {
;     ...
;         const bool has_next = S.next(ui + 1, nxt);
;         const char* nA = has_next ? (const char*)g.A + (size_t)nxt.pm * tstep : cA; const char* nB = has_next ? (const char*)g.Bt + (size_t)nxt.pn * tstep : cB;
;         for (int t = 0; t < nt; t += 2) {
;             const bool last = (t == nt - 2);
;             const char* a1 = cA + (size_t)(t + 1) * kstep;
;             const char* a2 = last ? nA : cA + (size_t)(t + 2) * kstep; const char* b2 = last ? nB : cB + (size_t)(t + 2) * kstep;
;             const char* a3 = a2 + kstep; const char* b3 = b2 + kstep;
;             PG8_LDB(B0, 0, 0); PG8_SCHED; PG8_LDA(At, 0, 0); PG8_STAGE(PG8_SA(1, 1), a1 + hstep, voffA);
;             PG8_WAIT_L(8); PG8_BAR; PG8_WAIT_L(0); PG8_MMA(0, 0, At, B0); PG8_BAR; PG8_SCHED;
;             PG8_LDB(B1, 0, 1); PG8_STAGE(PG8_SB(0, 0), b2, voffB);
;             PG8_BAR; PG8_WAIT_L(0); PG8_MMA(0, 1, At, B1); PG8_BAR;
;             PG8_LDA(At, 0, 1); PG8_STAGE(PG8_SA(0, 0), a2, voffA);
;             PG8_BAR; PG8_WAIT_L(0); PG8_MMA(1, 0, At, B0); PG8_BAR; PG8_SCHED;
;             PG8_STAGE(PG8_SB(0, 1), b2 + hstep, voffB);
;             PG8_WAIT_V(6); PG8_BAR; PG8_MMA(1, 1, At, B1); PG8_BAR;
.LBB0_825:
	s_ashr_i32 s7, s6, 31
	v_cmp_lt_i64_e32 vcc, s[8:9], v[156:157]
	s_lshl_b64 s[8:9], s[6:7], 20
	s_add_u32 s8, s22, s8
	s_addc_u32 s9, s23, s9
	s_and_b64 s[10:11], vcc, exec
	s_cselect_b32 s7, s9, s15
	s_cselect_b32 s39, s8, s14
	s_ashr_i32 s5, s4, 31
	s_lshl_b64 s[10:11], s[4:5], 20
	s_add_u32 s10, s50, s10
	s_addc_u32 s11, s51, s11
	s_and_b64 s[18:19], vcc, exec
	s_cselect_b32 s5, s11, s17
	s_cselect_b32 s40, s10, s16
	s_add_u32 s14, s14, 0x80080
	s_addc_u32 s15, s15, 0
	s_add_u32 s41, s16, 0x100
	s_addc_u32 s42, s17, 0
	s_mov_b32 s43, -2
	ds_read_b128 v[128:131], v168
	ds_read_b128 v[132:135], v168 offset:1024
	ds_read_b128 v[136:139], v168 offset:2048
	ds_read_b128 v[140:143], v168 offset:3072
	s_add_u32 s16, s14, 0xfff80080
	s_addc_u32 s17, s15, -1
	s_cmp_eq_u32 s43, 28
	s_cselect_b32 s19, s7, s17
	s_cselect_b32 s18, s39, s16
	s_cselect_b32 s17, s5, s42
	s_cselect_b32 s16, s40, s41
	s_add_i32 m0, s13, 0xc000
	ds_read_b128 v[162:165], v169
	ds_read_b128 v[172:175], v169 offset:1024
	ds_read_b128 v[176:179], v169 offset:2048
	ds_read_b128 v[180:183], v169 offset:3072
	ds_read_b128 v[184:187], v169 offset:4096
	ds_read_b128 v[188:191], v169 offset:5120
	ds_read_b128 v[192:195], v169 offset:6144
	ds_read_b128 v[196:199], v169 offset:7168
	global_load_lds_dwordx4 v152, s[14:15]
	s_add_i32 m0, s13, 0xe000
	s_nop 0
	global_load_lds_dwordx4 v154, s[14:15]
	s_waitcnt lgkmcnt(8)
	s_waitcnt vmcnt(8)
	s_setprio 1
	s_barrier
	s_waitcnt lgkmcnt(0)
	s_waitcnt lgkmcnt(0)
	v_mfma_f32_16x16x32_bf16 v[124:127], v[128:131], v[162:165], 0
	v_mfma_f32_16x16x32_bf16 v[120:123], v[136:139], v[162:165], 0
	v_mfma_f32_16x16x32_bf16 v[116:119], v[128:131], v[176:179], 0
	v_mfma_f32_16x16x32_bf16 v[112:115], v[136:139], v[176:179], 0
	v_mfma_f32_16x16x32_bf16 v[108:111], v[128:131], v[184:187], 0
	v_mfma_f32_16x16x32_bf16 v[100:103], v[136:139], v[184:187], 0
	v_mfma_f32_16x16x32_bf16 v[76:79], v[128:131], v[192:195], 0
	v_mfma_f32_16x16x32_bf16 v[72:75], v[136:139], v[192:195], 0
	v_mfma_f32_16x16x32_bf16 v[124:127], v[132:135], v[172:175], v[124:127]
	v_mfma_f32_16x16x32_bf16 v[120:123], v[140:143], v[172:175], v[120:123]
	v_mfma_f32_16x16x32_bf16 v[116:119], v[132:135], v[180:183], v[116:119]
	v_mfma_f32_16x16x32_bf16 v[112:115], v[140:143], v[180:183], v[112:115]
	v_mfma_f32_16x16x32_bf16 v[108:111], v[132:135], v[188:191], v[108:111]
	v_mfma_f32_16x16x32_bf16 v[100:103], v[140:143], v[188:191], v[100:103]
	v_mfma_f32_16x16x32_bf16 v[76:79], v[132:135], v[196:199], v[76:79]
	v_mfma_f32_16x16x32_bf16 v[72:75], v[140:143], v[196:199], v[72:75]
	s_setprio 0
	s_barrier
	s_add_i32 s44, s35, s24
	s_mov_b32 m0, s44
	ds_read_b128 v[202:205], v170
	ds_read_b128 v[206:209], v170 offset:1024
	ds_read_b128 v[210:213], v170 offset:2048
	ds_read_b128 v[214:217], v170 offset:3072
	global_load_lds_dwordx4 v146, s[16:17]
	s_add_i32 m0, s44, 0x2000
	s_nop 0
	global_load_lds_dwordx4 v150, s[16:17]
	s_waitcnt vmcnt(8)
	s_setprio 1
	s_barrier
	s_waitcnt lgkmcnt(0)
	s_waitcnt lgkmcnt(0)
	v_mfma_f32_16x16x32_bf16 v[104:107], v[202:205], v[162:165], 0
	v_mfma_f32_16x16x32_bf16 v[96:99], v[210:213], v[162:165], 0
	v_mfma_f32_16x16x32_bf16 v[92:95], v[202:205], v[176:179], 0
	v_mfma_f32_16x16x32_bf16 v[88:91], v[210:213], v[176:179], 0
	v_mfma_f32_16x16x32_bf16 v[84:87], v[202:205], v[184:187], 0
	v_mfma_f32_16x16x32_bf16 v[80:83], v[210:213], v[184:187], 0
	v_mfma_f32_16x16x32_bf16 v[68:71], v[202:205], v[192:195], 0
	v_mfma_f32_16x16x32_bf16 v[64:67], v[210:213], v[192:195], 0
	v_mfma_f32_16x16x32_bf16 v[104:107], v[206:209], v[172:175], v[104:107]
	v_mfma_f32_16x16x32_bf16 v[96:99], v[214:217], v[172:175], v[96:99]
	v_mfma_f32_16x16x32_bf16 v[92:95], v[206:209], v[180:183], v[92:95]
	v_mfma_f32_16x16x32_bf16 v[88:91], v[214:217], v[180:183], v[88:91]
	v_mfma_f32_16x16x32_bf16 v[84:87], v[206:209], v[188:191], v[84:87]
	v_mfma_f32_16x16x32_bf16 v[80:83], v[214:217], v[188:191], v[80:83]
	v_mfma_f32_16x16x32_bf16 v[68:71], v[206:209], v[196:199], v[68:71]
	v_mfma_f32_16x16x32_bf16 v[64:67], v[214:217], v[196:199], v[64:67]
	s_setprio 0
	s_mov_b32 m0, s13
	v_lshl_add_u64 v[222:223], s[18:19], 0, v[144:145]
	s_barrier
	ds_read_b128 v[162:165], v169 offset:16384
	ds_read_b128 v[172:175], v169 offset:17408
	ds_read_b128 v[176:179], v169 offset:18432
	ds_read_b128 v[180:183], v169 offset:19456
	ds_read_b128 v[184:187], v169 offset:20480
	ds_read_b128 v[188:191], v169 offset:21504
	ds_read_b128 v[192:195], v169 offset:22528
	ds_read_b128 v[196:199], v169 offset:23552
	global_load_lds_dwordx4 v144, s[18:19]
	v_lshl_add_u64 v[224:225], s[18:19], 0, v[148:149]
	s_mov_b32 m0, s25
	s_nop 0
	global_load_lds_dwordx4 v148, s[18:19]
	s_setprio 1
	s_barrier
	s_waitcnt lgkmcnt(0)
	s_waitcnt lgkmcnt(0)
	v_mfma_f32_16x16x32_bf16 v[60:63], v[128:131], v[162:165], 0
	v_mfma_f32_16x16x32_bf16 v[56:59], v[136:139], v[162:165], 0
	v_mfma_f32_16x16x32_bf16 v[48:51], v[128:131], v[176:179], 0
	v_mfma_f32_16x16x32_bf16 v[40:43], v[136:139], v[176:179], 0
	v_mfma_f32_16x16x32_bf16 v[32:35], v[128:131], v[184:187], 0
	v_mfma_f32_16x16x32_bf16 v[24:27], v[136:139], v[184:187], 0
	v_mfma_f32_16x16x32_bf16 v[16:19], v[128:131], v[192:195], 0
	v_mfma_f32_16x16x32_bf16 v[8:11], v[136:139], v[192:195], 0
	v_mfma_f32_16x16x32_bf16 v[60:63], v[132:135], v[172:175], v[60:63]
	v_mfma_f32_16x16x32_bf16 v[56:59], v[140:143], v[172:175], v[56:59]
	v_mfma_f32_16x16x32_bf16 v[48:51], v[132:135], v[180:183], v[48:51]
	v_mfma_f32_16x16x32_bf16 v[40:43], v[140:143], v[180:183], v[40:43]
	v_mfma_f32_16x16x32_bf16 v[32:35], v[132:135], v[188:191], v[32:35]
	v_mfma_f32_16x16x32_bf16 v[24:27], v[140:143], v[188:191], v[24:27]
	v_mfma_f32_16x16x32_bf16 v[16:19], v[132:135], v[196:199], v[16:19]
	v_mfma_f32_16x16x32_bf16 v[8:11], v[140:143], v[196:199], v[8:11]
	s_setprio 0
	s_barrier
; #define PG8_STAGE(bufoff, gbase, voff) do { _Pragma("unroll") for (int _i = 0; _i < 2; ++_i) \
;         __builtin_amdgcn_global_load_lds((const unsigned*)((const char*)(gbase) + (voff)[_i]), (LAS unsigned*)(lds + (bufoff) + ldsw + _i * 8192), 16, 0, 0); } while (0)
; #define PG8_LDA(dst, b, h) do { _Pragma("unroll") for (int m = 0; m < 4; ++m) _Pragma("unroll") for (int k = 0; k < 2; ++k) dst[m][k] = *(const LAS bf16x8*)(lds + PG8_SA(b, h) + aoff + m * 2048 + k * 1024); } while (0)
; #define PG8_LDB(dst, b, h) do { _Pragma("unroll") for (int n = 0; n < 2; ++n) _Pragma("unroll") for (int k = 0; k < 2; ++k) dst[n][k] = *(const LAS bf16x8*)(lds + PG8_SB(b, h) + boff + n * 2048 + k * 1024); } while (0)
; #define PG8_MMA(ai, bj, At, Bt) do { __builtin_amdgcn_s_setprio(1); _Pragma("unroll") for (int m = 0; m < 4; ++m) _Pragma("unroll") for (int n = 0; n < 2; ++n) _Pragma("unroll") for (int k = 0; k < 2; ++k) \
;         acc[ai][bj][m][n] = __builtin_amdgcn_mfma_f32_16x16x32_bf16(Bt[n][k], At[m][k], acc[ai][bj][m][n], 0, 0, 0); __builtin_amdgcn_s_setprio(0); } while (0)
; #define PG8_WAIT_V(n) asm volatile("s_waitcnt vmcnt(" #n ")" ::: "memory")
; #define PG8_WAIT_L(n) asm volatile("s_waitcnt lgkmcnt(" #n ")" ::: "memory")
; #define PG8_BAR __builtin_amdgcn_s_barrier()
; #define PG8_SCHED __builtin_amdgcn_sched_barrier(0)
; template <class Epi, class Sched>
; __device__ __forceinline__ void gemm_phase(LAS unsigned char* lds, const Gemm g, const Sched& S, const Epi& E) {
;     ...
;             PG8_STAGE(PG8_SB(0, 1), b2 + hstep, voffB);
;             PG8_WAIT_V(6); PG8_BAR; PG8_MMA(1, 1, At, B1); PG8_BAR;
;             PG8_LDB(B0, 1, 0); PG8_SCHED; PG8_LDA(At, 1, 0); PG8_STAGE(PG8_SA(0, 1), a2 + hstep, voffA);
;             PG8_WAIT_L(8); PG8_BAR; PG8_WAIT_L(0); PG8_MMA(0, 0, At, B0); PG8_BAR; PG8_SCHED;
;             PG8_LDB(B1, 1, 1); PG8_STAGE(PG8_SB(1, 0), b3, voffB);
;             PG8_BAR; PG8_WAIT_L(0); PG8_MMA(0, 1, At, B1); PG8_BAR;
;             PG8_LDA(At, 1, 1); PG8_STAGE(PG8_SA(1, 0), a3, voffA);
;             PG8_BAR; PG8_WAIT_L(0); PG8_MMA(1, 0, At, B0); PG8_BAR; PG8_SCHED;
	s_add_u32 s44, s16, 0x80000
	s_addc_u32 s45, s17, 0
	s_add_i32 s46, s36, s24
	s_mov_b32 m0, s46
	s_nop 0
	global_load_lds_dwordx4 v146, s[44:45]
	s_add_i32 m0, s46, 0x2000
	s_nop 0
	global_load_lds_dwordx4 v150, s[44:45]
	s_add_u32 s18, s18, 0x80000
	s_addc_u32 s19, s19, 0
	s_mov_b32 m0, s26
	s_nop 0
	global_load_lds_dwordx4 v144, s[18:19]
	s_mov_b32 m0, s27
	s_nop 0
	global_load_lds_dwordx4 v148, s[18:19]
	s_waitcnt vmcnt(10)
	s_setprio 1
	s_barrier
	v_mfma_f32_16x16x32_bf16 v[52:55], v[202:205], v[162:165], 0
	v_mfma_f32_16x16x32_bf16 v[44:47], v[210:213], v[162:165], 0
	v_mfma_f32_16x16x32_bf16 v[36:39], v[202:205], v[176:179], 0
	v_mfma_f32_16x16x32_bf16 v[28:31], v[210:213], v[176:179], 0
	v_mfma_f32_16x16x32_bf16 v[20:23], v[202:205], v[184:187], 0
	v_mfma_f32_16x16x32_bf16 v[12:15], v[210:213], v[184:187], 0
	v_mfma_f32_16x16x32_bf16 v[4:7], v[202:205], v[192:195], 0
	v_mfma_f32_16x16x32_bf16 v[0:3], v[210:213], v[192:195], 0
	v_mfma_f32_16x16x32_bf16 v[52:55], v[206:209], v[172:175], v[52:55]
	v_mfma_f32_16x16x32_bf16 v[44:47], v[214:217], v[172:175], v[44:47]
	v_mfma_f32_16x16x32_bf16 v[36:39], v[206:209], v[180:183], v[36:39]
	v_mfma_f32_16x16x32_bf16 v[28:31], v[214:217], v[180:183], v[28:31]
	v_mfma_f32_16x16x32_bf16 v[20:23], v[206:209], v[188:191], v[20:23]
	v_mfma_f32_16x16x32_bf16 v[12:15], v[214:217], v[188:191], v[12:15]
	v_mfma_f32_16x16x32_bf16 v[4:7], v[206:209], v[196:199], v[4:7]
	v_mfma_f32_16x16x32_bf16 v[0:3], v[214:217], v[196:199], v[0:3]
	s_setprio 0
	s_add_i32 s44, 0, 0x18000
	v_add_u32_e32 v140, s44, v167
	s_barrier
	ds_read_b128 v[128:131], v140
	ds_read_b128 v[132:135], v140 offset:1024
	ds_read_b128 v[136:139], v140 offset:2048
	ds_read_b128 v[140:143], v140 offset:3072
	ds_read_b128 v[162:165], v169 offset:32768
	ds_read_b128 v[172:175], v169 offset:33792
	ds_read_b128 v[176:179], v169 offset:34816
	ds_read_b128 v[180:183], v169 offset:35840
	ds_read_b128 v[184:187], v169 offset:36864
	ds_read_b128 v[188:191], v169 offset:37888
	ds_read_b128 v[192:195], v169 offset:38912
	ds_read_b128 v[196:199], v169 offset:39936
	s_waitcnt lgkmcnt(8)
	s_waitcnt vmcnt(8)
	s_setprio 1
	s_barrier
	s_waitcnt lgkmcnt(0)
	s_waitcnt lgkmcnt(0)
	v_mfma_f32_16x16x32_bf16 v[124:127], v[128:131], v[162:165], v[124:127]
	v_mfma_f32_16x16x32_bf16 v[120:123], v[136:139], v[162:165], v[120:123]
	v_mfma_f32_16x16x32_bf16 v[116:119], v[128:131], v[176:179], v[116:119]
	v_mfma_f32_16x16x32_bf16 v[112:115], v[136:139], v[176:179], v[112:115]
	v_mfma_f32_16x16x32_bf16 v[108:111], v[128:131], v[184:187], v[108:111]
	v_mfma_f32_16x16x32_bf16 v[100:103], v[136:139], v[184:187], v[100:103]
	v_mfma_f32_16x16x32_bf16 v[76:79], v[128:131], v[192:195], v[76:79]
	v_mfma_f32_16x16x32_bf16 v[72:75], v[136:139], v[192:195], v[72:75]
	v_mfma_f32_16x16x32_bf16 v[124:127], v[132:135], v[172:175], v[124:127]
	v_mfma_f32_16x16x32_bf16 v[120:123], v[140:143], v[172:175], v[120:123]
	v_mfma_f32_16x16x32_bf16 v[116:119], v[132:135], v[180:183], v[116:119]
	v_mfma_f32_16x16x32_bf16 v[112:115], v[140:143], v[180:183], v[112:115]
	v_mfma_f32_16x16x32_bf16 v[108:111], v[132:135], v[188:191], v[108:111]
	v_mfma_f32_16x16x32_bf16 v[100:103], v[140:143], v[188:191], v[100:103]
	v_mfma_f32_16x16x32_bf16 v[76:79], v[132:135], v[196:199], v[76:79]
	v_mfma_f32_16x16x32_bf16 v[72:75], v[140:143], v[196:199], v[72:75]
	s_setprio 0
	s_barrier
	s_add_i32 s18, 0, 0x1c000
	s_add_i32 s19, s44, s24
	v_add_u32_e32 v160, s18, v167
	s_add_u32 s0, s16, 0x80
	s_addc_u32 s1, s17, 0
	s_mov_b32 m0, s19
	ds_read_b128 v[202:205], v160
	ds_read_b128 v[206:209], v160 offset:1024
	ds_read_b128 v[210:213], v160 offset:2048
	ds_read_b128 v[214:217], v160 offset:3072
	global_load_lds_dwordx4 v146, s[0:1]
	s_add_i32 m0, s19, 0x2000
	s_nop 0
	global_load_lds_dwordx4 v150, s[0:1]
	s_waitcnt vmcnt(8)
	s_setprio 1
	s_barrier
	s_waitcnt lgkmcnt(0)
	s_waitcnt lgkmcnt(0)
	v_mfma_f32_16x16x32_bf16 v[104:107], v[202:205], v[162:165], v[104:107]
	v_mfma_f32_16x16x32_bf16 v[96:99], v[210:213], v[162:165], v[96:99]
	v_mfma_f32_16x16x32_bf16 v[92:95], v[202:205], v[176:179], v[92:95]
	v_mfma_f32_16x16x32_bf16 v[88:91], v[210:213], v[176:179], v[88:91]
	v_mfma_f32_16x16x32_bf16 v[84:87], v[202:205], v[184:187], v[84:87]
	v_mfma_f32_16x16x32_bf16 v[80:83], v[210:213], v[184:187], v[80:83]
	v_mfma_f32_16x16x32_bf16 v[68:71], v[202:205], v[192:195], v[68:71]
	v_mfma_f32_16x16x32_bf16 v[64:67], v[210:213], v[192:195], v[64:67]
	v_mfma_f32_16x16x32_bf16 v[104:107], v[206:209], v[172:175], v[104:107]
	v_mfma_f32_16x16x32_bf16 v[96:99], v[214:217], v[172:175], v[96:99]
	v_mfma_f32_16x16x32_bf16 v[92:95], v[206:209], v[180:183], v[92:95]
	v_mfma_f32_16x16x32_bf16 v[88:91], v[214:217], v[180:183], v[88:91]
	v_mfma_f32_16x16x32_bf16 v[84:87], v[206:209], v[188:191], v[84:87]
	v_mfma_f32_16x16x32_bf16 v[80:83], v[214:217], v[188:191], v[80:83]
	v_mfma_f32_16x16x32_bf16 v[68:71], v[206:209], v[196:199], v[68:71]
	v_mfma_f32_16x16x32_bf16 v[64:67], v[214:217], v[196:199], v[64:67]
	s_setprio 0
	s_mov_b32 m0, s31
	s_mov_b64 s[0:1], 0x80
	v_lshl_add_u64 v[218:219], v[222:223], 0, s[0:1]
	s_barrier
	ds_read_b128 v[162:165], v169 offset:49152
	ds_read_b128 v[172:175], v169 offset:50176
	ds_read_b128 v[176:179], v169 offset:51200
	ds_read_b128 v[180:183], v169 offset:52224
	ds_read_b128 v[184:187], v169 offset:53248
	ds_read_b128 v[188:191], v169 offset:54272
	ds_read_b128 v[192:195], v169 offset:55296
	ds_read_b128 v[196:199], v169 offset:56320
	global_load_lds_dwordx4 v[218:219], off
	v_lshl_add_u64 v[218:219], v[224:225], 0, s[0:1]
	s_mov_b32 m0, s33
	s_nop 0
	global_load_lds_dwordx4 v[218:219], off
	s_setprio 1
	s_barrier
; #define PG8_STAGE(bufoff, gbase, voff) do { _Pragma("unroll") for (int _i = 0; _i < 2; ++_i) \
;         __builtin_amdgcn_global_load_lds((const unsigned*)((const char*)(gbase) + (voff)[_i]), (LAS unsigned*)(lds + (bufoff) + ldsw + _i * 8192), 16, 0, 0); } while (0)
; #define PG8_LDA(dst, b, h) do { _Pragma("unroll") for (int m = 0; m < 4; ++m) _Pragma("unroll") for (int k = 0; k < 2; ++k) dst[m][k] = *(const LAS bf16x8*)(lds + PG8_SA(b, h) + aoff + m * 2048 + k * 1024); } while (0)
; #define PG8_LDB(dst, b, h) do { _Pragma("unroll") for (int n = 0; n < 2; ++n) _Pragma("unroll") for (int k = 0; k < 2; ++k) dst[n][k] = *(const LAS bf16x8*)(lds + PG8_SB(b, h) + boff + n * 2048 + k * 1024); } while (0)
; #define PG8_WAIT_V(n) asm volatile("s_waitcnt vmcnt(" #n ")" ::: "memory")
; #define PG8_WAIT_L(n) asm volatile("s_waitcnt lgkmcnt(" #n ")" ::: "memory")
; #define PG8_BAR __builtin_amdgcn_s_barrier()
; #define PG8_SCHED __builtin_amdgcn_sched_barrier(0)
; template <class Epi, class Sched>
; __device__ __forceinline__ void gemm_phase(LAS unsigned char* lds, const Gemm g, const Sched& S, const Epi& E) {
;     ...
;             PG8_LDB(B0, 0, 0); PG8_SCHED; PG8_LDA(At, 0, 0); PG8_STAGE(PG8_SA(1, 1), a1 + hstep, voffA);
;             PG8_WAIT_L(8); PG8_BAR; PG8_WAIT_L(0); PG8_MMA(0, 0, At, B0); PG8_BAR; PG8_SCHED;
;             PG8_LDB(B1, 0, 1); PG8_STAGE(PG8_SB(0, 0), b2, voffB);
;             PG8_BAR; PG8_WAIT_L(0); PG8_MMA(0, 1, At, B1); PG8_BAR;
;             PG8_LDA(At, 0, 1); PG8_STAGE(PG8_SA(0, 0), a2, voffA);
;             PG8_BAR; PG8_WAIT_L(0); PG8_MMA(1, 0, At, B0); PG8_BAR; PG8_SCHED;
;             PG8_STAGE(PG8_SB(0, 1), b2 + hstep, voffB);
;             PG8_WAIT_V(6); PG8_BAR; PG8_MMA(1, 1, At, B1); PG8_BAR;
;             PG8_LDB(B0, 1, 0); PG8_SCHED; PG8_LDA(At, 1, 0); PG8_STAGE(PG8_SA(0, 1), a2 + hstep, voffA);
;             PG8_WAIT_L(8); PG8_BAR; PG8_WAIT_L(0); PG8_MMA(0, 0, At, B0); PG8_BAR; PG8_SCHED;
;             PG8_LDB(B1, 1, 1); PG8_STAGE(PG8_SB(1, 0), b3, voffB);
;             PG8_BAR; PG8_WAIT_L(0); PG8_MMA(0, 1, At, B1); PG8_BAR;
;             PG8_LDA(At, 1, 1); PG8_STAGE(PG8_SA(1, 0), a3, voffA);
;             PG8_BAR; PG8_WAIT_L(0); PG8_MMA(1, 0, At, B0); PG8_BAR; PG8_SCHED;
;             PG8_STAGE(PG8_SB(1, 1), b3 + hstep, voffB);
;             PG8_WAIT_V(6); PG8_BAR; PG8_MMA(1, 1, At, B1); PG8_BAR;
	s_waitcnt lgkmcnt(0)
	s_waitcnt lgkmcnt(0)
	v_mfma_f32_16x16x32_bf16 v[60:63], v[128:131], v[162:165], v[60:63]
	v_mfma_f32_16x16x32_bf16 v[56:59], v[136:139], v[162:165], v[56:59]
	v_mfma_f32_16x16x32_bf16 v[48:51], v[128:131], v[176:179], v[48:51]
	v_mfma_f32_16x16x32_bf16 v[40:43], v[136:139], v[176:179], v[40:43]
	v_mfma_f32_16x16x32_bf16 v[32:35], v[128:131], v[184:187], v[32:35]
	v_mfma_f32_16x16x32_bf16 v[24:27], v[136:139], v[184:187], v[24:27]
	v_mfma_f32_16x16x32_bf16 v[16:19], v[128:131], v[192:195], v[16:19]
	v_mfma_f32_16x16x32_bf16 v[8:11], v[136:139], v[192:195], v[8:11]
	v_mfma_f32_16x16x32_bf16 v[60:63], v[132:135], v[172:175], v[60:63]
	v_mfma_f32_16x16x32_bf16 v[56:59], v[140:143], v[172:175], v[56:59]
	v_mfma_f32_16x16x32_bf16 v[48:51], v[132:135], v[180:183], v[48:51]
	v_mfma_f32_16x16x32_bf16 v[40:43], v[140:143], v[180:183], v[40:43]
	v_mfma_f32_16x16x32_bf16 v[32:35], v[132:135], v[188:191], v[32:35]
	v_mfma_f32_16x16x32_bf16 v[24:27], v[140:143], v[188:191], v[24:27]
	v_mfma_f32_16x16x32_bf16 v[16:19], v[132:135], v[196:199], v[16:19]
	v_mfma_f32_16x16x32_bf16 v[8:11], v[140:143], v[196:199], v[8:11]
	s_setprio 0
	s_barrier
	s_add_u32 s16, s16, 0x80080
	s_addc_u32 s17, s17, 0
	s_add_i32 s18, s18, s24
	s_mov_b32 m0, s18
	s_nop 0
	global_load_lds_dwordx4 v146, s[16:17]
	s_add_i32 m0, s18, 0x2000
	s_nop 0
	global_load_lds_dwordx4 v150, s[16:17]
	s_waitcnt vmcnt(8)
	s_setprio 1
	s_barrier
	v_mfma_f32_16x16x32_bf16 v[52:55], v[202:205], v[162:165], v[52:55]
	v_mfma_f32_16x16x32_bf16 v[44:47], v[210:213], v[162:165], v[44:47]
	v_mfma_f32_16x16x32_bf16 v[36:39], v[202:205], v[176:179], v[36:39]
	v_mfma_f32_16x16x32_bf16 v[28:31], v[210:213], v[176:179], v[28:31]
	v_mfma_f32_16x16x32_bf16 v[20:23], v[202:205], v[184:187], v[20:23]
	v_mfma_f32_16x16x32_bf16 v[12:15], v[210:213], v[184:187], v[12:15]
	v_mfma_f32_16x16x32_bf16 v[4:7], v[202:205], v[192:195], v[4:7]
	v_mfma_f32_16x16x32_bf16 v[0:3], v[210:213], v[192:195], v[0:3]
	v_mfma_f32_16x16x32_bf16 v[52:55], v[206:209], v[172:175], v[52:55]
	v_mfma_f32_16x16x32_bf16 v[44:47], v[214:217], v[172:175], v[44:47]
	v_mfma_f32_16x16x32_bf16 v[36:39], v[206:209], v[180:183], v[36:39]
	v_mfma_f32_16x16x32_bf16 v[28:31], v[214:217], v[180:183], v[28:31]
	v_mfma_f32_16x16x32_bf16 v[20:23], v[206:209], v[188:191], v[20:23]
	v_mfma_f32_16x16x32_bf16 v[12:15], v[214:217], v[188:191], v[12:15]
	v_mfma_f32_16x16x32_bf16 v[4:7], v[206:209], v[196:199], v[4:7]
	v_mfma_f32_16x16x32_bf16 v[0:3], v[214:217], v[196:199], v[0:3]
	s_setprio 0
	s_add_i32 s43, s43, 2
	s_add_u32 s14, s14, 0x100
	s_addc_u32 s15, s15, 0
	s_add_u32 s41, s41, 0x100
	s_addc_u32 s42, s42, 0
	s_cmp_gt_u32 s43, 29
	s_barrier
.LBB0_826:
	ds_read_b128 v[128:131], v168
	ds_read_b128 v[132:135], v168 offset:1024
	ds_read_b128 v[136:139], v168 offset:2048
	ds_read_b128 v[140:143], v168 offset:3072
	s_add_u32 s16, s14, 0xfff80080
	s_addc_u32 s17, s15, -1
	s_cmp_eq_u32 s43, 28
	s_cselect_b32 s19, s7, s17
	s_cselect_b32 s18, s39, s16
	s_cselect_b32 s17, s5, s42
	s_cselect_b32 s16, s40, s41
	s_add_i32 m0, s13, 0xc000
	ds_read_b128 v[162:165], v169
	ds_read_b128 v[172:175], v169 offset:1024
	ds_read_b128 v[176:179], v169 offset:2048
	ds_read_b128 v[180:183], v169 offset:3072
	ds_read_b128 v[184:187], v169 offset:4096
	ds_read_b128 v[188:191], v169 offset:5120
	ds_read_b128 v[192:195], v169 offset:6144
	ds_read_b128 v[196:199], v169 offset:7168
	global_load_lds_dwordx4 v152, s[14:15]
	s_add_i32 m0, s13, 0xe000
	s_nop 0
	global_load_lds_dwordx4 v154, s[14:15]
	s_waitcnt lgkmcnt(8)
	s_waitcnt vmcnt(8)
	s_setprio 1
	s_barrier
	s_waitcnt lgkmcnt(0)
	s_waitcnt lgkmcnt(0)
	v_mfma_f32_16x16x32_bf16 v[124:127], v[128:131], v[162:165], v[124:127]
	v_mfma_f32_16x16x32_bf16 v[120:123], v[136:139], v[162:165], v[120:123]
	v_mfma_f32_16x16x32_bf16 v[116:119], v[128:131], v[176:179], v[116:119]
	v_mfma_f32_16x16x32_bf16 v[112:115], v[136:139], v[176:179], v[112:115]
	v_mfma_f32_16x16x32_bf16 v[108:111], v[128:131], v[184:187], v[108:111]
	v_mfma_f32_16x16x32_bf16 v[100:103], v[136:139], v[184:187], v[100:103]
	v_mfma_f32_16x16x32_bf16 v[76:79], v[128:131], v[192:195], v[76:79]
	v_mfma_f32_16x16x32_bf16 v[72:75], v[136:139], v[192:195], v[72:75]
	v_mfma_f32_16x16x32_bf16 v[124:127], v[132:135], v[172:175], v[124:127]
	v_mfma_f32_16x16x32_bf16 v[120:123], v[140:143], v[172:175], v[120:123]
	v_mfma_f32_16x16x32_bf16 v[116:119], v[132:135], v[180:183], v[116:119]
	v_mfma_f32_16x16x32_bf16 v[112:115], v[140:143], v[180:183], v[112:115]
	v_mfma_f32_16x16x32_bf16 v[108:111], v[132:135], v[188:191], v[108:111]
	v_mfma_f32_16x16x32_bf16 v[100:103], v[140:143], v[188:191], v[100:103]
	v_mfma_f32_16x16x32_bf16 v[76:79], v[132:135], v[196:199], v[76:79]
	v_mfma_f32_16x16x32_bf16 v[72:75], v[140:143], v[196:199], v[72:75]
	s_setprio 0
	s_barrier
	s_add_i32 s44, s35, s24
	s_mov_b32 m0, s44
	ds_read_b128 v[202:205], v170
	ds_read_b128 v[206:209], v170 offset:1024
	ds_read_b128 v[210:213], v170 offset:2048
	ds_read_b128 v[214:217], v170 offset:3072
	global_load_lds_dwordx4 v146, s[16:17]
	s_add_i32 m0, s44, 0x2000
	s_nop 0
	global_load_lds_dwordx4 v150, s[16:17]
	s_waitcnt vmcnt(8)
	s_setprio 1
	s_barrier
; #define PG8_STAGE(bufoff, gbase, voff) do { _Pragma("unroll") for (int _i = 0; _i < 2; ++_i) \
;         __builtin_amdgcn_global_load_lds((const unsigned*)((const char*)(gbase) + (voff)[_i]), (LAS unsigned*)(lds + (bufoff) + ldsw + _i * 8192), 16, 0, 0); } while (0)
; #define PG8_LDA(dst, b, h) do { _Pragma("unroll") for (int m = 0; m < 4; ++m) _Pragma("unroll") for (int k = 0; k < 2; ++k) dst[m][k] = *(const LAS bf16x8*)(lds + PG8_SA(b, h) + aoff + m * 2048 + k * 1024); } while (0)
; #define PG8_LDB(dst, b, h) do { _Pragma("unroll") for (int n = 0; n < 2; ++n) _Pragma("unroll") for (int k = 0; k < 2; ++k) dst[n][k] = *(const LAS bf16x8*)(lds + PG8_SB(b, h) + boff + n * 2048 + k * 1024); } while (0)
; #define PG8_MMA(ai, bj, At, Bt) do { __builtin_amdgcn_s_setprio(1); _Pragma("unroll") for (int m = 0; m < 4; ++m) _Pragma("unroll") for (int n = 0; n < 2; ++n) _Pragma("unroll") for (int k = 0; k < 2; ++k) \
;         acc[ai][bj][m][n] = __builtin_amdgcn_mfma_f32_16x16x32_bf16(Bt[n][k], At[m][k], acc[ai][bj][m][n], 0, 0, 0); __builtin_amdgcn_s_setprio(0); } while (0)
; #define PG8_WAIT_V(n) asm volatile("s_waitcnt vmcnt(" #n ")" ::: "memory")
; #define PG8_WAIT_L(n) asm volatile("s_waitcnt lgkmcnt(" #n ")" ::: "memory")
; #define PG8_BAR __builtin_amdgcn_s_barrier()
; #define PG8_SCHED __builtin_amdgcn_sched_barrier(0)
; template <class Epi, class Sched>
; __device__ __forceinline__ void gemm_phase(LAS unsigned char* lds, const Gemm g, const Sched& S, const Epi& E) {
;     ...
;             PG8_LDB(B1, 0, 1); PG8_STAGE(PG8_SB(0, 0), b2, voffB);
;             PG8_BAR; PG8_WAIT_L(0); PG8_MMA(0, 1, At, B1); PG8_BAR;
;             PG8_LDA(At, 0, 1); PG8_STAGE(PG8_SA(0, 0), a2, voffA);
;             PG8_BAR; PG8_WAIT_L(0); PG8_MMA(1, 0, At, B0); PG8_BAR; PG8_SCHED;
;             PG8_STAGE(PG8_SB(0, 1), b2 + hstep, voffB);
;             PG8_WAIT_V(6); PG8_BAR; PG8_MMA(1, 1, At, B1); PG8_BAR;
;             PG8_LDB(B0, 1, 0); PG8_SCHED; PG8_LDA(At, 1, 0); PG8_STAGE(PG8_SA(0, 1), a2 + hstep, voffA);
;             PG8_WAIT_L(8); PG8_BAR; PG8_WAIT_L(0); PG8_MMA(0, 0, At, B0); PG8_BAR; PG8_SCHED;
	s_waitcnt lgkmcnt(0)
	s_waitcnt lgkmcnt(0)
	v_mfma_f32_16x16x32_bf16 v[104:107], v[202:205], v[162:165], v[104:107]
	v_mfma_f32_16x16x32_bf16 v[96:99], v[210:213], v[162:165], v[96:99]
	v_mfma_f32_16x16x32_bf16 v[92:95], v[202:205], v[176:179], v[92:95]
	v_mfma_f32_16x16x32_bf16 v[88:91], v[210:213], v[176:179], v[88:91]
	v_mfma_f32_16x16x32_bf16 v[84:87], v[202:205], v[184:187], v[84:87]
	v_mfma_f32_16x16x32_bf16 v[80:83], v[210:213], v[184:187], v[80:83]
	v_mfma_f32_16x16x32_bf16 v[68:71], v[202:205], v[192:195], v[68:71]
	v_mfma_f32_16x16x32_bf16 v[64:67], v[210:213], v[192:195], v[64:67]
	v_mfma_f32_16x16x32_bf16 v[104:107], v[206:209], v[172:175], v[104:107]
	v_mfma_f32_16x16x32_bf16 v[96:99], v[214:217], v[172:175], v[96:99]
	v_mfma_f32_16x16x32_bf16 v[92:95], v[206:209], v[180:183], v[92:95]
	v_mfma_f32_16x16x32_bf16 v[88:91], v[214:217], v[180:183], v[88:91]
	v_mfma_f32_16x16x32_bf16 v[84:87], v[206:209], v[188:191], v[84:87]
	v_mfma_f32_16x16x32_bf16 v[80:83], v[214:217], v[188:191], v[80:83]
	v_mfma_f32_16x16x32_bf16 v[68:71], v[206:209], v[196:199], v[68:71]
	v_mfma_f32_16x16x32_bf16 v[64:67], v[214:217], v[196:199], v[64:67]
	s_setprio 0
	s_mov_b32 m0, s13
	v_lshl_add_u64 v[222:223], s[18:19], 0, v[144:145]
	s_barrier
	ds_read_b128 v[162:165], v169 offset:16384
	ds_read_b128 v[172:175], v169 offset:17408
	ds_read_b128 v[176:179], v169 offset:18432
	ds_read_b128 v[180:183], v169 offset:19456
	ds_read_b128 v[184:187], v169 offset:20480
	ds_read_b128 v[188:191], v169 offset:21504
	ds_read_b128 v[192:195], v169 offset:22528
	ds_read_b128 v[196:199], v169 offset:23552
	global_load_lds_dwordx4 v144, s[18:19]
	v_lshl_add_u64 v[224:225], s[18:19], 0, v[148:149]
	s_mov_b32 m0, s25
	s_nop 0
	global_load_lds_dwordx4 v148, s[18:19]
	s_setprio 1
	s_barrier
	s_waitcnt lgkmcnt(0)
	s_waitcnt lgkmcnt(0)
	v_mfma_f32_16x16x32_bf16 v[60:63], v[128:131], v[162:165], v[60:63]
	v_mfma_f32_16x16x32_bf16 v[56:59], v[136:139], v[162:165], v[56:59]
	v_mfma_f32_16x16x32_bf16 v[48:51], v[128:131], v[176:179], v[48:51]
	v_mfma_f32_16x16x32_bf16 v[40:43], v[136:139], v[176:179], v[40:43]
	v_mfma_f32_16x16x32_bf16 v[32:35], v[128:131], v[184:187], v[32:35]
	v_mfma_f32_16x16x32_bf16 v[24:27], v[136:139], v[184:187], v[24:27]
	v_mfma_f32_16x16x32_bf16 v[16:19], v[128:131], v[192:195], v[16:19]
	v_mfma_f32_16x16x32_bf16 v[8:11], v[136:139], v[192:195], v[8:11]
	v_mfma_f32_16x16x32_bf16 v[60:63], v[132:135], v[172:175], v[60:63]
	v_mfma_f32_16x16x32_bf16 v[56:59], v[140:143], v[172:175], v[56:59]
	v_mfma_f32_16x16x32_bf16 v[48:51], v[132:135], v[180:183], v[48:51]
	v_mfma_f32_16x16x32_bf16 v[40:43], v[140:143], v[180:183], v[40:43]
	v_mfma_f32_16x16x32_bf16 v[32:35], v[132:135], v[188:191], v[32:35]
	v_mfma_f32_16x16x32_bf16 v[24:27], v[140:143], v[188:191], v[24:27]
	v_mfma_f32_16x16x32_bf16 v[16:19], v[132:135], v[196:199], v[16:19]
	v_mfma_f32_16x16x32_bf16 v[8:11], v[140:143], v[196:199], v[8:11]
	s_setprio 0
	s_barrier
	s_add_u32 s44, s16, 0x80000
	s_addc_u32 s45, s17, 0
	s_add_i32 s46, s36, s24
	s_mov_b32 m0, s46
	s_nop 0
	global_load_lds_dwordx4 v146, s[44:45]
	s_add_i32 m0, s46, 0x2000
	s_nop 0
	global_load_lds_dwordx4 v150, s[44:45]
	s_add_u32 s18, s18, 0x80000
	s_addc_u32 s19, s19, 0
	s_mov_b32 m0, s26
	s_nop 0
	global_load_lds_dwordx4 v144, s[18:19]
	s_mov_b32 m0, s27
	s_nop 0
	global_load_lds_dwordx4 v148, s[18:19]
	s_waitcnt vmcnt(10)
	s_setprio 1
	s_barrier
	v_mfma_f32_16x16x32_bf16 v[52:55], v[202:205], v[162:165], v[52:55]
	v_mfma_f32_16x16x32_bf16 v[44:47], v[210:213], v[162:165], v[44:47]
	v_mfma_f32_16x16x32_bf16 v[36:39], v[202:205], v[176:179], v[36:39]
	v_mfma_f32_16x16x32_bf16 v[28:31], v[210:213], v[176:179], v[28:31]
	v_mfma_f32_16x16x32_bf16 v[20:23], v[202:205], v[184:187], v[20:23]
	v_mfma_f32_16x16x32_bf16 v[12:15], v[210:213], v[184:187], v[12:15]
	v_mfma_f32_16x16x32_bf16 v[4:7], v[202:205], v[192:195], v[4:7]
	v_mfma_f32_16x16x32_bf16 v[0:3], v[210:213], v[192:195], v[0:3]
	v_mfma_f32_16x16x32_bf16 v[52:55], v[206:209], v[172:175], v[52:55]
	v_mfma_f32_16x16x32_bf16 v[44:47], v[214:217], v[172:175], v[44:47]
	v_mfma_f32_16x16x32_bf16 v[36:39], v[206:209], v[180:183], v[36:39]
	v_mfma_f32_16x16x32_bf16 v[28:31], v[214:217], v[180:183], v[28:31]
	v_mfma_f32_16x16x32_bf16 v[20:23], v[206:209], v[188:191], v[20:23]
	v_mfma_f32_16x16x32_bf16 v[12:15], v[214:217], v[188:191], v[12:15]
	v_mfma_f32_16x16x32_bf16 v[4:7], v[206:209], v[196:199], v[4:7]
	v_mfma_f32_16x16x32_bf16 v[0:3], v[214:217], v[196:199], v[0:3]
	s_setprio 0
	s_add_i32 s44, 0, 0x18000
	v_add_u32_e32 v140, s44, v167
	s_barrier
	ds_read_b128 v[128:131], v140
	ds_read_b128 v[132:135], v140 offset:1024
	ds_read_b128 v[136:139], v140 offset:2048
	ds_read_b128 v[140:143], v140 offset:3072
	ds_read_b128 v[162:165], v169 offset:32768
	ds_read_b128 v[172:175], v169 offset:33792
	ds_read_b128 v[176:179], v169 offset:34816
	ds_read_b128 v[180:183], v169 offset:35840
	ds_read_b128 v[184:187], v169 offset:36864
	ds_read_b128 v[188:191], v169 offset:37888
	ds_read_b128 v[192:195], v169 offset:38912
	ds_read_b128 v[196:199], v169 offset:39936
	s_waitcnt lgkmcnt(8)
	s_waitcnt vmcnt(8)
	s_setprio 1
	s_barrier
; #define PG8_STAGE(bufoff, gbase, voff) do { _Pragma("unroll") for (int _i = 0; _i < 2; ++_i) \
;         __builtin_amdgcn_global_load_lds((const unsigned*)((const char*)(gbase) + (voff)[_i]), (LAS unsigned*)(lds + (bufoff) + ldsw + _i * 8192), 16, 0, 0); } while (0)
; #define PG8_LDA(dst, b, h) do { _Pragma("unroll") for (int m = 0; m < 4; ++m) _Pragma("unroll") for (int k = 0; k < 2; ++k) dst[m][k] = *(const LAS bf16x8*)(lds + PG8_SA(b, h) + aoff + m * 2048 + k * 1024); } while (0)
; #define PG8_LDB(dst, b, h) do { _Pragma("unroll") for (int n = 0; n < 2; ++n) _Pragma("unroll") for (int k = 0; k < 2; ++k) dst[n][k] = *(const LAS bf16x8*)(lds + PG8_SB(b, h) + boff + n * 2048 + k * 1024); } while (0)
; #define PG8_MMA(ai, bj, At, Bt) do { __builtin_amdgcn_s_setprio(1); _Pragma("unroll") for (int m = 0; m < 4; ++m) _Pragma("unroll") for (int n = 0; n < 2; ++n) _Pragma("unroll") for (int k = 0; k < 2; ++k) \
;         acc[ai][bj][m][n] = __builtin_amdgcn_mfma_f32_16x16x32_bf16(Bt[n][k], At[m][k], acc[ai][bj][m][n], 0, 0, 0); __builtin_amdgcn_s_setprio(0); } while (0)
; #define PG8_WAIT_V(n) asm volatile("s_waitcnt vmcnt(" #n ")" ::: "memory")
; #define PG8_WAIT_L(n) asm volatile("s_waitcnt lgkmcnt(" #n ")" ::: "memory")
; #define PG8_BAR __builtin_amdgcn_s_barrier()
; #define PG8_SCHED __builtin_amdgcn_sched_barrier(0)
; template <class Epi, class Sched>
; __device__ __forceinline__ void gemm_phase(LAS unsigned char* lds, const Gemm g, const Sched& S, const Epi& E) {
;     ...
;             PG8_WAIT_L(8); PG8_BAR; PG8_WAIT_L(0); PG8_MMA(0, 0, At, B0); PG8_BAR; PG8_SCHED;
;             PG8_LDB(B1, 1, 1); PG8_STAGE(PG8_SB(1, 0), b3, voffB);
;             PG8_BAR; PG8_WAIT_L(0); PG8_MMA(0, 1, At, B1); PG8_BAR;
;             PG8_LDA(At, 1, 1); PG8_STAGE(PG8_SA(1, 0), a3, voffA);
;             PG8_BAR; PG8_WAIT_L(0); PG8_MMA(1, 0, At, B0); PG8_BAR; PG8_SCHED;
;             PG8_STAGE(PG8_SB(1, 1), b3 + hstep, voffB);
;             PG8_WAIT_V(6); PG8_BAR; PG8_MMA(1, 1, At, B1); PG8_BAR;
	s_waitcnt lgkmcnt(0)
	s_waitcnt lgkmcnt(0)
	v_mfma_f32_16x16x32_bf16 v[124:127], v[128:131], v[162:165], v[124:127]
	v_mfma_f32_16x16x32_bf16 v[120:123], v[136:139], v[162:165], v[120:123]
	v_mfma_f32_16x16x32_bf16 v[116:119], v[128:131], v[176:179], v[116:119]
	v_mfma_f32_16x16x32_bf16 v[112:115], v[136:139], v[176:179], v[112:115]
	v_mfma_f32_16x16x32_bf16 v[108:111], v[128:131], v[184:187], v[108:111]
	v_mfma_f32_16x16x32_bf16 v[100:103], v[136:139], v[184:187], v[100:103]
	v_mfma_f32_16x16x32_bf16 v[76:79], v[128:131], v[192:195], v[76:79]
	v_mfma_f32_16x16x32_bf16 v[72:75], v[136:139], v[192:195], v[72:75]
	v_mfma_f32_16x16x32_bf16 v[124:127], v[132:135], v[172:175], v[124:127]
	v_mfma_f32_16x16x32_bf16 v[120:123], v[140:143], v[172:175], v[120:123]
	v_mfma_f32_16x16x32_bf16 v[116:119], v[132:135], v[180:183], v[116:119]
	v_mfma_f32_16x16x32_bf16 v[112:115], v[140:143], v[180:183], v[112:115]
	v_mfma_f32_16x16x32_bf16 v[108:111], v[132:135], v[188:191], v[108:111]
	v_mfma_f32_16x16x32_bf16 v[100:103], v[140:143], v[188:191], v[100:103]
	v_mfma_f32_16x16x32_bf16 v[76:79], v[132:135], v[196:199], v[76:79]
	v_mfma_f32_16x16x32_bf16 v[72:75], v[140:143], v[196:199], v[72:75]
	s_setprio 0
	s_barrier
	s_add_i32 s18, 0, 0x1c000
	s_add_i32 s19, s44, s24
	v_add_u32_e32 v160, s18, v167
	s_add_u32 s0, s16, 0x80
	s_addc_u32 s1, s17, 0
	s_mov_b32 m0, s19
	ds_read_b128 v[202:205], v160
	ds_read_b128 v[206:209], v160 offset:1024
	ds_read_b128 v[210:213], v160 offset:2048
	ds_read_b128 v[214:217], v160 offset:3072
	global_load_lds_dwordx4 v146, s[0:1]
	s_add_i32 m0, s19, 0x2000
	s_nop 0
	global_load_lds_dwordx4 v150, s[0:1]
	s_waitcnt vmcnt(8)
	s_setprio 1
	s_barrier
	s_waitcnt lgkmcnt(0)
	s_waitcnt lgkmcnt(0)
	v_mfma_f32_16x16x32_bf16 v[104:107], v[202:205], v[162:165], v[104:107]
	v_mfma_f32_16x16x32_bf16 v[96:99], v[210:213], v[162:165], v[96:99]
	v_mfma_f32_16x16x32_bf16 v[92:95], v[202:205], v[176:179], v[92:95]
	v_mfma_f32_16x16x32_bf16 v[88:91], v[210:213], v[176:179], v[88:91]
	v_mfma_f32_16x16x32_bf16 v[84:87], v[202:205], v[184:187], v[84:87]
	v_mfma_f32_16x16x32_bf16 v[80:83], v[210:213], v[184:187], v[80:83]
	v_mfma_f32_16x16x32_bf16 v[68:71], v[202:205], v[192:195], v[68:71]
	v_mfma_f32_16x16x32_bf16 v[64:67], v[210:213], v[192:195], v[64:67]
	v_mfma_f32_16x16x32_bf16 v[104:107], v[206:209], v[172:175], v[104:107]
	v_mfma_f32_16x16x32_bf16 v[96:99], v[214:217], v[172:175], v[96:99]
	v_mfma_f32_16x16x32_bf16 v[92:95], v[206:209], v[180:183], v[92:95]
	v_mfma_f32_16x16x32_bf16 v[88:91], v[214:217], v[180:183], v[88:91]
	v_mfma_f32_16x16x32_bf16 v[84:87], v[206:209], v[188:191], v[84:87]
	v_mfma_f32_16x16x32_bf16 v[80:83], v[214:217], v[188:191], v[80:83]
	v_mfma_f32_16x16x32_bf16 v[68:71], v[206:209], v[196:199], v[68:71]
	v_mfma_f32_16x16x32_bf16 v[64:67], v[214:217], v[196:199], v[64:67]
	s_setprio 0
	s_mov_b32 m0, s31
	s_mov_b64 s[0:1], 0x80
	v_lshl_add_u64 v[218:219], v[222:223], 0, s[0:1]
	s_barrier
	ds_read_b128 v[162:165], v169 offset:49152
	ds_read_b128 v[172:175], v169 offset:50176
	ds_read_b128 v[176:179], v169 offset:51200
	ds_read_b128 v[180:183], v169 offset:52224
	ds_read_b128 v[184:187], v169 offset:53248
	ds_read_b128 v[188:191], v169 offset:54272
	ds_read_b128 v[192:195], v169 offset:55296
	ds_read_b128 v[196:199], v169 offset:56320
	global_load_lds_dwordx4 v[218:219], off
	v_lshl_add_u64 v[218:219], v[224:225], 0, s[0:1]
	s_mov_b32 m0, s33
	s_nop 0
	global_load_lds_dwordx4 v[218:219], off
	s_setprio 1
	s_barrier
	s_waitcnt lgkmcnt(0)
	s_waitcnt lgkmcnt(0)
	v_mfma_f32_16x16x32_bf16 v[60:63], v[128:131], v[162:165], v[60:63]
	v_mfma_f32_16x16x32_bf16 v[56:59], v[136:139], v[162:165], v[56:59]
	v_mfma_f32_16x16x32_bf16 v[48:51], v[128:131], v[176:179], v[48:51]
	v_mfma_f32_16x16x32_bf16 v[40:43], v[136:139], v[176:179], v[40:43]
	v_mfma_f32_16x16x32_bf16 v[32:35], v[128:131], v[184:187], v[32:35]
	v_mfma_f32_16x16x32_bf16 v[24:27], v[136:139], v[184:187], v[24:27]
	v_mfma_f32_16x16x32_bf16 v[16:19], v[128:131], v[192:195], v[16:19]
	v_mfma_f32_16x16x32_bf16 v[8:11], v[136:139], v[192:195], v[8:11]
	v_mfma_f32_16x16x32_bf16 v[60:63], v[132:135], v[172:175], v[60:63]
	v_mfma_f32_16x16x32_bf16 v[56:59], v[140:143], v[172:175], v[56:59]
	v_mfma_f32_16x16x32_bf16 v[48:51], v[132:135], v[180:183], v[48:51]
	v_mfma_f32_16x16x32_bf16 v[40:43], v[140:143], v[180:183], v[40:43]
	v_mfma_f32_16x16x32_bf16 v[32:35], v[132:135], v[188:191], v[32:35]
	v_mfma_f32_16x16x32_bf16 v[24:27], v[140:143], v[188:191], v[24:27]
	v_mfma_f32_16x16x32_bf16 v[16:19], v[132:135], v[196:199], v[16:19]
	v_mfma_f32_16x16x32_bf16 v[8:11], v[140:143], v[196:199], v[8:11]
	s_setprio 0
	s_barrier
	s_add_u32 s16, s16, 0x80080
	s_addc_u32 s17, s17, 0
	s_add_i32 s18, s18, s24
	s_mov_b32 m0, s18
	s_nop 0
	global_load_lds_dwordx4 v146, s[16:17]
	s_add_i32 m0, s18, 0x2000
	s_nop 0
	global_load_lds_dwordx4 v150, s[16:17]
	s_waitcnt vmcnt(8)
	s_setprio 1
	s_barrier
	v_mfma_f32_16x16x32_bf16 v[52:55], v[202:205], v[162:165], v[52:55]
	v_mfma_f32_16x16x32_bf16 v[44:47], v[210:213], v[162:165], v[44:47]
	v_mfma_f32_16x16x32_bf16 v[36:39], v[202:205], v[176:179], v[36:39]
	v_mfma_f32_16x16x32_bf16 v[28:31], v[210:213], v[176:179], v[28:31]
	v_mfma_f32_16x16x32_bf16 v[20:23], v[202:205], v[184:187], v[20:23]
	v_mfma_f32_16x16x32_bf16 v[12:15], v[210:213], v[184:187], v[12:15]
	v_mfma_f32_16x16x32_bf16 v[4:7], v[202:205], v[192:195], v[4:7]
	v_mfma_f32_16x16x32_bf16 v[0:3], v[210:213], v[192:195], v[0:3]
	v_mfma_f32_16x16x32_bf16 v[52:55], v[206:209], v[172:175], v[52:55]
	v_mfma_f32_16x16x32_bf16 v[44:47], v[214:217], v[172:175], v[44:47]
	v_mfma_f32_16x16x32_bf16 v[36:39], v[206:209], v[180:183], v[36:39]
	v_mfma_f32_16x16x32_bf16 v[28:31], v[214:217], v[180:183], v[28:31]
	v_mfma_f32_16x16x32_bf16 v[20:23], v[206:209], v[188:191], v[20:23]
	v_mfma_f32_16x16x32_bf16 v[12:15], v[214:217], v[188:191], v[12:15]
	v_mfma_f32_16x16x32_bf16 v[4:7], v[206:209], v[196:199], v[4:7]
	v_mfma_f32_16x16x32_bf16 v[0:3], v[214:217], v[196:199], v[0:3]
	s_setprio 0
	s_add_i32 s43, s43, 2
	s_add_u32 s14, s14, 0x100
	s_addc_u32 s15, s15, 0
	s_add_u32 s41, s41, 0x100
	s_addc_u32 s42, s42, 0
	s_cmp_gt_u32 s43, 29
	s_barrier
; __device__ __forceinline__ unsigned cvt_pk_bf16(float lo, float hi) { unsigned r; asm volatile("v_cvt_pk_bf16_f32 %0, %1, %2" : "=v"(r) : "v"(lo), "v"(hi)); return r; }
;     __device__ __forceinline__ void operator()(const AccT& acc, const Unit& u, int wr, int wc, int fr, int fq) const {
;         asm volatile("" : "+v"(fr), "+v"(fq));
;         const int row0 = u.pm * 256 + wr * 64 + fr; const int b = u.pn >> 1, ch0 = (u.pn & 1) * 256 + wc * 32 + 8 * fq;
;         const float sg = (fr & 1) ? -1.0f : 1.0f;
;         f32x4 yh[2][2];
; #pragma unroll
;         for (int bj = 0; bj < 2; ++bj)
; #pragma unroll
;             for (int n = 0; n < 2; ++n) yh[bj][n] = *(const f32x4*)(YCH + b * 512 + ch0 + bj * 128 + 4 * n) * sg;
; #pragma unroll
;         for (int ai = 0; ai < 2; ++ai)
; #pragma unroll
;             for (int m = 0; m < 4; ++m) {
;                 const int k = row0 + ai * 128 + m * 16;
; #pragma unroll
;                 for (int bj = 0; bj < 2; ++bj) {
;                     const f32x4 v0 = acc[ai][bj][m][0] + yh[bj][0], v1 = acc[ai][bj][m][1] + yh[bj][1];
;                     u32x4 w; w.x = cvt_pk_bf16(v0[0], v0[1]); w.y = cvt_pk_bf16(v0[2], v0[3]); w.z = cvt_pk_bf16(v1[0], v1[1]); w.w = cvt_pk_bf16(v1[2], v1[3]);
;                     *(u32x4*)(CAT + (size_t)(b * 2048 + k) * CATW + 1024 + ch0 + bj * 128) = w;
;                 }
	s_cbranch_scc0 .LBB0_826
	s_ashr_i32 s5, s38, 1
	s_lshl_b32 s7, s38, 8
	s_lshl_b32 s14, s5, 9
	s_and_b32 s7, s7, 0x100
	s_ashr_i32 s15, s14, 31
	v_mov_b32_e32 v171, v161
	v_mov_b32_e32 v128, v166
	s_or_b32 s7, s7, s30
	s_lshl_b64 s[14:15], s[14:15], 2
	s_add_u32 s14, s48, s14
	v_lshl_add_u32 v164, v128, 3, s7
	s_addc_u32 s15, s49, s15
	v_ashrrev_i32_e32 v165, 31, v164
	v_lshl_add_u64 v[128:129], v[164:165], 2, s[14:15]
	global_load_dwordx4 v[140:143], v[128:129], off
	global_load_dwordx4 v[136:139], v[128:129], off offset:16
	global_load_dwordx4 v[132:135], v[128:129], off offset:512
	s_nop 0
	global_load_dwordx4 v[128:131], v[128:129], off offset:528
	s_lshl_b32 s7, s12, 8
	s_lshl_b32 s5, s5, 11
	s_add_i32 s7, s7, s29
	v_and_b32_e32 v160, 1, v171
	s_add_i32 s7, s7, s5
	v_mov_b64_e32 v[162:163], s[96:97]
	v_cmp_eq_u32_e32 vcc, 0, v160
	v_add_u32_e32 v171, s7, v171
	v_lshlrev_b64 v[164:165], 1, v[164:165]
	v_cndmask_b32_e64 v160, -1.0, 1.0, vcc
	v_mad_i64_i32 v[172:173], s[14:15], v171, s37, v[162:163]
	v_add_u32_e32 v174, 16, v171
	v_lshl_add_u64 v[172:173], v[172:173], 0, v[164:165]
	v_mad_i64_i32 v[174:175], s[14:15], v174, s37, v[162:163]
	v_add_u32_e32 v176, 32, v171
	v_lshl_add_u64 v[174:175], v[174:175], 0, v[164:165]
	v_mad_i64_i32 v[176:177], s[14:15], v176, s37, v[162:163]
	v_lshl_add_u64 v[176:177], v[176:177], 0, v[164:165]
	v_add_u32_e32 v182, 48, v171
	s_and_b64 vcc, exec, s[2:3]
	s_mov_b32 s38, s4
	s_mov_b32 s12, s6
	s_mov_b64 s[16:17], s[10:11]
	s_waitcnt vmcnt(0)
	v_pk_fma_f32 v[126:127], v[142:143], v[160:161], v[126:127] op_sel_hi:[1,0,1]
	v_pk_fma_f32 v[124:125], v[140:141], v[160:161], v[124:125] op_sel_hi:[1,0,1]
	v_pk_fma_f32 v[122:123], v[138:139], v[160:161], v[122:123] op_sel_hi:[1,0,1]
	v_pk_fma_f32 v[180:181], v[128:129], v[160:161], v[80:81] op_sel_hi:[1,0,1]
	v_cvt_pk_bf16_f32 v80, v124, v125
	v_cvt_pk_bf16_f32 v81, v126, v127
	v_pk_fma_f32 v[120:121], v[136:137], v[160:161], v[120:121] op_sel_hi:[1,0,1]
	v_pk_fma_f32 v[106:107], v[134:135], v[160:161], v[106:107] op_sel_hi:[1,0,1]
	v_pk_fma_f32 v[104:105], v[132:133], v[160:161], v[104:105] op_sel_hi:[1,0,1]
	v_pk_fma_f32 v[178:179], v[130:131], v[160:161], v[82:83] op_sel_hi:[1,0,1]
	v_cvt_pk_bf16_f32 v82, v120, v121
	v_cvt_pk_bf16_f32 v83, v122, v123
	global_store_dwordx4 v[172:173], v[80:83], off offset:2048
	v_pk_fma_f32 v[98:99], v[130:131], v[160:161], v[98:99] op_sel_hi:[1,0,1]
	v_pk_fma_f32 v[96:97], v[128:129], v[160:161], v[96:97] op_sel_hi:[1,0,1]
	v_cvt_pk_bf16_f32 v80, v104, v105
	v_cvt_pk_bf16_f32 v81, v106, v107
	v_pk_fma_f32 v[118:119], v[142:143], v[160:161], v[118:119] op_sel_hi:[1,0,1]
	v_pk_fma_f32 v[116:117], v[140:141], v[160:161], v[116:117] op_sel_hi:[1,0,1]
	v_cvt_pk_bf16_f32 v82, v96, v97
	v_cvt_pk_bf16_f32 v83, v98, v99
	global_store_dwordx4 v[172:173], v[80:83], off offset:2304
	v_pk_fma_f32 v[114:115], v[138:139], v[160:161], v[114:115] op_sel_hi:[1,0,1]
	v_pk_fma_f32 v[112:113], v[136:137], v[160:161], v[112:113] op_sel_hi:[1,0,1]
	v_cvt_pk_bf16_f32 v80, v116, v117
	v_cvt_pk_bf16_f32 v81, v118, v119
	v_pk_fma_f32 v[94:95], v[134:135], v[160:161], v[94:95] op_sel_hi:[1,0,1]
	v_pk_fma_f32 v[92:93], v[132:133], v[160:161], v[92:93] op_sel_hi:[1,0,1]
	v_cvt_pk_bf16_f32 v82, v112, v113
	v_cvt_pk_bf16_f32 v83, v114, v115
	global_store_dwordx4 v[174:175], v[80:83], off offset:2048
	v_pk_fma_f32 v[90:91], v[130:131], v[160:161], v[90:91] op_sel_hi:[1,0,1]
	v_pk_fma_f32 v[88:89], v[128:129], v[160:161], v[88:89] op_sel_hi:[1,0,1]
	v_cvt_pk_bf16_f32 v80, v92, v93
	v_cvt_pk_bf16_f32 v81, v94, v95
	v_pk_fma_f32 v[110:111], v[142:143], v[160:161], v[110:111] op_sel_hi:[1,0,1]
	v_pk_fma_f32 v[108:109], v[140:141], v[160:161], v[108:109] op_sel_hi:[1,0,1]
	v_cvt_pk_bf16_f32 v82, v88, v89
	v_cvt_pk_bf16_f32 v83, v90, v91
	global_store_dwordx4 v[174:175], v[80:83], off offset:2304
	v_pk_fma_f32 v[102:103], v[138:139], v[160:161], v[102:103] op_sel_hi:[1,0,1]
	v_pk_fma_f32 v[100:101], v[136:137], v[160:161], v[100:101] op_sel_hi:[1,0,1]
	v_cvt_pk_bf16_f32 v80, v108, v109
	v_cvt_pk_bf16_f32 v81, v110, v111
	v_pk_fma_f32 v[86:87], v[134:135], v[160:161], v[86:87] op_sel_hi:[1,0,1]
	v_pk_fma_f32 v[84:85], v[132:133], v[160:161], v[84:85] op_sel_hi:[1,0,1]
	v_cvt_pk_bf16_f32 v82, v100, v101
	v_cvt_pk_bf16_f32 v83, v102, v103
	global_store_dwordx4 v[176:177], v[80:83], off offset:2048
	v_pk_fma_f32 v[76:77], v[140:141], v[160:161], v[76:77] op_sel_hi:[1,0,1]
	v_pk_fma_f32 v[78:79], v[142:143], v[160:161], v[78:79] op_sel_hi:[1,0,1]
	v_cvt_pk_bf16_f32 v80, v84, v85
	v_cvt_pk_bf16_f32 v81, v86, v87
	v_cvt_pk_bf16_f32 v82, v180, v181
	v_cvt_pk_bf16_f32 v83, v178, v179
	global_store_dwordx4 v[176:177], v[80:83], off offset:2304
	v_pk_fma_f32 v[70:71], v[134:135], v[160:161], v[70:71] op_sel_hi:[1,0,1]
	v_pk_fma_f32 v[68:69], v[132:133], v[160:161], v[68:69] op_sel_hi:[1,0,1]
	v_pk_fma_f32 v[80:81], v[138:139], v[160:161], v[74:75] op_sel_hi:[1,0,1]
	v_pk_fma_f32 v[74:75], v[136:137], v[160:161], v[72:73] op_sel_hi:[1,0,1]
	v_cvt_pk_bf16_f32 v72, v76, v77
	v_mad_i64_i32 v[76:77], s[14:15], v182, s37, v[162:163]
	v_cvt_pk_bf16_f32 v73, v78, v79
; __device__ __forceinline__ unsigned cvt_pk_bf16(float lo, float hi) { unsigned r; asm volatile("v_cvt_pk_bf16_f32 %0, %1, %2" : "=v"(r) : "v"(lo), "v"(hi)); return r; }
; #define PG8_WAIT_V(n) asm volatile("s_waitcnt vmcnt(" #n ")" ::: "memory")
; #define PG8_BAR __builtin_amdgcn_s_barrier()
; template <class Epi, class Sched>
; __device__ __forceinline__ void gemm_phase(LAS unsigned char* lds, const Gemm g, const Sched& S, const Epi& E) {
;     ...
;         E(acc, cur, wr, wc, fr, fq);
;         if (!has_next) break;
; #pragma unroll
;         for (int a = 0; a < 2; ++a)
; #pragma unroll
;             for (int b = 0; b < 2; ++b)
; #pragma unroll
;                 for (int m = 0; m < 4; ++m)
; #pragma unroll
;                     for (int n = 0; n < 2; ++n) acc[a][b][m][n] = (f32x4){0.f, 0.f, 0.f, 0.f};
;         cur = nxt; cA = nA; cB = nB; ++ui;
;     }
;     PG8_WAIT_V(0);
;     if (wr == 0) PG8_BAR;
;     PG8_BAR;
;     __device__ __forceinline__ void operator()(const AccT& acc, const Unit& u, int wr, int wc, int fr, int fq) const {
;     ...
;         for (int ai = 0; ai < 2; ++ai)
; #pragma unroll
;             for (int m = 0; m < 4; ++m) {
;                 const int k = row0 + ai * 128 + m * 16;
; #pragma unroll
;                 for (int bj = 0; bj < 2; ++bj) {
;                     const f32x4 v0 = acc[ai][bj][m][0] + yh[bj][0], v1 = acc[ai][bj][m][1] + yh[bj][1];
;                     u32x4 w; w.x = cvt_pk_bf16(v0[0], v0[1]); w.y = cvt_pk_bf16(v0[2], v0[3]); w.z = cvt_pk_bf16(v1[0], v1[1]); w.w = cvt_pk_bf16(v1[2], v1[3]);
;                     *(u32x4*)(CAT + (size_t)(b * 2048 + k) * CATW + 1024 + ch0 + bj * 128) = w;
;                 }
	v_lshl_add_u64 v[76:77], v[76:77], 0, v[164:165]
	v_cvt_pk_bf16_f32 v74, v74, v75
	v_cvt_pk_bf16_f32 v75, v80, v81
	global_store_dwordx4 v[76:77], v[72:75], off offset:2048
	v_pk_fma_f32 v[60:61], v[140:141], v[160:161], v[60:61] op_sel_hi:[1,0,1]
	v_pk_fma_f32 v[62:63], v[142:143], v[160:161], v[62:63] op_sel_hi:[1,0,1]
	v_pk_fma_f32 v[72:73], v[130:131], v[160:161], v[66:67] op_sel_hi:[1,0,1]
	v_pk_fma_f32 v[66:67], v[128:129], v[160:161], v[64:65] op_sel_hi:[1,0,1]
	v_cvt_pk_bf16_f32 v64, v68, v69
	v_cvt_pk_bf16_f32 v65, v70, v71
	v_pk_fma_f32 v[54:55], v[134:135], v[160:161], v[54:55] op_sel_hi:[1,0,1]
	v_cvt_pk_bf16_f32 v66, v66, v67
	v_cvt_pk_bf16_f32 v67, v72, v73
	global_store_dwordx4 v[76:77], v[64:67], off offset:2304
	v_pk_fma_f32 v[52:53], v[132:133], v[160:161], v[52:53] op_sel_hi:[1,0,1]
	v_pk_fma_f32 v[38:39], v[134:135], v[160:161], v[38:39] op_sel_hi:[1,0,1]
	v_add_u32_e32 v66, 0x80, v171
	v_pk_fma_f32 v[64:65], v[138:139], v[160:161], v[58:59] op_sel_hi:[1,0,1]
	v_pk_fma_f32 v[58:59], v[136:137], v[160:161], v[56:57] op_sel_hi:[1,0,1]
	v_cvt_pk_bf16_f32 v56, v60, v61
	v_mad_i64_i32 v[60:61], s[14:15], v66, s37, v[162:163]
	v_cvt_pk_bf16_f32 v57, v62, v63
	v_lshl_add_u64 v[60:61], v[60:61], 0, v[164:165]
	v_cvt_pk_bf16_f32 v58, v58, v59
	v_cvt_pk_bf16_f32 v59, v64, v65
	global_store_dwordx4 v[60:61], v[56:59], off offset:2048
	v_pk_fma_f32 v[36:37], v[132:133], v[160:161], v[36:37] op_sel_hi:[1,0,1]
	v_pk_fma_f32 v[22:23], v[134:135], v[160:161], v[22:23] op_sel_hi:[1,0,1]
	v_pk_fma_f32 v[56:57], v[130:131], v[160:161], v[46:47] op_sel_hi:[1,0,1]
	v_pk_fma_f32 v[46:47], v[128:129], v[160:161], v[44:45] op_sel_hi:[1,0,1]
	v_cvt_pk_bf16_f32 v44, v52, v53
	v_cvt_pk_bf16_f32 v45, v54, v55
	v_add_u32_e32 v52, 0x90, v171
	v_cvt_pk_bf16_f32 v46, v46, v47
	v_cvt_pk_bf16_f32 v47, v56, v57
	global_store_dwordx4 v[60:61], v[44:47], off offset:2304
	v_pk_fma_f32 v[20:21], v[132:133], v[160:161], v[20:21] op_sel_hi:[1,0,1]
	v_pk_fma_f32 v[6:7], v[134:135], v[160:161], v[6:7] op_sel_hi:[1,0,1]
	v_pk_fma_f32 v[44:45], v[142:143], v[160:161], v[50:51] op_sel_hi:[1,0,1]
	v_pk_fma_f32 v[46:47], v[140:141], v[160:161], v[48:49] op_sel_hi:[1,0,1]
	v_pk_fma_f32 v[48:49], v[138:139], v[160:161], v[42:43] op_sel_hi:[1,0,1]
	v_pk_fma_f32 v[42:43], v[136:137], v[160:161], v[40:41] op_sel_hi:[1,0,1]
	v_cvt_pk_bf16_f32 v40, v46, v47
	v_cvt_pk_bf16_f32 v41, v44, v45
	v_mad_i64_i32 v[44:45], s[14:15], v52, s37, v[162:163]
	v_lshl_add_u64 v[44:45], v[44:45], 0, v[164:165]
	v_cvt_pk_bf16_f32 v42, v42, v43
	v_cvt_pk_bf16_f32 v43, v48, v49
	global_store_dwordx4 v[44:45], v[40:43], off offset:2048
	v_pk_fma_f32 v[4:5], v[132:133], v[160:161], v[4:5] op_sel_hi:[1,0,1]
	s_nop 0
	v_pk_fma_f32 v[40:41], v[130:131], v[160:161], v[30:31] op_sel_hi:[1,0,1]
	v_pk_fma_f32 v[30:31], v[128:129], v[160:161], v[28:29] op_sel_hi:[1,0,1]
	v_cvt_pk_bf16_f32 v28, v36, v37
	v_cvt_pk_bf16_f32 v29, v38, v39
	v_add_u32_e32 v36, 0xa0, v171
	v_cvt_pk_bf16_f32 v30, v30, v31
	v_cvt_pk_bf16_f32 v31, v40, v41
	global_store_dwordx4 v[44:45], v[28:31], off offset:2304
	s_nop 1
	v_pk_fma_f32 v[28:29], v[142:143], v[160:161], v[34:35] op_sel_hi:[1,0,1]
	v_pk_fma_f32 v[30:31], v[140:141], v[160:161], v[32:33] op_sel_hi:[1,0,1]
	v_pk_fma_f32 v[32:33], v[138:139], v[160:161], v[26:27] op_sel_hi:[1,0,1]
	v_pk_fma_f32 v[26:27], v[136:137], v[160:161], v[24:25] op_sel_hi:[1,0,1]
	v_cvt_pk_bf16_f32 v24, v30, v31
	v_cvt_pk_bf16_f32 v25, v28, v29
	v_mad_i64_i32 v[28:29], s[14:15], v36, s37, v[162:163]
	v_lshl_add_u64 v[28:29], v[28:29], 0, v[164:165]
	v_cvt_pk_bf16_f32 v26, v26, v27
	v_cvt_pk_bf16_f32 v27, v32, v33
	global_store_dwordx4 v[28:29], v[24:27], off offset:2048
	s_nop 1
	v_pk_fma_f32 v[24:25], v[130:131], v[160:161], v[14:15] op_sel_hi:[1,0,1]
	v_pk_fma_f32 v[14:15], v[128:129], v[160:161], v[12:13] op_sel_hi:[1,0,1]
	v_cvt_pk_bf16_f32 v12, v20, v21
	v_cvt_pk_bf16_f32 v13, v22, v23
	v_add_u32_e32 v20, 0xb0, v171
	v_cvt_pk_bf16_f32 v14, v14, v15
	v_cvt_pk_bf16_f32 v15, v24, v25
	global_store_dwordx4 v[28:29], v[12:15], off offset:2304
	s_nop 1
	v_pk_fma_f32 v[12:13], v[142:143], v[160:161], v[18:19] op_sel_hi:[1,0,1]
	v_pk_fma_f32 v[14:15], v[140:141], v[160:161], v[16:17] op_sel_hi:[1,0,1]
	v_pk_fma_f32 v[16:17], v[138:139], v[160:161], v[10:11] op_sel_hi:[1,0,1]
	v_pk_fma_f32 v[10:11], v[136:137], v[160:161], v[8:9] op_sel_hi:[1,0,1]
	v_cvt_pk_bf16_f32 v8, v14, v15
	v_cvt_pk_bf16_f32 v9, v12, v13
	v_mad_i64_i32 v[12:13], s[14:15], v20, s37, v[162:163]
	v_lshl_add_u64 v[12:13], v[12:13], 0, v[164:165]
	v_cvt_pk_bf16_f32 v10, v10, v11
	v_cvt_pk_bf16_f32 v11, v16, v17
	global_store_dwordx4 v[12:13], v[8:11], off offset:2048
	s_mov_b64 s[14:15], s[8:9]
	s_nop 0
	v_pk_fma_f32 v[8:9], v[130:131], v[160:161], v[2:3] op_sel_hi:[1,0,1]
	v_pk_fma_f32 v[2:3], v[128:129], v[160:161], v[0:1] op_sel_hi:[1,0,1]
	v_cvt_pk_bf16_f32 v0, v4, v5
	v_cvt_pk_bf16_f32 v1, v6, v7
	s_nop 0
	v_cvt_pk_bf16_f32 v2, v2, v3
	v_cvt_pk_bf16_f32 v3, v8, v9
	global_store_dwordx4 v[12:13], v[0:3], off offset:2304
	s_cbranch_vccz .LBB0_819
	s_waitcnt vmcnt(0)
	s_cmpk_gt_u32 s20, 0xff
	s_cbranch_scc1 .LBB0_830
	s_barrier

; #define PG8_STAGE(bufoff, gbase, voff) do { _Pragma("unroll") for (int _i = 0; _i < 2; ++_i) \
;         __builtin_amdgcn_global_load_lds((const unsigned*)((const char*)(gbase) + (voff)[_i]), (LAS unsigned*)(lds + (bufoff) + ldsw + _i * 8192), 16, 0, 0); } while (0)
; #define PG8_LDA(dst, b, h) do { _Pragma("unroll") for (int m = 0; m < 4; ++m) _Pragma("unroll") for (int k = 0; k < 2; ++k) dst[m][k] = *(const LAS bf16x8*)(lds + PG8_SA(b, h) + aoff + m * 2048 + k * 1024); } while (0)
; #define PG8_LDB(dst, b, h) do { _Pragma("unroll") for (int n = 0; n < 2; ++n) _Pragma("unroll") for (int k = 0; k < 2; ++k) dst[n][k] = *(const LAS bf16x8*)(lds + PG8_SB(b, h) + boff + n * 2048 + k * 1024); } while (0)
; #define PG8_WAIT_V(n) asm volatile("s_waitcnt vmcnt(" #n ")" ::: "memory")
; #define PG8_WAIT_L(n) asm volatile("s_waitcnt lgkmcnt(" #n ")" ::: "memory")
; #define PG8_BAR __builtin_amdgcn_s_barrier()
; #define PG8_SCHED __builtin_amdgcn_sched_barrier(0)
; template <class Epi, class Sched>
; __device__ __forceinline__ void gemm_phase(LAS unsigned char* lds, const Gemm g, const Sched& S, const Epi& E) {
;     ...
;     for (;;) {
;         const bool has_next = S.next(ui + 1, nxt);
;         const char* nA = has_next ? (const char*)g.A + (size_t)nxt.pm * tstep : cA; const char* nB = has_next ? (const char*)g.Bt + (size_t)nxt.pn * tstep : cB;
;         for (int t = 0; t < nt; t += 2) {
;             const bool last = (t == nt - 2);
;             const char* a1 = cA + (size_t)(t + 1) * kstep;
;             const char* a2 = last ? nA : cA + (size_t)(t + 2) * kstep; const char* b2 = last ? nB : cB + (size_t)(t + 2) * kstep;
;             const char* a3 = a2 + kstep; const char* b3 = b2 + kstep;
;             PG8_LDB(B0, 0, 0); PG8_SCHED; PG8_LDA(At, 0, 0); PG8_STAGE(PG8_SA(1, 1), a1 + hstep, voffA);
;             PG8_WAIT_L(8); PG8_BAR; PG8_WAIT_L(0); PG8_MMA(0, 0, At, B0); PG8_BAR; PG8_SCHED;
;             PG8_LDB(B1, 0, 1); PG8_STAGE(PG8_SB(0, 0), b2, voffB);
;             PG8_BAR; PG8_WAIT_L(0); PG8_MMA(0, 1, At, B1); PG8_BAR;
;             PG8_LDA(At, 0, 1); PG8_STAGE(PG8_SA(0, 0), a2, voffA);
;             PG8_BAR; PG8_WAIT_L(0); PG8_MMA(1, 0, At, B0); PG8_BAR; PG8_SCHED;
;             PG8_STAGE(PG8_SB(0, 1), b2 + hstep, voffB);
;             PG8_WAIT_V(6); PG8_BAR; PG8_MMA(1, 1, At, B1); PG8_BAR;
.LBB0_901:
	s_add_u32 s56, s26, 0x100
	s_addc_u32 s57, s27, 0
	s_mov_b32 s58, -2
	s_waitcnt vmcnt(0)
	ds_read_b128 v[128:131], v237
	ds_read_b128 v[132:135], v237 offset:1024
	ds_read_b128 v[136:139], v237 offset:2048
	ds_read_b128 v[140:143], v237 offset:3072
	s_add_u32 s26, s24, 0x100
	s_addc_u32 s27, s25, 0
	s_cmp_eq_u32 s58, 20
	s_cselect_b32 s31, s5, s27
	s_cselect_b32 s30, s4, s26
	s_cselect_b32 s29, s7, s57
	s_cselect_b32 s28, s6, s56
	v_lshl_add_u64 v[176:177], s[24:25], 0, v[210:211]
	s_add_i32 m0, s38, 0xc000
	ds_read_b128 v[144:147], v238
	ds_read_b128 v[148:151], v238 offset:1024
	ds_read_b128 v[152:155], v238 offset:2048
	ds_read_b128 v[156:159], v238 offset:3072
	ds_read_b128 v[160:163], v238 offset:4096
	ds_read_b128 v[164:167], v238 offset:5120
	ds_read_b128 v[168:171], v238 offset:6144
	ds_read_b128 v[172:175], v238 offset:7168
	global_load_lds_dwordx4 v[176:177], off
	v_lshl_add_u64 v[176:177], s[24:25], 0, v[212:213]
	s_add_i32 m0, s38, 0xe000
	s_nop 0
	global_load_lds_dwordx4 v[176:177], off
	s_waitcnt lgkmcnt(8)
	s_waitcnt vmcnt(8)
	s_setprio 1
	s_barrier
	s_waitcnt lgkmcnt(0)
	s_waitcnt lgkmcnt(0)
	v_mfma_f32_16x16x32_bf16 v[124:127], v[128:131], v[144:147], 0
	v_mfma_f32_16x16x32_bf16 v[120:123], v[136:139], v[144:147], 0
	v_mfma_f32_16x16x32_bf16 v[108:111], v[128:131], v[152:155], 0
	v_mfma_f32_16x16x32_bf16 v[104:107], v[136:139], v[152:155], 0
	v_mfma_f32_16x16x32_bf16 v[92:95], v[128:131], v[160:163], 0
	v_mfma_f32_16x16x32_bf16 v[88:91], v[136:139], v[160:163], 0
	v_mfma_f32_16x16x32_bf16 v[76:79], v[128:131], v[168:171], 0
	v_mfma_f32_16x16x32_bf16 v[72:75], v[136:139], v[168:171], 0
	v_mfma_f32_16x16x32_bf16 v[124:127], v[132:135], v[148:151], v[124:127]
	v_mfma_f32_16x16x32_bf16 v[120:123], v[140:143], v[148:151], v[120:123]
	v_mfma_f32_16x16x32_bf16 v[108:111], v[132:135], v[156:159], v[108:111]
	v_mfma_f32_16x16x32_bf16 v[104:107], v[140:143], v[156:159], v[104:107]
	v_mfma_f32_16x16x32_bf16 v[92:95], v[132:135], v[164:167], v[92:95]
	v_mfma_f32_16x16x32_bf16 v[88:91], v[140:143], v[164:167], v[88:91]
	v_mfma_f32_16x16x32_bf16 v[76:79], v[132:135], v[172:175], v[76:79]
	v_mfma_f32_16x16x32_bf16 v[72:75], v[140:143], v[172:175], v[72:75]
	s_setprio 0
	s_barrier
	s_add_i32 s24, s50, s37
	s_mov_b32 m0, s24
	ds_read_b128 v[176:179], v239
	ds_read_b128 v[180:183], v239 offset:1024
	ds_read_b128 v[184:187], v239 offset:2048
	ds_read_b128 v[188:191], v239 offset:3072
	global_load_lds_dwordx4 v204, s[28:29]
	s_add_i32 m0, s24, 0x2000
	s_nop 0
	global_load_lds_dwordx4 v208, s[28:29]
	s_waitcnt vmcnt(8)
	s_setprio 1
	s_barrier
	s_waitcnt lgkmcnt(0)
	s_waitcnt lgkmcnt(0)
	v_mfma_f32_16x16x32_bf16 v[116:119], v[176:179], v[144:147], 0
	v_mfma_f32_16x16x32_bf16 v[112:115], v[184:187], v[144:147], 0
	v_mfma_f32_16x16x32_bf16 v[100:103], v[176:179], v[152:155], 0
	v_mfma_f32_16x16x32_bf16 v[96:99], v[184:187], v[152:155], 0
	v_mfma_f32_16x16x32_bf16 v[84:87], v[176:179], v[160:163], 0
	v_mfma_f32_16x16x32_bf16 v[80:83], v[184:187], v[160:163], 0
	v_mfma_f32_16x16x32_bf16 v[68:71], v[176:179], v[168:171], 0
	v_mfma_f32_16x16x32_bf16 v[64:67], v[184:187], v[168:171], 0
	v_mfma_f32_16x16x32_bf16 v[116:119], v[180:183], v[148:151], v[116:119]
	v_mfma_f32_16x16x32_bf16 v[112:115], v[188:191], v[148:151], v[112:115]
	v_mfma_f32_16x16x32_bf16 v[100:103], v[180:183], v[156:159], v[100:103]
	v_mfma_f32_16x16x32_bf16 v[96:99], v[188:191], v[156:159], v[96:99]
	v_mfma_f32_16x16x32_bf16 v[84:87], v[180:183], v[164:167], v[84:87]
	v_mfma_f32_16x16x32_bf16 v[80:83], v[188:191], v[164:167], v[80:83]
	v_mfma_f32_16x16x32_bf16 v[68:71], v[180:183], v[172:175], v[68:71]
	v_mfma_f32_16x16x32_bf16 v[64:67], v[188:191], v[172:175], v[64:67]
	s_setprio 0
	s_mov_b32 m0, s38
	v_lshl_add_u64 v[196:197], s[30:31], 0, v[202:203]
	s_barrier
	ds_read_b128 v[144:147], v238 offset:16384
	ds_read_b128 v[148:151], v238 offset:17408
	ds_read_b128 v[152:155], v238 offset:18432
	ds_read_b128 v[156:159], v238 offset:19456
	ds_read_b128 v[160:163], v238 offset:20480
	ds_read_b128 v[164:167], v238 offset:21504
	ds_read_b128 v[168:171], v238 offset:22528
	ds_read_b128 v[172:175], v238 offset:23552
	global_load_lds_dwordx4 v202, s[30:31]
	v_lshl_add_u64 v[198:199], s[30:31], 0, v[206:207]
	s_mov_b32 m0, s39
	s_nop 0
	global_load_lds_dwordx4 v206, s[30:31]
	s_setprio 1
	s_barrier
	s_waitcnt lgkmcnt(0)
	s_waitcnt lgkmcnt(0)
	v_mfma_f32_16x16x32_bf16 v[60:63], v[128:131], v[144:147], 0
	v_mfma_f32_16x16x32_bf16 v[56:59], v[136:139], v[144:147], 0
	v_mfma_f32_16x16x32_bf16 v[44:47], v[128:131], v[152:155], 0
	v_mfma_f32_16x16x32_bf16 v[40:43], v[136:139], v[152:155], 0
	v_mfma_f32_16x16x32_bf16 v[28:31], v[128:131], v[160:163], 0
	v_mfma_f32_16x16x32_bf16 v[24:27], v[136:139], v[160:163], 0
	v_mfma_f32_16x16x32_bf16 v[12:15], v[128:131], v[168:171], 0
	v_mfma_f32_16x16x32_bf16 v[8:11], v[136:139], v[168:171], 0
	v_mfma_f32_16x16x32_bf16 v[60:63], v[132:135], v[148:151], v[60:63]
	v_mfma_f32_16x16x32_bf16 v[56:59], v[140:143], v[148:151], v[56:59]
	v_mfma_f32_16x16x32_bf16 v[44:47], v[132:135], v[156:159], v[44:47]
	v_mfma_f32_16x16x32_bf16 v[40:43], v[140:143], v[156:159], v[40:43]
	v_mfma_f32_16x16x32_bf16 v[28:31], v[132:135], v[164:167], v[28:31]
	v_mfma_f32_16x16x32_bf16 v[24:27], v[140:143], v[164:167], v[24:27]
	v_mfma_f32_16x16x32_bf16 v[12:15], v[132:135], v[172:175], v[12:15]
	v_mfma_f32_16x16x32_bf16 v[8:11], v[140:143], v[172:175], v[8:11]
	s_setprio 0
	s_barrier
; #define PG8_STAGE(bufoff, gbase, voff) do { _Pragma("unroll") for (int _i = 0; _i < 2; ++_i) \
;         __builtin_amdgcn_global_load_lds((const unsigned*)((const char*)(gbase) + (voff)[_i]), (LAS unsigned*)(lds + (bufoff) + ldsw + _i * 8192), 16, 0, 0); } while (0)
; #define PG8_LDA(dst, b, h) do { _Pragma("unroll") for (int m = 0; m < 4; ++m) _Pragma("unroll") for (int k = 0; k < 2; ++k) dst[m][k] = *(const LAS bf16x8*)(lds + PG8_SA(b, h) + aoff + m * 2048 + k * 1024); } while (0)
; #define PG8_LDB(dst, b, h) do { _Pragma("unroll") for (int n = 0; n < 2; ++n) _Pragma("unroll") for (int k = 0; k < 2; ++k) dst[n][k] = *(const LAS bf16x8*)(lds + PG8_SB(b, h) + boff + n * 2048 + k * 1024); } while (0)
; #define PG8_MMA(ai, bj, At, Bt) do { __builtin_amdgcn_s_setprio(1); _Pragma("unroll") for (int m = 0; m < 4; ++m) _Pragma("unroll") for (int n = 0; n < 2; ++n) _Pragma("unroll") for (int k = 0; k < 2; ++k) \
;         acc[ai][bj][m][n] = __builtin_amdgcn_mfma_f32_16x16x32_bf16(Bt[n][k], At[m][k], acc[ai][bj][m][n], 0, 0, 0); __builtin_amdgcn_s_setprio(0); } while (0)
; #define PG8_WAIT_V(n) asm volatile("s_waitcnt vmcnt(" #n ")" ::: "memory")
; #define PG8_WAIT_L(n) asm volatile("s_waitcnt lgkmcnt(" #n ")" ::: "memory")
; #define PG8_BAR __builtin_amdgcn_s_barrier()
; #define PG8_SCHED __builtin_amdgcn_sched_barrier(0)
; template <class Epi, class Sched>
; __device__ __forceinline__ void gemm_phase(LAS unsigned char* lds, const Gemm g, const Sched& S, const Epi& E) {
;     ...
;             PG8_STAGE(PG8_SB(0, 1), b2 + hstep, voffB);
;             PG8_WAIT_V(6); PG8_BAR; PG8_MMA(1, 1, At, B1); PG8_BAR;
;             PG8_LDB(B0, 1, 0); PG8_SCHED; PG8_LDA(At, 1, 0); PG8_STAGE(PG8_SA(0, 1), a2 + hstep, voffA);
;             PG8_WAIT_L(8); PG8_BAR; PG8_WAIT_L(0); PG8_MMA(0, 0, At, B0); PG8_BAR; PG8_SCHED;
;             PG8_LDB(B1, 1, 1); PG8_STAGE(PG8_SB(1, 0), b3, voffB);
;             PG8_BAR; PG8_WAIT_L(0); PG8_MMA(0, 1, At, B1); PG8_BAR;
;             PG8_LDA(At, 1, 1); PG8_STAGE(PG8_SA(1, 0), a3, voffA);
;             PG8_BAR; PG8_WAIT_L(0); PG8_MMA(1, 0, At, B0); PG8_BAR; PG8_SCHED;
	s_add_u32 s24, s28, 0x60000
	s_addc_u32 s25, s29, 0
	s_add_i32 s59, s51, s37
	s_mov_b32 m0, s59
	s_nop 0
	global_load_lds_dwordx4 v204, s[24:25]
	s_add_i32 m0, s59, 0x2000
	s_nop 0
	global_load_lds_dwordx4 v208, s[24:25]
	s_add_u32 s24, s30, 0x60000
	s_addc_u32 s25, s31, 0
	s_mov_b32 m0, s40
	s_nop 0
	global_load_lds_dwordx4 v202, s[24:25]
	s_mov_b32 m0, s41
	s_nop 0
	global_load_lds_dwordx4 v206, s[24:25]
	s_waitcnt vmcnt(10)
	s_setprio 1
	s_barrier
	v_mfma_f32_16x16x32_bf16 v[52:55], v[176:179], v[144:147], 0
	v_mfma_f32_16x16x32_bf16 v[48:51], v[184:187], v[144:147], 0
	v_mfma_f32_16x16x32_bf16 v[36:39], v[176:179], v[152:155], 0
	v_mfma_f32_16x16x32_bf16 v[32:35], v[184:187], v[152:155], 0
	v_mfma_f32_16x16x32_bf16 v[20:23], v[176:179], v[160:163], 0
	v_mfma_f32_16x16x32_bf16 v[16:19], v[184:187], v[160:163], 0
	v_mfma_f32_16x16x32_bf16 v[4:7], v[176:179], v[168:171], 0
	v_mfma_f32_16x16x32_bf16 v[0:3], v[184:187], v[168:171], 0
	v_mfma_f32_16x16x32_bf16 v[52:55], v[180:183], v[148:151], v[52:55]
	v_mfma_f32_16x16x32_bf16 v[48:51], v[188:191], v[148:151], v[48:51]
	v_mfma_f32_16x16x32_bf16 v[36:39], v[180:183], v[156:159], v[36:39]
	v_mfma_f32_16x16x32_bf16 v[32:35], v[188:191], v[156:159], v[32:35]
	v_mfma_f32_16x16x32_bf16 v[20:23], v[180:183], v[164:167], v[20:23]
	v_mfma_f32_16x16x32_bf16 v[16:19], v[188:191], v[164:167], v[16:19]
	v_mfma_f32_16x16x32_bf16 v[4:7], v[180:183], v[172:175], v[4:7]
	v_mfma_f32_16x16x32_bf16 v[0:3], v[188:191], v[172:175], v[0:3]
	s_setprio 0
	s_add_i32 s59, 0, 0x18000
	v_add_u32_e32 v140, s59, v236
	s_barrier
	ds_read_b128 v[128:131], v140
	ds_read_b128 v[132:135], v140 offset:1024
	ds_read_b128 v[136:139], v140 offset:2048
	ds_read_b128 v[140:143], v140 offset:3072
	ds_read_b128 v[144:147], v238 offset:32768
	ds_read_b128 v[148:151], v238 offset:33792
	ds_read_b128 v[152:155], v238 offset:34816
	ds_read_b128 v[156:159], v238 offset:35840
	ds_read_b128 v[160:163], v238 offset:36864
	ds_read_b128 v[164:167], v238 offset:37888
	ds_read_b128 v[168:171], v238 offset:38912
	ds_read_b128 v[172:175], v238 offset:39936
	s_waitcnt lgkmcnt(8)
	s_waitcnt vmcnt(8)
	s_setprio 1
	s_barrier
	s_waitcnt lgkmcnt(0)
	s_waitcnt lgkmcnt(0)
	v_mfma_f32_16x16x32_bf16 v[124:127], v[128:131], v[144:147], v[124:127]
	v_mfma_f32_16x16x32_bf16 v[120:123], v[136:139], v[144:147], v[120:123]
	v_mfma_f32_16x16x32_bf16 v[108:111], v[128:131], v[152:155], v[108:111]
	v_mfma_f32_16x16x32_bf16 v[104:107], v[136:139], v[152:155], v[104:107]
	v_mfma_f32_16x16x32_bf16 v[92:95], v[128:131], v[160:163], v[92:95]
	v_mfma_f32_16x16x32_bf16 v[88:91], v[136:139], v[160:163], v[88:91]
	v_mfma_f32_16x16x32_bf16 v[76:79], v[128:131], v[168:171], v[76:79]
	v_mfma_f32_16x16x32_bf16 v[72:75], v[136:139], v[168:171], v[72:75]
	v_mfma_f32_16x16x32_bf16 v[124:127], v[132:135], v[148:151], v[124:127]
	v_mfma_f32_16x16x32_bf16 v[120:123], v[140:143], v[148:151], v[120:123]
	v_mfma_f32_16x16x32_bf16 v[108:111], v[132:135], v[156:159], v[108:111]
	v_mfma_f32_16x16x32_bf16 v[104:107], v[140:143], v[156:159], v[104:107]
	v_mfma_f32_16x16x32_bf16 v[92:95], v[132:135], v[164:167], v[92:95]
	v_mfma_f32_16x16x32_bf16 v[88:91], v[140:143], v[164:167], v[88:91]
	v_mfma_f32_16x16x32_bf16 v[76:79], v[132:135], v[172:175], v[76:79]
	v_mfma_f32_16x16x32_bf16 v[72:75], v[140:143], v[172:175], v[72:75]
	s_setprio 0
	s_barrier
	s_add_i32 s30, 0, 0x1c000
	s_add_i32 s24, s59, s37
	v_add_u32_e32 v188, s30, v236
	s_add_u32 s0, s28, 0x80
	s_addc_u32 s1, s29, 0
	s_mov_b32 m0, s24
	ds_read_b128 v[176:179], v188
	ds_read_b128 v[180:183], v188 offset:1024
	ds_read_b128 v[184:187], v188 offset:2048
	ds_read_b128 v[188:191], v188 offset:3072
	global_load_lds_dwordx4 v204, s[0:1]
	s_add_i32 m0, s24, 0x2000
	s_nop 0
	global_load_lds_dwordx4 v208, s[0:1]
	s_waitcnt vmcnt(8)
	s_setprio 1
	s_barrier
	s_waitcnt lgkmcnt(0)
	s_waitcnt lgkmcnt(0)
	v_mfma_f32_16x16x32_bf16 v[116:119], v[176:179], v[144:147], v[116:119]
	v_mfma_f32_16x16x32_bf16 v[112:115], v[184:187], v[144:147], v[112:115]
	v_mfma_f32_16x16x32_bf16 v[100:103], v[176:179], v[152:155], v[100:103]
	v_mfma_f32_16x16x32_bf16 v[96:99], v[184:187], v[152:155], v[96:99]
	v_mfma_f32_16x16x32_bf16 v[84:87], v[176:179], v[160:163], v[84:87]
	v_mfma_f32_16x16x32_bf16 v[80:83], v[184:187], v[160:163], v[80:83]
	v_mfma_f32_16x16x32_bf16 v[68:71], v[176:179], v[168:171], v[68:71]
	v_mfma_f32_16x16x32_bf16 v[64:67], v[184:187], v[168:171], v[64:67]
	v_mfma_f32_16x16x32_bf16 v[116:119], v[180:183], v[148:151], v[116:119]
	v_mfma_f32_16x16x32_bf16 v[112:115], v[188:191], v[148:151], v[112:115]
	v_mfma_f32_16x16x32_bf16 v[100:103], v[180:183], v[156:159], v[100:103]
	v_mfma_f32_16x16x32_bf16 v[96:99], v[188:191], v[156:159], v[96:99]
	v_mfma_f32_16x16x32_bf16 v[84:87], v[180:183], v[164:167], v[84:87]
	v_mfma_f32_16x16x32_bf16 v[80:83], v[188:191], v[164:167], v[80:83]
	v_mfma_f32_16x16x32_bf16 v[68:71], v[180:183], v[172:175], v[68:71]
	v_mfma_f32_16x16x32_bf16 v[64:67], v[188:191], v[172:175], v[64:67]
	s_setprio 0
	s_mov_b32 m0, s47
	s_mov_b64 s[0:1], 0x80
	v_lshl_add_u64 v[192:193], v[196:197], 0, s[0:1]
	s_barrier
	ds_read_b128 v[144:147], v238 offset:49152
	ds_read_b128 v[148:151], v238 offset:50176
	ds_read_b128 v[152:155], v238 offset:51200
	ds_read_b128 v[156:159], v238 offset:52224
	ds_read_b128 v[160:163], v238 offset:53248
	ds_read_b128 v[164:167], v238 offset:54272
	ds_read_b128 v[168:171], v238 offset:55296
	ds_read_b128 v[172:175], v238 offset:56320
	global_load_lds_dwordx4 v[192:193], off
	v_lshl_add_u64 v[192:193], v[198:199], 0, s[0:1]
	s_mov_b32 m0, s48
	s_nop 0
	global_load_lds_dwordx4 v[192:193], off
	s_setprio 1
	s_barrier
; #define PG8_STAGE(bufoff, gbase, voff) do { _Pragma("unroll") for (int _i = 0; _i < 2; ++_i) \
;         __builtin_amdgcn_global_load_lds((const unsigned*)((const char*)(gbase) + (voff)[_i]), (LAS unsigned*)(lds + (bufoff) + ldsw + _i * 8192), 16, 0, 0); } while (0)
; #define PG8_LDA(dst, b, h) do { _Pragma("unroll") for (int m = 0; m < 4; ++m) _Pragma("unroll") for (int k = 0; k < 2; ++k) dst[m][k] = *(const LAS bf16x8*)(lds + PG8_SA(b, h) + aoff + m * 2048 + k * 1024); } while (0)
; #define PG8_LDB(dst, b, h) do { _Pragma("unroll") for (int n = 0; n < 2; ++n) _Pragma("unroll") for (int k = 0; k < 2; ++k) dst[n][k] = *(const LAS bf16x8*)(lds + PG8_SB(b, h) + boff + n * 2048 + k * 1024); } while (0)
; #define PG8_MMA(ai, bj, At, Bt) do { __builtin_amdgcn_s_setprio(1); _Pragma("unroll") for (int m = 0; m < 4; ++m) _Pragma("unroll") for (int n = 0; n < 2; ++n) _Pragma("unroll") for (int k = 0; k < 2; ++k) \
;         acc[ai][bj][m][n] = __builtin_amdgcn_mfma_f32_16x16x32_bf16(Bt[n][k], At[m][k], acc[ai][bj][m][n], 0, 0, 0); __builtin_amdgcn_s_setprio(0); } while (0)
; #define PG8_WAIT_V(n) asm volatile("s_waitcnt vmcnt(" #n ")" ::: "memory")
; #define PG8_WAIT_L(n) asm volatile("s_waitcnt lgkmcnt(" #n ")" ::: "memory")
; #define PG8_BAR __builtin_amdgcn_s_barrier()
; #define PG8_SCHED __builtin_amdgcn_sched_barrier(0)
; template <class Epi, class Sched>
; __device__ __forceinline__ void gemm_phase(LAS unsigned char* lds, const Gemm g, const Sched& S, const Epi& E) {
;     ...
;             PG8_LDB(B0, 0, 0); PG8_SCHED; PG8_LDA(At, 0, 0); PG8_STAGE(PG8_SA(1, 1), a1 + hstep, voffA);
;             PG8_WAIT_L(8); PG8_BAR; PG8_WAIT_L(0); PG8_MMA(0, 0, At, B0); PG8_BAR; PG8_SCHED;
;             PG8_LDB(B1, 0, 1); PG8_STAGE(PG8_SB(0, 0), b2, voffB);
;             PG8_BAR; PG8_WAIT_L(0); PG8_MMA(0, 1, At, B1); PG8_BAR;
;     ...
;             PG8_BAR; PG8_WAIT_L(0); PG8_MMA(1, 0, At, B0); PG8_BAR; PG8_SCHED;
;             PG8_STAGE(PG8_SB(1, 1), b3 + hstep, voffB);
;             PG8_WAIT_V(6); PG8_BAR; PG8_MMA(1, 1, At, B1); PG8_BAR;
	s_waitcnt lgkmcnt(0)
	s_waitcnt lgkmcnt(0)
	v_mfma_f32_16x16x32_bf16 v[60:63], v[128:131], v[144:147], v[60:63]
	v_mfma_f32_16x16x32_bf16 v[56:59], v[136:139], v[144:147], v[56:59]
	v_mfma_f32_16x16x32_bf16 v[44:47], v[128:131], v[152:155], v[44:47]
	v_mfma_f32_16x16x32_bf16 v[40:43], v[136:139], v[152:155], v[40:43]
	v_mfma_f32_16x16x32_bf16 v[28:31], v[128:131], v[160:163], v[28:31]
	v_mfma_f32_16x16x32_bf16 v[24:27], v[136:139], v[160:163], v[24:27]
	v_mfma_f32_16x16x32_bf16 v[12:15], v[128:131], v[168:171], v[12:15]
	v_mfma_f32_16x16x32_bf16 v[8:11], v[136:139], v[168:171], v[8:11]
	v_mfma_f32_16x16x32_bf16 v[60:63], v[132:135], v[148:151], v[60:63]
	v_mfma_f32_16x16x32_bf16 v[56:59], v[140:143], v[148:151], v[56:59]
	v_mfma_f32_16x16x32_bf16 v[44:47], v[132:135], v[156:159], v[44:47]
	v_mfma_f32_16x16x32_bf16 v[40:43], v[140:143], v[156:159], v[40:43]
	v_mfma_f32_16x16x32_bf16 v[28:31], v[132:135], v[164:167], v[28:31]
	v_mfma_f32_16x16x32_bf16 v[24:27], v[140:143], v[164:167], v[24:27]
	v_mfma_f32_16x16x32_bf16 v[12:15], v[132:135], v[172:175], v[12:15]
	v_mfma_f32_16x16x32_bf16 v[8:11], v[140:143], v[172:175], v[8:11]
	s_setprio 0
	s_barrier
	s_add_u32 s24, s28, 0x60080
	s_addc_u32 s25, s29, 0
	s_add_i32 s28, s30, s37
	s_mov_b32 m0, s28
	s_nop 0
	global_load_lds_dwordx4 v204, s[24:25]
	s_add_i32 m0, s28, 0x2000
	s_nop 0
	global_load_lds_dwordx4 v208, s[24:25]
	s_waitcnt vmcnt(8)
	s_setprio 1
	s_barrier
	v_mfma_f32_16x16x32_bf16 v[52:55], v[176:179], v[144:147], v[52:55]
	v_mfma_f32_16x16x32_bf16 v[48:51], v[184:187], v[144:147], v[48:51]
	v_mfma_f32_16x16x32_bf16 v[36:39], v[176:179], v[152:155], v[36:39]
	v_mfma_f32_16x16x32_bf16 v[32:35], v[184:187], v[152:155], v[32:35]
	v_mfma_f32_16x16x32_bf16 v[20:23], v[176:179], v[160:163], v[20:23]
	v_mfma_f32_16x16x32_bf16 v[16:19], v[184:187], v[160:163], v[16:19]
	v_mfma_f32_16x16x32_bf16 v[4:7], v[176:179], v[168:171], v[4:7]
	v_mfma_f32_16x16x32_bf16 v[0:3], v[184:187], v[168:171], v[0:3]
	v_mfma_f32_16x16x32_bf16 v[52:55], v[180:183], v[148:151], v[52:55]
	v_mfma_f32_16x16x32_bf16 v[48:51], v[188:191], v[148:151], v[48:51]
	v_mfma_f32_16x16x32_bf16 v[36:39], v[180:183], v[156:159], v[36:39]
	v_mfma_f32_16x16x32_bf16 v[32:35], v[188:191], v[156:159], v[32:35]
	v_mfma_f32_16x16x32_bf16 v[20:23], v[180:183], v[164:167], v[20:23]
	v_mfma_f32_16x16x32_bf16 v[16:19], v[188:191], v[164:167], v[16:19]
	v_mfma_f32_16x16x32_bf16 v[4:7], v[180:183], v[172:175], v[4:7]
	v_mfma_f32_16x16x32_bf16 v[0:3], v[188:191], v[172:175], v[0:3]
	s_setprio 0
	s_add_i32 s58, s58, 2
	s_add_u32 s56, s56, 0x100
	s_addc_u32 s57, s57, 0
	s_cmp_gt_u32 s58, 21
	s_mov_b64 s[24:25], s[26:27]
	s_barrier
.LBB0_902:
	ds_read_b128 v[128:131], v237
	ds_read_b128 v[132:135], v237 offset:1024
	ds_read_b128 v[136:139], v237 offset:2048
	ds_read_b128 v[140:143], v237 offset:3072
	s_add_u32 s26, s24, 0x100
	s_addc_u32 s27, s25, 0
	s_cmp_eq_u32 s58, 20
	s_cselect_b32 s31, s5, s27
	s_cselect_b32 s30, s4, s26
	s_cselect_b32 s29, s7, s57
	s_cselect_b32 s28, s6, s56
	v_lshl_add_u64 v[176:177], s[24:25], 0, v[210:211]
	s_add_i32 m0, s38, 0xc000
	ds_read_b128 v[144:147], v238
	ds_read_b128 v[148:151], v238 offset:1024
	ds_read_b128 v[152:155], v238 offset:2048
	ds_read_b128 v[156:159], v238 offset:3072
	ds_read_b128 v[160:163], v238 offset:4096
	ds_read_b128 v[164:167], v238 offset:5120
	ds_read_b128 v[168:171], v238 offset:6144
	ds_read_b128 v[172:175], v238 offset:7168
	global_load_lds_dwordx4 v[176:177], off
	v_lshl_add_u64 v[176:177], s[24:25], 0, v[212:213]
	s_add_i32 m0, s38, 0xe000
	s_nop 0
	global_load_lds_dwordx4 v[176:177], off
	s_waitcnt lgkmcnt(8)
	s_waitcnt vmcnt(8)
	s_setprio 1
	s_barrier
	s_waitcnt lgkmcnt(0)
	s_waitcnt lgkmcnt(0)
	v_mfma_f32_16x16x32_bf16 v[124:127], v[128:131], v[144:147], v[124:127]
	v_mfma_f32_16x16x32_bf16 v[120:123], v[136:139], v[144:147], v[120:123]
	v_mfma_f32_16x16x32_bf16 v[108:111], v[128:131], v[152:155], v[108:111]
	v_mfma_f32_16x16x32_bf16 v[104:107], v[136:139], v[152:155], v[104:107]
	v_mfma_f32_16x16x32_bf16 v[92:95], v[128:131], v[160:163], v[92:95]
	v_mfma_f32_16x16x32_bf16 v[88:91], v[136:139], v[160:163], v[88:91]
	v_mfma_f32_16x16x32_bf16 v[76:79], v[128:131], v[168:171], v[76:79]
	v_mfma_f32_16x16x32_bf16 v[72:75], v[136:139], v[168:171], v[72:75]
	v_mfma_f32_16x16x32_bf16 v[124:127], v[132:135], v[148:151], v[124:127]
	v_mfma_f32_16x16x32_bf16 v[120:123], v[140:143], v[148:151], v[120:123]
	v_mfma_f32_16x16x32_bf16 v[108:111], v[132:135], v[156:159], v[108:111]
	v_mfma_f32_16x16x32_bf16 v[104:107], v[140:143], v[156:159], v[104:107]
	v_mfma_f32_16x16x32_bf16 v[92:95], v[132:135], v[164:167], v[92:95]
	v_mfma_f32_16x16x32_bf16 v[88:91], v[140:143], v[164:167], v[88:91]
	v_mfma_f32_16x16x32_bf16 v[76:79], v[132:135], v[172:175], v[76:79]
	v_mfma_f32_16x16x32_bf16 v[72:75], v[140:143], v[172:175], v[72:75]
	s_setprio 0
	s_barrier
	s_add_i32 s24, s50, s37
	s_mov_b32 m0, s24
	ds_read_b128 v[176:179], v239
	ds_read_b128 v[180:183], v239 offset:1024
	ds_read_b128 v[184:187], v239 offset:2048
	ds_read_b128 v[188:191], v239 offset:3072
	global_load_lds_dwordx4 v204, s[28:29]
	s_add_i32 m0, s24, 0x2000
	s_nop 0
	global_load_lds_dwordx4 v208, s[28:29]
	s_waitcnt vmcnt(8)
	s_setprio 1
	s_barrier
; #define PG8_STAGE(bufoff, gbase, voff) do { _Pragma("unroll") for (int _i = 0; _i < 2; ++_i) \
;         __builtin_amdgcn_global_load_lds((const unsigned*)((const char*)(gbase) + (voff)[_i]), (LAS unsigned*)(lds + (bufoff) + ldsw + _i * 8192), 16, 0, 0); } while (0)
; #define PG8_LDA(dst, b, h) do { _Pragma("unroll") for (int m = 0; m < 4; ++m) _Pragma("unroll") for (int k = 0; k < 2; ++k) dst[m][k] = *(const LAS bf16x8*)(lds + PG8_SA(b, h) + aoff + m * 2048 + k * 1024); } while (0)
; #define PG8_LDB(dst, b, h) do { _Pragma("unroll") for (int n = 0; n < 2; ++n) _Pragma("unroll") for (int k = 0; k < 2; ++k) dst[n][k] = *(const LAS bf16x8*)(lds + PG8_SB(b, h) + boff + n * 2048 + k * 1024); } while (0)
; #define PG8_MMA(ai, bj, At, Bt) do { __builtin_amdgcn_s_setprio(1); _Pragma("unroll") for (int m = 0; m < 4; ++m) _Pragma("unroll") for (int n = 0; n < 2; ++n) _Pragma("unroll") for (int k = 0; k < 2; ++k) \
;         acc[ai][bj][m][n] = __builtin_amdgcn_mfma_f32_16x16x32_bf16(Bt[n][k], At[m][k], acc[ai][bj][m][n], 0, 0, 0); __builtin_amdgcn_s_setprio(0); } while (0)
; #define PG8_WAIT_V(n) asm volatile("s_waitcnt vmcnt(" #n ")" ::: "memory")
; #define PG8_WAIT_L(n) asm volatile("s_waitcnt lgkmcnt(" #n ")" ::: "memory")
; #define PG8_BAR __builtin_amdgcn_s_barrier()
; #define PG8_SCHED __builtin_amdgcn_sched_barrier(0)
; template <class Epi, class Sched>
; __device__ __forceinline__ void gemm_phase(LAS unsigned char* lds, const Gemm g, const Sched& S, const Epi& E) {
;     ...
;             PG8_LDB(B1, 0, 1); PG8_STAGE(PG8_SB(0, 0), b2, voffB);
;             PG8_BAR; PG8_WAIT_L(0); PG8_MMA(0, 1, At, B1); PG8_BAR;
;             PG8_LDA(At, 0, 1); PG8_STAGE(PG8_SA(0, 0), a2, voffA);
;             PG8_BAR; PG8_WAIT_L(0); PG8_MMA(1, 0, At, B0); PG8_BAR; PG8_SCHED;
;             PG8_STAGE(PG8_SB(0, 1), b2 + hstep, voffB);
;             PG8_WAIT_V(6); PG8_BAR; PG8_MMA(1, 1, At, B1); PG8_BAR;
;             PG8_LDB(B0, 1, 0); PG8_SCHED; PG8_LDA(At, 1, 0); PG8_STAGE(PG8_SA(0, 1), a2 + hstep, voffA);
;             PG8_WAIT_L(8); PG8_BAR; PG8_WAIT_L(0); PG8_MMA(0, 0, At, B0); PG8_BAR; PG8_SCHED;
	s_waitcnt lgkmcnt(0)
	s_waitcnt lgkmcnt(0)
	v_mfma_f32_16x16x32_bf16 v[116:119], v[176:179], v[144:147], v[116:119]
	v_mfma_f32_16x16x32_bf16 v[112:115], v[184:187], v[144:147], v[112:115]
	v_mfma_f32_16x16x32_bf16 v[100:103], v[176:179], v[152:155], v[100:103]
	v_mfma_f32_16x16x32_bf16 v[96:99], v[184:187], v[152:155], v[96:99]
	v_mfma_f32_16x16x32_bf16 v[84:87], v[176:179], v[160:163], v[84:87]
	v_mfma_f32_16x16x32_bf16 v[80:83], v[184:187], v[160:163], v[80:83]
	v_mfma_f32_16x16x32_bf16 v[68:71], v[176:179], v[168:171], v[68:71]
	v_mfma_f32_16x16x32_bf16 v[64:67], v[184:187], v[168:171], v[64:67]
	v_mfma_f32_16x16x32_bf16 v[116:119], v[180:183], v[148:151], v[116:119]
	v_mfma_f32_16x16x32_bf16 v[112:115], v[188:191], v[148:151], v[112:115]
	v_mfma_f32_16x16x32_bf16 v[100:103], v[180:183], v[156:159], v[100:103]
	v_mfma_f32_16x16x32_bf16 v[96:99], v[188:191], v[156:159], v[96:99]
	v_mfma_f32_16x16x32_bf16 v[84:87], v[180:183], v[164:167], v[84:87]
	v_mfma_f32_16x16x32_bf16 v[80:83], v[188:191], v[164:167], v[80:83]
	v_mfma_f32_16x16x32_bf16 v[68:71], v[180:183], v[172:175], v[68:71]
	v_mfma_f32_16x16x32_bf16 v[64:67], v[188:191], v[172:175], v[64:67]
	s_setprio 0
	s_mov_b32 m0, s38
	v_lshl_add_u64 v[196:197], s[30:31], 0, v[202:203]
	s_barrier
	ds_read_b128 v[144:147], v238 offset:16384
	ds_read_b128 v[148:151], v238 offset:17408
	ds_read_b128 v[152:155], v238 offset:18432
	ds_read_b128 v[156:159], v238 offset:19456
	ds_read_b128 v[160:163], v238 offset:20480
	ds_read_b128 v[164:167], v238 offset:21504
	ds_read_b128 v[168:171], v238 offset:22528
	ds_read_b128 v[172:175], v238 offset:23552
	global_load_lds_dwordx4 v202, s[30:31]
	v_lshl_add_u64 v[198:199], s[30:31], 0, v[206:207]
	s_mov_b32 m0, s39
	s_nop 0
	global_load_lds_dwordx4 v206, s[30:31]
	s_setprio 1
	s_barrier
	s_waitcnt lgkmcnt(0)
	s_waitcnt lgkmcnt(0)
	v_mfma_f32_16x16x32_bf16 v[60:63], v[128:131], v[144:147], v[60:63]
	v_mfma_f32_16x16x32_bf16 v[56:59], v[136:139], v[144:147], v[56:59]
	v_mfma_f32_16x16x32_bf16 v[44:47], v[128:131], v[152:155], v[44:47]
	v_mfma_f32_16x16x32_bf16 v[40:43], v[136:139], v[152:155], v[40:43]
	v_mfma_f32_16x16x32_bf16 v[28:31], v[128:131], v[160:163], v[28:31]
	v_mfma_f32_16x16x32_bf16 v[24:27], v[136:139], v[160:163], v[24:27]
	v_mfma_f32_16x16x32_bf16 v[12:15], v[128:131], v[168:171], v[12:15]
	v_mfma_f32_16x16x32_bf16 v[8:11], v[136:139], v[168:171], v[8:11]
	v_mfma_f32_16x16x32_bf16 v[60:63], v[132:135], v[148:151], v[60:63]
	v_mfma_f32_16x16x32_bf16 v[56:59], v[140:143], v[148:151], v[56:59]
	v_mfma_f32_16x16x32_bf16 v[44:47], v[132:135], v[156:159], v[44:47]
	v_mfma_f32_16x16x32_bf16 v[40:43], v[140:143], v[156:159], v[40:43]
	v_mfma_f32_16x16x32_bf16 v[28:31], v[132:135], v[164:167], v[28:31]
	v_mfma_f32_16x16x32_bf16 v[24:27], v[140:143], v[164:167], v[24:27]
	v_mfma_f32_16x16x32_bf16 v[12:15], v[132:135], v[172:175], v[12:15]
	v_mfma_f32_16x16x32_bf16 v[8:11], v[140:143], v[172:175], v[8:11]
	s_setprio 0
	s_barrier
	s_add_u32 s24, s28, 0x60000
	s_addc_u32 s25, s29, 0
	s_add_i32 s59, s51, s37
	s_mov_b32 m0, s59
	s_nop 0
	global_load_lds_dwordx4 v204, s[24:25]
	s_add_i32 m0, s59, 0x2000
	s_nop 0
	global_load_lds_dwordx4 v208, s[24:25]
	s_add_u32 s24, s30, 0x60000
	s_addc_u32 s25, s31, 0
	s_mov_b32 m0, s40
	s_nop 0
	global_load_lds_dwordx4 v202, s[24:25]
	s_mov_b32 m0, s41
	s_nop 0
	global_load_lds_dwordx4 v206, s[24:25]
	s_waitcnt vmcnt(10)
	s_setprio 1
	s_barrier
	v_mfma_f32_16x16x32_bf16 v[52:55], v[176:179], v[144:147], v[52:55]
	v_mfma_f32_16x16x32_bf16 v[48:51], v[184:187], v[144:147], v[48:51]
	v_mfma_f32_16x16x32_bf16 v[36:39], v[176:179], v[152:155], v[36:39]
	v_mfma_f32_16x16x32_bf16 v[32:35], v[184:187], v[152:155], v[32:35]
	v_mfma_f32_16x16x32_bf16 v[20:23], v[176:179], v[160:163], v[20:23]
	v_mfma_f32_16x16x32_bf16 v[16:19], v[184:187], v[160:163], v[16:19]
	v_mfma_f32_16x16x32_bf16 v[4:7], v[176:179], v[168:171], v[4:7]
	v_mfma_f32_16x16x32_bf16 v[0:3], v[184:187], v[168:171], v[0:3]
	v_mfma_f32_16x16x32_bf16 v[52:55], v[180:183], v[148:151], v[52:55]
	v_mfma_f32_16x16x32_bf16 v[48:51], v[188:191], v[148:151], v[48:51]
	v_mfma_f32_16x16x32_bf16 v[36:39], v[180:183], v[156:159], v[36:39]
	v_mfma_f32_16x16x32_bf16 v[32:35], v[188:191], v[156:159], v[32:35]
	v_mfma_f32_16x16x32_bf16 v[20:23], v[180:183], v[164:167], v[20:23]
	v_mfma_f32_16x16x32_bf16 v[16:19], v[188:191], v[164:167], v[16:19]
	v_mfma_f32_16x16x32_bf16 v[4:7], v[180:183], v[172:175], v[4:7]
	v_mfma_f32_16x16x32_bf16 v[0:3], v[188:191], v[172:175], v[0:3]
	s_setprio 0
	s_add_i32 s59, 0, 0x18000
	v_add_u32_e32 v140, s59, v236
	s_barrier
	ds_read_b128 v[128:131], v140
	ds_read_b128 v[132:135], v140 offset:1024
	ds_read_b128 v[136:139], v140 offset:2048
	ds_read_b128 v[140:143], v140 offset:3072
	ds_read_b128 v[144:147], v238 offset:32768
	ds_read_b128 v[148:151], v238 offset:33792
	ds_read_b128 v[152:155], v238 offset:34816
	ds_read_b128 v[156:159], v238 offset:35840
	ds_read_b128 v[160:163], v238 offset:36864
	ds_read_b128 v[164:167], v238 offset:37888
	ds_read_b128 v[168:171], v238 offset:38912
	ds_read_b128 v[172:175], v238 offset:39936
	s_waitcnt lgkmcnt(8)
	s_waitcnt vmcnt(8)
	s_setprio 1
	s_barrier
; #define PG8_STAGE(bufoff, gbase, voff) do { _Pragma("unroll") for (int _i = 0; _i < 2; ++_i) \
;         __builtin_amdgcn_global_load_lds((const unsigned*)((const char*)(gbase) + (voff)[_i]), (LAS unsigned*)(lds + (bufoff) + ldsw + _i * 8192), 16, 0, 0); } while (0)
; #define PG8_LDA(dst, b, h) do { _Pragma("unroll") for (int m = 0; m < 4; ++m) _Pragma("unroll") for (int k = 0; k < 2; ++k) dst[m][k] = *(const LAS bf16x8*)(lds + PG8_SA(b, h) + aoff + m * 2048 + k * 1024); } while (0)
; #define PG8_LDB(dst, b, h) do { _Pragma("unroll") for (int n = 0; n < 2; ++n) _Pragma("unroll") for (int k = 0; k < 2; ++k) dst[n][k] = *(const LAS bf16x8*)(lds + PG8_SB(b, h) + boff + n * 2048 + k * 1024); } while (0)
; #define PG8_MMA(ai, bj, At, Bt) do { __builtin_amdgcn_s_setprio(1); _Pragma("unroll") for (int m = 0; m < 4; ++m) _Pragma("unroll") for (int n = 0; n < 2; ++n) _Pragma("unroll") for (int k = 0; k < 2; ++k) \
;         acc[ai][bj][m][n] = __builtin_amdgcn_mfma_f32_16x16x32_bf16(Bt[n][k], At[m][k], acc[ai][bj][m][n], 0, 0, 0); __builtin_amdgcn_s_setprio(0); } while (0)
; #define PG8_WAIT_V(n) asm volatile("s_waitcnt vmcnt(" #n ")" ::: "memory")
; #define PG8_WAIT_L(n) asm volatile("s_waitcnt lgkmcnt(" #n ")" ::: "memory")
; #define PG8_BAR __builtin_amdgcn_s_barrier()
; #define PG8_SCHED __builtin_amdgcn_sched_barrier(0)
; template <class Epi, class Sched>
; __device__ __forceinline__ void gemm_phase(LAS unsigned char* lds, const Gemm g, const Sched& S, const Epi& E) {
;     ...
;             PG8_WAIT_L(8); PG8_BAR; PG8_WAIT_L(0); PG8_MMA(0, 0, At, B0); PG8_BAR; PG8_SCHED;
;             PG8_LDB(B1, 1, 1); PG8_STAGE(PG8_SB(1, 0), b3, voffB);
;             PG8_BAR; PG8_WAIT_L(0); PG8_MMA(0, 1, At, B1); PG8_BAR;
;             PG8_LDA(At, 1, 1); PG8_STAGE(PG8_SA(1, 0), a3, voffA);
;             PG8_BAR; PG8_WAIT_L(0); PG8_MMA(1, 0, At, B0); PG8_BAR; PG8_SCHED;
;             PG8_STAGE(PG8_SB(1, 1), b3 + hstep, voffB);
;             PG8_WAIT_V(6); PG8_BAR; PG8_MMA(1, 1, At, B1); PG8_BAR;
	s_waitcnt lgkmcnt(0)
	s_waitcnt lgkmcnt(0)
	v_mfma_f32_16x16x32_bf16 v[124:127], v[128:131], v[144:147], v[124:127]
	v_mfma_f32_16x16x32_bf16 v[120:123], v[136:139], v[144:147], v[120:123]
	v_mfma_f32_16x16x32_bf16 v[108:111], v[128:131], v[152:155], v[108:111]
	v_mfma_f32_16x16x32_bf16 v[104:107], v[136:139], v[152:155], v[104:107]
	v_mfma_f32_16x16x32_bf16 v[92:95], v[128:131], v[160:163], v[92:95]
	v_mfma_f32_16x16x32_bf16 v[88:91], v[136:139], v[160:163], v[88:91]
	v_mfma_f32_16x16x32_bf16 v[76:79], v[128:131], v[168:171], v[76:79]
	v_mfma_f32_16x16x32_bf16 v[72:75], v[136:139], v[168:171], v[72:75]
	v_mfma_f32_16x16x32_bf16 v[124:127], v[132:135], v[148:151], v[124:127]
	v_mfma_f32_16x16x32_bf16 v[120:123], v[140:143], v[148:151], v[120:123]
	v_mfma_f32_16x16x32_bf16 v[108:111], v[132:135], v[156:159], v[108:111]
	v_mfma_f32_16x16x32_bf16 v[104:107], v[140:143], v[156:159], v[104:107]
	v_mfma_f32_16x16x32_bf16 v[92:95], v[132:135], v[164:167], v[92:95]
	v_mfma_f32_16x16x32_bf16 v[88:91], v[140:143], v[164:167], v[88:91]
	v_mfma_f32_16x16x32_bf16 v[76:79], v[132:135], v[172:175], v[76:79]
	v_mfma_f32_16x16x32_bf16 v[72:75], v[140:143], v[172:175], v[72:75]
	s_setprio 0
	s_barrier
	s_add_i32 s30, 0, 0x1c000
	s_add_i32 s24, s59, s37
	v_add_u32_e32 v188, s30, v236
	s_add_u32 s0, s28, 0x80
	s_addc_u32 s1, s29, 0
	s_mov_b32 m0, s24
	ds_read_b128 v[176:179], v188
	ds_read_b128 v[180:183], v188 offset:1024
	ds_read_b128 v[184:187], v188 offset:2048
	ds_read_b128 v[188:191], v188 offset:3072
	global_load_lds_dwordx4 v204, s[0:1]
	s_add_i32 m0, s24, 0x2000
	s_nop 0
	global_load_lds_dwordx4 v208, s[0:1]
	s_waitcnt vmcnt(8)
	s_setprio 1
	s_barrier
	s_waitcnt lgkmcnt(0)
	s_waitcnt lgkmcnt(0)
	v_mfma_f32_16x16x32_bf16 v[116:119], v[176:179], v[144:147], v[116:119]
	v_mfma_f32_16x16x32_bf16 v[112:115], v[184:187], v[144:147], v[112:115]
	v_mfma_f32_16x16x32_bf16 v[100:103], v[176:179], v[152:155], v[100:103]
	v_mfma_f32_16x16x32_bf16 v[96:99], v[184:187], v[152:155], v[96:99]
	v_mfma_f32_16x16x32_bf16 v[84:87], v[176:179], v[160:163], v[84:87]
	v_mfma_f32_16x16x32_bf16 v[80:83], v[184:187], v[160:163], v[80:83]
	v_mfma_f32_16x16x32_bf16 v[68:71], v[176:179], v[168:171], v[68:71]
	v_mfma_f32_16x16x32_bf16 v[64:67], v[184:187], v[168:171], v[64:67]
	v_mfma_f32_16x16x32_bf16 v[116:119], v[180:183], v[148:151], v[116:119]
	v_mfma_f32_16x16x32_bf16 v[112:115], v[188:191], v[148:151], v[112:115]
	v_mfma_f32_16x16x32_bf16 v[100:103], v[180:183], v[156:159], v[100:103]
	v_mfma_f32_16x16x32_bf16 v[96:99], v[188:191], v[156:159], v[96:99]
	v_mfma_f32_16x16x32_bf16 v[84:87], v[180:183], v[164:167], v[84:87]
	v_mfma_f32_16x16x32_bf16 v[80:83], v[188:191], v[164:167], v[80:83]
	v_mfma_f32_16x16x32_bf16 v[68:71], v[180:183], v[172:175], v[68:71]
	v_mfma_f32_16x16x32_bf16 v[64:67], v[188:191], v[172:175], v[64:67]
	s_setprio 0
	s_mov_b32 m0, s47
	s_mov_b64 s[0:1], 0x80
	v_lshl_add_u64 v[192:193], v[196:197], 0, s[0:1]
	s_barrier
	ds_read_b128 v[144:147], v238 offset:49152
	ds_read_b128 v[148:151], v238 offset:50176
	ds_read_b128 v[152:155], v238 offset:51200
	ds_read_b128 v[156:159], v238 offset:52224
	ds_read_b128 v[160:163], v238 offset:53248
	ds_read_b128 v[164:167], v238 offset:54272
	ds_read_b128 v[168:171], v238 offset:55296
	ds_read_b128 v[172:175], v238 offset:56320
	global_load_lds_dwordx4 v[192:193], off
	v_lshl_add_u64 v[192:193], v[198:199], 0, s[0:1]
	s_mov_b32 m0, s48
	s_nop 0
	global_load_lds_dwordx4 v[192:193], off
	s_setprio 1
	s_barrier
	s_waitcnt lgkmcnt(0)
	s_waitcnt lgkmcnt(0)
	v_mfma_f32_16x16x32_bf16 v[60:63], v[128:131], v[144:147], v[60:63]
	v_mfma_f32_16x16x32_bf16 v[56:59], v[136:139], v[144:147], v[56:59]
	v_mfma_f32_16x16x32_bf16 v[44:47], v[128:131], v[152:155], v[44:47]
	v_mfma_f32_16x16x32_bf16 v[40:43], v[136:139], v[152:155], v[40:43]
	v_mfma_f32_16x16x32_bf16 v[28:31], v[128:131], v[160:163], v[28:31]
	v_mfma_f32_16x16x32_bf16 v[24:27], v[136:139], v[160:163], v[24:27]
	v_mfma_f32_16x16x32_bf16 v[12:15], v[128:131], v[168:171], v[12:15]
	v_mfma_f32_16x16x32_bf16 v[8:11], v[136:139], v[168:171], v[8:11]
	v_mfma_f32_16x16x32_bf16 v[60:63], v[132:135], v[148:151], v[60:63]
	v_mfma_f32_16x16x32_bf16 v[56:59], v[140:143], v[148:151], v[56:59]
	v_mfma_f32_16x16x32_bf16 v[44:47], v[132:135], v[156:159], v[44:47]
	v_mfma_f32_16x16x32_bf16 v[40:43], v[140:143], v[156:159], v[40:43]
	v_mfma_f32_16x16x32_bf16 v[28:31], v[132:135], v[164:167], v[28:31]
	v_mfma_f32_16x16x32_bf16 v[24:27], v[140:143], v[164:167], v[24:27]
	v_mfma_f32_16x16x32_bf16 v[12:15], v[132:135], v[172:175], v[12:15]
	v_mfma_f32_16x16x32_bf16 v[8:11], v[140:143], v[172:175], v[8:11]
	s_setprio 0
	s_barrier
	s_add_u32 s24, s28, 0x60080
	s_addc_u32 s25, s29, 0
	s_add_i32 s28, s30, s37
	s_mov_b32 m0, s28
	s_nop 0
	global_load_lds_dwordx4 v204, s[24:25]
	s_add_i32 m0, s28, 0x2000
	s_nop 0
	global_load_lds_dwordx4 v208, s[24:25]
	s_waitcnt vmcnt(8)
	s_setprio 1
	s_barrier
	v_mfma_f32_16x16x32_bf16 v[52:55], v[176:179], v[144:147], v[52:55]
	v_mfma_f32_16x16x32_bf16 v[48:51], v[184:187], v[144:147], v[48:51]
	v_mfma_f32_16x16x32_bf16 v[36:39], v[176:179], v[152:155], v[36:39]
	v_mfma_f32_16x16x32_bf16 v[32:35], v[184:187], v[152:155], v[32:35]
	v_mfma_f32_16x16x32_bf16 v[20:23], v[176:179], v[160:163], v[20:23]
	v_mfma_f32_16x16x32_bf16 v[16:19], v[184:187], v[160:163], v[16:19]
	v_mfma_f32_16x16x32_bf16 v[4:7], v[176:179], v[168:171], v[4:7]
	v_mfma_f32_16x16x32_bf16 v[0:3], v[184:187], v[168:171], v[0:3]
	v_mfma_f32_16x16x32_bf16 v[52:55], v[180:183], v[148:151], v[52:55]
	v_mfma_f32_16x16x32_bf16 v[48:51], v[188:191], v[148:151], v[48:51]
	v_mfma_f32_16x16x32_bf16 v[36:39], v[180:183], v[156:159], v[36:39]
	v_mfma_f32_16x16x32_bf16 v[32:35], v[188:191], v[156:159], v[32:35]
	v_mfma_f32_16x16x32_bf16 v[20:23], v[180:183], v[164:167], v[20:23]
	v_mfma_f32_16x16x32_bf16 v[16:19], v[188:191], v[164:167], v[16:19]
	v_mfma_f32_16x16x32_bf16 v[4:7], v[180:183], v[172:175], v[4:7]
	v_mfma_f32_16x16x32_bf16 v[0:3], v[188:191], v[172:175], v[0:3]
	s_setprio 0
	s_add_i32 s58, s58, 2
	s_add_u32 s56, s56, 0x100
	s_addc_u32 s57, s57, 0
	s_cmp_gt_u32 s58, 21
	s_mov_b64 s[24:25], s[26:27]
	s_barrier
; __device__ __forceinline__ unsigned cvt_pk_bf16(float lo, float hi) { unsigned r; asm volatile("v_cvt_pk_bf16_f32 %0, %1, %2" : "=v"(r) : "v"(lo), "v"(hi)); return r; }
; __device__ __forceinline__ float bf_lo(unsigned u) { return __uint_as_float(u << 16); }
; __device__ __forceinline__ float bf_hi(unsigned u) { return __uint_as_float(u & 0xffff0000u); }
;     __device__ __forceinline__ void operator()(const AccT& acc, const Unit& u, int wr, int wc, int fr, int fq) const {
;         asm volatile("" : "+v"(fr), "+v"(fq));
;         const int rowt = u.pm * 256; const int b = rowt >> 11;
;         const bf16_t* res = res_b + (size_t)rowt * DM; bf16_t* out = hb + (size_t)rowt * DM;
;         const int col0 = u.pn * 256 + wc * 32 + 8 * fq;
;         f32x4 gv[2][2];
; #pragma unroll
;         for (int bj = 0; bj < 2; ++bj)
; #pragma unroll
;             for (int n = 0; n < 2; ++n) gv[bj][n] = *(const f32x4*)(gate + (size_t)b * NMOD + col0 + bj * 128 + n * 4) * gs;
;         u32x4 r[2][4][2];
; #pragma unroll
;         for (int ai = 0; ai < 2; ++ai)
; #pragma unroll
;             for (int m = 0; m < 4; ++m)
; #pragma unroll
;                 for (int bj = 0; bj < 2; ++bj) r[ai][m][bj] = *(const u32x4*)(res + (size_t)(wr * 64 + fr + ai * 128 + m * 16) * DM + col0 + bj * 128);
; #pragma unroll
;         for (int ai = 0; ai < 2; ++ai)
; #pragma unroll
;             for (int m = 0; m < 4; ++m)
; #pragma unroll
;                 for (int bj = 0; bj < 2; ++bj) {
;                     const u32x4 q = r[ai][m][bj];
;                     const f32x4 r0 = {bf_lo(q.x), bf_hi(q.x), bf_lo(q.y), bf_hi(q.y)}, r1 = {bf_lo(q.z), bf_hi(q.z), bf_lo(q.w), bf_hi(q.w)};
;                     const f32x4 h0 = r0 + gv[bj][0] * acc[ai][bj][m][0], h1 = r1 + gv[bj][1] * acc[ai][bj][m][1];
;                     u32x4 w; w.x = cvt_pk_bf16(h0[0], h0[1]); w.y = cvt_pk_bf16(h0[2], h0[3]); w.z = cvt_pk_bf16(h1[0], h1[1]); w.w = cvt_pk_bf16(h1[2], h1[3]);
;                     *(u32x4*)(out + (size_t)(wr * 64 + fr + ai * 128 + m * 16) * DM + col0 + bj * 128) = w;
;                 }
	s_cbranch_scc0 .LBB0_902
	s_lshl_b32 s27, s55, 8
	v_mov_b32_e32 v146, v235
	v_mov_b32_e32 v128, v234
	s_lshl_b32 s24, s54, 8
	s_ashr_i32 s26, s54, 3
	s_or_b32 s27, s27, s46
	s_ashr_i32 s25, s24, 31
	v_lshl_add_u32 v144, v128, 3, s27
	s_mul_hi_i32 s27, s26, 0x9000
	s_mul_i32 s26, s26, 0x9000
	s_add_u32 s26, s43, s26
	s_addc_u32 s27, s44, s27
	v_ashrrev_i32_e32 v145, 31, v144
	s_lshl_b64 s[24:25], s[24:25], 11
	v_lshl_add_u64 v[132:133], v[144:145], 2, s[26:27]
	s_add_u32 s26, s62, s24
	v_add_u32_e32 v146, s45, v146
	s_addc_u32 s27, s63, s25
	v_lshlrev_b64 v[222:223], 1, v[144:145]
	v_ashrrev_i32_e32 v147, 31, v146
	v_lshl_add_u64 v[144:145], s[26:27], 0, v[222:223]
	v_lshlrev_b64 v[248:249], 11, v[146:147]
	v_lshl_add_u64 v[146:147], v[144:145], 0, v[248:249]
	global_load_dwordx4 v[136:139], v[132:133], off offset:16
	global_load_dwordx4 v[140:143], v[132:133], off
	global_load_dwordx4 v[128:131], v[132:133], off offset:528
	s_nop 0
	global_load_dwordx4 v[132:135], v[132:133], off offset:512
	s_nop 0
	global_load_dwordx4 v[240:243], v[146:147], off
	global_load_dwordx4 v[244:247], v[146:147], off offset:256
	v_lshl_add_u64 v[232:233], v[248:249], 0, s[10:11]
	v_lshl_add_u64 v[146:147], v[144:145], 0, v[232:233]
	global_load_dwordx4 v[196:199], v[146:147], off
	global_load_dwordx4 v[192:195], v[146:147], off offset:256
	v_lshl_add_u64 v[230:231], v[248:249], 0, s[12:13]
	v_lshl_add_u64 v[146:147], v[144:145], 0, v[230:231]
	global_load_dwordx4 v[188:191], v[146:147], off
	global_load_dwordx4 v[184:187], v[146:147], off offset:256
	v_lshl_add_u64 v[228:229], v[248:249], 0, s[14:15]
	v_lshl_add_u64 v[146:147], v[144:145], 0, v[228:229]
	global_load_dwordx4 v[180:183], v[146:147], off
	global_load_dwordx4 v[176:179], v[146:147], off offset:256
	v_lshl_add_u64 v[226:227], v[248:249], 0, s[16:17]
	v_lshl_add_u64 v[146:147], v[144:145], 0, v[226:227]
	global_load_dwordx4 v[172:175], v[146:147], off
	global_load_dwordx4 v[168:171], v[146:147], off offset:256
	v_lshl_add_u64 v[224:225], v[248:249], 0, s[18:19]
	v_lshl_add_u64 v[146:147], v[144:145], 0, v[224:225]
	global_load_dwordx4 v[164:167], v[146:147], off
	global_load_dwordx4 v[160:163], v[146:147], off offset:256
	v_lshl_add_u64 v[220:221], v[248:249], 0, s[20:21]
	v_lshl_add_u64 v[146:147], v[144:145], 0, v[220:221]
	global_load_dwordx4 v[156:159], v[146:147], off
	global_load_dwordx4 v[152:155], v[146:147], off offset:256
	v_lshl_add_u64 v[218:219], v[248:249], 0, s[22:23]
	v_lshl_add_u64 v[144:145], v[144:145], 0, v[218:219]
	global_load_dwordx4 v[148:151], v[144:145], off
	s_nop 0
	global_load_dwordx4 v[144:147], v[144:145], off offset:256
	s_add_u32 s24, s80, s24
	s_addc_u32 s25, s81, s25
	v_lshl_add_u64 v[222:223], s[24:25], 0, v[222:223]
	v_lshl_add_u64 v[248:249], v[222:223], 0, v[248:249]
	s_and_b64 vcc, exec, s[2:3]
	s_mov_b32 s55, s52
	s_mov_b32 s54, s53
	s_mov_b64 s[26:27], s[6:7]
	s_mov_b64 s[24:25], s[4:5]
	s_waitcnt vmcnt(0)
	v_lshlrev_b32_e32 v250, 16, v240
	v_and_b32_e32 v251, 0xffff0000, v240
	v_lshlrev_b32_e32 v240, 16, v241
	v_and_b32_e32 v241, 0xffff0000, v241
	v_lshlrev_b32_e32 v252, 16, v242
	v_and_b32_e32 v253, 0xffff0000, v242
	v_lshlrev_b32_e32 v242, 16, v243
	v_and_b32_e32 v243, 0xffff0000, v243
	v_pk_fma_f32 v[126:127], v[126:127], v[142:143], v[240:241]
	v_pk_fma_f32 v[124:125], v[124:125], v[140:141], v[250:251]
	v_pk_fma_f32 v[240:241], v[122:123], v[138:139], v[242:243]
	v_pk_fma_f32 v[122:123], v[120:121], v[136:137], v[252:253]
	v_cvt_pk_bf16_f32 v120, v124, v125
	v_cvt_pk_bf16_f32 v121, v126, v127
	v_lshlrev_b32_e32 v124, 16, v246
	v_cvt_pk_bf16_f32 v122, v122, v123
	v_cvt_pk_bf16_f32 v123, v240, v241
	global_store_dwordx4 v[248:249], v[120:123], off
	v_and_b32_e32 v125, 0xffff0000, v246
	v_lshlrev_b32_e32 v126, 16, v247
	v_lshlrev_b32_e32 v120, 16, v244
	v_and_b32_e32 v121, 0xffff0000, v244
	v_and_b32_e32 v127, 0xffff0000, v247
	v_lshlrev_b32_e32 v122, 16, v245
	v_and_b32_e32 v123, 0xffff0000, v245
	v_pk_fma_f32 v[116:117], v[116:117], v[132:133], v[120:121]
	v_pk_fma_f32 v[120:121], v[114:115], v[130:131], v[126:127]
	v_pk_fma_f32 v[114:115], v[112:113], v[128:129], v[124:125]
	v_pk_fma_f32 v[118:119], v[118:119], v[134:135], v[122:123]
	v_cvt_pk_bf16_f32 v112, v116, v117
	v_lshlrev_b32_e32 v116, 16, v197
	v_cvt_pk_bf16_f32 v113, v118, v119
	v_cvt_pk_bf16_f32 v114, v114, v115
	v_cvt_pk_bf16_f32 v115, v120, v121
	global_store_dwordx4 v[248:249], v[112:115], off offset:256
	v_and_b32_e32 v117, 0xffff0000, v197
	v_lshlrev_b32_e32 v118, 16, v198
	v_lshlrev_b32_e32 v114, 16, v196
	v_and_b32_e32 v115, 0xffff0000, v196
	v_and_b32_e32 v119, 0xffff0000, v198
	v_lshlrev_b32_e32 v120, 16, v199
	v_and_b32_e32 v121, 0xffff0000, v199
	v_lshl_add_u64 v[112:113], v[222:223], 0, v[232:233]
	v_pk_fma_f32 v[110:111], v[110:111], v[142:143], v[116:117]
	v_pk_fma_f32 v[108:109], v[108:109], v[140:141], v[114:115]
	v_pk_fma_f32 v[114:115], v[106:107], v[138:139], v[120:121]
	v_pk_fma_f32 v[106:107], v[104:105], v[136:137], v[118:119]
	v_cvt_pk_bf16_f32 v104, v108, v109
	v_cvt_pk_bf16_f32 v105, v110, v111
	v_lshlrev_b32_e32 v108, 16, v194
	v_cvt_pk_bf16_f32 v106, v106, v107
	v_cvt_pk_bf16_f32 v107, v114, v115
	global_store_dwordx4 v[112:113], v[104:107], off
	v_and_b32_e32 v109, 0xffff0000, v194
	v_lshlrev_b32_e32 v110, 16, v195
	v_lshlrev_b32_e32 v104, 16, v192
	v_and_b32_e32 v105, 0xffff0000, v192
	v_and_b32_e32 v111, 0xffff0000, v195
	v_lshlrev_b32_e32 v106, 16, v193
	v_and_b32_e32 v107, 0xffff0000, v193
	v_pk_fma_f32 v[100:101], v[100:101], v[132:133], v[104:105]
	v_pk_fma_f32 v[104:105], v[98:99], v[130:131], v[110:111]
	v_pk_fma_f32 v[98:99], v[96:97], v[128:129], v[108:109]
; __device__ __forceinline__ unsigned cvt_pk_bf16(float lo, float hi) { unsigned r; asm volatile("v_cvt_pk_bf16_f32 %0, %1, %2" : "=v"(r) : "v"(lo), "v"(hi)); return r; }
; __device__ __forceinline__ float bf_lo(unsigned u) { return __uint_as_float(u << 16); }
; __device__ __forceinline__ float bf_hi(unsigned u) { return __uint_as_float(u & 0xffff0000u); }
;     __device__ __forceinline__ void operator()(const AccT& acc, const Unit& u, int wr, int wc, int fr, int fq) const {
;     ...
; #pragma unroll
;         for (int ai = 0; ai < 2; ++ai)
; #pragma unroll
;             for (int m = 0; m < 4; ++m)
; #pragma unroll
;                 for (int bj = 0; bj < 2; ++bj) {
;                     const u32x4 q = r[ai][m][bj];
;                     const f32x4 r0 = {bf_lo(q.x), bf_hi(q.x), bf_lo(q.y), bf_hi(q.y)}, r1 = {bf_lo(q.z), bf_hi(q.z), bf_lo(q.w), bf_hi(q.w)};
;                     const f32x4 h0 = r0 + gv[bj][0] * acc[ai][bj][m][0], h1 = r1 + gv[bj][1] * acc[ai][bj][m][1];
;                     u32x4 w; w.x = cvt_pk_bf16(h0[0], h0[1]); w.y = cvt_pk_bf16(h0[2], h0[3]); w.z = cvt_pk_bf16(h1[0], h1[1]); w.w = cvt_pk_bf16(h1[2], h1[3]);
;                     *(u32x4*)(out + (size_t)(wr * 64 + fr + ai * 128 + m * 16) * DM + col0 + bj * 128) = w;
;                 }
	v_pk_fma_f32 v[102:103], v[102:103], v[134:135], v[106:107]
	v_cvt_pk_bf16_f32 v96, v100, v101
	v_lshlrev_b32_e32 v100, 16, v189
	v_cvt_pk_bf16_f32 v97, v102, v103
	v_cvt_pk_bf16_f32 v98, v98, v99
	v_cvt_pk_bf16_f32 v99, v104, v105
	global_store_dwordx4 v[112:113], v[96:99], off offset:256
	v_and_b32_e32 v101, 0xffff0000, v189
	v_lshlrev_b32_e32 v102, 16, v190
	v_lshlrev_b32_e32 v98, 16, v188
	v_and_b32_e32 v99, 0xffff0000, v188
	v_and_b32_e32 v103, 0xffff0000, v190
	v_lshlrev_b32_e32 v104, 16, v191
	v_and_b32_e32 v105, 0xffff0000, v191
	v_lshl_add_u64 v[96:97], v[222:223], 0, v[230:231]
	v_pk_fma_f32 v[94:95], v[94:95], v[142:143], v[100:101]
	v_pk_fma_f32 v[92:93], v[92:93], v[140:141], v[98:99]
	v_pk_fma_f32 v[98:99], v[90:91], v[138:139], v[104:105]
	v_pk_fma_f32 v[90:91], v[88:89], v[136:137], v[102:103]
	v_cvt_pk_bf16_f32 v88, v92, v93
	v_cvt_pk_bf16_f32 v89, v94, v95
	v_lshlrev_b32_e32 v92, 16, v186
	v_cvt_pk_bf16_f32 v90, v90, v91
	v_cvt_pk_bf16_f32 v91, v98, v99
	global_store_dwordx4 v[96:97], v[88:91], off
	v_and_b32_e32 v93, 0xffff0000, v186
	v_lshlrev_b32_e32 v94, 16, v187
	v_lshlrev_b32_e32 v88, 16, v184
	v_and_b32_e32 v89, 0xffff0000, v184
	v_and_b32_e32 v95, 0xffff0000, v187
	v_lshlrev_b32_e32 v90, 16, v185
	v_and_b32_e32 v91, 0xffff0000, v185
	v_pk_fma_f32 v[84:85], v[84:85], v[132:133], v[88:89]
	v_pk_fma_f32 v[88:89], v[82:83], v[130:131], v[94:95]
	v_pk_fma_f32 v[82:83], v[80:81], v[128:129], v[92:93]
	v_pk_fma_f32 v[86:87], v[86:87], v[134:135], v[90:91]
	v_cvt_pk_bf16_f32 v80, v84, v85
	v_lshlrev_b32_e32 v84, 16, v181
	v_cvt_pk_bf16_f32 v81, v86, v87
	v_cvt_pk_bf16_f32 v82, v82, v83
	v_cvt_pk_bf16_f32 v83, v88, v89
	global_store_dwordx4 v[96:97], v[80:83], off offset:256
	v_and_b32_e32 v85, 0xffff0000, v181
	v_lshlrev_b32_e32 v86, 16, v182
	v_lshlrev_b32_e32 v82, 16, v180
	v_and_b32_e32 v83, 0xffff0000, v180
	v_and_b32_e32 v87, 0xffff0000, v182
	v_lshlrev_b32_e32 v88, 16, v183
	v_and_b32_e32 v89, 0xffff0000, v183
	v_lshl_add_u64 v[80:81], v[222:223], 0, v[228:229]
	v_pk_fma_f32 v[78:79], v[78:79], v[142:143], v[84:85]
	v_pk_fma_f32 v[76:77], v[76:77], v[140:141], v[82:83]
	v_pk_fma_f32 v[82:83], v[74:75], v[138:139], v[88:89]
	v_pk_fma_f32 v[74:75], v[72:73], v[136:137], v[86:87]
	v_cvt_pk_bf16_f32 v72, v76, v77
	v_cvt_pk_bf16_f32 v73, v78, v79
	v_lshlrev_b32_e32 v76, 16, v178
	v_cvt_pk_bf16_f32 v74, v74, v75
	v_cvt_pk_bf16_f32 v75, v82, v83
	global_store_dwordx4 v[80:81], v[72:75], off
	v_and_b32_e32 v77, 0xffff0000, v178
	v_lshlrev_b32_e32 v78, 16, v179
	v_lshlrev_b32_e32 v72, 16, v176
	v_and_b32_e32 v73, 0xffff0000, v176
	v_and_b32_e32 v79, 0xffff0000, v179
	v_lshlrev_b32_e32 v74, 16, v177
	v_and_b32_e32 v75, 0xffff0000, v177
	v_pk_fma_f32 v[68:69], v[68:69], v[132:133], v[72:73]
	v_pk_fma_f32 v[72:73], v[66:67], v[130:131], v[78:79]
	v_pk_fma_f32 v[66:67], v[64:65], v[128:129], v[76:77]
	v_pk_fma_f32 v[70:71], v[70:71], v[134:135], v[74:75]
	v_cvt_pk_bf16_f32 v64, v68, v69
	v_lshlrev_b32_e32 v68, 16, v173
	v_cvt_pk_bf16_f32 v65, v70, v71
	v_cvt_pk_bf16_f32 v66, v66, v67
	v_cvt_pk_bf16_f32 v67, v72, v73
	global_store_dwordx4 v[80:81], v[64:67], off offset:256
	v_and_b32_e32 v69, 0xffff0000, v173
	v_lshlrev_b32_e32 v70, 16, v174
	v_lshlrev_b32_e32 v66, 16, v172
	v_and_b32_e32 v67, 0xffff0000, v172
	v_and_b32_e32 v71, 0xffff0000, v174
	v_lshlrev_b32_e32 v72, 16, v175
	v_and_b32_e32 v73, 0xffff0000, v175
	v_lshl_add_u64 v[64:65], v[222:223], 0, v[226:227]
	v_pk_fma_f32 v[62:63], v[62:63], v[142:143], v[68:69]
	v_pk_fma_f32 v[60:61], v[60:61], v[140:141], v[66:67]
	v_pk_fma_f32 v[66:67], v[58:59], v[138:139], v[72:73]
	v_pk_fma_f32 v[58:59], v[56:57], v[136:137], v[70:71]
	v_cvt_pk_bf16_f32 v56, v60, v61
	v_cvt_pk_bf16_f32 v57, v62, v63
	v_lshlrev_b32_e32 v60, 16, v170
	v_cvt_pk_bf16_f32 v58, v58, v59
	v_cvt_pk_bf16_f32 v59, v66, v67
	global_store_dwordx4 v[64:65], v[56:59], off
	v_and_b32_e32 v61, 0xffff0000, v170
	v_lshlrev_b32_e32 v62, 16, v171
	v_lshlrev_b32_e32 v56, 16, v168
	v_and_b32_e32 v57, 0xffff0000, v168
	v_and_b32_e32 v63, 0xffff0000, v171
	v_lshlrev_b32_e32 v58, 16, v169
	v_and_b32_e32 v59, 0xffff0000, v169
	v_pk_fma_f32 v[52:53], v[52:53], v[132:133], v[56:57]
	v_pk_fma_f32 v[56:57], v[50:51], v[130:131], v[62:63]
	v_pk_fma_f32 v[50:51], v[48:49], v[128:129], v[60:61]
	v_pk_fma_f32 v[54:55], v[54:55], v[134:135], v[58:59]
	v_cvt_pk_bf16_f32 v48, v52, v53
	v_lshlrev_b32_e32 v52, 16, v165
	v_cvt_pk_bf16_f32 v49, v54, v55
; __device__ __forceinline__ unsigned cvt_pk_bf16(float lo, float hi) { unsigned r; asm volatile("v_cvt_pk_bf16_f32 %0, %1, %2" : "=v"(r) : "v"(lo), "v"(hi)); return r; }
; __device__ __forceinline__ float bf_lo(unsigned u) { return __uint_as_float(u << 16); }
; __device__ __forceinline__ float bf_hi(unsigned u) { return __uint_as_float(u & 0xffff0000u); }
; #define PG8_WAIT_V(n) asm volatile("s_waitcnt vmcnt(" #n ")" ::: "memory")
; #define PG8_BAR __builtin_amdgcn_s_barrier()
; template <class Epi, class Sched>
; __device__ __forceinline__ void gemm_phase(LAS unsigned char* lds, const Gemm g, const Sched& S, const Epi& E) {
;     ...
;         E(acc, cur, wr, wc, fr, fq);
;         if (!has_next) break;
; #pragma unroll
;         for (int a = 0; a < 2; ++a)
; #pragma unroll
;             for (int b = 0; b < 2; ++b)
; #pragma unroll
;                 for (int m = 0; m < 4; ++m)
; #pragma unroll
;                     for (int n = 0; n < 2; ++n) acc[a][b][m][n] = (f32x4){0.f, 0.f, 0.f, 0.f};
;         cur = nxt; cA = nA; cB = nB; ++ui;
;     }
;     PG8_WAIT_V(0);
;     if (wr == 0) PG8_BAR;
;     PG8_BAR;
;     __device__ __forceinline__ void operator()(const AccT& acc, const Unit& u, int wr, int wc, int fr, int fq) const {
;     ...
; #pragma unroll
;         for (int ai = 0; ai < 2; ++ai)
; #pragma unroll
;             for (int m = 0; m < 4; ++m)
; #pragma unroll
;                 for (int bj = 0; bj < 2; ++bj) {
;                     const u32x4 q = r[ai][m][bj];
;                     const f32x4 r0 = {bf_lo(q.x), bf_hi(q.x), bf_lo(q.y), bf_hi(q.y)}, r1 = {bf_lo(q.z), bf_hi(q.z), bf_lo(q.w), bf_hi(q.w)};
;                     const f32x4 h0 = r0 + gv[bj][0] * acc[ai][bj][m][0], h1 = r1 + gv[bj][1] * acc[ai][bj][m][1];
;                     u32x4 w; w.x = cvt_pk_bf16(h0[0], h0[1]); w.y = cvt_pk_bf16(h0[2], h0[3]); w.z = cvt_pk_bf16(h1[0], h1[1]); w.w = cvt_pk_bf16(h1[2], h1[3]);
;                     *(u32x4*)(out + (size_t)(wr * 64 + fr + ai * 128 + m * 16) * DM + col0 + bj * 128) = w;
;                 }
	v_cvt_pk_bf16_f32 v50, v50, v51
	v_cvt_pk_bf16_f32 v51, v56, v57
	global_store_dwordx4 v[64:65], v[48:51], off offset:256
	v_and_b32_e32 v53, 0xffff0000, v165
	v_lshlrev_b32_e32 v54, 16, v166
	v_lshlrev_b32_e32 v50, 16, v164
	v_and_b32_e32 v51, 0xffff0000, v164
	v_and_b32_e32 v55, 0xffff0000, v166
	v_lshlrev_b32_e32 v56, 16, v167
	v_and_b32_e32 v57, 0xffff0000, v167
	v_lshl_add_u64 v[48:49], v[222:223], 0, v[224:225]
	v_pk_fma_f32 v[46:47], v[46:47], v[142:143], v[52:53]
	v_pk_fma_f32 v[44:45], v[44:45], v[140:141], v[50:51]
	v_pk_fma_f32 v[50:51], v[42:43], v[138:139], v[56:57]
	v_pk_fma_f32 v[42:43], v[40:41], v[136:137], v[54:55]
	v_cvt_pk_bf16_f32 v40, v44, v45
	v_cvt_pk_bf16_f32 v41, v46, v47
	v_lshlrev_b32_e32 v44, 16, v162
	v_cvt_pk_bf16_f32 v42, v42, v43
	v_cvt_pk_bf16_f32 v43, v50, v51
	global_store_dwordx4 v[48:49], v[40:43], off
	v_and_b32_e32 v45, 0xffff0000, v162
	v_lshlrev_b32_e32 v46, 16, v163
	v_lshlrev_b32_e32 v40, 16, v160
	v_and_b32_e32 v41, 0xffff0000, v160
	v_and_b32_e32 v47, 0xffff0000, v163
	v_lshlrev_b32_e32 v42, 16, v161
	v_and_b32_e32 v43, 0xffff0000, v161
	v_pk_fma_f32 v[36:37], v[36:37], v[132:133], v[40:41]
	v_pk_fma_f32 v[40:41], v[34:35], v[130:131], v[46:47]
	v_pk_fma_f32 v[34:35], v[32:33], v[128:129], v[44:45]
	v_pk_fma_f32 v[38:39], v[38:39], v[134:135], v[42:43]
	v_cvt_pk_bf16_f32 v32, v36, v37
	v_lshlrev_b32_e32 v36, 16, v157
	v_cvt_pk_bf16_f32 v33, v38, v39
	v_cvt_pk_bf16_f32 v34, v34, v35
	v_cvt_pk_bf16_f32 v35, v40, v41
	global_store_dwordx4 v[48:49], v[32:35], off offset:256
	v_and_b32_e32 v37, 0xffff0000, v157
	v_lshlrev_b32_e32 v38, 16, v158
	v_lshlrev_b32_e32 v34, 16, v156
	v_and_b32_e32 v35, 0xffff0000, v156
	v_and_b32_e32 v39, 0xffff0000, v158
	v_lshlrev_b32_e32 v40, 16, v159
	v_and_b32_e32 v41, 0xffff0000, v159
	v_lshl_add_u64 v[32:33], v[222:223], 0, v[220:221]
	v_pk_fma_f32 v[30:31], v[30:31], v[142:143], v[36:37]
	v_pk_fma_f32 v[28:29], v[28:29], v[140:141], v[34:35]
	v_pk_fma_f32 v[34:35], v[26:27], v[138:139], v[40:41]
	v_pk_fma_f32 v[26:27], v[24:25], v[136:137], v[38:39]
	v_cvt_pk_bf16_f32 v24, v28, v29
	v_cvt_pk_bf16_f32 v25, v30, v31
	v_lshlrev_b32_e32 v28, 16, v154
	v_cvt_pk_bf16_f32 v26, v26, v27
	v_cvt_pk_bf16_f32 v27, v34, v35
	global_store_dwordx4 v[32:33], v[24:27], off
	v_and_b32_e32 v29, 0xffff0000, v154
	v_lshlrev_b32_e32 v30, 16, v155
	v_lshlrev_b32_e32 v24, 16, v152
	v_and_b32_e32 v25, 0xffff0000, v152
	v_and_b32_e32 v31, 0xffff0000, v155
	v_lshlrev_b32_e32 v26, 16, v153
	v_and_b32_e32 v27, 0xffff0000, v153
	v_pk_fma_f32 v[20:21], v[20:21], v[132:133], v[24:25]
	v_pk_fma_f32 v[24:25], v[18:19], v[130:131], v[30:31]
	v_pk_fma_f32 v[18:19], v[16:17], v[128:129], v[28:29]
	v_pk_fma_f32 v[22:23], v[22:23], v[134:135], v[26:27]
	v_cvt_pk_bf16_f32 v16, v20, v21
	v_lshlrev_b32_e32 v20, 16, v149
	v_cvt_pk_bf16_f32 v17, v22, v23
	v_cvt_pk_bf16_f32 v18, v18, v19
	v_cvt_pk_bf16_f32 v19, v24, v25
	global_store_dwordx4 v[32:33], v[16:19], off offset:256
	v_and_b32_e32 v21, 0xffff0000, v149
	v_lshlrev_b32_e32 v22, 16, v150
	v_lshlrev_b32_e32 v18, 16, v148
	v_and_b32_e32 v19, 0xffff0000, v148
	v_and_b32_e32 v23, 0xffff0000, v150
	v_lshlrev_b32_e32 v24, 16, v151
	v_and_b32_e32 v25, 0xffff0000, v151
	v_lshl_add_u64 v[16:17], v[222:223], 0, v[218:219]
	v_pk_fma_f32 v[14:15], v[14:15], v[142:143], v[20:21]
	v_pk_fma_f32 v[12:13], v[12:13], v[140:141], v[18:19]
	v_pk_fma_f32 v[18:19], v[10:11], v[138:139], v[24:25]
	v_pk_fma_f32 v[10:11], v[8:9], v[136:137], v[22:23]
	v_cvt_pk_bf16_f32 v8, v12, v13
	v_cvt_pk_bf16_f32 v9, v14, v15
	v_lshlrev_b32_e32 v12, 16, v146
	v_cvt_pk_bf16_f32 v10, v10, v11
	v_cvt_pk_bf16_f32 v11, v18, v19
	global_store_dwordx4 v[16:17], v[8:11], off
	v_and_b32_e32 v13, 0xffff0000, v146
	v_lshlrev_b32_e32 v14, 16, v147
	v_lshlrev_b32_e32 v8, 16, v144
	v_and_b32_e32 v9, 0xffff0000, v144
	v_and_b32_e32 v15, 0xffff0000, v147
	v_lshlrev_b32_e32 v10, 16, v145
	v_and_b32_e32 v11, 0xffff0000, v145
	v_pk_fma_f32 v[4:5], v[4:5], v[132:133], v[8:9]
	v_pk_fma_f32 v[8:9], v[2:3], v[130:131], v[14:15]
	v_pk_fma_f32 v[2:3], v[0:1], v[128:129], v[12:13]
	v_pk_fma_f32 v[6:7], v[6:7], v[134:135], v[10:11]
	v_cvt_pk_bf16_f32 v0, v4, v5
	s_nop 0
	v_cvt_pk_bf16_f32 v1, v6, v7
	v_cvt_pk_bf16_f32 v2, v2, v3
	v_cvt_pk_bf16_f32 v3, v8, v9
	global_store_dwordx4 v[16:17], v[0:3], off offset:256
	s_cbranch_vccz .LBB0_891
	s_waitcnt vmcnt(0)
	s_cmpk_gt_u32 s33, 0xff
	s_cbranch_scc1 .LBB0_906
	s_barrier

; #define PG8_STAGE(bufoff, gbase, voff) do { _Pragma("unroll") for (int _i = 0; _i < 2; ++_i) \
;         __builtin_amdgcn_global_load_lds((const unsigned*)((const char*)(gbase) + (voff)[_i]), (LAS unsigned*)(lds + (bufoff) + ldsw + _i * 8192), 16, 0, 0); } while (0)
; #define PG8_LDA(dst, b, h) do { _Pragma("unroll") for (int m = 0; m < 4; ++m) _Pragma("unroll") for (int k = 0; k < 2; ++k) dst[m][k] = *(const LAS bf16x8*)(lds + PG8_SA(b, h) + aoff + m * 2048 + k * 1024); } while (0)
; #define PG8_LDB(dst, b, h) do { _Pragma("unroll") for (int n = 0; n < 2; ++n) _Pragma("unroll") for (int k = 0; k < 2; ++k) dst[n][k] = *(const LAS bf16x8*)(lds + PG8_SB(b, h) + boff + n * 2048 + k * 1024); } while (0)
; #define PG8_WAIT_V(n) asm volatile("s_waitcnt vmcnt(" #n ")" ::: "memory")
; #define PG8_WAIT_L(n) asm volatile("s_waitcnt lgkmcnt(" #n ")" ::: "memory")
; #define PG8_BAR __builtin_amdgcn_s_barrier()
; #define PG8_SCHED __builtin_amdgcn_sched_barrier(0)
; template <class Epi, class Sched>
; __device__ __forceinline__ void gemm_phase(LAS unsigned char* lds, const Gemm g, const Sched& S, const Epi& E) {
;     ...
;     for (;;) {
;         const bool has_next = S.next(ui + 1, nxt);
;         const char* nA = has_next ? (const char*)g.A + (size_t)nxt.pm * tstep : cA; const char* nB = has_next ? (const char*)g.Bt + (size_t)nxt.pn * tstep : cB;
;         for (int t = 0; t < nt; t += 2) {
;             const bool last = (t == nt - 2);
;             const char* a1 = cA + (size_t)(t + 1) * kstep;
;             const char* a2 = last ? nA : cA + (size_t)(t + 2) * kstep; const char* b2 = last ? nB : cB + (size_t)(t + 2) * kstep;
;             const char* a3 = a2 + kstep; const char* b3 = b2 + kstep;
;             PG8_LDB(B0, 0, 0); PG8_SCHED; PG8_LDA(At, 0, 0); PG8_STAGE(PG8_SA(1, 1), a1 + hstep, voffA);
;             PG8_WAIT_L(8); PG8_BAR; PG8_WAIT_L(0); PG8_MMA(0, 0, At, B0); PG8_BAR; PG8_SCHED;
;             PG8_LDB(B1, 0, 1); PG8_STAGE(PG8_SB(0, 0), b2, voffB);
;             PG8_BAR; PG8_WAIT_L(0); PG8_MMA(0, 1, At, B1); PG8_BAR;
;             PG8_LDA(At, 0, 1); PG8_STAGE(PG8_SA(0, 0), a2, voffA);
;             PG8_BAR; PG8_WAIT_L(0); PG8_MMA(1, 0, At, B0); PG8_BAR; PG8_SCHED;
;             PG8_STAGE(PG8_SB(0, 1), b2 + hstep, voffB);
;             PG8_WAIT_V(6); PG8_BAR; PG8_MMA(1, 1, At, B1); PG8_BAR;
.LBB0_1020:
	s_ashr_i32 s7, s6, 31
	v_cmp_lt_i64_e32 vcc, s[10:11], v[140:141]
	s_lshl_b64 s[10:11], s[6:7], 19
	s_add_u32 s10, s96, s10
	s_addc_u32 s11, s97, s11
	s_and_b64 s[12:13], vcc, exec
	s_cselect_b32 s7, s11, s17
	s_cselect_b32 s42, s10, s16
	s_ashr_i32 s5, s4, 31
	s_lshl_b64 s[12:13], s[4:5], 19
	s_add_u32 s12, s23, s12
	s_addc_u32 s13, s24, s13
	s_and_b64 s[20:21], vcc, exec
	s_cselect_b32 s5, s13, s19
	s_cselect_b32 s43, s12, s18
	s_add_u32 s16, s16, 0x40080
	s_addc_u32 s17, s17, 0
	s_add_u32 s44, s18, 0x100
	s_addc_u32 s45, s19, 0
	s_mov_b32 s46, -2
	ds_read_b128 v[150:153], v147
	ds_read_b128 v[154:157], v147 offset:1024
	ds_read_b128 v[158:161], v147 offset:2048
	ds_read_b128 v[162:165], v147 offset:3072
	s_add_u32 s18, s16, 0xfffc0080
	s_addc_u32 s19, s17, -1
	s_cmp_eq_u32 s46, 12
	s_cselect_b32 s21, s7, s19
	s_cselect_b32 s20, s42, s18
	s_cselect_b32 s19, s5, s45
	s_cselect_b32 s18, s43, s44
	s_add_i32 m0, s15, 0xc000
	ds_read_b128 v[166:169], v148
	ds_read_b128 v[170:173], v148 offset:1024
	ds_read_b128 v[174:177], v148 offset:2048
	ds_read_b128 v[178:181], v148 offset:3072
	ds_read_b128 v[182:185], v148 offset:4096
	ds_read_b128 v[186:189], v148 offset:5120
	ds_read_b128 v[190:193], v148 offset:6144
	ds_read_b128 v[194:197], v148 offset:7168
	global_load_lds_dwordx4 v136, s[16:17]
	s_add_i32 m0, s15, 0xe000
	s_nop 0
	global_load_lds_dwordx4 v138, s[16:17]
	s_waitcnt lgkmcnt(8)
	s_waitcnt vmcnt(8)
	s_setprio 1
	s_barrier
	s_waitcnt lgkmcnt(0)
	s_waitcnt lgkmcnt(0)
	v_mfma_f32_16x16x32_bf16 v[124:127], v[150:153], v[166:169], 0
	v_mfma_f32_16x16x32_bf16 v[116:119], v[158:161], v[166:169], 0
	v_mfma_f32_16x16x32_bf16 v[108:111], v[150:153], v[174:177], 0
	v_mfma_f32_16x16x32_bf16 v[100:103], v[158:161], v[174:177], 0
	v_mfma_f32_16x16x32_bf16 v[92:95], v[150:153], v[182:185], 0
	v_mfma_f32_16x16x32_bf16 v[84:87], v[158:161], v[182:185], 0
	v_mfma_f32_16x16x32_bf16 v[76:79], v[150:153], v[190:193], 0
	v_mfma_f32_16x16x32_bf16 v[68:71], v[158:161], v[190:193], 0
	v_mfma_f32_16x16x32_bf16 v[124:127], v[154:157], v[170:173], v[124:127]
	v_mfma_f32_16x16x32_bf16 v[116:119], v[162:165], v[170:173], v[116:119]
	v_mfma_f32_16x16x32_bf16 v[108:111], v[154:157], v[178:181], v[108:111]
	v_mfma_f32_16x16x32_bf16 v[100:103], v[162:165], v[178:181], v[100:103]
	v_mfma_f32_16x16x32_bf16 v[92:95], v[154:157], v[186:189], v[92:95]
	v_mfma_f32_16x16x32_bf16 v[84:87], v[162:165], v[186:189], v[84:87]
	v_mfma_f32_16x16x32_bf16 v[76:79], v[154:157], v[194:197], v[76:79]
	v_mfma_f32_16x16x32_bf16 v[68:71], v[162:165], v[194:197], v[68:71]
	s_setprio 0
	s_barrier
	s_add_i32 s47, s38, s25
	s_mov_b32 m0, s47
	ds_read_b128 v[202:205], v149
	ds_read_b128 v[206:209], v149 offset:1024
	ds_read_b128 v[210:213], v149 offset:2048
	ds_read_b128 v[214:217], v149 offset:3072
	global_load_lds_dwordx4 v132, s[18:19]
	s_add_i32 m0, s47, 0x2000
	s_nop 0
	global_load_lds_dwordx4 v128, s[18:19]
	s_waitcnt vmcnt(8)
	s_setprio 1
	s_barrier
	s_waitcnt lgkmcnt(0)
	s_waitcnt lgkmcnt(0)
	v_mfma_f32_16x16x32_bf16 v[120:123], v[202:205], v[166:169], 0
	v_mfma_f32_16x16x32_bf16 v[112:115], v[210:213], v[166:169], 0
	v_mfma_f32_16x16x32_bf16 v[104:107], v[202:205], v[174:177], 0
	v_mfma_f32_16x16x32_bf16 v[96:99], v[210:213], v[174:177], 0
	v_mfma_f32_16x16x32_bf16 v[88:91], v[202:205], v[182:185], 0
	v_mfma_f32_16x16x32_bf16 v[80:83], v[210:213], v[182:185], 0
	v_mfma_f32_16x16x32_bf16 v[72:75], v[202:205], v[190:193], 0
	v_mfma_f32_16x16x32_bf16 v[64:67], v[210:213], v[190:193], 0
	v_mfma_f32_16x16x32_bf16 v[120:123], v[206:209], v[170:173], v[120:123]
	v_mfma_f32_16x16x32_bf16 v[112:115], v[214:217], v[170:173], v[112:115]
	v_mfma_f32_16x16x32_bf16 v[104:107], v[206:209], v[178:181], v[104:107]
	v_mfma_f32_16x16x32_bf16 v[96:99], v[214:217], v[178:181], v[96:99]
	v_mfma_f32_16x16x32_bf16 v[88:91], v[206:209], v[186:189], v[88:91]
	v_mfma_f32_16x16x32_bf16 v[80:83], v[214:217], v[186:189], v[80:83]
	v_mfma_f32_16x16x32_bf16 v[72:75], v[206:209], v[194:197], v[72:75]
	v_mfma_f32_16x16x32_bf16 v[64:67], v[214:217], v[194:197], v[64:67]
	s_setprio 0
	s_mov_b32 m0, s15
	v_lshl_add_u64 v[220:221], s[20:21], 0, v[134:135]
	s_barrier
	ds_read_b128 v[166:169], v148 offset:16384
	ds_read_b128 v[170:173], v148 offset:17408
	ds_read_b128 v[174:177], v148 offset:18432
	ds_read_b128 v[178:181], v148 offset:19456
	ds_read_b128 v[182:185], v148 offset:20480
	ds_read_b128 v[186:189], v148 offset:21504
	ds_read_b128 v[190:193], v148 offset:22528
	ds_read_b128 v[194:197], v148 offset:23552
	global_load_lds_dwordx4 v134, s[20:21]
	v_lshl_add_u64 v[222:223], s[20:21], 0, v[130:131]
	s_mov_b32 m0, s28
	s_nop 0
	global_load_lds_dwordx4 v130, s[20:21]
	s_setprio 1
	s_barrier
	s_waitcnt lgkmcnt(0)
	s_waitcnt lgkmcnt(0)
	v_mfma_f32_16x16x32_bf16 v[60:63], v[150:153], v[166:169], 0
	v_mfma_f32_16x16x32_bf16 v[56:59], v[158:161], v[166:169], 0
	v_mfma_f32_16x16x32_bf16 v[44:47], v[150:153], v[174:177], 0
	v_mfma_f32_16x16x32_bf16 v[40:43], v[158:161], v[174:177], 0
	v_mfma_f32_16x16x32_bf16 v[28:31], v[150:153], v[182:185], 0
	v_mfma_f32_16x16x32_bf16 v[24:27], v[158:161], v[182:185], 0
	v_mfma_f32_16x16x32_bf16 v[12:15], v[150:153], v[190:193], 0
	v_mfma_f32_16x16x32_bf16 v[8:11], v[158:161], v[190:193], 0
	v_mfma_f32_16x16x32_bf16 v[60:63], v[154:157], v[170:173], v[60:63]
	v_mfma_f32_16x16x32_bf16 v[56:59], v[162:165], v[170:173], v[56:59]
	v_mfma_f32_16x16x32_bf16 v[44:47], v[154:157], v[178:181], v[44:47]
	v_mfma_f32_16x16x32_bf16 v[40:43], v[162:165], v[178:181], v[40:43]
	v_mfma_f32_16x16x32_bf16 v[28:31], v[154:157], v[186:189], v[28:31]
	v_mfma_f32_16x16x32_bf16 v[24:27], v[162:165], v[186:189], v[24:27]
	v_mfma_f32_16x16x32_bf16 v[12:15], v[154:157], v[194:197], v[12:15]
	v_mfma_f32_16x16x32_bf16 v[8:11], v[162:165], v[194:197], v[8:11]
	s_setprio 0
	s_barrier
; #define PG8_STAGE(bufoff, gbase, voff) do { _Pragma("unroll") for (int _i = 0; _i < 2; ++_i) \
;         __builtin_amdgcn_global_load_lds((const unsigned*)((const char*)(gbase) + (voff)[_i]), (LAS unsigned*)(lds + (bufoff) + ldsw + _i * 8192), 16, 0, 0); } while (0)
; #define PG8_LDA(dst, b, h) do { _Pragma("unroll") for (int m = 0; m < 4; ++m) _Pragma("unroll") for (int k = 0; k < 2; ++k) dst[m][k] = *(const LAS bf16x8*)(lds + PG8_SA(b, h) + aoff + m * 2048 + k * 1024); } while (0)
; #define PG8_LDB(dst, b, h) do { _Pragma("unroll") for (int n = 0; n < 2; ++n) _Pragma("unroll") for (int k = 0; k < 2; ++k) dst[n][k] = *(const LAS bf16x8*)(lds + PG8_SB(b, h) + boff + n * 2048 + k * 1024); } while (0)
; #define PG8_MMA(ai, bj, At, Bt) do { __builtin_amdgcn_s_setprio(1); _Pragma("unroll") for (int m = 0; m < 4; ++m) _Pragma("unroll") for (int n = 0; n < 2; ++n) _Pragma("unroll") for (int k = 0; k < 2; ++k) \
;         acc[ai][bj][m][n] = __builtin_amdgcn_mfma_f32_16x16x32_bf16(Bt[n][k], At[m][k], acc[ai][bj][m][n], 0, 0, 0); __builtin_amdgcn_s_setprio(0); } while (0)
; #define PG8_WAIT_V(n) asm volatile("s_waitcnt vmcnt(" #n ")" ::: "memory")
; #define PG8_WAIT_L(n) asm volatile("s_waitcnt lgkmcnt(" #n ")" ::: "memory")
; #define PG8_BAR __builtin_amdgcn_s_barrier()
; #define PG8_SCHED __builtin_amdgcn_sched_barrier(0)
; template <class Epi, class Sched>
; __device__ __forceinline__ void gemm_phase(LAS unsigned char* lds, const Gemm g, const Sched& S, const Epi& E) {
;     ...
;             PG8_STAGE(PG8_SB(0, 1), b2 + hstep, voffB);
;             PG8_WAIT_V(6); PG8_BAR; PG8_MMA(1, 1, At, B1); PG8_BAR;
;             PG8_LDB(B0, 1, 0); PG8_SCHED; PG8_LDA(At, 1, 0); PG8_STAGE(PG8_SA(0, 1), a2 + hstep, voffA);
;             PG8_WAIT_L(8); PG8_BAR; PG8_WAIT_L(0); PG8_MMA(0, 0, At, B0); PG8_BAR; PG8_SCHED;
;             PG8_LDB(B1, 1, 1); PG8_STAGE(PG8_SB(1, 0), b3, voffB);
;             PG8_BAR; PG8_WAIT_L(0); PG8_MMA(0, 1, At, B1); PG8_BAR;
;             PG8_LDA(At, 1, 1); PG8_STAGE(PG8_SA(1, 0), a3, voffA);
;             PG8_BAR; PG8_WAIT_L(0); PG8_MMA(1, 0, At, B0); PG8_BAR; PG8_SCHED;
	s_add_u32 s48, s18, 0x40000
	s_addc_u32 s49, s19, 0
	s_add_i32 s47, s39, s25
	s_mov_b32 m0, s47
	s_nop 0
	global_load_lds_dwordx4 v132, s[48:49]
	s_add_i32 m0, s47, 0x2000
	s_nop 0
	global_load_lds_dwordx4 v128, s[48:49]
	s_add_u32 s20, s20, 0x40000
	s_addc_u32 s21, s21, 0
	s_mov_b32 m0, s29
	s_nop 0
	global_load_lds_dwordx4 v134, s[20:21]
	s_mov_b32 m0, s30
	s_nop 0
	global_load_lds_dwordx4 v130, s[20:21]
	s_waitcnt vmcnt(10)
	s_setprio 1
	s_barrier
	v_mfma_f32_16x16x32_bf16 v[52:55], v[202:205], v[166:169], 0
	v_mfma_f32_16x16x32_bf16 v[48:51], v[210:213], v[166:169], 0
	v_mfma_f32_16x16x32_bf16 v[36:39], v[202:205], v[174:177], 0
	v_mfma_f32_16x16x32_bf16 v[32:35], v[210:213], v[174:177], 0
	v_mfma_f32_16x16x32_bf16 v[20:23], v[202:205], v[182:185], 0
	v_mfma_f32_16x16x32_bf16 v[16:19], v[210:213], v[182:185], 0
	v_mfma_f32_16x16x32_bf16 v[4:7], v[202:205], v[190:193], 0
	v_mfma_f32_16x16x32_bf16 v[0:3], v[210:213], v[190:193], 0
	v_mfma_f32_16x16x32_bf16 v[52:55], v[206:209], v[170:173], v[52:55]
	v_mfma_f32_16x16x32_bf16 v[48:51], v[214:217], v[170:173], v[48:51]
	v_mfma_f32_16x16x32_bf16 v[36:39], v[206:209], v[178:181], v[36:39]
	v_mfma_f32_16x16x32_bf16 v[32:35], v[214:217], v[178:181], v[32:35]
	v_mfma_f32_16x16x32_bf16 v[20:23], v[206:209], v[186:189], v[20:23]
	v_mfma_f32_16x16x32_bf16 v[16:19], v[214:217], v[186:189], v[16:19]
	v_mfma_f32_16x16x32_bf16 v[4:7], v[206:209], v[194:197], v[4:7]
	v_mfma_f32_16x16x32_bf16 v[0:3], v[214:217], v[194:197], v[0:3]
	s_setprio 0
	s_add_i32 s47, 0, 0x18000
	v_add_u32_e32 v162, s47, v146
	s_barrier
	ds_read_b128 v[150:153], v162
	ds_read_b128 v[154:157], v162 offset:1024
	ds_read_b128 v[158:161], v162 offset:2048
	ds_read_b128 v[162:165], v162 offset:3072
	ds_read_b128 v[166:169], v148 offset:32768
	ds_read_b128 v[170:173], v148 offset:33792
	ds_read_b128 v[174:177], v148 offset:34816
	ds_read_b128 v[178:181], v148 offset:35840
	ds_read_b128 v[182:185], v148 offset:36864
	ds_read_b128 v[186:189], v148 offset:37888
	ds_read_b128 v[190:193], v148 offset:38912
	ds_read_b128 v[194:197], v148 offset:39936
	s_waitcnt lgkmcnt(8)
	s_waitcnt vmcnt(8)
	s_setprio 1
	s_barrier
	s_waitcnt lgkmcnt(0)
	s_waitcnt lgkmcnt(0)
	v_mfma_f32_16x16x32_bf16 v[124:127], v[150:153], v[166:169], v[124:127]
	v_mfma_f32_16x16x32_bf16 v[116:119], v[158:161], v[166:169], v[116:119]
	v_mfma_f32_16x16x32_bf16 v[108:111], v[150:153], v[174:177], v[108:111]
	v_mfma_f32_16x16x32_bf16 v[100:103], v[158:161], v[174:177], v[100:103]
	v_mfma_f32_16x16x32_bf16 v[92:95], v[150:153], v[182:185], v[92:95]
	v_mfma_f32_16x16x32_bf16 v[84:87], v[158:161], v[182:185], v[84:87]
	v_mfma_f32_16x16x32_bf16 v[76:79], v[150:153], v[190:193], v[76:79]
	v_mfma_f32_16x16x32_bf16 v[68:71], v[158:161], v[190:193], v[68:71]
	v_mfma_f32_16x16x32_bf16 v[124:127], v[154:157], v[170:173], v[124:127]
	v_mfma_f32_16x16x32_bf16 v[116:119], v[162:165], v[170:173], v[116:119]
	v_mfma_f32_16x16x32_bf16 v[108:111], v[154:157], v[178:181], v[108:111]
	v_mfma_f32_16x16x32_bf16 v[100:103], v[162:165], v[178:181], v[100:103]
	v_mfma_f32_16x16x32_bf16 v[92:95], v[154:157], v[186:189], v[92:95]
	v_mfma_f32_16x16x32_bf16 v[84:87], v[162:165], v[186:189], v[84:87]
	v_mfma_f32_16x16x32_bf16 v[76:79], v[154:157], v[194:197], v[76:79]
	v_mfma_f32_16x16x32_bf16 v[68:71], v[162:165], v[194:197], v[68:71]
	s_setprio 0
	s_barrier
	s_add_i32 s20, 0, 0x1c000
	s_add_i32 s21, s47, s25
	v_add_u32_e32 v214, s20, v146
	s_add_u32 s0, s18, 0x80
	s_addc_u32 s1, s19, 0
	s_mov_b32 m0, s21
	ds_read_b128 v[202:205], v214
	ds_read_b128 v[206:209], v214 offset:1024
	ds_read_b128 v[210:213], v214 offset:2048
	ds_read_b128 v[214:217], v214 offset:3072
	global_load_lds_dwordx4 v132, s[0:1]
	s_add_i32 m0, s21, 0x2000
	s_nop 0
	global_load_lds_dwordx4 v128, s[0:1]
	s_waitcnt vmcnt(8)
	s_setprio 1
	s_barrier
	s_waitcnt lgkmcnt(0)
	s_waitcnt lgkmcnt(0)
	v_mfma_f32_16x16x32_bf16 v[120:123], v[202:205], v[166:169], v[120:123]
	v_mfma_f32_16x16x32_bf16 v[112:115], v[210:213], v[166:169], v[112:115]
	v_mfma_f32_16x16x32_bf16 v[104:107], v[202:205], v[174:177], v[104:107]
	v_mfma_f32_16x16x32_bf16 v[96:99], v[210:213], v[174:177], v[96:99]
	v_mfma_f32_16x16x32_bf16 v[88:91], v[202:205], v[182:185], v[88:91]
	v_mfma_f32_16x16x32_bf16 v[80:83], v[210:213], v[182:185], v[80:83]
	v_mfma_f32_16x16x32_bf16 v[72:75], v[202:205], v[190:193], v[72:75]
	v_mfma_f32_16x16x32_bf16 v[64:67], v[210:213], v[190:193], v[64:67]
	v_mfma_f32_16x16x32_bf16 v[120:123], v[206:209], v[170:173], v[120:123]
	v_mfma_f32_16x16x32_bf16 v[112:115], v[214:217], v[170:173], v[112:115]
	v_mfma_f32_16x16x32_bf16 v[104:107], v[206:209], v[178:181], v[104:107]
	v_mfma_f32_16x16x32_bf16 v[96:99], v[214:217], v[178:181], v[96:99]
	v_mfma_f32_16x16x32_bf16 v[88:91], v[206:209], v[186:189], v[88:91]
	v_mfma_f32_16x16x32_bf16 v[80:83], v[214:217], v[186:189], v[80:83]
	v_mfma_f32_16x16x32_bf16 v[72:75], v[206:209], v[194:197], v[72:75]
	v_mfma_f32_16x16x32_bf16 v[64:67], v[214:217], v[194:197], v[64:67]
	s_setprio 0
	s_mov_b32 m0, s35
	s_mov_b64 s[0:1], 0x80
	v_lshl_add_u64 v[198:199], v[220:221], 0, s[0:1]
	s_barrier
	ds_read_b128 v[166:169], v148 offset:49152
	ds_read_b128 v[170:173], v148 offset:50176
	ds_read_b128 v[174:177], v148 offset:51200
	ds_read_b128 v[178:181], v148 offset:52224
	ds_read_b128 v[182:185], v148 offset:53248
	ds_read_b128 v[186:189], v148 offset:54272
	ds_read_b128 v[190:193], v148 offset:55296
	ds_read_b128 v[194:197], v148 offset:56320
	global_load_lds_dwordx4 v[198:199], off
	v_lshl_add_u64 v[198:199], v[222:223], 0, s[0:1]
	s_mov_b32 m0, s36
	s_nop 0
	global_load_lds_dwordx4 v[198:199], off
	s_setprio 1
	s_barrier
; #define PG8_STAGE(bufoff, gbase, voff) do { _Pragma("unroll") for (int _i = 0; _i < 2; ++_i) \
;         __builtin_amdgcn_global_load_lds((const unsigned*)((const char*)(gbase) + (voff)[_i]), (LAS unsigned*)(lds + (bufoff) + ldsw + _i * 8192), 16, 0, 0); } while (0)
; #define PG8_LDA(dst, b, h) do { _Pragma("unroll") for (int m = 0; m < 4; ++m) _Pragma("unroll") for (int k = 0; k < 2; ++k) dst[m][k] = *(const LAS bf16x8*)(lds + PG8_SA(b, h) + aoff + m * 2048 + k * 1024); } while (0)
; #define PG8_LDB(dst, b, h) do { _Pragma("unroll") for (int n = 0; n < 2; ++n) _Pragma("unroll") for (int k = 0; k < 2; ++k) dst[n][k] = *(const LAS bf16x8*)(lds + PG8_SB(b, h) + boff + n * 2048 + k * 1024); } while (0)
; #define PG8_MMA(ai, bj, At, Bt) do { __builtin_amdgcn_s_setprio(1); _Pragma("unroll") for (int m = 0; m < 4; ++m) _Pragma("unroll") for (int n = 0; n < 2; ++n) _Pragma("unroll") for (int k = 0; k < 2; ++k) \
;         acc[ai][bj][m][n] = __builtin_amdgcn_mfma_f32_16x16x32_bf16(Bt[n][k], At[m][k], acc[ai][bj][m][n], 0, 0, 0); __builtin_amdgcn_s_setprio(0); } while (0)
; #define PG8_WAIT_V(n) asm volatile("s_waitcnt vmcnt(" #n ")" ::: "memory")
; #define PG8_WAIT_L(n) asm volatile("s_waitcnt lgkmcnt(" #n ")" ::: "memory")
; #define PG8_BAR __builtin_amdgcn_s_barrier()
; #define PG8_SCHED __builtin_amdgcn_sched_barrier(0)
; template <class Epi, class Sched>
; __device__ __forceinline__ void gemm_phase(LAS unsigned char* lds, const Gemm g, const Sched& S, const Epi& E) {
;     ...
;             PG8_LDB(B0, 0, 0); PG8_SCHED; PG8_LDA(At, 0, 0); PG8_STAGE(PG8_SA(1, 1), a1 + hstep, voffA);
;             PG8_WAIT_L(8); PG8_BAR; PG8_WAIT_L(0); PG8_MMA(0, 0, At, B0); PG8_BAR; PG8_SCHED;
;             PG8_LDB(B1, 0, 1); PG8_STAGE(PG8_SB(0, 0), b2, voffB);
;             PG8_BAR; PG8_WAIT_L(0); PG8_MMA(0, 1, At, B1); PG8_BAR;
;     ...
;             PG8_BAR; PG8_WAIT_L(0); PG8_MMA(1, 0, At, B0); PG8_BAR; PG8_SCHED;
;             PG8_STAGE(PG8_SB(1, 1), b3 + hstep, voffB);
;             PG8_WAIT_V(6); PG8_BAR; PG8_MMA(1, 1, At, B1); PG8_BAR;
	s_waitcnt lgkmcnt(0)
	s_waitcnt lgkmcnt(0)
	v_mfma_f32_16x16x32_bf16 v[60:63], v[150:153], v[166:169], v[60:63]
	v_mfma_f32_16x16x32_bf16 v[56:59], v[158:161], v[166:169], v[56:59]
	v_mfma_f32_16x16x32_bf16 v[44:47], v[150:153], v[174:177], v[44:47]
	v_mfma_f32_16x16x32_bf16 v[40:43], v[158:161], v[174:177], v[40:43]
	v_mfma_f32_16x16x32_bf16 v[28:31], v[150:153], v[182:185], v[28:31]
	v_mfma_f32_16x16x32_bf16 v[24:27], v[158:161], v[182:185], v[24:27]
	v_mfma_f32_16x16x32_bf16 v[12:15], v[150:153], v[190:193], v[12:15]
	v_mfma_f32_16x16x32_bf16 v[8:11], v[158:161], v[190:193], v[8:11]
	v_mfma_f32_16x16x32_bf16 v[60:63], v[154:157], v[170:173], v[60:63]
	v_mfma_f32_16x16x32_bf16 v[56:59], v[162:165], v[170:173], v[56:59]
	v_mfma_f32_16x16x32_bf16 v[44:47], v[154:157], v[178:181], v[44:47]
	v_mfma_f32_16x16x32_bf16 v[40:43], v[162:165], v[178:181], v[40:43]
	v_mfma_f32_16x16x32_bf16 v[28:31], v[154:157], v[186:189], v[28:31]
	v_mfma_f32_16x16x32_bf16 v[24:27], v[162:165], v[186:189], v[24:27]
	v_mfma_f32_16x16x32_bf16 v[12:15], v[154:157], v[194:197], v[12:15]
	v_mfma_f32_16x16x32_bf16 v[8:11], v[162:165], v[194:197], v[8:11]
	s_setprio 0
	s_barrier
	s_add_u32 s18, s18, 0x40080
	s_addc_u32 s19, s19, 0
	s_add_i32 s20, s20, s25
	s_mov_b32 m0, s20
	s_nop 0
	global_load_lds_dwordx4 v132, s[18:19]
	s_add_i32 m0, s20, 0x2000
	s_nop 0
	global_load_lds_dwordx4 v128, s[18:19]
	s_waitcnt vmcnt(8)
	s_setprio 1
	s_barrier
	v_mfma_f32_16x16x32_bf16 v[52:55], v[202:205], v[166:169], v[52:55]
	v_mfma_f32_16x16x32_bf16 v[48:51], v[210:213], v[166:169], v[48:51]
	v_mfma_f32_16x16x32_bf16 v[36:39], v[202:205], v[174:177], v[36:39]
	v_mfma_f32_16x16x32_bf16 v[32:35], v[210:213], v[174:177], v[32:35]
	v_mfma_f32_16x16x32_bf16 v[20:23], v[202:205], v[182:185], v[20:23]
	v_mfma_f32_16x16x32_bf16 v[16:19], v[210:213], v[182:185], v[16:19]
	v_mfma_f32_16x16x32_bf16 v[4:7], v[202:205], v[190:193], v[4:7]
	v_mfma_f32_16x16x32_bf16 v[0:3], v[210:213], v[190:193], v[0:3]
	v_mfma_f32_16x16x32_bf16 v[52:55], v[206:209], v[170:173], v[52:55]
	v_mfma_f32_16x16x32_bf16 v[48:51], v[214:217], v[170:173], v[48:51]
	v_mfma_f32_16x16x32_bf16 v[36:39], v[206:209], v[178:181], v[36:39]
	v_mfma_f32_16x16x32_bf16 v[32:35], v[214:217], v[178:181], v[32:35]
	v_mfma_f32_16x16x32_bf16 v[20:23], v[206:209], v[186:189], v[20:23]
	v_mfma_f32_16x16x32_bf16 v[16:19], v[214:217], v[186:189], v[16:19]
	v_mfma_f32_16x16x32_bf16 v[4:7], v[206:209], v[194:197], v[4:7]
	v_mfma_f32_16x16x32_bf16 v[0:3], v[214:217], v[194:197], v[0:3]
	s_setprio 0
	s_add_i32 s46, s46, 2
	s_add_u32 s16, s16, 0x100
	s_addc_u32 s17, s17, 0
	s_add_u32 s44, s44, 0x100
	s_addc_u32 s45, s45, 0
	s_cmp_gt_u32 s46, 13
	s_barrier
.LBB0_1021:
	ds_read_b128 v[150:153], v147
	ds_read_b128 v[154:157], v147 offset:1024
	ds_read_b128 v[158:161], v147 offset:2048
	ds_read_b128 v[162:165], v147 offset:3072
	s_add_u32 s18, s16, 0xfffc0080
	s_addc_u32 s19, s17, -1
	s_cmp_eq_u32 s46, 12
	s_cselect_b32 s21, s7, s19
	s_cselect_b32 s20, s42, s18
	s_cselect_b32 s19, s5, s45
	s_cselect_b32 s18, s43, s44
	s_add_i32 m0, s15, 0xc000
	ds_read_b128 v[166:169], v148
	ds_read_b128 v[170:173], v148 offset:1024
	ds_read_b128 v[174:177], v148 offset:2048
	ds_read_b128 v[178:181], v148 offset:3072
	ds_read_b128 v[182:185], v148 offset:4096
	ds_read_b128 v[186:189], v148 offset:5120
	ds_read_b128 v[190:193], v148 offset:6144
	ds_read_b128 v[194:197], v148 offset:7168
	global_load_lds_dwordx4 v136, s[16:17]
	s_add_i32 m0, s15, 0xe000
	s_nop 0
	global_load_lds_dwordx4 v138, s[16:17]
	s_waitcnt lgkmcnt(8)
	s_waitcnt vmcnt(8)
	s_setprio 1
	s_barrier
	s_waitcnt lgkmcnt(0)
	s_waitcnt lgkmcnt(0)
	v_mfma_f32_16x16x32_bf16 v[124:127], v[150:153], v[166:169], v[124:127]
	v_mfma_f32_16x16x32_bf16 v[116:119], v[158:161], v[166:169], v[116:119]
	v_mfma_f32_16x16x32_bf16 v[108:111], v[150:153], v[174:177], v[108:111]
	v_mfma_f32_16x16x32_bf16 v[100:103], v[158:161], v[174:177], v[100:103]
	v_mfma_f32_16x16x32_bf16 v[92:95], v[150:153], v[182:185], v[92:95]
	v_mfma_f32_16x16x32_bf16 v[84:87], v[158:161], v[182:185], v[84:87]
	v_mfma_f32_16x16x32_bf16 v[76:79], v[150:153], v[190:193], v[76:79]
	v_mfma_f32_16x16x32_bf16 v[68:71], v[158:161], v[190:193], v[68:71]
	v_mfma_f32_16x16x32_bf16 v[124:127], v[154:157], v[170:173], v[124:127]
	v_mfma_f32_16x16x32_bf16 v[116:119], v[162:165], v[170:173], v[116:119]
	v_mfma_f32_16x16x32_bf16 v[108:111], v[154:157], v[178:181], v[108:111]
	v_mfma_f32_16x16x32_bf16 v[100:103], v[162:165], v[178:181], v[100:103]
	v_mfma_f32_16x16x32_bf16 v[92:95], v[154:157], v[186:189], v[92:95]
	v_mfma_f32_16x16x32_bf16 v[84:87], v[162:165], v[186:189], v[84:87]
	v_mfma_f32_16x16x32_bf16 v[76:79], v[154:157], v[194:197], v[76:79]
	v_mfma_f32_16x16x32_bf16 v[68:71], v[162:165], v[194:197], v[68:71]
	s_setprio 0
	s_barrier
	s_add_i32 s47, s38, s25
	s_mov_b32 m0, s47
	ds_read_b128 v[202:205], v149
	ds_read_b128 v[206:209], v149 offset:1024
	ds_read_b128 v[210:213], v149 offset:2048
	ds_read_b128 v[214:217], v149 offset:3072
	global_load_lds_dwordx4 v132, s[18:19]
	s_add_i32 m0, s47, 0x2000
	s_nop 0
	global_load_lds_dwordx4 v128, s[18:19]
	s_waitcnt vmcnt(8)
	s_setprio 1
	s_barrier
; #define PG8_STAGE(bufoff, gbase, voff) do { _Pragma("unroll") for (int _i = 0; _i < 2; ++_i) \
;         __builtin_amdgcn_global_load_lds((const unsigned*)((const char*)(gbase) + (voff)[_i]), (LAS unsigned*)(lds + (bufoff) + ldsw + _i * 8192), 16, 0, 0); } while (0)
; #define PG8_LDA(dst, b, h) do { _Pragma("unroll") for (int m = 0; m < 4; ++m) _Pragma("unroll") for (int k = 0; k < 2; ++k) dst[m][k] = *(const LAS bf16x8*)(lds + PG8_SA(b, h) + aoff + m * 2048 + k * 1024); } while (0)
; #define PG8_LDB(dst, b, h) do { _Pragma("unroll") for (int n = 0; n < 2; ++n) _Pragma("unroll") for (int k = 0; k < 2; ++k) dst[n][k] = *(const LAS bf16x8*)(lds + PG8_SB(b, h) + boff + n * 2048 + k * 1024); } while (0)
; #define PG8_MMA(ai, bj, At, Bt) do { __builtin_amdgcn_s_setprio(1); _Pragma("unroll") for (int m = 0; m < 4; ++m) _Pragma("unroll") for (int n = 0; n < 2; ++n) _Pragma("unroll") for (int k = 0; k < 2; ++k) \
;         acc[ai][bj][m][n] = __builtin_amdgcn_mfma_f32_16x16x32_bf16(Bt[n][k], At[m][k], acc[ai][bj][m][n], 0, 0, 0); __builtin_amdgcn_s_setprio(0); } while (0)
; #define PG8_WAIT_V(n) asm volatile("s_waitcnt vmcnt(" #n ")" ::: "memory")
; #define PG8_WAIT_L(n) asm volatile("s_waitcnt lgkmcnt(" #n ")" ::: "memory")
; #define PG8_BAR __builtin_amdgcn_s_barrier()
; #define PG8_SCHED __builtin_amdgcn_sched_barrier(0)
; template <class Epi, class Sched>
; __device__ __forceinline__ void gemm_phase(LAS unsigned char* lds, const Gemm g, const Sched& S, const Epi& E) {
;     ...
;             PG8_BAR; PG8_WAIT_L(0); PG8_MMA(0, 1, At, B1); PG8_BAR;
;             PG8_LDA(At, 0, 1); PG8_STAGE(PG8_SA(0, 0), a2, voffA);
;             PG8_BAR; PG8_WAIT_L(0); PG8_MMA(1, 0, At, B0); PG8_BAR; PG8_SCHED;
;             PG8_STAGE(PG8_SB(0, 1), b2 + hstep, voffB);
;             PG8_WAIT_V(6); PG8_BAR; PG8_MMA(1, 1, At, B1); PG8_BAR;
;             PG8_LDB(B0, 1, 0); PG8_SCHED; PG8_LDA(At, 1, 0); PG8_STAGE(PG8_SA(0, 1), a2 + hstep, voffA);
;             PG8_WAIT_L(8); PG8_BAR; PG8_WAIT_L(0); PG8_MMA(0, 0, At, B0); PG8_BAR; PG8_SCHED;
	s_waitcnt lgkmcnt(0)
	s_waitcnt lgkmcnt(0)
	v_mfma_f32_16x16x32_bf16 v[120:123], v[202:205], v[166:169], v[120:123]
	v_mfma_f32_16x16x32_bf16 v[112:115], v[210:213], v[166:169], v[112:115]
	v_mfma_f32_16x16x32_bf16 v[104:107], v[202:205], v[174:177], v[104:107]
	v_mfma_f32_16x16x32_bf16 v[96:99], v[210:213], v[174:177], v[96:99]
	v_mfma_f32_16x16x32_bf16 v[88:91], v[202:205], v[182:185], v[88:91]
	v_mfma_f32_16x16x32_bf16 v[80:83], v[210:213], v[182:185], v[80:83]
	v_mfma_f32_16x16x32_bf16 v[72:75], v[202:205], v[190:193], v[72:75]
	v_mfma_f32_16x16x32_bf16 v[64:67], v[210:213], v[190:193], v[64:67]
	v_mfma_f32_16x16x32_bf16 v[120:123], v[206:209], v[170:173], v[120:123]
	v_mfma_f32_16x16x32_bf16 v[112:115], v[214:217], v[170:173], v[112:115]
	v_mfma_f32_16x16x32_bf16 v[104:107], v[206:209], v[178:181], v[104:107]
	v_mfma_f32_16x16x32_bf16 v[96:99], v[214:217], v[178:181], v[96:99]
	v_mfma_f32_16x16x32_bf16 v[88:91], v[206:209], v[186:189], v[88:91]
	v_mfma_f32_16x16x32_bf16 v[80:83], v[214:217], v[186:189], v[80:83]
	v_mfma_f32_16x16x32_bf16 v[72:75], v[206:209], v[194:197], v[72:75]
	v_mfma_f32_16x16x32_bf16 v[64:67], v[214:217], v[194:197], v[64:67]
	s_setprio 0
	s_mov_b32 m0, s15
	v_lshl_add_u64 v[220:221], s[20:21], 0, v[134:135]
	s_barrier
	ds_read_b128 v[166:169], v148 offset:16384
	ds_read_b128 v[170:173], v148 offset:17408
	ds_read_b128 v[174:177], v148 offset:18432
	ds_read_b128 v[178:181], v148 offset:19456
	ds_read_b128 v[182:185], v148 offset:20480
	ds_read_b128 v[186:189], v148 offset:21504
	ds_read_b128 v[190:193], v148 offset:22528
	ds_read_b128 v[194:197], v148 offset:23552
	global_load_lds_dwordx4 v134, s[20:21]
	v_lshl_add_u64 v[222:223], s[20:21], 0, v[130:131]
	s_mov_b32 m0, s28
	s_nop 0
	global_load_lds_dwordx4 v130, s[20:21]
	s_setprio 1
	s_barrier
	s_waitcnt lgkmcnt(0)
	s_waitcnt lgkmcnt(0)
	v_mfma_f32_16x16x32_bf16 v[60:63], v[150:153], v[166:169], v[60:63]
	v_mfma_f32_16x16x32_bf16 v[56:59], v[158:161], v[166:169], v[56:59]
	v_mfma_f32_16x16x32_bf16 v[44:47], v[150:153], v[174:177], v[44:47]
	v_mfma_f32_16x16x32_bf16 v[40:43], v[158:161], v[174:177], v[40:43]
	v_mfma_f32_16x16x32_bf16 v[28:31], v[150:153], v[182:185], v[28:31]
	v_mfma_f32_16x16x32_bf16 v[24:27], v[158:161], v[182:185], v[24:27]
	v_mfma_f32_16x16x32_bf16 v[12:15], v[150:153], v[190:193], v[12:15]
	v_mfma_f32_16x16x32_bf16 v[8:11], v[158:161], v[190:193], v[8:11]
	v_mfma_f32_16x16x32_bf16 v[60:63], v[154:157], v[170:173], v[60:63]
	v_mfma_f32_16x16x32_bf16 v[56:59], v[162:165], v[170:173], v[56:59]
	v_mfma_f32_16x16x32_bf16 v[44:47], v[154:157], v[178:181], v[44:47]
	v_mfma_f32_16x16x32_bf16 v[40:43], v[162:165], v[178:181], v[40:43]
	v_mfma_f32_16x16x32_bf16 v[28:31], v[154:157], v[186:189], v[28:31]
	v_mfma_f32_16x16x32_bf16 v[24:27], v[162:165], v[186:189], v[24:27]
	v_mfma_f32_16x16x32_bf16 v[12:15], v[154:157], v[194:197], v[12:15]
	v_mfma_f32_16x16x32_bf16 v[8:11], v[162:165], v[194:197], v[8:11]
	s_setprio 0
	s_barrier
	s_add_u32 s48, s18, 0x40000
	s_addc_u32 s49, s19, 0
	s_add_i32 s47, s39, s25
	s_mov_b32 m0, s47
	s_nop 0
	global_load_lds_dwordx4 v132, s[48:49]
	s_add_i32 m0, s47, 0x2000
	s_nop 0
	global_load_lds_dwordx4 v128, s[48:49]
	s_add_u32 s20, s20, 0x40000
	s_addc_u32 s21, s21, 0
	s_mov_b32 m0, s29
	s_nop 0
	global_load_lds_dwordx4 v134, s[20:21]
	s_mov_b32 m0, s30
	s_nop 0
	global_load_lds_dwordx4 v130, s[20:21]
	s_waitcnt vmcnt(10)
	s_setprio 1
	s_barrier
	v_mfma_f32_16x16x32_bf16 v[52:55], v[202:205], v[166:169], v[52:55]
	v_mfma_f32_16x16x32_bf16 v[48:51], v[210:213], v[166:169], v[48:51]
	v_mfma_f32_16x16x32_bf16 v[36:39], v[202:205], v[174:177], v[36:39]
	v_mfma_f32_16x16x32_bf16 v[32:35], v[210:213], v[174:177], v[32:35]
	v_mfma_f32_16x16x32_bf16 v[20:23], v[202:205], v[182:185], v[20:23]
	v_mfma_f32_16x16x32_bf16 v[16:19], v[210:213], v[182:185], v[16:19]
	v_mfma_f32_16x16x32_bf16 v[4:7], v[202:205], v[190:193], v[4:7]
	v_mfma_f32_16x16x32_bf16 v[0:3], v[210:213], v[190:193], v[0:3]
	v_mfma_f32_16x16x32_bf16 v[52:55], v[206:209], v[170:173], v[52:55]
	v_mfma_f32_16x16x32_bf16 v[48:51], v[214:217], v[170:173], v[48:51]
	v_mfma_f32_16x16x32_bf16 v[36:39], v[206:209], v[178:181], v[36:39]
	v_mfma_f32_16x16x32_bf16 v[32:35], v[214:217], v[178:181], v[32:35]
	v_mfma_f32_16x16x32_bf16 v[20:23], v[206:209], v[186:189], v[20:23]
	v_mfma_f32_16x16x32_bf16 v[16:19], v[214:217], v[186:189], v[16:19]
	v_mfma_f32_16x16x32_bf16 v[4:7], v[206:209], v[194:197], v[4:7]
	v_mfma_f32_16x16x32_bf16 v[0:3], v[214:217], v[194:197], v[0:3]
	s_setprio 0
	s_add_i32 s47, 0, 0x18000
	v_add_u32_e32 v162, s47, v146
	s_barrier
	ds_read_b128 v[150:153], v162
	ds_read_b128 v[154:157], v162 offset:1024
	ds_read_b128 v[158:161], v162 offset:2048
	ds_read_b128 v[162:165], v162 offset:3072
	ds_read_b128 v[166:169], v148 offset:32768
	ds_read_b128 v[170:173], v148 offset:33792
	ds_read_b128 v[174:177], v148 offset:34816
	ds_read_b128 v[178:181], v148 offset:35840
	ds_read_b128 v[182:185], v148 offset:36864
	ds_read_b128 v[186:189], v148 offset:37888
	ds_read_b128 v[190:193], v148 offset:38912
	ds_read_b128 v[194:197], v148 offset:39936
	s_waitcnt lgkmcnt(8)
	s_waitcnt vmcnt(8)
	s_setprio 1
	s_barrier
; #define PG8_STAGE(bufoff, gbase, voff) do { _Pragma("unroll") for (int _i = 0; _i < 2; ++_i) \
;         __builtin_amdgcn_global_load_lds((const unsigned*)((const char*)(gbase) + (voff)[_i]), (LAS unsigned*)(lds + (bufoff) + ldsw + _i * 8192), 16, 0, 0); } while (0)
; #define PG8_LDA(dst, b, h) do { _Pragma("unroll") for (int m = 0; m < 4; ++m) _Pragma("unroll") for (int k = 0; k < 2; ++k) dst[m][k] = *(const LAS bf16x8*)(lds + PG8_SA(b, h) + aoff + m * 2048 + k * 1024); } while (0)
; #define PG8_LDB(dst, b, h) do { _Pragma("unroll") for (int n = 0; n < 2; ++n) _Pragma("unroll") for (int k = 0; k < 2; ++k) dst[n][k] = *(const LAS bf16x8*)(lds + PG8_SB(b, h) + boff + n * 2048 + k * 1024); } while (0)
; #define PG8_MMA(ai, bj, At, Bt) do { __builtin_amdgcn_s_setprio(1); _Pragma("unroll") for (int m = 0; m < 4; ++m) _Pragma("unroll") for (int n = 0; n < 2; ++n) _Pragma("unroll") for (int k = 0; k < 2; ++k) \
;         acc[ai][bj][m][n] = __builtin_amdgcn_mfma_f32_16x16x32_bf16(Bt[n][k], At[m][k], acc[ai][bj][m][n], 0, 0, 0); __builtin_amdgcn_s_setprio(0); } while (0)
; #define PG8_WAIT_V(n) asm volatile("s_waitcnt vmcnt(" #n ")" ::: "memory")
; #define PG8_WAIT_L(n) asm volatile("s_waitcnt lgkmcnt(" #n ")" ::: "memory")
; #define PG8_BAR __builtin_amdgcn_s_barrier()
; #define PG8_SCHED __builtin_amdgcn_sched_barrier(0)
; template <class Epi, class Sched>
; __device__ __forceinline__ void gemm_phase(LAS unsigned char* lds, const Gemm g, const Sched& S, const Epi& E) {
;     ...
;             PG8_WAIT_L(8); PG8_BAR; PG8_WAIT_L(0); PG8_MMA(0, 0, At, B0); PG8_BAR; PG8_SCHED;
;             PG8_LDB(B1, 1, 1); PG8_STAGE(PG8_SB(1, 0), b3, voffB);
;             PG8_BAR; PG8_WAIT_L(0); PG8_MMA(0, 1, At, B1); PG8_BAR;
;             PG8_LDA(At, 1, 1); PG8_STAGE(PG8_SA(1, 0), a3, voffA);
;             PG8_BAR; PG8_WAIT_L(0); PG8_MMA(1, 0, At, B0); PG8_BAR; PG8_SCHED;
;             PG8_STAGE(PG8_SB(1, 1), b3 + hstep, voffB);
;             PG8_WAIT_V(6); PG8_BAR; PG8_MMA(1, 1, At, B1); PG8_BAR;
	s_waitcnt lgkmcnt(0)
	s_waitcnt lgkmcnt(0)
	v_mfma_f32_16x16x32_bf16 v[124:127], v[150:153], v[166:169], v[124:127]
	v_mfma_f32_16x16x32_bf16 v[116:119], v[158:161], v[166:169], v[116:119]
	v_mfma_f32_16x16x32_bf16 v[108:111], v[150:153], v[174:177], v[108:111]
	v_mfma_f32_16x16x32_bf16 v[100:103], v[158:161], v[174:177], v[100:103]
	v_mfma_f32_16x16x32_bf16 v[92:95], v[150:153], v[182:185], v[92:95]
	v_mfma_f32_16x16x32_bf16 v[84:87], v[158:161], v[182:185], v[84:87]
	v_mfma_f32_16x16x32_bf16 v[76:79], v[150:153], v[190:193], v[76:79]
	v_mfma_f32_16x16x32_bf16 v[68:71], v[158:161], v[190:193], v[68:71]
	v_mfma_f32_16x16x32_bf16 v[124:127], v[154:157], v[170:173], v[124:127]
	v_mfma_f32_16x16x32_bf16 v[116:119], v[162:165], v[170:173], v[116:119]
	v_mfma_f32_16x16x32_bf16 v[108:111], v[154:157], v[178:181], v[108:111]
	v_mfma_f32_16x16x32_bf16 v[100:103], v[162:165], v[178:181], v[100:103]
	v_mfma_f32_16x16x32_bf16 v[92:95], v[154:157], v[186:189], v[92:95]
	v_mfma_f32_16x16x32_bf16 v[84:87], v[162:165], v[186:189], v[84:87]
	v_mfma_f32_16x16x32_bf16 v[76:79], v[154:157], v[194:197], v[76:79]
	v_mfma_f32_16x16x32_bf16 v[68:71], v[162:165], v[194:197], v[68:71]
	s_setprio 0
	s_barrier
	s_add_i32 s20, 0, 0x1c000
	s_add_i32 s21, s47, s25
	v_add_u32_e32 v214, s20, v146
	s_add_u32 s0, s18, 0x80
	s_addc_u32 s1, s19, 0
	s_mov_b32 m0, s21
	ds_read_b128 v[202:205], v214
	ds_read_b128 v[206:209], v214 offset:1024
	ds_read_b128 v[210:213], v214 offset:2048
	ds_read_b128 v[214:217], v214 offset:3072
	global_load_lds_dwordx4 v132, s[0:1]
	s_add_i32 m0, s21, 0x2000
	s_nop 0
	global_load_lds_dwordx4 v128, s[0:1]
	s_waitcnt vmcnt(8)
	s_setprio 1
	s_barrier
	s_waitcnt lgkmcnt(0)
	s_waitcnt lgkmcnt(0)
	v_mfma_f32_16x16x32_bf16 v[120:123], v[202:205], v[166:169], v[120:123]
	v_mfma_f32_16x16x32_bf16 v[112:115], v[210:213], v[166:169], v[112:115]
	v_mfma_f32_16x16x32_bf16 v[104:107], v[202:205], v[174:177], v[104:107]
	v_mfma_f32_16x16x32_bf16 v[96:99], v[210:213], v[174:177], v[96:99]
	v_mfma_f32_16x16x32_bf16 v[88:91], v[202:205], v[182:185], v[88:91]
	v_mfma_f32_16x16x32_bf16 v[80:83], v[210:213], v[182:185], v[80:83]
	v_mfma_f32_16x16x32_bf16 v[72:75], v[202:205], v[190:193], v[72:75]
	v_mfma_f32_16x16x32_bf16 v[64:67], v[210:213], v[190:193], v[64:67]
	v_mfma_f32_16x16x32_bf16 v[120:123], v[206:209], v[170:173], v[120:123]
	v_mfma_f32_16x16x32_bf16 v[112:115], v[214:217], v[170:173], v[112:115]
	v_mfma_f32_16x16x32_bf16 v[104:107], v[206:209], v[178:181], v[104:107]
	v_mfma_f32_16x16x32_bf16 v[96:99], v[214:217], v[178:181], v[96:99]
	v_mfma_f32_16x16x32_bf16 v[88:91], v[206:209], v[186:189], v[88:91]
	v_mfma_f32_16x16x32_bf16 v[80:83], v[214:217], v[186:189], v[80:83]
	v_mfma_f32_16x16x32_bf16 v[72:75], v[206:209], v[194:197], v[72:75]
	v_mfma_f32_16x16x32_bf16 v[64:67], v[214:217], v[194:197], v[64:67]
	s_setprio 0
	s_mov_b32 m0, s35
	s_mov_b64 s[0:1], 0x80
	v_lshl_add_u64 v[198:199], v[220:221], 0, s[0:1]
	s_barrier
	ds_read_b128 v[166:169], v148 offset:49152
	ds_read_b128 v[170:173], v148 offset:50176
	ds_read_b128 v[174:177], v148 offset:51200
	ds_read_b128 v[178:181], v148 offset:52224
	ds_read_b128 v[182:185], v148 offset:53248
	ds_read_b128 v[186:189], v148 offset:54272
	ds_read_b128 v[190:193], v148 offset:55296
	ds_read_b128 v[194:197], v148 offset:56320
	global_load_lds_dwordx4 v[198:199], off
	v_lshl_add_u64 v[198:199], v[222:223], 0, s[0:1]
	s_mov_b32 m0, s36
	s_nop 0
	global_load_lds_dwordx4 v[198:199], off
	s_setprio 1
	s_barrier
	s_waitcnt lgkmcnt(0)
	s_waitcnt lgkmcnt(0)
	v_mfma_f32_16x16x32_bf16 v[60:63], v[150:153], v[166:169], v[60:63]
	v_mfma_f32_16x16x32_bf16 v[56:59], v[158:161], v[166:169], v[56:59]
	v_mfma_f32_16x16x32_bf16 v[44:47], v[150:153], v[174:177], v[44:47]
	v_mfma_f32_16x16x32_bf16 v[40:43], v[158:161], v[174:177], v[40:43]
	v_mfma_f32_16x16x32_bf16 v[28:31], v[150:153], v[182:185], v[28:31]
	v_mfma_f32_16x16x32_bf16 v[24:27], v[158:161], v[182:185], v[24:27]
	v_mfma_f32_16x16x32_bf16 v[12:15], v[150:153], v[190:193], v[12:15]
	v_mfma_f32_16x16x32_bf16 v[8:11], v[158:161], v[190:193], v[8:11]
	v_mfma_f32_16x16x32_bf16 v[60:63], v[154:157], v[170:173], v[60:63]
	v_mfma_f32_16x16x32_bf16 v[56:59], v[162:165], v[170:173], v[56:59]
	v_mfma_f32_16x16x32_bf16 v[44:47], v[154:157], v[178:181], v[44:47]
	v_mfma_f32_16x16x32_bf16 v[40:43], v[162:165], v[178:181], v[40:43]
	v_mfma_f32_16x16x32_bf16 v[28:31], v[154:157], v[186:189], v[28:31]
	v_mfma_f32_16x16x32_bf16 v[24:27], v[162:165], v[186:189], v[24:27]
	v_mfma_f32_16x16x32_bf16 v[12:15], v[154:157], v[194:197], v[12:15]
	v_mfma_f32_16x16x32_bf16 v[8:11], v[162:165], v[194:197], v[8:11]
	s_setprio 0
	s_barrier
	s_add_u32 s18, s18, 0x40080
	s_addc_u32 s19, s19, 0
	s_add_i32 s20, s20, s25
	s_mov_b32 m0, s20
	s_nop 0
	global_load_lds_dwordx4 v132, s[18:19]
	s_add_i32 m0, s20, 0x2000
	s_nop 0
	global_load_lds_dwordx4 v128, s[18:19]
	s_waitcnt vmcnt(8)
	s_setprio 1
	s_barrier
	v_mfma_f32_16x16x32_bf16 v[52:55], v[202:205], v[166:169], v[52:55]
	v_mfma_f32_16x16x32_bf16 v[48:51], v[210:213], v[166:169], v[48:51]
	v_mfma_f32_16x16x32_bf16 v[36:39], v[202:205], v[174:177], v[36:39]
	v_mfma_f32_16x16x32_bf16 v[32:35], v[210:213], v[174:177], v[32:35]
	v_mfma_f32_16x16x32_bf16 v[20:23], v[202:205], v[182:185], v[20:23]
	v_mfma_f32_16x16x32_bf16 v[16:19], v[210:213], v[182:185], v[16:19]
	v_mfma_f32_16x16x32_bf16 v[4:7], v[202:205], v[190:193], v[4:7]
	v_mfma_f32_16x16x32_bf16 v[0:3], v[210:213], v[190:193], v[0:3]
	v_mfma_f32_16x16x32_bf16 v[52:55], v[206:209], v[170:173], v[52:55]
	v_mfma_f32_16x16x32_bf16 v[48:51], v[214:217], v[170:173], v[48:51]
	v_mfma_f32_16x16x32_bf16 v[36:39], v[206:209], v[178:181], v[36:39]
	v_mfma_f32_16x16x32_bf16 v[32:35], v[214:217], v[178:181], v[32:35]
	v_mfma_f32_16x16x32_bf16 v[20:23], v[206:209], v[186:189], v[20:23]
	v_mfma_f32_16x16x32_bf16 v[16:19], v[214:217], v[186:189], v[16:19]
	v_mfma_f32_16x16x32_bf16 v[4:7], v[206:209], v[194:197], v[4:7]
	v_mfma_f32_16x16x32_bf16 v[0:3], v[214:217], v[194:197], v[0:3]
	s_setprio 0
	s_add_i32 s46, s46, 2
	s_add_u32 s16, s16, 0x100
	s_addc_u32 s17, s17, 0
	s_add_u32 s44, s44, 0x100
	s_addc_u32 s45, s45, 0
	s_cmp_gt_u32 s46, 13
	s_cbranch_scc1 .Lconc_last_g11
	s_barrier
	s_branch .LBB0_1021

; #define PG8_STAGE(bufoff, gbase, voff) do { _Pragma("unroll") for (int _i = 0; _i < 2; ++_i) \
;         __builtin_amdgcn_global_load_lds((const unsigned*)((const char*)(gbase) + (voff)[_i]), (LAS unsigned*)(lds + (bufoff) + ldsw + _i * 8192), 16, 0, 0); } while (0)
; #define PG8_LDA(dst, b, h) do { _Pragma("unroll") for (int m = 0; m < 4; ++m) _Pragma("unroll") for (int k = 0; k < 2; ++k) dst[m][k] = *(const LAS bf16x8*)(lds + PG8_SA(b, h) + aoff + m * 2048 + k * 1024); } while (0)
; #define PG8_LDB(dst, b, h) do { _Pragma("unroll") for (int n = 0; n < 2; ++n) _Pragma("unroll") for (int k = 0; k < 2; ++k) dst[n][k] = *(const LAS bf16x8*)(lds + PG8_SB(b, h) + boff + n * 2048 + k * 1024); } while (0)
; #define PG8_WAIT_V(n) asm volatile("s_waitcnt vmcnt(" #n ")" ::: "memory")
; #define PG8_WAIT_L(n) asm volatile("s_waitcnt lgkmcnt(" #n ")" ::: "memory")
; #define PG8_BAR __builtin_amdgcn_s_barrier()
; #define PG8_SCHED __builtin_amdgcn_sched_barrier(0)
; template <class Epi, class Sched>
; __device__ __forceinline__ void gemm_phase(LAS unsigned char* lds, const Gemm g, const Sched& S, const Epi& E) {
;     ...
;     for (;;) {
;         const bool has_next = S.next(ui + 1, nxt);
;         const char* nA = has_next ? (const char*)g.A + (size_t)nxt.pm * tstep : cA; const char* nB = has_next ? (const char*)g.Bt + (size_t)nxt.pn * tstep : cB;
;         for (int t = 0; t < nt; t += 2) {
;             const bool last = (t == nt - 2);
;             const char* a1 = cA + (size_t)(t + 1) * kstep;
;             const char* a2 = last ? nA : cA + (size_t)(t + 2) * kstep; const char* b2 = last ? nB : cB + (size_t)(t + 2) * kstep;
;             const char* a3 = a2 + kstep; const char* b3 = b2 + kstep;
;             PG8_LDB(B0, 0, 0); PG8_SCHED; PG8_LDA(At, 0, 0); PG8_STAGE(PG8_SA(1, 1), a1 + hstep, voffA);
;             PG8_WAIT_L(8); PG8_BAR; PG8_WAIT_L(0); PG8_MMA(0, 0, At, B0); PG8_BAR; PG8_SCHED;
;             PG8_LDB(B1, 0, 1); PG8_STAGE(PG8_SB(0, 0), b2, voffB);
;             PG8_BAR; PG8_WAIT_L(0); PG8_MMA(0, 1, At, B1); PG8_BAR;
;             PG8_LDA(At, 0, 1); PG8_STAGE(PG8_SA(0, 0), a2, voffA);
;             PG8_BAR; PG8_WAIT_L(0); PG8_MMA(1, 0, At, B0); PG8_BAR; PG8_SCHED;
;             PG8_STAGE(PG8_SB(0, 1), b2 + hstep, voffB);
;             PG8_WAIT_V(6); PG8_BAR; PG8_MMA(1, 1, At, B1); PG8_BAR;
.LBB0_1096:
	s_add_u32 s54, s24, 0x100
	s_addc_u32 s55, s25, 0
	s_mov_b32 s56, -2
	ds_read_b128 v[128:131], v241
	ds_read_b128 v[132:135], v241 offset:1024
	ds_read_b128 v[136:139], v241 offset:2048
	ds_read_b128 v[140:143], v241 offset:3072
	s_add_u32 s24, s22, 0x100
	s_addc_u32 s25, s23, 0
	s_cmp_eq_u32 s56, 40
	s_cselect_b32 s29, s5, s25
	s_cselect_b32 s28, s4, s24
	s_cselect_b32 s27, s7, s55
	s_cselect_b32 s26, s6, s54
	v_lshl_add_u64 v[176:177], s[22:23], 0, v[196:197]
	s_add_i32 m0, s35, 0xc000
	ds_read_b128 v[144:147], v242
	ds_read_b128 v[148:151], v242 offset:1024
	ds_read_b128 v[152:155], v242 offset:2048
	ds_read_b128 v[156:159], v242 offset:3072
	ds_read_b128 v[160:163], v242 offset:4096
	ds_read_b128 v[164:167], v242 offset:5120
	ds_read_b128 v[168:171], v242 offset:6144
	ds_read_b128 v[172:175], v242 offset:7168
	global_load_lds_dwordx4 v[176:177], off
	v_lshl_add_u64 v[176:177], s[22:23], 0, v[198:199]
	s_add_i32 m0, s35, 0xe000
	s_nop 0
	global_load_lds_dwordx4 v[176:177], off
	s_waitcnt lgkmcnt(8)
	s_waitcnt vmcnt(8)
	s_setprio 1
	s_barrier
	s_waitcnt lgkmcnt(0)
	s_waitcnt lgkmcnt(0)
	v_mfma_f32_16x16x32_bf16 v[124:127], v[128:131], v[144:147], 0
	v_mfma_f32_16x16x32_bf16 v[120:123], v[136:139], v[144:147], 0
	v_mfma_f32_16x16x32_bf16 v[108:111], v[128:131], v[152:155], 0
	v_mfma_f32_16x16x32_bf16 v[104:107], v[136:139], v[152:155], 0
	v_mfma_f32_16x16x32_bf16 v[92:95], v[128:131], v[160:163], 0
	v_mfma_f32_16x16x32_bf16 v[88:91], v[136:139], v[160:163], 0
	v_mfma_f32_16x16x32_bf16 v[76:79], v[128:131], v[168:171], 0
	v_mfma_f32_16x16x32_bf16 v[72:75], v[136:139], v[168:171], 0
	v_mfma_f32_16x16x32_bf16 v[124:127], v[132:135], v[148:151], v[124:127]
	v_mfma_f32_16x16x32_bf16 v[120:123], v[140:143], v[148:151], v[120:123]
	v_mfma_f32_16x16x32_bf16 v[108:111], v[132:135], v[156:159], v[108:111]
	v_mfma_f32_16x16x32_bf16 v[104:107], v[140:143], v[156:159], v[104:107]
	v_mfma_f32_16x16x32_bf16 v[92:95], v[132:135], v[164:167], v[92:95]
	v_mfma_f32_16x16x32_bf16 v[88:91], v[140:143], v[164:167], v[88:91]
	v_mfma_f32_16x16x32_bf16 v[76:79], v[132:135], v[172:175], v[76:79]
	v_mfma_f32_16x16x32_bf16 v[72:75], v[140:143], v[172:175], v[72:75]
	s_setprio 0
	s_barrier
	s_add_i32 s22, s48, s34
	s_mov_b32 m0, s22
	ds_read_b128 v[176:179], v243
	ds_read_b128 v[180:183], v243 offset:1024
	ds_read_b128 v[184:187], v243 offset:2048
	ds_read_b128 v[206:209], v243 offset:3072
	global_load_lds_dwordx4 v190, s[26:27]
	s_add_i32 m0, s22, 0x2000
	s_nop 0
	global_load_lds_dwordx4 v194, s[26:27]
	s_waitcnt vmcnt(8)
	s_setprio 1
	s_barrier
	s_waitcnt lgkmcnt(0)
	s_waitcnt lgkmcnt(0)
	v_mfma_f32_16x16x32_bf16 v[116:119], v[176:179], v[144:147], 0
	v_mfma_f32_16x16x32_bf16 v[112:115], v[184:187], v[144:147], 0
	v_mfma_f32_16x16x32_bf16 v[100:103], v[176:179], v[152:155], 0
	v_mfma_f32_16x16x32_bf16 v[96:99], v[184:187], v[152:155], 0
	v_mfma_f32_16x16x32_bf16 v[84:87], v[176:179], v[160:163], 0
	v_mfma_f32_16x16x32_bf16 v[80:83], v[184:187], v[160:163], 0
	v_mfma_f32_16x16x32_bf16 v[68:71], v[176:179], v[168:171], 0
	v_mfma_f32_16x16x32_bf16 v[64:67], v[184:187], v[168:171], 0
	v_mfma_f32_16x16x32_bf16 v[116:119], v[180:183], v[148:151], v[116:119]
	v_mfma_f32_16x16x32_bf16 v[112:115], v[206:209], v[148:151], v[112:115]
	v_mfma_f32_16x16x32_bf16 v[100:103], v[180:183], v[156:159], v[100:103]
	v_mfma_f32_16x16x32_bf16 v[96:99], v[206:209], v[156:159], v[96:99]
	v_mfma_f32_16x16x32_bf16 v[84:87], v[180:183], v[164:167], v[84:87]
	v_mfma_f32_16x16x32_bf16 v[80:83], v[206:209], v[164:167], v[80:83]
	v_mfma_f32_16x16x32_bf16 v[68:71], v[180:183], v[172:175], v[68:71]
	v_mfma_f32_16x16x32_bf16 v[64:67], v[206:209], v[172:175], v[64:67]
	s_setprio 0
	s_mov_b32 m0, s35
	v_lshl_add_u64 v[214:215], s[28:29], 0, v[188:189]
	s_barrier
	ds_read_b128 v[144:147], v242 offset:16384
	ds_read_b128 v[148:151], v242 offset:17408
	ds_read_b128 v[152:155], v242 offset:18432
	ds_read_b128 v[156:159], v242 offset:19456
	ds_read_b128 v[160:163], v242 offset:20480
	ds_read_b128 v[164:167], v242 offset:21504
	ds_read_b128 v[168:171], v242 offset:22528
	ds_read_b128 v[172:175], v242 offset:23552
	global_load_lds_dwordx4 v188, s[28:29]
	v_lshl_add_u64 v[216:217], s[28:29], 0, v[192:193]
	s_mov_b32 m0, s36
	s_nop 0
	global_load_lds_dwordx4 v192, s[28:29]
	s_setprio 1
	s_barrier
	s_waitcnt lgkmcnt(0)
	s_waitcnt lgkmcnt(0)
	v_mfma_f32_16x16x32_bf16 v[60:63], v[128:131], v[144:147], 0
	v_mfma_f32_16x16x32_bf16 v[56:59], v[136:139], v[144:147], 0
	v_mfma_f32_16x16x32_bf16 v[44:47], v[128:131], v[152:155], 0
	v_mfma_f32_16x16x32_bf16 v[40:43], v[136:139], v[152:155], 0
	v_mfma_f32_16x16x32_bf16 v[28:31], v[128:131], v[160:163], 0
	v_mfma_f32_16x16x32_bf16 v[24:27], v[136:139], v[160:163], 0
	v_mfma_f32_16x16x32_bf16 v[12:15], v[128:131], v[168:171], 0
	v_mfma_f32_16x16x32_bf16 v[8:11], v[136:139], v[168:171], 0
	v_mfma_f32_16x16x32_bf16 v[60:63], v[132:135], v[148:151], v[60:63]
	v_mfma_f32_16x16x32_bf16 v[56:59], v[140:143], v[148:151], v[56:59]
	v_mfma_f32_16x16x32_bf16 v[44:47], v[132:135], v[156:159], v[44:47]
	v_mfma_f32_16x16x32_bf16 v[40:43], v[140:143], v[156:159], v[40:43]
	v_mfma_f32_16x16x32_bf16 v[28:31], v[132:135], v[164:167], v[28:31]
	v_mfma_f32_16x16x32_bf16 v[24:27], v[140:143], v[164:167], v[24:27]
	v_mfma_f32_16x16x32_bf16 v[12:15], v[132:135], v[172:175], v[12:15]
	v_mfma_f32_16x16x32_bf16 v[8:11], v[140:143], v[172:175], v[8:11]
	s_setprio 0
	s_barrier
; #define PG8_STAGE(bufoff, gbase, voff) do { _Pragma("unroll") for (int _i = 0; _i < 2; ++_i) \
;         __builtin_amdgcn_global_load_lds((const unsigned*)((const char*)(gbase) + (voff)[_i]), (LAS unsigned*)(lds + (bufoff) + ldsw + _i * 8192), 16, 0, 0); } while (0)
; #define PG8_LDA(dst, b, h) do { _Pragma("unroll") for (int m = 0; m < 4; ++m) _Pragma("unroll") for (int k = 0; k < 2; ++k) dst[m][k] = *(const LAS bf16x8*)(lds + PG8_SA(b, h) + aoff + m * 2048 + k * 1024); } while (0)
; #define PG8_LDB(dst, b, h) do { _Pragma("unroll") for (int n = 0; n < 2; ++n) _Pragma("unroll") for (int k = 0; k < 2; ++k) dst[n][k] = *(const LAS bf16x8*)(lds + PG8_SB(b, h) + boff + n * 2048 + k * 1024); } while (0)
; #define PG8_MMA(ai, bj, At, Bt) do { __builtin_amdgcn_s_setprio(1); _Pragma("unroll") for (int m = 0; m < 4; ++m) _Pragma("unroll") for (int n = 0; n < 2; ++n) _Pragma("unroll") for (int k = 0; k < 2; ++k) \
;         acc[ai][bj][m][n] = __builtin_amdgcn_mfma_f32_16x16x32_bf16(Bt[n][k], At[m][k], acc[ai][bj][m][n], 0, 0, 0); __builtin_amdgcn_s_setprio(0); } while (0)
; #define PG8_WAIT_V(n) asm volatile("s_waitcnt vmcnt(" #n ")" ::: "memory")
; #define PG8_WAIT_L(n) asm volatile("s_waitcnt lgkmcnt(" #n ")" ::: "memory")
; #define PG8_BAR __builtin_amdgcn_s_barrier()
; #define PG8_SCHED __builtin_amdgcn_sched_barrier(0)
; template <class Epi, class Sched>
; __device__ __forceinline__ void gemm_phase(LAS unsigned char* lds, const Gemm g, const Sched& S, const Epi& E) {
;     ...
;             PG8_STAGE(PG8_SB(0, 1), b2 + hstep, voffB);
;             PG8_WAIT_V(6); PG8_BAR; PG8_MMA(1, 1, At, B1); PG8_BAR;
;             PG8_LDB(B0, 1, 0); PG8_SCHED; PG8_LDA(At, 1, 0); PG8_STAGE(PG8_SA(0, 1), a2 + hstep, voffA);
;             PG8_WAIT_L(8); PG8_BAR; PG8_WAIT_L(0); PG8_MMA(0, 0, At, B0); PG8_BAR; PG8_SCHED;
;             PG8_LDB(B1, 1, 1); PG8_STAGE(PG8_SB(1, 0), b3, voffB);
;             PG8_BAR; PG8_WAIT_L(0); PG8_MMA(0, 1, At, B1); PG8_BAR;
;             PG8_LDA(At, 1, 1); PG8_STAGE(PG8_SA(1, 0), a3, voffA);
;             PG8_BAR; PG8_WAIT_L(0); PG8_MMA(1, 0, At, B0); PG8_BAR; PG8_SCHED;
	s_add_u32 s22, s26, 0xb0000
	s_addc_u32 s23, s27, 0
	s_add_i32 s57, s49, s34
	s_mov_b32 m0, s57
	s_nop 0
	global_load_lds_dwordx4 v190, s[22:23]
	s_add_i32 m0, s57, 0x2000
	s_nop 0
	global_load_lds_dwordx4 v194, s[22:23]
	s_add_u32 s22, s28, 0xb0000
	s_addc_u32 s23, s29, 0
	s_mov_b32 m0, s37
	s_nop 0
	global_load_lds_dwordx4 v188, s[22:23]
	s_mov_b32 m0, s38
	s_nop 0
	global_load_lds_dwordx4 v192, s[22:23]
	s_waitcnt vmcnt(10)
	s_setprio 1
	s_barrier
	v_mfma_f32_16x16x32_bf16 v[52:55], v[176:179], v[144:147], 0
	v_mfma_f32_16x16x32_bf16 v[48:51], v[184:187], v[144:147], 0
	v_mfma_f32_16x16x32_bf16 v[36:39], v[176:179], v[152:155], 0
	v_mfma_f32_16x16x32_bf16 v[32:35], v[184:187], v[152:155], 0
	v_mfma_f32_16x16x32_bf16 v[20:23], v[176:179], v[160:163], 0
	v_mfma_f32_16x16x32_bf16 v[16:19], v[184:187], v[160:163], 0
	v_mfma_f32_16x16x32_bf16 v[4:7], v[176:179], v[168:171], 0
	v_mfma_f32_16x16x32_bf16 v[0:3], v[184:187], v[168:171], 0
	v_mfma_f32_16x16x32_bf16 v[52:55], v[180:183], v[148:151], v[52:55]
	v_mfma_f32_16x16x32_bf16 v[48:51], v[206:209], v[148:151], v[48:51]
	v_mfma_f32_16x16x32_bf16 v[36:39], v[180:183], v[156:159], v[36:39]
	v_mfma_f32_16x16x32_bf16 v[32:35], v[206:209], v[156:159], v[32:35]
	v_mfma_f32_16x16x32_bf16 v[20:23], v[180:183], v[164:167], v[20:23]
	v_mfma_f32_16x16x32_bf16 v[16:19], v[206:209], v[164:167], v[16:19]
	v_mfma_f32_16x16x32_bf16 v[4:7], v[180:183], v[172:175], v[4:7]
	v_mfma_f32_16x16x32_bf16 v[0:3], v[206:209], v[172:175], v[0:3]
	s_setprio 0
	s_add_i32 s57, 0, 0x18000
	v_add_u32_e32 v140, s57, v240
	s_barrier
	ds_read_b128 v[128:131], v140
	ds_read_b128 v[132:135], v140 offset:1024
	ds_read_b128 v[136:139], v140 offset:2048
	ds_read_b128 v[140:143], v140 offset:3072
	ds_read_b128 v[144:147], v242 offset:32768
	ds_read_b128 v[148:151], v242 offset:33792
	ds_read_b128 v[152:155], v242 offset:34816
	ds_read_b128 v[156:159], v242 offset:35840
	ds_read_b128 v[160:163], v242 offset:36864
	ds_read_b128 v[164:167], v242 offset:37888
	ds_read_b128 v[168:171], v242 offset:38912
	ds_read_b128 v[172:175], v242 offset:39936
	s_waitcnt lgkmcnt(8)
	s_waitcnt vmcnt(8)
	s_setprio 1
	s_barrier
	s_waitcnt lgkmcnt(0)
	s_waitcnt lgkmcnt(0)
	v_mfma_f32_16x16x32_bf16 v[124:127], v[128:131], v[144:147], v[124:127]
	v_mfma_f32_16x16x32_bf16 v[120:123], v[136:139], v[144:147], v[120:123]
	v_mfma_f32_16x16x32_bf16 v[108:111], v[128:131], v[152:155], v[108:111]
	v_mfma_f32_16x16x32_bf16 v[104:107], v[136:139], v[152:155], v[104:107]
	v_mfma_f32_16x16x32_bf16 v[92:95], v[128:131], v[160:163], v[92:95]
	v_mfma_f32_16x16x32_bf16 v[88:91], v[136:139], v[160:163], v[88:91]
	v_mfma_f32_16x16x32_bf16 v[76:79], v[128:131], v[168:171], v[76:79]
	v_mfma_f32_16x16x32_bf16 v[72:75], v[136:139], v[168:171], v[72:75]
	v_mfma_f32_16x16x32_bf16 v[124:127], v[132:135], v[148:151], v[124:127]
	v_mfma_f32_16x16x32_bf16 v[120:123], v[140:143], v[148:151], v[120:123]
	v_mfma_f32_16x16x32_bf16 v[108:111], v[132:135], v[156:159], v[108:111]
	v_mfma_f32_16x16x32_bf16 v[104:107], v[140:143], v[156:159], v[104:107]
	v_mfma_f32_16x16x32_bf16 v[92:95], v[132:135], v[164:167], v[92:95]
	v_mfma_f32_16x16x32_bf16 v[88:91], v[140:143], v[164:167], v[88:91]
	v_mfma_f32_16x16x32_bf16 v[76:79], v[132:135], v[172:175], v[76:79]
	v_mfma_f32_16x16x32_bf16 v[72:75], v[140:143], v[172:175], v[72:75]
	s_setprio 0
	s_barrier
	s_add_i32 s28, 0, 0x1c000
	s_add_i32 s22, s57, s34
	v_add_u32_e32 v206, s28, v240
	s_add_u32 s0, s26, 0x80
	s_addc_u32 s1, s27, 0
	s_mov_b32 m0, s22
	ds_read_b128 v[176:179], v206
	ds_read_b128 v[180:183], v206 offset:1024
	ds_read_b128 v[184:187], v206 offset:2048
	ds_read_b128 v[206:209], v206 offset:3072
	global_load_lds_dwordx4 v190, s[0:1]
	s_add_i32 m0, s22, 0x2000
	s_nop 0
	global_load_lds_dwordx4 v194, s[0:1]
	s_waitcnt vmcnt(8)
	s_setprio 1
	s_barrier
	s_waitcnt lgkmcnt(0)
	s_waitcnt lgkmcnt(0)
	v_mfma_f32_16x16x32_bf16 v[116:119], v[176:179], v[144:147], v[116:119]
	v_mfma_f32_16x16x32_bf16 v[112:115], v[184:187], v[144:147], v[112:115]
	v_mfma_f32_16x16x32_bf16 v[100:103], v[176:179], v[152:155], v[100:103]
	v_mfma_f32_16x16x32_bf16 v[96:99], v[184:187], v[152:155], v[96:99]
	v_mfma_f32_16x16x32_bf16 v[84:87], v[176:179], v[160:163], v[84:87]
	v_mfma_f32_16x16x32_bf16 v[80:83], v[184:187], v[160:163], v[80:83]
	v_mfma_f32_16x16x32_bf16 v[68:71], v[176:179], v[168:171], v[68:71]
	v_mfma_f32_16x16x32_bf16 v[64:67], v[184:187], v[168:171], v[64:67]
	v_mfma_f32_16x16x32_bf16 v[116:119], v[180:183], v[148:151], v[116:119]
	v_mfma_f32_16x16x32_bf16 v[112:115], v[206:209], v[148:151], v[112:115]
	v_mfma_f32_16x16x32_bf16 v[100:103], v[180:183], v[156:159], v[100:103]
	v_mfma_f32_16x16x32_bf16 v[96:99], v[206:209], v[156:159], v[96:99]
	v_mfma_f32_16x16x32_bf16 v[84:87], v[180:183], v[164:167], v[84:87]
	v_mfma_f32_16x16x32_bf16 v[80:83], v[206:209], v[164:167], v[80:83]
	v_mfma_f32_16x16x32_bf16 v[68:71], v[180:183], v[172:175], v[68:71]
	v_mfma_f32_16x16x32_bf16 v[64:67], v[206:209], v[172:175], v[64:67]
	s_setprio 0
	s_mov_b32 m0, s44
	s_mov_b64 s[0:1], 0x80
	v_lshl_add_u64 v[210:211], v[214:215], 0, s[0:1]
	s_barrier
	ds_read_b128 v[144:147], v242 offset:49152
	ds_read_b128 v[148:151], v242 offset:50176
	ds_read_b128 v[152:155], v242 offset:51200
	ds_read_b128 v[156:159], v242 offset:52224
	ds_read_b128 v[160:163], v242 offset:53248
	ds_read_b128 v[164:167], v242 offset:54272
	ds_read_b128 v[168:171], v242 offset:55296
	ds_read_b128 v[172:175], v242 offset:56320
	global_load_lds_dwordx4 v[210:211], off
	v_lshl_add_u64 v[210:211], v[216:217], 0, s[0:1]
	s_mov_b32 m0, s45
	s_nop 0
	global_load_lds_dwordx4 v[210:211], off
	s_setprio 1
	s_barrier
; #define PG8_STAGE(bufoff, gbase, voff) do { _Pragma("unroll") for (int _i = 0; _i < 2; ++_i) \
;         __builtin_amdgcn_global_load_lds((const unsigned*)((const char*)(gbase) + (voff)[_i]), (LAS unsigned*)(lds + (bufoff) + ldsw + _i * 8192), 16, 0, 0); } while (0)
; #define PG8_LDA(dst, b, h) do { _Pragma("unroll") for (int m = 0; m < 4; ++m) _Pragma("unroll") for (int k = 0; k < 2; ++k) dst[m][k] = *(const LAS bf16x8*)(lds + PG8_SA(b, h) + aoff + m * 2048 + k * 1024); } while (0)
; #define PG8_LDB(dst, b, h) do { _Pragma("unroll") for (int n = 0; n < 2; ++n) _Pragma("unroll") for (int k = 0; k < 2; ++k) dst[n][k] = *(const LAS bf16x8*)(lds + PG8_SB(b, h) + boff + n * 2048 + k * 1024); } while (0)
; #define PG8_MMA(ai, bj, At, Bt) do { __builtin_amdgcn_s_setprio(1); _Pragma("unroll") for (int m = 0; m < 4; ++m) _Pragma("unroll") for (int n = 0; n < 2; ++n) _Pragma("unroll") for (int k = 0; k < 2; ++k) \
;         acc[ai][bj][m][n] = __builtin_amdgcn_mfma_f32_16x16x32_bf16(Bt[n][k], At[m][k], acc[ai][bj][m][n], 0, 0, 0); __builtin_amdgcn_s_setprio(0); } while (0)
; #define PG8_WAIT_V(n) asm volatile("s_waitcnt vmcnt(" #n ")" ::: "memory")
; #define PG8_WAIT_L(n) asm volatile("s_waitcnt lgkmcnt(" #n ")" ::: "memory")
; #define PG8_BAR __builtin_amdgcn_s_barrier()
; #define PG8_SCHED __builtin_amdgcn_sched_barrier(0)
; template <class Epi, class Sched>
; __device__ __forceinline__ void gemm_phase(LAS unsigned char* lds, const Gemm g, const Sched& S, const Epi& E) {
;     ...
;         for (int t = 0; t < nt; t += 2) {
;             const bool last = (t == nt - 2);
;             const char* a1 = cA + (size_t)(t + 1) * kstep;
;             const char* a2 = last ? nA : cA + (size_t)(t + 2) * kstep; const char* b2 = last ? nB : cB + (size_t)(t + 2) * kstep;
;             const char* a3 = a2 + kstep; const char* b3 = b2 + kstep;
;             PG8_LDB(B0, 0, 0); PG8_SCHED; PG8_LDA(At, 0, 0); PG8_STAGE(PG8_SA(1, 1), a1 + hstep, voffA);
;             PG8_WAIT_L(8); PG8_BAR; PG8_WAIT_L(0); PG8_MMA(0, 0, At, B0); PG8_BAR; PG8_SCHED;
;             PG8_LDB(B1, 0, 1); PG8_STAGE(PG8_SB(0, 0), b2, voffB);
;     ...
;             PG8_BAR; PG8_WAIT_L(0); PG8_MMA(1, 0, At, B0); PG8_BAR; PG8_SCHED;
;             PG8_STAGE(PG8_SB(1, 1), b3 + hstep, voffB);
;             PG8_WAIT_V(6); PG8_BAR; PG8_MMA(1, 1, At, B1); PG8_BAR;
	s_waitcnt lgkmcnt(0)
	s_waitcnt lgkmcnt(0)
	v_mfma_f32_16x16x32_bf16 v[60:63], v[128:131], v[144:147], v[60:63]
	v_mfma_f32_16x16x32_bf16 v[56:59], v[136:139], v[144:147], v[56:59]
	v_mfma_f32_16x16x32_bf16 v[44:47], v[128:131], v[152:155], v[44:47]
	v_mfma_f32_16x16x32_bf16 v[40:43], v[136:139], v[152:155], v[40:43]
	v_mfma_f32_16x16x32_bf16 v[28:31], v[128:131], v[160:163], v[28:31]
	v_mfma_f32_16x16x32_bf16 v[24:27], v[136:139], v[160:163], v[24:27]
	v_mfma_f32_16x16x32_bf16 v[12:15], v[128:131], v[168:171], v[12:15]
	v_mfma_f32_16x16x32_bf16 v[8:11], v[136:139], v[168:171], v[8:11]
	v_mfma_f32_16x16x32_bf16 v[60:63], v[132:135], v[148:151], v[60:63]
	v_mfma_f32_16x16x32_bf16 v[56:59], v[140:143], v[148:151], v[56:59]
	v_mfma_f32_16x16x32_bf16 v[44:47], v[132:135], v[156:159], v[44:47]
	v_mfma_f32_16x16x32_bf16 v[40:43], v[140:143], v[156:159], v[40:43]
	v_mfma_f32_16x16x32_bf16 v[28:31], v[132:135], v[164:167], v[28:31]
	v_mfma_f32_16x16x32_bf16 v[24:27], v[140:143], v[164:167], v[24:27]
	v_mfma_f32_16x16x32_bf16 v[12:15], v[132:135], v[172:175], v[12:15]
	v_mfma_f32_16x16x32_bf16 v[8:11], v[140:143], v[172:175], v[8:11]
	s_setprio 0
	s_barrier
	s_add_u32 s22, s26, 0xb0080
	s_addc_u32 s23, s27, 0
	s_add_i32 s26, s28, s34
	s_mov_b32 m0, s26
	s_nop 0
	global_load_lds_dwordx4 v190, s[22:23]
	s_add_i32 m0, s26, 0x2000
	s_nop 0
	global_load_lds_dwordx4 v194, s[22:23]
	s_waitcnt vmcnt(8)
	s_setprio 1
	s_barrier
	v_mfma_f32_16x16x32_bf16 v[52:55], v[176:179], v[144:147], v[52:55]
	v_mfma_f32_16x16x32_bf16 v[48:51], v[184:187], v[144:147], v[48:51]
	v_mfma_f32_16x16x32_bf16 v[36:39], v[176:179], v[152:155], v[36:39]
	v_mfma_f32_16x16x32_bf16 v[32:35], v[184:187], v[152:155], v[32:35]
	v_mfma_f32_16x16x32_bf16 v[20:23], v[176:179], v[160:163], v[20:23]
	v_mfma_f32_16x16x32_bf16 v[16:19], v[184:187], v[160:163], v[16:19]
	v_mfma_f32_16x16x32_bf16 v[4:7], v[176:179], v[168:171], v[4:7]
	v_mfma_f32_16x16x32_bf16 v[0:3], v[184:187], v[168:171], v[0:3]
	v_mfma_f32_16x16x32_bf16 v[52:55], v[180:183], v[148:151], v[52:55]
	v_mfma_f32_16x16x32_bf16 v[48:51], v[206:209], v[148:151], v[48:51]
	v_mfma_f32_16x16x32_bf16 v[36:39], v[180:183], v[156:159], v[36:39]
	v_mfma_f32_16x16x32_bf16 v[32:35], v[206:209], v[156:159], v[32:35]
	v_mfma_f32_16x16x32_bf16 v[20:23], v[180:183], v[164:167], v[20:23]
	v_mfma_f32_16x16x32_bf16 v[16:19], v[206:209], v[164:167], v[16:19]
	v_mfma_f32_16x16x32_bf16 v[4:7], v[180:183], v[172:175], v[4:7]
	v_mfma_f32_16x16x32_bf16 v[0:3], v[206:209], v[172:175], v[0:3]
	s_setprio 0
	s_add_i32 s56, s56, 2
	s_add_u32 s54, s54, 0x100
	s_addc_u32 s55, s55, 0
	s_cmp_gt_u32 s56, 41
	s_mov_b64 s[22:23], s[24:25]
	s_barrier
.LBB0_1097:
	ds_read_b128 v[128:131], v241
	ds_read_b128 v[132:135], v241 offset:1024
	ds_read_b128 v[136:139], v241 offset:2048
	ds_read_b128 v[140:143], v241 offset:3072
	s_add_u32 s24, s22, 0x100
	s_addc_u32 s25, s23, 0
	s_cmp_eq_u32 s56, 40
	s_cselect_b32 s29, s5, s25
	s_cselect_b32 s28, s4, s24
	s_cselect_b32 s27, s7, s55
	s_cselect_b32 s26, s6, s54
	v_lshl_add_u64 v[176:177], s[22:23], 0, v[196:197]
	s_add_i32 m0, s35, 0xc000
	ds_read_b128 v[144:147], v242
	ds_read_b128 v[148:151], v242 offset:1024
	ds_read_b128 v[152:155], v242 offset:2048
	ds_read_b128 v[156:159], v242 offset:3072
	ds_read_b128 v[160:163], v242 offset:4096
	ds_read_b128 v[164:167], v242 offset:5120
	ds_read_b128 v[168:171], v242 offset:6144
	ds_read_b128 v[172:175], v242 offset:7168
	global_load_lds_dwordx4 v[176:177], off
	v_lshl_add_u64 v[176:177], s[22:23], 0, v[198:199]
	s_add_i32 m0, s35, 0xe000
	s_nop 0
	global_load_lds_dwordx4 v[176:177], off
	s_waitcnt lgkmcnt(8)
	s_waitcnt vmcnt(8)
	s_setprio 1
	s_barrier
	s_waitcnt lgkmcnt(0)
	s_waitcnt lgkmcnt(0)
	v_mfma_f32_16x16x32_bf16 v[124:127], v[128:131], v[144:147], v[124:127]
	v_mfma_f32_16x16x32_bf16 v[120:123], v[136:139], v[144:147], v[120:123]
	v_mfma_f32_16x16x32_bf16 v[108:111], v[128:131], v[152:155], v[108:111]
	v_mfma_f32_16x16x32_bf16 v[104:107], v[136:139], v[152:155], v[104:107]
	v_mfma_f32_16x16x32_bf16 v[92:95], v[128:131], v[160:163], v[92:95]
	v_mfma_f32_16x16x32_bf16 v[88:91], v[136:139], v[160:163], v[88:91]
	v_mfma_f32_16x16x32_bf16 v[76:79], v[128:131], v[168:171], v[76:79]
	v_mfma_f32_16x16x32_bf16 v[72:75], v[136:139], v[168:171], v[72:75]
	v_mfma_f32_16x16x32_bf16 v[124:127], v[132:135], v[148:151], v[124:127]
	v_mfma_f32_16x16x32_bf16 v[120:123], v[140:143], v[148:151], v[120:123]
	v_mfma_f32_16x16x32_bf16 v[108:111], v[132:135], v[156:159], v[108:111]
	v_mfma_f32_16x16x32_bf16 v[104:107], v[140:143], v[156:159], v[104:107]
	v_mfma_f32_16x16x32_bf16 v[92:95], v[132:135], v[164:167], v[92:95]
	v_mfma_f32_16x16x32_bf16 v[88:91], v[140:143], v[164:167], v[88:91]
	v_mfma_f32_16x16x32_bf16 v[76:79], v[132:135], v[172:175], v[76:79]
	v_mfma_f32_16x16x32_bf16 v[72:75], v[140:143], v[172:175], v[72:75]
	s_setprio 0
	s_barrier
	s_add_i32 s22, s48, s34
	s_mov_b32 m0, s22
	ds_read_b128 v[176:179], v243
	ds_read_b128 v[180:183], v243 offset:1024
	ds_read_b128 v[184:187], v243 offset:2048
	ds_read_b128 v[206:209], v243 offset:3072
	global_load_lds_dwordx4 v190, s[26:27]
	s_add_i32 m0, s22, 0x2000
	s_nop 0
	global_load_lds_dwordx4 v194, s[26:27]
	s_waitcnt vmcnt(8)
	s_setprio 1
	s_barrier
; #define PG8_STAGE(bufoff, gbase, voff) do { _Pragma("unroll") for (int _i = 0; _i < 2; ++_i) \
;         __builtin_amdgcn_global_load_lds((const unsigned*)((const char*)(gbase) + (voff)[_i]), (LAS unsigned*)(lds + (bufoff) + ldsw + _i * 8192), 16, 0, 0); } while (0)
; #define PG8_LDA(dst, b, h) do { _Pragma("unroll") for (int m = 0; m < 4; ++m) _Pragma("unroll") for (int k = 0; k < 2; ++k) dst[m][k] = *(const LAS bf16x8*)(lds + PG8_SA(b, h) + aoff + m * 2048 + k * 1024); } while (0)
; #define PG8_LDB(dst, b, h) do { _Pragma("unroll") for (int n = 0; n < 2; ++n) _Pragma("unroll") for (int k = 0; k < 2; ++k) dst[n][k] = *(const LAS bf16x8*)(lds + PG8_SB(b, h) + boff + n * 2048 + k * 1024); } while (0)
; #define PG8_MMA(ai, bj, At, Bt) do { __builtin_amdgcn_s_setprio(1); _Pragma("unroll") for (int m = 0; m < 4; ++m) _Pragma("unroll") for (int n = 0; n < 2; ++n) _Pragma("unroll") for (int k = 0; k < 2; ++k) \
;         acc[ai][bj][m][n] = __builtin_amdgcn_mfma_f32_16x16x32_bf16(Bt[n][k], At[m][k], acc[ai][bj][m][n], 0, 0, 0); __builtin_amdgcn_s_setprio(0); } while (0)
; #define PG8_WAIT_V(n) asm volatile("s_waitcnt vmcnt(" #n ")" ::: "memory")
; #define PG8_WAIT_L(n) asm volatile("s_waitcnt lgkmcnt(" #n ")" ::: "memory")
; #define PG8_BAR __builtin_amdgcn_s_barrier()
; #define PG8_SCHED __builtin_amdgcn_sched_barrier(0)
; template <class Epi, class Sched>
; __device__ __forceinline__ void gemm_phase(LAS unsigned char* lds, const Gemm g, const Sched& S, const Epi& E) {
;     ...
;             PG8_BAR; PG8_WAIT_L(0); PG8_MMA(0, 1, At, B1); PG8_BAR;
;             PG8_LDA(At, 0, 1); PG8_STAGE(PG8_SA(0, 0), a2, voffA);
;             PG8_BAR; PG8_WAIT_L(0); PG8_MMA(1, 0, At, B0); PG8_BAR; PG8_SCHED;
;             PG8_STAGE(PG8_SB(0, 1), b2 + hstep, voffB);
;             PG8_WAIT_V(6); PG8_BAR; PG8_MMA(1, 1, At, B1); PG8_BAR;
;             PG8_LDB(B0, 1, 0); PG8_SCHED; PG8_LDA(At, 1, 0); PG8_STAGE(PG8_SA(0, 1), a2 + hstep, voffA);
;             PG8_WAIT_L(8); PG8_BAR; PG8_WAIT_L(0); PG8_MMA(0, 0, At, B0); PG8_BAR; PG8_SCHED;
	s_waitcnt lgkmcnt(0)
	s_waitcnt lgkmcnt(0)
	v_mfma_f32_16x16x32_bf16 v[116:119], v[176:179], v[144:147], v[116:119]
	v_mfma_f32_16x16x32_bf16 v[112:115], v[184:187], v[144:147], v[112:115]
	v_mfma_f32_16x16x32_bf16 v[100:103], v[176:179], v[152:155], v[100:103]
	v_mfma_f32_16x16x32_bf16 v[96:99], v[184:187], v[152:155], v[96:99]
	v_mfma_f32_16x16x32_bf16 v[84:87], v[176:179], v[160:163], v[84:87]
	v_mfma_f32_16x16x32_bf16 v[80:83], v[184:187], v[160:163], v[80:83]
	v_mfma_f32_16x16x32_bf16 v[68:71], v[176:179], v[168:171], v[68:71]
	v_mfma_f32_16x16x32_bf16 v[64:67], v[184:187], v[168:171], v[64:67]
	v_mfma_f32_16x16x32_bf16 v[116:119], v[180:183], v[148:151], v[116:119]
	v_mfma_f32_16x16x32_bf16 v[112:115], v[206:209], v[148:151], v[112:115]
	v_mfma_f32_16x16x32_bf16 v[100:103], v[180:183], v[156:159], v[100:103]
	v_mfma_f32_16x16x32_bf16 v[96:99], v[206:209], v[156:159], v[96:99]
	v_mfma_f32_16x16x32_bf16 v[84:87], v[180:183], v[164:167], v[84:87]
	v_mfma_f32_16x16x32_bf16 v[80:83], v[206:209], v[164:167], v[80:83]
	v_mfma_f32_16x16x32_bf16 v[68:71], v[180:183], v[172:175], v[68:71]
	v_mfma_f32_16x16x32_bf16 v[64:67], v[206:209], v[172:175], v[64:67]
	s_setprio 0
	s_mov_b32 m0, s35
	v_lshl_add_u64 v[214:215], s[28:29], 0, v[188:189]
	s_barrier
	ds_read_b128 v[144:147], v242 offset:16384
	ds_read_b128 v[148:151], v242 offset:17408
	ds_read_b128 v[152:155], v242 offset:18432
	ds_read_b128 v[156:159], v242 offset:19456
	ds_read_b128 v[160:163], v242 offset:20480
	ds_read_b128 v[164:167], v242 offset:21504
	ds_read_b128 v[168:171], v242 offset:22528
	ds_read_b128 v[172:175], v242 offset:23552
	global_load_lds_dwordx4 v188, s[28:29]
	v_lshl_add_u64 v[216:217], s[28:29], 0, v[192:193]
	s_mov_b32 m0, s36
	s_nop 0
	global_load_lds_dwordx4 v192, s[28:29]
	s_setprio 1
	s_barrier
	s_waitcnt lgkmcnt(0)
	s_waitcnt lgkmcnt(0)
	v_mfma_f32_16x16x32_bf16 v[60:63], v[128:131], v[144:147], v[60:63]
	v_mfma_f32_16x16x32_bf16 v[56:59], v[136:139], v[144:147], v[56:59]
	v_mfma_f32_16x16x32_bf16 v[44:47], v[128:131], v[152:155], v[44:47]
	v_mfma_f32_16x16x32_bf16 v[40:43], v[136:139], v[152:155], v[40:43]
	v_mfma_f32_16x16x32_bf16 v[28:31], v[128:131], v[160:163], v[28:31]
	v_mfma_f32_16x16x32_bf16 v[24:27], v[136:139], v[160:163], v[24:27]
	v_mfma_f32_16x16x32_bf16 v[12:15], v[128:131], v[168:171], v[12:15]
	v_mfma_f32_16x16x32_bf16 v[8:11], v[136:139], v[168:171], v[8:11]
	v_mfma_f32_16x16x32_bf16 v[60:63], v[132:135], v[148:151], v[60:63]
	v_mfma_f32_16x16x32_bf16 v[56:59], v[140:143], v[148:151], v[56:59]
	v_mfma_f32_16x16x32_bf16 v[44:47], v[132:135], v[156:159], v[44:47]
	v_mfma_f32_16x16x32_bf16 v[40:43], v[140:143], v[156:159], v[40:43]
	v_mfma_f32_16x16x32_bf16 v[28:31], v[132:135], v[164:167], v[28:31]
	v_mfma_f32_16x16x32_bf16 v[24:27], v[140:143], v[164:167], v[24:27]
	v_mfma_f32_16x16x32_bf16 v[12:15], v[132:135], v[172:175], v[12:15]
	v_mfma_f32_16x16x32_bf16 v[8:11], v[140:143], v[172:175], v[8:11]
	s_setprio 0
	s_barrier
	s_add_u32 s22, s26, 0xb0000
	s_addc_u32 s23, s27, 0
	s_add_i32 s57, s49, s34
	s_mov_b32 m0, s57
	s_nop 0
	global_load_lds_dwordx4 v190, s[22:23]
	s_add_i32 m0, s57, 0x2000
	s_nop 0
	global_load_lds_dwordx4 v194, s[22:23]
	s_add_u32 s22, s28, 0xb0000
	s_addc_u32 s23, s29, 0
	s_mov_b32 m0, s37
	s_nop 0
	global_load_lds_dwordx4 v188, s[22:23]
	s_mov_b32 m0, s38
	s_nop 0
	global_load_lds_dwordx4 v192, s[22:23]
	s_waitcnt vmcnt(10)
	s_setprio 1
	s_barrier
	v_mfma_f32_16x16x32_bf16 v[52:55], v[176:179], v[144:147], v[52:55]
	v_mfma_f32_16x16x32_bf16 v[48:51], v[184:187], v[144:147], v[48:51]
	v_mfma_f32_16x16x32_bf16 v[36:39], v[176:179], v[152:155], v[36:39]
	v_mfma_f32_16x16x32_bf16 v[32:35], v[184:187], v[152:155], v[32:35]
	v_mfma_f32_16x16x32_bf16 v[20:23], v[176:179], v[160:163], v[20:23]
	v_mfma_f32_16x16x32_bf16 v[16:19], v[184:187], v[160:163], v[16:19]
	v_mfma_f32_16x16x32_bf16 v[4:7], v[176:179], v[168:171], v[4:7]
	v_mfma_f32_16x16x32_bf16 v[0:3], v[184:187], v[168:171], v[0:3]
	v_mfma_f32_16x16x32_bf16 v[52:55], v[180:183], v[148:151], v[52:55]
	v_mfma_f32_16x16x32_bf16 v[48:51], v[206:209], v[148:151], v[48:51]
	v_mfma_f32_16x16x32_bf16 v[36:39], v[180:183], v[156:159], v[36:39]
	v_mfma_f32_16x16x32_bf16 v[32:35], v[206:209], v[156:159], v[32:35]
	v_mfma_f32_16x16x32_bf16 v[20:23], v[180:183], v[164:167], v[20:23]
	v_mfma_f32_16x16x32_bf16 v[16:19], v[206:209], v[164:167], v[16:19]
	v_mfma_f32_16x16x32_bf16 v[4:7], v[180:183], v[172:175], v[4:7]
	v_mfma_f32_16x16x32_bf16 v[0:3], v[206:209], v[172:175], v[0:3]
	s_setprio 0
	s_add_i32 s57, 0, 0x18000
	v_add_u32_e32 v140, s57, v240
	s_barrier
	ds_read_b128 v[128:131], v140
	ds_read_b128 v[132:135], v140 offset:1024
	ds_read_b128 v[136:139], v140 offset:2048
	ds_read_b128 v[140:143], v140 offset:3072
	ds_read_b128 v[144:147], v242 offset:32768
	ds_read_b128 v[148:151], v242 offset:33792
	ds_read_b128 v[152:155], v242 offset:34816
	ds_read_b128 v[156:159], v242 offset:35840
	ds_read_b128 v[160:163], v242 offset:36864
	ds_read_b128 v[164:167], v242 offset:37888
	ds_read_b128 v[168:171], v242 offset:38912
	ds_read_b128 v[172:175], v242 offset:39936
	s_waitcnt lgkmcnt(8)
	s_waitcnt vmcnt(8)
	s_setprio 1
	s_barrier
; #define PG8_STAGE(bufoff, gbase, voff) do { _Pragma("unroll") for (int _i = 0; _i < 2; ++_i) \
;         __builtin_amdgcn_global_load_lds((const unsigned*)((const char*)(gbase) + (voff)[_i]), (LAS unsigned*)(lds + (bufoff) + ldsw + _i * 8192), 16, 0, 0); } while (0)
; #define PG8_LDA(dst, b, h) do { _Pragma("unroll") for (int m = 0; m < 4; ++m) _Pragma("unroll") for (int k = 0; k < 2; ++k) dst[m][k] = *(const LAS bf16x8*)(lds + PG8_SA(b, h) + aoff + m * 2048 + k * 1024); } while (0)
; #define PG8_LDB(dst, b, h) do { _Pragma("unroll") for (int n = 0; n < 2; ++n) _Pragma("unroll") for (int k = 0; k < 2; ++k) dst[n][k] = *(const LAS bf16x8*)(lds + PG8_SB(b, h) + boff + n * 2048 + k * 1024); } while (0)
; #define PG8_MMA(ai, bj, At, Bt) do { __builtin_amdgcn_s_setprio(1); _Pragma("unroll") for (int m = 0; m < 4; ++m) _Pragma("unroll") for (int n = 0; n < 2; ++n) _Pragma("unroll") for (int k = 0; k < 2; ++k) \
;         acc[ai][bj][m][n] = __builtin_amdgcn_mfma_f32_16x16x32_bf16(Bt[n][k], At[m][k], acc[ai][bj][m][n], 0, 0, 0); __builtin_amdgcn_s_setprio(0); } while (0)
; #define PG8_WAIT_V(n) asm volatile("s_waitcnt vmcnt(" #n ")" ::: "memory")
; #define PG8_WAIT_L(n) asm volatile("s_waitcnt lgkmcnt(" #n ")" ::: "memory")
; #define PG8_BAR __builtin_amdgcn_s_barrier()
; #define PG8_SCHED __builtin_amdgcn_sched_barrier(0)
; template <class Epi, class Sched>
; __device__ __forceinline__ void gemm_phase(LAS unsigned char* lds, const Gemm g, const Sched& S, const Epi& E) {
;     ...
;             PG8_WAIT_L(8); PG8_BAR; PG8_WAIT_L(0); PG8_MMA(0, 0, At, B0); PG8_BAR; PG8_SCHED;
;             PG8_LDB(B1, 1, 1); PG8_STAGE(PG8_SB(1, 0), b3, voffB);
;             PG8_BAR; PG8_WAIT_L(0); PG8_MMA(0, 1, At, B1); PG8_BAR;
;             PG8_LDA(At, 1, 1); PG8_STAGE(PG8_SA(1, 0), a3, voffA);
;             PG8_BAR; PG8_WAIT_L(0); PG8_MMA(1, 0, At, B0); PG8_BAR; PG8_SCHED;
;             PG8_STAGE(PG8_SB(1, 1), b3 + hstep, voffB);
;             PG8_WAIT_V(6); PG8_BAR; PG8_MMA(1, 1, At, B1); PG8_BAR;
	s_waitcnt lgkmcnt(0)
	s_waitcnt lgkmcnt(0)
	v_mfma_f32_16x16x32_bf16 v[124:127], v[128:131], v[144:147], v[124:127]
	v_mfma_f32_16x16x32_bf16 v[120:123], v[136:139], v[144:147], v[120:123]
	v_mfma_f32_16x16x32_bf16 v[108:111], v[128:131], v[152:155], v[108:111]
	v_mfma_f32_16x16x32_bf16 v[104:107], v[136:139], v[152:155], v[104:107]
	v_mfma_f32_16x16x32_bf16 v[92:95], v[128:131], v[160:163], v[92:95]
	v_mfma_f32_16x16x32_bf16 v[88:91], v[136:139], v[160:163], v[88:91]
	v_mfma_f32_16x16x32_bf16 v[76:79], v[128:131], v[168:171], v[76:79]
	v_mfma_f32_16x16x32_bf16 v[72:75], v[136:139], v[168:171], v[72:75]
	v_mfma_f32_16x16x32_bf16 v[124:127], v[132:135], v[148:151], v[124:127]
	v_mfma_f32_16x16x32_bf16 v[120:123], v[140:143], v[148:151], v[120:123]
	v_mfma_f32_16x16x32_bf16 v[108:111], v[132:135], v[156:159], v[108:111]
	v_mfma_f32_16x16x32_bf16 v[104:107], v[140:143], v[156:159], v[104:107]
	v_mfma_f32_16x16x32_bf16 v[92:95], v[132:135], v[164:167], v[92:95]
	v_mfma_f32_16x16x32_bf16 v[88:91], v[140:143], v[164:167], v[88:91]
	v_mfma_f32_16x16x32_bf16 v[76:79], v[132:135], v[172:175], v[76:79]
	v_mfma_f32_16x16x32_bf16 v[72:75], v[140:143], v[172:175], v[72:75]
	s_setprio 0
	s_barrier
	s_add_i32 s28, 0, 0x1c000
	s_add_i32 s22, s57, s34
	v_add_u32_e32 v206, s28, v240
	s_add_u32 s0, s26, 0x80
	s_addc_u32 s1, s27, 0
	s_mov_b32 m0, s22
	ds_read_b128 v[176:179], v206
	ds_read_b128 v[180:183], v206 offset:1024
	ds_read_b128 v[184:187], v206 offset:2048
	ds_read_b128 v[206:209], v206 offset:3072
	global_load_lds_dwordx4 v190, s[0:1]
	s_add_i32 m0, s22, 0x2000
	s_nop 0
	global_load_lds_dwordx4 v194, s[0:1]
	s_waitcnt vmcnt(8)
	s_setprio 1
	s_barrier
	s_waitcnt lgkmcnt(0)
	s_waitcnt lgkmcnt(0)
	v_mfma_f32_16x16x32_bf16 v[116:119], v[176:179], v[144:147], v[116:119]
	v_mfma_f32_16x16x32_bf16 v[112:115], v[184:187], v[144:147], v[112:115]
	v_mfma_f32_16x16x32_bf16 v[100:103], v[176:179], v[152:155], v[100:103]
	v_mfma_f32_16x16x32_bf16 v[96:99], v[184:187], v[152:155], v[96:99]
	v_mfma_f32_16x16x32_bf16 v[84:87], v[176:179], v[160:163], v[84:87]
	v_mfma_f32_16x16x32_bf16 v[80:83], v[184:187], v[160:163], v[80:83]
	v_mfma_f32_16x16x32_bf16 v[68:71], v[176:179], v[168:171], v[68:71]
	v_mfma_f32_16x16x32_bf16 v[64:67], v[184:187], v[168:171], v[64:67]
	v_mfma_f32_16x16x32_bf16 v[116:119], v[180:183], v[148:151], v[116:119]
	v_mfma_f32_16x16x32_bf16 v[112:115], v[206:209], v[148:151], v[112:115]
	v_mfma_f32_16x16x32_bf16 v[100:103], v[180:183], v[156:159], v[100:103]
	v_mfma_f32_16x16x32_bf16 v[96:99], v[206:209], v[156:159], v[96:99]
	v_mfma_f32_16x16x32_bf16 v[84:87], v[180:183], v[164:167], v[84:87]
	v_mfma_f32_16x16x32_bf16 v[80:83], v[206:209], v[164:167], v[80:83]
	v_mfma_f32_16x16x32_bf16 v[68:71], v[180:183], v[172:175], v[68:71]
	v_mfma_f32_16x16x32_bf16 v[64:67], v[206:209], v[172:175], v[64:67]
	s_setprio 0
	s_mov_b32 m0, s44
	s_mov_b64 s[0:1], 0x80
	v_lshl_add_u64 v[210:211], v[214:215], 0, s[0:1]
	s_barrier
	ds_read_b128 v[144:147], v242 offset:49152
	ds_read_b128 v[148:151], v242 offset:50176
	ds_read_b128 v[152:155], v242 offset:51200
	ds_read_b128 v[156:159], v242 offset:52224
	ds_read_b128 v[160:163], v242 offset:53248
	ds_read_b128 v[164:167], v242 offset:54272
	ds_read_b128 v[168:171], v242 offset:55296
	ds_read_b128 v[172:175], v242 offset:56320
	global_load_lds_dwordx4 v[210:211], off
	v_lshl_add_u64 v[210:211], v[216:217], 0, s[0:1]
	s_mov_b32 m0, s45
	s_nop 0
	global_load_lds_dwordx4 v[210:211], off
	s_setprio 1
	s_barrier
	s_waitcnt lgkmcnt(0)
	s_waitcnt lgkmcnt(0)
	v_mfma_f32_16x16x32_bf16 v[60:63], v[128:131], v[144:147], v[60:63]
	v_mfma_f32_16x16x32_bf16 v[56:59], v[136:139], v[144:147], v[56:59]
	v_mfma_f32_16x16x32_bf16 v[44:47], v[128:131], v[152:155], v[44:47]
	v_mfma_f32_16x16x32_bf16 v[40:43], v[136:139], v[152:155], v[40:43]
	v_mfma_f32_16x16x32_bf16 v[28:31], v[128:131], v[160:163], v[28:31]
	v_mfma_f32_16x16x32_bf16 v[24:27], v[136:139], v[160:163], v[24:27]
	v_mfma_f32_16x16x32_bf16 v[12:15], v[128:131], v[168:171], v[12:15]
	v_mfma_f32_16x16x32_bf16 v[8:11], v[136:139], v[168:171], v[8:11]
	v_mfma_f32_16x16x32_bf16 v[60:63], v[132:135], v[148:151], v[60:63]
	v_mfma_f32_16x16x32_bf16 v[56:59], v[140:143], v[148:151], v[56:59]
	v_mfma_f32_16x16x32_bf16 v[44:47], v[132:135], v[156:159], v[44:47]
	v_mfma_f32_16x16x32_bf16 v[40:43], v[140:143], v[156:159], v[40:43]
	v_mfma_f32_16x16x32_bf16 v[28:31], v[132:135], v[164:167], v[28:31]
	v_mfma_f32_16x16x32_bf16 v[24:27], v[140:143], v[164:167], v[24:27]
	v_mfma_f32_16x16x32_bf16 v[12:15], v[132:135], v[172:175], v[12:15]
	v_mfma_f32_16x16x32_bf16 v[8:11], v[140:143], v[172:175], v[8:11]
	s_setprio 0
	s_barrier
	s_add_u32 s22, s26, 0xb0080
	s_addc_u32 s23, s27, 0
	s_add_i32 s26, s28, s34
	s_mov_b32 m0, s26
	s_nop 0
	global_load_lds_dwordx4 v190, s[22:23]
	s_add_i32 m0, s26, 0x2000
	s_nop 0
	global_load_lds_dwordx4 v194, s[22:23]
	s_waitcnt vmcnt(8)
	s_setprio 1
	s_barrier
	v_mfma_f32_16x16x32_bf16 v[52:55], v[176:179], v[144:147], v[52:55]
	v_mfma_f32_16x16x32_bf16 v[48:51], v[184:187], v[144:147], v[48:51]
	v_mfma_f32_16x16x32_bf16 v[36:39], v[176:179], v[152:155], v[36:39]
	v_mfma_f32_16x16x32_bf16 v[32:35], v[184:187], v[152:155], v[32:35]
	v_mfma_f32_16x16x32_bf16 v[20:23], v[176:179], v[160:163], v[20:23]
	v_mfma_f32_16x16x32_bf16 v[16:19], v[184:187], v[160:163], v[16:19]
	v_mfma_f32_16x16x32_bf16 v[4:7], v[176:179], v[168:171], v[4:7]
	v_mfma_f32_16x16x32_bf16 v[0:3], v[184:187], v[168:171], v[0:3]
	v_mfma_f32_16x16x32_bf16 v[52:55], v[180:183], v[148:151], v[52:55]
	v_mfma_f32_16x16x32_bf16 v[48:51], v[206:209], v[148:151], v[48:51]
	v_mfma_f32_16x16x32_bf16 v[36:39], v[180:183], v[156:159], v[36:39]
	v_mfma_f32_16x16x32_bf16 v[32:35], v[206:209], v[156:159], v[32:35]
	v_mfma_f32_16x16x32_bf16 v[20:23], v[180:183], v[164:167], v[20:23]
	v_mfma_f32_16x16x32_bf16 v[16:19], v[206:209], v[164:167], v[16:19]
	v_mfma_f32_16x16x32_bf16 v[4:7], v[180:183], v[172:175], v[4:7]
	v_mfma_f32_16x16x32_bf16 v[0:3], v[206:209], v[172:175], v[0:3]
	s_setprio 0
	s_add_i32 s56, s56, 2
	s_add_u32 s54, s54, 0x100
	s_addc_u32 s55, s55, 0
	s_cmp_gt_u32 s56, 41
	s_mov_b64 s[22:23], s[24:25]
	s_barrier
; __device__ __forceinline__ unsigned cvt_pk_bf16(float lo, float hi) { unsigned r; asm volatile("v_cvt_pk_bf16_f32 %0, %1, %2" : "=v"(r) : "v"(lo), "v"(hi)); return r; }
; __device__ __forceinline__ float bf_lo(unsigned u) { return __uint_as_float(u << 16); }
; __device__ __forceinline__ float bf_hi(unsigned u) { return __uint_as_float(u & 0xffff0000u); }
;     __device__ __forceinline__ void operator()(const AccT& acc, const Unit& u, int wr, int wc, int fr, int fq) const {
;     ...
;         const int rowt = u.pm * 256; const int b = rowt >> 11;
;         const bf16_t* res = res_b + (size_t)rowt * DM; bf16_t* out = hb + (size_t)rowt * DM;
;         const int col0 = u.pn * 256 + wc * 32 + 8 * fq;
;         f32x4 gv[2][2];
; #pragma unroll
;         for (int bj = 0; bj < 2; ++bj)
; #pragma unroll
;             for (int n = 0; n < 2; ++n) gv[bj][n] = *(const f32x4*)(gate + (size_t)b * NMOD + col0 + bj * 128 + n * 4) * gs;
;         u32x4 r[2][4][2];
; #pragma unroll
;         for (int ai = 0; ai < 2; ++ai)
; #pragma unroll
;             for (int m = 0; m < 4; ++m)
; #pragma unroll
;                 for (int bj = 0; bj < 2; ++bj) r[ai][m][bj] = *(const u32x4*)(res + (size_t)(wr * 64 + fr + ai * 128 + m * 16) * DM + col0 + bj * 128);
; #pragma unroll
;         for (int ai = 0; ai < 2; ++ai)
; #pragma unroll
;             for (int m = 0; m < 4; ++m)
; #pragma unroll
;                 for (int bj = 0; bj < 2; ++bj) {
;                     const u32x4 q = r[ai][m][bj];
;                     const f32x4 r0 = {bf_lo(q.x), bf_hi(q.x), bf_lo(q.y), bf_hi(q.y)}, r1 = {bf_lo(q.z), bf_hi(q.z), bf_lo(q.w), bf_hi(q.w)};
;                     const f32x4 h0 = r0 + gv[bj][0] * acc[ai][bj][m][0], h1 = r1 + gv[bj][1] * acc[ai][bj][m][1];
;                     u32x4 w; w.x = cvt_pk_bf16(h0[0], h0[1]); w.y = cvt_pk_bf16(h0[2], h0[3]); w.z = cvt_pk_bf16(h1[0], h1[1]); w.w = cvt_pk_bf16(h1[2], h1[3]);
	s_cbranch_scc0 .LBB0_1097
	s_lshl_b32 s25, s52, 8
	v_mov_b32_e32 v140, v239
	v_mov_b32_e32 v128, v238
	s_lshl_b32 s22, s53, 8
	s_ashr_i32 s24, s53, 3
	s_or_b32 s25, s25, s43
	s_ashr_i32 s23, s22, 31
	v_lshl_add_u32 v136, v128, 3, s25
	s_mul_hi_i32 s25, s24, 0x9000
	s_mul_i32 s24, s24, 0x9000
	s_add_u32 s24, s40, s24
	s_addc_u32 s25, s41, s25
	v_ashrrev_i32_e32 v137, 31, v136
	v_lshl_add_u64 v[138:139], v[136:137], 2, s[24:25]
	global_load_dwordx4 v[128:131], v[138:139], off offset:16
	global_load_dwordx4 v[132:135], v[138:139], off
	s_lshl_b64 s[22:23], s[22:23], 11
	s_add_u32 s24, s80, s22
	s_addc_u32 s25, s81, s23
	v_lshlrev_b64 v[226:227], 1, v[136:137]
	s_add_u32 s22, s96, s22
	s_addc_u32 s23, s97, s23
	s_and_b64 vcc, exec, s[2:3]
	s_mov_b32 s52, s50
	s_mov_b32 s53, s51
	s_waitcnt vmcnt(0)
	v_pk_mul_f32 v[216:217], v[130:131], 0.5 op_sel_hi:[1,0]
	v_pk_mul_f32 v[220:221], v[134:135], 0.5 op_sel_hi:[1,0]
	v_pk_mul_f32 v[218:219], v[132:133], 0.5 op_sel_hi:[1,0]
	v_pk_mul_f32 v[214:215], v[128:129], 0.5 op_sel_hi:[1,0]
	global_load_dwordx4 v[128:131], v[138:139], off offset:528
	global_load_dwordx4 v[132:135], v[138:139], off offset:512
	s_waitcnt vmcnt(0)
	v_pk_mul_f32 v[206:207], v[128:129], 0.5 op_sel_hi:[1,0]
	v_add_u32_e32 v128, s42, v140
	v_ashrrev_i32_e32 v129, 31, v128
	v_pk_mul_f32 v[208:209], v[130:131], 0.5 op_sel_hi:[1,0]
	v_lshl_add_u64 v[130:131], s[24:25], 0, v[226:227]
	v_lshlrev_b64 v[248:249], 11, v[128:129]
	v_lshl_add_u64 v[128:129], v[130:131], 0, v[248:249]
	global_load_dwordx4 v[244:247], v[128:129], off
	global_load_dwordx4 v[184:187], v[128:129], off offset:256
	v_lshl_add_u64 v[236:237], v[248:249], 0, s[8:9]
	v_lshl_add_u64 v[128:129], v[130:131], 0, v[236:237]
	global_load_dwordx4 v[180:183], v[128:129], off
	global_load_dwordx4 v[176:179], v[128:129], off offset:256
	v_lshl_add_u64 v[234:235], v[248:249], 0, s[10:11]
	v_lshl_add_u64 v[128:129], v[130:131], 0, v[234:235]
	global_load_dwordx4 v[172:175], v[128:129], off
	global_load_dwordx4 v[168:171], v[128:129], off offset:256
	v_lshl_add_u64 v[232:233], v[248:249], 0, s[12:13]
	v_lshl_add_u64 v[128:129], v[130:131], 0, v[232:233]
	global_load_dwordx4 v[164:167], v[128:129], off
	global_load_dwordx4 v[160:163], v[128:129], off offset:256
	v_lshl_add_u64 v[230:231], v[248:249], 0, s[14:15]
	v_lshl_add_u64 v[128:129], v[130:131], 0, v[230:231]
	global_load_dwordx4 v[156:159], v[128:129], off
	global_load_dwordx4 v[152:155], v[128:129], off offset:256
	v_lshl_add_u64 v[228:229], v[248:249], 0, s[16:17]
	v_lshl_add_u64 v[128:129], v[130:131], 0, v[228:229]
	global_load_dwordx4 v[148:151], v[128:129], off
	global_load_dwordx4 v[144:147], v[128:129], off offset:256
	v_lshl_add_u64 v[224:225], v[248:249], 0, s[18:19]
	v_lshl_add_u64 v[128:129], v[130:131], 0, v[224:225]
	global_load_dwordx4 v[140:143], v[128:129], off
	global_load_dwordx4 v[136:139], v[128:129], off offset:256
	v_lshl_add_u64 v[222:223], v[248:249], 0, s[20:21]
	v_lshl_add_u64 v[128:129], v[130:131], 0, v[222:223]
	v_pk_mul_f32 v[212:213], v[134:135], 0.5 op_sel_hi:[1,0]
	v_pk_mul_f32 v[210:211], v[132:133], 0.5 op_sel_hi:[1,0]
	global_load_dwordx4 v[132:135], v[128:129], off
	s_nop 0
	global_load_dwordx4 v[128:131], v[128:129], off offset:256
	v_lshl_add_u64 v[226:227], s[22:23], 0, v[226:227]
	v_lshl_add_u64 v[248:249], v[226:227], 0, v[248:249]
	s_mov_b64 s[24:25], s[6:7]
	s_mov_b64 s[22:23], s[4:5]
	s_waitcnt vmcnt(0)
	v_lshlrev_b32_e32 v250, 16, v244
	v_and_b32_e32 v251, 0xffff0000, v244
	v_lshlrev_b32_e32 v244, 16, v245
	v_and_b32_e32 v245, 0xffff0000, v245
	v_lshlrev_b32_e32 v252, 16, v246
	v_and_b32_e32 v253, 0xffff0000, v246
	v_lshlrev_b32_e32 v246, 16, v247
	v_and_b32_e32 v247, 0xffff0000, v247
	v_pk_fma_f32 v[126:127], v[126:127], v[220:221], v[244:245]
	v_pk_fma_f32 v[124:125], v[124:125], v[218:219], v[250:251]
	v_pk_fma_f32 v[244:245], v[122:123], v[216:217], v[246:247]
	v_pk_fma_f32 v[122:123], v[120:121], v[214:215], v[252:253]
	v_cvt_pk_bf16_f32 v120, v124, v125
	v_cvt_pk_bf16_f32 v121, v126, v127
	v_lshlrev_b32_e32 v124, 16, v186
	v_cvt_pk_bf16_f32 v122, v122, v123
	v_cvt_pk_bf16_f32 v123, v244, v245
	global_store_dwordx4 v[248:249], v[120:123], off
	v_and_b32_e32 v125, 0xffff0000, v186
	v_lshlrev_b32_e32 v126, 16, v187
	v_lshlrev_b32_e32 v120, 16, v184
	v_and_b32_e32 v121, 0xffff0000, v184
	v_and_b32_e32 v127, 0xffff0000, v187
	v_lshlrev_b32_e32 v122, 16, v185
	v_and_b32_e32 v123, 0xffff0000, v185
	v_pk_fma_f32 v[116:117], v[116:117], v[210:211], v[120:121]
	v_pk_fma_f32 v[120:121], v[114:115], v[208:209], v[126:127]
	v_pk_fma_f32 v[114:115], v[112:113], v[206:207], v[124:125]
	v_pk_fma_f32 v[118:119], v[118:119], v[212:213], v[122:123]
	v_cvt_pk_bf16_f32 v112, v116, v117
	v_lshlrev_b32_e32 v116, 16, v181
	v_cvt_pk_bf16_f32 v113, v118, v119
	v_cvt_pk_bf16_f32 v114, v114, v115
	v_cvt_pk_bf16_f32 v115, v120, v121
	global_store_dwordx4 v[248:249], v[112:115], off offset:256
	v_and_b32_e32 v117, 0xffff0000, v181
	v_lshlrev_b32_e32 v118, 16, v182
	v_lshlrev_b32_e32 v114, 16, v180
	v_and_b32_e32 v115, 0xffff0000, v180
	v_and_b32_e32 v119, 0xffff0000, v182
	v_lshlrev_b32_e32 v120, 16, v183
	v_and_b32_e32 v121, 0xffff0000, v183
	v_lshl_add_u64 v[112:113], v[226:227], 0, v[236:237]
	v_pk_fma_f32 v[110:111], v[110:111], v[220:221], v[116:117]
	v_pk_fma_f32 v[108:109], v[108:109], v[218:219], v[114:115]
	v_pk_fma_f32 v[114:115], v[106:107], v[216:217], v[120:121]
	v_pk_fma_f32 v[106:107], v[104:105], v[214:215], v[118:119]
	v_cvt_pk_bf16_f32 v104, v108, v109
	v_cvt_pk_bf16_f32 v105, v110, v111
	v_lshlrev_b32_e32 v108, 16, v178
	v_cvt_pk_bf16_f32 v106, v106, v107
	v_cvt_pk_bf16_f32 v107, v114, v115
; __device__ __forceinline__ unsigned cvt_pk_bf16(float lo, float hi) { unsigned r; asm volatile("v_cvt_pk_bf16_f32 %0, %1, %2" : "=v"(r) : "v"(lo), "v"(hi)); return r; }
; __device__ __forceinline__ float bf_lo(unsigned u) { return __uint_as_float(u << 16); }
; __device__ __forceinline__ float bf_hi(unsigned u) { return __uint_as_float(u & 0xffff0000u); }
;     __device__ __forceinline__ void operator()(const AccT& acc, const Unit& u, int wr, int wc, int fr, int fq) const {
;     ...
;         for (int ai = 0; ai < 2; ++ai)
; #pragma unroll
;             for (int m = 0; m < 4; ++m)
; #pragma unroll
;                 for (int bj = 0; bj < 2; ++bj) {
;                     const u32x4 q = r[ai][m][bj];
;                     const f32x4 r0 = {bf_lo(q.x), bf_hi(q.x), bf_lo(q.y), bf_hi(q.y)}, r1 = {bf_lo(q.z), bf_hi(q.z), bf_lo(q.w), bf_hi(q.w)};
;                     const f32x4 h0 = r0 + gv[bj][0] * acc[ai][bj][m][0], h1 = r1 + gv[bj][1] * acc[ai][bj][m][1];
;                     u32x4 w; w.x = cvt_pk_bf16(h0[0], h0[1]); w.y = cvt_pk_bf16(h0[2], h0[3]); w.z = cvt_pk_bf16(h1[0], h1[1]); w.w = cvt_pk_bf16(h1[2], h1[3]);
;                     *(u32x4*)(out + (size_t)(wr * 64 + fr + ai * 128 + m * 16) * DM + col0 + bj * 128) = w;
;                 }
	global_store_dwordx4 v[112:113], v[104:107], off
	v_and_b32_e32 v109, 0xffff0000, v178
	v_lshlrev_b32_e32 v110, 16, v179
	v_lshlrev_b32_e32 v104, 16, v176
	v_and_b32_e32 v105, 0xffff0000, v176
	v_and_b32_e32 v111, 0xffff0000, v179
	v_lshlrev_b32_e32 v106, 16, v177
	v_and_b32_e32 v107, 0xffff0000, v177
	v_pk_fma_f32 v[100:101], v[100:101], v[210:211], v[104:105]
	v_pk_fma_f32 v[104:105], v[98:99], v[208:209], v[110:111]
	v_pk_fma_f32 v[98:99], v[96:97], v[206:207], v[108:109]
	v_pk_fma_f32 v[102:103], v[102:103], v[212:213], v[106:107]
	v_cvt_pk_bf16_f32 v96, v100, v101
	v_lshlrev_b32_e32 v100, 16, v173
	v_cvt_pk_bf16_f32 v97, v102, v103
	v_cvt_pk_bf16_f32 v98, v98, v99
	v_cvt_pk_bf16_f32 v99, v104, v105
	global_store_dwordx4 v[112:113], v[96:99], off offset:256
	v_and_b32_e32 v101, 0xffff0000, v173
	v_lshlrev_b32_e32 v102, 16, v174
	v_lshlrev_b32_e32 v98, 16, v172
	v_and_b32_e32 v99, 0xffff0000, v172
	v_and_b32_e32 v103, 0xffff0000, v174
	v_lshlrev_b32_e32 v104, 16, v175
	v_and_b32_e32 v105, 0xffff0000, v175
	v_lshl_add_u64 v[96:97], v[226:227], 0, v[234:235]
	v_pk_fma_f32 v[94:95], v[94:95], v[220:221], v[100:101]
	v_pk_fma_f32 v[92:93], v[92:93], v[218:219], v[98:99]
	v_pk_fma_f32 v[98:99], v[90:91], v[216:217], v[104:105]
	v_pk_fma_f32 v[90:91], v[88:89], v[214:215], v[102:103]
	v_cvt_pk_bf16_f32 v88, v92, v93
	v_cvt_pk_bf16_f32 v89, v94, v95
	v_lshlrev_b32_e32 v92, 16, v170
	v_cvt_pk_bf16_f32 v90, v90, v91
	v_cvt_pk_bf16_f32 v91, v98, v99
	global_store_dwordx4 v[96:97], v[88:91], off
	v_and_b32_e32 v93, 0xffff0000, v170
	v_lshlrev_b32_e32 v94, 16, v171
	v_lshlrev_b32_e32 v88, 16, v168
	v_and_b32_e32 v89, 0xffff0000, v168
	v_and_b32_e32 v95, 0xffff0000, v171
	v_lshlrev_b32_e32 v90, 16, v169
	v_and_b32_e32 v91, 0xffff0000, v169
	v_pk_fma_f32 v[84:85], v[84:85], v[210:211], v[88:89]
	v_pk_fma_f32 v[88:89], v[82:83], v[208:209], v[94:95]
	v_pk_fma_f32 v[82:83], v[80:81], v[206:207], v[92:93]
	v_pk_fma_f32 v[86:87], v[86:87], v[212:213], v[90:91]
	v_cvt_pk_bf16_f32 v80, v84, v85
	v_lshlrev_b32_e32 v84, 16, v165
	v_cvt_pk_bf16_f32 v81, v86, v87
	v_cvt_pk_bf16_f32 v82, v82, v83
	v_cvt_pk_bf16_f32 v83, v88, v89
	global_store_dwordx4 v[96:97], v[80:83], off offset:256
	v_and_b32_e32 v85, 0xffff0000, v165
	v_lshlrev_b32_e32 v86, 16, v166
	v_lshlrev_b32_e32 v82, 16, v164
	v_and_b32_e32 v83, 0xffff0000, v164
	v_and_b32_e32 v87, 0xffff0000, v166
	v_lshlrev_b32_e32 v88, 16, v167
	v_and_b32_e32 v89, 0xffff0000, v167
	v_lshl_add_u64 v[80:81], v[226:227], 0, v[232:233]
	v_pk_fma_f32 v[78:79], v[78:79], v[220:221], v[84:85]
	v_pk_fma_f32 v[76:77], v[76:77], v[218:219], v[82:83]
	v_pk_fma_f32 v[82:83], v[74:75], v[216:217], v[88:89]
	v_pk_fma_f32 v[74:75], v[72:73], v[214:215], v[86:87]
	v_cvt_pk_bf16_f32 v72, v76, v77
	v_cvt_pk_bf16_f32 v73, v78, v79
	v_lshlrev_b32_e32 v76, 16, v162
	v_cvt_pk_bf16_f32 v74, v74, v75
	v_cvt_pk_bf16_f32 v75, v82, v83
	global_store_dwordx4 v[80:81], v[72:75], off
	v_and_b32_e32 v77, 0xffff0000, v162
	v_lshlrev_b32_e32 v78, 16, v163
	v_lshlrev_b32_e32 v72, 16, v160
	v_and_b32_e32 v73, 0xffff0000, v160
	v_and_b32_e32 v79, 0xffff0000, v163
	v_lshlrev_b32_e32 v74, 16, v161
	v_and_b32_e32 v75, 0xffff0000, v161
	v_pk_fma_f32 v[68:69], v[68:69], v[210:211], v[72:73]
	v_pk_fma_f32 v[72:73], v[66:67], v[208:209], v[78:79]
	v_pk_fma_f32 v[66:67], v[64:65], v[206:207], v[76:77]
	v_pk_fma_f32 v[70:71], v[70:71], v[212:213], v[74:75]
	v_cvt_pk_bf16_f32 v64, v68, v69
	v_lshlrev_b32_e32 v68, 16, v157
	v_cvt_pk_bf16_f32 v65, v70, v71
	v_cvt_pk_bf16_f32 v66, v66, v67
	v_cvt_pk_bf16_f32 v67, v72, v73
	global_store_dwordx4 v[80:81], v[64:67], off offset:256
	v_and_b32_e32 v69, 0xffff0000, v157
	v_lshlrev_b32_e32 v70, 16, v158
	v_lshlrev_b32_e32 v66, 16, v156
	v_and_b32_e32 v67, 0xffff0000, v156
	v_and_b32_e32 v71, 0xffff0000, v158
	v_lshlrev_b32_e32 v72, 16, v159
	v_and_b32_e32 v73, 0xffff0000, v159
	v_lshl_add_u64 v[64:65], v[226:227], 0, v[230:231]
	v_pk_fma_f32 v[62:63], v[62:63], v[220:221], v[68:69]
	v_pk_fma_f32 v[60:61], v[60:61], v[218:219], v[66:67]
	v_pk_fma_f32 v[66:67], v[58:59], v[216:217], v[72:73]
	v_pk_fma_f32 v[58:59], v[56:57], v[214:215], v[70:71]
	v_cvt_pk_bf16_f32 v56, v60, v61
	v_cvt_pk_bf16_f32 v57, v62, v63
	v_lshlrev_b32_e32 v60, 16, v154
	v_cvt_pk_bf16_f32 v58, v58, v59
	v_cvt_pk_bf16_f32 v59, v66, v67
	global_store_dwordx4 v[64:65], v[56:59], off
	v_and_b32_e32 v61, 0xffff0000, v154
	v_lshlrev_b32_e32 v62, 16, v155
	v_lshlrev_b32_e32 v56, 16, v152
	v_and_b32_e32 v57, 0xffff0000, v152
	v_and_b32_e32 v63, 0xffff0000, v155
	v_lshlrev_b32_e32 v58, 16, v153
	v_and_b32_e32 v59, 0xffff0000, v153
	v_pk_fma_f32 v[52:53], v[52:53], v[210:211], v[56:57]
; __device__ __forceinline__ unsigned cvt_pk_bf16(float lo, float hi) { unsigned r; asm volatile("v_cvt_pk_bf16_f32 %0, %1, %2" : "=v"(r) : "v"(lo), "v"(hi)); return r; }
; __device__ __forceinline__ float bf_lo(unsigned u) { return __uint_as_float(u << 16); }
; __device__ __forceinline__ float bf_hi(unsigned u) { return __uint_as_float(u & 0xffff0000u); }
; #define PG8_WAIT_V(n) asm volatile("s_waitcnt vmcnt(" #n ")" ::: "memory")
; #define PG8_BAR __builtin_amdgcn_s_barrier()
; template <class Epi, class Sched>
; __device__ __forceinline__ void gemm_phase(LAS unsigned char* lds, const Gemm g, const Sched& S, const Epi& E) {
;     ...
;         if (!has_next) break;
; #pragma unroll
;         for (int a = 0; a < 2; ++a)
; #pragma unroll
;             for (int b = 0; b < 2; ++b)
; #pragma unroll
;                 for (int m = 0; m < 4; ++m)
; #pragma unroll
;                     for (int n = 0; n < 2; ++n) acc[a][b][m][n] = (f32x4){0.f, 0.f, 0.f, 0.f};
;         cur = nxt; cA = nA; cB = nB; ++ui;
;     }
;     PG8_WAIT_V(0);
;     if (wr == 0) PG8_BAR;
;     PG8_BAR;
;     __device__ __forceinline__ void operator()(const AccT& acc, const Unit& u, int wr, int wc, int fr, int fq) const {
;     ...
;                 for (int bj = 0; bj < 2; ++bj) {
;                     const u32x4 q = r[ai][m][bj];
;                     const f32x4 r0 = {bf_lo(q.x), bf_hi(q.x), bf_lo(q.y), bf_hi(q.y)}, r1 = {bf_lo(q.z), bf_hi(q.z), bf_lo(q.w), bf_hi(q.w)};
;                     const f32x4 h0 = r0 + gv[bj][0] * acc[ai][bj][m][0], h1 = r1 + gv[bj][1] * acc[ai][bj][m][1];
;                     u32x4 w; w.x = cvt_pk_bf16(h0[0], h0[1]); w.y = cvt_pk_bf16(h0[2], h0[3]); w.z = cvt_pk_bf16(h1[0], h1[1]); w.w = cvt_pk_bf16(h1[2], h1[3]);
;                     *(u32x4*)(out + (size_t)(wr * 64 + fr + ai * 128 + m * 16) * DM + col0 + bj * 128) = w;
;                 }
	v_pk_fma_f32 v[56:57], v[50:51], v[208:209], v[62:63]
	v_pk_fma_f32 v[50:51], v[48:49], v[206:207], v[60:61]
	v_pk_fma_f32 v[54:55], v[54:55], v[212:213], v[58:59]
	v_cvt_pk_bf16_f32 v48, v52, v53
	v_lshlrev_b32_e32 v52, 16, v149
	v_cvt_pk_bf16_f32 v49, v54, v55
	v_cvt_pk_bf16_f32 v50, v50, v51
	v_cvt_pk_bf16_f32 v51, v56, v57
	global_store_dwordx4 v[64:65], v[48:51], off offset:256
	v_and_b32_e32 v53, 0xffff0000, v149
	v_lshlrev_b32_e32 v54, 16, v150
	v_lshlrev_b32_e32 v50, 16, v148
	v_and_b32_e32 v51, 0xffff0000, v148
	v_and_b32_e32 v55, 0xffff0000, v150
	v_lshlrev_b32_e32 v56, 16, v151
	v_and_b32_e32 v57, 0xffff0000, v151
	v_lshl_add_u64 v[48:49], v[226:227], 0, v[228:229]
	v_pk_fma_f32 v[46:47], v[46:47], v[220:221], v[52:53]
	v_pk_fma_f32 v[44:45], v[44:45], v[218:219], v[50:51]
	v_pk_fma_f32 v[50:51], v[42:43], v[216:217], v[56:57]
	v_pk_fma_f32 v[42:43], v[40:41], v[214:215], v[54:55]
	v_cvt_pk_bf16_f32 v40, v44, v45
	v_cvt_pk_bf16_f32 v41, v46, v47
	v_lshlrev_b32_e32 v44, 16, v146
	v_cvt_pk_bf16_f32 v42, v42, v43
	v_cvt_pk_bf16_f32 v43, v50, v51
	global_store_dwordx4 v[48:49], v[40:43], off
	v_and_b32_e32 v45, 0xffff0000, v146
	v_lshlrev_b32_e32 v46, 16, v147
	v_lshlrev_b32_e32 v40, 16, v144
	v_and_b32_e32 v41, 0xffff0000, v144
	v_and_b32_e32 v47, 0xffff0000, v147
	v_lshlrev_b32_e32 v42, 16, v145
	v_and_b32_e32 v43, 0xffff0000, v145
	v_pk_fma_f32 v[36:37], v[36:37], v[210:211], v[40:41]
	v_pk_fma_f32 v[40:41], v[34:35], v[208:209], v[46:47]
	v_pk_fma_f32 v[34:35], v[32:33], v[206:207], v[44:45]
	v_pk_fma_f32 v[38:39], v[38:39], v[212:213], v[42:43]
	v_cvt_pk_bf16_f32 v32, v36, v37
	v_lshlrev_b32_e32 v36, 16, v141
	v_cvt_pk_bf16_f32 v33, v38, v39
	v_cvt_pk_bf16_f32 v34, v34, v35
	v_cvt_pk_bf16_f32 v35, v40, v41
	global_store_dwordx4 v[48:49], v[32:35], off offset:256
	v_and_b32_e32 v37, 0xffff0000, v141
	v_lshlrev_b32_e32 v38, 16, v142
	v_lshlrev_b32_e32 v34, 16, v140
	v_and_b32_e32 v35, 0xffff0000, v140
	v_and_b32_e32 v39, 0xffff0000, v142
	v_lshlrev_b32_e32 v40, 16, v143
	v_and_b32_e32 v41, 0xffff0000, v143
	v_lshl_add_u64 v[32:33], v[226:227], 0, v[224:225]
	v_pk_fma_f32 v[30:31], v[30:31], v[220:221], v[36:37]
	v_pk_fma_f32 v[28:29], v[28:29], v[218:219], v[34:35]
	v_pk_fma_f32 v[34:35], v[26:27], v[216:217], v[40:41]
	v_pk_fma_f32 v[26:27], v[24:25], v[214:215], v[38:39]
	v_cvt_pk_bf16_f32 v24, v28, v29
	v_cvt_pk_bf16_f32 v25, v30, v31
	v_lshlrev_b32_e32 v28, 16, v138
	v_cvt_pk_bf16_f32 v26, v26, v27
	v_cvt_pk_bf16_f32 v27, v34, v35
	global_store_dwordx4 v[32:33], v[24:27], off
	v_and_b32_e32 v29, 0xffff0000, v138
	v_lshlrev_b32_e32 v30, 16, v139
	v_lshlrev_b32_e32 v24, 16, v136
	v_and_b32_e32 v25, 0xffff0000, v136
	v_and_b32_e32 v31, 0xffff0000, v139
	v_lshlrev_b32_e32 v26, 16, v137
	v_and_b32_e32 v27, 0xffff0000, v137
	v_pk_fma_f32 v[20:21], v[20:21], v[210:211], v[24:25]
	v_pk_fma_f32 v[24:25], v[18:19], v[208:209], v[30:31]
	v_pk_fma_f32 v[18:19], v[16:17], v[206:207], v[28:29]
	v_pk_fma_f32 v[22:23], v[22:23], v[212:213], v[26:27]
	v_cvt_pk_bf16_f32 v16, v20, v21
	v_lshlrev_b32_e32 v20, 16, v133
	v_cvt_pk_bf16_f32 v17, v22, v23
	v_cvt_pk_bf16_f32 v18, v18, v19
	v_cvt_pk_bf16_f32 v19, v24, v25
	global_store_dwordx4 v[32:33], v[16:19], off offset:256
	v_and_b32_e32 v21, 0xffff0000, v133
	v_lshlrev_b32_e32 v22, 16, v134
	v_lshlrev_b32_e32 v18, 16, v132
	v_and_b32_e32 v19, 0xffff0000, v132
	v_and_b32_e32 v23, 0xffff0000, v134
	v_lshlrev_b32_e32 v24, 16, v135
	v_and_b32_e32 v25, 0xffff0000, v135
	v_lshl_add_u64 v[16:17], v[226:227], 0, v[222:223]
	v_pk_fma_f32 v[14:15], v[14:15], v[220:221], v[20:21]
	v_pk_fma_f32 v[12:13], v[12:13], v[218:219], v[18:19]
	v_pk_fma_f32 v[18:19], v[10:11], v[216:217], v[24:25]
	v_pk_fma_f32 v[10:11], v[8:9], v[214:215], v[22:23]
	v_cvt_pk_bf16_f32 v8, v12, v13
	v_cvt_pk_bf16_f32 v9, v14, v15
	v_lshlrev_b32_e32 v12, 16, v130
	v_cvt_pk_bf16_f32 v10, v10, v11
	v_cvt_pk_bf16_f32 v11, v18, v19
	global_store_dwordx4 v[16:17], v[8:11], off
	v_and_b32_e32 v13, 0xffff0000, v130
	v_lshlrev_b32_e32 v14, 16, v131
	v_lshlrev_b32_e32 v8, 16, v128
	v_and_b32_e32 v9, 0xffff0000, v128
	v_and_b32_e32 v15, 0xffff0000, v131
	v_lshlrev_b32_e32 v10, 16, v129
	v_and_b32_e32 v11, 0xffff0000, v129
	v_pk_fma_f32 v[4:5], v[4:5], v[210:211], v[8:9]
	v_pk_fma_f32 v[8:9], v[2:3], v[208:209], v[14:15]
	v_pk_fma_f32 v[2:3], v[0:1], v[206:207], v[12:13]
	v_pk_fma_f32 v[6:7], v[6:7], v[212:213], v[10:11]
	v_cvt_pk_bf16_f32 v0, v4, v5
	s_nop 0
	v_cvt_pk_bf16_f32 v1, v6, v7
	v_cvt_pk_bf16_f32 v2, v2, v3
	v_cvt_pk_bf16_f32 v3, v8, v9
	global_store_dwordx4 v[16:17], v[0:3], off offset:256
	s_cbranch_vccz .LBB0_1086
	s_waitcnt vmcnt(0)
	s_cmpk_gt_u32 s30, 0xff
	s_cbranch_scc1 .LBB0_1101
	s_barrier
